# row_bcast DPP reductions folded into single v_add_f32_dpp (312 sites, hazard-padded), step-2 bf16 operand-copy stores use one base VGPR + immediate offsets
# baseline (speedup 1.0000x reference)
.LBB0_103:
	v_mov_b32_e32 v28, v242
	s_and_b32 s42, s40, 0xfffff000
	v_readfirstlane_b32 s7, v28
	s_ashr_i32 s6, s7, 6
	s_add_i32 s8, s34, s45
	s_cmpk_lt_i32 s8, 0x800
	s_cselect_b32 s8, s8, s45
	s_lshl_b32 s9, s8, 4
	s_lshl_b32 s10, s8, 6
	s_and_b32 s9, s9, 0xfffff000
	s_and_b32 s10, s10, 0xfc0
	s_or_b32 s43, s9, s10
	s_ashr_i32 s9, s8, 31
	s_lshl_b64 s[10:11], s[8:9], 14
	v_lshl_add_u64 v[6:7], v[36:37], 0, s[10:11]
	s_add_i32 s10, s43, s5
	s_mul_i32 s11, s10, 0x1800
	s_mul_hi_i32 s9, s10, 0x1800
	s_add_u32 s11, s80, s11
	s_addc_u32 s9, s81, s9
	s_lshl_b32 s8, s8, 2
	s_and_b32 s43, s8, 0x300
	s_add_u32 s8, s11, s43
	s_addc_u32 s9, s9, 0
	v_lshl_add_u64 v[26:27], s[8:9], 0, v[130:131]
	s_or_b32 s8, s10, 1
	s_mul_hi_i32 s9, s8, 0x1800
	s_mulk_i32 s8, 0x1800
	s_add_u32 s8, s80, s8
	s_addc_u32 s9, s81, s9
	v_add_co_u32_e32 v26, vcc, s90, v26
	s_add_u32 s8, s8, s43
	s_nop 0
	v_addc_co_u32_e32 v27, vcc, 0, v27, vcc
	s_addc_u32 s9, s9, 0
	s_waitcnt vmcnt(0)
	v_mov_b32_e32 v60, v44
	global_load_dwordx4 v[2:5], v[6:7], off
	s_nop 0
	global_load_dwordx4 v[6:9], v[6:7], off offset:1024
	v_mov_b32_e32 v59, v43
	global_load_dword v44, v[26:27], off offset:1024
	v_lshl_add_u64 v[26:27], s[8:9], 0, v[130:131]
	s_or_b32 s8, s10, 2
	s_mul_hi_i32 s9, s8, 0x1800
	s_mulk_i32 s8, 0x1800
	s_add_u32 s8, s80, s8
	s_addc_u32 s9, s81, s9
	v_add_co_u32_e32 v26, vcc, s90, v26
	s_add_u32 s8, s8, s43
	s_nop 0
	v_addc_co_u32_e32 v27, vcc, 0, v27, vcc
	s_addc_u32 s9, s9, 0
	global_load_dword v43, v[26:27], off offset:1024
	v_lshl_add_u64 v[26:27], s[8:9], 0, v[130:131]
	s_or_b32 s8, s10, 3
	s_mul_hi_i32 s9, s8, 0x1800
	s_mulk_i32 s8, 0x1800
	s_add_u32 s8, s80, s8
	s_addc_u32 s9, s81, s9
	v_add_co_u32_e32 v26, vcc, s90, v26
	s_add_u32 s8, s8, s43
	s_nop 0
	v_addc_co_u32_e32 v27, vcc, 0, v27, vcc
	s_addc_u32 s9, s9, 0
	v_mov_b32_e32 v58, v42
	global_load_dword v42, v[26:27], off offset:1024
	v_lshl_add_u64 v[26:27], s[8:9], 0, v[130:131]
	s_or_b32 s8, s10, 4
	s_mul_hi_i32 s9, s8, 0x1800
	s_mulk_i32 s8, 0x1800
	s_add_u32 s8, s80, s8
	s_addc_u32 s9, s81, s9
	v_add_co_u32_e32 v26, vcc, s90, v26
	s_add_u32 s8, s8, s43
	s_nop 0
	v_addc_co_u32_e32 v27, vcc, 0, v27, vcc
	s_addc_u32 s9, s9, 0
	v_mov_b32_e32 v57, v41
	global_load_dword v41, v[26:27], off offset:1024
	v_lshl_add_u64 v[26:27], s[8:9], 0, v[130:131]
	s_or_b32 s8, s10, 5
	s_mul_hi_i32 s9, s8, 0x1800
	s_mulk_i32 s8, 0x1800
	s_add_u32 s8, s80, s8
	s_addc_u32 s9, s81, s9
	v_add_co_u32_e32 v26, vcc, s90, v26
	s_add_u32 s8, s8, s43
	s_nop 0
	v_addc_co_u32_e32 v27, vcc, 0, v27, vcc
	s_addc_u32 s9, s9, 0
	v_mov_b32_e32 v56, v40
	global_load_dword v40, v[26:27], off offset:1024
	v_lshl_add_u64 v[26:27], s[8:9], 0, v[130:131]
	s_or_b32 s8, s10, 6
	s_mul_hi_i32 s9, s8, 0x1800
	s_mulk_i32 s8, 0x1800
	s_add_u32 s8, s80, s8
	s_addc_u32 s9, s81, s9
	v_add_co_u32_e32 v26, vcc, s90, v26
	s_add_u32 s8, s8, s43
	s_nop 0
	v_addc_co_u32_e32 v27, vcc, 0, v27, vcc
	s_addc_u32 s9, s9, 0
	v_mov_b32_e32 v55, v39
	global_load_dword v39, v[26:27], off offset:1024
	v_lshl_add_u64 v[26:27], s[8:9], 0, v[130:131]
	s_or_b32 s8, s10, 7
	s_mul_hi_i32 s9, s8, 0x1800
	s_mulk_i32 s8, 0x1800
	s_add_u32 s8, s80, s8
	s_addc_u32 s9, s81, s9
	v_add_co_u32_e32 v26, vcc, s90, v26
	s_add_u32 s8, s8, s43
	s_nop 0
	v_addc_co_u32_e32 v27, vcc, 0, v27, vcc
	s_addc_u32 s9, s9, 0
	v_mov_b32_e32 v54, v38
	global_load_dword v38, v[26:27], off offset:1024
	v_lshl_add_u64 v[26:27], s[8:9], 0, v[130:131]
	v_add_co_u32_e32 v26, vcc, s90, v26
	v_mov_b32_e32 v53, v1
	s_nop 0
	v_addc_co_u32_e32 v27, vcc, 0, v27, vcc
	global_load_dword v1, v[26:27], off offset:1024
	v_lshrrev_b32_e32 v27, 3, v28
	s_lshl_b32 s8, s6, 5
	v_and_b32_e32 v27, 4, v27
	v_and_b32_e32 v26, 31, v28
	v_and_or_b32 v27, s8, 32, v27
	s_and_b32 s7, s7, 0xffffff80
	s_add_i32 s7, s7, 0
	v_lshlrev_b32_e32 v26, 2, v26
	v_mul_u32_u24_e32 v27, 0x210, v27
	v_and_b32_e32 v61, 63, v28
	v_lshlrev_b32_e32 v28, 16, v22
	v_add3_u32 v26, s7, v26, v27
	v_and_b32_e32 v22, 0xffff0000, v22
	ds_write2_b32 v26, v28, v22 offset1:132
	v_lshlrev_b32_e32 v22, 16, v23
	v_and_b32_e32 v23, 0xffff0000, v23
	v_add_u32_e32 v27, 0x400, v26
	ds_write2_b32 v27, v22, v23 offset0:8 offset1:140
	v_lshlrev_b32_e32 v22, 16, v24
	v_and_b32_e32 v23, 0xffff0000, v24
	v_add_u32_e32 v24, 0x1000, v26
	ds_write2_b32 v24, v22, v23 offset0:32 offset1:164
	v_lshlrev_b32_e32 v22, 16, v25
	v_and_b32_e32 v23, 0xffff0000, v25
	v_add_u32_e32 v24, 0x1400, v26
	ds_write2_b32 v24, v22, v23 offset0:40 offset1:172
	v_lshlrev_b32_e32 v22, 16, v18
	v_and_b32_e32 v18, 0xffff0000, v18
	v_add_u32_e32 v23, 0x2000, v26
	ds_write2_b32 v23, v22, v18 offset0:64 offset1:196
	v_lshlrev_b32_e32 v18, 16, v19
	v_and_b32_e32 v19, 0xffff0000, v19
	v_add_u32_e32 v22, 0x2400, v26
	ds_write2_b32 v22, v18, v19 offset0:72 offset1:204
	v_lshlrev_b32_e32 v18, 16, v20
	v_and_b32_e32 v19, 0xffff0000, v20
	v_add_u32_e32 v20, 0x3000, v26
	s_lshl_b32 s43, s6, 3
	s_mulk_i32 s6, 0x1080
	ds_write2_b32 v20, v18, v19 offset0:96 offset1:228
	v_lshlrev_b32_e32 v18, 16, v21
	v_and_b32_e32 v19, 0xffff0000, v21
	v_add_u32_e32 v20, 0x3400, v26
	s_add_i32 s6, s6, 0
	ds_write2_b32 v20, v18, v19 offset0:104 offset1:236
	v_lshl_add_u32 v20, v61, 3, s6
	s_waitcnt lgkmcnt(0)
	s_barrier
	ds_read2_b64 v[30:33], v20 offset1:66
	ds_read2_b64 v[26:29], v20 offset0:132 offset1:198
	v_add_u32_e32 v20, 0x800, v20
	ds_read2_b64 v[22:25], v20 offset0:8 offset1:74
	s_and_b32 s8, s41, 0xfc0
	s_waitcnt lgkmcnt(2)
	v_pk_mul_f32 v[18:19], v[30:31], v[30:31]
	s_or_b32 s8, s42, s8
	v_add_f32_e32 v64, v18, v19
	v_pk_mul_f32 v[18:19], v[32:33], v[32:33]
	s_add_i32 s42, s43, s8
	v_add_f32_e32 v65, v18, v19
	s_waitcnt lgkmcnt(1)
	v_pk_mul_f32 v[18:19], v[26:27], v[26:27]
	s_ashr_i32 s43, s42, 31
	v_add_f32_e32 v66, v18, v19
	v_pk_mul_f32 v[18:19], v[28:29], v[28:29]
	s_and_b32 s11, s44, 0x180
	v_add_f32_e32 v67, v18, v19
	s_waitcnt lgkmcnt(0)
	v_pk_mul_f32 v[18:19], v[22:23], v[22:23]
	s_lshl_b64 s[8:9], s[42:43], 11
	v_add_f32_e32 v68, v18, v19
	v_pk_mul_f32 v[18:19], v[24:25], v[24:25]
	s_add_u32 s8, s76, s8
	v_add_f32_e32 v69, v18, v19
	ds_read2_b64 v[18:21], v20 offset0:140 offset1:206
	s_addc_u32 s9, s77, s9
	s_waitcnt lgkmcnt(0)
	v_pk_mul_f32 v[62:63], v[18:19], v[18:19]
	v_add_f32_e32 v70, v62, v63
	v_pk_mul_f32 v[62:63], v[20:21], v[20:21]
	v_add_f32_e32 v62, v62, v63
	v_add_f32_dpp v63, v64, v64 quad_perm:[1,0,3,2] row_mask:0xf bank_mask:0xf bound_ctrl:1
	v_add_f32_dpp v64, v65, v65 quad_perm:[1,0,3,2] row_mask:0xf bank_mask:0xf bound_ctrl:1
	v_add_f32_dpp v65, v66, v66 quad_perm:[1,0,3,2] row_mask:0xf bank_mask:0xf bound_ctrl:1
	v_add_f32_dpp v63, v63, v63 quad_perm:[2,3,0,1] row_mask:0xf bank_mask:0xf bound_ctrl:1
	v_add_f32_dpp v66, v67, v67 quad_perm:[1,0,3,2] row_mask:0xf bank_mask:0xf bound_ctrl:1
	v_add_f32_dpp v67, v68, v68 quad_perm:[1,0,3,2] row_mask:0xf bank_mask:0xf bound_ctrl:1
	v_add_f32_dpp v63, v63, v63 row_half_mirror row_mask:0xf bank_mask:0xf bound_ctrl:1
	v_add_f32_dpp v68, v69, v69 quad_perm:[1,0,3,2] row_mask:0xf bank_mask:0xf bound_ctrl:1
	v_add_f32_dpp v69, v70, v70 quad_perm:[1,0,3,2] row_mask:0xf bank_mask:0xf bound_ctrl:1
	v_add_f32_dpp v64, v64, v64 quad_perm:[2,3,0,1] row_mask:0xf bank_mask:0xf bound_ctrl:1
	v_add_f32_dpp v63, v63, v63 row_mirror row_mask:0xf bank_mask:0xf bound_ctrl:1
	s_nop 0
	v_add_f32_dpp v64, v64, v64 row_half_mirror row_mask:0xf bank_mask:0xf bound_ctrl:1
	v_add_f32_dpp v65, v65, v65 quad_perm:[2,3,0,1] row_mask:0xf bank_mask:0xf bound_ctrl:1
	v_add_f32_dpp v63, v63, v63 row_bcast:15 row_mask:0xa bank_mask:0xf
	v_add_f32_dpp v64, v64, v64 row_mirror row_mask:0xf bank_mask:0xf bound_ctrl:1
	v_add_f32_dpp v65, v65, v65 row_half_mirror row_mask:0xf bank_mask:0xf bound_ctrl:1
	v_add_f32_dpp v66, v66, v66 quad_perm:[2,3,0,1] row_mask:0xf bank_mask:0xf bound_ctrl:1
	v_add_f32_dpp v64, v64, v64 row_bcast:15 row_mask:0xa bank_mask:0xf
	v_add_f32_dpp v65, v65, v65 row_mirror row_mask:0xf bank_mask:0xf bound_ctrl:1
	v_add_f32_dpp v66, v66, v66 row_half_mirror row_mask:0xf bank_mask:0xf bound_ctrl:1
	v_add_f32_dpp v67, v67, v67 quad_perm:[2,3,0,1] row_mask:0xf bank_mask:0xf bound_ctrl:1
	v_add_f32_dpp v65, v65, v65 row_bcast:15 row_mask:0xa bank_mask:0xf
	v_add_f32_dpp v66, v66, v66 row_mirror row_mask:0xf bank_mask:0xf bound_ctrl:1
	v_add_f32_dpp v67, v67, v67 row_half_mirror row_mask:0xf bank_mask:0xf bound_ctrl:1
	v_add_f32_dpp v68, v68, v68 quad_perm:[2,3,0,1] row_mask:0xf bank_mask:0xf bound_ctrl:1
	v_add_f32_dpp v66, v66, v66 row_bcast:15 row_mask:0xa bank_mask:0xf
	v_add_f32_dpp v67, v67, v67 row_mirror row_mask:0xf bank_mask:0xf bound_ctrl:1
	v_add_f32_dpp v68, v68, v68 row_half_mirror row_mask:0xf bank_mask:0xf bound_ctrl:1
	v_add_f32_dpp v69, v69, v69 quad_perm:[2,3,0,1] row_mask:0xf bank_mask:0xf bound_ctrl:1
	v_add_f32_dpp v67, v67, v67 row_bcast:15 row_mask:0xa bank_mask:0xf
	v_add_f32_dpp v68, v68, v68 row_mirror row_mask:0xf bank_mask:0xf bound_ctrl:1
	v_add_f32_dpp v62, v62, v62 quad_perm:[1,0,3,2] row_mask:0xf bank_mask:0xf bound_ctrl:1
	v_add_f32_dpp v69, v69, v69 row_half_mirror row_mask:0xf bank_mask:0xf bound_ctrl:1
	v_add_f32_dpp v68, v68, v68 row_bcast:15 row_mask:0xa bank_mask:0xf
	v_add_f32_dpp v62, v62, v62 quad_perm:[2,3,0,1] row_mask:0xf bank_mask:0xf bound_ctrl:1
	v_add_f32_dpp v69, v69, v69 row_mirror row_mask:0xf bank_mask:0xf bound_ctrl:1
	s_nop 0
	v_add_f32_dpp v62, v62, v62 row_half_mirror row_mask:0xf bank_mask:0xf bound_ctrl:1
	s_nop 0
	v_add_f32_dpp v69, v69, v69 row_bcast:15 row_mask:0xa bank_mask:0xf
	v_add_f32_dpp v62, v62, v62 row_mirror row_mask:0xf bank_mask:0xf bound_ctrl:1
	s_nop 1
	v_add_f32_dpp v62, v62, v62 row_bcast:15 row_mask:0xa bank_mask:0xf
	s_nop 1
	v_add_f32_dpp v63, v63, v63 row_bcast:31 row_mask:0xc bank_mask:0xf
	s_nop 0
	v_readlane_b32 s6, v63, 63
	s_nop 0
	v_add_f32_dpp v64, v64, v64 row_bcast:31 row_mask:0xc bank_mask:0xf
	s_nop 0
	v_readlane_b32 s10, v64, 63
	v_lshlrev_b32_e32 v64, 16, v52
	v_add_f32_dpp v65, v65, v65 row_bcast:31 row_mask:0xc bank_mask:0xf
	s_nop 0
	v_readlane_b32 s50, v65, 63
	v_and_b32_e32 v65, 0xffff0000, v52
	v_add_f32_dpp v66, v66, v66 row_bcast:31 row_mask:0xc bank_mask:0xf
	v_mul_f32_e32 v52, 0xbfb8aa3b, v64
	v_exp_f32_e32 v52, v52
	v_readlane_b32 s49, v66, 63
	v_add_f32_dpp v67, v67, v67 row_bcast:31 row_mask:0xc bank_mask:0xf
	v_add_f32_e32 v52, 1.0, v52
	v_rcp_f32_e32 v66, v52
	v_add_f32_dpp v68, v68, v68 row_bcast:31 row_mask:0xc bank_mask:0xf
	v_mul_f32_e32 v52, 0xbfb8aa3b, v65
	v_exp_f32_e32 v52, v52
	v_add_f32_dpp v69, v69, v69 row_bcast:31 row_mask:0xc bank_mask:0xf
	v_mov_b32_e32 v70, v131
	v_add_f32_e32 v52, 1.0, v52
	v_readlane_b32 s48, v67, 63
	v_mov_b32_dpp v70, v62 row_bcast:31 row_mask:0xc bank_mask:0xf
	v_add_f32_e32 v62, v62, v70
	v_rcp_f32_e32 v67, v52
	v_readlane_b32 s7, v62, 63
	v_fma_f32 v62, s6, v233, v225
	v_rsq_f32_e32 v62, v62
	s_lshl_b32 s6, s11, 1
	s_add_u32 s8, s8, s6
	s_addc_u32 s9, s9, 0
	v_pk_mul_f32 v[30:31], v[30:31], v[62:63] op_sel_hi:[1,0]
	v_pk_mul_f32 v[62:63], v[66:67], v[64:65]
	v_pk_mul_f32 v[30:31], v[34:35], v[30:31]
	v_readlane_b32 s47, v68, 63
	v_pk_mul_f32 v[30:31], v[62:63], v[30:31]
	v_lshlrev_b32_e32 v62, 16, v51
	v_cvt_pk_bf16_f32 v31, v30, v31
	v_lshlrev_b32_e32 v30, 2, v61
	global_store_dword v30, v31, s[8:9] offset:1024
	v_fma_f32 v31, s10, v233, v225
	v_rsq_f32_e32 v52, v31
	v_mul_f32_e32 v31, 0xbfb8aa3b, v62
	v_exp_f32_e32 v31, v31
	v_and_b32_e32 v63, 0xffff0000, v51
	s_or_b32 s8, s42, 1
	s_ashr_i32 s9, s8, 31
	v_add_f32_e32 v31, 1.0, v31
	v_rcp_f32_e32 v64, v31
	v_mul_f32_e32 v31, 0xbfb8aa3b, v63
	v_exp_f32_e32 v31, v31
	s_lshl_b64 s[8:9], s[8:9], 11
	v_pk_mul_f32 v[32:33], v[32:33], v[52:53] op_sel_hi:[1,0]
	s_add_u32 s8, s76, s8
	v_add_f32_e32 v31, 1.0, v31
	v_rcp_f32_e32 v65, v31
	v_pk_mul_f32 v[32:33], v[34:35], v[32:33]
	s_addc_u32 s9, s77, s9
	s_add_u32 s8, s8, s6
	v_pk_mul_f32 v[62:63], v[64:65], v[62:63]
	s_addc_u32 s9, s9, 0
	v_pk_mul_f32 v[32:33], v[62:63], v[32:33]
	v_lshlrev_b32_e32 v62, 16, v50
	v_cvt_pk_bf16_f32 v31, v32, v33
	global_store_dword v30, v31, s[8:9] offset:1024
	v_fma_f32 v31, s50, v233, v225
	v_rsq_f32_e32 v32, v31
	v_mul_f32_e32 v31, 0xbfb8aa3b, v62
	v_exp_f32_e32 v31, v31
	v_and_b32_e32 v63, 0xffff0000, v50
	s_or_b32 s8, s42, 2
	s_ashr_i32 s9, s8, 31
	v_add_f32_e32 v31, 1.0, v31
	v_rcp_f32_e32 v50, v31
	v_mul_f32_e32 v31, 0xbfb8aa3b, v63
	v_exp_f32_e32 v31, v31
	v_pk_mul_f32 v[26:27], v[26:27], v[32:33] op_sel_hi:[1,0]
	s_lshl_b64 s[8:9], s[8:9], 11
	v_pk_mul_f32 v[26:27], v[34:35], v[26:27]
	v_add_f32_e32 v31, 1.0, v31
	v_rcp_f32_e32 v51, v31
	s_add_u32 s8, s76, s8
	s_addc_u32 s9, s77, s9
	s_add_u32 s8, s8, s6
	v_pk_mul_f32 v[32:33], v[50:51], v[62:63]
	s_addc_u32 s9, s9, 0
	v_pk_mul_f32 v[26:27], v[32:33], v[26:27]
	v_lshlrev_b32_e32 v32, 16, v49
	v_cvt_pk_bf16_f32 v26, v26, v27
	v_mul_f32_e32 v27, 0xbfb8aa3b, v32
	v_exp_f32_e32 v27, v27
	global_store_dword v30, v26, s[8:9] offset:1024
	v_fma_f32 v26, s49, v233, v225
	v_rsq_f32_e32 v26, v26
	v_add_f32_e32 v27, 1.0, v27
	v_and_b32_e32 v33, 0xffff0000, v49
	v_rcp_f32_e32 v50, v27
	s_or_b32 s8, s42, 3
	v_pk_mul_f32 v[26:27], v[28:29], v[26:27] op_sel_hi:[1,0]
	v_mul_f32_e32 v28, 0xbfb8aa3b, v33
	v_exp_f32_e32 v28, v28
	s_ashr_i32 s9, s8, 31
	s_lshl_b64 s[8:9], s[8:9], 11
	s_add_u32 s8, s76, s8
	v_add_f32_e32 v28, 1.0, v28
	v_rcp_f32_e32 v51, v28
	v_pk_mul_f32 v[26:27], v[34:35], v[26:27]
	s_addc_u32 s9, s77, s9
	s_add_u32 s8, s8, s6
	v_pk_mul_f32 v[28:29], v[50:51], v[32:33]
	s_addc_u32 s9, s9, 0
	v_pk_mul_f32 v[26:27], v[28:29], v[26:27]
	v_lshlrev_b32_e32 v28, 16, v48
	v_cvt_pk_bf16_f32 v26, v26, v27
	v_mul_f32_e32 v27, 0xbfb8aa3b, v28
	global_store_dword v30, v26, s[8:9] offset:1024
	v_fma_f32 v26, s48, v233, v225
	v_exp_f32_e32 v27, v27
	v_rsq_f32_e32 v26, v26
	v_and_b32_e32 v29, 0xffff0000, v48
	s_or_b32 s8, s42, 4
	v_add_f32_e32 v27, 1.0, v27
	v_rcp_f32_e32 v32, v27
	v_pk_mul_f32 v[22:23], v[22:23], v[26:27] op_sel_hi:[1,0]
	v_mul_f32_e32 v26, 0xbfb8aa3b, v29
	v_exp_f32_e32 v26, v26
	s_ashr_i32 s9, s8, 31
	s_lshl_b64 s[8:9], s[8:9], 11
	v_pk_mul_f32 v[22:23], v[34:35], v[22:23]
	v_add_f32_e32 v26, 1.0, v26
	v_rcp_f32_e32 v33, v26
	s_add_u32 s8, s76, s8
	s_addc_u32 s9, s77, s9
	s_add_u32 s8, s8, s6
	v_pk_mul_f32 v[26:27], v[32:33], v[28:29]
	s_addc_u32 s9, s9, 0
	v_pk_mul_f32 v[22:23], v[26:27], v[22:23]
	v_lshlrev_b32_e32 v26, 16, v47
	v_cvt_pk_bf16_f32 v22, v22, v23
	v_mul_f32_e32 v23, 0xbfb8aa3b, v26
	v_exp_f32_e32 v23, v23
	global_store_dword v30, v22, s[8:9] offset:1024
	v_fma_f32 v22, s47, v233, v225
	v_rsq_f32_e32 v22, v22
	v_add_f32_e32 v23, 1.0, v23
	v_and_b32_e32 v27, 0xffff0000, v47
	v_rcp_f32_e32 v28, v23
	s_or_b32 s8, s42, 5
	v_pk_mul_f32 v[22:23], v[24:25], v[22:23] op_sel_hi:[1,0]
	v_mul_f32_e32 v24, 0xbfb8aa3b, v27
	v_exp_f32_e32 v24, v24
	s_ashr_i32 s9, s8, 31
	s_lshl_b64 s[8:9], s[8:9], 11
	s_add_u32 s8, s76, s8
	v_add_f32_e32 v24, 1.0, v24
	v_rcp_f32_e32 v29, v24
	v_pk_mul_f32 v[22:23], v[34:35], v[22:23]
	s_addc_u32 s9, s77, s9
	s_add_u32 s8, s8, s6
	v_pk_mul_f32 v[24:25], v[28:29], v[26:27]
	v_readlane_b32 s46, v69, 63
	v_pk_mul_f32 v[22:23], v[24:25], v[22:23]
	v_lshlrev_b32_e32 v24, 16, v46
	v_cvt_pk_bf16_f32 v22, v22, v23
	s_addc_u32 s9, s9, 0
	v_mul_f32_e32 v23, 0xbfb8aa3b, v24
	global_store_dword v30, v22, s[8:9] offset:1024
	v_fma_f32 v22, s46, v233, v225
	v_exp_f32_e32 v23, v23
	v_rsq_f32_e32 v22, v22
	v_and_b32_e32 v25, 0xffff0000, v46
	s_or_b32 s8, s42, 6
	v_add_f32_e32 v23, 1.0, v23
	v_rcp_f32_e32 v26, v23
	v_pk_mul_f32 v[18:19], v[18:19], v[22:23] op_sel_hi:[1,0]
	v_mul_f32_e32 v22, 0xbfb8aa3b, v25
	v_exp_f32_e32 v22, v22
	s_ashr_i32 s9, s8, 31
	s_lshl_b64 s[8:9], s[8:9], 11
	v_pk_mul_f32 v[18:19], v[34:35], v[18:19]
	v_add_f32_e32 v22, 1.0, v22
	v_rcp_f32_e32 v27, v22
	s_add_u32 s8, s76, s8
	s_addc_u32 s9, s77, s9
	s_add_u32 s8, s8, s6
	v_pk_mul_f32 v[22:23], v[26:27], v[24:25]
	s_addc_u32 s9, s9, 0
	v_pk_mul_f32 v[18:19], v[22:23], v[18:19]
	v_lshlrev_b32_e32 v22, 16, v45
	v_cvt_pk_bf16_f32 v18, v18, v19
	v_mul_f32_e32 v19, 0xbfb8aa3b, v22
	v_exp_f32_e32 v19, v19
	global_store_dword v30, v18, s[8:9] offset:1024
	v_fma_f32 v18, s7, v233, v225
	v_rsq_f32_e32 v18, v18
	v_add_f32_e32 v19, 1.0, v19
	v_and_b32_e32 v23, 0xffff0000, v45
	v_rcp_f32_e32 v24, v19
	s_or_b32 s8, s42, 7
	v_pk_mul_f32 v[18:19], v[20:21], v[18:19] op_sel_hi:[1,0]
	v_mul_f32_e32 v20, 0xbfb8aa3b, v23
	v_exp_f32_e32 v20, v20
	s_ashr_i32 s9, s8, 31
	s_lshl_b64 s[8:9], s[8:9], 11
	s_add_u32 s7, s76, s8
	v_add_f32_e32 v20, 1.0, v20
	v_rcp_f32_e32 v25, v20
	v_pk_mul_f32 v[18:19], v[34:35], v[18:19]
	s_addc_u32 s8, s77, s9
	s_add_u32 s6, s7, s6
	v_pk_mul_f32 v[20:21], v[24:25], v[22:23]
	s_addc_u32 s7, s8, 0
	v_pk_mul_f32 v[18:19], v[20:21], v[18:19]
	v_mov_b64_e32 v[24:25], v[16:17]
	v_cvt_pk_bf16_f32 v18, v18, v19
	global_store_dword v30, v18, s[6:7] offset:1024
	v_mov_b64_e32 v[20:21], v[12:13]
	s_add_i32 s45, s45, s4
	s_add_i32 s44, s44, s34
	s_add_i32 s41, s41, s28
	s_add_i32 s40, s40, s29
	v_mov_b64_e32 v[22:23], v[14:15]
	v_mov_b64_e32 v[18:19], v[10:11]
	s_waitcnt vmcnt(17)
	v_mov_b64_e32 v[16:17], v[4:5]
	s_waitcnt vmcnt(16)
	v_mov_b64_e32 v[12:13], v[8:9]
	s_cmpk_gt_i32 s45, 0x7ff
	v_mov_b32_e32 v52, v60
	v_mov_b32_e32 v51, v59
	v_mov_b32_e32 v50, v58
	v_mov_b32_e32 v49, v57
	v_mov_b32_e32 v48, v56
	v_mov_b32_e32 v47, v55
	v_mov_b32_e32 v46, v54
	v_mov_b32_e32 v45, v53
	v_mov_b64_e32 v[14:15], v[2:3]
	v_mov_b64_e32 v[10:11], v[6:7]
	s_barrier
	s_cbranch_scc0 .LBB0_103

.LBB0_133:
	s_or_b64 exec, exec, s[28:29]
	s_add_i32 s47, s50, s5
	s_cmpk_gt_i32 s47, 0x7ff
	s_cselect_b64 s[44:45], -1, 0
	s_lshl_b32 s6, s47, 6
	s_and_b32 s6, s6, 0x7c0
	s_ashr_i32 s7, s47, 5
	s_or_b32 s6, s6, s7
	s_cmpk_lt_i32 s47, 0x800
	s_cselect_b32 s7, s6, s42
	s_and_b32 s10, s7, 63
	s_lshl_b32 s6, s7, 4
	s_lshl_b32 s8, s7, 2
	s_and_b32 s6, s6, 0xfffff000
	s_lshl_b32 s11, s10, 6
	s_and_b32 s8, s8, 0x300
	s_add_u32 s8, s88, s8
	s_addc_u32 s9, s89, 0
	s_cmp_lg_u32 s10, 0
	s_cselect_b64 s[28:29], -1, 0
	s_or_b32 s10, s11, s6
	s_add_i32 s10, s10, -3
	s_mul_i32 s11, s10, 0x1800
	s_mul_hi_i32 s34, s10, 0x1800
	s_add_u32 s8, s8, s11
	s_addc_u32 s9, s9, s34
	v_cmp_eq_u32_e64 s[56:57], v132, v139
	v_cmp_eq_u32_e64 s[58:59], v133, v140
	v_cmp_eq_u32_e64 s[60:61], v134, v141
	v_cmp_eq_u32_e64 s[62:63], v135, v142
	v_cmp_eq_u32_e64 s[64:65], v136, v143
	v_cmp_eq_u32_e64 s[66:67], v137, v144
	v_cmp_eq_u32_e64 s[68:69], v138, v145
	s_or_b64 s[56:57], s[56:57], s[28:29]
	s_or_b64 s[58:59], s[58:59], s[28:29]
	s_or_b64 s[60:61], s[60:61], s[28:29]
	s_or_b64 s[62:63], s[62:63], s[28:29]
	s_or_b64 s[64:65], s[64:65], s[28:29]
	s_or_b64 s[66:67], s[66:67], s[28:29]
	s_or_b64 s[68:69], s[68:69], s[28:29]
	v_cndmask_b32_e64 v2, v139, v132, s[56:57]
	v_cndmask_b32_e64 v3, v140, v133, s[58:59]
	v_cndmask_b32_e64 v4, v141, v134, s[60:61]
	v_cndmask_b32_e64 v5, v142, v135, s[62:63]
	v_cndmask_b32_e64 v6, v143, v136, s[64:65]
	v_cndmask_b32_e64 v7, v144, v137, s[66:67]
	v_cndmask_b32_e64 v8, v145, v138, s[68:69]
	global_load_dwordx4 v[38:41], v2, s[8:9]
	global_load_dwordx4 v[34:37], v3, s[8:9]
	global_load_dwordx4 v[46:49], v4, s[8:9]
	global_load_dwordx4 v[42:45], v5, s[8:9]
	global_load_dwordx4 v[54:57], v6, s[8:9]
	global_load_dwordx4 v[50:53], v7, s[8:9]
	global_load_dwordx4 v[58:61], v8, s[8:9]
	s_bfe_u32 s28, s7, 0x20006
	s_lshl_b32 s34, s28, 9
	v_lshl_add_u64 v[2:3], v[70:71], 0, s[34:35]
	v_add_co_u32_e32 v4, vcc, s90, v2
	s_movk_i32 s8, 0x3000
	s_nop 0
	v_addc_co_u32_e32 v5, vcc, 0, v3, vcc
	v_add_co_u32_e32 v6, vcc, s8, v2
	s_movk_i32 s8, 0x2000
	s_nop 0
	v_addc_co_u32_e32 v7, vcc, 0, v3, vcc
	v_add_co_u32_e32 v8, vcc, s97, v2
	s_lshl_b32 s7, s7, 6
	s_nop 0
	v_addc_co_u32_e32 v9, vcc, 0, v3, vcc
	v_add_co_u32_e32 v10, vcc, s8, v2
	s_movk_i32 s8, 0x5000
	s_nop 0
	v_addc_co_u32_e32 v11, vcc, 0, v3, vcc
	s_and_b32 s7, s7, 0xfc0
	v_add_co_u32_e32 v12, vcc, s8, v2
	s_lshl_b32 s34, s28, 2
	s_nop 0
	v_addc_co_u32_e32 v13, vcc, 0, v3, vcc
	global_load_dwordx2 v[74:75], v[10:11], off
	global_load_dwordx2 v[76:77], v[12:13], off
	global_load_dwordx2 v[64:65], v[10:11], off offset:2048
	global_load_dwordx2 v[78:79], v[6:7], off offset:2048
	global_load_dwordx2 v[86:87], v[2:3], off
	global_load_dwordx2 v[84:85], v[4:5], off offset:2048
	global_load_dwordx2 v[72:73], v[2:3], off offset:2048
	global_load_dwordx2 v[66:67], v[4:5], off
	global_load_dwordx2 v[80:81], v[8:9], off offset:-4096
	global_load_dwordx2 v[82:83], v[8:9], off offset:2048
	global_load_dwordx2 v[62:63], v[8:9], off
	global_load_dwordx2 v[68:69], v[12:13], off offset:2048
	v_or_b32_e32 v2, s7, v224
	v_or_b32_e32 v2, s6, v2
	v_ashrrev_i32_e32 v3, 31, v2
	v_readlane_b32 s6, v254, 22
	s_load_dwordx4 s[8:11], s[0:1], 0x60
	v_lshlrev_b64 v[2:3], 5, v[2:3]
	v_readlane_b32 s7, v254, 23
	s_nop 1
	v_lshl_add_u64 v[2:3], s[6:7], 0, v[2:3]
	s_or_b32 s6, s28, s18
	s_ashr_i32 s7, s6, 31
	s_lshl_b64 s[6:7], s[6:7], 2
	s_waitcnt lgkmcnt(0)
	s_add_u32 s10, s10, s6
	s_addc_u32 s11, s11, s7
	s_add_u32 s6, s8, s6
	v_lshl_add_u64 v[2:3], v[2:3], 0, s[34:35]
	s_addc_u32 s7, s9, s7
	s_lshl_b32 s34, s48, 10
	global_load_dword v99, v[2:3], off
	global_load_dword v98, v[2:3], off offset:16
	v_or_b32_e32 v2, s34, v93
	v_lshl_add_u32 v95, v2, 2, 0
	global_load_dword v100, v131, s[10:11]
	global_load_dword v97, v131, s[6:7]
	ds_read2st64_b32 v[30:31], v95 offset1:1
	ds_read2st64_b32 v[26:27], v95 offset0:128 offset1:129
	ds_read2st64_b32 v[28:29], v95 offset0:2 offset1:3
	ds_read2st64_b32 v[24:25], v95 offset0:4 offset1:5
	ds_read2st64_b32 v[22:23], v95 offset0:6 offset1:7
	ds_read2st64_b32 v[32:33], v95 offset0:130 offset1:131
	ds_read2st64_b32 v[20:21], v95 offset0:132 offset1:133
	ds_read2st64_b32 v[18:19], v95 offset0:134 offset1:135
	s_waitcnt lgkmcnt(6)
	v_pk_mul_f32 v[2:3], v[26:27], v[26:27]
	ds_read2st64_b32 v[14:15], v95 offset0:8 offset1:9
	ds_read2st64_b32 v[10:11], v95 offset0:136 offset1:137
	ds_read2st64_b32 v[12:13], v95 offset0:10 offset1:11
	ds_read2st64_b32 v[8:9], v95 offset0:12 offset1:13
	ds_read2st64_b32 v[6:7], v95 offset0:14 offset1:15
	v_add_f32_e32 v101, v2, v3
	s_waitcnt lgkmcnt(7)
	v_pk_mul_f32 v[2:3], v[32:33], v[32:33]
	v_mul_f32_e32 v96, v31, v31
	v_add_f32_e32 v105, v2, v3
	s_waitcnt lgkmcnt(6)
	v_pk_mul_f32 v[2:3], v[20:21], v[20:21]
	v_fmac_f32_e32 v96, v30, v30
	v_add_f32_e32 v107, v2, v3
	s_waitcnt lgkmcnt(5)
	v_pk_mul_f32 v[2:3], v[18:19], v[18:19]
	s_waitcnt lgkmcnt(3)
	v_pk_mul_f32 v[102:103], v[10:11], v[10:11]
	v_add_f32_e32 v109, v2, v3
	ds_read2st64_b32 v[16:17], v95 offset0:138 offset1:139
	ds_read2st64_b32 v[4:5], v95 offset0:140 offset1:141
	ds_read2st64_b32 v[2:3], v95 offset0:142 offset1:143
	v_add_f32_e32 v111, v102, v103
	v_add_f32_dpp v96, v96, v96 quad_perm:[1,0,3,2] row_mask:0xf bank_mask:0xf bound_ctrl:1
	s_waitcnt lgkmcnt(2)
	v_pk_mul_f32 v[102:103], v[16:17], v[16:17]
	v_mul_f32_e32 v104, v29, v29
	v_mul_f32_e32 v106, v25, v25
	v_mul_f32_e32 v108, v23, v23
	v_mul_f32_e32 v110, v15, v15
	v_mul_f32_e32 v112, v13, v13
	v_add_f32_e32 v113, v102, v103
	v_mul_f32_e32 v114, v9, v9
	s_waitcnt lgkmcnt(1)
	v_pk_mul_f32 v[102:103], v[4:5], v[4:5]
	v_mul_f32_e32 v116, v7, v7
	v_add_f32_dpp v96, v96, v96 quad_perm:[2,3,0,1] row_mask:0xf bank_mask:0xf bound_ctrl:1
	v_fmac_f32_e32 v104, v28, v28
	v_fmac_f32_e32 v106, v24, v24
	v_fmac_f32_e32 v108, v22, v22
	v_fmac_f32_e32 v110, v14, v14
	v_fmac_f32_e32 v112, v12, v12
	v_fmac_f32_e32 v114, v8, v8
	v_add_f32_e32 v115, v102, v103
	v_fmac_f32_e32 v116, v6, v6
	s_waitcnt lgkmcnt(0)
	v_pk_mul_f32 v[102:103], v[2:3], v[2:3]
	v_add_f32_dpp v101, v101, v101 quad_perm:[1,0,3,2] row_mask:0xf bank_mask:0xf bound_ctrl:1
	v_add_f32_dpp v96, v96, v96 row_half_mirror row_mask:0xf bank_mask:0xf bound_ctrl:1
	v_add_f32_e32 v102, v102, v103
	v_add_f32_dpp v103, v104, v104 quad_perm:[1,0,3,2] row_mask:0xf bank_mask:0xf bound_ctrl:1
	v_add_f32_dpp v104, v105, v105 quad_perm:[1,0,3,2] row_mask:0xf bank_mask:0xf bound_ctrl:1
	v_add_f32_dpp v105, v106, v106 quad_perm:[1,0,3,2] row_mask:0xf bank_mask:0xf bound_ctrl:1
	v_add_f32_dpp v106, v107, v107 quad_perm:[1,0,3,2] row_mask:0xf bank_mask:0xf bound_ctrl:1
	v_add_f32_dpp v107, v108, v108 quad_perm:[1,0,3,2] row_mask:0xf bank_mask:0xf bound_ctrl:1
	v_add_f32_dpp v108, v109, v109 quad_perm:[1,0,3,2] row_mask:0xf bank_mask:0xf bound_ctrl:1
	v_add_f32_dpp v109, v110, v110 quad_perm:[1,0,3,2] row_mask:0xf bank_mask:0xf bound_ctrl:1
	v_add_f32_dpp v110, v111, v111 quad_perm:[1,0,3,2] row_mask:0xf bank_mask:0xf bound_ctrl:1
	v_add_f32_dpp v111, v112, v112 quad_perm:[1,0,3,2] row_mask:0xf bank_mask:0xf bound_ctrl:1
	v_add_f32_dpp v112, v113, v113 quad_perm:[1,0,3,2] row_mask:0xf bank_mask:0xf bound_ctrl:1
	v_add_f32_dpp v113, v114, v114 quad_perm:[1,0,3,2] row_mask:0xf bank_mask:0xf bound_ctrl:1
	v_add_f32_dpp v114, v115, v115 quad_perm:[1,0,3,2] row_mask:0xf bank_mask:0xf bound_ctrl:1
	v_add_f32_dpp v115, v116, v116 quad_perm:[1,0,3,2] row_mask:0xf bank_mask:0xf bound_ctrl:1
	v_add_f32_dpp v101, v101, v101 quad_perm:[2,3,0,1] row_mask:0xf bank_mask:0xf bound_ctrl:1
	v_add_f32_dpp v96, v96, v96 row_mirror row_mask:0xf bank_mask:0xf bound_ctrl:1
	s_nop 0
	v_add_f32_dpp v101, v101, v101 row_half_mirror row_mask:0xf bank_mask:0xf bound_ctrl:1
	v_add_f32_dpp v103, v103, v103 quad_perm:[2,3,0,1] row_mask:0xf bank_mask:0xf bound_ctrl:1
	v_add_f32_dpp v96, v96, v96 row_bcast:15 row_mask:0xa bank_mask:0xf
	v_add_f32_dpp v101, v101, v101 row_mirror row_mask:0xf bank_mask:0xf bound_ctrl:1
	v_add_f32_dpp v103, v103, v103 row_half_mirror row_mask:0xf bank_mask:0xf bound_ctrl:1
	v_add_f32_dpp v104, v104, v104 quad_perm:[2,3,0,1] row_mask:0xf bank_mask:0xf bound_ctrl:1
	v_add_f32_dpp v101, v101, v101 row_bcast:15 row_mask:0xa bank_mask:0xf
	v_add_f32_dpp v103, v103, v103 row_mirror row_mask:0xf bank_mask:0xf bound_ctrl:1
	v_add_f32_dpp v104, v104, v104 row_half_mirror row_mask:0xf bank_mask:0xf bound_ctrl:1
	v_add_f32_dpp v105, v105, v105 quad_perm:[2,3,0,1] row_mask:0xf bank_mask:0xf bound_ctrl:1
	v_add_f32_dpp v103, v103, v103 row_bcast:15 row_mask:0xa bank_mask:0xf
	v_add_f32_dpp v104, v104, v104 row_mirror row_mask:0xf bank_mask:0xf bound_ctrl:1
	v_add_f32_dpp v105, v105, v105 row_half_mirror row_mask:0xf bank_mask:0xf bound_ctrl:1
	v_add_f32_dpp v106, v106, v106 quad_perm:[2,3,0,1] row_mask:0xf bank_mask:0xf bound_ctrl:1
	v_add_f32_dpp v104, v104, v104 row_bcast:15 row_mask:0xa bank_mask:0xf
	v_add_f32_dpp v105, v105, v105 row_mirror row_mask:0xf bank_mask:0xf bound_ctrl:1
	v_add_f32_dpp v106, v106, v106 row_half_mirror row_mask:0xf bank_mask:0xf bound_ctrl:1
	v_add_f32_dpp v107, v107, v107 quad_perm:[2,3,0,1] row_mask:0xf bank_mask:0xf bound_ctrl:1
	v_add_f32_dpp v105, v105, v105 row_bcast:15 row_mask:0xa bank_mask:0xf
	v_add_f32_dpp v106, v106, v106 row_mirror row_mask:0xf bank_mask:0xf bound_ctrl:1
	v_add_f32_dpp v107, v107, v107 row_half_mirror row_mask:0xf bank_mask:0xf bound_ctrl:1
	v_add_f32_dpp v108, v108, v108 quad_perm:[2,3,0,1] row_mask:0xf bank_mask:0xf bound_ctrl:1
	v_add_f32_dpp v106, v106, v106 row_bcast:15 row_mask:0xa bank_mask:0xf
	v_add_f32_dpp v107, v107, v107 row_mirror row_mask:0xf bank_mask:0xf bound_ctrl:1
	v_add_f32_dpp v108, v108, v108 row_half_mirror row_mask:0xf bank_mask:0xf bound_ctrl:1
	v_add_f32_dpp v109, v109, v109 quad_perm:[2,3,0,1] row_mask:0xf bank_mask:0xf bound_ctrl:1
	v_add_f32_dpp v107, v107, v107 row_bcast:15 row_mask:0xa bank_mask:0xf
	v_add_f32_dpp v108, v108, v108 row_mirror row_mask:0xf bank_mask:0xf bound_ctrl:1
	v_add_f32_dpp v109, v109, v109 row_half_mirror row_mask:0xf bank_mask:0xf bound_ctrl:1
	v_add_f32_dpp v110, v110, v110 quad_perm:[2,3,0,1] row_mask:0xf bank_mask:0xf bound_ctrl:1
	v_add_f32_dpp v108, v108, v108 row_bcast:15 row_mask:0xa bank_mask:0xf
	v_add_f32_dpp v109, v109, v109 row_mirror row_mask:0xf bank_mask:0xf bound_ctrl:1
	v_add_f32_dpp v110, v110, v110 row_half_mirror row_mask:0xf bank_mask:0xf bound_ctrl:1
	v_add_f32_dpp v111, v111, v111 quad_perm:[2,3,0,1] row_mask:0xf bank_mask:0xf bound_ctrl:1
	v_add_f32_dpp v109, v109, v109 row_bcast:15 row_mask:0xa bank_mask:0xf
	v_add_f32_dpp v110, v110, v110 row_mirror row_mask:0xf bank_mask:0xf bound_ctrl:1
	v_add_f32_dpp v111, v111, v111 row_half_mirror row_mask:0xf bank_mask:0xf bound_ctrl:1
	v_add_f32_dpp v112, v112, v112 quad_perm:[2,3,0,1] row_mask:0xf bank_mask:0xf bound_ctrl:1
	v_add_f32_dpp v110, v110, v110 row_bcast:15 row_mask:0xa bank_mask:0xf
	v_add_f32_dpp v111, v111, v111 row_mirror row_mask:0xf bank_mask:0xf bound_ctrl:1
	v_add_f32_dpp v112, v112, v112 row_half_mirror row_mask:0xf bank_mask:0xf bound_ctrl:1
	v_add_f32_dpp v113, v113, v113 quad_perm:[2,3,0,1] row_mask:0xf bank_mask:0xf bound_ctrl:1
	v_add_f32_dpp v111, v111, v111 row_bcast:15 row_mask:0xa bank_mask:0xf
	v_add_f32_dpp v112, v112, v112 row_mirror row_mask:0xf bank_mask:0xf bound_ctrl:1
	v_add_f32_dpp v113, v113, v113 row_half_mirror row_mask:0xf bank_mask:0xf bound_ctrl:1
	v_add_f32_dpp v114, v114, v114 quad_perm:[2,3,0,1] row_mask:0xf bank_mask:0xf bound_ctrl:1
	v_add_f32_dpp v112, v112, v112 row_bcast:15 row_mask:0xa bank_mask:0xf
	v_add_f32_dpp v113, v113, v113 row_mirror row_mask:0xf bank_mask:0xf bound_ctrl:1
	v_add_f32_dpp v114, v114, v114 row_half_mirror row_mask:0xf bank_mask:0xf bound_ctrl:1
	v_add_f32_dpp v115, v115, v115 quad_perm:[2,3,0,1] row_mask:0xf bank_mask:0xf bound_ctrl:1
	v_add_f32_dpp v113, v113, v113 row_bcast:15 row_mask:0xa bank_mask:0xf
	v_add_f32_dpp v114, v114, v114 row_mirror row_mask:0xf bank_mask:0xf bound_ctrl:1
	v_add_f32_dpp v102, v102, v102 quad_perm:[1,0,3,2] row_mask:0xf bank_mask:0xf bound_ctrl:1
	v_add_f32_dpp v115, v115, v115 row_half_mirror row_mask:0xf bank_mask:0xf bound_ctrl:1
	v_add_f32_dpp v114, v114, v114 row_bcast:15 row_mask:0xa bank_mask:0xf
	v_add_f32_dpp v102, v102, v102 quad_perm:[2,3,0,1] row_mask:0xf bank_mask:0xf bound_ctrl:1
	v_add_f32_dpp v115, v115, v115 row_mirror row_mask:0xf bank_mask:0xf bound_ctrl:1
	s_nop 0
	v_add_f32_dpp v102, v102, v102 row_half_mirror row_mask:0xf bank_mask:0xf bound_ctrl:1
	s_lshl_b32 vcc_hi, s48, 3
	v_add_f32_dpp v115, v115, v115 row_bcast:15 row_mask:0xa bank_mask:0xf
	v_add_f32_dpp v102, v102, v102 row_mirror row_mask:0xf bank_mask:0xf bound_ctrl:1
	s_nop 1
	v_add_f32_dpp v102, v102, v102 row_bcast:15 row_mask:0xa bank_mask:0xf
	s_nop 1
	v_add_f32_dpp v96, v96, v96 row_bcast:31 row_mask:0xc bank_mask:0xf
	s_nop 0
	v_readlane_b32 s7, v96, 63
	s_nop 0
	v_add_f32_dpp v101, v101, v101 row_bcast:31 row_mask:0xc bank_mask:0xf
	v_add_f32_e32 v96, s7, v225
	v_rsq_f32_e32 v96, v96
	v_add_f32_dpp v103, v103, v103 row_bcast:31 row_mask:0xc bank_mask:0xf
	v_readlane_b32 s8, v101, 63
	v_mul_f32_e32 v96, 0x3db504f3, v96
	v_add_f32_dpp v104, v104, v104 row_bcast:31 row_mask:0xc bank_mask:0xf
	v_mul_f32_e32 v30, v30, v96
	v_mul_f32_e32 v31, v31, v96
	v_add_f32_dpp v105, v105, v105 row_bcast:31 row_mask:0xc bank_mask:0xf
	v_readlane_b32 s9, v103, 63
	v_or_b32_e32 v101, 64, v93
	v_add_f32_dpp v106, v106, v106 row_bcast:31 row_mask:0xc bank_mask:0xf
	ds_write2st64_b32 v95, v30, v31 offset1:1
	v_cvt_pk_bf16_f32 v30, v30, s0
	v_add_f32_dpp v107, v107, v107 row_bcast:31 row_mask:0xc bank_mask:0xf
	v_readlane_b32 s10, v104, 63
	v_readlane_b32 s11, v105, 63
	v_add_f32_dpp v108, v108, v108 row_bcast:31 row_mask:0xc bank_mask:0xf
	v_readlane_b32 s40, v107, 63
	v_readlane_b32 s29, v106, 63
	v_add_f32_dpp v109, v109, v109 row_bcast:31 row_mask:0xc bank_mask:0xf
	v_readlane_b32 s41, v108, 63
	v_readlane_b32 s52, v109, 63
	v_add_f32_dpp v110, v110, v110 row_bcast:31 row_mask:0xc bank_mask:0xf
	s_nop 0
	v_readlane_b32 s53, v110, 63
	s_nop 0
	v_add_f32_dpp v111, v111, v111 row_bcast:31 row_mask:0xc bank_mask:0xf
	s_nop 0
	v_readlane_b32 s84, v111, 63
	s_nop 0
	v_add_f32_dpp v112, v112, v112 row_bcast:31 row_mask:0xc bank_mask:0xf
	s_nop 0
	v_readlane_b32 s85, v112, 63
	s_nop 0
	v_add_f32_dpp v113, v113, v113 row_bcast:31 row_mask:0xc bank_mask:0xf
	s_nop 0
	v_readlane_b32 vcc_lo, v113, 63
	s_nop 0
	v_add_f32_dpp v114, v114, v114 row_bcast:31 row_mask:0xc bank_mask:0xf
	s_nop 0
	v_readlane_b32 s28, v114, 63
	s_nop 0
	v_add_f32_dpp v115, v115, v115 row_bcast:31 row_mask:0xc bank_mask:0xf
	v_mov_b32_e32 v116, v131
	v_readlane_b32 s6, v115, 63
	s_nop 0
	v_mov_b32_dpp v116, v102 row_bcast:31 row_mask:0xc bank_mask:0xf
	v_add_f32_e32 v102, v102, v116
	s_nop 0
	v_readlane_b32 s7, v102, 63
	v_add_f32_e32 v102, s8, v225
	s_mul_i32 s8, s48, 0x440
	v_or_b32_e32 v218, s8, v93
	v_lshlrev_b32_e32 v218, 1, v218
	v_add_u32_e32 v218, s49, v218
	ds_write_b16 v218, v30
	v_cvt_pk_bf16_f32 v30, v31, s0
	ds_write_b16 v218, v30 offset:128
	v_add_f32_e32 v30, s9, v225
	v_rsq_f32_e32 v30, v30
	v_add_f32_e32 v103, s10, v225
	v_rsq_f32_e32 v102, v102
	v_rsq_f32_e32 v103, v103
	v_mul_f32_e32 v30, 0x3db504f3, v30
	v_mul_f32_e32 v104, v28, v30
	v_mul_f32_e32 v30, v29, v30
	v_mov_b32_e32 v28, v26
	v_mov_b32_e32 v29, v32
	v_pk_mul_f32 v[28:29], v[28:29], v[102:103]
	v_cvt_pk_bf16_f32 v26, v28, s0
	v_mov_b32_e32 v32, v27
	ds_write_b16 v218, v26 offset:17408
	v_pk_mul_f32 v[26:27], v[32:33], v[102:103]
	s_or_b32 s8, vcc_hi, 1
	v_cvt_pk_bf16_f32 v32, v26, s0
	ds_write_b16 v218, v32 offset:17536
	v_lshl_or_b32 v31, s8, 9, v94
	s_mulk_i32 s8, 0x88
	v_add_u32_e32 v31, 0, v31
	ds_write2st64_b32 v95, v28, v26 offset0:128 offset1:129
	ds_write2st64_b32 v31, v104, v30 offset1:1
	ds_write2st64_b32 v31, v29, v27 offset0:128 offset1:129
	v_cvt_pk_bf16_f32 v31, v104, s0
	ds_write_b16 v218, v31 offset:272
	v_cvt_pk_bf16_f32 v30, v30, s0
	ds_write_b16 v218, v30 offset:400
	v_cvt_pk_bf16_f32 v30, v29, s0
	ds_write_b16 v218, v30 offset:17680
	v_add_f32_e32 v30, s11, v225
	v_rsq_f32_e32 v30, v30
	v_cvt_pk_bf16_f32 v32, v27, s0
	ds_write_b16 v218, v32 offset:17808
	v_mul_f32_e32 v31, 0x3db504f3, v30
	v_mul_f32_e32 v24, v24, v31
	v_mul_f32_e32 v25, v25, v31
	v_lshl_or_b32 v31, s48, 12, v94
	s_add_i32 s9, s8, 0x88
	v_add_u32_e32 v32, 0, v31
	ds_write2st64_b32 v32, v24, v25 offset0:4 offset1:5
	v_cvt_pk_bf16_f32 v24, v24, s0
	ds_write_b16 v218, v24 offset:544
	v_cvt_pk_bf16_f32 v24, v25, s0
	v_add_f32_e32 v94, s40, v225
	v_rsq_f32_e32 v94, v94
	v_add_f32_e32 v30, s29, v225
	ds_write_b16 v218, v24 offset:672
	v_add_f32_e32 v31, s41, v225
	v_rsq_f32_e32 v30, v30
	v_rsq_f32_e32 v31, v31
	v_mul_f32_e32 v33, 0x3db504f3, v94
	v_mul_f32_e32 v94, v22, v33
	v_mul_f32_e32 v33, v23, v33
	v_mov_b32_e32 v22, v20
	v_mov_b32_e32 v23, v18
	v_pk_mul_f32 v[22:23], v[22:23], v[30:31]
	s_add_i32 s9, s8, 0x110
	v_cvt_pk_bf16_f32 v18, v22, s0
	ds_write_b16 v218, v18 offset:17952
	v_mov_b32_e32 v18, v21
	v_pk_mul_f32 v[18:19], v[18:19], v[30:31]
	v_cvt_pk_bf16_f32 v20, v18, s0
	ds_write2st64_b32 v32, v22, v18 offset0:132 offset1:133
	ds_write_b16 v218, v20 offset:18080
	ds_write2st64_b32 v32, v94, v33 offset0:6 offset1:7
	ds_write2st64_b32 v32, v23, v19 offset0:134 offset1:135
	v_cvt_pk_bf16_f32 v20, v94, s0
	ds_write_b16 v218, v20 offset:816
	v_cvt_pk_bf16_f32 v20, v33, s0
	ds_write_b16 v218, v20 offset:944
	v_cvt_pk_bf16_f32 v20, v23, s0
	ds_write_b16 v218, v20 offset:18224
	v_add_f32_e32 v20, s52, v225
	v_rsq_f32_e32 v20, v20
	v_cvt_pk_bf16_f32 v21, v19, s0
	ds_write_b16 v218, v21 offset:18352
	v_mul_f32_e32 v21, 0x3db504f3, v20
	s_add_i32 s9, s8, 0x198
	v_mul_f32_e32 v14, v14, v21
	v_mul_f32_e32 v15, v15, v21
	ds_write2st64_b32 v32, v14, v15 offset0:8 offset1:9
	v_cvt_pk_bf16_f32 v14, v14, s0
	ds_write_b16 v218, v14 offset:1088
	v_cvt_pk_bf16_f32 v14, v15, s0
	v_add_f32_e32 v25, s84, v225
	v_rsq_f32_e32 v25, v25
	v_add_f32_e32 v20, s53, v225
	ds_write_b16 v218, v14 offset:1216
	v_add_f32_e32 v21, s85, v225
	v_rsq_f32_e32 v20, v20
	v_rsq_f32_e32 v21, v21
	v_mul_f32_e32 v24, 0x3db504f3, v25
	v_mul_f32_e32 v25, v12, v24
	v_mul_f32_e32 v24, v13, v24
	v_mov_b32_e32 v12, v10
	v_mov_b32_e32 v13, v16
	v_pk_mul_f32 v[12:13], v[12:13], v[20:21]
	v_mov_b32_e32 v16, v11
	v_cvt_pk_bf16_f32 v10, v12, s0
	ds_write_b16 v218, v10 offset:18496
	v_pk_mul_f32 v[10:11], v[16:17], v[20:21]
	v_cvt_pk_bf16_f32 v14, v10, s0
	s_add_i32 s9, s8, 0x220
	ds_write2st64_b32 v32, v12, v10 offset0:136 offset1:137
	ds_write_b16 v218, v14 offset:18624
	ds_write2st64_b32 v32, v25, v24 offset0:10 offset1:11
	ds_write2st64_b32 v32, v13, v11 offset0:138 offset1:139
	v_cvt_pk_bf16_f32 v14, v25, s0
	ds_write_b16 v218, v14 offset:1360
	v_cvt_pk_bf16_f32 v14, v24, s0
	ds_write_b16 v218, v14 offset:1488
	v_cvt_pk_bf16_f32 v14, v13, s0
	ds_write_b16 v218, v14 offset:18768
	v_add_f32_e32 v14, vcc_lo, v225
	v_rsq_f32_e32 v14, v14
	v_cvt_pk_bf16_f32 v15, v11, s0
	ds_write_b16 v218, v15 offset:18896
	v_mul_f32_e32 v15, 0x3db504f3, v14
	s_add_i32 s9, s8, 0x2a8
	v_mul_f32_e32 v8, v8, v15
	v_mul_f32_e32 v9, v9, v15
	ds_write2st64_b32 v32, v8, v9 offset0:12 offset1:13
	v_cvt_pk_bf16_f32 v8, v8, s0
	ds_write_b16 v218, v8 offset:1632
	v_cvt_pk_bf16_f32 v8, v9, s0
	v_add_f32_e32 v17, s6, v225
	v_rsq_f32_e32 v17, v17
	v_add_f32_e32 v14, s28, v225
	ds_write_b16 v218, v8 offset:1760
	v_add_f32_e32 v15, s7, v225
	v_rsq_f32_e32 v14, v14
	v_rsq_f32_e32 v15, v15
	v_mul_f32_e32 v9, 0x3db504f3, v17
	v_mul_f32_e32 v17, v6, v9
	v_mul_f32_e32 v20, v7, v9
	v_mov_b32_e32 v6, v4
	v_mov_b32_e32 v7, v2
	v_pk_mul_f32 v[6:7], v[6:7], v[14:15]
	s_addk_i32 s8, 0x330
	v_cvt_pk_bf16_f32 v2, v6, s0
	ds_write_b16 v218, v2 offset:19040
	v_mov_b32_e32 v2, v5
	v_pk_mul_f32 v[8:9], v[2:3], v[14:15]
	v_cvt_pk_bf16_f32 v2, v8, s0
	ds_write2st64_b32 v32, v6, v8 offset0:140 offset1:141
	ds_write_b16 v218, v2 offset:19168
	ds_write2st64_b32 v32, v17, v20 offset0:14 offset1:15
	ds_write2st64_b32 v32, v7, v9 offset0:142 offset1:143
	v_cvt_pk_bf16_f32 v2, v17, s0
	ds_write_b16 v218, v2 offset:1904
	v_cvt_pk_bf16_f32 v2, v20, s0
	ds_write_b16 v218, v2 offset:2032
	v_cvt_pk_bf16_f32 v5, v6, v7
	v_bitop3_b32 v6, s48, v1, 7 bitop3:0x78
	v_cvt_pk_bf16_f32 v2, v7, s0
	v_lshlrev_b32_e32 v7, 7, v93
	s_add_i32 s6, 0, 0x14000
	v_lshlrev_b32_e32 v6, 4, v6
	s_ashr_i32 s53, s48, 1
	v_add3_u32 v6, s6, v7, v6
	s_and_b32 s6, s53, 1
	s_and_b32 s52, s48, 1
	s_cmp_eq_u32 s6, 0
	ds_write_b16 v218, v2 offset:19312
	v_cvt_pk_bf16_f32 v2, v9, s0
	s_cselect_b64 s[8:9], -1, 0
	s_bitcmp1_b32 s48, 0
	ds_write_b16 v218, v2 offset:19440
	v_cvt_pk_bf16_f32 v4, v12, v13
	v_cvt_pk_bf16_f32 v3, v22, v23
	v_cvt_pk_bf16_f32 v2, v28, v29
	s_cselect_b64 s[10:11], -1, 0
	ds_write_b128 v6, v[2:5]
	v_cvt_pk_bf16_f32 v5, v8, v9
	v_cvt_pk_bf16_f32 v4, v10, v11
	v_cvt_pk_bf16_f32 v3, v18, v19
	v_cvt_pk_bf16_f32 v2, v26, v27
	s_and_b64 s[8:9], s[8:9], s[10:11]
	ds_write_b128 v6, v[2:5] offset:8192
	v_and_b32_e32 v94, 31, v1
	v_lshrrev_b32_e32 v95, 5, v93
	v_mov_b32_e32 v2, 0
	s_and_b64 vcc, exec, s[8:9]
	v_mov_b32_e32 v3, 0
	v_mov_b32_e32 v4, 0
	v_mov_b32_e32 v5, 0
	v_mov_b32_e32 v6, 0
	v_mov_b32_e32 v7, 0
	v_mov_b32_e32 v8, 0
	v_mov_b32_e32 v9, 0
	v_mov_b32_e32 v10, 0
	v_mov_b32_e32 v11, 0
	v_mov_b32_e32 v12, 0
	v_mov_b32_e32 v13, 0
	v_mov_b32_e32 v14, 0
	v_mov_b32_e32 v15, 0
	v_mov_b32_e32 v16, 0
	v_mov_b32_e32 v17, 0
	s_waitcnt lgkmcnt(0)
	s_barrier
	s_cbranch_vccz .LBB0_136
	s_cmp_gt_u32 s48, 3
	v_lshlrev_b32_e32 v25, 2, v95
	s_mov_b64 s[28:29], -1
	s_cbranch_scc1 .LBB0_137

.LBB0_254:
	v_mov_b32_e32 v3, v242
	s_nop 0
	v_writelane_b32 v254, s6, 27
	s_load_dwordx4 s[8:11], s[0:1], 0x18
	s_load_dwordx2 s[6:7], s[0:1], 0x30
	s_waitcnt lgkmcnt(0)
	v_add_u32_e32 v4, s66, v3
	v_ashrrev_i32_e32 v5, 31, v4
	v_and_b32_e32 v1, 63, v3
	v_readfirstlane_b32 s5, v3
	v_lshl_add_u64 v[4:5], v[4:5], 2, s[6:7]
	global_load_dword v2, v[4:5], off
	v_lshl_add_u32 v4, v3, 2, s40
	s_ashr_i32 s34, s5, 6
	s_lshl_b32 s6, s34, 4
	s_add_i32 s6, s17, s6
	s_add_i32 s7, s6, -1
	s_mul_hi_i32 s7, s7, 0x1800
	v_lshlrev_b32_e32 v7, 1, v1
	s_mov_b32 s19, s60
	s_mov_b32 s13, s66
	v_lshlrev_b32_e32 v130, 4, v1
	s_waitcnt vmcnt(0)
	ds_write_b32 v4, v2
	v_or_b32_e32 v4, s84, v1
	v_ashrrev_i32_e32 v5, 31, v4
	v_lshlrev_b64 v[4:5], 2, v[4:5]
	v_lshl_add_u64 v[18:19], s[8:9], 0, v[4:5]
	s_mul_i32 s8, s6, 0x1800
	s_add_i32 s9, s8, 0xffffe800
	s_add_u32 s28, s80, s9
	s_addc_u32 s29, s81, s7
	s_mul_hi_i32 s7, s6, 0x1800
	s_add_u32 s88, s80, s8
	s_addc_u32 s89, s81, s7
	s_add_i32 s7, s6, 1
	s_add_i32 s9, s8, 0x1800
	v_lshl_add_u64 v[4:5], s[10:11], 0, v[4:5]
	s_mul_hi_i32 s7, s7, 0x1800
	s_mov_b64 s[10:11], s[84:85]
	s_add_u32 s84, s80, s9
	s_addc_u32 s85, s81, s7
	s_add_i32 s7, s6, 2
	s_add_i32 s9, s8, 0x3000
	s_mul_hi_i32 s7, s7, 0x1800
	s_add_u32 s40, s80, s9
	global_load_dword v14, v[18:19], off
	global_load_dword v16, v[4:5], off
	global_load_dword v10, v[18:19], off offset:256
	global_load_dword v12, v[4:5], off offset:256
	global_load_dword v6, v[18:19], off offset:512
	global_load_dword v8, v[4:5], off offset:512
	global_load_dword v2, v[18:19], off offset:768
	s_nop 0
	global_load_dword v4, v[4:5], off offset:768
	s_addc_u32 s41, s81, s7
	global_load_ushort v9, v7, s[28:29] offset:512
	global_load_ushort v11, v7, s[88:89] offset:512
	global_load_ushort v13, v7, s[84:85] offset:512
	global_load_ushort v15, v7, s[40:41] offset:512
	s_add_i32 s7, s6, 3
	s_add_i32 s9, s8, 0x4800
	s_mul_hi_i32 s7, s7, 0x1800
	s_add_u32 s58, s80, s9
	s_addc_u32 s59, s81, s7
	s_add_i32 s7, s6, 4
	s_add_i32 s9, s8, 0x6000
	s_mul_hi_i32 s7, s7, 0x1800
	s_add_u32 s60, s80, s9
	s_addc_u32 s61, s81, s7
	s_add_i32 s7, s6, 5
	s_add_i32 s9, s8, 0x7800
	s_mul_hi_i32 s7, s7, 0x1800
	s_add_u32 s56, s80, s9
	s_addc_u32 s57, s81, s7
	s_add_i32 s7, s6, 6
	s_add_i32 s9, s8, 0x9000
	s_mul_hi_i32 s7, s7, 0x1800
	s_add_u32 s94, s80, s9
	s_addc_u32 s95, s81, s7
	s_add_i32 s7, s6, 7
	s_add_i32 s9, s8, 0xa800
	s_mul_hi_i32 s7, s7, 0x1800
	s_add_u32 s48, s80, s9
	s_addc_u32 s49, s81, s7
	s_add_i32 s7, s6, 8
	s_add_i32 s9, s8, 0xc000
	s_mul_hi_i32 s7, s7, 0x1800
	s_add_u32 s50, s80, s9
	s_addc_u32 s51, s81, s7
	s_add_i32 s7, s6, 9
	s_add_i32 s9, s8, 0xd800
	s_mul_hi_i32 s7, s7, 0x1800
	s_add_u32 s54, s80, s9
	s_addc_u32 s55, s81, s7
	s_add_i32 s7, s6, 10
	s_add_i32 s9, s8, 0xf000
	s_mul_hi_i32 s7, s7, 0x1800
	s_add_u32 s66, s80, s9
	s_addc_u32 s67, s81, s7
	s_add_i32 s7, s6, 11
	s_add_i32 s9, s8, 0x10800
	s_mul_hi_i32 s7, s7, 0x1800
	s_add_u32 s52, s80, s9
	v_mov_b64_e32 v[18:19], s[44:45]
	s_addc_u32 s53, s81, s7
	s_add_i32 s7, s6, 12
	s_add_i32 s9, s8, 0x12000
	s_mul_hi_i32 s7, s7, 0x1800
	s_add_u32 s64, s80, s9
	s_addc_u32 s65, s81, s7
	s_add_i32 s7, s6, 13
	s_add_i32 s9, s8, 0x13800
	s_mul_hi_i32 s7, s7, 0x1800
	s_add_u32 s68, s80, s9
	s_addc_u32 s69, s81, s7
	s_add_i32 s6, s6, 14
	s_add_i32 s8, s8, 0x15000
	s_mul_hi_i32 s6, s6, 0x1800
	s_add_u32 s72, s80, s8
	s_addc_u32 s73, s81, s6
	s_lshl_b32 s34, s34, 5
	s_add_i32 s6, s34, 0
	v_mov_b32_e32 v5, s6
	v_mad_u32_u24 v5, v1, s42, v5
	s_ashr_i32 s5, s5, 7
	s_waitcnt vmcnt(3)
	v_lshlrev_b32_e32 v22, 16, v9
	v_fma_f32 v9, |v22|, s92, 1.0
	v_rcp_f32_e32 v26, v9
	v_mul_f32_e32 v9, v22, v22
	s_waitcnt vmcnt(2)
	v_lshlrev_b32_e32 v23, 16, v11
	v_mul_f32_e32 v9, 0xbf38aa3b, v9
	v_exp_f32_e32 v24, v9
	v_fma_f32 v9, |v23|, s92, 1.0
	v_rcp_f32_e32 v27, v9
	v_mul_f32_e32 v9, v23, v23
	s_waitcnt vmcnt(1)
	v_lshlrev_b32_e32 v20, 16, v13
	v_mul_f32_e32 v9, 0xbf38aa3b, v9
	v_exp_f32_e32 v25, v9
	v_fma_f32 v9, |v20|, s92, 1.0
	v_rcp_f32_e32 v30, v9
	v_mul_f32_e32 v9, v20, v20
	s_waitcnt vmcnt(0)
	v_lshlrev_b32_e32 v21, 16, v15
	v_mul_f32_e32 v9, 0xbf38aa3b, v9
	v_exp_f32_e32 v28, v9
	v_fma_f32 v9, |v21|, s92, 1.0
	v_rcp_f32_e32 v31, v9
	v_mul_f32_e32 v9, v21, v21
	v_mul_f32_e32 v9, 0xbf38aa3b, v9
	v_exp_f32_e32 v29, v9
	global_load_ushort v9, v7, s[28:29] offset:640
	global_load_ushort v11, v7, s[88:89] offset:640
	global_load_ushort v13, v7, s[84:85] offset:640
	global_load_ushort v15, v7, s[40:41] offset:640
	v_pk_fma_f32 v[32:33], v[26:27], s[12:13], v[18:19] op_sel_hi:[1,0,0]
	v_pk_fma_f32 v[34:35], v[30:31], s[12:13], v[18:19] op_sel_hi:[1,0,0]
	v_pk_fma_f32 v[32:33], v[26:27], v[32:33], s[14:15] op_sel_hi:[1,1,0]
	v_pk_fma_f32 v[34:35], v[30:31], v[34:35], s[14:15] op_sel_hi:[1,1,0]
	v_pk_fma_f32 v[32:33], v[26:27], v[32:33], s[16:17] op_sel_hi:[1,1,0]
	v_pk_fma_f32 v[34:35], v[30:31], v[34:35], s[16:17] op_sel_hi:[1,1,0]
	v_pk_fma_f32 v[32:33], v[26:27], v[32:33], s[18:19] op_sel_hi:[1,1,0]
	v_pk_fma_f32 v[34:35], v[30:31], v[34:35], s[18:19] op_sel_hi:[1,1,0]
	v_pk_mul_f32 v[26:27], v[26:27], v[32:33]
	v_cmp_gt_f32_e32 vcc, 0, v22
	v_pk_mul_f32 v[24:25], v[24:25], v[26:27]
	v_pk_mul_f32 v[30:31], v[30:31], v[34:35]
	v_pk_mul_f32 v[26:27], v[24:25], v[22:23]
	v_pk_fma_f32 v[32:33], v[24:25], v[22:23], v[22:23] neg_lo:[1,0,0] neg_hi:[1,0,0]
	v_pk_mul_f32 v[28:29], v[28:29], v[30:31]
	v_cndmask_b32_e32 v22, v32, v26, vcc
	v_pk_mul_f32 v[30:31], v[28:29], v[20:21]
	v_pk_fma_f32 v[24:25], v[28:29], v[20:21], v[20:21] neg_lo:[1,0,0] neg_hi:[1,0,0]
	v_cmp_gt_f32_e64 s[42:43], 0, v23
	v_cmp_gt_f32_e64 s[44:45], 0, v20
	v_cmp_gt_f32_e64 s[46:47], 0, v21
	v_cndmask_b32_e64 v23, v33, v27, s[42:43]
	v_cndmask_b32_e64 v24, v24, v30, s[44:45]
	v_cndmask_b32_e64 v25, v25, v31, s[46:47]
	s_waitcnt vmcnt(3)
	v_lshlrev_b32_e32 v26, 16, v9
	v_fma_f32 v9, |v26|, s92, 1.0
	v_rcp_f32_e32 v28, v9
	v_mul_f32_e32 v9, v26, v26
	s_waitcnt vmcnt(2)
	v_lshlrev_b32_e32 v27, 16, v11
	v_mul_f32_e32 v9, 0xbf38aa3b, v9
	v_exp_f32_e32 v30, v9
	v_fma_f32 v9, |v27|, s92, 1.0
	v_rcp_f32_e32 v29, v9
	v_mul_f32_e32 v9, v27, v27
	s_waitcnt vmcnt(1)
	v_lshlrev_b32_e32 v20, 16, v13
	v_mul_f32_e32 v9, 0xbf38aa3b, v9
	v_exp_f32_e32 v31, v9
	v_fma_f32 v9, |v20|, s92, 1.0
	v_rcp_f32_e32 v32, v9
	v_mul_f32_e32 v9, v20, v20
	s_waitcnt vmcnt(0)
	v_lshlrev_b32_e32 v21, 16, v15
	v_mul_f32_e32 v9, 0xbf38aa3b, v9
	v_exp_f32_e32 v34, v9
	v_fma_f32 v9, |v21|, s92, 1.0
	v_rcp_f32_e32 v33, v9
	v_mul_f32_e32 v9, v21, v21
	v_mul_f32_e32 v9, 0xbf38aa3b, v9
	v_exp_f32_e32 v35, v9
	global_load_ushort v9, v7, s[28:29] offset:768
	global_load_ushort v11, v7, s[88:89] offset:768
	global_load_ushort v13, v7, s[84:85] offset:768
	global_load_ushort v15, v7, s[40:41] offset:768
	v_pk_fma_f32 v[36:37], v[28:29], s[12:13], v[18:19] op_sel_hi:[1,0,0]
	v_pk_fma_f32 v[38:39], v[32:33], s[12:13], v[18:19] op_sel_hi:[1,0,0]
	v_pk_fma_f32 v[36:37], v[28:29], v[36:37], s[14:15] op_sel_hi:[1,1,0]
	v_pk_fma_f32 v[38:39], v[32:33], v[38:39], s[14:15] op_sel_hi:[1,1,0]
	v_pk_fma_f32 v[36:37], v[28:29], v[36:37], s[16:17] op_sel_hi:[1,1,0]
	v_pk_fma_f32 v[38:39], v[32:33], v[38:39], s[16:17] op_sel_hi:[1,1,0]
	v_pk_fma_f32 v[36:37], v[28:29], v[36:37], s[18:19] op_sel_hi:[1,1,0]
	v_pk_fma_f32 v[38:39], v[32:33], v[38:39], s[18:19] op_sel_hi:[1,1,0]
	v_pk_mul_f32 v[28:29], v[28:29], v[36:37]
	v_pk_mul_f32 v[32:33], v[32:33], v[38:39]
	v_pk_mul_f32 v[28:29], v[30:31], v[28:29]
	v_cmp_gt_f32_e32 vcc, 0, v26
	v_pk_mul_f32 v[30:31], v[28:29], v[26:27]
	v_pk_fma_f32 v[28:29], v[28:29], v[26:27], v[26:27] neg_lo:[1,0,0] neg_hi:[1,0,0]
	v_pk_mul_f32 v[32:33], v[34:35], v[32:33]
	v_cndmask_b32_e32 v28, v28, v30, vcc
	v_pk_mul_f32 v[34:35], v[32:33], v[20:21]
	v_pk_fma_f32 v[32:33], v[32:33], v[20:21], v[20:21] neg_lo:[1,0,0] neg_hi:[1,0,0]
	v_cmp_gt_f32_e64 s[44:45], 0, v20
	v_cmp_gt_f32_e64 s[42:43], 0, v27
	v_cmp_gt_f32_e64 s[46:47], 0, v21
	v_cndmask_b32_e64 v26, v32, v34, s[44:45]
	v_cndmask_b32_e64 v29, v29, v31, s[42:43]
	v_cndmask_b32_e64 v27, v33, v35, s[46:47]
	s_waitcnt vmcnt(3)
	v_lshlrev_b32_e32 v30, 16, v9
	v_fma_f32 v9, |v30|, s92, 1.0
	v_rcp_f32_e32 v32, v9
	v_mul_f32_e32 v9, v30, v30
	s_waitcnt vmcnt(2)
	v_lshlrev_b32_e32 v31, 16, v11
	v_mul_f32_e32 v9, 0xbf38aa3b, v9
	v_exp_f32_e32 v34, v9
	v_fma_f32 v9, |v31|, s92, 1.0
	v_rcp_f32_e32 v33, v9
	v_mul_f32_e32 v9, v31, v31
	s_waitcnt vmcnt(1)
	v_lshlrev_b32_e32 v20, 16, v13
	v_mul_f32_e32 v9, 0xbf38aa3b, v9
	v_exp_f32_e32 v35, v9
	v_fma_f32 v9, |v20|, s92, 1.0
	v_rcp_f32_e32 v36, v9
	v_mul_f32_e32 v9, v20, v20
	s_waitcnt vmcnt(0)
	v_lshlrev_b32_e32 v21, 16, v15
	v_mul_f32_e32 v9, 0xbf38aa3b, v9
	v_exp_f32_e32 v38, v9
	v_fma_f32 v9, |v21|, s92, 1.0
	v_rcp_f32_e32 v37, v9
	v_mul_f32_e32 v9, v21, v21
	v_mul_f32_e32 v9, 0xbf38aa3b, v9
	v_exp_f32_e32 v39, v9
	global_load_ushort v9, v7, s[28:29] offset:896
	global_load_ushort v11, v7, s[88:89] offset:896
	global_load_ushort v13, v7, s[84:85] offset:896
	global_load_ushort v15, v7, s[40:41] offset:896
	v_pk_fma_f32 v[40:41], v[32:33], s[12:13], v[18:19] op_sel_hi:[1,0,0]
	v_pk_fma_f32 v[42:43], v[36:37], s[12:13], v[18:19] op_sel_hi:[1,0,0]
	v_pk_fma_f32 v[40:41], v[32:33], v[40:41], s[14:15] op_sel_hi:[1,1,0]
	v_pk_fma_f32 v[42:43], v[36:37], v[42:43], s[14:15] op_sel_hi:[1,1,0]
	v_pk_fma_f32 v[40:41], v[32:33], v[40:41], s[16:17] op_sel_hi:[1,1,0]
	v_pk_fma_f32 v[42:43], v[36:37], v[42:43], s[16:17] op_sel_hi:[1,1,0]
	v_pk_fma_f32 v[40:41], v[32:33], v[40:41], s[18:19] op_sel_hi:[1,1,0]
	v_pk_fma_f32 v[42:43], v[36:37], v[42:43], s[18:19] op_sel_hi:[1,1,0]
	v_pk_mul_f32 v[32:33], v[32:33], v[40:41]
	v_pk_mul_f32 v[36:37], v[36:37], v[42:43]
	v_pk_mul_f32 v[32:33], v[34:35], v[32:33]
	v_cmp_gt_f32_e32 vcc, 0, v30
	v_pk_mul_f32 v[34:35], v[32:33], v[30:31]
	v_pk_fma_f32 v[32:33], v[32:33], v[30:31], v[30:31] neg_lo:[1,0,0] neg_hi:[1,0,0]
	v_pk_mul_f32 v[36:37], v[38:39], v[36:37]
	v_cndmask_b32_e32 v32, v32, v34, vcc
	v_pk_mul_f32 v[38:39], v[36:37], v[20:21]
	v_pk_fma_f32 v[36:37], v[36:37], v[20:21], v[20:21] neg_lo:[1,0,0] neg_hi:[1,0,0]
	v_cmp_gt_f32_e64 s[44:45], 0, v20
	v_cmp_gt_f32_e64 s[42:43], 0, v31
	v_cmp_gt_f32_e64 s[46:47], 0, v21
	v_cndmask_b32_e64 v30, v36, v38, s[44:45]
	v_cndmask_b32_e64 v33, v33, v35, s[42:43]
	v_cndmask_b32_e64 v31, v37, v39, s[46:47]
	s_mov_b64 s[84:85], s[10:11]
	s_mov_b32 s10, 0x3b800000
	v_readlane_b32 s40, v253, 54
	s_waitcnt vmcnt(3)
	v_lshlrev_b32_e32 v34, 16, v9
	v_fma_f32 v9, |v34|, s92, 1.0
	v_rcp_f32_e32 v36, v9
	v_mul_f32_e32 v9, v34, v34
	s_waitcnt vmcnt(2)
	v_lshlrev_b32_e32 v35, 16, v11
	v_mul_f32_e32 v9, 0xbf38aa3b, v9
	v_exp_f32_e32 v38, v9
	v_fma_f32 v9, |v35|, s92, 1.0
	v_rcp_f32_e32 v37, v9
	v_mul_f32_e32 v9, v35, v35
	s_waitcnt vmcnt(1)
	v_lshlrev_b32_e32 v20, 16, v13
	v_mul_f32_e32 v9, 0xbf38aa3b, v9
	v_exp_f32_e32 v39, v9
	v_fma_f32 v9, |v20|, s92, 1.0
	v_rcp_f32_e32 v40, v9
	v_mul_f32_e32 v9, v20, v20
	s_waitcnt vmcnt(0)
	v_lshlrev_b32_e32 v21, 16, v15
	v_mul_f32_e32 v9, 0xbf38aa3b, v9
	v_exp_f32_e32 v42, v9
	v_fma_f32 v9, |v21|, s92, 1.0
	v_rcp_f32_e32 v41, v9
	v_pk_fma_f32 v[44:45], v[36:37], s[12:13], v[18:19] op_sel_hi:[1,0,0]
	v_mul_f32_e32 v9, v21, v21
	v_pk_fma_f32 v[44:45], v[36:37], v[44:45], s[14:15] op_sel_hi:[1,1,0]
	v_pk_fma_f32 v[46:47], v[40:41], s[12:13], v[18:19] op_sel_hi:[1,0,0]
	v_pk_fma_f32 v[44:45], v[36:37], v[44:45], s[16:17] op_sel_hi:[1,1,0]
	v_mul_f32_e32 v9, 0xbf38aa3b, v9
	v_pk_fma_f32 v[46:47], v[40:41], v[46:47], s[14:15] op_sel_hi:[1,1,0]
	v_pk_fma_f32 v[44:45], v[36:37], v[44:45], s[18:19] op_sel_hi:[1,1,0]
	v_exp_f32_e32 v43, v9
	v_pk_fma_f32 v[46:47], v[40:41], v[46:47], s[16:17] op_sel_hi:[1,1,0]
	v_pk_mul_f32 v[36:37], v[36:37], v[44:45]
	v_pk_fma_f32 v[46:47], v[40:41], v[46:47], s[18:19] op_sel_hi:[1,1,0]
	v_pk_mul_f32 v[36:37], v[38:39], v[36:37]
	v_pk_mul_f32 v[40:41], v[40:41], v[46:47]
	v_pk_mul_f32 v[38:39], v[36:37], v[34:35]
	v_pk_fma_f32 v[36:37], v[36:37], v[34:35], v[34:35] neg_lo:[1,0,0] neg_hi:[1,0,0]
	v_cmp_gt_f32_e32 vcc, 0, v34
	v_pk_mul_f32 v[40:41], v[42:43], v[40:41]
	v_cmp_gt_f32_e64 s[42:43], 0, v35
	v_cndmask_b32_e32 v36, v36, v38, vcc
	v_pk_mul_f32 v[42:43], v[40:41], v[20:21]
	v_pk_fma_f32 v[40:41], v[40:41], v[20:21], v[20:21] neg_lo:[1,0,0] neg_hi:[1,0,0]
	v_cmp_gt_f32_e64 s[44:45], 0, v20
	v_cmp_gt_f32_e64 s[46:47], 0, v21
	v_cndmask_b32_e64 v37, v37, v39, s[42:43]
	v_mov_b32_e32 v20, v22
	v_mov_b32_e32 v21, v32
	v_mov_b32_e32 v38, v28
	v_mov_b32_e32 v39, v36
	v_cndmask_b32_e64 v35, v41, v43, s[46:47]
	v_cndmask_b32_e64 v34, v40, v42, s[44:45]
	v_pk_add_f32 v[42:43], v[20:21], v[38:39]
	v_mov_b32_e32 v11, v131
	v_add_f32_e32 v9, v42, v43
	v_mov_b32_e32 v20, v23
	v_mov_b32_e32 v21, v33
	v_add_f32_dpp v9, v9, v9 quad_perm:[1,0,3,2] row_mask:0xf bank_mask:0xf bound_ctrl:1
	v_mov_b32_e32 v38, v29
	v_mov_b32_e32 v39, v37
	v_add_f32_dpp v9, v9, v9 quad_perm:[2,3,0,1] row_mask:0xf bank_mask:0xf bound_ctrl:1
	v_pk_add_f32 v[40:41], v[20:21], v[38:39]
	v_mov_b32_e32 v20, v24
	v_add_f32_dpp v9, v9, v9 row_half_mirror row_mask:0xf bank_mask:0xf bound_ctrl:1
	v_mov_b32_e32 v21, v30
	v_mov_b32_e32 v38, v26
	v_add_f32_dpp v9, v9, v9 row_mirror row_mask:0xf bank_mask:0xf bound_ctrl:1
	v_mov_b32_e32 v39, v34
	v_pk_add_f32 v[38:39], v[20:21], v[38:39]
	v_mov_b32_dpp v11, v9 row_bcast:15 row_mask:0xa bank_mask:0xf
	v_add_f32_e32 v9, v9, v11
	v_mov_b32_e32 v20, v25
	v_mov_b32_e32 v21, v31
	v_add_f32_dpp v9, v9, v9 row_bcast:31 row_mask:0xc bank_mask:0xf
	s_nop 0
	v_readlane_b32 s6, v9, 63
	v_add_f32_e32 v9, v40, v41
	v_mov_b32_e32 v44, v27
	v_mov_b32_e32 v45, v35
	v_add_f32_dpp v9, v9, v9 quad_perm:[1,0,3,2] row_mask:0xf bank_mask:0xf bound_ctrl:1
	v_pk_add_f32 v[20:21], v[20:21], v[44:45]
	s_xor_b32 s6, s6, 0x80000000
	v_add_f32_dpp v9, v9, v9 quad_perm:[2,3,0,1] row_mask:0xf bank_mask:0xf bound_ctrl:1
	s_nop 1
	v_add_f32_dpp v9, v9, v9 row_half_mirror row_mask:0xf bank_mask:0xf bound_ctrl:1
	s_nop 1
	v_add_f32_dpp v9, v9, v9 row_mirror row_mask:0xf bank_mask:0xf bound_ctrl:1
	s_nop 1
	v_add_f32_dpp v9, v9, v9 row_bcast:15 row_mask:0xa bank_mask:0xf
	s_nop 1
	v_add_f32_dpp v9, v9, v9 row_bcast:31 row_mask:0xc bank_mask:0xf
	s_nop 0
	v_readlane_b32 s7, v9, 63
	v_add_f32_e32 v9, v38, v39
	s_xor_b32 s7, s7, 0x80000000
	s_nop 0
	v_add_f32_dpp v9, v9, v9 quad_perm:[1,0,3,2] row_mask:0xf bank_mask:0xf bound_ctrl:1
	s_nop 1
	v_add_f32_dpp v9, v9, v9 quad_perm:[2,3,0,1] row_mask:0xf bank_mask:0xf bound_ctrl:1
	s_nop 1
	v_add_f32_dpp v9, v9, v9 row_half_mirror row_mask:0xf bank_mask:0xf bound_ctrl:1
	s_nop 1
	v_add_f32_dpp v9, v9, v9 row_mirror row_mask:0xf bank_mask:0xf bound_ctrl:1
	s_nop 1
	v_add_f32_dpp v9, v9, v9 row_bcast:15 row_mask:0xa bank_mask:0xf
	s_nop 1
	v_add_f32_dpp v9, v9, v9 row_bcast:31 row_mask:0xc bank_mask:0xf
	v_mov_b32_e32 v11, v131
	v_readlane_b32 s8, v9, 63
	v_add_f32_e32 v9, v20, v21
	v_mov_b64_e32 v[20:21], s[10:11]
	v_pk_fma_f32 v[42:43], s[6:7], v[20:21], v[28:29] op_sel_hi:[1,0,1]
	v_add_f32_dpp v9, v9, v9 quad_perm:[1,0,3,2] row_mask:0xf bank_mask:0xf bound_ctrl:1
	v_pk_fma_f32 v[38:39], s[6:7], v[20:21], v[36:37] op_sel_hi:[1,0,1]
	s_xor_b32 s8, s8, 0x80000000
	v_add_f32_dpp v9, v9, v9 quad_perm:[2,3,0,1] row_mask:0xf bank_mask:0xf bound_ctrl:1
	v_pk_fma_f32 v[44:45], s[6:7], v[20:21], v[22:23] op_sel_hi:[1,0,1]
	v_pk_fma_f32 v[28:29], s[6:7], v[20:21], v[32:33] op_sel_hi:[1,0,1]
	v_add_f32_dpp v9, v9, v9 row_half_mirror row_mask:0xf bank_mask:0xf bound_ctrl:1
	v_mov_b32_e32 v32, v42
	v_mov_b32_e32 v33, v38
	v_add_f32_dpp v9, v9, v9 row_mirror row_mask:0xf bank_mask:0xf bound_ctrl:1
	v_pk_mul_f32 v[32:33], v[32:33], v[32:33]
	s_nop 0
	v_mov_b32_dpp v11, v9 row_bcast:15 row_mask:0xa bank_mask:0xf
	v_add_f32_e32 v9, v9, v11
	s_nop 1
	v_add_f32_dpp v9, v9, v9 row_bcast:31 row_mask:0xc bank_mask:0xf
	v_mov_b32_e32 v11, v131
	v_readlane_b32 s9, v9, 63
	s_xor_b32 s9, s9, 0x80000000
	s_nop 0
	v_pk_fma_f32 v[40:41], s[8:9], v[20:21], v[24:25] op_sel_hi:[1,0,1]
	v_pk_fma_f32 v[24:25], s[8:9], v[20:21], v[30:31] op_sel_hi:[1,0,1]
	v_mov_b32_e32 v30, v44
	v_mov_b32_e32 v31, v28
	v_pk_fma_f32 v[30:31], v[30:31], v[30:31], v[32:33]
	v_mov_b32_e32 v32, v43
	v_add_f32_e32 v9, v30, v31
	v_mov_b32_e32 v33, v39
	v_mov_b32_e32 v30, v45
	v_add_f32_dpp v9, v9, v9 quad_perm:[1,0,3,2] row_mask:0xf bank_mask:0xf bound_ctrl:1
	v_mov_b32_e32 v31, v29
	v_pk_mul_f32 v[32:33], v[32:33], v[32:33]
	v_add_f32_dpp v9, v9, v9 quad_perm:[2,3,0,1] row_mask:0xf bank_mask:0xf bound_ctrl:1
	v_pk_fma_f32 v[30:31], v[30:31], v[30:31], v[32:33]
	v_pk_fma_f32 v[26:27], s[8:9], v[20:21], v[26:27] op_sel_hi:[1,0,1]
	v_add_f32_dpp v9, v9, v9 row_half_mirror row_mask:0xf bank_mask:0xf bound_ctrl:1
	v_pk_fma_f32 v[22:23], s[8:9], v[20:21], v[34:35] op_sel_hi:[1,0,1]
	v_mov_b32_e32 v32, v26
	v_add_f32_dpp v9, v9, v9 row_mirror row_mask:0xf bank_mask:0xf bound_ctrl:1
	v_mov_b32_e32 v33, v22
	v_pk_mul_f32 v[32:33], v[32:33], v[32:33]
	v_mov_b32_dpp v11, v9 row_bcast:15 row_mask:0xa bank_mask:0xf
	v_add_f32_e32 v9, v9, v11
	s_nop 1
	v_add_f32_dpp v9, v9, v9 row_bcast:31 row_mask:0xc bank_mask:0xf
	v_mov_b32_e32 v11, v131
	v_readlane_b32 s6, v9, 63
	s_nop 1
	v_fma_f32 v9, s6, v235, v225
	v_rsq_f32_e32 v46, v9
	v_add_f32_e32 v9, v30, v31
	v_mov_b32_e32 v30, v40
	v_mov_b32_e32 v31, v24
	v_add_f32_dpp v9, v9, v9 quad_perm:[1,0,3,2] row_mask:0xf bank_mask:0xf bound_ctrl:1
	v_pk_fma_f32 v[30:31], v[30:31], v[30:31], v[32:33]
	v_mov_b32_e32 v32, v27
	v_add_f32_dpp v9, v9, v9 quad_perm:[2,3,0,1] row_mask:0xf bank_mask:0xf bound_ctrl:1
	v_mov_b32_e32 v33, v23
	v_pk_mul_f32 v[32:33], v[32:33], v[32:33]
	v_add_f32_dpp v9, v9, v9 row_half_mirror row_mask:0xf bank_mask:0xf bound_ctrl:1
	s_nop 1
	v_add_f32_dpp v9, v9, v9 row_mirror row_mask:0xf bank_mask:0xf bound_ctrl:1
	s_nop 1
	v_mov_b32_dpp v11, v9 row_bcast:15 row_mask:0xa bank_mask:0xf
	v_add_f32_e32 v9, v9, v11
	s_nop 1
	v_add_f32_dpp v9, v9, v9 row_bcast:31 row_mask:0xc bank_mask:0xf
	v_mov_b32_e32 v11, v131
	v_readlane_b32 s6, v9, 63
	s_nop 1
	v_fma_f32 v9, s6, v235, v225
	v_rsq_f32_e32 v47, v9
	v_add_f32_e32 v9, v30, v31
	v_mov_b32_e32 v30, v41
	v_mov_b32_e32 v31, v25
	v_add_f32_dpp v9, v9, v9 quad_perm:[1,0,3,2] row_mask:0xf bank_mask:0xf bound_ctrl:1
	v_pk_fma_f32 v[30:31], v[30:31], v[30:31], v[32:33]
	v_pk_mul_f32 v[28:29], v[28:29], v[46:47]
	v_add_f32_dpp v9, v9, v9 quad_perm:[2,3,0,1] row_mask:0xf bank_mask:0xf bound_ctrl:1
	s_nop 1
	v_add_f32_dpp v9, v9, v9 row_half_mirror row_mask:0xf bank_mask:0xf bound_ctrl:1
	s_nop 1
	v_add_f32_dpp v9, v9, v9 row_mirror row_mask:0xf bank_mask:0xf bound_ctrl:1
	s_nop 1
	v_mov_b32_dpp v11, v9 row_bcast:15 row_mask:0xa bank_mask:0xf
	v_add_f32_e32 v9, v9, v11
	s_nop 1
	v_add_f32_dpp v9, v9, v9 row_bcast:31 row_mask:0xc bank_mask:0xf
	v_mov_b32_e32 v11, v131
	v_readlane_b32 s6, v9, 63
	s_nop 1
	v_fma_f32 v9, s6, v235, v225
	v_rsq_f32_e32 v48, v9
	v_add_f32_e32 v9, v30, v31
	v_pk_mul_f32 v[30:31], v[44:45], v[46:47]
	s_nop 0
	v_add_f32_dpp v9, v9, v9 quad_perm:[1,0,3,2] row_mask:0xf bank_mask:0xf bound_ctrl:1
	v_pk_fma_f32 v[36:37], v[14:15], v[30:31], v[16:17] op_sel_hi:[0,1,0]
	s_nop 0
	v_add_f32_dpp v9, v9, v9 quad_perm:[2,3,0,1] row_mask:0xf bank_mask:0xf bound_ctrl:1
	s_nop 1
	v_add_f32_dpp v9, v9, v9 row_half_mirror row_mask:0xf bank_mask:0xf bound_ctrl:1
	s_nop 1
	v_add_f32_dpp v9, v9, v9 row_mirror row_mask:0xf bank_mask:0xf bound_ctrl:1
	s_nop 1
	v_mov_b32_dpp v11, v9 row_bcast:15 row_mask:0xa bank_mask:0xf
	v_add_f32_e32 v9, v9, v11
	v_mov_b32_e32 v11, v131
	s_nop 1
	v_mov_b32_dpp v11, v9 row_bcast:31 row_mask:0xc bank_mask:0xf
	v_add_f32_e32 v9, v9, v11
	s_nop 0
	v_readlane_b32 s6, v9, 63
	s_nop 1
	v_fma_f32 v9, s6, v235, v225
	v_rsq_f32_e32 v49, v9
	v_pk_fma_f32 v[28:29], v[6:7], v[28:29], v[8:9] op_sel_hi:[0,1,0]
	v_pk_mul_f32 v[32:33], v[40:41], v[48:49]
	v_pk_fma_f32 v[34:35], v[14:15], v[32:33], v[16:17] op_sel_hi:[0,1,0]
	v_pk_mul_f32 v[32:33], v[42:43], v[46:47]
	v_pk_mul_f32 v[26:27], v[26:27], v[48:49]
	v_pk_mul_f32 v[24:25], v[24:25], v[48:49]
	v_pk_fma_f32 v[30:31], v[10:11], v[26:27], v[12:13] op_sel_hi:[0,1,0]
	v_pk_fma_f32 v[32:33], v[10:11], v[32:33], v[12:13] op_sel_hi:[0,1,0]
	v_pk_fma_f32 v[26:27], v[6:7], v[24:25], v[8:9] op_sel_hi:[0,1,0]
	global_load_ushort v9, v7, s[58:59] offset:512
	global_load_ushort v11, v7, s[60:61] offset:512
	global_load_ushort v13, v7, s[56:57] offset:512
	global_load_ushort v15, v7, s[94:95] offset:512
	v_pk_mul_f32 v[24:25], v[38:39], v[46:47]
	v_pk_mul_f32 v[22:23], v[22:23], v[48:49]
	v_pk_fma_f32 v[24:25], v[2:3], v[24:25], v[4:5] op_sel_hi:[0,1,0]
	v_pk_fma_f32 v[22:23], v[2:3], v[22:23], v[4:5] op_sel_hi:[0,1,0]
	s_waitcnt vmcnt(3)
	v_lshlrev_b32_e32 v40, 16, v9
	v_fma_f32 v9, |v40|, s92, 1.0
	v_rcp_f32_e32 v42, v9
	v_mul_f32_e32 v9, v40, v40
	s_waitcnt vmcnt(2)
	v_lshlrev_b32_e32 v41, 16, v11
	v_mul_f32_e32 v9, 0xbf38aa3b, v9
	v_exp_f32_e32 v44, v9
	v_fma_f32 v9, |v41|, s92, 1.0
	v_rcp_f32_e32 v43, v9
	v_mul_f32_e32 v9, v41, v41
	s_waitcnt vmcnt(1)
	v_lshlrev_b32_e32 v38, 16, v13
	v_mul_f32_e32 v9, 0xbf38aa3b, v9
	v_exp_f32_e32 v45, v9
	v_fma_f32 v9, |v38|, s92, 1.0
	v_rcp_f32_e32 v46, v9
	v_mul_f32_e32 v9, v38, v38
	s_waitcnt vmcnt(0)
	v_lshlrev_b32_e32 v39, 16, v15
	v_mul_f32_e32 v9, 0xbf38aa3b, v9
	v_exp_f32_e32 v48, v9
	v_fma_f32 v9, |v39|, s92, 1.0
	v_rcp_f32_e32 v47, v9
	v_mul_f32_e32 v9, v39, v39
	v_mul_f32_e32 v9, 0xbf38aa3b, v9
	v_exp_f32_e32 v49, v9
	global_load_ushort v9, v7, s[58:59] offset:640
	global_load_ushort v11, v7, s[60:61] offset:640
	global_load_ushort v13, v7, s[56:57] offset:640
	global_load_ushort v15, v7, s[94:95] offset:640
	v_pk_fma_f32 v[50:51], v[42:43], s[12:13], v[18:19] op_sel_hi:[1,0,0]
	v_pk_fma_f32 v[52:53], v[46:47], s[12:13], v[18:19] op_sel_hi:[1,0,0]
	v_pk_fma_f32 v[50:51], v[42:43], v[50:51], s[14:15] op_sel_hi:[1,1,0]
	v_pk_fma_f32 v[52:53], v[46:47], v[52:53], s[14:15] op_sel_hi:[1,1,0]
	v_pk_fma_f32 v[50:51], v[42:43], v[50:51], s[16:17] op_sel_hi:[1,1,0]
	v_pk_fma_f32 v[52:53], v[46:47], v[52:53], s[16:17] op_sel_hi:[1,1,0]
	v_pk_fma_f32 v[50:51], v[42:43], v[50:51], s[18:19] op_sel_hi:[1,1,0]
	v_pk_fma_f32 v[52:53], v[46:47], v[52:53], s[18:19] op_sel_hi:[1,1,0]
	v_pk_mul_f32 v[42:43], v[42:43], v[50:51]
	v_pk_mul_f32 v[46:47], v[46:47], v[52:53]
	v_pk_mul_f32 v[42:43], v[44:45], v[42:43]
	v_pk_mul_f32 v[46:47], v[48:49], v[46:47]
	v_pk_mul_f32 v[44:45], v[42:43], v[40:41]
	v_pk_fma_f32 v[42:43], v[42:43], v[40:41], v[40:41] neg_lo:[1,0,0] neg_hi:[1,0,0]
	v_cmp_gt_f32_e32 vcc, 0, v40
	v_pk_mul_f32 v[48:49], v[46:47], v[38:39]
	v_pk_fma_f32 v[46:47], v[46:47], v[38:39], v[38:39] neg_lo:[1,0,0] neg_hi:[1,0,0]
	v_cmp_gt_f32_e64 s[44:45], 0, v38
	v_cndmask_b32_e32 v38, v42, v44, vcc
	v_cmp_gt_f32_e64 s[42:43], 0, v41
	v_cndmask_b32_e64 v40, v46, v48, s[44:45]
	v_cmp_gt_f32_e64 s[46:47], 0, v39
	v_cndmask_b32_e64 v39, v43, v45, s[42:43]
	s_waitcnt vmcnt(3)
	v_lshlrev_b32_e32 v44, 16, v9
	v_fma_f32 v9, |v44|, s92, 1.0
	v_rcp_f32_e32 v46, v9
	v_mul_f32_e32 v9, v44, v44
	s_waitcnt vmcnt(2)
	v_lshlrev_b32_e32 v45, 16, v11
	v_mul_f32_e32 v9, 0xbf38aa3b, v9
	v_exp_f32_e32 v48, v9
	v_fma_f32 v9, |v45|, s92, 1.0
	v_cndmask_b32_e64 v41, v47, v49, s[46:47]
	v_rcp_f32_e32 v47, v9
	v_mul_f32_e32 v9, v45, v45
	s_waitcnt vmcnt(1)
	v_lshlrev_b32_e32 v42, 16, v13
	v_mul_f32_e32 v9, 0xbf38aa3b, v9
	v_exp_f32_e32 v49, v9
	v_fma_f32 v9, |v42|, s92, 1.0
	v_rcp_f32_e32 v50, v9
	v_mul_f32_e32 v9, v42, v42
	s_waitcnt vmcnt(0)
	v_lshlrev_b32_e32 v43, 16, v15
	v_mul_f32_e32 v9, 0xbf38aa3b, v9
	v_exp_f32_e32 v52, v9
	v_fma_f32 v9, |v43|, s92, 1.0
	v_rcp_f32_e32 v51, v9
	v_mul_f32_e32 v9, v43, v43
	v_mul_f32_e32 v9, 0xbf38aa3b, v9
	v_exp_f32_e32 v53, v9
	global_load_ushort v9, v7, s[58:59] offset:768
	global_load_ushort v11, v7, s[60:61] offset:768
	global_load_ushort v13, v7, s[56:57] offset:768
	global_load_ushort v15, v7, s[94:95] offset:768
	v_pk_fma_f32 v[54:55], v[46:47], s[12:13], v[18:19] op_sel_hi:[1,0,0]
	v_pk_fma_f32 v[56:57], v[50:51], s[12:13], v[18:19] op_sel_hi:[1,0,0]
	v_pk_fma_f32 v[54:55], v[46:47], v[54:55], s[14:15] op_sel_hi:[1,1,0]
	v_pk_fma_f32 v[56:57], v[50:51], v[56:57], s[14:15] op_sel_hi:[1,1,0]
	v_pk_fma_f32 v[54:55], v[46:47], v[54:55], s[16:17] op_sel_hi:[1,1,0]
	v_pk_fma_f32 v[56:57], v[50:51], v[56:57], s[16:17] op_sel_hi:[1,1,0]
	v_pk_fma_f32 v[54:55], v[46:47], v[54:55], s[18:19] op_sel_hi:[1,1,0]
	v_pk_fma_f32 v[56:57], v[50:51], v[56:57], s[18:19] op_sel_hi:[1,1,0]
	v_pk_mul_f32 v[46:47], v[46:47], v[54:55]
	v_pk_mul_f32 v[50:51], v[50:51], v[56:57]
	v_pk_mul_f32 v[46:47], v[48:49], v[46:47]
	v_cmp_gt_f32_e32 vcc, 0, v44
	v_pk_mul_f32 v[48:49], v[46:47], v[44:45]
	v_pk_fma_f32 v[46:47], v[46:47], v[44:45], v[44:45] neg_lo:[1,0,0] neg_hi:[1,0,0]
	v_pk_mul_f32 v[50:51], v[52:53], v[50:51]
	v_cndmask_b32_e32 v44, v46, v48, vcc
	v_pk_mul_f32 v[52:53], v[50:51], v[42:43]
	v_pk_fma_f32 v[50:51], v[50:51], v[42:43], v[42:43] neg_lo:[1,0,0] neg_hi:[1,0,0]
	v_cmp_gt_f32_e64 s[44:45], 0, v42
	v_cmp_gt_f32_e64 s[42:43], 0, v45
	v_cmp_gt_f32_e64 s[46:47], 0, v43
	v_cndmask_b32_e64 v42, v50, v52, s[44:45]
	v_cndmask_b32_e64 v45, v47, v49, s[42:43]
	v_cndmask_b32_e64 v43, v51, v53, s[46:47]
	s_waitcnt vmcnt(3)
	v_lshlrev_b32_e32 v48, 16, v9
	v_fma_f32 v9, |v48|, s92, 1.0
	v_rcp_f32_e32 v50, v9
	v_mul_f32_e32 v9, v48, v48
	s_waitcnt vmcnt(2)
	v_lshlrev_b32_e32 v49, 16, v11
	v_mul_f32_e32 v9, 0xbf38aa3b, v9
	v_exp_f32_e32 v52, v9
	v_fma_f32 v9, |v49|, s92, 1.0
	v_rcp_f32_e32 v51, v9
	v_mul_f32_e32 v9, v49, v49
	s_waitcnt vmcnt(1)
	v_lshlrev_b32_e32 v46, 16, v13
	v_mul_f32_e32 v9, 0xbf38aa3b, v9
	v_exp_f32_e32 v53, v9
	v_fma_f32 v9, |v46|, s92, 1.0
	v_rcp_f32_e32 v54, v9
	v_mul_f32_e32 v9, v46, v46
	s_waitcnt vmcnt(0)
	v_lshlrev_b32_e32 v47, 16, v15
	v_mul_f32_e32 v9, 0xbf38aa3b, v9
	v_exp_f32_e32 v56, v9
	v_fma_f32 v9, |v47|, s92, 1.0
	v_rcp_f32_e32 v55, v9
	v_mul_f32_e32 v9, v47, v47
	v_mul_f32_e32 v9, 0xbf38aa3b, v9
	v_exp_f32_e32 v57, v9
	global_load_ushort v9, v7, s[58:59] offset:896
	global_load_ushort v11, v7, s[60:61] offset:896
	global_load_ushort v13, v7, s[56:57] offset:896
	global_load_ushort v15, v7, s[94:95] offset:896
	v_pk_fma_f32 v[58:59], v[50:51], s[12:13], v[18:19] op_sel_hi:[1,0,0]
	v_pk_fma_f32 v[60:61], v[54:55], s[12:13], v[18:19] op_sel_hi:[1,0,0]
	v_pk_fma_f32 v[58:59], v[50:51], v[58:59], s[14:15] op_sel_hi:[1,1,0]
	v_pk_fma_f32 v[60:61], v[54:55], v[60:61], s[14:15] op_sel_hi:[1,1,0]
	v_pk_fma_f32 v[58:59], v[50:51], v[58:59], s[16:17] op_sel_hi:[1,1,0]
	v_pk_fma_f32 v[60:61], v[54:55], v[60:61], s[16:17] op_sel_hi:[1,1,0]
	v_pk_fma_f32 v[58:59], v[50:51], v[58:59], s[18:19] op_sel_hi:[1,1,0]
	v_pk_fma_f32 v[60:61], v[54:55], v[60:61], s[18:19] op_sel_hi:[1,1,0]
	v_pk_mul_f32 v[50:51], v[50:51], v[58:59]
	v_pk_mul_f32 v[54:55], v[54:55], v[60:61]
	v_pk_mul_f32 v[50:51], v[52:53], v[50:51]
	v_cmp_gt_f32_e32 vcc, 0, v48
	v_pk_mul_f32 v[52:53], v[50:51], v[48:49]
	v_pk_fma_f32 v[50:51], v[50:51], v[48:49], v[48:49] neg_lo:[1,0,0] neg_hi:[1,0,0]
	v_pk_mul_f32 v[54:55], v[56:57], v[54:55]
	v_cndmask_b32_e32 v48, v50, v52, vcc
	v_pk_mul_f32 v[56:57], v[54:55], v[46:47]
	v_pk_fma_f32 v[54:55], v[54:55], v[46:47], v[46:47] neg_lo:[1,0,0] neg_hi:[1,0,0]
	v_cmp_gt_f32_e64 s[44:45], 0, v46
	v_cmp_gt_f32_e64 s[42:43], 0, v49
	v_cmp_gt_f32_e64 s[46:47], 0, v47
	v_cndmask_b32_e64 v46, v54, v56, s[44:45]
	v_cndmask_b32_e64 v49, v51, v53, s[42:43]
	v_cndmask_b32_e64 v47, v55, v57, s[46:47]
	global_load_ushort v68, v7, s[48:49] offset:512
	global_load_ushort v69, v7, s[50:51] offset:512
	global_load_ushort v70, v7, s[54:55] offset:512
	global_load_ushort v71, v7, s[66:67] offset:512
	global_load_ushort v72, v7, s[48:49] offset:640
	global_load_ushort v73, v7, s[50:51] offset:640
	global_load_ushort v74, v7, s[54:55] offset:640
	global_load_ushort v75, v7, s[66:67] offset:640
	global_load_ushort v76, v7, s[48:49] offset:768
	global_load_ushort v77, v7, s[50:51] offset:768
	global_load_ushort v78, v7, s[54:55] offset:768
	global_load_ushort v79, v7, s[66:67] offset:768
	global_load_ushort v80, v7, s[48:49] offset:896
	global_load_ushort v81, v7, s[50:51] offset:896
	global_load_ushort v82, v7, s[54:55] offset:896
	global_load_ushort v83, v7, s[66:67] offset:896
	s_mov_b32 s60, s19
	s_mov_b32 s66, s13
	s_waitcnt vmcnt(19)
	v_lshlrev_b32_e32 v52, 16, v9
	v_fma_f32 v9, |v52|, s92, 1.0
	v_rcp_f32_e32 v54, v9
	v_mul_f32_e32 v9, v52, v52
	s_waitcnt vmcnt(18)
	v_lshlrev_b32_e32 v53, 16, v11
	v_mul_f32_e32 v9, 0xbf38aa3b, v9
	v_exp_f32_e32 v56, v9
	v_fma_f32 v9, |v53|, s92, 1.0
	v_rcp_f32_e32 v55, v9
	v_mul_f32_e32 v9, v53, v53
	s_waitcnt vmcnt(17)
	v_lshlrev_b32_e32 v50, 16, v13
	v_mul_f32_e32 v9, 0xbf38aa3b, v9
	v_exp_f32_e32 v57, v9
	v_fma_f32 v9, |v50|, s92, 1.0
	v_rcp_f32_e32 v58, v9
	v_mul_f32_e32 v9, v50, v50
	s_waitcnt vmcnt(16)
	v_lshlrev_b32_e32 v51, 16, v15
	v_mul_f32_e32 v9, 0xbf38aa3b, v9
	v_exp_f32_e32 v60, v9
	v_fma_f32 v9, |v51|, s92, 1.0
	v_rcp_f32_e32 v59, v9
	v_pk_fma_f32 v[62:63], v[54:55], s[12:13], v[18:19] op_sel_hi:[1,0,0]
	v_mul_f32_e32 v9, v51, v51
	v_pk_fma_f32 v[62:63], v[54:55], v[62:63], s[14:15] op_sel_hi:[1,1,0]
	v_pk_fma_f32 v[64:65], v[58:59], s[12:13], v[18:19] op_sel_hi:[1,0,0]
	v_pk_fma_f32 v[62:63], v[54:55], v[62:63], s[16:17] op_sel_hi:[1,1,0]
	v_mul_f32_e32 v9, 0xbf38aa3b, v9
	v_pk_fma_f32 v[64:65], v[58:59], v[64:65], s[14:15] op_sel_hi:[1,1,0]
	v_pk_fma_f32 v[62:63], v[54:55], v[62:63], s[18:19] op_sel_hi:[1,1,0]
	v_exp_f32_e32 v61, v9
	v_pk_fma_f32 v[64:65], v[58:59], v[64:65], s[16:17] op_sel_hi:[1,1,0]
	v_pk_mul_f32 v[54:55], v[54:55], v[62:63]
	v_pk_fma_f32 v[64:65], v[58:59], v[64:65], s[18:19] op_sel_hi:[1,1,0]
	v_pk_mul_f32 v[54:55], v[56:57], v[54:55]
	v_pk_mul_f32 v[58:59], v[58:59], v[64:65]
	v_pk_mul_f32 v[56:57], v[54:55], v[52:53]
	v_pk_fma_f32 v[54:55], v[54:55], v[52:53], v[52:53] neg_lo:[1,0,0] neg_hi:[1,0,0]
	v_cmp_gt_f32_e32 vcc, 0, v52
	v_pk_mul_f32 v[58:59], v[60:61], v[58:59]
	v_cmp_gt_f32_e64 s[42:43], 0, v53
	v_cndmask_b32_e32 v52, v54, v56, vcc
	v_pk_mul_f32 v[60:61], v[58:59], v[50:51]
	v_pk_fma_f32 v[58:59], v[58:59], v[50:51], v[50:51] neg_lo:[1,0,0] neg_hi:[1,0,0]
	v_cmp_gt_f32_e64 s[44:45], 0, v50
	v_cmp_gt_f32_e64 s[46:47], 0, v51
	v_cndmask_b32_e64 v53, v55, v57, s[42:43]
	v_mov_b32_e32 v54, v38
	v_mov_b32_e32 v55, v48
	v_mov_b32_e32 v56, v44
	v_mov_b32_e32 v57, v52
	v_cndmask_b32_e64 v51, v59, v61, s[46:47]
	v_cndmask_b32_e64 v50, v58, v60, s[44:45]
	v_pk_add_f32 v[60:61], v[54:55], v[56:57]
	v_mov_b32_e32 v11, v131
	v_add_f32_e32 v9, v60, v61
	v_mov_b32_e32 v54, v39
	v_mov_b32_e32 v55, v49
	v_add_f32_dpp v9, v9, v9 quad_perm:[1,0,3,2] row_mask:0xf bank_mask:0xf bound_ctrl:1
	v_mov_b32_e32 v56, v45
	v_mov_b32_e32 v57, v53
	v_add_f32_dpp v9, v9, v9 quad_perm:[2,3,0,1] row_mask:0xf bank_mask:0xf bound_ctrl:1
	v_pk_add_f32 v[58:59], v[54:55], v[56:57]
	v_mov_b32_e32 v54, v40
	v_add_f32_dpp v9, v9, v9 row_half_mirror row_mask:0xf bank_mask:0xf bound_ctrl:1
	v_mov_b32_e32 v55, v46
	v_mov_b32_e32 v56, v42
	v_add_f32_dpp v9, v9, v9 row_mirror row_mask:0xf bank_mask:0xf bound_ctrl:1
	v_mov_b32_e32 v57, v50
	v_pk_add_f32 v[56:57], v[54:55], v[56:57]
	v_mov_b32_dpp v11, v9 row_bcast:15 row_mask:0xa bank_mask:0xf
	v_add_f32_e32 v9, v9, v11
	v_mov_b32_e32 v54, v41
	v_mov_b32_e32 v55, v47
	v_add_f32_dpp v9, v9, v9 row_bcast:31 row_mask:0xc bank_mask:0xf
	s_nop 0
	v_readlane_b32 s6, v9, 63
	v_add_f32_e32 v9, v58, v59
	v_mov_b32_e32 v62, v43
	v_mov_b32_e32 v63, v51
	v_add_f32_dpp v9, v9, v9 quad_perm:[1,0,3,2] row_mask:0xf bank_mask:0xf bound_ctrl:1
	v_pk_add_f32 v[54:55], v[54:55], v[62:63]
	s_xor_b32 s6, s6, 0x80000000
	v_add_f32_dpp v9, v9, v9 quad_perm:[2,3,0,1] row_mask:0xf bank_mask:0xf bound_ctrl:1
	v_cvt_pk_bf16_f32 v63, v34, v35
	v_cvt_pk_bf16_f32 v62, v36, v37
	v_add_f32_dpp v9, v9, v9 row_half_mirror row_mask:0xf bank_mask:0xf bound_ctrl:1
	s_nop 1
	v_add_f32_dpp v9, v9, v9 row_mirror row_mask:0xf bank_mask:0xf bound_ctrl:1
	s_nop 1
	v_add_f32_dpp v9, v9, v9 row_bcast:15 row_mask:0xa bank_mask:0xf
	s_nop 1
	v_add_f32_dpp v9, v9, v9 row_bcast:31 row_mask:0xc bank_mask:0xf
	s_nop 0
	v_readlane_b32 s7, v9, 63
	v_add_f32_e32 v9, v56, v57
	s_xor_b32 s7, s7, 0x80000000
	v_pk_fma_f32 v[56:57], s[6:7], v[20:21], v[44:45] op_sel_hi:[1,0,1]
	v_add_f32_dpp v9, v9, v9 quad_perm:[1,0,3,2] row_mask:0xf bank_mask:0xf bound_ctrl:1
	v_pk_fma_f32 v[60:61], s[6:7], v[20:21], v[38:39] op_sel_hi:[1,0,1]
	v_pk_fma_f32 v[44:45], s[6:7], v[20:21], v[48:49] op_sel_hi:[1,0,1]
	v_add_f32_dpp v9, v9, v9 quad_perm:[2,3,0,1] row_mask:0xf bank_mask:0xf bound_ctrl:1
	v_mov_b32_e32 v48, v56
	s_nop 0
	v_add_f32_dpp v9, v9, v9 row_half_mirror row_mask:0xf bank_mask:0xf bound_ctrl:1
	s_nop 1
	v_add_f32_dpp v9, v9, v9 row_mirror row_mask:0xf bank_mask:0xf bound_ctrl:1
	s_nop 1
	v_add_f32_dpp v9, v9, v9 row_bcast:15 row_mask:0xa bank_mask:0xf
	s_nop 1
	v_add_f32_dpp v9, v9, v9 row_bcast:31 row_mask:0xc bank_mask:0xf
	s_nop 0
	v_readlane_b32 s8, v9, 63
	v_add_f32_e32 v9, v54, v55
	s_xor_b32 s8, s8, 0x80000000
	s_nop 0
	v_add_f32_dpp v9, v9, v9 quad_perm:[1,0,3,2] row_mask:0xf bank_mask:0xf bound_ctrl:1
	s_nop 1
	v_add_f32_dpp v9, v9, v9 quad_perm:[2,3,0,1] row_mask:0xf bank_mask:0xf bound_ctrl:1
	s_nop 1
	v_add_f32_dpp v9, v9, v9 row_half_mirror row_mask:0xf bank_mask:0xf bound_ctrl:1
	s_nop 1
	v_add_f32_dpp v9, v9, v9 row_mirror row_mask:0xf bank_mask:0xf bound_ctrl:1
	s_nop 1
	v_add_f32_dpp v9, v9, v9 row_bcast:15 row_mask:0xa bank_mask:0xf
	s_nop 1
	v_add_f32_dpp v9, v9, v9 row_bcast:31 row_mask:0xc bank_mask:0xf
	v_mov_b32_e32 v11, v131
	v_readlane_b32 s9, v9, 63
	s_xor_b32 s9, s9, 0x80000000
	s_nop 0
	v_pk_fma_f32 v[58:59], s[8:9], v[20:21], v[40:41] op_sel_hi:[1,0,1]
	v_pk_fma_f32 v[40:41], s[6:7], v[20:21], v[52:53] op_sel_hi:[1,0,1]
	v_pk_fma_f32 v[54:55], s[8:9], v[20:21], v[42:43] op_sel_hi:[1,0,1]
	v_mov_b32_e32 v49, v40
	v_pk_fma_f32 v[42:43], s[8:9], v[20:21], v[46:47] op_sel_hi:[1,0,1]
	v_mov_b32_e32 v46, v60
	v_mov_b32_e32 v47, v44
	v_pk_mul_f32 v[48:49], v[48:49], v[48:49]
	v_pk_fma_f32 v[38:39], s[8:9], v[20:21], v[50:51] op_sel_hi:[1,0,1]
	v_pk_fma_f32 v[46:47], v[46:47], v[46:47], v[48:49]
	v_mov_b32_e32 v50, v57
	v_add_f32_e32 v9, v46, v47
	v_mov_b32_e32 v51, v41
	v_mov_b32_e32 v48, v61
	v_add_f32_dpp v9, v9, v9 quad_perm:[1,0,3,2] row_mask:0xf bank_mask:0xf bound_ctrl:1
	v_mov_b32_e32 v49, v45
	v_pk_mul_f32 v[50:51], v[50:51], v[50:51]
	v_add_f32_dpp v9, v9, v9 quad_perm:[2,3,0,1] row_mask:0xf bank_mask:0xf bound_ctrl:1
	v_pk_fma_f32 v[48:49], v[48:49], v[48:49], v[50:51]
	v_mov_b32_e32 v50, v54
	v_add_f32_dpp v9, v9, v9 row_half_mirror row_mask:0xf bank_mask:0xf bound_ctrl:1
	v_mov_b32_e32 v51, v38
	v_pk_mul_f32 v[50:51], v[50:51], v[50:51]
	v_add_f32_dpp v9, v9, v9 row_mirror row_mask:0xf bank_mask:0xf bound_ctrl:1
	s_nop 1
	v_mov_b32_dpp v11, v9 row_bcast:15 row_mask:0xa bank_mask:0xf
	v_add_f32_e32 v9, v9, v11
	s_nop 1
	v_add_f32_dpp v9, v9, v9 row_bcast:31 row_mask:0xc bank_mask:0xf
	v_mov_b32_e32 v11, v131
	v_readlane_b32 s6, v9, 63
	s_nop 1
	v_fma_f32 v9, s6, v235, v225
	v_rsq_f32_e32 v46, v9
	v_add_f32_e32 v9, v48, v49
	v_mov_b32_e32 v48, v58
	v_mov_b32_e32 v49, v42
	v_add_f32_dpp v9, v9, v9 quad_perm:[1,0,3,2] row_mask:0xf bank_mask:0xf bound_ctrl:1
	v_pk_fma_f32 v[48:49], v[48:49], v[48:49], v[50:51]
	v_mov_b32_e32 v50, v55
	v_add_f32_dpp v9, v9, v9 quad_perm:[2,3,0,1] row_mask:0xf bank_mask:0xf bound_ctrl:1
	v_mov_b32_e32 v51, v39
	v_pk_mul_f32 v[50:51], v[50:51], v[50:51]
	v_add_f32_dpp v9, v9, v9 row_half_mirror row_mask:0xf bank_mask:0xf bound_ctrl:1
	s_nop 1
	v_add_f32_dpp v9, v9, v9 row_mirror row_mask:0xf bank_mask:0xf bound_ctrl:1
	s_nop 1
	v_mov_b32_dpp v11, v9 row_bcast:15 row_mask:0xa bank_mask:0xf
	v_add_f32_e32 v9, v9, v11
	s_nop 1
	v_add_f32_dpp v9, v9, v9 row_bcast:31 row_mask:0xc bank_mask:0xf
	v_mov_b32_e32 v11, v131
	v_readlane_b32 s6, v9, 63
	s_nop 1
	v_fma_f32 v9, s6, v235, v225
	v_rsq_f32_e32 v47, v9
	v_add_f32_e32 v9, v48, v49
	v_mov_b32_e32 v48, v59
	v_mov_b32_e32 v49, v43
	v_add_f32_dpp v9, v9, v9 quad_perm:[1,0,3,2] row_mask:0xf bank_mask:0xf bound_ctrl:1
	v_pk_fma_f32 v[48:49], v[48:49], v[48:49], v[50:51]
	v_pk_mul_f32 v[34:35], v[56:57], v[46:47]
	v_add_f32_dpp v9, v9, v9 quad_perm:[2,3,0,1] row_mask:0xf bank_mask:0xf bound_ctrl:1
	s_nop 1
	v_add_f32_dpp v9, v9, v9 row_half_mirror row_mask:0xf bank_mask:0xf bound_ctrl:1
	s_nop 1
	v_add_f32_dpp v9, v9, v9 row_mirror row_mask:0xf bank_mask:0xf bound_ctrl:1
	s_nop 1
	v_mov_b32_dpp v11, v9 row_bcast:15 row_mask:0xa bank_mask:0xf
	v_add_f32_e32 v9, v9, v11
	s_nop 1
	v_add_f32_dpp v9, v9, v9 row_bcast:31 row_mask:0xc bank_mask:0xf
	v_mov_b32_e32 v11, v131
	v_readlane_b32 s6, v9, 63
	s_nop 1
	v_fma_f32 v9, s6, v235, v225
	v_rsq_f32_e32 v66, v9
	v_add_f32_e32 v9, v48, v49
	v_pk_mul_f32 v[48:49], v[60:61], v[46:47]
	s_nop 0
	v_add_f32_dpp v9, v9, v9 quad_perm:[1,0,3,2] row_mask:0xf bank_mask:0xf bound_ctrl:1
	v_pk_fma_f32 v[48:49], v[14:15], v[48:49], v[16:17] op_sel_hi:[0,1,0]
	v_cvt_pk_bf16_f32 v64, v48, v49
	v_add_f32_dpp v9, v9, v9 quad_perm:[2,3,0,1] row_mask:0xf bank_mask:0xf bound_ctrl:1
	s_nop 1
	v_add_f32_dpp v9, v9, v9 row_half_mirror row_mask:0xf bank_mask:0xf bound_ctrl:1
	s_nop 1
	v_add_f32_dpp v9, v9, v9 row_mirror row_mask:0xf bank_mask:0xf bound_ctrl:1
	s_nop 1
	v_mov_b32_dpp v11, v9 row_bcast:15 row_mask:0xa bank_mask:0xf
	v_add_f32_e32 v9, v9, v11
	s_nop 1
	v_add_f32_dpp v9, v9, v9 row_bcast:31 row_mask:0xc bank_mask:0xf
	s_nop 0
	v_readlane_b32 s6, v9, 63
	s_nop 1
	v_fma_f32 v9, s6, v235, v225
	v_rsq_f32_e32 v67, v9
	s_nop 0
	v_pk_mul_f32 v[50:51], v[58:59], v[66:67]
	v_pk_fma_f32 v[50:51], v[14:15], v[50:51], v[16:17] op_sel_hi:[0,1,0]
	v_cvt_pk_bf16_f32 v65, v50, v51
	global_load_ushort v58, v7, s[52:53] offset:512
	global_load_ushort v59, v7, s[64:65] offset:512
	global_load_ushort v60, v7, s[68:69] offset:512
	global_load_ushort v61, v7, s[72:73] offset:512
	global_load_ushort v50, v7, s[52:53] offset:640
	global_load_ushort v51, v7, s[64:65] offset:640
	global_load_ushort v52, v7, s[68:69] offset:640
	global_load_ushort v53, v7, s[72:73] offset:640
	global_load_ushort v15, v7, s[52:53] offset:768
	global_load_ushort v17, v7, s[64:65] offset:768
	global_load_ushort v48, v7, s[68:69] offset:768
	global_load_ushort v49, v7, s[72:73] offset:768
	global_load_ushort v9, v7, s[52:53] offset:896
	global_load_ushort v11, v7, s[64:65] offset:896
	global_load_ushort v13, v7, s[68:69] offset:896
	s_nop 0
	global_load_ushort v7, v7, s[72:73] offset:896
	v_pk_mul_f32 v[36:37], v[54:55], v[66:67]
	ds_write_b128 v5, v[62:65]
	s_waitcnt vmcnt(1)
	v_pk_fma_f32 v[36:37], v[10:11], v[36:37], v[12:13] op_sel_hi:[0,1,0]
	v_pk_fma_f32 v[34:35], v[10:11], v[34:35], v[12:13] op_sel_hi:[0,1,0]
	v_cvt_pk_bf16_f32 v37, v36, v37
	v_cvt_pk_bf16_f32 v36, v34, v35
	v_cvt_pk_bf16_f32 v35, v30, v31
	v_cvt_pk_bf16_f32 v34, v32, v33
	v_pk_mul_f32 v[30:31], v[44:45], v[46:47]
	v_pk_mul_f32 v[32:33], v[42:43], v[66:67]
	s_waitcnt vmcnt(0)
	v_pk_fma_f32 v[30:31], v[6:7], v[30:31], v[8:9] op_sel_hi:[0,1,0]
	v_pk_fma_f32 v[32:33], v[6:7], v[32:33], v[8:9] op_sel_hi:[0,1,0]
	v_cvt_pk_bf16_f32 v33, v32, v33
	v_cvt_pk_bf16_f32 v32, v30, v31
	v_cvt_pk_bf16_f32 v31, v26, v27
	v_cvt_pk_bf16_f32 v30, v28, v29
	v_pk_mul_f32 v[26:27], v[40:41], v[46:47]
	v_pk_mul_f32 v[28:29], v[38:39], v[66:67]
	v_pk_fma_f32 v[26:27], v[2:3], v[26:27], v[4:5] op_sel_hi:[0,1,0]
	v_pk_fma_f32 v[28:29], v[2:3], v[28:29], v[4:5] op_sel_hi:[0,1,0]
	v_cvt_pk_bf16_f32 v29, v28, v29
	v_cvt_pk_bf16_f32 v28, v26, v27
	v_cvt_pk_bf16_f32 v27, v22, v23
	v_cvt_pk_bf16_f32 v26, v24, v25
	v_lshlrev_b32_e32 v24, 16, v68
	ds_write_b128 v5, v[26:29] offset:52224
	v_lshlrev_b32_e32 v22, 16, v70
	v_mul_f32_e32 v27, v24, v24
	ds_write_b128 v5, v[30:33] offset:34816
	v_lshlrev_b32_e32 v25, 16, v69
	v_mul_f32_e32 v27, 0xbf38aa3b, v27
	v_mul_f32_e32 v31, v22, v22
	v_lshlrev_b32_e32 v23, 16, v71
	v_fma_f32 v26, |v24|, s92, 1.0
	v_exp_f32_e32 v28, v27
	v_fma_f32 v27, |v25|, s92, 1.0
	v_mul_f32_e32 v31, 0xbf38aa3b, v31
	v_rcp_f32_e32 v26, v26
	v_rcp_f32_e32 v27, v27
	v_fma_f32 v30, |v22|, s92, 1.0
	v_exp_f32_e32 v32, v31
	v_fma_f32 v31, |v23|, s92, 1.0
	v_rcp_f32_e32 v30, v30
	v_rcp_f32_e32 v31, v31
	v_mul_f32_e32 v29, v25, v25
	ds_write_b128 v5, v[34:37] offset:17408
	v_mul_f32_e32 v29, 0xbf38aa3b, v29
	v_pk_fma_f32 v[34:35], v[26:27], s[12:13], v[18:19] op_sel_hi:[1,0,0]
	v_mul_f32_e32 v33, v23, v23
	v_exp_f32_e32 v29, v29
	v_pk_fma_f32 v[36:37], v[30:31], s[12:13], v[18:19] op_sel_hi:[1,0,0]
	v_pk_fma_f32 v[34:35], v[26:27], v[34:35], s[14:15] op_sel_hi:[1,1,0]
	v_mul_f32_e32 v33, 0xbf38aa3b, v33
	v_pk_fma_f32 v[36:37], v[30:31], v[36:37], s[14:15] op_sel_hi:[1,1,0]
	v_pk_fma_f32 v[34:35], v[26:27], v[34:35], s[16:17] op_sel_hi:[1,1,0]
	v_exp_f32_e32 v33, v33
	v_pk_fma_f32 v[36:37], v[30:31], v[36:37], s[16:17] op_sel_hi:[1,1,0]
	v_pk_fma_f32 v[34:35], v[26:27], v[34:35], s[18:19] op_sel_hi:[1,1,0]
	v_pk_fma_f32 v[36:37], v[30:31], v[36:37], s[18:19] op_sel_hi:[1,1,0]
	v_pk_mul_f32 v[26:27], v[26:27], v[34:35]
	v_pk_mul_f32 v[30:31], v[30:31], v[36:37]
	v_pk_mul_f32 v[26:27], v[28:29], v[26:27]
	v_pk_mul_f32 v[30:31], v[32:33], v[30:31]
	v_pk_mul_f32 v[28:29], v[26:27], v[24:25]
	v_pk_fma_f32 v[26:27], v[26:27], v[24:25], v[24:25] neg_lo:[1,0,0] neg_hi:[1,0,0]
	v_cmp_gt_f32_e32 vcc, 0, v24
	v_pk_mul_f32 v[32:33], v[30:31], v[22:23]
	v_pk_fma_f32 v[30:31], v[30:31], v[22:23], v[22:23] neg_lo:[1,0,0] neg_hi:[1,0,0]
	v_cmp_gt_f32_e64 s[44:45], 0, v22
	v_cmp_gt_f32_e64 s[46:47], 0, v23
	v_cndmask_b32_e32 v22, v26, v28, vcc
	v_lshlrev_b32_e32 v28, 16, v72
	v_cmp_gt_f32_e64 s[42:43], 0, v25
	v_cndmask_b32_e64 v25, v31, v33, s[46:47]
	v_lshlrev_b32_e32 v26, 16, v74
	v_mul_f32_e32 v31, v28, v28
	v_cndmask_b32_e64 v23, v27, v29, s[42:43]
	v_lshlrev_b32_e32 v29, 16, v73
	v_mul_f32_e32 v31, 0xbf38aa3b, v31
	v_mul_f32_e32 v35, v26, v26
	v_cndmask_b32_e64 v24, v30, v32, s[44:45]
	v_lshlrev_b32_e32 v27, 16, v75
	v_fma_f32 v30, |v28|, s92, 1.0
	v_exp_f32_e32 v32, v31
	v_fma_f32 v31, |v29|, s92, 1.0
	v_mul_f32_e32 v35, 0xbf38aa3b, v35
	v_rcp_f32_e32 v30, v30
	v_rcp_f32_e32 v31, v31
	v_fma_f32 v34, |v26|, s92, 1.0
	v_exp_f32_e32 v36, v35
	v_fma_f32 v35, |v27|, s92, 1.0
	v_rcp_f32_e32 v34, v34
	v_rcp_f32_e32 v35, v35
	v_mul_f32_e32 v33, v29, v29
	v_mul_f32_e32 v33, 0xbf38aa3b, v33
	v_pk_fma_f32 v[38:39], v[30:31], s[12:13], v[18:19] op_sel_hi:[1,0,0]
	v_mul_f32_e32 v37, v27, v27
	v_exp_f32_e32 v33, v33
	v_pk_fma_f32 v[40:41], v[34:35], s[12:13], v[18:19] op_sel_hi:[1,0,0]
	v_pk_fma_f32 v[38:39], v[30:31], v[38:39], s[14:15] op_sel_hi:[1,1,0]
	v_mul_f32_e32 v37, 0xbf38aa3b, v37
	v_pk_fma_f32 v[40:41], v[34:35], v[40:41], s[14:15] op_sel_hi:[1,1,0]
	v_pk_fma_f32 v[38:39], v[30:31], v[38:39], s[16:17] op_sel_hi:[1,1,0]
	v_exp_f32_e32 v37, v37
	v_pk_fma_f32 v[40:41], v[34:35], v[40:41], s[16:17] op_sel_hi:[1,1,0]
	v_pk_fma_f32 v[38:39], v[30:31], v[38:39], s[18:19] op_sel_hi:[1,1,0]
	v_pk_fma_f32 v[40:41], v[34:35], v[40:41], s[18:19] op_sel_hi:[1,1,0]
	v_pk_mul_f32 v[30:31], v[30:31], v[38:39]
	v_pk_mul_f32 v[34:35], v[34:35], v[40:41]
	v_pk_mul_f32 v[30:31], v[32:33], v[30:31]
	v_pk_mul_f32 v[34:35], v[36:37], v[34:35]
	v_pk_mul_f32 v[32:33], v[30:31], v[28:29]
	v_pk_fma_f32 v[30:31], v[30:31], v[28:29], v[28:29] neg_lo:[1,0,0] neg_hi:[1,0,0]
	v_cmp_gt_f32_e32 vcc, 0, v28
	v_pk_mul_f32 v[36:37], v[34:35], v[26:27]
	v_pk_fma_f32 v[34:35], v[34:35], v[26:27], v[26:27] neg_lo:[1,0,0] neg_hi:[1,0,0]
	v_cmp_gt_f32_e64 s[46:47], 0, v27
	v_cndmask_b32_e32 v28, v30, v32, vcc
	v_lshlrev_b32_e32 v32, 16, v76
	v_cmp_gt_f32_e64 s[42:43], 0, v29
	v_cndmask_b32_e64 v27, v35, v37, s[46:47]
	v_lshlrev_b32_e32 v30, 16, v78
	v_mul_f32_e32 v35, v32, v32
	v_cmp_gt_f32_e64 s[44:45], 0, v26
	v_cndmask_b32_e64 v29, v31, v33, s[42:43]
	v_lshlrev_b32_e32 v33, 16, v77
	v_mul_f32_e32 v35, 0xbf38aa3b, v35
	v_mul_f32_e32 v39, v30, v30
	v_cndmask_b32_e64 v26, v34, v36, s[44:45]
	v_lshlrev_b32_e32 v31, 16, v79
	v_fma_f32 v34, |v32|, s92, 1.0
	v_exp_f32_e32 v36, v35
	v_fma_f32 v35, |v33|, s92, 1.0
	v_mul_f32_e32 v39, 0xbf38aa3b, v39
	v_rcp_f32_e32 v34, v34
	v_rcp_f32_e32 v35, v35
	v_fma_f32 v38, |v30|, s92, 1.0
	v_exp_f32_e32 v40, v39
	v_fma_f32 v39, |v31|, s92, 1.0
	v_rcp_f32_e32 v38, v38
	v_rcp_f32_e32 v39, v39
	v_mul_f32_e32 v37, v33, v33
	v_mul_f32_e32 v37, 0xbf38aa3b, v37
	v_pk_fma_f32 v[42:43], v[34:35], s[12:13], v[18:19] op_sel_hi:[1,0,0]
	v_mul_f32_e32 v41, v31, v31
	v_exp_f32_e32 v37, v37
	v_pk_fma_f32 v[44:45], v[38:39], s[12:13], v[18:19] op_sel_hi:[1,0,0]
	v_pk_fma_f32 v[42:43], v[34:35], v[42:43], s[14:15] op_sel_hi:[1,1,0]
	v_mul_f32_e32 v41, 0xbf38aa3b, v41
	v_pk_fma_f32 v[44:45], v[38:39], v[44:45], s[14:15] op_sel_hi:[1,1,0]
	v_pk_fma_f32 v[42:43], v[34:35], v[42:43], s[16:17] op_sel_hi:[1,1,0]
	v_exp_f32_e32 v41, v41
	v_pk_fma_f32 v[44:45], v[38:39], v[44:45], s[16:17] op_sel_hi:[1,1,0]
	v_pk_fma_f32 v[42:43], v[34:35], v[42:43], s[18:19] op_sel_hi:[1,1,0]
	v_pk_fma_f32 v[44:45], v[38:39], v[44:45], s[18:19] op_sel_hi:[1,1,0]
	v_pk_mul_f32 v[34:35], v[34:35], v[42:43]
	v_pk_mul_f32 v[38:39], v[38:39], v[44:45]
	v_pk_mul_f32 v[34:35], v[36:37], v[34:35]
	v_pk_mul_f32 v[38:39], v[40:41], v[38:39]
	v_pk_mul_f32 v[36:37], v[34:35], v[32:33]
	v_pk_fma_f32 v[34:35], v[34:35], v[32:33], v[32:33] neg_lo:[1,0,0] neg_hi:[1,0,0]
	v_cmp_gt_f32_e32 vcc, 0, v32
	v_pk_mul_f32 v[40:41], v[38:39], v[30:31]
	v_pk_fma_f32 v[38:39], v[38:39], v[30:31], v[30:31] neg_lo:[1,0,0] neg_hi:[1,0,0]
	v_cmp_gt_f32_e64 s[46:47], 0, v31
	v_cndmask_b32_e32 v32, v34, v36, vcc
	v_lshlrev_b32_e32 v36, 16, v80
	v_cmp_gt_f32_e64 s[42:43], 0, v33
	v_cndmask_b32_e64 v31, v39, v41, s[46:47]
	v_mul_f32_e32 v39, v36, v36
	v_cmp_gt_f32_e64 s[44:45], 0, v30
	v_cndmask_b32_e64 v33, v35, v37, s[42:43]
	v_lshlrev_b32_e32 v34, 16, v82
	v_lshlrev_b32_e32 v37, 16, v81
	v_mul_f32_e32 v39, 0xbf38aa3b, v39
	v_cndmask_b32_e64 v30, v38, v40, s[44:45]
	v_fma_f32 v38, |v36|, s92, 1.0
	v_exp_f32_e32 v40, v39
	v_fma_f32 v39, |v37|, s92, 1.0
	v_mul_f32_e32 v43, v34, v34
	v_lshlrev_b32_e32 v35, 16, v83
	v_rcp_f32_e32 v38, v38
	v_rcp_f32_e32 v39, v39
	v_mul_f32_e32 v43, 0xbf38aa3b, v43
	v_fma_f32 v42, |v34|, s92, 1.0
	v_exp_f32_e32 v44, v43
	v_fma_f32 v43, |v35|, s92, 1.0
	v_rcp_f32_e32 v42, v42
	v_rcp_f32_e32 v43, v43
	v_mul_f32_e32 v41, v37, v37
	v_mul_f32_e32 v41, 0xbf38aa3b, v41
	v_pk_fma_f32 v[46:47], v[38:39], s[12:13], v[18:19] op_sel_hi:[1,0,0]
	v_exp_f32_e32 v41, v41
	v_pk_fma_f32 v[46:47], v[38:39], v[46:47], s[14:15] op_sel_hi:[1,1,0]
	v_mul_f32_e32 v45, v35, v35
	v_pk_fma_f32 v[54:55], v[42:43], s[12:13], v[18:19] op_sel_hi:[1,0,0]
	v_pk_fma_f32 v[46:47], v[38:39], v[46:47], s[16:17] op_sel_hi:[1,1,0]
	v_mul_f32_e32 v45, 0xbf38aa3b, v45
	v_pk_fma_f32 v[54:55], v[42:43], v[54:55], s[14:15] op_sel_hi:[1,1,0]
	v_pk_fma_f32 v[46:47], v[38:39], v[46:47], s[18:19] op_sel_hi:[1,1,0]
	v_exp_f32_e32 v45, v45
	v_pk_fma_f32 v[54:55], v[42:43], v[54:55], s[16:17] op_sel_hi:[1,1,0]
	v_pk_mul_f32 v[38:39], v[38:39], v[46:47]
	v_pk_fma_f32 v[54:55], v[42:43], v[54:55], s[18:19] op_sel_hi:[1,1,0]
	v_pk_mul_f32 v[38:39], v[40:41], v[38:39]
	v_pk_mul_f32 v[42:43], v[42:43], v[54:55]
	v_pk_mul_f32 v[40:41], v[38:39], v[36:37]
	v_pk_fma_f32 v[38:39], v[38:39], v[36:37], v[36:37] neg_lo:[1,0,0] neg_hi:[1,0,0]
	v_cmp_gt_f32_e32 vcc, 0, v36
	v_pk_mul_f32 v[42:43], v[44:45], v[42:43]
	v_cmp_gt_f32_e64 s[42:43], 0, v37
	v_cndmask_b32_e32 v36, v38, v40, vcc
	v_pk_mul_f32 v[44:45], v[42:43], v[34:35]
	v_pk_fma_f32 v[42:43], v[42:43], v[34:35], v[34:35] neg_lo:[1,0,0] neg_hi:[1,0,0]
	v_cmp_gt_f32_e64 s[44:45], 0, v34
	v_cmp_gt_f32_e64 s[46:47], 0, v35
	v_cndmask_b32_e64 v37, v39, v41, s[42:43]
	v_mov_b32_e32 v38, v22
	v_mov_b32_e32 v39, v32
	v_mov_b32_e32 v40, v28
	v_mov_b32_e32 v41, v36
	v_cndmask_b32_e64 v35, v43, v45, s[46:47]
	v_cndmask_b32_e64 v34, v42, v44, s[44:45]
	v_pk_add_f32 v[44:45], v[38:39], v[40:41]
	v_mov_b32_e32 v38, v23
	v_mov_b32_e32 v39, v33
	v_mov_b32_e32 v40, v29
	v_mov_b32_e32 v41, v37
	v_pk_add_f32 v[42:43], v[38:39], v[40:41]
	v_mov_b32_e32 v38, v24
	v_mov_b32_e32 v39, v30
	v_mov_b32_e32 v40, v26
	v_mov_b32_e32 v41, v34
	v_pk_add_f32 v[40:41], v[38:39], v[40:41]
	v_mov_b32_e32 v38, v25
	v_mov_b32_e32 v39, v31
	v_mov_b32_e32 v46, v27
	v_mov_b32_e32 v47, v35
	v_add_f32_e32 v44, v44, v45
	v_add_f32_e32 v42, v42, v43
	v_pk_add_f32 v[38:39], v[38:39], v[46:47]
	v_add_f32_dpp v44, v44, v44 quad_perm:[1,0,3,2] row_mask:0xf bank_mask:0xf bound_ctrl:1
	v_add_f32_dpp v42, v42, v42 quad_perm:[1,0,3,2] row_mask:0xf bank_mask:0xf bound_ctrl:1
	v_add_f32_e32 v40, v40, v41
	v_add_f32_dpp v44, v44, v44 quad_perm:[2,3,0,1] row_mask:0xf bank_mask:0xf bound_ctrl:1
	v_add_f32_dpp v42, v42, v42 quad_perm:[2,3,0,1] row_mask:0xf bank_mask:0xf bound_ctrl:1
	v_add_f32_e32 v38, v38, v39
	v_add_f32_dpp v44, v44, v44 row_half_mirror row_mask:0xf bank_mask:0xf bound_ctrl:1
	v_add_f32_dpp v42, v42, v42 row_half_mirror row_mask:0xf bank_mask:0xf bound_ctrl:1
	v_add_f32_dpp v40, v40, v40 quad_perm:[1,0,3,2] row_mask:0xf bank_mask:0xf bound_ctrl:1
	v_add_f32_dpp v38, v38, v38 quad_perm:[1,0,3,2] row_mask:0xf bank_mask:0xf bound_ctrl:1
	v_add_f32_dpp v44, v44, v44 row_mirror row_mask:0xf bank_mask:0xf bound_ctrl:1
	v_add_f32_dpp v42, v42, v42 row_mirror row_mask:0xf bank_mask:0xf bound_ctrl:1
	v_add_f32_dpp v40, v40, v40 quad_perm:[2,3,0,1] row_mask:0xf bank_mask:0xf bound_ctrl:1
	v_add_f32_dpp v38, v38, v38 quad_perm:[2,3,0,1] row_mask:0xf bank_mask:0xf bound_ctrl:1
	v_add_f32_dpp v44, v44, v44 row_bcast:15 row_mask:0xa bank_mask:0xf
	v_add_f32_dpp v42, v42, v42 row_bcast:15 row_mask:0xa bank_mask:0xf
	v_add_f32_dpp v40, v40, v40 row_half_mirror row_mask:0xf bank_mask:0xf bound_ctrl:1
	v_add_f32_dpp v38, v38, v38 row_half_mirror row_mask:0xf bank_mask:0xf bound_ctrl:1
	s_nop 0
	v_add_f32_dpp v40, v40, v40 row_mirror row_mask:0xf bank_mask:0xf bound_ctrl:1
	s_nop 0
	v_add_f32_dpp v38, v38, v38 row_mirror row_mask:0xf bank_mask:0xf bound_ctrl:1
	v_add_f32_dpp v44, v44, v44 row_bcast:31 row_mask:0xc bank_mask:0xf
	v_add_f32_dpp v42, v42, v42 row_bcast:31 row_mask:0xc bank_mask:0xf
	v_add_f32_dpp v40, v40, v40 row_bcast:15 row_mask:0xa bank_mask:0xf
	v_add_f32_dpp v38, v38, v38 row_bcast:15 row_mask:0xa bank_mask:0xf
	v_readlane_b32 s6, v44, 63
	v_readlane_b32 s7, v42, 63
	v_add_f32_dpp v40, v40, v40 row_bcast:31 row_mask:0xc bank_mask:0xf
	v_add_f32_dpp v38, v38, v38 row_bcast:31 row_mask:0xc bank_mask:0xf
	s_xor_b32 s7, s7, 0x80000000
	s_xor_b32 s6, s6, 0x80000000
	v_readlane_b32 s8, v40, 63
	v_readlane_b32 s9, v38, 63
	v_pk_fma_f32 v[42:43], s[6:7], v[20:21], v[28:29] op_sel_hi:[1,0,1]
	v_pk_fma_f32 v[38:39], s[6:7], v[20:21], v[36:37] op_sel_hi:[1,0,1]
	s_xor_b32 s9, s9, 0x80000000
	s_xor_b32 s8, s8, 0x80000000
	v_pk_fma_f32 v[44:45], s[6:7], v[20:21], v[22:23] op_sel_hi:[1,0,1]
	v_pk_fma_f32 v[28:29], s[6:7], v[20:21], v[32:33] op_sel_hi:[1,0,1]
	v_mov_b32_e32 v32, v42
	v_mov_b32_e32 v33, v38
	v_pk_fma_f32 v[40:41], s[8:9], v[20:21], v[24:25] op_sel_hi:[1,0,1]
	v_pk_fma_f32 v[24:25], s[8:9], v[20:21], v[30:31] op_sel_hi:[1,0,1]
	v_mov_b32_e32 v30, v44
	v_mov_b32_e32 v31, v28
	v_pk_mul_f32 v[32:33], v[32:33], v[32:33]
	v_pk_fma_f32 v[26:27], s[8:9], v[20:21], v[26:27] op_sel_hi:[1,0,1]
	v_pk_fma_f32 v[30:31], v[30:31], v[30:31], v[32:33]
	v_mov_b32_e32 v32, v43
	v_add_f32_e32 v30, v30, v31
	v_mov_b32_e32 v33, v39
	s_nop 0
	v_add_f32_dpp v30, v30, v30 quad_perm:[1,0,3,2] row_mask:0xf bank_mask:0xf bound_ctrl:1
	v_pk_mul_f32 v[32:33], v[32:33], v[32:33]
	v_pk_fma_f32 v[22:23], s[8:9], v[20:21], v[34:35] op_sel_hi:[1,0,1]
	v_add_f32_dpp v30, v30, v30 quad_perm:[2,3,0,1] row_mask:0xf bank_mask:0xf bound_ctrl:1
	s_nop 1
	v_add_f32_dpp v30, v30, v30 row_half_mirror row_mask:0xf bank_mask:0xf bound_ctrl:1
	s_nop 1
	v_add_f32_dpp v30, v30, v30 row_mirror row_mask:0xf bank_mask:0xf bound_ctrl:1
	s_nop 1
	v_add_f32_dpp v30, v30, v30 row_bcast:15 row_mask:0xa bank_mask:0xf
	s_nop 1
	v_add_f32_dpp v30, v30, v30 row_bcast:31 row_mask:0xc bank_mask:0xf
	v_mov_b32_e32 v31, v29
	v_readlane_b32 s6, v30, 63
	s_nop 1
	v_fma_f32 v30, s6, v235, v225
	v_rsq_f32_e32 v46, v30
	v_mov_b32_e32 v30, v45
	v_pk_fma_f32 v[30:31], v[30:31], v[30:31], v[32:33]
	v_mov_b32_e32 v32, v26
	v_add_f32_e32 v30, v30, v31
	v_mov_b32_e32 v33, v22
	s_nop 0
	v_add_f32_dpp v30, v30, v30 quad_perm:[1,0,3,2] row_mask:0xf bank_mask:0xf bound_ctrl:1
	v_pk_mul_f32 v[32:33], v[32:33], v[32:33]
	s_nop 0
	v_add_f32_dpp v30, v30, v30 quad_perm:[2,3,0,1] row_mask:0xf bank_mask:0xf bound_ctrl:1
	s_nop 1
	v_add_f32_dpp v30, v30, v30 row_half_mirror row_mask:0xf bank_mask:0xf bound_ctrl:1
	s_nop 1
	v_add_f32_dpp v30, v30, v30 row_mirror row_mask:0xf bank_mask:0xf bound_ctrl:1
	s_nop 1
	v_add_f32_dpp v30, v30, v30 row_bcast:15 row_mask:0xa bank_mask:0xf
	s_nop 1
	v_add_f32_dpp v30, v30, v30 row_bcast:31 row_mask:0xc bank_mask:0xf
	v_mov_b32_e32 v31, v24
	v_readlane_b32 s6, v30, 63
	s_nop 1
	v_fma_f32 v30, s6, v235, v225
	v_rsq_f32_e32 v47, v30
	v_mov_b32_e32 v30, v40
	v_pk_fma_f32 v[30:31], v[30:31], v[30:31], v[32:33]
	v_mov_b32_e32 v32, v27
	v_add_f32_e32 v30, v30, v31
	v_mov_b32_e32 v33, v23
	s_nop 0
	v_add_f32_dpp v30, v30, v30 quad_perm:[1,0,3,2] row_mask:0xf bank_mask:0xf bound_ctrl:1
	v_pk_mul_f32 v[32:33], v[32:33], v[32:33]
	v_pk_mul_f32 v[28:29], v[28:29], v[46:47]
	v_add_f32_dpp v30, v30, v30 quad_perm:[2,3,0,1] row_mask:0xf bank_mask:0xf bound_ctrl:1
	v_pk_fma_f32 v[28:29], v[6:7], v[28:29], v[8:9] op_sel_hi:[0,1,0]
	s_nop 0
	v_add_f32_dpp v30, v30, v30 row_half_mirror row_mask:0xf bank_mask:0xf bound_ctrl:1
	s_nop 1
	v_add_f32_dpp v30, v30, v30 row_mirror row_mask:0xf bank_mask:0xf bound_ctrl:1
	s_nop 1
	v_add_f32_dpp v30, v30, v30 row_bcast:15 row_mask:0xa bank_mask:0xf
	s_nop 1
	v_add_f32_dpp v30, v30, v30 row_bcast:31 row_mask:0xc bank_mask:0xf
	v_mov_b32_e32 v31, v25
	v_readlane_b32 s6, v30, 63
	s_nop 1
	v_fma_f32 v30, s6, v235, v225
	v_rsq_f32_e32 v54, v30
	v_mov_b32_e32 v30, v41
	v_pk_fma_f32 v[30:31], v[30:31], v[30:31], v[32:33]
	v_add_f32_e32 v30, v30, v31
	s_nop 0
	s_nop 0
	v_add_f32_dpp v30, v30, v30 quad_perm:[1,0,3,2] row_mask:0xf bank_mask:0xf bound_ctrl:1
	s_nop 1
	v_add_f32_dpp v30, v30, v30 quad_perm:[2,3,0,1] row_mask:0xf bank_mask:0xf bound_ctrl:1
	s_nop 1
	v_add_f32_dpp v30, v30, v30 row_half_mirror row_mask:0xf bank_mask:0xf bound_ctrl:1
	s_nop 1
	v_add_f32_dpp v30, v30, v30 row_mirror row_mask:0xf bank_mask:0xf bound_ctrl:1
	s_nop 1
	v_add_f32_dpp v30, v30, v30 row_bcast:15 row_mask:0xa bank_mask:0xf
	s_nop 1
	v_add_f32_dpp v30, v30, v30 row_bcast:31 row_mask:0xc bank_mask:0xf
	s_nop 0
	v_readlane_b32 s6, v30, 63
	s_nop 1
	v_fma_f32 v30, s6, v235, v225
	v_rsq_f32_e32 v55, v30
	v_pk_mul_f32 v[30:31], v[44:45], v[46:47]
	v_pk_mul_f32 v[32:33], v[40:41], v[54:55]
	v_pk_mul_f32 v[26:27], v[26:27], v[54:55]
	v_pk_mul_f32 v[24:25], v[24:25], v[54:55]
	v_lshlrev_b32_e32 v40, 16, v58
	v_pk_fma_f32 v[34:35], v[14:15], v[32:33], v[16:17] op_sel_hi:[0,1,0]
	v_pk_fma_f32 v[36:37], v[14:15], v[30:31], v[16:17] op_sel_hi:[0,1,0]
	v_pk_mul_f32 v[32:33], v[42:43], v[46:47]
	v_pk_fma_f32 v[30:31], v[10:11], v[26:27], v[12:13] op_sel_hi:[0,1,0]
	v_pk_fma_f32 v[26:27], v[6:7], v[24:25], v[8:9] op_sel_hi:[0,1,0]
	v_pk_mul_f32 v[24:25], v[38:39], v[46:47]
	v_lshlrev_b32_e32 v38, 16, v60
	v_mul_f32_e32 v43, v40, v40
	v_lshlrev_b32_e32 v41, 16, v59
	v_mul_f32_e32 v43, 0xbf38aa3b, v43
	v_mul_f32_e32 v47, v38, v38
	v_lshlrev_b32_e32 v39, 16, v61
	v_fma_f32 v42, |v40|, s92, 1.0
	v_exp_f32_e32 v44, v43
	v_fma_f32 v43, |v41|, s92, 1.0
	v_mul_f32_e32 v47, 0xbf38aa3b, v47
	v_pk_mul_f32 v[22:23], v[22:23], v[54:55]
	v_rcp_f32_e32 v42, v42
	v_rcp_f32_e32 v43, v43
	v_fma_f32 v46, |v38|, s92, 1.0
	v_exp_f32_e32 v54, v47
	v_fma_f32 v47, |v39|, s92, 1.0
	v_rcp_f32_e32 v46, v46
	v_rcp_f32_e32 v47, v47
	v_mul_f32_e32 v45, v41, v41
	v_mul_f32_e32 v45, 0xbf38aa3b, v45
	v_pk_fma_f32 v[56:57], v[42:43], s[12:13], v[18:19] op_sel_hi:[1,0,0]
	v_mul_f32_e32 v55, v39, v39
	v_exp_f32_e32 v45, v45
	v_pk_fma_f32 v[58:59], v[46:47], s[12:13], v[18:19] op_sel_hi:[1,0,0]
	v_pk_fma_f32 v[56:57], v[42:43], v[56:57], s[14:15] op_sel_hi:[1,1,0]
	v_mul_f32_e32 v55, 0xbf38aa3b, v55
	v_pk_fma_f32 v[58:59], v[46:47], v[58:59], s[14:15] op_sel_hi:[1,1,0]
	v_pk_fma_f32 v[56:57], v[42:43], v[56:57], s[16:17] op_sel_hi:[1,1,0]
	v_exp_f32_e32 v55, v55
	v_pk_fma_f32 v[58:59], v[46:47], v[58:59], s[16:17] op_sel_hi:[1,1,0]
	v_pk_fma_f32 v[56:57], v[42:43], v[56:57], s[18:19] op_sel_hi:[1,1,0]
	v_pk_fma_f32 v[58:59], v[46:47], v[58:59], s[18:19] op_sel_hi:[1,1,0]
	v_pk_mul_f32 v[42:43], v[42:43], v[56:57]
	v_pk_mul_f32 v[46:47], v[46:47], v[58:59]
	v_pk_mul_f32 v[42:43], v[44:45], v[42:43]
	v_pk_mul_f32 v[46:47], v[54:55], v[46:47]
	v_pk_mul_f32 v[44:45], v[42:43], v[40:41]
	v_pk_fma_f32 v[42:43], v[42:43], v[40:41], v[40:41] neg_lo:[1,0,0] neg_hi:[1,0,0]
	v_cmp_gt_f32_e32 vcc, 0, v40
	v_pk_mul_f32 v[54:55], v[46:47], v[38:39]
	v_pk_fma_f32 v[46:47], v[46:47], v[38:39], v[38:39] neg_lo:[1,0,0] neg_hi:[1,0,0]
	v_cmp_gt_f32_e64 s[44:45], 0, v38
	v_cmp_gt_f32_e64 s[46:47], 0, v39
	v_cndmask_b32_e32 v38, v42, v44, vcc
	v_lshlrev_b32_e32 v44, 16, v50
	v_cmp_gt_f32_e64 s[42:43], 0, v41
	v_cndmask_b32_e64 v41, v47, v55, s[46:47]
	v_mul_f32_e32 v47, v44, v44
	v_cndmask_b32_e64 v39, v43, v45, s[42:43]
	v_lshlrev_b32_e32 v45, 16, v51
	v_mul_f32_e32 v47, 0xbf38aa3b, v47
	v_cndmask_b32_e64 v40, v46, v54, s[44:45]
	v_fma_f32 v46, |v44|, s92, 1.0
	v_exp_f32_e32 v50, v47
	v_fma_f32 v47, |v45|, s92, 1.0
	v_lshlrev_b32_e32 v42, 16, v52
	v_rcp_f32_e32 v46, v46
	v_rcp_f32_e32 v47, v47
	v_lshlrev_b32_e32 v43, 16, v53
	v_mul_f32_e32 v53, v42, v42
	v_mul_f32_e32 v53, 0xbf38aa3b, v53
	v_mul_f32_e32 v51, v45, v45
	v_fma_f32 v52, |v42|, s92, 1.0
	v_exp_f32_e32 v54, v53
	v_fma_f32 v53, |v43|, s92, 1.0
	v_mul_f32_e32 v51, 0xbf38aa3b, v51
	v_rcp_f32_e32 v52, v52
	v_rcp_f32_e32 v53, v53
	v_pk_fma_f32 v[56:57], v[46:47], s[12:13], v[18:19] op_sel_hi:[1,0,0]
	v_exp_f32_e32 v51, v51
	v_pk_fma_f32 v[56:57], v[46:47], v[56:57], s[14:15] op_sel_hi:[1,1,0]
	v_mul_f32_e32 v55, v43, v43
	v_pk_fma_f32 v[56:57], v[46:47], v[56:57], s[16:17] op_sel_hi:[1,1,0]
	v_pk_fma_f32 v[58:59], v[52:53], s[12:13], v[18:19] op_sel_hi:[1,0,0]
	v_pk_fma_f32 v[56:57], v[46:47], v[56:57], s[18:19] op_sel_hi:[1,1,0]
	v_mul_f32_e32 v55, 0xbf38aa3b, v55
	v_pk_mul_f32 v[46:47], v[46:47], v[56:57]
	v_pk_fma_f32 v[58:59], v[52:53], v[58:59], s[14:15] op_sel_hi:[1,1,0]
	v_exp_f32_e32 v55, v55
	v_pk_mul_f32 v[46:47], v[50:51], v[46:47]
	v_pk_fma_f32 v[58:59], v[52:53], v[58:59], s[16:17] op_sel_hi:[1,1,0]
	v_pk_mul_f32 v[50:51], v[46:47], v[44:45]
	v_pk_fma_f32 v[46:47], v[46:47], v[44:45], v[44:45] neg_lo:[1,0,0] neg_hi:[1,0,0]
	v_cmp_gt_f32_e32 vcc, 0, v44
	v_pk_fma_f32 v[58:59], v[52:53], v[58:59], s[18:19] op_sel_hi:[1,1,0]
	v_cmp_gt_f32_e64 s[42:43], 0, v45
	v_cndmask_b32_e32 v44, v46, v50, vcc
	v_lshlrev_b32_e32 v46, 16, v48
	v_lshlrev_b32_e32 v48, 16, v15
	v_pk_mul_f32 v[52:53], v[52:53], v[58:59]
	v_fma_f32 v15, |v48|, s92, 1.0
	v_pk_mul_f32 v[52:53], v[54:55], v[52:53]
	v_rcp_f32_e32 v50, v15
	v_mul_f32_e32 v15, v48, v48
	v_pk_mul_f32 v[54:55], v[52:53], v[42:43]
	v_pk_fma_f32 v[52:53], v[52:53], v[42:43], v[42:43] neg_lo:[1,0,0] neg_hi:[1,0,0]
	v_cmp_gt_f32_e64 s[44:45], 0, v42
	v_cndmask_b32_e64 v45, v47, v51, s[42:43]
	v_lshlrev_b32_e32 v47, 16, v49
	v_lshlrev_b32_e32 v49, 16, v17
	v_mul_f32_e32 v15, 0xbf38aa3b, v15
	v_cndmask_b32_e64 v42, v52, v54, s[44:45]
	v_exp_f32_e32 v52, v15
	v_fma_f32 v15, |v49|, s92, 1.0
	v_rcp_f32_e32 v51, v15
	v_mul_f32_e32 v15, v49, v49
	v_cmp_gt_f32_e64 s[46:47], 0, v43
	v_mul_f32_e32 v15, 0xbf38aa3b, v15
	v_pk_fma_f32 v[58:59], v[50:51], s[12:13], v[18:19] op_sel_hi:[1,0,0]
	v_cndmask_b32_e64 v43, v53, v55, s[46:47]
	v_exp_f32_e32 v53, v15
	v_fma_f32 v15, |v46|, s92, 1.0
	v_rcp_f32_e32 v54, v15
	v_mul_f32_e32 v15, v46, v46
	v_mul_f32_e32 v15, 0xbf38aa3b, v15
	v_exp_f32_e32 v56, v15
	v_fma_f32 v15, |v47|, s92, 1.0
	v_rcp_f32_e32 v55, v15
	v_pk_fma_f32 v[58:59], v[50:51], v[58:59], s[14:15] op_sel_hi:[1,1,0]
	v_mul_f32_e32 v15, v47, v47
	v_pk_fma_f32 v[58:59], v[50:51], v[58:59], s[16:17] op_sel_hi:[1,1,0]
	v_pk_fma_f32 v[60:61], v[54:55], s[12:13], v[18:19] op_sel_hi:[1,0,0]
	v_mul_f32_e32 v15, 0xbf38aa3b, v15
	v_pk_fma_f32 v[60:61], v[54:55], v[60:61], s[14:15] op_sel_hi:[1,1,0]
	v_pk_fma_f32 v[58:59], v[50:51], v[58:59], s[18:19] op_sel_hi:[1,1,0]
	v_exp_f32_e32 v57, v15
	v_pk_fma_f32 v[60:61], v[54:55], v[60:61], s[16:17] op_sel_hi:[1,1,0]
	v_pk_mul_f32 v[50:51], v[50:51], v[58:59]
	v_pk_fma_f32 v[60:61], v[54:55], v[60:61], s[18:19] op_sel_hi:[1,1,0]
	v_pk_mul_f32 v[50:51], v[52:53], v[50:51]
	v_pk_mul_f32 v[54:55], v[54:55], v[60:61]
	v_pk_mul_f32 v[52:53], v[50:51], v[48:49]
	v_pk_fma_f32 v[50:51], v[50:51], v[48:49], v[48:49] neg_lo:[1,0,0] neg_hi:[1,0,0]
	v_cmp_gt_f32_e32 vcc, 0, v48
	v_pk_mul_f32 v[54:55], v[56:57], v[54:55]
	v_cmp_gt_f32_e64 s[42:43], 0, v49
	v_cndmask_b32_e32 v48, v50, v52, vcc
	v_lshlrev_b32_e32 v52, 16, v9
	v_pk_mul_f32 v[56:57], v[54:55], v[46:47]
	v_pk_fma_f32 v[54:55], v[54:55], v[46:47], v[46:47] neg_lo:[1,0,0] neg_hi:[1,0,0]
	v_cmp_gt_f32_e64 s[44:45], 0, v46
	v_cndmask_b32_e64 v49, v51, v53, s[42:43]
	v_lshlrev_b32_e32 v51, 16, v7
	v_fma_f32 v7, |v52|, s92, 1.0
	v_cndmask_b32_e64 v46, v54, v56, s[44:45]
	v_rcp_f32_e32 v54, v7
	v_mul_f32_e32 v7, v52, v52
	v_lshlrev_b32_e32 v53, 16, v11
	v_mul_f32_e32 v7, 0xbf38aa3b, v7
	v_cmp_gt_f32_e64 s[46:47], 0, v47
	v_exp_f32_e32 v56, v7
	v_fma_f32 v7, |v53|, s92, 1.0
	v_cndmask_b32_e64 v47, v55, v57, s[46:47]
	v_rcp_f32_e32 v55, v7
	v_mul_f32_e32 v7, v53, v53
	v_lshlrev_b32_e32 v50, 16, v13
	v_mul_f32_e32 v7, 0xbf38aa3b, v7
	v_exp_f32_e32 v57, v7
	v_fma_f32 v7, |v50|, s92, 1.0
	v_rcp_f32_e32 v58, v7
	v_mul_f32_e32 v7, v50, v50
	v_mul_f32_e32 v7, 0xbf38aa3b, v7
	v_exp_f32_e32 v60, v7
	v_fma_f32 v7, |v51|, s92, 1.0
	v_rcp_f32_e32 v59, v7
	v_pk_fma_f32 v[62:63], v[54:55], s[12:13], v[18:19] op_sel_hi:[1,0,0]
	v_mul_f32_e32 v7, v51, v51
	v_pk_fma_f32 v[62:63], v[54:55], v[62:63], s[14:15] op_sel_hi:[1,1,0]
	v_pk_fma_f32 v[18:19], v[58:59], s[12:13], v[18:19] op_sel_hi:[1,0,0]
	v_mul_f32_e32 v7, 0xbf38aa3b, v7
	v_pk_fma_f32 v[18:19], v[58:59], v[18:19], s[14:15] op_sel_hi:[1,1,0]
	v_pk_fma_f32 v[62:63], v[54:55], v[62:63], s[16:17] op_sel_hi:[1,1,0]
	v_exp_f32_e32 v61, v7
	v_pk_fma_f32 v[18:19], v[58:59], v[18:19], s[16:17] op_sel_hi:[1,1,0]
	v_pk_fma_f32 v[62:63], v[54:55], v[62:63], s[18:19] op_sel_hi:[1,1,0]
	v_pk_fma_f32 v[18:19], v[58:59], v[18:19], s[18:19] op_sel_hi:[1,1,0]
	v_pk_mul_f32 v[54:55], v[54:55], v[62:63]
	v_pk_mul_f32 v[18:19], v[58:59], v[18:19]
	v_pk_mul_f32 v[54:55], v[56:57], v[54:55]
	v_pk_mul_f32 v[18:19], v[60:61], v[18:19]
	v_pk_mul_f32 v[56:57], v[54:55], v[52:53]
	v_pk_fma_f32 v[54:55], v[54:55], v[52:53], v[52:53] neg_lo:[1,0,0] neg_hi:[1,0,0]
	v_cmp_gt_f32_e32 vcc, 0, v52
	v_pk_mul_f32 v[58:59], v[18:19], v[50:51]
	v_pk_fma_f32 v[18:19], v[18:19], v[50:51], v[50:51] neg_lo:[1,0,0] neg_hi:[1,0,0]
	v_cmp_gt_f32_e64 s[42:43], 0, v53
	v_cmp_gt_f32_e64 s[44:45], 0, v50
	v_cndmask_b32_e32 v50, v54, v56, vcc
	v_cmp_gt_f32_e64 s[46:47], 0, v51
	v_cndmask_b32_e64 v51, v55, v57, s[42:43]
	v_mov_b32_e32 v52, v38
	v_mov_b32_e32 v53, v48
	v_mov_b32_e32 v54, v44
	v_mov_b32_e32 v55, v50
	v_cndmask_b32_e64 v19, v19, v59, s[46:47]
	v_cndmask_b32_e64 v18, v18, v58, s[44:45]
	v_pk_add_f32 v[58:59], v[52:53], v[54:55]
	v_mov_b32_e32 v9, v131
	v_add_f32_e32 v7, v58, v59
	v_mov_b32_e32 v52, v39
	v_mov_b32_e32 v53, v49
	v_add_f32_dpp v7, v7, v7 quad_perm:[1,0,3,2] row_mask:0xf bank_mask:0xf bound_ctrl:1
	v_mov_b32_e32 v54, v45
	v_mov_b32_e32 v55, v51
	v_add_f32_dpp v7, v7, v7 quad_perm:[2,3,0,1] row_mask:0xf bank_mask:0xf bound_ctrl:1
	v_pk_add_f32 v[56:57], v[52:53], v[54:55]
	v_mov_b32_e32 v52, v40
	v_add_f32_dpp v7, v7, v7 row_half_mirror row_mask:0xf bank_mask:0xf bound_ctrl:1
	v_mov_b32_e32 v53, v46
	v_mov_b32_e32 v54, v42
	v_add_f32_dpp v7, v7, v7 row_mirror row_mask:0xf bank_mask:0xf bound_ctrl:1
	v_mov_b32_e32 v55, v18
	v_pk_add_f32 v[54:55], v[52:53], v[54:55]
	v_mov_b32_dpp v9, v7 row_bcast:15 row_mask:0xa bank_mask:0xf
	v_add_f32_e32 v7, v7, v9
	v_mov_b32_e32 v52, v41
	v_mov_b32_e32 v53, v47
	v_add_f32_dpp v7, v7, v7 row_bcast:31 row_mask:0xc bank_mask:0xf
	v_mov_b32_e32 v9, v131
	v_readlane_b32 s6, v7, 63
	v_add_f32_e32 v7, v56, v57
	v_mov_b32_e32 v60, v43
	v_mov_b32_e32 v61, v19
	v_add_f32_dpp v7, v7, v7 quad_perm:[1,0,3,2] row_mask:0xf bank_mask:0xf bound_ctrl:1
	v_pk_add_f32 v[52:53], v[52:53], v[60:61]
	s_xor_b32 s6, s6, 0x80000000
	v_add_f32_dpp v7, v7, v7 quad_perm:[2,3,0,1] row_mask:0xf bank_mask:0xf bound_ctrl:1
	v_pk_fma_f32 v[32:33], v[10:11], v[32:33], v[12:13] op_sel_hi:[0,1,0]
	v_pk_fma_f32 v[22:23], v[2:3], v[22:23], v[4:5] op_sel_hi:[0,1,0]
	v_add_f32_dpp v7, v7, v7 row_half_mirror row_mask:0xf bank_mask:0xf bound_ctrl:1
	v_pk_fma_f32 v[24:25], v[2:3], v[24:25], v[4:5] op_sel_hi:[0,1,0]
	s_movk_i32 s42, 0x110
	v_add_f32_dpp v7, v7, v7 row_mirror row_mask:0xf bank_mask:0xf bound_ctrl:1
	s_mov_b32 s44, 0xbf3a00e3
	s_nop 0
	v_mov_b32_dpp v9, v7 row_bcast:15 row_mask:0xa bank_mask:0xf
	v_add_f32_e32 v7, v7, v9
	s_nop 1
	v_add_f32_dpp v7, v7, v7 row_bcast:31 row_mask:0xc bank_mask:0xf
	s_nop 0
	v_readlane_b32 s7, v7, 63
	v_add_f32_e32 v7, v54, v55
	s_xor_b32 s7, s7, 0x80000000
	v_pk_fma_f32 v[54:55], s[6:7], v[20:21], v[38:39] op_sel_hi:[1,0,1]
	v_add_f32_dpp v7, v7, v7 quad_perm:[1,0,3,2] row_mask:0xf bank_mask:0xf bound_ctrl:1
	v_pk_fma_f32 v[44:45], s[6:7], v[20:21], v[44:45] op_sel_hi:[1,0,1]
	s_nop 0
	v_add_f32_dpp v7, v7, v7 quad_perm:[2,3,0,1] row_mask:0xf bank_mask:0xf bound_ctrl:1
	s_nop 1
	v_add_f32_dpp v7, v7, v7 row_half_mirror row_mask:0xf bank_mask:0xf bound_ctrl:1
	s_nop 1
	v_add_f32_dpp v7, v7, v7 row_mirror row_mask:0xf bank_mask:0xf bound_ctrl:1
	s_nop 1
	v_add_f32_dpp v7, v7, v7 row_bcast:15 row_mask:0xa bank_mask:0xf
	s_nop 1
	v_add_f32_dpp v7, v7, v7 row_bcast:31 row_mask:0xc bank_mask:0xf
	s_nop 0
	v_readlane_b32 s8, v7, 63
	v_add_f32_e32 v7, v52, v53
	s_xor_b32 s8, s8, 0x80000000
	s_nop 0
	v_add_f32_dpp v7, v7, v7 quad_perm:[1,0,3,2] row_mask:0xf bank_mask:0xf bound_ctrl:1
	s_nop 1
	v_add_f32_dpp v7, v7, v7 quad_perm:[2,3,0,1] row_mask:0xf bank_mask:0xf bound_ctrl:1
	s_nop 1
	v_add_f32_dpp v7, v7, v7 row_half_mirror row_mask:0xf bank_mask:0xf bound_ctrl:1
	s_nop 1
	v_add_f32_dpp v7, v7, v7 row_mirror row_mask:0xf bank_mask:0xf bound_ctrl:1
	s_nop 1
	v_add_f32_dpp v7, v7, v7 row_bcast:15 row_mask:0xa bank_mask:0xf
	s_nop 1
	v_add_f32_dpp v7, v7, v7 row_bcast:31 row_mask:0xc bank_mask:0xf
	v_mov_b32_e32 v9, v131
	v_readlane_b32 s9, v7, 63
	s_xor_b32 s9, s9, 0x80000000
	s_nop 0
	v_pk_fma_f32 v[52:53], s[8:9], v[20:21], v[40:41] op_sel_hi:[1,0,1]
	v_pk_fma_f32 v[42:43], s[8:9], v[20:21], v[42:43] op_sel_hi:[1,0,1]
	v_pk_fma_f32 v[38:39], s[8:9], v[20:21], v[46:47] op_sel_hi:[1,0,1]
	v_pk_fma_f32 v[40:41], s[6:7], v[20:21], v[48:49] op_sel_hi:[1,0,1]
	v_pk_fma_f32 v[18:19], s[8:9], v[20:21], v[18:19] op_sel_hi:[1,0,1]
	v_pk_fma_f32 v[20:21], s[6:7], v[20:21], v[50:51] op_sel_hi:[1,0,1]
	v_mov_b32_e32 v48, v44
	v_mov_b32_e32 v49, v20
	v_mov_b32_e32 v46, v54
	v_mov_b32_e32 v47, v40
	v_pk_mul_f32 v[48:49], v[48:49], v[48:49]
	v_mov_b32_e32 v50, v45
	v_pk_fma_f32 v[46:47], v[46:47], v[46:47], v[48:49]
	v_mov_b32_e32 v51, v21
	v_add_f32_e32 v7, v46, v47
	v_mov_b32_e32 v48, v55
	v_mov_b32_e32 v49, v41
	v_add_f32_dpp v7, v7, v7 quad_perm:[1,0,3,2] row_mask:0xf bank_mask:0xf bound_ctrl:1
	v_pk_mul_f32 v[50:51], v[50:51], v[50:51]
	v_mov_b32_e32 v56, v43
	v_add_f32_dpp v7, v7, v7 quad_perm:[2,3,0,1] row_mask:0xf bank_mask:0xf bound_ctrl:1
	v_pk_fma_f32 v[48:49], v[48:49], v[48:49], v[50:51]
	v_mov_b32_e32 v50, v42
	v_add_f32_dpp v7, v7, v7 row_half_mirror row_mask:0xf bank_mask:0xf bound_ctrl:1
	v_mov_b32_e32 v51, v18
	v_pk_mul_f32 v[50:51], v[50:51], v[50:51]
	v_add_f32_dpp v7, v7, v7 row_mirror row_mask:0xf bank_mask:0xf bound_ctrl:1
	v_mov_b32_e32 v57, v19
	v_pk_mul_f32 v[56:57], v[56:57], v[56:57]
	v_mov_b32_dpp v9, v7 row_bcast:15 row_mask:0xa bank_mask:0xf
	v_add_f32_e32 v7, v7, v9
	v_readlane_b32 s9, v254, 29
	s_movk_i32 s8, 0x2000
	v_add_f32_dpp v7, v7, v7 row_bcast:31 row_mask:0xc bank_mask:0xf
	v_mov_b32_e32 v9, v131
	v_readlane_b32 s6, v7, 63
	s_nop 1
	v_fma_f32 v7, s6, v235, v225
	v_rsq_f32_e32 v46, v7
	v_add_f32_e32 v7, v48, v49
	v_mov_b32_e32 v48, v52
	v_mov_b32_e32 v49, v38
	v_add_f32_dpp v7, v7, v7 quad_perm:[1,0,3,2] row_mask:0xf bank_mask:0xf bound_ctrl:1
	v_pk_fma_f32 v[48:49], v[48:49], v[48:49], v[50:51]
	v_mov_b32_e32 v50, v53
	v_add_f32_dpp v7, v7, v7 quad_perm:[2,3,0,1] row_mask:0xf bank_mask:0xf bound_ctrl:1
	v_mov_b32_e32 v51, v39
	v_pk_fma_f32 v[50:51], v[50:51], v[50:51], v[56:57]
	v_add_f32_dpp v7, v7, v7 row_half_mirror row_mask:0xf bank_mask:0xf bound_ctrl:1
	s_nop 1
	v_add_f32_dpp v7, v7, v7 row_mirror row_mask:0xf bank_mask:0xf bound_ctrl:1
	s_nop 1
	v_mov_b32_dpp v9, v7 row_bcast:15 row_mask:0xa bank_mask:0xf
	v_add_f32_e32 v7, v7, v9
	s_nop 1
	v_add_f32_dpp v7, v7, v7 row_bcast:31 row_mask:0xc bank_mask:0xf
	s_nop 0
	v_readlane_b32 s6, v7, 63
	s_nop 1
	v_fma_f32 v7, s6, v235, v225
	v_rsq_f32_e32 v47, v7
	v_add_f32_e32 v7, v48, v49
	s_nop 1
	v_add_f32_dpp v7, v7, v7 quad_perm:[1,0,3,2] row_mask:0xf bank_mask:0xf bound_ctrl:1
	s_nop 1
	v_add_f32_dpp v7, v7, v7 quad_perm:[2,3,0,1] row_mask:0xf bank_mask:0xf bound_ctrl:1
	s_nop 1
	v_add_f32_dpp v7, v7, v7 row_half_mirror row_mask:0xf bank_mask:0xf bound_ctrl:1
	s_nop 1
	v_add_f32_dpp v7, v7, v7 row_mirror row_mask:0xf bank_mask:0xf bound_ctrl:1
	s_nop 1
	v_add_f32_dpp v7, v7, v7 row_bcast:15 row_mask:0xa bank_mask:0xf
	s_nop 1
	v_add_f32_dpp v7, v7, v7 row_bcast:31 row_mask:0xc bank_mask:0xf
	v_mov_b32_e32 v9, v131
	v_readlane_b32 s6, v7, 63
	s_nop 1
	v_fma_f32 v7, s6, v235, v225
	v_rsq_f32_e32 v48, v7
	v_add_f32_e32 v7, v50, v51
	v_pk_mul_f32 v[50:51], v[54:55], v[46:47]
	s_nop 0
	v_add_f32_dpp v7, v7, v7 quad_perm:[1,0,3,2] row_mask:0xf bank_mask:0xf bound_ctrl:1
	s_nop 1
	v_add_f32_dpp v7, v7, v7 quad_perm:[2,3,0,1] row_mask:0xf bank_mask:0xf bound_ctrl:1
	s_nop 1
	v_add_f32_dpp v7, v7, v7 row_half_mirror row_mask:0xf bank_mask:0xf bound_ctrl:1
	s_nop 1
	v_add_f32_dpp v7, v7, v7 row_mirror row_mask:0xf bank_mask:0xf bound_ctrl:1
	s_nop 1
	v_mov_b32_dpp v9, v7 row_bcast:15 row_mask:0xa bank_mask:0xf
	v_add_f32_e32 v7, v7, v9
	v_mov_b32_e32 v9, v131
	s_nop 1
	v_mov_b32_dpp v9, v7 row_bcast:31 row_mask:0xc bank_mask:0xf
	v_add_f32_e32 v7, v7, v9
	s_nop 0
	v_readlane_b32 s6, v7, 63
	s_nop 1
	v_fma_f32 v7, s6, v235, v225
	v_rsq_f32_e32 v49, v7
	s_add_i32 s6, s5, s15
	s_mul_hi_i32 s7, s6, 0x5000
	s_mulk_i32 s6, 0x5000
	v_pk_mul_f32 v[52:53], v[52:53], v[48:49]
	s_lshl_b32 s5, s5, 9
	v_pk_fma_f32 v[52:53], v[14:15], v[52:53], v[16:17] op_sel_hi:[0,1,0]
	v_pk_fma_f32 v[14:15], v[14:15], v[50:51], v[16:17] op_sel_hi:[0,1,0]
	v_cvt_pk_bf16_f32 v17, v52, v53
	v_cvt_pk_bf16_f32 v16, v14, v15
	v_cvt_pk_bf16_f32 v15, v34, v35
	v_cvt_pk_bf16_f32 v14, v36, v37
	ds_write_b128 v5, v[14:17] offset:16
	v_pk_mul_f32 v[14:15], v[44:45], v[46:47]
	v_pk_mul_f32 v[16:17], v[42:43], v[48:49]
	s_add_u32 s28, s9, s6
	v_pk_fma_f32 v[16:17], v[10:11], v[16:17], v[12:13] op_sel_hi:[0,1,0]
	v_pk_fma_f32 v[10:11], v[10:11], v[14:15], v[12:13] op_sel_hi:[0,1,0]
	v_cvt_pk_bf16_f32 v13, v16, v17
	v_cvt_pk_bf16_f32 v12, v10, v11
	v_cvt_pk_bf16_f32 v11, v30, v31
	v_cvt_pk_bf16_f32 v10, v32, v33
	ds_write_b128 v5, v[10:13] offset:17424
	v_pk_mul_f32 v[10:11], v[40:41], v[46:47]
	v_pk_mul_f32 v[12:13], v[38:39], v[48:49]
	v_readlane_b32 s6, v254, 31
	v_pk_fma_f32 v[12:13], v[6:7], v[12:13], v[8:9] op_sel_hi:[0,1,0]
	v_pk_fma_f32 v[6:7], v[6:7], v[10:11], v[8:9] op_sel_hi:[0,1,0]
	v_cvt_pk_bf16_f32 v9, v12, v13
	v_cvt_pk_bf16_f32 v8, v6, v7
	v_cvt_pk_bf16_f32 v7, v26, v27
	v_cvt_pk_bf16_f32 v6, v28, v29
	ds_write_b128 v5, v[6:9] offset:34832
	v_pk_mul_f32 v[6:7], v[20:21], v[46:47]
	v_pk_mul_f32 v[8:9], v[18:19], v[48:49]
	v_pk_fma_f32 v[6:7], v[2:3], v[6:7], v[4:5] op_sel_hi:[0,1,0]
	v_pk_fma_f32 v[8:9], v[2:3], v[8:9], v[4:5] op_sel_hi:[0,1,0]
	v_bfe_u32 v4, v3, 5, 1
	v_and_or_b32 v2, v3, 31, s34
	v_mul_lo_u32 v3, v2, s42
	v_lshlrev_b32_e32 v164, 4, v4
	v_cvt_pk_bf16_f32 v9, v8, v9
	v_cvt_pk_bf16_f32 v8, v6, v7
	v_cvt_pk_bf16_f32 v7, v22, v23
	v_cvt_pk_bf16_f32 v6, v24, v25
	v_add3_u32 v3, 0, v3, v164
	ds_write_b128 v5, v[6:9] offset:52240
	s_waitcnt lgkmcnt(0)
	s_barrier
	ds_read_b128 v[18:21], v3
	ds_read_b128 v[22:25], v3 offset:32
	ds_read_b128 v[26:29], v3 offset:64
	ds_read_b128 v[30:33], v3 offset:96
	ds_read_b128 v[34:37], v3 offset:128
	ds_read_b128 v[38:41], v3 offset:160
	ds_read_b128 v[42:45], v3 offset:192
	ds_read_b128 v[46:49], v3 offset:224
	s_addc_u32 s29, s6, s7
	v_ashrrev_i32_e32 v3, 31, v2
	v_lshl_add_u32 v94, v4, 2, s17
	v_lshlrev_b64 v[106:107], 1, v[2:3]
	global_load_dwordx4 v[2:5], v130, s[28:29]
	global_load_dwordx4 v[50:53], v130, s[28:29] offset:1024
	v_lshl_add_u64 v[90:91], s[28:29], 0, v[130:131]
	v_add_co_u32_e32 v54, vcc, s90, v90
	v_lshl_add_u64 v[92:93], s[80:81], 0, v[106:107]
	s_nop 0
	v_addc_co_u32_e32 v55, vcc, 0, v91, vcc
	v_add_u32_e32 v72, 15, v94
	v_add_u32_e32 v68, 16, v94
	v_add_u32_e32 v66, 17, v94
	v_add_u32_e32 v64, 18, v94
	v_add_u32_e32 v158, 33, v94
	v_add_u32_e32 v156, 34, v94
	v_add_u32_e32 v154, 39, v94
	v_add_u32_e32 v152, 40, v94
	v_add_u32_e32 v150, 41, v94
	v_add_co_u32_e32 v70, vcc, s8, v90
	v_add_u32_e32 v120, -1, v94
	v_add_u32_e32 v118, 1, v94
	v_add_u32_e32 v116, 2, v94
	v_add_u32_e32 v114, 7, v94
	v_add_u32_e32 v112, 8, v94
	v_add_u32_e32 v110, 9, v94
	v_add_u32_e32 v108, 10, v94
	v_mad_i64_i32 v[126:127], s[6:7], v72, s87, v[92:93]
	v_mad_i64_i32 v[128:129], s[6:7], v68, s87, v[92:93]
	v_mad_i64_i32 v[132:133], s[6:7], v66, s87, v[92:93]
	v_mad_i64_i32 v[134:135], s[6:7], v64, s87, v[92:93]
	v_add_u32_e32 v62, 23, v94
	v_add_u32_e32 v60, 24, v94
	v_add_u32_e32 v58, 25, v94
	v_add_u32_e32 v56, 26, v94
	v_add_u32_e32 v162, 31, v94
	v_add_u32_e32 v160, 32, v94
	v_mad_i64_i32 v[172:173], s[6:7], v158, s87, v[92:93]
	v_mad_i64_i32 v[174:175], s[6:7], v156, s87, v[92:93]
	v_mad_i64_i32 v[176:177], s[6:7], v154, s87, v[92:93]
	v_mad_i64_i32 v[178:179], s[6:7], v152, s87, v[92:93]
	v_mad_i64_i32 v[180:181], s[6:7], v150, s87, v[92:93]
	v_add_u32_e32 v148, 42, v94
	v_add_u32_e32 v146, 47, v94
	v_add_u32_e32 v144, 48, v94
	v_add_u32_e32 v142, 49, v94
	v_add_u32_e32 v104, 50, v94
	v_add_u32_e32 v102, 55, v94
	v_add_u32_e32 v100, 56, v94
	v_add_u32_e32 v98, 57, v94
	v_add_u32_e32 v96, 58, v94
	v_addc_co_u32_e32 v71, vcc, 0, v91, vcc
	v_mad_i64_i32 v[6:7], s[6:7], v120, s87, v[92:93]
	v_mad_i64_i32 v[8:9], s[6:7], v94, s87, v[92:93]
	v_mad_i64_i32 v[10:11], s[6:7], v118, s87, v[92:93]
	v_mad_i64_i32 v[12:13], s[6:7], v116, s87, v[92:93]
	v_mad_i64_i32 v[14:15], s[6:7], v114, s87, v[92:93]
	v_mad_i64_i32 v[16:17], s[6:7], v112, s87, v[92:93]
	v_mad_i64_i32 v[122:123], s[6:7], v110, s87, v[92:93]
	v_mad_i64_i32 v[124:125], s[6:7], v108, s87, v[92:93]
	v_mad_i64_i32 v[136:137], s[6:7], v62, s87, v[92:93]
	v_mad_i64_i32 v[138:139], s[6:7], v60, s87, v[92:93]
	v_mad_i64_i32 v[140:141], s[6:7], v58, s87, v[92:93]
	v_mad_i64_i32 v[166:167], s[6:7], v56, s87, v[92:93]
	v_mad_i64_i32 v[168:169], s[6:7], v162, s87, v[92:93]
	v_mad_i64_i32 v[170:171], s[6:7], v160, s87, v[92:93]
	v_mad_i64_i32 v[188:189], s[6:7], v148, s87, v[92:93]
	v_mad_i64_i32 v[190:191], s[6:7], v146, s87, v[92:93]
	v_mad_i64_i32 v[192:193], s[6:7], v144, s87, v[92:93]
	v_mad_i64_i32 v[194:195], s[6:7], v142, s87, v[92:93]
	v_mad_i64_i32 v[196:197], s[6:7], v104, s87, v[92:93]
	v_mad_i64_i32 v[198:199], s[6:7], v102, s87, v[92:93]
	v_mad_i64_i32 v[200:201], s[6:7], v100, s87, v[92:93]
	v_mad_i64_i32 v[202:203], s[6:7], v98, s87, v[92:93]
	v_mad_i64_i32 v[204:205], s[6:7], v96, s87, v[92:93]
	global_load_dwordx4 v[74:77], v130, s[28:29] offset:2048
	global_load_dwordx4 v[78:81], v130, s[28:29] offset:3072
	global_load_dwordx4 v[82:85], v[70:71], off offset:-4096
	global_load_dwordx4 v[86:89], v[54:55], off offset:1024
	global_load_ushort v1, v[6:7], off
	s_nop 0
	global_load_ushort v130, v[8:9], off
	global_load_ushort v165, v[10:11], off
	global_load_ushort v206, v[12:13], off
	global_load_ushort v207, v[14:15], off
	global_load_ushort v208, v[16:17], off
	global_load_ushort v209, v[122:123], off
	global_load_ushort v210, v[124:125], off
	s_nop 0
	global_load_ushort v126, v[126:127], off
	s_nop 0
	global_load_ushort v127, v[128:129], off
	s_nop 0
	global_load_ushort v128, v[132:133], off
	global_load_ushort v129, v[134:135], off
	s_nop 0
	global_load_ushort v132, v[136:137], off
	global_load_ushort v133, v[138:139], off
	global_load_ushort v134, v[140:141], off
	global_load_ushort v135, v[166:167], off
	global_load_ushort v187, v[168:169], off
	global_load_ushort v186, v[170:171], off
	global_load_ushort v185, v[172:173], off
	global_load_ushort v184, v[174:175], off
	global_load_ushort v183, v[176:177], off
	global_load_ushort v182, v[178:179], off
	s_nop 0
	global_load_ushort v181, v[180:181], off
	s_nop 0
	global_load_ushort v180, v[188:189], off
	global_load_ushort v179, v[190:191], off
	global_load_ushort v178, v[192:193], off
	global_load_ushort v177, v[194:195], off
	global_load_ushort v176, v[196:197], off
	global_load_ushort v175, v[198:199], off
	global_load_ushort v174, v[200:201], off
	global_load_ushort v173, v[202:203], off
	global_load_ushort v172, v[204:205], off
	s_waitcnt vmcnt(37) lgkmcnt(7)
	v_mfma_f32_32x32x16_bf16 v[2:17], v[2:5], v[18:21], 0
	s_add_i32 s5, s40, s5
	v_ashrrev_i32_e32 v121, 31, v120
	v_lshl_add_u64 v[106:107], s[76:77], 0, v[106:107]
	v_lshlrev_b64 v[120:121], 11, v[120:121]
	v_lshl_add_u64 v[120:121], v[106:107], 0, v[120:121]
	v_ashrrev_i32_e32 v95, 31, v94
	s_waitcnt vmcnt(36) lgkmcnt(6)
	v_mfma_f32_32x32x16_bf16 v[2:17], v[50:53], v[22:25], v[2:17]
	v_ashrrev_i32_e32 v119, 31, v118
	v_ashrrev_i32_e32 v117, 31, v116
	v_ashrrev_i32_e32 v115, 31, v114
	v_ashrrev_i32_e32 v113, 31, v112
	v_ashrrev_i32_e32 v111, 31, v110
	v_ashrrev_i32_e32 v109, 31, v108
	v_ashrrev_i32_e32 v73, 31, v72
	v_ashrrev_i32_e32 v69, 31, v68
	v_ashrrev_i32_e32 v67, 31, v66
	v_ashrrev_i32_e32 v65, 31, v64
	v_ashrrev_i32_e32 v63, 31, v62
	v_ashrrev_i32_e32 v61, 31, v60
	v_ashrrev_i32_e32 v59, 31, v58
	v_ashrrev_i32_e32 v57, 31, v56
	v_add_u32_e32 v140, 63, v94
	v_add_u32_e32 v138, 64, v94
	v_ashrrev_i32_e32 v163, 31, v162
	v_ashrrev_i32_e32 v161, 31, v160
	v_ashrrev_i32_e32 v159, 31, v158
	v_ashrrev_i32_e32 v157, 31, v156
	v_ashrrev_i32_e32 v155, 31, v154
	v_ashrrev_i32_e32 v153, 31, v152
	v_ashrrev_i32_e32 v151, 31, v150
	v_ashrrev_i32_e32 v149, 31, v148
	v_ashrrev_i32_e32 v147, 31, v146
	v_ashrrev_i32_e32 v145, 31, v144
	v_ashrrev_i32_e32 v143, 31, v142
	v_ashrrev_i32_e32 v105, 31, v104
	v_ashrrev_i32_e32 v103, 31, v102
	v_ashrrev_i32_e32 v101, 31, v100
	v_ashrrev_i32_e32 v99, 31, v98
	v_ashrrev_i32_e32 v97, 31, v96
	v_ashrrev_i32_e32 v141, 31, v140
	v_ashrrev_i32_e32 v139, 31, v138
	s_waitcnt vmcnt(31)
	v_lshlrev_b32_e32 v1, 16, v1
	v_fma_f32 v50, |v1|, s92, 1.0
	v_rcp_f32_e32 v50, v50
	v_cmp_gt_f32_e32 vcc, 0, v1
	v_fmamk_f32 v51, v50, 0x3f07dc22, v236
	v_fmaak_f32 v51, v50, v51, 0x3f35f0e3
	v_fmaak_f32 v51, v50, v51, 0xbe11a98e
	v_fmaak_f32 v51, v50, v51, 0x3e027906
	v_mul_f32_e32 v50, v50, v51
	v_mul_f32_e32 v51, v1, v1
	v_mul_f32_e32 v51, 0xbf38aa3b, v51
	v_exp_f32_e32 v51, v51
	s_nop 0
	v_mul_f32_e32 v50, v51, v50
	v_mul_f32_e32 v51, v50, v1
	v_fma_f32 v50, -v50, v1, v1
	v_add_u32_e32 v1, s5, v164
	v_cndmask_b32_e32 v136, v50, v51, vcc
	ds_read_b128 v[50:53], v1
	ds_read_b128 v[122:125], v1 offset:32
	s_movk_i32 s5, 0x3000
	s_waitcnt lgkmcnt(1)
	v_add_f32_e32 v2, v2, v50
	v_mul_f32_e32 v2, v136, v2
	v_cvt_pk_bf16_f32 v2, v2, s0
	global_store_short v[120:121], v2, off
	s_waitcnt vmcnt(31)
	v_lshlrev_b32_e32 v2, 16, v130
	v_fma_f32 v50, |v2|, s92, 1.0
	v_rcp_f32_e32 v50, v50
	v_cmp_gt_f32_e32 vcc, 0, v2
	v_add_f32_e32 v3, v3, v51
	v_add_u32_e32 v136, 0x41, v94
	v_fmamk_f32 v120, v50, 0x3f07dc22, v236
	v_fmaak_f32 v120, v50, v120, 0x3f35f0e3
	v_fmaak_f32 v120, v50, v120, 0xbe11a98e
	v_fmaak_f32 v120, v50, v120, 0x3e027906
	v_mul_f32_e32 v50, v50, v120
	v_mul_f32_e32 v120, v2, v2
	v_mul_f32_e32 v120, 0xbf38aa3b, v120
	v_exp_f32_e32 v120, v120
	v_ashrrev_i32_e32 v137, 31, v136
	v_mul_f32_e32 v50, v120, v50
	v_mul_f32_e32 v120, v50, v2
	v_fma_f32 v50, -v50, v2, v2
	v_cndmask_b32_e32 v2, v50, v120, vcc
	v_mul_f32_e32 v2, v2, v3
	v_cvt_pk_bf16_f32 v50, v2, s0
	v_lshlrev_b64 v[2:3], 11, v[94:95]
	v_lshl_add_u64 v[2:3], v[106:107], 0, v[2:3]
	global_store_short v[2:3], v50, off
	s_waitcnt vmcnt(31)
	v_lshlrev_b32_e32 v2, 16, v165
	v_fma_f32 v3, |v2|, s92, 1.0
	v_rcp_f32_e32 v3, v3
	v_cmp_gt_f32_e32 vcc, 0, v2
	v_add_u32_e32 v120, 0x59, v94
	v_ashrrev_i32_e32 v121, 31, v120
	v_fmamk_f32 v50, v3, 0x3f07dc22, v236
	v_fmaak_f32 v50, v3, v50, 0x3f35f0e3
	v_fmaak_f32 v50, v3, v50, 0xbe11a98e
	v_fmaak_f32 v50, v3, v50, 0x3e027906
	v_mul_f32_e32 v3, v3, v50
	v_mul_f32_e32 v50, v2, v2
	v_mul_f32_e32 v50, 0xbf38aa3b, v50
	v_exp_f32_e32 v50, v50
	s_nop 0
	v_mul_f32_e32 v3, v50, v3
	v_mul_f32_e32 v50, v3, v2
	v_fma_f32 v3, -v3, v2, v2
	v_cndmask_b32_e32 v2, v3, v50, vcc
	v_add_f32_e32 v3, v4, v52
	v_mul_f32_e32 v2, v2, v3
	v_cvt_pk_bf16_f32 v4, v2, s0
	v_lshlrev_b64 v[2:3], 11, v[118:119]
	v_lshl_add_u64 v[2:3], v[106:107], 0, v[2:3]
	global_store_short v[2:3], v4, off
	s_waitcnt vmcnt(31)
	v_lshlrev_b32_e32 v2, 16, v206
	v_fma_f32 v3, |v2|, s92, 1.0
	v_rcp_f32_e32 v3, v3
	v_cmp_gt_f32_e32 vcc, 0, v2
	v_add_u32_e32 v118, 0x4a, v94
	v_ashrrev_i32_e32 v119, 31, v118
	v_fmamk_f32 v4, v3, 0x3f07dc22, v236
	v_fmaak_f32 v4, v3, v4, 0x3f35f0e3
	v_fmaak_f32 v4, v3, v4, 0xbe11a98e
	v_fmaak_f32 v4, v3, v4, 0x3e027906
	v_mul_f32_e32 v3, v3, v4
	v_mul_f32_e32 v4, v2, v2
	v_mul_f32_e32 v4, 0xbf38aa3b, v4
	v_exp_f32_e32 v4, v4
	s_nop 0
	v_mul_f32_e32 v3, v4, v3
	v_mul_f32_e32 v4, v3, v2
	v_fma_f32 v3, -v3, v2, v2
	v_cndmask_b32_e32 v2, v3, v4, vcc
	v_add_f32_e32 v3, v5, v53
	v_mul_f32_e32 v2, v2, v3
	v_cvt_pk_bf16_f32 v4, v2, s0
	v_lshlrev_b64 v[2:3], 11, v[116:117]
	v_lshl_add_u64 v[2:3], v[106:107], 0, v[2:3]
	global_store_short v[2:3], v4, off
	s_waitcnt vmcnt(31)
	v_lshlrev_b32_e32 v2, 16, v207
	v_fma_f32 v3, |v2|, s92, 1.0
	v_rcp_f32_e32 v3, v3
	v_cmp_gt_f32_e32 vcc, 0, v2
	v_add_u32_e32 v116, 0x4f, v94
	v_mad_i64_i32 v[164:165], s[6:7], v116, s87, v[92:93]
	v_fmamk_f32 v4, v3, 0x3f07dc22, v236
	v_fmaak_f32 v4, v3, v4, 0x3f35f0e3
	v_fmaak_f32 v4, v3, v4, 0xbe11a98e
	v_fmaak_f32 v4, v3, v4, 0x3e027906
	v_mul_f32_e32 v3, v3, v4
	v_mul_f32_e32 v4, v2, v2
	v_mul_f32_e32 v4, 0xbf38aa3b, v4
	v_exp_f32_e32 v4, v4
	v_mad_i64_i32 v[206:207], s[6:7], v120, s87, v[92:93]
	v_ashrrev_i32_e32 v117, 31, v116
	v_mul_f32_e32 v3, v4, v3
	v_mul_f32_e32 v4, v3, v2
	v_fma_f32 v3, -v3, v2, v2
	v_cndmask_b32_e32 v2, v3, v4, vcc
	s_waitcnt lgkmcnt(0)
	v_add_f32_e32 v3, v6, v122
	v_mul_f32_e32 v2, v2, v3
	v_cvt_pk_bf16_f32 v4, v2, s0
	v_lshlrev_b64 v[2:3], 11, v[114:115]
	v_lshl_add_u64 v[2:3], v[106:107], 0, v[2:3]
	global_store_short v[2:3], v4, off
	s_waitcnt vmcnt(31)
	v_lshlrev_b32_e32 v2, 16, v208
	v_fma_f32 v3, |v2|, s92, 1.0
	v_rcp_f32_e32 v3, v3
	v_cmp_gt_f32_e32 vcc, 0, v2
	v_add_u32_e32 v122, 0x49, v94
	v_add_u32_e32 v114, 0x5a, v94
	v_fmamk_f32 v4, v3, 0x3f07dc22, v236
	v_fmaak_f32 v4, v3, v4, 0x3f35f0e3
	v_fmaak_f32 v4, v3, v4, 0xbe11a98e
	v_fmaak_f32 v4, v3, v4, 0x3e027906
	v_mul_f32_e32 v3, v3, v4
	v_mul_f32_e32 v4, v2, v2
	v_mul_f32_e32 v4, 0xbf38aa3b, v4
	v_exp_f32_e32 v4, v4
	v_ashrrev_i32_e32 v115, 31, v114
	v_mul_f32_e32 v3, v4, v3
	v_mul_f32_e32 v4, v3, v2
	v_fma_f32 v3, -v3, v2, v2
	v_cndmask_b32_e32 v2, v3, v4, vcc
	v_add_f32_e32 v3, v7, v123
	v_mul_f32_e32 v2, v2, v3
	v_cvt_pk_bf16_f32 v4, v2, s0
	v_lshlrev_b64 v[2:3], 11, v[112:113]
	v_lshl_add_u64 v[2:3], v[106:107], 0, v[2:3]
	global_store_short v[2:3], v4, off
	s_waitcnt vmcnt(31)
	v_lshlrev_b32_e32 v2, 16, v209
	v_fma_f32 v3, |v2|, s92, 1.0
	v_rcp_f32_e32 v3, v3
	v_cmp_gt_f32_e32 vcc, 0, v2
	v_add_u32_e32 v112, 0x50, v94
	v_mad_i64_i32 v[166:167], s[6:7], v112, s87, v[92:93]
	v_fmamk_f32 v4, v3, 0x3f07dc22, v236
	v_fmaak_f32 v4, v3, v4, 0x3f35f0e3
	v_fmaak_f32 v4, v3, v4, 0xbe11a98e
	v_fmaak_f32 v4, v3, v4, 0x3e027906
	v_mul_f32_e32 v3, v3, v4
	v_mul_f32_e32 v4, v2, v2
	v_mul_f32_e32 v4, 0xbf38aa3b, v4
	v_exp_f32_e32 v4, v4
	v_mad_i64_i32 v[208:209], s[6:7], v114, s87, v[92:93]
	v_ashrrev_i32_e32 v123, 31, v122
	v_mul_f32_e32 v3, v4, v3
	v_mul_f32_e32 v4, v3, v2
	v_fma_f32 v3, -v3, v2, v2
	v_cndmask_b32_e32 v2, v3, v4, vcc
	v_add_f32_e32 v3, v8, v124
	v_mul_f32_e32 v2, v2, v3
	v_cvt_pk_bf16_f32 v4, v2, s0
	v_lshlrev_b64 v[2:3], 11, v[110:111]
	v_lshl_add_u64 v[2:3], v[106:107], 0, v[2:3]
	global_store_short v[2:3], v4, off
	s_waitcnt vmcnt(31)
	v_lshlrev_b32_e32 v2, 16, v210
	v_fma_f32 v3, |v2|, s92, 1.0
	v_rcp_f32_e32 v3, v3
	v_cmp_gt_f32_e32 vcc, 0, v2
	v_add_u32_e32 v110, 0x51, v94
	v_add_u32_e32 v124, 0x58, v94
	v_fmamk_f32 v4, v3, 0x3f07dc22, v236
	v_fmaak_f32 v4, v3, v4, 0x3f35f0e3
	v_fmaak_f32 v4, v3, v4, 0xbe11a98e
	v_fmaak_f32 v4, v3, v4, 0x3e027906
	v_mul_f32_e32 v3, v3, v4
	v_mul_f32_e32 v4, v2, v2
	v_mul_f32_e32 v4, 0xbf38aa3b, v4
	v_exp_f32_e32 v4, v4
	v_mad_i64_i32 v[168:169], s[6:7], v110, s87, v[92:93]
	v_mad_i64_i32 v[204:205], s[6:7], v124, s87, v[92:93]
	v_mul_f32_e32 v3, v4, v3
	v_mul_f32_e32 v4, v3, v2
	v_fma_f32 v3, -v3, v2, v2
	v_cndmask_b32_e32 v2, v3, v4, vcc
	v_add_f32_e32 v3, v9, v125
	v_mul_f32_e32 v2, v2, v3
	v_cvt_pk_bf16_f32 v4, v2, s0
	v_lshlrev_b64 v[2:3], 11, v[108:109]
	v_lshl_add_u64 v[2:3], v[106:107], 0, v[2:3]
	global_store_short v[2:3], v4, off
	s_waitcnt vmcnt(31)
	v_lshlrev_b32_e32 v2, 16, v126
	v_fma_f32 v3, |v2|, s92, 1.0
	v_rcp_f32_e32 v3, v3
	v_cmp_gt_f32_e32 vcc, 0, v2
	v_add_u32_e32 v126, 0x48, v94
	v_add_u32_e32 v108, 0x52, v94
	v_fmamk_f32 v4, v3, 0x3f07dc22, v236
	v_fmaak_f32 v4, v3, v4, 0x3f35f0e3
	v_fmaak_f32 v4, v3, v4, 0xbe11a98e
	v_fmaak_f32 v4, v3, v4, 0x3e027906
	v_mul_f32_e32 v3, v3, v4
	v_mul_f32_e32 v4, v2, v2
	v_mul_f32_e32 v4, 0xbf38aa3b, v4
	v_exp_f32_e32 v4, v4
	v_mad_i64_i32 v[170:171], s[6:7], v108, s87, v[92:93]
	v_ashrrev_i32_e32 v113, 31, v112
	v_mul_f32_e32 v3, v4, v3
	v_mul_f32_e32 v4, v3, v2
	v_fma_f32 v3, -v3, v2, v2
	v_cndmask_b32_e32 v6, v3, v4, vcc
	ds_read_b128 v[2:5], v1 offset:64
	v_ashrrev_i32_e32 v111, 31, v110
	v_ashrrev_i32_e32 v109, 31, v108
	v_ashrrev_i32_e32 v125, 31, v124
	s_waitcnt lgkmcnt(0)
	v_add_f32_e32 v2, v10, v2
	v_mul_f32_e32 v2, v6, v2
	v_lshlrev_b64 v[6:7], 11, v[72:73]
	v_cvt_pk_bf16_f32 v2, v2, s0
	v_lshl_add_u64 v[6:7], v[106:107], 0, v[6:7]
	global_store_short v[6:7], v2, off
	s_waitcnt vmcnt(31)
	v_lshlrev_b32_e32 v2, 16, v127
	v_fma_f32 v6, |v2|, s92, 1.0
	v_rcp_f32_e32 v6, v6
	v_cmp_gt_f32_e32 vcc, 0, v2
	v_add_f32_e32 v3, v11, v3
	v_ashrrev_i32_e32 v127, 31, v126
	v_fmamk_f32 v7, v6, 0x3f07dc22, v236
	v_fmaak_f32 v7, v6, v7, 0x3f35f0e3
	v_fmaak_f32 v7, v6, v7, 0xbe11a98e
	v_fmaak_f32 v7, v6, v7, 0x3e027906
	v_mul_f32_e32 v6, v6, v7
	v_mul_f32_e32 v7, v2, v2
	v_mul_f32_e32 v7, 0xbf38aa3b, v7
	v_exp_f32_e32 v7, v7
	s_nop 0
	v_mul_f32_e32 v6, v7, v6
	v_mul_f32_e32 v7, v6, v2
	v_fma_f32 v6, -v6, v2, v2
	v_cndmask_b32_e32 v2, v6, v7, vcc
	v_mul_f32_e32 v2, v2, v3
	v_cvt_pk_bf16_f32 v6, v2, s0
	v_lshlrev_b64 v[2:3], 11, v[68:69]
	v_lshl_add_u64 v[2:3], v[106:107], 0, v[2:3]
	global_store_short v[2:3], v6, off
	s_waitcnt vmcnt(31)
	v_lshlrev_b32_e32 v2, 16, v128
	v_fma_f32 v3, |v2|, s92, 1.0
	v_rcp_f32_e32 v3, v3
	v_cmp_gt_f32_e32 vcc, 0, v2
	v_add_u32_e32 v128, 0x57, v94
	v_mad_i64_i32 v[188:189], s[6:7], v128, s87, v[92:93]
	v_fmamk_f32 v6, v3, 0x3f07dc22, v236
	v_fmaak_f32 v6, v3, v6, 0x3f35f0e3
	v_fmaak_f32 v6, v3, v6, 0xbe11a98e
	v_fmaak_f32 v6, v3, v6, 0x3e027906
	v_mul_f32_e32 v3, v3, v6
	v_mul_f32_e32 v6, v2, v2
	v_mul_f32_e32 v6, 0xbf38aa3b, v6
	v_exp_f32_e32 v6, v6
	s_nop 0
	v_mul_f32_e32 v3, v6, v3
	v_mul_f32_e32 v6, v3, v2
	v_fma_f32 v3, -v3, v2, v2
	v_cndmask_b32_e32 v2, v3, v6, vcc
	v_add_f32_e32 v3, v12, v4
	v_mul_f32_e32 v2, v2, v3
	v_cvt_pk_bf16_f32 v4, v2, s0
	v_lshlrev_b64 v[2:3], 11, v[66:67]
	v_lshl_add_u64 v[2:3], v[106:107], 0, v[2:3]
	global_store_short v[2:3], v4, off
	s_waitcnt vmcnt(31)
	v_lshlrev_b32_e32 v2, 16, v129
	v_fma_f32 v3, |v2|, s92, 1.0
	v_rcp_f32_e32 v3, v3
	v_cmp_gt_f32_e32 vcc, 0, v2
	v_ashrrev_i32_e32 v129, 31, v128
	v_fmamk_f32 v4, v3, 0x3f07dc22, v236
	v_fmaak_f32 v4, v3, v4, 0x3f35f0e3
	v_fmaak_f32 v4, v3, v4, 0xbe11a98e
	v_fmaak_f32 v4, v3, v4, 0x3e027906
	v_mul_f32_e32 v3, v3, v4
	v_mul_f32_e32 v4, v2, v2
	v_mul_f32_e32 v4, 0xbf38aa3b, v4
	v_exp_f32_e32 v4, v4
	s_nop 0
	v_mul_f32_e32 v3, v4, v3
	v_mul_f32_e32 v4, v3, v2
	v_fma_f32 v3, -v3, v2, v2
	v_cndmask_b32_e32 v2, v3, v4, vcc
	v_add_f32_e32 v3, v13, v5
	v_mul_f32_e32 v2, v2, v3
	v_cvt_pk_bf16_f32 v4, v2, s0
	v_lshlrev_b64 v[2:3], 11, v[64:65]
	v_lshl_add_u64 v[2:3], v[106:107], 0, v[2:3]
	global_store_short v[2:3], v4, off
	s_waitcnt vmcnt(31)
	v_lshlrev_b32_e32 v2, 16, v132
	v_fma_f32 v3, |v2|, s92, 1.0
	v_rcp_f32_e32 v3, v3
	v_cmp_gt_f32_e32 vcc, 0, v2
	v_add_u32_e32 v132, 0x47, v94
	v_mad_i64_i32 v[10:11], s[6:7], v132, s87, v[92:93]
	v_fmamk_f32 v4, v3, 0x3f07dc22, v236
	v_fmaak_f32 v4, v3, v4, 0x3f35f0e3
	v_fmaak_f32 v4, v3, v4, 0xbe11a98e
	v_fmaak_f32 v4, v3, v4, 0x3e027906
	v_mul_f32_e32 v3, v3, v4
	v_mul_f32_e32 v4, v2, v2
	v_mul_f32_e32 v4, 0xbf38aa3b, v4
	v_exp_f32_e32 v4, v4
	v_mad_i64_i32 v[12:13], s[6:7], v126, s87, v[92:93]
	v_mul_f32_e32 v3, v4, v3
	v_mul_f32_e32 v4, v3, v2
	v_fma_f32 v3, -v3, v2, v2
	v_cndmask_b32_e32 v6, v3, v4, vcc
	ds_read_b128 v[2:5], v1 offset:96
	s_waitcnt lgkmcnt(0)
	v_add_f32_e32 v2, v14, v2
	v_mul_f32_e32 v2, v6, v2
	v_lshlrev_b64 v[6:7], 11, v[62:63]
	v_cvt_pk_bf16_f32 v2, v2, s0
	v_lshl_add_u64 v[6:7], v[106:107], 0, v[6:7]
	global_store_short v[6:7], v2, off
	s_waitcnt vmcnt(31)
	v_lshlrev_b32_e32 v2, 16, v133
	v_fma_f32 v6, |v2|, s92, 1.0
	v_rcp_f32_e32 v6, v6
	v_cmp_gt_f32_e32 vcc, 0, v2
	v_add_f32_e32 v3, v15, v3
	v_mad_i64_i32 v[14:15], s[6:7], v122, s87, v[92:93]
	v_fmamk_f32 v7, v6, 0x3f07dc22, v236
	v_fmaak_f32 v7, v6, v7, 0x3f35f0e3
	v_fmaak_f32 v7, v6, v7, 0xbe11a98e
	v_fmaak_f32 v7, v6, v7, 0x3e027906
	v_mul_f32_e32 v6, v6, v7
	v_mul_f32_e32 v7, v2, v2
	v_mul_f32_e32 v7, 0xbf38aa3b, v7
	v_exp_f32_e32 v7, v7
	v_ashrrev_i32_e32 v133, 31, v132
	v_mul_f32_e32 v6, v7, v6
	v_mul_f32_e32 v7, v6, v2
	v_fma_f32 v6, -v6, v2, v2
	v_cndmask_b32_e32 v2, v6, v7, vcc
	v_mul_f32_e32 v2, v2, v3
	v_cvt_pk_bf16_f32 v6, v2, s0
	v_lshlrev_b64 v[2:3], 11, v[60:61]
	v_lshl_add_u64 v[2:3], v[106:107], 0, v[2:3]
	global_store_short v[2:3], v6, off
	s_waitcnt vmcnt(31)
	v_lshlrev_b32_e32 v2, 16, v134
	v_fma_f32 v3, |v2|, s92, 1.0
	v_rcp_f32_e32 v3, v3
	v_cmp_gt_f32_e32 vcc, 0, v2
	v_add_u32_e32 v134, 0x42, v94
	v_mad_i64_i32 v[8:9], s[6:7], v134, s87, v[92:93]
	v_fmamk_f32 v6, v3, 0x3f07dc22, v236
	v_fmaak_f32 v6, v3, v6, 0x3f35f0e3
	v_fmaak_f32 v6, v3, v6, 0xbe11a98e
	v_fmaak_f32 v6, v3, v6, 0x3e027906
	v_mul_f32_e32 v3, v3, v6
	v_mul_f32_e32 v6, v2, v2
	v_mul_f32_e32 v6, 0xbf38aa3b, v6
	v_exp_f32_e32 v6, v6
	s_nop 0
	v_mul_f32_e32 v3, v6, v3
	v_mul_f32_e32 v6, v3, v2
	v_fma_f32 v3, -v3, v2, v2
	v_cndmask_b32_e32 v2, v3, v6, vcc
	v_add_f32_e32 v3, v16, v4
	v_mul_f32_e32 v2, v2, v3
	v_cvt_pk_bf16_f32 v4, v2, s0
	v_lshlrev_b64 v[2:3], 11, v[58:59]
	v_lshl_add_u64 v[2:3], v[106:107], 0, v[2:3]
	global_store_short v[2:3], v4, off
	s_waitcnt vmcnt(31)
	v_lshlrev_b32_e32 v2, 16, v135
	v_fma_f32 v3, |v2|, s92, 1.0
	v_rcp_f32_e32 v3, v3
	v_cmp_gt_f32_e32 vcc, 0, v2
	v_mad_i64_i32 v[6:7], s[6:7], v136, s87, v[92:93]
	v_fmamk_f32 v4, v3, 0x3f07dc22, v236
	v_fmaak_f32 v4, v3, v4, 0x3f35f0e3
	v_fmaak_f32 v4, v3, v4, 0xbe11a98e
	v_fmaak_f32 v4, v3, v4, 0x3e027906
	v_mul_f32_e32 v3, v3, v4
	v_mul_f32_e32 v4, v2, v2
	v_mul_f32_e32 v4, 0xbf38aa3b, v4
	v_exp_f32_e32 v4, v4
	v_ashrrev_i32_e32 v135, 31, v134
	v_mul_f32_e32 v3, v4, v3
	v_mul_f32_e32 v4, v3, v2
	v_fma_f32 v3, -v3, v2, v2
	v_cndmask_b32_e32 v2, v3, v4, vcc
	v_add_f32_e32 v3, v17, v5
	v_mul_f32_e32 v2, v2, v3
	v_cvt_pk_bf16_f32 v4, v2, s0
	v_lshlrev_b64 v[2:3], 11, v[56:57]
	v_lshl_add_u64 v[2:3], v[106:107], 0, v[2:3]
	global_store_short v[2:3], v4, off
	v_mad_i64_i32 v[2:3], s[6:7], v140, s87, v[92:93]
	v_mad_i64_i32 v[4:5], s[6:7], v138, s87, v[92:93]
	v_mad_i64_i32 v[16:17], s[6:7], v118, s87, v[92:93]
	global_load_dwordx4 v[50:53], v[54:55], off offset:2048
	s_nop 0
	global_load_dwordx4 v[54:57], v[54:55], off offset:3072
	s_nop 0
	global_load_dwordx4 v[58:61], v[70:71], off
	global_load_dwordx4 v[62:65], v[70:71], off offset:1024
	global_load_dwordx4 v[66:69], v[70:71], off offset:2048
	s_nop 0
	global_load_dwordx4 v[70:73], v[70:71], off offset:3072
	s_nop 0
	global_load_ushort v202, v[2:3], off
	global_load_ushort v201, v[4:5], off
	global_load_ushort v200, v[6:7], off
	global_load_ushort v199, v[8:9], off
	global_load_ushort v198, v[10:11], off
	global_load_ushort v197, v[12:13], off
	global_load_ushort v196, v[14:15], off
	global_load_ushort v195, v[16:17], off
	global_load_ushort v194, v[164:165], off
	global_load_ushort v193, v[166:167], off
	global_load_ushort v192, v[168:169], off
	global_load_ushort v191, v[170:171], off
	global_load_ushort v190, v[188:189], off
	s_nop 0
	global_load_ushort v189, v[204:205], off
	global_load_ushort v188, v[206:207], off
	global_load_ushort v130, v[208:209], off
	v_mfma_f32_32x32x16_bf16 v[2:17], v[74:77], v[18:21], 0
	s_waitcnt vmcnt(53)
	v_lshlrev_b32_e32 v74, 16, v187
	v_fma_f32 v75, |v74|, s92, 1.0
	v_rcp_f32_e32 v75, v75
	v_cmp_gt_f32_e32 vcc, 0, v74
	v_add_u32_e32 v170, 0x6f, v94
	v_fmamk_f32 v76, v75, 0x3f07dc22, v236
	v_mfma_f32_32x32x16_bf16 v[2:17], v[78:81], v[22:25], v[2:17]
	v_fmaak_f32 v76, v75, v76, 0x3f35f0e3
	v_fmaak_f32 v76, v75, v76, 0xbe11a98e
	v_fmaak_f32 v76, v75, v76, 0x3e027906
	v_mul_f32_e32 v75, v75, v76
	v_mul_f32_e32 v76, v74, v74
	v_mul_f32_e32 v76, 0xbf38aa3b, v76
	v_exp_f32_e32 v76, v76
	v_mfma_f32_32x32x16_bf16 v[2:17], v[82:85], v[26:29], v[2:17]
	v_add_u32_e32 v168, 0x70, v94
	v_add_u32_e32 v166, 0x71, v94
	v_mul_f32_e32 v75, v76, v75
	v_mul_f32_e32 v76, v75, v74
	v_fma_f32 v75, -v75, v74, v74
	v_cndmask_b32_e32 v82, v75, v76, vcc
	ds_read_b128 v[74:77], v1 offset:128
	ds_read_b128 v[78:81], v1 offset:160
	v_mfma_f32_32x32x16_bf16 v[2:17], v[86:89], v[30:33], v[2:17]
	v_add_u32_e32 v164, 0x72, v94
	v_ashrrev_i32_e32 v171, 31, v170
	v_ashrrev_i32_e32 v169, 31, v168
	v_ashrrev_i32_e32 v167, 31, v166
	v_ashrrev_i32_e32 v165, 31, v164
	s_waitcnt lgkmcnt(1)
	s_nop 5
	v_add_f32_e32 v2, v2, v74
	v_mul_f32_e32 v2, v82, v2
	v_lshlrev_b64 v[82:83], 11, v[162:163]
	v_cvt_pk_bf16_f32 v2, v2, s0
	v_lshl_add_u64 v[82:83], v[106:107], 0, v[82:83]
	global_store_short v[82:83], v2, off
	s_waitcnt vmcnt(53)
	v_lshlrev_b32_e32 v2, 16, v186
	v_fma_f32 v74, |v2|, s92, 1.0
	v_rcp_f32_e32 v74, v74
	v_cmp_gt_f32_e32 vcc, 0, v2
	v_add_f32_e32 v3, v3, v75
	v_add_u32_e32 v162, 0x77, v94
	v_fmamk_f32 v82, v74, 0x3f07dc22, v236
	v_fmaak_f32 v82, v74, v82, 0x3f35f0e3
	v_fmaak_f32 v82, v74, v82, 0xbe11a98e
	v_fmaak_f32 v82, v74, v82, 0x3e027906
	v_mul_f32_e32 v74, v74, v82
	v_mul_f32_e32 v82, v2, v2
	v_mul_f32_e32 v82, 0xbf38aa3b, v82
	v_exp_f32_e32 v82, v82
	v_ashrrev_i32_e32 v163, 31, v162
	v_mul_f32_e32 v74, v82, v74
	v_mul_f32_e32 v82, v74, v2
	v_fma_f32 v74, -v74, v2, v2
	v_cndmask_b32_e32 v2, v74, v82, vcc
	v_mul_f32_e32 v2, v2, v3
	v_cvt_pk_bf16_f32 v74, v2, s0
	v_lshlrev_b64 v[2:3], 11, v[160:161]
	v_lshl_add_u64 v[2:3], v[106:107], 0, v[2:3]
	global_store_short v[2:3], v74, off
	s_waitcnt vmcnt(53)
	v_lshlrev_b32_e32 v2, 16, v185
	v_fma_f32 v3, |v2|, s92, 1.0
	v_rcp_f32_e32 v3, v3
	v_cmp_gt_f32_e32 vcc, 0, v2
	v_add_u32_e32 v160, 0x78, v94
	v_ashrrev_i32_e32 v161, 31, v160
	v_fmamk_f32 v74, v3, 0x3f07dc22, v236
	v_fmaak_f32 v74, v3, v74, 0x3f35f0e3
	v_fmaak_f32 v74, v3, v74, 0xbe11a98e
	v_fmaak_f32 v74, v3, v74, 0x3e027906
	v_mul_f32_e32 v3, v3, v74
	v_mul_f32_e32 v74, v2, v2
	v_mul_f32_e32 v74, 0xbf38aa3b, v74
	v_exp_f32_e32 v74, v74
	s_nop 0
	v_mul_f32_e32 v3, v74, v3
	v_mul_f32_e32 v74, v3, v2
	v_fma_f32 v3, -v3, v2, v2
	v_cndmask_b32_e32 v2, v3, v74, vcc
	v_add_f32_e32 v3, v4, v76
	v_mul_f32_e32 v2, v2, v3
	v_cvt_pk_bf16_f32 v4, v2, s0
	v_lshlrev_b64 v[2:3], 11, v[158:159]
	v_lshl_add_u64 v[2:3], v[106:107], 0, v[2:3]
	global_store_short v[2:3], v4, off
	s_waitcnt vmcnt(53)
	v_lshlrev_b32_e32 v2, 16, v184
	v_fma_f32 v3, |v2|, s92, 1.0
	v_rcp_f32_e32 v3, v3
	v_cmp_gt_f32_e32 vcc, 0, v2
	v_add_u32_e32 v158, 0x79, v94
	v_mad_i64_i32 v[184:185], s[6:7], v160, s87, v[92:93]
	v_fmamk_f32 v4, v3, 0x3f07dc22, v236
	v_fmaak_f32 v4, v3, v4, 0x3f35f0e3
	v_fmaak_f32 v4, v3, v4, 0xbe11a98e
	v_fmaak_f32 v4, v3, v4, 0x3e027906
	v_mul_f32_e32 v3, v3, v4
	v_mul_f32_e32 v4, v2, v2
	v_mul_f32_e32 v4, 0xbf38aa3b, v4
	v_exp_f32_e32 v4, v4
	v_mad_i64_i32 v[186:187], s[6:7], v158, s87, v[92:93]
	v_ashrrev_i32_e32 v159, 31, v158
	v_mul_f32_e32 v3, v4, v3
	v_mul_f32_e32 v4, v3, v2
	v_fma_f32 v3, -v3, v2, v2
	v_cndmask_b32_e32 v2, v3, v4, vcc
	v_add_f32_e32 v3, v5, v77
	v_mul_f32_e32 v2, v2, v3
	v_cvt_pk_bf16_f32 v4, v2, s0
	v_lshlrev_b64 v[2:3], 11, v[156:157]
	v_lshl_add_u64 v[2:3], v[106:107], 0, v[2:3]
	global_store_short v[2:3], v4, off
	s_waitcnt vmcnt(53)
	v_lshlrev_b32_e32 v2, 16, v183
	v_fma_f32 v3, |v2|, s92, 1.0
	v_rcp_f32_e32 v3, v3
	v_cmp_gt_f32_e32 vcc, 0, v2
	v_add_u32_e32 v156, 0x7a, v94
	v_mad_i64_i32 v[214:215], s[6:7], v156, s87, v[92:93]
	v_fmamk_f32 v4, v3, 0x3f07dc22, v236
	v_fmaak_f32 v4, v3, v4, 0x3f35f0e3
	v_fmaak_f32 v4, v3, v4, 0xbe11a98e
	v_fmaak_f32 v4, v3, v4, 0x3e027906
	v_mul_f32_e32 v3, v3, v4
	v_mul_f32_e32 v4, v2, v2
	v_mul_f32_e32 v4, 0xbf38aa3b, v4
	v_exp_f32_e32 v4, v4
	v_ashrrev_i32_e32 v157, 31, v156
	v_mul_f32_e32 v3, v4, v3
	v_mul_f32_e32 v4, v3, v2
	v_fma_f32 v3, -v3, v2, v2
	v_cndmask_b32_e32 v2, v3, v4, vcc
	s_waitcnt lgkmcnt(0)
	v_add_f32_e32 v3, v6, v78
	v_mul_f32_e32 v2, v2, v3
	v_cvt_pk_bf16_f32 v4, v2, s0
	v_lshlrev_b64 v[2:3], 11, v[154:155]
	v_lshl_add_u64 v[2:3], v[106:107], 0, v[2:3]
	global_store_short v[2:3], v4, off
	s_waitcnt vmcnt(53)
	v_lshlrev_b32_e32 v2, 16, v182
	v_fma_f32 v3, |v2|, s92, 1.0
	v_rcp_f32_e32 v3, v3
	v_cmp_gt_f32_e32 vcc, 0, v2
	v_add_u32_e32 v154, 0x60, v94
	v_mad_i64_i32 v[182:183], s[6:7], v162, s87, v[92:93]
	v_fmamk_f32 v4, v3, 0x3f07dc22, v236
	v_fmaak_f32 v4, v3, v4, 0x3f35f0e3
	v_fmaak_f32 v4, v3, v4, 0xbe11a98e
	v_fmaak_f32 v4, v3, v4, 0x3e027906
	v_mul_f32_e32 v3, v3, v4
	v_mul_f32_e32 v4, v2, v2
	v_mul_f32_e32 v4, 0xbf38aa3b, v4
	v_exp_f32_e32 v4, v4
	v_ashrrev_i32_e32 v155, 31, v154
	v_mul_f32_e32 v3, v4, v3
	v_mul_f32_e32 v4, v3, v2
	v_fma_f32 v3, -v3, v2, v2
	v_cndmask_b32_e32 v2, v3, v4, vcc
	v_add_f32_e32 v3, v7, v79
	v_mul_f32_e32 v2, v2, v3
	v_cvt_pk_bf16_f32 v4, v2, s0
	v_lshlrev_b64 v[2:3], 11, v[152:153]
	v_lshl_add_u64 v[2:3], v[106:107], 0, v[2:3]
	global_store_short v[2:3], v4, off
	s_waitcnt vmcnt(53)
	v_lshlrev_b32_e32 v2, 16, v181
	v_fma_f32 v3, |v2|, s92, 1.0
	v_rcp_f32_e32 v3, v3
	v_cmp_gt_f32_e32 vcc, 0, v2
	v_add_u32_e32 v152, 0x61, v94
	v_ashrrev_i32_e32 v153, 31, v152
	v_fmamk_f32 v4, v3, 0x3f07dc22, v236
	v_fmaak_f32 v4, v3, v4, 0x3f35f0e3
	v_fmaak_f32 v4, v3, v4, 0xbe11a98e
	v_fmaak_f32 v4, v3, v4, 0x3e027906
	v_mul_f32_e32 v3, v3, v4
	v_mul_f32_e32 v4, v2, v2
	v_mul_f32_e32 v4, 0xbf38aa3b, v4
	v_exp_f32_e32 v4, v4
	s_nop 0
	v_mul_f32_e32 v3, v4, v3
	v_mul_f32_e32 v4, v3, v2
	v_fma_f32 v3, -v3, v2, v2
	v_cndmask_b32_e32 v2, v3, v4, vcc
	v_add_f32_e32 v3, v8, v80
	v_mul_f32_e32 v2, v2, v3
	v_cvt_pk_bf16_f32 v4, v2, s0
	v_lshlrev_b64 v[2:3], 11, v[150:151]
	v_lshl_add_u64 v[2:3], v[106:107], 0, v[2:3]
	global_store_short v[2:3], v4, off
	s_waitcnt vmcnt(53)
	v_lshlrev_b32_e32 v2, 16, v180
	v_fma_f32 v3, |v2|, s92, 1.0
	v_rcp_f32_e32 v3, v3
	v_cmp_gt_f32_e32 vcc, 0, v2
	v_add_u32_e32 v150, 0x67, v94
	v_mad_i64_i32 v[180:181], s[6:7], v164, s87, v[92:93]
	v_fmamk_f32 v4, v3, 0x3f07dc22, v236
	v_fmaak_f32 v4, v3, v4, 0x3f35f0e3
	v_fmaak_f32 v4, v3, v4, 0xbe11a98e
	v_fmaak_f32 v4, v3, v4, 0x3e027906
	v_mul_f32_e32 v3, v3, v4
	v_mul_f32_e32 v4, v2, v2
	v_mul_f32_e32 v4, 0xbf38aa3b, v4
	v_exp_f32_e32 v4, v4
	v_ashrrev_i32_e32 v151, 31, v150
	v_mul_f32_e32 v3, v4, v3
	v_mul_f32_e32 v4, v3, v2
	v_fma_f32 v3, -v3, v2, v2
	v_cndmask_b32_e32 v2, v3, v4, vcc
	v_add_f32_e32 v3, v9, v81
	v_mul_f32_e32 v2, v2, v3
	v_cvt_pk_bf16_f32 v4, v2, s0
	v_lshlrev_b64 v[2:3], 11, v[148:149]
	v_lshl_add_u64 v[2:3], v[106:107], 0, v[2:3]
	global_store_short v[2:3], v4, off
	s_waitcnt vmcnt(53)
	v_lshlrev_b32_e32 v2, 16, v179
	v_fma_f32 v3, |v2|, s92, 1.0
	v_rcp_f32_e32 v3, v3
	v_cmp_gt_f32_e32 vcc, 0, v2
	v_add_u32_e32 v148, 0x62, v94
	v_mad_i64_i32 v[8:9], s[6:7], v148, s87, v[92:93]
	v_fmamk_f32 v4, v3, 0x3f07dc22, v236
	v_fmaak_f32 v4, v3, v4, 0x3f35f0e3
	v_fmaak_f32 v4, v3, v4, 0xbe11a98e
	v_fmaak_f32 v4, v3, v4, 0x3e027906
	v_mul_f32_e32 v3, v3, v4
	v_mul_f32_e32 v4, v2, v2
	v_mul_f32_e32 v4, 0xbf38aa3b, v4
	v_exp_f32_e32 v4, v4
	v_ashrrev_i32_e32 v149, 31, v148
	v_mul_f32_e32 v3, v4, v3
	v_mul_f32_e32 v4, v3, v2
	v_fma_f32 v3, -v3, v2, v2
	v_cndmask_b32_e32 v6, v3, v4, vcc
	ds_read_b128 v[2:5], v1 offset:192
	s_waitcnt lgkmcnt(0)
	v_add_f32_e32 v2, v10, v2
	v_mul_f32_e32 v2, v6, v2
	v_lshlrev_b64 v[6:7], 11, v[146:147]
	v_cvt_pk_bf16_f32 v2, v2, s0
	v_lshl_add_u64 v[6:7], v[106:107], 0, v[6:7]
	global_store_short v[6:7], v2, off
	s_waitcnt vmcnt(53)
	v_lshlrev_b32_e32 v2, 16, v178
	v_fma_f32 v6, |v2|, s92, 1.0
	v_rcp_f32_e32 v6, v6
	v_cmp_gt_f32_e32 vcc, 0, v2
	v_add_f32_e32 v3, v11, v3
	v_add_u32_e32 v146, 0x68, v94
	v_fmamk_f32 v7, v6, 0x3f07dc22, v236
	v_fmaak_f32 v7, v6, v7, 0x3f35f0e3
	v_fmaak_f32 v7, v6, v7, 0xbe11a98e
	v_fmaak_f32 v7, v6, v7, 0x3e027906
	v_mul_f32_e32 v6, v6, v7
	v_mul_f32_e32 v7, v2, v2
	v_mul_f32_e32 v7, 0xbf38aa3b, v7
	v_exp_f32_e32 v7, v7
	v_mad_i64_i32 v[10:11], s[6:7], v150, s87, v[92:93]
	v_mad_i64_i32 v[178:179], s[6:7], v166, s87, v[92:93]
	v_mul_f32_e32 v6, v7, v6
	v_mul_f32_e32 v7, v6, v2
	v_fma_f32 v6, -v6, v2, v2
	v_cndmask_b32_e32 v2, v6, v7, vcc
	v_mul_f32_e32 v2, v2, v3
	v_cvt_pk_bf16_f32 v6, v2, s0
	v_lshlrev_b64 v[2:3], 11, v[144:145]
	v_lshl_add_u64 v[2:3], v[106:107], 0, v[2:3]
	global_store_short v[2:3], v6, off
	s_waitcnt vmcnt(53)
	v_lshlrev_b32_e32 v2, 16, v177
	v_fma_f32 v3, |v2|, s92, 1.0
	v_rcp_f32_e32 v3, v3
	v_cmp_gt_f32_e32 vcc, 0, v2
	v_add_u32_e32 v144, 0x69, v94
	v_ashrrev_i32_e32 v147, 31, v146
	v_fmamk_f32 v6, v3, 0x3f07dc22, v236
	v_fmaak_f32 v6, v3, v6, 0x3f35f0e3
	v_fmaak_f32 v6, v3, v6, 0xbe11a98e
	v_fmaak_f32 v6, v3, v6, 0x3e027906
	v_mul_f32_e32 v3, v3, v6
	v_mul_f32_e32 v6, v2, v2
	v_mul_f32_e32 v6, 0xbf38aa3b, v6
	v_exp_f32_e32 v6, v6
	v_ashrrev_i32_e32 v145, 31, v144
	v_mul_f32_e32 v3, v6, v3
	v_mul_f32_e32 v6, v3, v2
	v_fma_f32 v3, -v3, v2, v2
	v_cndmask_b32_e32 v2, v3, v6, vcc
	v_add_f32_e32 v3, v12, v4
	v_mul_f32_e32 v2, v2, v3
	v_cvt_pk_bf16_f32 v4, v2, s0
	v_lshlrev_b64 v[2:3], 11, v[142:143]
	v_lshl_add_u64 v[2:3], v[106:107], 0, v[2:3]
	global_store_short v[2:3], v4, off
	s_waitcnt vmcnt(53)
	v_lshlrev_b32_e32 v2, 16, v176
	v_fma_f32 v3, |v2|, s92, 1.0
	v_rcp_f32_e32 v3, v3
	v_cmp_gt_f32_e32 vcc, 0, v2
	v_add_u32_e32 v142, 0x5f, v94
	v_mad_i64_i32 v[176:177], s[6:7], v168, s87, v[92:93]
	v_fmamk_f32 v4, v3, 0x3f07dc22, v236
	v_fmaak_f32 v4, v3, v4, 0x3f35f0e3
	v_fmaak_f32 v4, v3, v4, 0xbe11a98e
	v_fmaak_f32 v4, v3, v4, 0x3e027906
	v_mul_f32_e32 v3, v3, v4
	v_mul_f32_e32 v4, v2, v2
	v_mul_f32_e32 v4, 0xbf38aa3b, v4
	v_exp_f32_e32 v4, v4
	v_ashrrev_i32_e32 v143, 31, v142
	v_mul_f32_e32 v3, v4, v3
	v_mul_f32_e32 v4, v3, v2
	v_fma_f32 v3, -v3, v2, v2
	v_cndmask_b32_e32 v2, v3, v4, vcc
	v_add_f32_e32 v3, v13, v5
	v_mul_f32_e32 v2, v2, v3
	v_cvt_pk_bf16_f32 v4, v2, s0
	v_lshlrev_b64 v[2:3], 11, v[104:105]
	v_lshl_add_u64 v[2:3], v[106:107], 0, v[2:3]
	global_store_short v[2:3], v4, off
	s_waitcnt vmcnt(53)
	v_lshlrev_b32_e32 v2, 16, v175
	v_fma_f32 v3, |v2|, s92, 1.0
	v_rcp_f32_e32 v3, v3
	v_cmp_gt_f32_e32 vcc, 0, v2
	v_mad_i64_i32 v[12:13], s[6:7], v146, s87, v[92:93]
	v_fmamk_f32 v4, v3, 0x3f07dc22, v236
	v_fmaak_f32 v4, v3, v4, 0x3f35f0e3
	v_fmaak_f32 v4, v3, v4, 0xbe11a98e
	v_fmaak_f32 v4, v3, v4, 0x3e027906
	v_mul_f32_e32 v3, v3, v4
	v_mul_f32_e32 v4, v2, v2
	v_mul_f32_e32 v4, 0xbf38aa3b, v4
	v_exp_f32_e32 v4, v4
	s_nop 0
	v_mul_f32_e32 v3, v4, v3
	v_mul_f32_e32 v4, v3, v2
	v_fma_f32 v3, -v3, v2, v2
	v_cndmask_b32_e32 v6, v3, v4, vcc
	ds_read_b128 v[2:5], v1 offset:224
	s_waitcnt lgkmcnt(0)
	v_add_f32_e32 v2, v14, v2
	v_mul_f32_e32 v2, v6, v2
	v_lshlrev_b64 v[6:7], 11, v[102:103]
	v_cvt_pk_bf16_f32 v2, v2, s0
	v_lshl_add_u64 v[6:7], v[106:107], 0, v[6:7]
	global_store_short v[6:7], v2, off
	s_waitcnt vmcnt(53)
	v_lshlrev_b32_e32 v2, 16, v174
	v_fma_f32 v6, |v2|, s92, 1.0
	v_rcp_f32_e32 v6, v6
	v_cmp_gt_f32_e32 vcc, 0, v2
	v_add_f32_e32 v3, v15, v3
	v_mad_i64_i32 v[14:15], s[6:7], v144, s87, v[92:93]
	v_fmamk_f32 v7, v6, 0x3f07dc22, v236
	v_fmaak_f32 v7, v6, v7, 0x3f35f0e3
	v_fmaak_f32 v7, v6, v7, 0xbe11a98e
	v_fmaak_f32 v7, v6, v7, 0x3e027906
	v_mul_f32_e32 v6, v6, v7
	v_mul_f32_e32 v7, v2, v2
	v_mul_f32_e32 v7, 0xbf38aa3b, v7
	v_exp_f32_e32 v7, v7
	v_mad_i64_i32 v[174:175], s[6:7], v170, s87, v[92:93]
	v_mul_f32_e32 v6, v7, v6
	v_mul_f32_e32 v7, v6, v2
	v_fma_f32 v6, -v6, v2, v2
	v_cndmask_b32_e32 v2, v6, v7, vcc
	v_mul_f32_e32 v2, v2, v3
	v_cvt_pk_bf16_f32 v6, v2, s0
	v_lshlrev_b64 v[2:3], 11, v[100:101]
	v_lshl_add_u64 v[2:3], v[106:107], 0, v[2:3]
	global_store_short v[2:3], v6, off
	s_waitcnt vmcnt(53)
	v_lshlrev_b32_e32 v2, 16, v173
	v_fma_f32 v3, |v2|, s92, 1.0
	v_rcp_f32_e32 v3, v3
	v_cmp_gt_f32_e32 vcc, 0, v2
	v_fmamk_f32 v6, v3, 0x3f07dc22, v236
	v_fmaak_f32 v6, v3, v6, 0x3f35f0e3
	v_fmaak_f32 v6, v3, v6, 0xbe11a98e
	v_fmaak_f32 v6, v3, v6, 0x3e027906
	v_mul_f32_e32 v3, v3, v6
	v_mul_f32_e32 v6, v2, v2
	v_mul_f32_e32 v6, 0xbf38aa3b, v6
	v_exp_f32_e32 v6, v6
	s_nop 0
	v_mul_f32_e32 v3, v6, v3
	v_mul_f32_e32 v6, v3, v2
	v_fma_f32 v3, -v3, v2, v2
	v_cndmask_b32_e32 v2, v3, v6, vcc
	v_add_f32_e32 v3, v16, v4
	v_mul_f32_e32 v2, v2, v3
	v_cvt_pk_bf16_f32 v4, v2, s0
	v_lshlrev_b64 v[2:3], 11, v[98:99]
	v_lshl_add_u64 v[2:3], v[106:107], 0, v[2:3]
	global_store_short v[2:3], v4, off
	s_waitcnt vmcnt(53)
	v_lshlrev_b32_e32 v2, 16, v172
	v_fma_f32 v3, |v2|, s92, 1.0
	v_rcp_f32_e32 v3, v3
	v_cmp_gt_f32_e32 vcc, 0, v2
	v_add_u32_e32 v172, 0x6a, v94
	v_mad_i64_i32 v[6:7], s[6:7], v152, s87, v[92:93]
	v_fmamk_f32 v4, v3, 0x3f07dc22, v236
	v_fmaak_f32 v4, v3, v4, 0x3f35f0e3
	v_fmaak_f32 v4, v3, v4, 0xbe11a98e
	v_fmaak_f32 v4, v3, v4, 0x3e027906
	v_mul_f32_e32 v3, v3, v4
	v_mul_f32_e32 v4, v2, v2
	v_mul_f32_e32 v4, 0xbf38aa3b, v4
	v_exp_f32_e32 v4, v4
	v_ashrrev_i32_e32 v173, 31, v172
	v_mul_f32_e32 v3, v4, v3
	v_mul_f32_e32 v4, v3, v2
	v_fma_f32 v3, -v3, v2, v2
	v_cndmask_b32_e32 v2, v3, v4, vcc
	v_add_f32_e32 v3, v17, v5
	v_mul_f32_e32 v2, v2, v3
	v_cvt_pk_bf16_f32 v4, v2, s0
	v_lshlrev_b64 v[2:3], 11, v[96:97]
	v_add_co_u32_e32 v86, vcc, s5, v90
	v_lshl_add_u64 v[2:3], v[106:107], 0, v[2:3]
	s_nop 0
	v_addc_co_u32_e32 v87, vcc, 0, v91, vcc
	global_store_short v[2:3], v4, off
	v_add_co_u32_e32 v102, vcc, s97, v90
	v_mad_i64_i32 v[2:3], s[6:7], v142, s87, v[92:93]
	v_mad_i64_i32 v[4:5], s[6:7], v154, s87, v[92:93]
	v_mad_i64_i32 v[16:17], s[6:7], v172, s87, v[92:93]
	v_addc_co_u32_e32 v103, vcc, 0, v91, vcc
	global_load_dwordx4 v[74:77], v[102:103], off offset:-4096
	global_load_dwordx4 v[78:81], v[86:87], off offset:1024
	global_load_dwordx4 v[82:85], v[86:87], off offset:2048
	s_nop 0
	global_load_dwordx4 v[86:89], v[86:87], off offset:3072
	s_nop 0
	global_load_dwordx4 v[90:93], v[102:103], off
	global_load_dwordx4 v[94:97], v[102:103], off offset:1024
	global_load_dwordx4 v[98:101], v[102:103], off offset:2048
	s_nop 0
	global_load_dwordx4 v[102:105], v[102:103], off offset:3072
	s_nop 0
	global_load_ushort v212, v[2:3], off
	global_load_ushort v211, v[4:5], off
	global_load_ushort v210, v[6:7], off
	global_load_ushort v209, v[8:9], off
	global_load_ushort v208, v[10:11], off
	global_load_ushort v207, v[12:13], off
	global_load_ushort v206, v[14:15], off
	global_load_ushort v205, v[16:17], off
	global_load_ushort v204, v[174:175], off
	global_load_ushort v203, v[176:177], off
	s_nop 0
	global_load_ushort v179, v[178:179], off
	s_nop 0
	global_load_ushort v178, v[180:181], off
	global_load_ushort v177, v[182:183], off
	global_load_ushort v176, v[184:185], off
	global_load_ushort v175, v[186:187], off
	global_load_ushort v174, v[214:215], off
	s_waitcnt vmcnt(61)
	v_mfma_f32_32x32x16_bf16 v[2:17], v[50:53], v[18:21], 0
	s_waitcnt vmcnt(55)
	v_lshlrev_b32_e32 v50, 16, v202
	v_fma_f32 v51, |v50|, s92, 1.0
	v_rcp_f32_e32 v51, v51
	v_cmp_gt_f32_e32 vcc, 0, v50
	v_readlane_b32 s6, v254, 27
	v_fmamk_f32 v52, v51, 0x3f07dc22, v236
	v_mfma_f32_32x32x16_bf16 v[2:17], v[54:57], v[22:25], v[2:17]
	v_fmaak_f32 v52, v51, v52, 0x3f35f0e3
	v_fmaak_f32 v52, v51, v52, 0xbe11a98e
	v_fmaak_f32 v52, v51, v52, 0x3e027906
	v_mul_f32_e32 v51, v51, v52
	v_mul_f32_e32 v52, v50, v50
	v_mul_f32_e32 v52, 0xbf38aa3b, v52
	v_exp_f32_e32 v52, v52
	v_mfma_f32_32x32x16_bf16 v[2:17], v[58:61], v[26:29], v[2:17]
	v_readlane_b32 s5, v254, 33
	s_add_i32 s6, s6, s19
	v_mul_f32_e32 v51, v52, v51
	v_mul_f32_e32 v52, v51, v50
	v_fma_f32 v51, -v51, v50, v50
	v_cndmask_b32_e32 v58, v51, v52, vcc
	ds_read_b128 v[54:57], v1 offset:256
	ds_read_b128 v[50:53], v1 offset:288
	v_mfma_f32_32x32x16_bf16 v[2:17], v[62:65], v[30:33], v[2:17]
	s_add_i32 s17, s17, s5
	s_cmpk_gt_i32 s6, 0xff
	v_mfma_f32_32x32x16_bf16 v[2:17], v[66:69], v[34:37], v[2:17]
	v_mfma_f32_32x32x16_bf16 v[2:17], v[70:73], v[38:41], v[2:17]
	s_waitcnt lgkmcnt(1)
	s_nop 10
	v_add_f32_e32 v2, v2, v54
	v_mul_f32_e32 v2, v58, v2
	v_lshlrev_b64 v[58:59], 11, v[140:141]
	v_cvt_pk_bf16_f32 v2, v2, s0
	v_lshl_add_u64 v[58:59], v[106:107], 0, v[58:59]
	global_store_short v[58:59], v2, off
	s_waitcnt vmcnt(55)
	v_lshlrev_b32_e32 v2, 16, v201
	v_fma_f32 v54, |v2|, s92, 1.0
	v_rcp_f32_e32 v54, v54
	v_cmp_gt_f32_e32 vcc, 0, v2
	v_add_f32_e32 v3, v3, v55
	v_fmamk_f32 v58, v54, 0x3f07dc22, v236
	v_fmaak_f32 v58, v54, v58, 0x3f35f0e3
	v_fmaak_f32 v58, v54, v58, 0xbe11a98e
	v_fmaak_f32 v58, v54, v58, 0x3e027906
	v_mul_f32_e32 v54, v54, v58
	v_mul_f32_e32 v58, v2, v2
	v_mul_f32_e32 v58, 0xbf38aa3b, v58
	v_exp_f32_e32 v58, v58
	s_nop 0
	v_mul_f32_e32 v54, v58, v54
	v_mul_f32_e32 v58, v54, v2
	v_fma_f32 v54, -v54, v2, v2
	v_cndmask_b32_e32 v2, v54, v58, vcc
	v_mul_f32_e32 v2, v2, v3
	v_cvt_pk_bf16_f32 v54, v2, s0
	v_lshlrev_b64 v[2:3], 11, v[138:139]
	v_lshl_add_u64 v[2:3], v[106:107], 0, v[2:3]
	global_store_short v[2:3], v54, off
	s_waitcnt vmcnt(55)
	v_lshlrev_b32_e32 v2, 16, v200
	v_fma_f32 v3, |v2|, s92, 1.0
	v_rcp_f32_e32 v3, v3
	v_cmp_gt_f32_e32 vcc, 0, v2
	v_fmamk_f32 v54, v3, 0x3f07dc22, v236
	v_fmaak_f32 v54, v3, v54, 0x3f35f0e3
	v_fmaak_f32 v54, v3, v54, 0xbe11a98e
	v_fmaak_f32 v54, v3, v54, 0x3e027906
	v_mul_f32_e32 v3, v3, v54
	v_mul_f32_e32 v54, v2, v2
	v_mul_f32_e32 v54, 0xbf38aa3b, v54
	v_exp_f32_e32 v54, v54
	s_nop 0
	v_mul_f32_e32 v3, v54, v3
	v_mul_f32_e32 v54, v3, v2
	v_fma_f32 v3, -v3, v2, v2
	v_cndmask_b32_e32 v2, v3, v54, vcc
	v_add_f32_e32 v3, v4, v56
	v_mul_f32_e32 v2, v2, v3
	v_cvt_pk_bf16_f32 v4, v2, s0
	v_lshlrev_b64 v[2:3], 11, v[136:137]
	v_lshl_add_u64 v[2:3], v[106:107], 0, v[2:3]
	global_store_short v[2:3], v4, off
	s_waitcnt vmcnt(55)
	v_lshlrev_b32_e32 v2, 16, v199
	v_fma_f32 v3, |v2|, s92, 1.0
	v_rcp_f32_e32 v3, v3
	v_cmp_gt_f32_e32 vcc, 0, v2
	v_fmamk_f32 v4, v3, 0x3f07dc22, v236
	v_fmaak_f32 v4, v3, v4, 0x3f35f0e3
	v_fmaak_f32 v4, v3, v4, 0xbe11a98e
	v_fmaak_f32 v4, v3, v4, 0x3e027906
	v_mul_f32_e32 v3, v3, v4
	v_mul_f32_e32 v4, v2, v2
	v_mul_f32_e32 v4, 0xbf38aa3b, v4
	v_exp_f32_e32 v4, v4
	s_nop 0
	v_mul_f32_e32 v3, v4, v3
	v_mul_f32_e32 v4, v3, v2
	v_fma_f32 v3, -v3, v2, v2
	v_cndmask_b32_e32 v2, v3, v4, vcc
	v_add_f32_e32 v3, v5, v57
	v_mul_f32_e32 v2, v2, v3
	v_cvt_pk_bf16_f32 v4, v2, s0
	v_lshlrev_b64 v[2:3], 11, v[134:135]
	v_lshl_add_u64 v[2:3], v[106:107], 0, v[2:3]
	global_store_short v[2:3], v4, off
	s_waitcnt vmcnt(55)
	v_lshlrev_b32_e32 v2, 16, v198
	v_fma_f32 v3, |v2|, s92, 1.0
	v_rcp_f32_e32 v3, v3
	v_cmp_gt_f32_e32 vcc, 0, v2
	v_fmamk_f32 v4, v3, 0x3f07dc22, v236
	v_fmaak_f32 v4, v3, v4, 0x3f35f0e3
	v_fmaak_f32 v4, v3, v4, 0xbe11a98e
	v_fmaak_f32 v4, v3, v4, 0x3e027906
	v_mul_f32_e32 v3, v3, v4
	v_mul_f32_e32 v4, v2, v2
	v_mul_f32_e32 v4, 0xbf38aa3b, v4
	v_exp_f32_e32 v4, v4
	s_nop 0
	v_mul_f32_e32 v3, v4, v3
	v_mul_f32_e32 v4, v3, v2
	v_fma_f32 v3, -v3, v2, v2
	v_cndmask_b32_e32 v2, v3, v4, vcc
	s_waitcnt lgkmcnt(0)
	v_add_f32_e32 v3, v6, v50
	v_mul_f32_e32 v2, v2, v3
	v_cvt_pk_bf16_f32 v4, v2, s0
	v_lshlrev_b64 v[2:3], 11, v[132:133]
	v_lshl_add_u64 v[2:3], v[106:107], 0, v[2:3]
	global_store_short v[2:3], v4, off
	s_waitcnt vmcnt(55)
	v_lshlrev_b32_e32 v2, 16, v197
	v_fma_f32 v3, |v2|, s92, 1.0
	v_rcp_f32_e32 v3, v3
	v_cmp_gt_f32_e32 vcc, 0, v2
	v_fmamk_f32 v4, v3, 0x3f07dc22, v236
	v_fmaak_f32 v4, v3, v4, 0x3f35f0e3
	v_fmaak_f32 v4, v3, v4, 0xbe11a98e
	v_fmaak_f32 v4, v3, v4, 0x3e027906
	v_mul_f32_e32 v3, v3, v4
	v_mul_f32_e32 v4, v2, v2
	v_mul_f32_e32 v4, 0xbf38aa3b, v4
	v_exp_f32_e32 v4, v4
	s_nop 0
	v_mul_f32_e32 v3, v4, v3
	v_mul_f32_e32 v4, v3, v2
	v_fma_f32 v3, -v3, v2, v2
	v_cndmask_b32_e32 v2, v3, v4, vcc
	v_add_f32_e32 v3, v7, v51
	v_mul_f32_e32 v2, v2, v3
	v_cvt_pk_bf16_f32 v4, v2, s0
	v_lshlrev_b64 v[2:3], 11, v[126:127]
	v_lshl_add_u64 v[2:3], v[106:107], 0, v[2:3]
	global_store_short v[2:3], v4, off
	s_waitcnt vmcnt(55)
	v_lshlrev_b32_e32 v2, 16, v196
	v_fma_f32 v3, |v2|, s92, 1.0
	v_rcp_f32_e32 v3, v3
	v_cmp_gt_f32_e32 vcc, 0, v2
	v_fmamk_f32 v4, v3, 0x3f07dc22, v236
	v_fmaak_f32 v4, v3, v4, 0x3f35f0e3
	v_fmaak_f32 v4, v3, v4, 0xbe11a98e
	v_fmaak_f32 v4, v3, v4, 0x3e027906
	v_mul_f32_e32 v3, v3, v4
	v_mul_f32_e32 v4, v2, v2
	v_mul_f32_e32 v4, 0xbf38aa3b, v4
	v_exp_f32_e32 v4, v4
	s_nop 0
	v_mul_f32_e32 v3, v4, v3
	v_mul_f32_e32 v4, v3, v2
	v_fma_f32 v3, -v3, v2, v2
	v_cndmask_b32_e32 v2, v3, v4, vcc
	v_add_f32_e32 v3, v8, v52
	v_mul_f32_e32 v2, v2, v3
	v_cvt_pk_bf16_f32 v4, v2, s0
	v_lshlrev_b64 v[2:3], 11, v[122:123]
	v_lshl_add_u64 v[2:3], v[106:107], 0, v[2:3]
	global_store_short v[2:3], v4, off
	s_waitcnt vmcnt(55)
	v_lshlrev_b32_e32 v2, 16, v195
	v_fma_f32 v3, |v2|, s92, 1.0
	v_rcp_f32_e32 v3, v3
	v_cmp_gt_f32_e32 vcc, 0, v2
	v_fmamk_f32 v4, v3, 0x3f07dc22, v236
	v_fmaak_f32 v4, v3, v4, 0x3f35f0e3
	v_fmaak_f32 v4, v3, v4, 0xbe11a98e
	v_fmaak_f32 v4, v3, v4, 0x3e027906
	v_mul_f32_e32 v3, v3, v4
	v_mul_f32_e32 v4, v2, v2
	v_mul_f32_e32 v4, 0xbf38aa3b, v4
	v_exp_f32_e32 v4, v4
	s_nop 0
	v_mul_f32_e32 v3, v4, v3
	v_mul_f32_e32 v4, v3, v2
	v_fma_f32 v3, -v3, v2, v2
	v_cndmask_b32_e32 v2, v3, v4, vcc
	v_add_f32_e32 v3, v9, v53
	v_mul_f32_e32 v2, v2, v3
	v_cvt_pk_bf16_f32 v4, v2, s0
	v_lshlrev_b64 v[2:3], 11, v[118:119]
	v_lshl_add_u64 v[2:3], v[106:107], 0, v[2:3]
	global_store_short v[2:3], v4, off
	s_waitcnt vmcnt(55)
	v_lshlrev_b32_e32 v2, 16, v194
	v_fma_f32 v3, |v2|, s92, 1.0
	v_rcp_f32_e32 v3, v3
	v_cmp_gt_f32_e32 vcc, 0, v2
	v_fmamk_f32 v4, v3, 0x3f07dc22, v236
	v_fmaak_f32 v4, v3, v4, 0x3f35f0e3
	v_fmaak_f32 v4, v3, v4, 0xbe11a98e
	v_fmaak_f32 v4, v3, v4, 0x3e027906
	v_mul_f32_e32 v3, v3, v4
	v_mul_f32_e32 v4, v2, v2
	v_mul_f32_e32 v4, 0xbf38aa3b, v4
	v_exp_f32_e32 v4, v4
	s_nop 0
	v_mul_f32_e32 v3, v4, v3
	v_mul_f32_e32 v4, v3, v2
	v_fma_f32 v3, -v3, v2, v2
	v_cndmask_b32_e32 v6, v3, v4, vcc
	ds_read_b128 v[2:5], v1 offset:320
	s_waitcnt lgkmcnt(0)
	v_add_f32_e32 v2, v10, v2
	v_mul_f32_e32 v2, v6, v2
	v_lshlrev_b64 v[6:7], 11, v[116:117]
	v_cvt_pk_bf16_f32 v2, v2, s0
	v_lshl_add_u64 v[6:7], v[106:107], 0, v[6:7]
	global_store_short v[6:7], v2, off
	s_waitcnt vmcnt(55)
	v_lshlrev_b32_e32 v2, 16, v193
	v_fma_f32 v6, |v2|, s92, 1.0
	v_rcp_f32_e32 v6, v6
	v_cmp_gt_f32_e32 vcc, 0, v2
	v_add_f32_e32 v3, v11, v3
	v_fmamk_f32 v7, v6, 0x3f07dc22, v236
	v_fmaak_f32 v7, v6, v7, 0x3f35f0e3
	v_fmaak_f32 v7, v6, v7, 0xbe11a98e
	v_fmaak_f32 v7, v6, v7, 0x3e027906
	v_mul_f32_e32 v6, v6, v7
	v_mul_f32_e32 v7, v2, v2
	v_mul_f32_e32 v7, 0xbf38aa3b, v7
	v_exp_f32_e32 v7, v7
	s_nop 0
	v_mul_f32_e32 v6, v7, v6
	v_mul_f32_e32 v7, v6, v2
	v_fma_f32 v6, -v6, v2, v2
	v_cndmask_b32_e32 v2, v6, v7, vcc
	v_mul_f32_e32 v2, v2, v3
	v_cvt_pk_bf16_f32 v6, v2, s0
	v_lshlrev_b64 v[2:3], 11, v[112:113]
	v_lshl_add_u64 v[2:3], v[106:107], 0, v[2:3]
	global_store_short v[2:3], v6, off
	s_waitcnt vmcnt(55)
	v_lshlrev_b32_e32 v2, 16, v192
	v_fma_f32 v3, |v2|, s92, 1.0
	v_rcp_f32_e32 v3, v3
	v_cmp_gt_f32_e32 vcc, 0, v2
	v_fmamk_f32 v6, v3, 0x3f07dc22, v236
	v_fmaak_f32 v6, v3, v6, 0x3f35f0e3
	v_fmaak_f32 v6, v3, v6, 0xbe11a98e
	v_fmaak_f32 v6, v3, v6, 0x3e027906
	v_mul_f32_e32 v3, v3, v6
	v_mul_f32_e32 v6, v2, v2
	v_mul_f32_e32 v6, 0xbf38aa3b, v6
	v_exp_f32_e32 v6, v6
	s_nop 0
	v_mul_f32_e32 v3, v6, v3
	v_mul_f32_e32 v6, v3, v2
	v_fma_f32 v3, -v3, v2, v2
	v_cndmask_b32_e32 v2, v3, v6, vcc
	v_add_f32_e32 v3, v12, v4
	v_mul_f32_e32 v2, v2, v3
	v_cvt_pk_bf16_f32 v4, v2, s0
	v_lshlrev_b64 v[2:3], 11, v[110:111]
	v_lshl_add_u64 v[2:3], v[106:107], 0, v[2:3]
	global_store_short v[2:3], v4, off
	s_waitcnt vmcnt(55)
	v_lshlrev_b32_e32 v2, 16, v191
	v_fma_f32 v3, |v2|, s92, 1.0
	v_rcp_f32_e32 v3, v3
	v_cmp_gt_f32_e32 vcc, 0, v2
	v_fmamk_f32 v4, v3, 0x3f07dc22, v236
	v_fmaak_f32 v4, v3, v4, 0x3f35f0e3
	v_fmaak_f32 v4, v3, v4, 0xbe11a98e
	v_fmaak_f32 v4, v3, v4, 0x3e027906
	v_mul_f32_e32 v3, v3, v4
	v_mul_f32_e32 v4, v2, v2
	v_mul_f32_e32 v4, 0xbf38aa3b, v4
	v_exp_f32_e32 v4, v4
	s_nop 0
	v_mul_f32_e32 v3, v4, v3
	v_mul_f32_e32 v4, v3, v2
	v_fma_f32 v3, -v3, v2, v2
	v_cndmask_b32_e32 v2, v3, v4, vcc
	v_add_f32_e32 v3, v13, v5
	v_mul_f32_e32 v2, v2, v3
	v_cvt_pk_bf16_f32 v4, v2, s0
	v_lshlrev_b64 v[2:3], 11, v[108:109]
	v_lshl_add_u64 v[2:3], v[106:107], 0, v[2:3]
	global_store_short v[2:3], v4, off
	s_waitcnt vmcnt(55)
	v_lshlrev_b32_e32 v2, 16, v190
	v_fma_f32 v3, |v2|, s92, 1.0
	v_rcp_f32_e32 v3, v3
	v_cmp_gt_f32_e32 vcc, 0, v2
	v_fmamk_f32 v4, v3, 0x3f07dc22, v236
	v_fmaak_f32 v4, v3, v4, 0x3f35f0e3
	v_fmaak_f32 v4, v3, v4, 0xbe11a98e
	v_fmaak_f32 v4, v3, v4, 0x3e027906
	v_mul_f32_e32 v3, v3, v4
	v_mul_f32_e32 v4, v2, v2
	v_mul_f32_e32 v4, 0xbf38aa3b, v4
	v_exp_f32_e32 v4, v4
	s_nop 0
	v_mul_f32_e32 v3, v4, v3
	v_mul_f32_e32 v4, v3, v2
	v_fma_f32 v3, -v3, v2, v2
	v_cndmask_b32_e32 v6, v3, v4, vcc
	ds_read_b128 v[2:5], v1 offset:352
	s_waitcnt lgkmcnt(0)
	v_add_f32_e32 v2, v14, v2
	v_mul_f32_e32 v2, v6, v2
	v_lshlrev_b64 v[6:7], 11, v[128:129]
	v_cvt_pk_bf16_f32 v2, v2, s0
	v_lshl_add_u64 v[6:7], v[106:107], 0, v[6:7]
	global_store_short v[6:7], v2, off
	s_waitcnt vmcnt(55)
	v_lshlrev_b32_e32 v2, 16, v189
	v_fma_f32 v6, |v2|, s92, 1.0
	v_rcp_f32_e32 v6, v6
	v_cmp_gt_f32_e32 vcc, 0, v2
	v_add_f32_e32 v3, v15, v3
	v_fmamk_f32 v7, v6, 0x3f07dc22, v236
	v_fmaak_f32 v7, v6, v7, 0x3f35f0e3
	v_fmaak_f32 v7, v6, v7, 0xbe11a98e
	v_fmaak_f32 v7, v6, v7, 0x3e027906
	v_mul_f32_e32 v6, v6, v7
	v_mul_f32_e32 v7, v2, v2
	v_mul_f32_e32 v7, 0xbf38aa3b, v7
	v_exp_f32_e32 v7, v7
	s_nop 0
	v_mul_f32_e32 v6, v7, v6
	v_mul_f32_e32 v7, v6, v2
	v_fma_f32 v6, -v6, v2, v2
	v_cndmask_b32_e32 v2, v6, v7, vcc
	v_mul_f32_e32 v2, v2, v3
	v_cvt_pk_bf16_f32 v6, v2, s0
	v_lshlrev_b64 v[2:3], 11, v[124:125]
	v_lshl_add_u64 v[2:3], v[106:107], 0, v[2:3]
	global_store_short v[2:3], v6, off
	s_waitcnt vmcnt(55)
	v_lshlrev_b32_e32 v2, 16, v188
	v_fma_f32 v3, |v2|, s92, 1.0
	v_rcp_f32_e32 v3, v3
	v_cmp_gt_f32_e32 vcc, 0, v2
	v_fmamk_f32 v6, v3, 0x3f07dc22, v236
	v_fmaak_f32 v6, v3, v6, 0x3f35f0e3
	v_fmaak_f32 v6, v3, v6, 0xbe11a98e
	v_fmaak_f32 v6, v3, v6, 0x3e027906
	v_mul_f32_e32 v3, v3, v6
	v_mul_f32_e32 v6, v2, v2
	v_mul_f32_e32 v6, 0xbf38aa3b, v6
	v_exp_f32_e32 v6, v6
	s_nop 0
	v_mul_f32_e32 v3, v6, v3
	v_mul_f32_e32 v6, v3, v2
	v_fma_f32 v3, -v3, v2, v2
	v_cndmask_b32_e32 v2, v3, v6, vcc
	v_add_f32_e32 v3, v16, v4
	v_mul_f32_e32 v2, v2, v3
	v_cvt_pk_bf16_f32 v4, v2, s0
	v_lshlrev_b64 v[2:3], 11, v[120:121]
	v_lshl_add_u64 v[2:3], v[106:107], 0, v[2:3]
	global_store_short v[2:3], v4, off
	s_waitcnt vmcnt(55)
	v_lshlrev_b32_e32 v2, 16, v130
	v_fma_f32 v3, |v2|, s92, 1.0
	v_rcp_f32_e32 v3, v3
	v_cmp_gt_f32_e32 vcc, 0, v2
	v_fmamk_f32 v4, v3, 0x3f07dc22, v236
	v_fmaak_f32 v4, v3, v4, 0x3f35f0e3
	v_fmaak_f32 v4, v3, v4, 0xbe11a98e
	v_fmaak_f32 v4, v3, v4, 0x3e027906
	v_mul_f32_e32 v3, v3, v4
	v_mul_f32_e32 v4, v2, v2
	v_mul_f32_e32 v4, 0xbf38aa3b, v4
	v_exp_f32_e32 v4, v4
	s_nop 0
	v_mul_f32_e32 v3, v4, v3
	v_mul_f32_e32 v4, v3, v2
	v_fma_f32 v3, -v3, v2, v2
	v_cndmask_b32_e32 v2, v3, v4, vcc
	v_add_f32_e32 v3, v17, v5
	v_mul_f32_e32 v2, v2, v3
	v_cvt_pk_bf16_f32 v4, v2, s0
	v_lshlrev_b64 v[2:3], 11, v[114:115]
	v_lshl_add_u64 v[2:3], v[106:107], 0, v[2:3]
	global_store_short v[2:3], v4, off
	s_waitcnt vmcnt(39)
	v_mfma_f32_32x32x16_bf16 v[2:17], v[74:77], v[18:21], 0
	s_waitcnt vmcnt(31)
	v_lshlrev_b32_e32 v18, 16, v212
	v_fma_f32 v19, |v18|, s92, 1.0
	v_rcp_f32_e32 v19, v19
	v_cmp_gt_f32_e32 vcc, 0, v18
	v_fmamk_f32 v20, v19, 0x3f07dc22, v236
	v_mfma_f32_32x32x16_bf16 v[2:17], v[78:81], v[22:25], v[2:17]
	v_fmaak_f32 v20, v19, v20, 0x3f35f0e3
	v_fmaak_f32 v20, v19, v20, 0xbe11a98e
	v_fmaak_f32 v20, v19, v20, 0x3e027906
	v_mul_f32_e32 v19, v19, v20
	v_mul_f32_e32 v20, v18, v18
	v_mul_f32_e32 v20, 0xbf38aa3b, v20
	v_exp_f32_e32 v20, v20
	v_mfma_f32_32x32x16_bf16 v[2:17], v[82:85], v[26:29], v[2:17]
	v_mul_f32_e32 v19, v20, v19
	v_mul_f32_e32 v20, v19, v18
	v_fma_f32 v19, -v19, v18, v18
	v_cndmask_b32_e32 v26, v19, v20, vcc
	ds_read_b128 v[22:25], v1 offset:384
	ds_read_b128 v[18:21], v1 offset:416
	v_mfma_f32_32x32x16_bf16 v[2:17], v[86:89], v[30:33], v[2:17]
	v_mfma_f32_32x32x16_bf16 v[2:17], v[90:93], v[34:37], v[2:17]
	v_mfma_f32_32x32x16_bf16 v[2:17], v[94:97], v[38:41], v[2:17]
	v_mfma_f32_32x32x16_bf16 v[2:17], v[98:101], v[42:45], v[2:17]
	v_mfma_f32_32x32x16_bf16 v[2:17], v[102:105], v[46:49], v[2:17]
	s_waitcnt lgkmcnt(1)
	s_nop 10
	v_add_f32_e32 v2, v2, v22
	v_mul_f32_e32 v2, v26, v2
	v_lshlrev_b64 v[26:27], 11, v[142:143]
	v_cvt_pk_bf16_f32 v2, v2, s0
	v_lshl_add_u64 v[26:27], v[106:107], 0, v[26:27]
	global_store_short v[26:27], v2, off
	s_waitcnt vmcnt(31)
	v_lshlrev_b32_e32 v2, 16, v211
	v_fma_f32 v22, |v2|, s92, 1.0
	v_rcp_f32_e32 v22, v22
	v_cmp_gt_f32_e32 vcc, 0, v2
	v_add_f32_e32 v3, v3, v23
	v_fmamk_f32 v26, v22, 0x3f07dc22, v236
	v_fmaak_f32 v26, v22, v26, 0x3f35f0e3
	v_fmaak_f32 v26, v22, v26, 0xbe11a98e
	v_fmaak_f32 v26, v22, v26, 0x3e027906
	v_mul_f32_e32 v22, v22, v26
	v_mul_f32_e32 v26, v2, v2
	v_mul_f32_e32 v26, 0xbf38aa3b, v26
	v_exp_f32_e32 v26, v26
	s_nop 0
	v_mul_f32_e32 v22, v26, v22
	v_mul_f32_e32 v26, v22, v2
	v_fma_f32 v22, -v22, v2, v2
	v_cndmask_b32_e32 v2, v22, v26, vcc
	v_mul_f32_e32 v2, v2, v3
	v_cvt_pk_bf16_f32 v22, v2, s0
	v_lshlrev_b64 v[2:3], 11, v[154:155]
	v_lshl_add_u64 v[2:3], v[106:107], 0, v[2:3]
	global_store_short v[2:3], v22, off
	s_waitcnt vmcnt(31)
	v_lshlrev_b32_e32 v2, 16, v210
	v_fma_f32 v3, |v2|, s92, 1.0
	v_rcp_f32_e32 v3, v3
	v_cmp_gt_f32_e32 vcc, 0, v2
	v_fmamk_f32 v22, v3, 0x3f07dc22, v236
	v_fmaak_f32 v22, v3, v22, 0x3f35f0e3
	v_fmaak_f32 v22, v3, v22, 0xbe11a98e
	v_fmaak_f32 v22, v3, v22, 0x3e027906
	v_mul_f32_e32 v3, v3, v22
	v_mul_f32_e32 v22, v2, v2
	v_mul_f32_e32 v22, 0xbf38aa3b, v22
	v_exp_f32_e32 v22, v22
	s_nop 0
	v_mul_f32_e32 v3, v22, v3
	v_mul_f32_e32 v22, v3, v2
	v_fma_f32 v3, -v3, v2, v2
	v_cndmask_b32_e32 v2, v3, v22, vcc
	v_add_f32_e32 v3, v4, v24
	v_mul_f32_e32 v2, v2, v3
	v_cvt_pk_bf16_f32 v4, v2, s0
	v_lshlrev_b64 v[2:3], 11, v[152:153]
	v_lshl_add_u64 v[2:3], v[106:107], 0, v[2:3]
	global_store_short v[2:3], v4, off
	s_waitcnt vmcnt(31)
	v_lshlrev_b32_e32 v2, 16, v209
	v_fma_f32 v3, |v2|, s92, 1.0
	v_rcp_f32_e32 v3, v3
	v_cmp_gt_f32_e32 vcc, 0, v2
	v_fmamk_f32 v4, v3, 0x3f07dc22, v236
	v_fmaak_f32 v4, v3, v4, 0x3f35f0e3
	v_fmaak_f32 v4, v3, v4, 0xbe11a98e
	v_fmaak_f32 v4, v3, v4, 0x3e027906
	v_mul_f32_e32 v3, v3, v4
	v_mul_f32_e32 v4, v2, v2
	v_mul_f32_e32 v4, 0xbf38aa3b, v4
	v_exp_f32_e32 v4, v4
	s_nop 0
	v_mul_f32_e32 v3, v4, v3
	v_mul_f32_e32 v4, v3, v2
	v_fma_f32 v3, -v3, v2, v2
	v_cndmask_b32_e32 v2, v3, v4, vcc
	v_add_f32_e32 v3, v5, v25
	v_mul_f32_e32 v2, v2, v3
	v_cvt_pk_bf16_f32 v4, v2, s0
	v_lshlrev_b64 v[2:3], 11, v[148:149]
	v_lshl_add_u64 v[2:3], v[106:107], 0, v[2:3]
	global_store_short v[2:3], v4, off
	s_waitcnt vmcnt(31)
	v_lshlrev_b32_e32 v2, 16, v208
	v_fma_f32 v3, |v2|, s92, 1.0
	v_rcp_f32_e32 v3, v3
	v_cmp_gt_f32_e32 vcc, 0, v2
	v_fmamk_f32 v4, v3, 0x3f07dc22, v236
	v_fmaak_f32 v4, v3, v4, 0x3f35f0e3
	v_fmaak_f32 v4, v3, v4, 0xbe11a98e
	v_fmaak_f32 v4, v3, v4, 0x3e027906
	v_mul_f32_e32 v3, v3, v4
	v_mul_f32_e32 v4, v2, v2
	v_mul_f32_e32 v4, 0xbf38aa3b, v4
	v_exp_f32_e32 v4, v4
	s_nop 0
	v_mul_f32_e32 v3, v4, v3
	v_mul_f32_e32 v4, v3, v2
	v_fma_f32 v3, -v3, v2, v2
	v_cndmask_b32_e32 v2, v3, v4, vcc
	s_waitcnt lgkmcnt(0)
	v_add_f32_e32 v3, v6, v18
	v_mul_f32_e32 v2, v2, v3
	v_cvt_pk_bf16_f32 v4, v2, s0
	v_lshlrev_b64 v[2:3], 11, v[150:151]
	v_lshl_add_u64 v[2:3], v[106:107], 0, v[2:3]
	global_store_short v[2:3], v4, off
	s_waitcnt vmcnt(31)
	v_lshlrev_b32_e32 v2, 16, v207
	v_fma_f32 v3, |v2|, s92, 1.0
	v_rcp_f32_e32 v3, v3
	v_cmp_gt_f32_e32 vcc, 0, v2
	v_fmamk_f32 v4, v3, 0x3f07dc22, v236
	v_fmaak_f32 v4, v3, v4, 0x3f35f0e3
	v_fmaak_f32 v4, v3, v4, 0xbe11a98e
	v_fmaak_f32 v4, v3, v4, 0x3e027906
	v_mul_f32_e32 v3, v3, v4
	v_mul_f32_e32 v4, v2, v2
	v_mul_f32_e32 v4, 0xbf38aa3b, v4
	v_exp_f32_e32 v4, v4
	s_nop 0
	v_mul_f32_e32 v3, v4, v3
	v_mul_f32_e32 v4, v3, v2
	v_fma_f32 v3, -v3, v2, v2
	v_cndmask_b32_e32 v2, v3, v4, vcc
	v_add_f32_e32 v3, v7, v19
	v_mul_f32_e32 v2, v2, v3
	v_cvt_pk_bf16_f32 v4, v2, s0
	v_lshlrev_b64 v[2:3], 11, v[146:147]
	v_lshl_add_u64 v[2:3], v[106:107], 0, v[2:3]
	global_store_short v[2:3], v4, off
	s_waitcnt vmcnt(31)
	v_lshlrev_b32_e32 v2, 16, v206
	v_fma_f32 v3, |v2|, s92, 1.0
	v_rcp_f32_e32 v3, v3
	v_cmp_gt_f32_e32 vcc, 0, v2
	v_fmamk_f32 v4, v3, 0x3f07dc22, v236
	v_fmaak_f32 v4, v3, v4, 0x3f35f0e3
	v_fmaak_f32 v4, v3, v4, 0xbe11a98e
	v_fmaak_f32 v4, v3, v4, 0x3e027906
	v_mul_f32_e32 v3, v3, v4
	v_mul_f32_e32 v4, v2, v2
	v_mul_f32_e32 v4, 0xbf38aa3b, v4
	v_exp_f32_e32 v4, v4
	s_nop 0
	v_mul_f32_e32 v3, v4, v3
	v_mul_f32_e32 v4, v3, v2
	v_fma_f32 v3, -v3, v2, v2
	v_cndmask_b32_e32 v2, v3, v4, vcc
	v_add_f32_e32 v3, v8, v20
	v_mul_f32_e32 v2, v2, v3
	v_cvt_pk_bf16_f32 v4, v2, s0
	v_lshlrev_b64 v[2:3], 11, v[144:145]
	v_lshl_add_u64 v[2:3], v[106:107], 0, v[2:3]
	global_store_short v[2:3], v4, off
	s_waitcnt vmcnt(31)
	v_lshlrev_b32_e32 v2, 16, v205
	v_fma_f32 v3, |v2|, s92, 1.0
	v_rcp_f32_e32 v3, v3
	v_cmp_gt_f32_e32 vcc, 0, v2
	v_fmamk_f32 v4, v3, 0x3f07dc22, v236
	v_fmaak_f32 v4, v3, v4, 0x3f35f0e3
	v_fmaak_f32 v4, v3, v4, 0xbe11a98e
	v_fmaak_f32 v4, v3, v4, 0x3e027906
	v_mul_f32_e32 v3, v3, v4
	v_mul_f32_e32 v4, v2, v2
	v_mul_f32_e32 v4, 0xbf38aa3b, v4
	v_exp_f32_e32 v4, v4
	s_nop 0
	v_mul_f32_e32 v3, v4, v3
	v_mul_f32_e32 v4, v3, v2
	v_fma_f32 v3, -v3, v2, v2
	v_cndmask_b32_e32 v2, v3, v4, vcc
	v_add_f32_e32 v3, v9, v21
	v_mul_f32_e32 v2, v2, v3
	v_cvt_pk_bf16_f32 v4, v2, s0
	v_lshlrev_b64 v[2:3], 11, v[172:173]
	v_lshl_add_u64 v[2:3], v[106:107], 0, v[2:3]
	global_store_short v[2:3], v4, off
	s_waitcnt vmcnt(31)
	v_lshlrev_b32_e32 v2, 16, v204
	v_fma_f32 v3, |v2|, s92, 1.0
	v_rcp_f32_e32 v3, v3
	v_cmp_gt_f32_e32 vcc, 0, v2
	v_fmamk_f32 v4, v3, 0x3f07dc22, v236
	v_fmaak_f32 v4, v3, v4, 0x3f35f0e3
	v_fmaak_f32 v4, v3, v4, 0xbe11a98e
	v_fmaak_f32 v4, v3, v4, 0x3e027906
	v_mul_f32_e32 v3, v3, v4
	v_mul_f32_e32 v4, v2, v2
	v_mul_f32_e32 v4, 0xbf38aa3b, v4
	v_exp_f32_e32 v4, v4
	s_nop 0
	v_mul_f32_e32 v3, v4, v3
	v_mul_f32_e32 v4, v3, v2
	v_fma_f32 v3, -v3, v2, v2
	v_cndmask_b32_e32 v6, v3, v4, vcc
	ds_read_b128 v[2:5], v1 offset:448
	s_waitcnt lgkmcnt(0)
	v_add_f32_e32 v2, v10, v2
	v_mul_f32_e32 v2, v6, v2
	v_lshlrev_b64 v[6:7], 11, v[170:171]
	v_cvt_pk_bf16_f32 v2, v2, s0
	v_lshl_add_u64 v[6:7], v[106:107], 0, v[6:7]
	global_store_short v[6:7], v2, off
	s_waitcnt vmcnt(31)
	v_lshlrev_b32_e32 v2, 16, v203
	v_fma_f32 v6, |v2|, s92, 1.0
	v_rcp_f32_e32 v6, v6
	v_cmp_gt_f32_e32 vcc, 0, v2
	v_add_f32_e32 v3, v11, v3
	v_fmamk_f32 v7, v6, 0x3f07dc22, v236
	v_fmaak_f32 v7, v6, v7, 0x3f35f0e3
	v_fmaak_f32 v7, v6, v7, 0xbe11a98e
	v_fmaak_f32 v7, v6, v7, 0x3e027906
	v_mul_f32_e32 v6, v6, v7
	v_mul_f32_e32 v7, v2, v2
	v_mul_f32_e32 v7, 0xbf38aa3b, v7
	v_exp_f32_e32 v7, v7
	s_nop 0
	v_mul_f32_e32 v6, v7, v6
	v_mul_f32_e32 v7, v6, v2
	v_fma_f32 v6, -v6, v2, v2
	v_cndmask_b32_e32 v2, v6, v7, vcc
	v_mul_f32_e32 v2, v2, v3
	v_cvt_pk_bf16_f32 v6, v2, s0
	v_lshlrev_b64 v[2:3], 11, v[168:169]
	v_lshl_add_u64 v[2:3], v[106:107], 0, v[2:3]
	global_store_short v[2:3], v6, off
	s_waitcnt vmcnt(31)
	v_lshlrev_b32_e32 v2, 16, v179
	v_fma_f32 v3, |v2|, s92, 1.0
	v_rcp_f32_e32 v3, v3
	v_cmp_gt_f32_e32 vcc, 0, v2
	v_fmamk_f32 v6, v3, 0x3f07dc22, v236
	v_fmaak_f32 v6, v3, v6, 0x3f35f0e3
	v_fmaak_f32 v6, v3, v6, 0xbe11a98e
	v_fmaak_f32 v6, v3, v6, 0x3e027906
	v_mul_f32_e32 v3, v3, v6
	v_mul_f32_e32 v6, v2, v2
	v_mul_f32_e32 v6, 0xbf38aa3b, v6
	v_exp_f32_e32 v6, v6
	s_nop 0
	v_mul_f32_e32 v3, v6, v3
	v_mul_f32_e32 v6, v3, v2
	v_fma_f32 v3, -v3, v2, v2
	v_cndmask_b32_e32 v2, v3, v6, vcc
	v_add_f32_e32 v3, v12, v4
	v_mul_f32_e32 v2, v2, v3
	v_cvt_pk_bf16_f32 v4, v2, s0
	v_lshlrev_b64 v[2:3], 11, v[166:167]
	v_lshl_add_u64 v[2:3], v[106:107], 0, v[2:3]
	global_store_short v[2:3], v4, off
	s_waitcnt vmcnt(31)
	v_lshlrev_b32_e32 v2, 16, v178
	v_fma_f32 v3, |v2|, s92, 1.0
	v_rcp_f32_e32 v3, v3
	v_cmp_gt_f32_e32 vcc, 0, v2
	v_fmamk_f32 v4, v3, 0x3f07dc22, v236
	v_fmaak_f32 v4, v3, v4, 0x3f35f0e3
	v_fmaak_f32 v4, v3, v4, 0xbe11a98e
	v_fmaak_f32 v4, v3, v4, 0x3e027906
	v_mul_f32_e32 v3, v3, v4
	v_mul_f32_e32 v4, v2, v2
	v_mul_f32_e32 v4, 0xbf38aa3b, v4
	v_exp_f32_e32 v4, v4
	s_nop 0
	v_mul_f32_e32 v3, v4, v3
	v_mul_f32_e32 v4, v3, v2
	v_fma_f32 v3, -v3, v2, v2
	v_cndmask_b32_e32 v2, v3, v4, vcc
	v_add_f32_e32 v3, v13, v5
	v_mul_f32_e32 v2, v2, v3
	v_cvt_pk_bf16_f32 v4, v2, s0
	v_lshlrev_b64 v[2:3], 11, v[164:165]
	v_lshl_add_u64 v[2:3], v[106:107], 0, v[2:3]
	global_store_short v[2:3], v4, off
	s_waitcnt vmcnt(31)
	v_lshlrev_b32_e32 v2, 16, v177
	v_fma_f32 v3, |v2|, s92, 1.0
	v_rcp_f32_e32 v3, v3
	v_cmp_gt_f32_e32 vcc, 0, v2
	v_fmamk_f32 v4, v3, 0x3f07dc22, v236
	v_fmaak_f32 v4, v3, v4, 0x3f35f0e3
	v_fmaak_f32 v4, v3, v4, 0xbe11a98e
	v_fmaak_f32 v4, v3, v4, 0x3e027906
	v_mul_f32_e32 v3, v3, v4
	v_mul_f32_e32 v4, v2, v2
	v_mul_f32_e32 v4, 0xbf38aa3b, v4
	v_exp_f32_e32 v4, v4
	s_nop 0
	v_mul_f32_e32 v3, v4, v3
	v_mul_f32_e32 v4, v3, v2
	v_fma_f32 v3, -v3, v2, v2
	v_cndmask_b32_e32 v6, v3, v4, vcc
	ds_read_b128 v[2:5], v1 offset:480
	s_waitcnt lgkmcnt(0)
	v_add_f32_e32 v1, v14, v2
	v_mul_f32_e32 v1, v6, v1
	v_lshlrev_b64 v[6:7], 11, v[162:163]
	v_cvt_pk_bf16_f32 v1, v1, s0
	v_lshl_add_u64 v[6:7], v[106:107], 0, v[6:7]
	global_store_short v[6:7], v1, off
	s_waitcnt vmcnt(31)
	v_lshlrev_b32_e32 v1, 16, v176
	v_fma_f32 v2, |v1|, s92, 1.0
	v_rcp_f32_e32 v2, v2
	v_cmp_gt_f32_e32 vcc, 0, v1
	v_fmamk_f32 v6, v2, 0x3f07dc22, v236
	v_fmaak_f32 v6, v2, v6, 0x3f35f0e3
	v_fmaak_f32 v6, v2, v6, 0xbe11a98e
	v_fmaak_f32 v6, v2, v6, 0x3e027906
	v_mul_f32_e32 v2, v2, v6
	v_mul_f32_e32 v6, v1, v1
	v_mul_f32_e32 v6, 0xbf38aa3b, v6
	v_exp_f32_e32 v6, v6
	s_nop 0
	v_mul_f32_e32 v2, v6, v2
	v_mul_f32_e32 v6, v2, v1
	v_fma_f32 v2, -v2, v1, v1
	v_cndmask_b32_e32 v1, v2, v6, vcc
	v_add_f32_e32 v2, v15, v3
	v_mul_f32_e32 v1, v1, v2
	v_lshlrev_b64 v[2:3], 11, v[160:161]
	v_cvt_pk_bf16_f32 v1, v1, s0
	v_lshl_add_u64 v[2:3], v[106:107], 0, v[2:3]
	global_store_short v[2:3], v1, off
	s_waitcnt vmcnt(31)
	v_lshlrev_b32_e32 v1, 16, v175
	v_fma_f32 v2, |v1|, s92, 1.0
	v_rcp_f32_e32 v2, v2
	v_cmp_gt_f32_e32 vcc, 0, v1
	v_fmamk_f32 v3, v2, 0x3f07dc22, v236
	v_fmaak_f32 v3, v2, v3, 0x3f35f0e3
	v_fmaak_f32 v3, v2, v3, 0xbe11a98e
	v_fmaak_f32 v3, v2, v3, 0x3e027906
	v_mul_f32_e32 v2, v2, v3
	v_mul_f32_e32 v3, v1, v1
	v_mul_f32_e32 v3, 0xbf38aa3b, v3
	v_exp_f32_e32 v3, v3
	s_nop 0
	v_mul_f32_e32 v2, v3, v2
	v_mul_f32_e32 v3, v2, v1
	v_fma_f32 v2, -v2, v1, v1
	v_cndmask_b32_e32 v1, v2, v3, vcc
	v_add_f32_e32 v2, v16, v4
	v_mul_f32_e32 v1, v1, v2
	v_lshlrev_b64 v[2:3], 11, v[158:159]
	v_cvt_pk_bf16_f32 v1, v1, s0
	v_lshl_add_u64 v[2:3], v[106:107], 0, v[2:3]
	global_store_short v[2:3], v1, off
	s_waitcnt vmcnt(31)
	v_lshlrev_b32_e32 v1, 16, v174
	v_fma_f32 v2, |v1|, s92, 1.0
	v_rcp_f32_e32 v2, v2
	v_cmp_gt_f32_e32 vcc, 0, v1
	v_fmamk_f32 v3, v2, 0x3f07dc22, v236
	v_fmaak_f32 v3, v2, v3, 0x3f35f0e3
	v_fmaak_f32 v3, v2, v3, 0xbe11a98e
	v_fmaak_f32 v3, v2, v3, 0x3e027906
	v_mul_f32_e32 v2, v2, v3
	v_mul_f32_e32 v3, v1, v1
	v_mul_f32_e32 v3, 0xbf38aa3b, v3
	v_exp_f32_e32 v3, v3
	s_nop 0
	v_mul_f32_e32 v2, v3, v2
	v_mul_f32_e32 v3, v2, v1
	v_fma_f32 v2, -v2, v1, v1
	v_cndmask_b32_e32 v1, v2, v3, vcc
	v_add_f32_e32 v2, v17, v5
	v_mul_f32_e32 v1, v1, v2
	v_lshlrev_b64 v[2:3], 11, v[156:157]
	v_cvt_pk_bf16_f32 v1, v1, s0
	v_lshl_add_u64 v[2:3], v[106:107], 0, v[2:3]
	global_store_short v[2:3], v1, off
	s_barrier
	s_cbranch_scc0 .LBB0_254

.LBB0_257:
	s_add_i32 s7, s50, s54
	s_add_i32 s8, s51, s54
	s_cmpk_lt_i32 s8, 0x200
	s_cselect_b32 s7, s8, s7
	s_lshl_b32 s7, s7, 6
	s_and_b32 s8, s7, 0xfc0
	s_sub_i32 s10, s8, 30
	s_add_i32 s8, s10, s49
	s_and_b32 s7, s7, 0xfffff000
	s_max_i32 s8, s8, 0
	s_add_i32 s8, s8, s7
	v_and_b32_e32 v14, 0xff, v10
	v_mad_i64_i32 v[10:11], s[8:9], s8, v238, v[42:43]
	s_add_i32 s8, s10, s48
	s_max_i32 s8, s8, 0
	s_add_i32 s8, s8, s7
	v_mad_i64_i32 v[12:13], s[8:9], s8, v238, v[42:43]
	s_add_i32 s8, s10, s47
	s_max_i32 s8, s8, 0
	s_add_i32 s8, s8, s7
	s_waitcnt lgkmcnt(0)
	s_barrier
	global_load_dwordx2 v[152:153], v[10:11], off offset:1024
	global_load_dwordx2 v[154:155], v[10:11], off offset:1536
	global_load_dwordx2 v[148:149], v[12:13], off offset:1024
	global_load_dwordx2 v[150:151], v[12:13], off offset:1536
	v_mad_i64_i32 v[10:11], s[8:9], s8, v238, v[42:43]
	s_add_i32 s8, s10, s46
	s_max_i32 s8, s8, 0
	s_add_i32 s8, s8, s7
	v_mad_i64_i32 v[12:13], s[8:9], s8, v238, v[42:43]
	s_add_i32 s8, s10, s45
	s_max_i32 s8, s8, 0
	s_add_i32 s8, s8, s7
	global_load_dwordx2 v[144:145], v[10:11], off offset:1024
	global_load_dwordx2 v[146:147], v[10:11], off offset:1536
	global_load_dwordx2 v[140:141], v[12:13], off offset:1024
	global_load_dwordx2 v[142:143], v[12:13], off offset:1536
	v_mad_i64_i32 v[10:11], s[8:9], s8, v238, v[42:43]
	s_add_i32 s8, s10, s44
	s_max_i32 s8, s8, 0
	s_add_i32 s8, s8, s7
	v_mad_i64_i32 v[12:13], s[8:9], s8, v238, v[42:43]
	s_add_i32 s8, s10, s43
	s_max_i32 s8, s8, 0
	s_add_i32 s8, s8, s7
	global_load_dwordx2 v[136:137], v[10:11], off offset:1024
	global_load_dwordx2 v[138:139], v[10:11], off offset:1536
	global_load_dwordx2 v[132:133], v[12:13], off offset:1024
	global_load_dwordx2 v[134:135], v[12:13], off offset:1536
	v_mad_i64_i32 v[10:11], s[8:9], s8, v238, v[42:43]
	s_add_i32 s8, s10, s42
	s_max_i32 s8, s8, 0
	s_add_i32 s8, s8, s7
	v_mad_i64_i32 v[12:13], s[8:9], s8, v238, v[42:43]
	s_add_i32 s8, s10, s41
	s_max_i32 s8, s8, 0
	s_add_i32 s8, s8, s7
	global_load_dwordx2 v[126:127], v[10:11], off offset:1024
	global_load_dwordx2 v[128:129], v[10:11], off offset:1536
	global_load_dwordx2 v[122:123], v[12:13], off offset:1024
	global_load_dwordx2 v[124:125], v[12:13], off offset:1536
	v_mad_i64_i32 v[10:11], s[8:9], s8, v238, v[42:43]
	s_add_i32 s8, s10, s40
	s_max_i32 s8, s8, 0
	s_add_i32 s8, s8, s7
	v_mad_i64_i32 v[12:13], s[8:9], s8, v238, v[42:43]
	s_add_i32 s8, s10, s34
	s_max_i32 s8, s8, 0
	s_add_i32 s8, s8, s7
	global_load_dwordx2 v[118:119], v[10:11], off offset:1024
	global_load_dwordx2 v[120:121], v[10:11], off offset:1536
	global_load_dwordx2 v[114:115], v[12:13], off offset:1024
	global_load_dwordx2 v[116:117], v[12:13], off offset:1536
	v_mad_i64_i32 v[10:11], s[8:9], s8, v238, v[42:43]
	s_add_i32 s10, s10, s5
	s_lshl_b32 s6, s6, 7
	s_max_i32 s8, s10, 0
	s_and_b32 s6, s6, 0xffff8000
	s_add_i32 s8, s8, s7
	s_add_i32 s6, s6, 0
	v_mad_i64_i32 v[12:13], s[8:9], s8, v238, v[42:43]
	v_lshl_add_u32 v163, v14, 2, s6
	global_load_dwordx2 v[110:111], v[10:11], off offset:1024
	global_load_dwordx2 v[112:113], v[10:11], off offset:1536
	global_load_dwordx2 v[106:107], v[12:13], off offset:1024
	global_load_dwordx2 v[108:109], v[12:13], off offset:1536
	ds_read2st64_b32 v[26:27], v163 offset1:4
	ds_read2st64_b32 v[28:29], v163 offset0:8 offset1:12
	ds_read2st64_b32 v[30:31], v163 offset0:16 offset1:20
	ds_read2st64_b32 v[32:33], v163 offset0:24 offset1:28
	ds_read2st64_b32 v[160:161], v163 offset0:32 offset1:36
	ds_read2st64_b32 v[158:159], v163 offset0:40 offset1:44
	ds_read2st64_b32 v[156:157], v163 offset0:48 offset1:52
	ds_read2st64_b32 v[40:41], v163 offset0:56 offset1:60
	ds_read2st64_b32 v[38:39], v163 offset0:64 offset1:68
	ds_read2st64_b32 v[36:37], v163 offset0:72 offset1:76
	ds_read2st64_b32 v[34:35], v163 offset0:80 offset1:84
	ds_read2st64_b32 v[24:25], v163 offset0:88 offset1:92
	ds_read2st64_b32 v[22:23], v163 offset0:96 offset1:100
	ds_read2st64_b32 v[20:21], v163 offset0:104 offset1:108
	ds_read2st64_b32 v[10:11], v163 offset0:120 offset1:124
	ds_read2st64_b32 v[18:19], v163 offset0:112 offset1:116
	ds_read2st64_b32 v[12:13], v163 offset0:128 offset1:132
	ds_read2st64_b32 v[14:15], v163 offset0:136 offset1:140
	ds_read2st64_b32 v[16:17], v163 offset0:144 offset1:148
	s_waitcnt vmcnt(49) lgkmcnt(4)
	v_mul_f32_e32 v105, v103, v10
	v_mul_f32_e32 v165, v44, v27
	s_waitcnt vmcnt(24)
	v_mov_b32_e32 v164, v104
	v_pk_fma_f32 v[26:27], v[44:45], v[26:27], v[104:105]
	v_pk_fma_f32 v[164:165], v[46:47], v[28:29], v[164:165]
	v_pk_fma_f32 v[26:27], v[48:49], v[28:29], v[26:27]
	v_pk_fma_f32 v[164:165], v[50:51], v[30:31], v[164:165]
	v_pk_fma_f32 v[26:27], v[52:53], v[30:31], v[26:27]
	v_pk_fma_f32 v[164:165], v[54:55], v[32:33], v[164:165]
	v_pk_fma_f32 v[26:27], v[56:57], v[32:33], v[26:27]
	v_pk_fma_f32 v[164:165], v[58:59], v[160:161], v[164:165]
	v_pk_fma_f32 v[26:27], v[60:61], v[160:161], v[26:27]
	v_pk_fma_f32 v[164:165], v[62:63], v[158:159], v[164:165]
	v_pk_fma_f32 v[26:27], v[64:65], v[158:159], v[26:27]
	v_pk_fma_f32 v[164:165], v[66:67], v[156:157], v[164:165]
	v_pk_fma_f32 v[26:27], v[68:69], v[156:157], v[26:27]
	v_pk_fma_f32 v[164:165], v[70:71], v[40:41], v[164:165]
	v_pk_fma_f32 v[26:27], v[72:73], v[40:41], v[26:27]
	v_pk_fma_f32 v[164:165], v[74:75], v[38:39], v[164:165]
	v_pk_fma_f32 v[26:27], v[76:77], v[38:39], v[26:27]
	v_pk_fma_f32 v[164:165], v[78:79], v[36:37], v[164:165]
	v_pk_fma_f32 v[26:27], v[80:81], v[36:37], v[26:27]
	v_pk_fma_f32 v[164:165], v[82:83], v[34:35], v[164:165]
	v_pk_fma_f32 v[26:27], v[84:85], v[34:35], v[26:27]
	v_pk_fma_f32 v[164:165], v[86:87], v[24:25], v[164:165]
	v_pk_fma_f32 v[26:27], v[88:89], v[24:25], v[26:27]
	v_pk_fma_f32 v[164:165], v[90:91], v[22:23], v[164:165]
	v_pk_fma_f32 v[26:27], v[92:93], v[22:23], v[26:27]
	v_pk_fma_f32 v[164:165], v[94:95], v[20:21], v[164:165]
	v_pk_fma_f32 v[26:27], v[96:97], v[20:21], v[26:27]
	s_waitcnt lgkmcnt(3)
	v_pk_fma_f32 v[164:165], v[98:99], v[18:19], v[164:165]
	v_pk_fma_f32 v[26:27], v[100:101], v[18:19], v[26:27]
	v_pk_fma_f32 v[166:167], v[102:103], v[10:11], v[164:165]
	v_add_f32_e32 v164, v26, v27
	v_mul_f32_e32 v27, v44, v29
	v_mov_b32_e32 v26, v104
	v_pk_fma_f32 v[26:27], v[46:47], v[30:31], v[26:27]
	v_add_f32_e32 v165, v166, v167
	v_pk_fma_f32 v[26:27], v[50:51], v[32:33], v[26:27]
	s_waitcnt lgkmcnt(2)
	v_mul_f32_e32 v105, v103, v12
	v_pk_fma_f32 v[26:27], v[54:55], v[160:161], v[26:27]
	v_pk_fma_f32 v[28:29], v[44:45], v[28:29], v[104:105]
	v_pk_fma_f32 v[26:27], v[58:59], v[158:159], v[26:27]
	v_pk_fma_f32 v[28:29], v[48:49], v[30:31], v[28:29]
	v_pk_fma_f32 v[26:27], v[62:63], v[156:157], v[26:27]
	v_pk_fma_f32 v[28:29], v[52:53], v[32:33], v[28:29]
	v_pk_fma_f32 v[26:27], v[66:67], v[40:41], v[26:27]
	v_pk_fma_f32 v[28:29], v[56:57], v[160:161], v[28:29]
	v_pk_fma_f32 v[26:27], v[70:71], v[38:39], v[26:27]
	v_pk_fma_f32 v[28:29], v[60:61], v[158:159], v[28:29]
	v_pk_fma_f32 v[26:27], v[74:75], v[36:37], v[26:27]
	v_pk_fma_f32 v[28:29], v[64:65], v[156:157], v[28:29]
	v_pk_fma_f32 v[26:27], v[78:79], v[34:35], v[26:27]
	v_pk_fma_f32 v[28:29], v[68:69], v[40:41], v[28:29]
	v_pk_fma_f32 v[26:27], v[82:83], v[24:25], v[26:27]
	v_pk_fma_f32 v[28:29], v[72:73], v[38:39], v[28:29]
	v_pk_fma_f32 v[26:27], v[86:87], v[22:23], v[26:27]
	v_pk_fma_f32 v[28:29], v[76:77], v[36:37], v[28:29]
	v_pk_fma_f32 v[26:27], v[90:91], v[20:21], v[26:27]
	v_pk_fma_f32 v[28:29], v[80:81], v[34:35], v[28:29]
	v_pk_fma_f32 v[26:27], v[94:95], v[18:19], v[26:27]
	v_pk_fma_f32 v[28:29], v[84:85], v[24:25], v[28:29]
	v_pk_fma_f32 v[26:27], v[98:99], v[10:11], v[26:27]
	v_pk_fma_f32 v[28:29], v[88:89], v[22:23], v[28:29]
	v_pk_fma_f32 v[26:27], v[102:103], v[12:13], v[26:27]
	v_pk_fma_f32 v[28:29], v[92:93], v[20:21], v[28:29]
	v_add_f32_e32 v167, v26, v27
	v_mul_f32_e32 v27, v44, v31
	v_mov_b32_e32 v26, v104
	v_pk_fma_f32 v[26:27], v[46:47], v[32:33], v[26:27]
	v_pk_fma_f32 v[28:29], v[96:97], v[18:19], v[28:29]
	v_pk_fma_f32 v[26:27], v[50:51], v[160:161], v[26:27]
	v_pk_fma_f32 v[28:29], v[100:101], v[10:11], v[28:29]
	v_pk_fma_f32 v[26:27], v[54:55], v[158:159], v[26:27]
	s_waitcnt lgkmcnt(1)
	v_mul_f32_e32 v105, v103, v14
	v_pk_fma_f32 v[26:27], v[58:59], v[156:157], v[26:27]
	v_add_f32_e32 v166, v28, v29
	v_pk_fma_f32 v[26:27], v[62:63], v[40:41], v[26:27]
	v_pk_fma_f32 v[28:29], v[44:45], v[30:31], v[104:105]
	v_pk_fma_f32 v[26:27], v[66:67], v[38:39], v[26:27]
	v_pk_fma_f32 v[28:29], v[48:49], v[32:33], v[28:29]
	v_pk_fma_f32 v[26:27], v[70:71], v[36:37], v[26:27]
	v_pk_fma_f32 v[28:29], v[52:53], v[160:161], v[28:29]
	v_pk_fma_f32 v[26:27], v[74:75], v[34:35], v[26:27]
	v_pk_fma_f32 v[28:29], v[56:57], v[158:159], v[28:29]
	v_pk_fma_f32 v[26:27], v[78:79], v[24:25], v[26:27]
	v_pk_fma_f32 v[28:29], v[60:61], v[156:157], v[28:29]
	v_pk_fma_f32 v[26:27], v[82:83], v[22:23], v[26:27]
	v_pk_fma_f32 v[28:29], v[64:65], v[40:41], v[28:29]
	v_pk_fma_f32 v[26:27], v[86:87], v[20:21], v[26:27]
	v_pk_fma_f32 v[28:29], v[68:69], v[38:39], v[28:29]
	v_pk_fma_f32 v[26:27], v[90:91], v[18:19], v[26:27]
	v_pk_fma_f32 v[28:29], v[72:73], v[36:37], v[28:29]
	v_pk_fma_f32 v[26:27], v[94:95], v[10:11], v[26:27]
	v_pk_fma_f32 v[28:29], v[76:77], v[34:35], v[28:29]
	v_pk_fma_f32 v[26:27], v[98:99], v[12:13], v[26:27]
	v_pk_fma_f32 v[28:29], v[80:81], v[24:25], v[28:29]
	v_pk_fma_f32 v[26:27], v[102:103], v[14:15], v[26:27]
	v_pk_fma_f32 v[28:29], v[84:85], v[22:23], v[28:29]
	v_add_f32_e32 v169, v26, v27
	v_mul_f32_e32 v27, v44, v33
	v_mov_b32_e32 v26, v104
	v_pk_fma_f32 v[26:27], v[46:47], v[160:161], v[26:27]
	v_pk_fma_f32 v[28:29], v[88:89], v[20:21], v[28:29]
	v_pk_fma_f32 v[26:27], v[50:51], v[158:159], v[26:27]
	v_pk_fma_f32 v[28:29], v[92:93], v[18:19], v[28:29]
	v_pk_fma_f32 v[26:27], v[54:55], v[156:157], v[26:27]
	v_pk_fma_f32 v[28:29], v[96:97], v[10:11], v[28:29]
	v_pk_fma_f32 v[26:27], v[58:59], v[40:41], v[26:27]
	v_pk_fma_f32 v[28:29], v[100:101], v[12:13], v[28:29]
	v_pk_fma_f32 v[26:27], v[62:63], v[38:39], v[26:27]
	s_waitcnt lgkmcnt(0)
	v_mul_f32_e32 v105, v103, v16
	v_pk_fma_f32 v[26:27], v[66:67], v[36:37], v[26:27]
	v_add_f32_e32 v168, v28, v29
	v_pk_fma_f32 v[26:27], v[70:71], v[34:35], v[26:27]
	v_pk_fma_f32 v[28:29], v[44:45], v[32:33], v[104:105]
	v_pk_fma_f32 v[26:27], v[74:75], v[24:25], v[26:27]
	v_pk_fma_f32 v[28:29], v[48:49], v[160:161], v[28:29]
	v_pk_fma_f32 v[26:27], v[78:79], v[22:23], v[26:27]
	v_pk_fma_f32 v[28:29], v[52:53], v[158:159], v[28:29]
	v_pk_fma_f32 v[26:27], v[82:83], v[20:21], v[26:27]
	v_pk_fma_f32 v[28:29], v[56:57], v[156:157], v[28:29]
	v_pk_fma_f32 v[26:27], v[86:87], v[18:19], v[26:27]
	v_pk_fma_f32 v[28:29], v[60:61], v[40:41], v[28:29]
	v_pk_fma_f32 v[26:27], v[90:91], v[10:11], v[26:27]
	v_mul_f32_e32 v173, v44, v161
	v_pk_fma_f32 v[26:27], v[94:95], v[12:13], v[26:27]
	v_pk_fma_f32 v[28:29], v[64:65], v[38:39], v[28:29]
	v_pk_fma_f32 v[26:27], v[98:99], v[14:15], v[26:27]
	v_pk_fma_f32 v[28:29], v[68:69], v[36:37], v[28:29]
	v_pk_fma_f32 v[30:31], v[102:103], v[16:17], v[26:27]
	ds_read2st64_b32 v[26:27], v163 offset0:152 offset1:156
	v_pk_fma_f32 v[28:29], v[72:73], v[34:35], v[28:29]
	v_add_f32_e32 v171, v30, v31
	v_pk_fma_f32 v[28:29], v[76:77], v[24:25], v[28:29]
	v_mov_b32_e32 v172, v104
	s_waitcnt lgkmcnt(0)
	v_mul_f32_e32 v105, v103, v26
	v_pk_fma_f32 v[160:161], v[44:45], v[160:161], v[104:105]
	v_pk_fma_f32 v[28:29], v[80:81], v[22:23], v[28:29]
	v_pk_fma_f32 v[160:161], v[48:49], v[158:159], v[160:161]
	v_pk_fma_f32 v[28:29], v[84:85], v[20:21], v[28:29]
	v_pk_fma_f32 v[160:161], v[52:53], v[156:157], v[160:161]
	v_pk_fma_f32 v[28:29], v[88:89], v[18:19], v[28:29]
	v_pk_fma_f32 v[160:161], v[56:57], v[40:41], v[160:161]
	v_pk_fma_f32 v[28:29], v[92:93], v[10:11], v[28:29]
	v_pk_fma_f32 v[160:161], v[60:61], v[38:39], v[160:161]
	v_pk_fma_f32 v[28:29], v[96:97], v[12:13], v[28:29]
	v_pk_fma_f32 v[160:161], v[64:65], v[36:37], v[160:161]
	v_pk_fma_f32 v[28:29], v[100:101], v[14:15], v[28:29]
	v_pk_fma_f32 v[160:161], v[68:69], v[34:35], v[160:161]
	v_add_f32_e32 v170, v28, v29
	v_pk_fma_f32 v[160:161], v[72:73], v[24:25], v[160:161]
	ds_read2st64_b32 v[28:29], v163 offset0:160 offset1:164
	ds_read2st64_b32 v[30:31], v163 offset0:168 offset1:172
	ds_read2st64_b32 v[32:33], v163 offset0:176 offset1:180
	v_pk_fma_f32 v[160:161], v[76:77], v[22:23], v[160:161]
	v_pk_fma_f32 v[172:173], v[46:47], v[158:159], v[172:173]
	v_pk_fma_f32 v[160:161], v[80:81], v[20:21], v[160:161]
	s_waitcnt lgkmcnt(2)
	v_mul_f32_e32 v105, v103, v28
	v_pk_fma_f32 v[160:161], v[84:85], v[18:19], v[160:161]
	v_pk_fma_f32 v[172:173], v[50:51], v[156:157], v[172:173]
	v_pk_fma_f32 v[160:161], v[88:89], v[10:11], v[160:161]
	v_pk_fma_f32 v[172:173], v[54:55], v[40:41], v[172:173]
	v_pk_fma_f32 v[160:161], v[92:93], v[12:13], v[160:161]
	v_pk_fma_f32 v[172:173], v[58:59], v[38:39], v[172:173]
	v_pk_fma_f32 v[160:161], v[96:97], v[14:15], v[160:161]
	v_pk_fma_f32 v[172:173], v[62:63], v[36:37], v[172:173]
	v_pk_fma_f32 v[160:161], v[100:101], v[16:17], v[160:161]
	v_pk_fma_f32 v[172:173], v[66:67], v[34:35], v[172:173]
	v_add_f32_e32 v174, v160, v161
	v_mul_f32_e32 v161, v44, v159
	v_pk_fma_f32 v[158:159], v[44:45], v[158:159], v[104:105]
	v_mov_b32_e32 v160, v104
	v_pk_fma_f32 v[158:159], v[48:49], v[156:157], v[158:159]
	s_waitcnt lgkmcnt(1)
	v_mul_f32_e32 v105, v103, v30
	v_pk_fma_f32 v[158:159], v[52:53], v[40:41], v[158:159]
	v_pk_fma_f32 v[160:161], v[46:47], v[156:157], v[160:161]
	v_pk_fma_f32 v[158:159], v[56:57], v[38:39], v[158:159]
	v_pk_fma_f32 v[160:161], v[50:51], v[40:41], v[160:161]
	v_pk_fma_f32 v[158:159], v[60:61], v[36:37], v[158:159]
	v_pk_fma_f32 v[172:173], v[70:71], v[24:25], v[172:173]
	v_pk_fma_f32 v[158:159], v[64:65], v[34:35], v[158:159]
	v_pk_fma_f32 v[172:173], v[74:75], v[22:23], v[172:173]
	v_pk_fma_f32 v[158:159], v[68:69], v[24:25], v[158:159]
	v_pk_fma_f32 v[172:173], v[78:79], v[20:21], v[172:173]
	v_pk_fma_f32 v[158:159], v[72:73], v[22:23], v[158:159]
	v_pk_fma_f32 v[172:173], v[82:83], v[18:19], v[172:173]
	v_pk_fma_f32 v[158:159], v[76:77], v[20:21], v[158:159]
	v_pk_fma_f32 v[172:173], v[86:87], v[10:11], v[172:173]
	v_pk_fma_f32 v[158:159], v[80:81], v[18:19], v[158:159]
	v_pk_fma_f32 v[172:173], v[90:91], v[12:13], v[172:173]
	v_pk_fma_f32 v[158:159], v[84:85], v[10:11], v[158:159]
	v_pk_fma_f32 v[172:173], v[94:95], v[14:15], v[172:173]
	v_pk_fma_f32 v[158:159], v[88:89], v[12:13], v[158:159]
	v_pk_fma_f32 v[172:173], v[98:99], v[16:17], v[172:173]
	v_pk_fma_f32 v[158:159], v[92:93], v[14:15], v[158:159]
	v_pk_fma_f32 v[160:161], v[54:55], v[38:39], v[160:161]
	v_pk_fma_f32 v[158:159], v[96:97], v[16:17], v[158:159]
	v_pk_fma_f32 v[172:173], v[102:103], v[26:27], v[172:173]
	v_pk_fma_f32 v[158:159], v[100:101], v[26:27], v[158:159]
	v_pk_fma_f32 v[160:161], v[58:59], v[36:37], v[160:161]
	v_add_f32_e32 v176, v158, v159
	v_mul_f32_e32 v159, v44, v157
	v_pk_fma_f32 v[156:157], v[44:45], v[156:157], v[104:105]
	v_mov_b32_e32 v158, v104
	v_pk_fma_f32 v[156:157], v[48:49], v[40:41], v[156:157]
	s_waitcnt lgkmcnt(0)
	v_mul_f32_e32 v105, v103, v32
	v_pk_fma_f32 v[156:157], v[52:53], v[38:39], v[156:157]
	v_pk_fma_f32 v[158:159], v[46:47], v[40:41], v[158:159]
	v_pk_fma_f32 v[156:157], v[56:57], v[36:37], v[156:157]
	v_pk_fma_f32 v[158:159], v[50:51], v[38:39], v[158:159]
	v_pk_fma_f32 v[156:157], v[60:61], v[34:35], v[156:157]
	v_pk_fma_f32 v[158:159], v[54:55], v[36:37], v[158:159]
	v_pk_fma_f32 v[156:157], v[64:65], v[24:25], v[156:157]
	v_pk_fma_f32 v[158:159], v[58:59], v[34:35], v[158:159]
	v_pk_fma_f32 v[156:157], v[68:69], v[22:23], v[156:157]
	v_add_f32_e32 v175, v172, v173
	v_pk_fma_f32 v[156:157], v[72:73], v[20:21], v[156:157]
	v_pk_fma_f32 v[160:161], v[62:63], v[34:35], v[160:161]
	v_pk_fma_f32 v[156:157], v[76:77], v[18:19], v[156:157]
	v_pk_fma_f32 v[158:159], v[62:63], v[24:25], v[158:159]
	v_pk_fma_f32 v[156:157], v[80:81], v[10:11], v[156:157]
	v_mul_f32_e32 v173, v44, v39
	v_pk_fma_f32 v[156:157], v[84:85], v[12:13], v[156:157]
	v_pk_fma_f32 v[160:161], v[66:67], v[24:25], v[160:161]
	v_pk_fma_f32 v[156:157], v[88:89], v[14:15], v[156:157]
	v_pk_fma_f32 v[158:159], v[66:67], v[22:23], v[158:159]
	v_pk_fma_f32 v[156:157], v[92:93], v[16:17], v[156:157]
	v_pk_fma_f32 v[160:161], v[70:71], v[22:23], v[160:161]
	v_pk_fma_f32 v[156:157], v[96:97], v[26:27], v[156:157]
	v_pk_fma_f32 v[158:159], v[70:71], v[20:21], v[158:159]
	v_pk_fma_f32 v[156:157], v[100:101], v[28:29], v[156:157]
	v_pk_fma_f32 v[160:161], v[74:75], v[20:21], v[160:161]
	v_add_f32_e32 v178, v156, v157
	v_mul_f32_e32 v157, v44, v41
	v_pk_fma_f32 v[40:41], v[44:45], v[40:41], v[104:105]
	v_mov_b32_e32 v156, v104
	v_pk_fma_f32 v[40:41], v[48:49], v[38:39], v[40:41]
	v_pk_fma_f32 v[156:157], v[46:47], v[38:39], v[156:157]
	v_pk_fma_f32 v[40:41], v[52:53], v[36:37], v[40:41]
	v_pk_fma_f32 v[156:157], v[50:51], v[36:37], v[156:157]
	v_pk_fma_f32 v[40:41], v[56:57], v[34:35], v[40:41]
	v_pk_fma_f32 v[156:157], v[54:55], v[34:35], v[156:157]
	v_pk_fma_f32 v[40:41], v[60:61], v[24:25], v[40:41]
	v_pk_fma_f32 v[156:157], v[58:59], v[24:25], v[156:157]
	v_pk_fma_f32 v[40:41], v[64:65], v[22:23], v[40:41]
	v_pk_fma_f32 v[156:157], v[62:63], v[22:23], v[156:157]
	v_pk_fma_f32 v[40:41], v[68:69], v[20:21], v[40:41]
	v_pk_fma_f32 v[156:157], v[66:67], v[20:21], v[156:157]
	v_pk_fma_f32 v[40:41], v[72:73], v[18:19], v[40:41]
	v_pk_fma_f32 v[156:157], v[70:71], v[18:19], v[156:157]
	v_pk_fma_f32 v[40:41], v[76:77], v[10:11], v[40:41]
	v_pk_fma_f32 v[158:159], v[74:75], v[18:19], v[158:159]
	v_pk_fma_f32 v[40:41], v[80:81], v[12:13], v[40:41]
	v_pk_fma_f32 v[156:157], v[74:75], v[10:11], v[156:157]
	v_pk_fma_f32 v[40:41], v[84:85], v[14:15], v[40:41]
	v_pk_fma_f32 v[160:161], v[78:79], v[18:19], v[160:161]
	v_pk_fma_f32 v[40:41], v[88:89], v[16:17], v[40:41]
	v_pk_fma_f32 v[158:159], v[78:79], v[10:11], v[158:159]
	v_pk_fma_f32 v[40:41], v[92:93], v[26:27], v[40:41]
	v_pk_fma_f32 v[156:157], v[78:79], v[12:13], v[156:157]
	v_pk_fma_f32 v[40:41], v[96:97], v[28:29], v[40:41]
	v_pk_fma_f32 v[160:161], v[82:83], v[10:11], v[160:161]
	v_pk_fma_f32 v[40:41], v[100:101], v[30:31], v[40:41]
	v_pk_fma_f32 v[158:159], v[82:83], v[12:13], v[158:159]
	v_add_f32_e32 v180, v40, v41
	ds_read2st64_b32 v[40:41], v163 offset0:184 offset1:188
	v_pk_fma_f32 v[156:157], v[82:83], v[14:15], v[156:157]
	v_pk_fma_f32 v[160:161], v[86:87], v[12:13], v[160:161]
	v_pk_fma_f32 v[158:159], v[86:87], v[14:15], v[158:159]
	v_pk_fma_f32 v[156:157], v[86:87], v[16:17], v[156:157]
	s_waitcnt lgkmcnt(0)
	v_mul_f32_e32 v105, v103, v40
	v_pk_fma_f32 v[38:39], v[44:45], v[38:39], v[104:105]
	v_pk_fma_f32 v[160:161], v[90:91], v[14:15], v[160:161]
	v_pk_fma_f32 v[38:39], v[48:49], v[36:37], v[38:39]
	v_pk_fma_f32 v[158:159], v[90:91], v[16:17], v[158:159]
	v_pk_fma_f32 v[38:39], v[52:53], v[34:35], v[38:39]
	v_pk_fma_f32 v[156:157], v[90:91], v[26:27], v[156:157]
	v_pk_fma_f32 v[38:39], v[56:57], v[24:25], v[38:39]
	v_pk_fma_f32 v[160:161], v[94:95], v[16:17], v[160:161]
	v_pk_fma_f32 v[38:39], v[60:61], v[22:23], v[38:39]
	v_pk_fma_f32 v[158:159], v[94:95], v[26:27], v[158:159]
	v_pk_fma_f32 v[38:39], v[64:65], v[20:21], v[38:39]
	v_pk_fma_f32 v[156:157], v[94:95], v[28:29], v[156:157]
	v_pk_fma_f32 v[38:39], v[68:69], v[18:19], v[38:39]
	v_pk_fma_f32 v[160:161], v[98:99], v[26:27], v[160:161]
	v_pk_fma_f32 v[38:39], v[72:73], v[10:11], v[38:39]
	v_pk_fma_f32 v[158:159], v[98:99], v[28:29], v[158:159]
	v_pk_fma_f32 v[38:39], v[76:77], v[12:13], v[38:39]
	v_pk_fma_f32 v[156:157], v[98:99], v[30:31], v[156:157]
	v_pk_fma_f32 v[38:39], v[80:81], v[14:15], v[38:39]
	v_pk_fma_f32 v[160:161], v[102:103], v[28:29], v[160:161]
	v_pk_fma_f32 v[158:159], v[102:103], v[30:31], v[158:159]
	v_pk_fma_f32 v[156:157], v[102:103], v[32:33], v[156:157]
	v_pk_fma_f32 v[38:39], v[84:85], v[16:17], v[38:39]
	v_add_f32_e32 v177, v160, v161
	v_add_f32_e32 v179, v158, v159
	v_add_f32_e32 v181, v156, v157
	ds_read2st64_b32 v[156:157], v163 offset0:192 offset1:196
	ds_read2st64_b32 v[158:159], v163 offset0:200 offset1:204
	ds_read2st64_b32 v[160:161], v163 offset0:208 offset1:212
	v_pk_fma_f32 v[38:39], v[88:89], v[26:27], v[38:39]
	v_mov_b32_e32 v172, v104
	v_pk_fma_f32 v[38:39], v[92:93], v[28:29], v[38:39]
	s_waitcnt lgkmcnt(2)
	v_mul_f32_e32 v105, v103, v156
	v_pk_fma_f32 v[38:39], v[96:97], v[30:31], v[38:39]
	v_pk_fma_f32 v[172:173], v[46:47], v[36:37], v[172:173]
	v_pk_fma_f32 v[38:39], v[100:101], v[32:33], v[38:39]
	v_pk_fma_f32 v[172:173], v[50:51], v[34:35], v[172:173]
	v_add_f32_e32 v182, v38, v39
	v_mul_f32_e32 v39, v44, v37
	v_pk_fma_f32 v[36:37], v[44:45], v[36:37], v[104:105]
	v_mov_b32_e32 v38, v104
	v_pk_fma_f32 v[36:37], v[48:49], v[34:35], v[36:37]
	s_waitcnt lgkmcnt(1)
	v_mul_f32_e32 v105, v103, v158
	v_pk_fma_f32 v[36:37], v[52:53], v[24:25], v[36:37]
	v_pk_fma_f32 v[38:39], v[46:47], v[34:35], v[38:39]
	v_pk_fma_f32 v[36:37], v[56:57], v[22:23], v[36:37]
	v_pk_fma_f32 v[172:173], v[54:55], v[24:25], v[172:173]
	v_pk_fma_f32 v[36:37], v[60:61], v[20:21], v[36:37]
	v_pk_fma_f32 v[38:39], v[50:51], v[24:25], v[38:39]
	v_pk_fma_f32 v[36:37], v[64:65], v[18:19], v[36:37]
	v_pk_fma_f32 v[172:173], v[58:59], v[22:23], v[172:173]
	v_pk_fma_f32 v[36:37], v[68:69], v[10:11], v[36:37]
	v_pk_fma_f32 v[172:173], v[62:63], v[20:21], v[172:173]
	v_pk_fma_f32 v[36:37], v[72:73], v[12:13], v[36:37]
	v_pk_fma_f32 v[172:173], v[66:67], v[18:19], v[172:173]
	v_pk_fma_f32 v[36:37], v[76:77], v[14:15], v[36:37]
	v_pk_fma_f32 v[172:173], v[70:71], v[10:11], v[172:173]
	v_pk_fma_f32 v[36:37], v[80:81], v[16:17], v[36:37]
	v_pk_fma_f32 v[172:173], v[74:75], v[12:13], v[172:173]
	v_pk_fma_f32 v[36:37], v[84:85], v[26:27], v[36:37]
	v_pk_fma_f32 v[172:173], v[78:79], v[14:15], v[172:173]
	v_pk_fma_f32 v[36:37], v[88:89], v[28:29], v[36:37]
	v_pk_fma_f32 v[172:173], v[82:83], v[16:17], v[172:173]
	v_pk_fma_f32 v[36:37], v[92:93], v[30:31], v[36:37]
	v_pk_fma_f32 v[172:173], v[86:87], v[26:27], v[172:173]
	v_pk_fma_f32 v[36:37], v[96:97], v[32:33], v[36:37]
	v_pk_fma_f32 v[172:173], v[90:91], v[28:29], v[172:173]
	v_pk_fma_f32 v[36:37], v[100:101], v[40:41], v[36:37]
	v_pk_fma_f32 v[172:173], v[94:95], v[30:31], v[172:173]
	v_add_f32_e32 v184, v36, v37
	v_mul_f32_e32 v37, v44, v35
	v_pk_fma_f32 v[34:35], v[44:45], v[34:35], v[104:105]
	v_mov_b32_e32 v36, v104
	v_pk_fma_f32 v[34:35], v[48:49], v[24:25], v[34:35]
	s_waitcnt lgkmcnt(0)
	v_mul_f32_e32 v105, v103, v160
	v_pk_fma_f32 v[34:35], v[52:53], v[22:23], v[34:35]
	v_pk_fma_f32 v[36:37], v[46:47], v[24:25], v[36:37]
	v_pk_fma_f32 v[34:35], v[56:57], v[20:21], v[34:35]
	v_pk_fma_f32 v[36:37], v[50:51], v[22:23], v[36:37]
	v_pk_fma_f32 v[34:35], v[60:61], v[18:19], v[34:35]
	v_pk_fma_f32 v[172:173], v[98:99], v[32:33], v[172:173]
	v_pk_fma_f32 v[34:35], v[64:65], v[10:11], v[34:35]
	v_pk_fma_f32 v[38:39], v[54:55], v[22:23], v[38:39]
	v_pk_fma_f32 v[34:35], v[68:69], v[12:13], v[34:35]
	v_pk_fma_f32 v[36:37], v[54:55], v[20:21], v[36:37]
	v_pk_fma_f32 v[34:35], v[72:73], v[14:15], v[34:35]
	v_pk_fma_f32 v[172:173], v[102:103], v[40:41], v[172:173]
	v_pk_fma_f32 v[34:35], v[76:77], v[16:17], v[34:35]
	v_pk_fma_f32 v[38:39], v[58:59], v[20:21], v[38:39]
	v_pk_fma_f32 v[34:35], v[80:81], v[26:27], v[34:35]
	v_pk_fma_f32 v[36:37], v[58:59], v[18:19], v[36:37]
	v_pk_fma_f32 v[34:35], v[84:85], v[28:29], v[34:35]
	v_add_f32_e32 v183, v172, v173
	v_pk_fma_f32 v[34:35], v[88:89], v[30:31], v[34:35]
	v_pk_fma_f32 v[38:39], v[62:63], v[18:19], v[38:39]
	v_pk_fma_f32 v[34:35], v[92:93], v[32:33], v[34:35]
	v_pk_fma_f32 v[36:37], v[62:63], v[10:11], v[36:37]
	v_pk_fma_f32 v[34:35], v[96:97], v[40:41], v[34:35]
	v_mul_f32_e32 v173, v44, v23
	v_pk_fma_f32 v[34:35], v[100:101], v[156:157], v[34:35]
	v_pk_fma_f32 v[38:39], v[66:67], v[10:11], v[38:39]
	v_add_f32_e32 v186, v34, v35
	v_mul_f32_e32 v35, v44, v25
	v_pk_fma_f32 v[24:25], v[44:45], v[24:25], v[104:105]
	v_mov_b32_e32 v34, v104
	v_pk_fma_f32 v[24:25], v[48:49], v[22:23], v[24:25]
	v_pk_fma_f32 v[34:35], v[46:47], v[22:23], v[34:35]
	v_pk_fma_f32 v[24:25], v[52:53], v[20:21], v[24:25]
	v_pk_fma_f32 v[34:35], v[50:51], v[20:21], v[34:35]
	v_pk_fma_f32 v[24:25], v[56:57], v[18:19], v[24:25]
	v_pk_fma_f32 v[34:35], v[54:55], v[18:19], v[34:35]
	v_pk_fma_f32 v[24:25], v[60:61], v[10:11], v[24:25]
	v_pk_fma_f32 v[34:35], v[58:59], v[10:11], v[34:35]
	v_pk_fma_f32 v[24:25], v[64:65], v[12:13], v[24:25]
	v_pk_fma_f32 v[34:35], v[62:63], v[12:13], v[34:35]
	v_pk_fma_f32 v[24:25], v[68:69], v[14:15], v[24:25]
	v_pk_fma_f32 v[36:37], v[66:67], v[12:13], v[36:37]
	v_pk_fma_f32 v[24:25], v[72:73], v[16:17], v[24:25]
	v_pk_fma_f32 v[34:35], v[66:67], v[14:15], v[34:35]
	v_pk_fma_f32 v[24:25], v[76:77], v[26:27], v[24:25]
	v_pk_fma_f32 v[38:39], v[70:71], v[12:13], v[38:39]
	v_pk_fma_f32 v[24:25], v[80:81], v[28:29], v[24:25]
	v_pk_fma_f32 v[36:37], v[70:71], v[14:15], v[36:37]
	v_pk_fma_f32 v[24:25], v[84:85], v[30:31], v[24:25]
	v_pk_fma_f32 v[34:35], v[70:71], v[16:17], v[34:35]
	v_pk_fma_f32 v[24:25], v[88:89], v[32:33], v[24:25]
	v_pk_fma_f32 v[38:39], v[74:75], v[14:15], v[38:39]
	v_pk_fma_f32 v[24:25], v[92:93], v[40:41], v[24:25]
	v_pk_fma_f32 v[36:37], v[74:75], v[16:17], v[36:37]
	v_pk_fma_f32 v[24:25], v[96:97], v[156:157], v[24:25]
	v_pk_fma_f32 v[34:35], v[74:75], v[26:27], v[34:35]
	v_pk_fma_f32 v[24:25], v[100:101], v[158:159], v[24:25]
	v_pk_fma_f32 v[38:39], v[78:79], v[16:17], v[38:39]
	v_add_f32_e32 v188, v24, v25
	ds_read2st64_b32 v[24:25], v163 offset0:216 offset1:220
	v_pk_fma_f32 v[36:37], v[78:79], v[26:27], v[36:37]
	v_pk_fma_f32 v[34:35], v[78:79], v[28:29], v[34:35]
	v_pk_fma_f32 v[38:39], v[82:83], v[26:27], v[38:39]
	v_pk_fma_f32 v[36:37], v[82:83], v[28:29], v[36:37]
	s_waitcnt lgkmcnt(0)
	v_mul_f32_e32 v105, v103, v24
	v_pk_fma_f32 v[22:23], v[44:45], v[22:23], v[104:105]
	v_pk_fma_f32 v[34:35], v[82:83], v[30:31], v[34:35]
	v_pk_fma_f32 v[22:23], v[48:49], v[20:21], v[22:23]
	v_pk_fma_f32 v[38:39], v[86:87], v[28:29], v[38:39]
	v_pk_fma_f32 v[22:23], v[52:53], v[18:19], v[22:23]
	v_pk_fma_f32 v[36:37], v[86:87], v[30:31], v[36:37]
	v_pk_fma_f32 v[22:23], v[56:57], v[10:11], v[22:23]
	v_pk_fma_f32 v[34:35], v[86:87], v[32:33], v[34:35]
	v_pk_fma_f32 v[22:23], v[60:61], v[12:13], v[22:23]
	v_pk_fma_f32 v[38:39], v[90:91], v[30:31], v[38:39]
	v_pk_fma_f32 v[22:23], v[64:65], v[14:15], v[22:23]
	v_pk_fma_f32 v[36:37], v[90:91], v[32:33], v[36:37]
	v_pk_fma_f32 v[22:23], v[68:69], v[16:17], v[22:23]
	v_pk_fma_f32 v[34:35], v[90:91], v[40:41], v[34:35]
	v_pk_fma_f32 v[22:23], v[72:73], v[26:27], v[22:23]
	v_pk_fma_f32 v[38:39], v[94:95], v[32:33], v[38:39]
	v_pk_fma_f32 v[36:37], v[94:95], v[40:41], v[36:37]
	v_pk_fma_f32 v[34:35], v[94:95], v[156:157], v[34:35]
	v_pk_fma_f32 v[22:23], v[76:77], v[28:29], v[22:23]
	v_pk_fma_f32 v[38:39], v[98:99], v[40:41], v[38:39]
	v_pk_fma_f32 v[36:37], v[98:99], v[156:157], v[36:37]
	v_pk_fma_f32 v[34:35], v[98:99], v[158:159], v[34:35]
	v_pk_fma_f32 v[22:23], v[80:81], v[30:31], v[22:23]
	v_pk_fma_f32 v[38:39], v[102:103], v[156:157], v[38:39]
	v_pk_fma_f32 v[36:37], v[102:103], v[158:159], v[36:37]
	v_pk_fma_f32 v[34:35], v[102:103], v[160:161], v[34:35]
	v_pk_fma_f32 v[22:23], v[84:85], v[32:33], v[22:23]
	v_add_f32_e32 v185, v38, v39
	v_add_f32_e32 v187, v36, v37
	v_add_f32_e32 v189, v34, v35
	ds_read2st64_b32 v[34:35], v163 offset0:224 offset1:228
	ds_read2st64_b32 v[36:37], v163 offset0:232 offset1:236
	ds_read2st64_b32 v[38:39], v163 offset0:240 offset1:244
	v_pk_fma_f32 v[22:23], v[88:89], v[40:41], v[22:23]
	v_mov_b32_e32 v172, v104
	v_pk_fma_f32 v[22:23], v[92:93], v[156:157], v[22:23]
	s_waitcnt lgkmcnt(2)
	v_mul_f32_e32 v105, v103, v34
	v_pk_fma_f32 v[22:23], v[96:97], v[158:159], v[22:23]
	v_pk_fma_f32 v[172:173], v[46:47], v[20:21], v[172:173]
	v_pk_fma_f32 v[22:23], v[100:101], v[160:161], v[22:23]
	v_pk_fma_f32 v[172:173], v[50:51], v[18:19], v[172:173]
	v_add_f32_e32 v190, v22, v23
	v_mul_f32_e32 v23, v44, v21
	v_pk_fma_f32 v[20:21], v[44:45], v[20:21], v[104:105]
	v_pk_fma_f32 v[172:173], v[54:55], v[10:11], v[172:173]
	v_pk_fma_f32 v[20:21], v[48:49], v[18:19], v[20:21]
	v_pk_fma_f32 v[172:173], v[58:59], v[12:13], v[172:173]
	v_pk_fma_f32 v[20:21], v[52:53], v[10:11], v[20:21]
	v_pk_fma_f32 v[172:173], v[62:63], v[14:15], v[172:173]
	v_pk_fma_f32 v[20:21], v[56:57], v[12:13], v[20:21]
	v_pk_fma_f32 v[172:173], v[66:67], v[16:17], v[172:173]
	v_pk_fma_f32 v[20:21], v[60:61], v[14:15], v[20:21]
	v_pk_fma_f32 v[172:173], v[70:71], v[26:27], v[172:173]
	v_pk_fma_f32 v[20:21], v[64:65], v[16:17], v[20:21]
	v_pk_fma_f32 v[172:173], v[74:75], v[28:29], v[172:173]
	v_pk_fma_f32 v[20:21], v[68:69], v[26:27], v[20:21]
	v_pk_fma_f32 v[172:173], v[78:79], v[30:31], v[172:173]
	v_pk_fma_f32 v[20:21], v[72:73], v[28:29], v[20:21]
	v_pk_fma_f32 v[172:173], v[82:83], v[32:33], v[172:173]
	v_pk_fma_f32 v[20:21], v[76:77], v[30:31], v[20:21]
	v_pk_fma_f32 v[172:173], v[86:87], v[40:41], v[172:173]
	v_pk_fma_f32 v[20:21], v[80:81], v[32:33], v[20:21]
	v_pk_fma_f32 v[172:173], v[90:91], v[156:157], v[172:173]
	v_pk_fma_f32 v[20:21], v[84:85], v[40:41], v[20:21]
	v_pk_fma_f32 v[172:173], v[94:95], v[158:159], v[172:173]
	v_pk_fma_f32 v[20:21], v[88:89], v[156:157], v[20:21]
	v_pk_fma_f32 v[172:173], v[98:99], v[160:161], v[172:173]
	v_pk_fma_f32 v[20:21], v[92:93], v[158:159], v[20:21]
	v_pk_fma_f32 v[172:173], v[102:103], v[24:25], v[172:173]
	v_pk_fma_f32 v[20:21], v[96:97], v[160:161], v[20:21]
	v_mov_b32_e32 v22, v104
	v_pk_fma_f32 v[20:21], v[100:101], v[24:25], v[20:21]
	s_waitcnt lgkmcnt(1)
	v_mul_f32_e32 v105, v103, v36
	v_add_f32_e32 v172, v172, v173
	v_pk_fma_f32 v[22:23], v[46:47], v[18:19], v[22:23]
	v_add_f32_e32 v173, v20, v21
	v_mul_f32_e32 v21, v44, v19
	v_pk_fma_f32 v[18:19], v[44:45], v[18:19], v[104:105]
	v_pk_fma_f32 v[22:23], v[50:51], v[10:11], v[22:23]
	v_pk_fma_f32 v[18:19], v[48:49], v[10:11], v[18:19]
	v_pk_fma_f32 v[22:23], v[54:55], v[12:13], v[22:23]
	v_pk_fma_f32 v[18:19], v[52:53], v[12:13], v[18:19]
	v_pk_fma_f32 v[22:23], v[58:59], v[14:15], v[22:23]
	v_pk_fma_f32 v[18:19], v[56:57], v[14:15], v[18:19]
	v_pk_fma_f32 v[22:23], v[62:63], v[16:17], v[22:23]
	v_pk_fma_f32 v[18:19], v[60:61], v[16:17], v[18:19]
	v_pk_fma_f32 v[22:23], v[66:67], v[26:27], v[22:23]
	v_pk_fma_f32 v[18:19], v[64:65], v[26:27], v[18:19]
	v_pk_fma_f32 v[22:23], v[70:71], v[28:29], v[22:23]
	v_pk_fma_f32 v[18:19], v[68:69], v[28:29], v[18:19]
	v_pk_fma_f32 v[22:23], v[74:75], v[30:31], v[22:23]
	v_pk_fma_f32 v[18:19], v[72:73], v[30:31], v[18:19]
	v_pk_fma_f32 v[22:23], v[78:79], v[32:33], v[22:23]
	v_pk_fma_f32 v[18:19], v[76:77], v[32:33], v[18:19]
	v_pk_fma_f32 v[22:23], v[82:83], v[40:41], v[22:23]
	v_pk_fma_f32 v[18:19], v[80:81], v[40:41], v[18:19]
	v_pk_fma_f32 v[22:23], v[86:87], v[156:157], v[22:23]
	v_pk_fma_f32 v[18:19], v[84:85], v[156:157], v[18:19]
	v_pk_fma_f32 v[22:23], v[90:91], v[158:159], v[22:23]
	v_pk_fma_f32 v[18:19], v[88:89], v[158:159], v[18:19]
	v_pk_fma_f32 v[22:23], v[94:95], v[160:161], v[22:23]
	v_pk_fma_f32 v[18:19], v[92:93], v[160:161], v[18:19]
	v_pk_fma_f32 v[22:23], v[98:99], v[24:25], v[22:23]
	v_pk_fma_f32 v[18:19], v[96:97], v[24:25], v[18:19]
	v_pk_fma_f32 v[22:23], v[102:103], v[34:35], v[22:23]
	v_pk_fma_f32 v[18:19], v[100:101], v[34:35], v[18:19]
	v_add_f32_e32 v22, v22, v23
	v_mov_b32_e32 v20, v104
	v_add_f32_e32 v23, v18, v19
	s_waitcnt lgkmcnt(0)
	v_mul_f32_e32 v105, v103, v38
	v_mul_f32_e32 v19, v44, v11
	v_mov_b32_e32 v18, v104
	v_pk_fma_f32 v[20:21], v[46:47], v[10:11], v[20:21]
	v_pk_fma_f32 v[10:11], v[44:45], v[10:11], v[104:105]
	v_pk_fma_f32 v[18:19], v[46:47], v[12:13], v[18:19]
	v_pk_fma_f32 v[20:21], v[50:51], v[12:13], v[20:21]
	v_pk_fma_f32 v[10:11], v[48:49], v[12:13], v[10:11]
	v_pk_fma_f32 v[12:13], v[50:51], v[14:15], v[18:19]
	v_pk_fma_f32 v[20:21], v[54:55], v[14:15], v[20:21]
	v_pk_fma_f32 v[10:11], v[52:53], v[14:15], v[10:11]
	v_pk_fma_f32 v[12:13], v[54:55], v[16:17], v[12:13]
	v_pk_fma_f32 v[20:21], v[58:59], v[16:17], v[20:21]
	v_pk_fma_f32 v[10:11], v[56:57], v[16:17], v[10:11]
	v_pk_fma_f32 v[12:13], v[58:59], v[26:27], v[12:13]
	v_pk_fma_f32 v[20:21], v[62:63], v[26:27], v[20:21]
	v_pk_fma_f32 v[10:11], v[60:61], v[26:27], v[10:11]
	v_pk_fma_f32 v[12:13], v[62:63], v[28:29], v[12:13]
	v_pk_fma_f32 v[20:21], v[66:67], v[28:29], v[20:21]
	v_pk_fma_f32 v[10:11], v[64:65], v[28:29], v[10:11]
	v_pk_fma_f32 v[12:13], v[66:67], v[30:31], v[12:13]
	v_pk_fma_f32 v[20:21], v[70:71], v[30:31], v[20:21]
	v_pk_fma_f32 v[10:11], v[68:69], v[30:31], v[10:11]
	v_pk_fma_f32 v[12:13], v[70:71], v[32:33], v[12:13]
	v_pk_fma_f32 v[20:21], v[74:75], v[32:33], v[20:21]
	v_pk_fma_f32 v[10:11], v[72:73], v[32:33], v[10:11]
	v_pk_fma_f32 v[12:13], v[74:75], v[40:41], v[12:13]
	v_pk_fma_f32 v[20:21], v[78:79], v[40:41], v[20:21]
	v_pk_fma_f32 v[10:11], v[76:77], v[40:41], v[10:11]
	v_pk_fma_f32 v[12:13], v[78:79], v[156:157], v[12:13]
	v_pk_fma_f32 v[20:21], v[82:83], v[156:157], v[20:21]
	v_pk_fma_f32 v[10:11], v[80:81], v[156:157], v[10:11]
	v_pk_fma_f32 v[12:13], v[82:83], v[158:159], v[12:13]
	v_pk_fma_f32 v[20:21], v[86:87], v[158:159], v[20:21]
	v_pk_fma_f32 v[10:11], v[84:85], v[158:159], v[10:11]
	v_pk_fma_f32 v[12:13], v[86:87], v[160:161], v[12:13]
	v_pk_fma_f32 v[20:21], v[90:91], v[160:161], v[20:21]
	v_pk_fma_f32 v[10:11], v[88:89], v[160:161], v[10:11]
	v_pk_fma_f32 v[12:13], v[90:91], v[24:25], v[12:13]
	v_pk_fma_f32 v[20:21], v[94:95], v[24:25], v[20:21]
	v_pk_fma_f32 v[10:11], v[92:93], v[24:25], v[10:11]
	v_pk_fma_f32 v[12:13], v[94:95], v[34:35], v[12:13]
	s_lshl_b32 s6, s28, 10
	v_pk_fma_f32 v[20:21], v[98:99], v[34:35], v[20:21]
	v_pk_fma_f32 v[10:11], v[96:97], v[34:35], v[10:11]
	v_pk_fma_f32 v[12:13], v[98:99], v[36:37], v[12:13]
	s_add_i32 s6, s6, 0
	v_pk_fma_f32 v[20:21], v[102:103], v[36:37], v[20:21]
	v_pk_fma_f32 v[10:11], v[100:101], v[36:37], v[10:11]
	v_pk_fma_f32 v[12:13], v[102:103], v[38:39], v[12:13]
	v_add_u32_e32 v105, s6, v162
	v_add_f32_e32 v20, v20, v21
	v_add_f32_e32 v10, v10, v11
	v_add_f32_e32 v11, v12, v13
	s_barrier
	ds_write2st64_b32 v163, v164, v165 offset1:4
	ds_write2st64_b32 v163, v166, v167 offset0:8 offset1:12
	ds_write2st64_b32 v163, v168, v169 offset0:16 offset1:20
	ds_write2st64_b32 v163, v170, v171 offset0:24 offset1:28
	ds_write2st64_b32 v163, v174, v175 offset0:32 offset1:36
	ds_write2st64_b32 v163, v176, v177 offset0:40 offset1:44
	ds_write2st64_b32 v163, v178, v179 offset0:48 offset1:52
	ds_write2st64_b32 v163, v180, v181 offset0:56 offset1:60
	ds_write2st64_b32 v163, v182, v183 offset0:64 offset1:68
	ds_write2st64_b32 v163, v184, v185 offset0:72 offset1:76
	ds_write2st64_b32 v163, v186, v187 offset0:80 offset1:84
	ds_write2st64_b32 v163, v188, v189 offset0:88 offset1:92
	ds_write2st64_b32 v163, v190, v172 offset0:96 offset1:100
	ds_write2st64_b32 v163, v173, v22 offset0:104 offset1:108
	ds_write2st64_b32 v163, v23, v20 offset0:112 offset1:116
	ds_write2st64_b32 v163, v10, v11 offset0:120 offset1:124
	s_waitcnt lgkmcnt(0)
	s_barrier
	ds_read_b128 v[38:41], v105
	ds_read_b128 v[34:37], v105 offset:8192
	ds_read_b128 v[30:33], v105 offset:16384
	ds_read_b128 v[26:29], v105 offset:24576
	ds_read_b128 v[22:25], v105 offset:32768
	ds_read_b128 v[18:21], v105 offset:40960
	s_waitcnt lgkmcnt(5)
	v_mov_b32_e32 v10, v39
	v_mov_b32_e32 v11, v40
	v_mov_b32_e32 v12, v38
	v_mov_b32_e32 v13, v41
	v_pk_add_f32 v[10:11], v[10:11], v[12:13]
	s_waitcnt lgkmcnt(4)
	v_mov_b32_e32 v12, v34
	v_add_f32_e32 v160, v10, v11
	v_mov_b32_e32 v10, v35
	v_mov_b32_e32 v11, v36
	v_mov_b32_e32 v13, v37
	v_pk_add_f32 v[10:11], v[10:11], v[12:13]
	s_waitcnt lgkmcnt(3)
	v_mov_b32_e32 v12, v30
	v_add_f32_e32 v161, v10, v11
	v_mov_b32_e32 v10, v31
	v_mov_b32_e32 v11, v32
	v_mov_b32_e32 v13, v33
	v_pk_add_f32 v[10:11], v[10:11], v[12:13]
	s_waitcnt lgkmcnt(2)
	v_mov_b32_e32 v12, v26
	v_add_f32_e32 v162, v10, v11
	v_mov_b32_e32 v10, v27
	v_mov_b32_e32 v11, v28
	v_mov_b32_e32 v13, v29
	v_pk_add_f32 v[10:11], v[10:11], v[12:13]
	s_waitcnt lgkmcnt(1)
	v_mov_b32_e32 v12, v22
	v_add_f32_e32 v163, v10, v11
	v_mov_b32_e32 v10, v23
	v_mov_b32_e32 v11, v24
	v_mov_b32_e32 v13, v25
	v_pk_add_f32 v[10:11], v[10:11], v[12:13]
	s_waitcnt lgkmcnt(0)
	v_mov_b32_e32 v12, v18
	v_add_f32_e32 v164, v10, v11
	v_mov_b32_e32 v10, v19
	v_mov_b32_e32 v11, v20
	ds_read_b128 v[14:17], v105 offset:49152
	v_mov_b32_e32 v13, v21
	v_pk_add_f32 v[10:11], v[10:11], v[12:13]
	s_add_i32 s28, s52, s28
	v_add_f32_e32 v165, v10, v11
	ds_read_b128 v[10:13], v105 offset:57344
	s_waitcnt lgkmcnt(1)
	v_mov_b32_e32 v156, v15
	v_mov_b32_e32 v157, v16
	v_mov_b32_e32 v158, v14
	v_mov_b32_e32 v159, v17
	v_pk_add_f32 v[156:157], v[156:157], v[158:159]
	s_waitcnt lgkmcnt(0)
	v_mov_b32_e32 v158, v10
	v_add_f32_e32 v105, v156, v157
	v_mov_b32_e32 v156, v11
	v_mov_b32_e32 v157, v12
	v_mov_b32_e32 v159, v13
	v_pk_add_f32 v[156:157], v[156:157], v[158:159]
	v_add_f32_dpp v158, v161, v161 quad_perm:[1,0,3,2] row_mask:0xf bank_mask:0xf bound_ctrl:1
	v_add_f32_e32 v156, v156, v157
	v_add_f32_dpp v157, v160, v160 quad_perm:[1,0,3,2] row_mask:0xf bank_mask:0xf bound_ctrl:1
	v_add_f32_dpp v160, v163, v163 quad_perm:[1,0,3,2] row_mask:0xf bank_mask:0xf bound_ctrl:1
	v_add_f32_dpp v158, v158, v158 quad_perm:[2,3,0,1] row_mask:0xf bank_mask:0xf bound_ctrl:1
	v_add_f32_dpp v157, v157, v157 quad_perm:[2,3,0,1] row_mask:0xf bank_mask:0xf bound_ctrl:1
	v_add_f32_dpp v159, v162, v162 quad_perm:[1,0,3,2] row_mask:0xf bank_mask:0xf bound_ctrl:1
	s_nop 0
	v_add_f32_dpp v157, v157, v157 row_half_mirror row_mask:0xf bank_mask:0xf bound_ctrl:1
	v_add_f32_dpp v158, v158, v158 row_half_mirror row_mask:0xf bank_mask:0xf bound_ctrl:1
	v_add_f32_dpp v159, v159, v159 quad_perm:[2,3,0,1] row_mask:0xf bank_mask:0xf bound_ctrl:1
	v_add_f32_dpp v157, v157, v157 row_mirror row_mask:0xf bank_mask:0xf bound_ctrl:1
	v_add_f32_dpp v158, v158, v158 row_mirror row_mask:0xf bank_mask:0xf bound_ctrl:1
	v_add_f32_dpp v159, v159, v159 row_half_mirror row_mask:0xf bank_mask:0xf bound_ctrl:1
	v_add_f32_dpp v157, v157, v157 row_bcast:15 row_mask:0xa bank_mask:0xf
	v_add_f32_dpp v160, v160, v160 quad_perm:[2,3,0,1] row_mask:0xf bank_mask:0xf bound_ctrl:1
	v_add_f32_dpp v159, v159, v159 row_mirror row_mask:0xf bank_mask:0xf bound_ctrl:1
	v_add_f32_dpp v158, v158, v158 row_bcast:15 row_mask:0xa bank_mask:0xf
	v_add_f32_dpp v161, v164, v164 quad_perm:[1,0,3,2] row_mask:0xf bank_mask:0xf bound_ctrl:1
	v_add_f32_dpp v160, v160, v160 row_half_mirror row_mask:0xf bank_mask:0xf bound_ctrl:1
	v_add_f32_dpp v159, v159, v159 row_bcast:15 row_mask:0xa bank_mask:0xf
	v_add_f32_dpp v161, v161, v161 quad_perm:[2,3,0,1] row_mask:0xf bank_mask:0xf bound_ctrl:1
	v_add_f32_dpp v160, v160, v160 row_mirror row_mask:0xf bank_mask:0xf bound_ctrl:1
	v_add_f32_dpp v162, v165, v165 quad_perm:[1,0,3,2] row_mask:0xf bank_mask:0xf bound_ctrl:1
	v_add_f32_dpp v161, v161, v161 row_half_mirror row_mask:0xf bank_mask:0xf bound_ctrl:1
	v_add_f32_dpp v160, v160, v160 row_bcast:15 row_mask:0xa bank_mask:0xf
	v_add_f32_dpp v162, v162, v162 quad_perm:[2,3,0,1] row_mask:0xf bank_mask:0xf bound_ctrl:1
	v_add_f32_dpp v161, v161, v161 row_mirror row_mask:0xf bank_mask:0xf bound_ctrl:1
	v_add_f32_dpp v105, v105, v105 quad_perm:[1,0,3,2] row_mask:0xf bank_mask:0xf bound_ctrl:1
	v_add_f32_dpp v162, v162, v162 row_half_mirror row_mask:0xf bank_mask:0xf bound_ctrl:1
	v_add_f32_dpp v161, v161, v161 row_bcast:15 row_mask:0xa bank_mask:0xf
	v_add_f32_dpp v105, v105, v105 quad_perm:[2,3,0,1] row_mask:0xf bank_mask:0xf bound_ctrl:1
	v_add_f32_dpp v162, v162, v162 row_mirror row_mask:0xf bank_mask:0xf bound_ctrl:1
	v_add_f32_dpp v156, v156, v156 quad_perm:[1,0,3,2] row_mask:0xf bank_mask:0xf bound_ctrl:1
	v_add_f32_dpp v105, v105, v105 row_half_mirror row_mask:0xf bank_mask:0xf bound_ctrl:1
	v_add_f32_dpp v162, v162, v162 row_bcast:15 row_mask:0xa bank_mask:0xf
	v_add_f32_dpp v156, v156, v156 quad_perm:[2,3,0,1] row_mask:0xf bank_mask:0xf bound_ctrl:1
	v_add_f32_dpp v105, v105, v105 row_mirror row_mask:0xf bank_mask:0xf bound_ctrl:1
	s_nop 0
	v_add_f32_dpp v156, v156, v156 row_half_mirror row_mask:0xf bank_mask:0xf bound_ctrl:1
	s_nop 0
	v_add_f32_dpp v105, v105, v105 row_bcast:15 row_mask:0xa bank_mask:0xf
	v_add_f32_dpp v156, v156, v156 row_mirror row_mask:0xf bank_mask:0xf bound_ctrl:1
	s_nop 1
	v_add_f32_dpp v156, v156, v156 row_bcast:15 row_mask:0xa bank_mask:0xf
	s_nop 1
	v_add_f32_dpp v157, v157, v157 row_bcast:31 row_mask:0xc bank_mask:0xf
	s_nop 0
	v_readlane_b32 s6, v157, 63
	s_nop 0
	v_add_f32_dpp v158, v158, v158 row_bcast:31 row_mask:0xc bank_mask:0xf
	v_fma_f32 v39, s6, v239, v39
	v_fma_f32 v38, s6, v239, v38
	v_add_f32_dpp v159, v159, v159 row_bcast:31 row_mask:0xc bank_mask:0xf
	v_fma_f32 v41, s6, v239, v41
	v_fmac_f32_e32 v40, s6, v239
	v_add_f32_dpp v160, v160, v160 row_bcast:31 row_mask:0xc bank_mask:0xf
	v_readlane_b32 s7, v158, 63
	v_readlane_b32 s8, v159, 63
	v_add_f32_dpp v161, v161, v161 row_bcast:31 row_mask:0xc bank_mask:0xf
	v_pk_mul_f32 v[158:159], v[38:39], v[38:39]
	v_readlane_b32 s9, v160, 63
	v_add_f32_dpp v162, v162, v162 row_bcast:31 row_mask:0xc bank_mask:0xf
	v_readlane_b32 s10, v161, 63
	v_fma_f32 v35, s7, v239, v35
	v_add_f32_dpp v105, v105, v105 row_bcast:31 row_mask:0xc bank_mask:0xf
	v_fma_f32 v34, s7, v239, v34
	v_fma_f32 v37, s7, v239, v37
	v_add_f32_dpp v156, v156, v156 row_bcast:31 row_mask:0xc bank_mask:0xf
	v_fmac_f32_e32 v36, s7, v239
	v_readlane_b32 s55, v156, 63
	v_pk_mul_f32 v[156:157], v[40:41], v[40:41]
	v_readlane_b32 s29, v105, 63
	v_pk_mov_b32 v[160:161], v[158:159], v[156:157] op_sel:[1,0]
	v_mov_b32_e32 v159, v157
	v_pk_add_f32 v[156:157], v[160:161], v[158:159]
	v_pk_mul_f32 v[158:159], v[34:35], v[34:35]
	v_add_f32_e32 v105, v156, v157
	v_pk_mul_f32 v[156:157], v[36:37], v[36:37]
	v_fma_f32 v31, s8, v239, v31
	v_pk_mov_b32 v[160:161], v[158:159], v[156:157] op_sel:[1,0]
	v_mov_b32_e32 v159, v157
	v_pk_add_f32 v[156:157], v[160:161], v[158:159]
	v_fma_f32 v30, s8, v239, v30
	v_fma_f32 v33, s8, v239, v33
	v_fmac_f32_e32 v32, s8, v239
	v_readlane_b32 s11, v162, 63
	v_add_f32_e32 v162, v156, v157
	v_pk_mul_f32 v[156:157], v[32:33], v[32:33]
	v_pk_mul_f32 v[158:159], v[30:31], v[30:31]
	v_fma_f32 v27, s9, v239, v27
	v_pk_mov_b32 v[160:161], v[158:159], v[156:157] op_sel:[1,0]
	v_mov_b32_e32 v159, v157
	v_pk_add_f32 v[156:157], v[160:161], v[158:159]
	v_fma_f32 v26, s9, v239, v26
	v_fma_f32 v29, s9, v239, v29
	v_fmac_f32_e32 v28, s9, v239
	v_add_f32_e32 v163, v156, v157
	v_pk_mul_f32 v[156:157], v[28:29], v[28:29]
	v_pk_mul_f32 v[158:159], v[26:27], v[26:27]
	v_fma_f32 v23, s10, v239, v23
	v_pk_mov_b32 v[160:161], v[158:159], v[156:157] op_sel:[1,0]
	v_mov_b32_e32 v159, v157
	v_pk_add_f32 v[156:157], v[160:161], v[158:159]
	v_fma_f32 v22, s10, v239, v22
	v_fma_f32 v25, s10, v239, v25
	v_fmac_f32_e32 v24, s10, v239
	v_add_f32_e32 v164, v156, v157
	v_pk_mul_f32 v[156:157], v[24:25], v[24:25]
	v_pk_mul_f32 v[158:159], v[22:23], v[22:23]
	v_fma_f32 v19, s11, v239, v19
	v_pk_mov_b32 v[160:161], v[158:159], v[156:157] op_sel:[1,0]
	v_mov_b32_e32 v159, v157
	v_pk_add_f32 v[156:157], v[160:161], v[158:159]
	v_fma_f32 v18, s11, v239, v18
	v_fma_f32 v21, s11, v239, v21
	v_fmac_f32_e32 v20, s11, v239
	v_add_f32_e32 v165, v156, v157
	v_pk_mul_f32 v[156:157], v[20:21], v[20:21]
	v_pk_mul_f32 v[158:159], v[18:19], v[18:19]
	v_fma_f32 v15, s29, v239, v15
	v_pk_mov_b32 v[160:161], v[158:159], v[156:157] op_sel:[1,0]
	v_mov_b32_e32 v159, v157
	v_pk_add_f32 v[156:157], v[160:161], v[158:159]
	v_fma_f32 v14, s29, v239, v14
	v_fma_f32 v17, s29, v239, v17
	v_fmac_f32_e32 v16, s29, v239
	v_add_f32_e32 v166, v156, v157
	v_pk_mul_f32 v[156:157], v[16:17], v[16:17]
	v_pk_mul_f32 v[158:159], v[14:15], v[14:15]
	v_fma_f32 v11, s55, v239, v11
	v_pk_mov_b32 v[160:161], v[158:159], v[156:157] op_sel:[1,0]
	v_mov_b32_e32 v159, v157
	v_pk_add_f32 v[156:157], v[160:161], v[158:159]
	v_fma_f32 v10, s55, v239, v10
	v_fma_f32 v13, s55, v239, v13
	v_fmac_f32_e32 v12, s55, v239
	v_add_f32_e32 v167, v156, v157
	v_pk_mul_f32 v[156:157], v[12:13], v[12:13]
	v_pk_mul_f32 v[158:159], v[10:11], v[10:11]
	v_add_f32_dpp v105, v105, v105 quad_perm:[1,0,3,2] row_mask:0xf bank_mask:0xf bound_ctrl:1
	v_pk_mov_b32 v[160:161], v[158:159], v[156:157] op_sel:[1,0]
	v_mov_b32_e32 v159, v157
	v_pk_add_f32 v[156:157], v[160:161], v[158:159]
	v_add_f32_dpp v105, v105, v105 quad_perm:[2,3,0,1] row_mask:0xf bank_mask:0xf bound_ctrl:1
	v_add_f32_e32 v156, v156, v157
	v_add_f32_dpp v157, v162, v162 quad_perm:[1,0,3,2] row_mask:0xf bank_mask:0xf bound_ctrl:1
	v_add_f32_dpp v105, v105, v105 row_half_mirror row_mask:0xf bank_mask:0xf bound_ctrl:1
	v_add_f32_dpp v158, v163, v163 quad_perm:[1,0,3,2] row_mask:0xf bank_mask:0xf bound_ctrl:1
	v_add_f32_dpp v157, v157, v157 quad_perm:[2,3,0,1] row_mask:0xf bank_mask:0xf bound_ctrl:1
	v_add_f32_dpp v105, v105, v105 row_mirror row_mask:0xf bank_mask:0xf bound_ctrl:1
	s_nop 0
	v_add_f32_dpp v157, v157, v157 row_half_mirror row_mask:0xf bank_mask:0xf bound_ctrl:1
	v_add_f32_dpp v158, v158, v158 quad_perm:[2,3,0,1] row_mask:0xf bank_mask:0xf bound_ctrl:1
	v_add_f32_dpp v105, v105, v105 row_bcast:15 row_mask:0xa bank_mask:0xf
	v_add_f32_dpp v157, v157, v157 row_mirror row_mask:0xf bank_mask:0xf bound_ctrl:1
	v_add_f32_dpp v159, v164, v164 quad_perm:[1,0,3,2] row_mask:0xf bank_mask:0xf bound_ctrl:1
	v_add_f32_dpp v158, v158, v158 row_half_mirror row_mask:0xf bank_mask:0xf bound_ctrl:1
	v_add_f32_dpp v157, v157, v157 row_bcast:15 row_mask:0xa bank_mask:0xf
	v_add_f32_dpp v159, v159, v159 quad_perm:[2,3,0,1] row_mask:0xf bank_mask:0xf bound_ctrl:1
	v_add_f32_dpp v158, v158, v158 row_mirror row_mask:0xf bank_mask:0xf bound_ctrl:1
	v_add_f32_dpp v160, v165, v165 quad_perm:[1,0,3,2] row_mask:0xf bank_mask:0xf bound_ctrl:1
	v_add_f32_dpp v159, v159, v159 row_half_mirror row_mask:0xf bank_mask:0xf bound_ctrl:1
	v_add_f32_dpp v158, v158, v158 row_bcast:15 row_mask:0xa bank_mask:0xf
	v_add_f32_dpp v160, v160, v160 quad_perm:[2,3,0,1] row_mask:0xf bank_mask:0xf bound_ctrl:1
	v_add_f32_dpp v159, v159, v159 row_mirror row_mask:0xf bank_mask:0xf bound_ctrl:1
	v_add_f32_dpp v161, v166, v166 quad_perm:[1,0,3,2] row_mask:0xf bank_mask:0xf bound_ctrl:1
	v_add_f32_dpp v160, v160, v160 row_half_mirror row_mask:0xf bank_mask:0xf bound_ctrl:1
	v_add_f32_dpp v159, v159, v159 row_bcast:15 row_mask:0xa bank_mask:0xf
	v_add_f32_dpp v161, v161, v161 quad_perm:[2,3,0,1] row_mask:0xf bank_mask:0xf bound_ctrl:1
	v_add_f32_dpp v160, v160, v160 row_mirror row_mask:0xf bank_mask:0xf bound_ctrl:1
	v_add_f32_dpp v162, v167, v167 quad_perm:[1,0,3,2] row_mask:0xf bank_mask:0xf bound_ctrl:1
	v_add_f32_dpp v161, v161, v161 row_half_mirror row_mask:0xf bank_mask:0xf bound_ctrl:1
	v_add_f32_dpp v160, v160, v160 row_bcast:15 row_mask:0xa bank_mask:0xf
	v_add_f32_dpp v162, v162, v162 quad_perm:[2,3,0,1] row_mask:0xf bank_mask:0xf bound_ctrl:1
	v_add_f32_dpp v161, v161, v161 row_mirror row_mask:0xf bank_mask:0xf bound_ctrl:1
	v_add_f32_dpp v156, v156, v156 quad_perm:[1,0,3,2] row_mask:0xf bank_mask:0xf bound_ctrl:1
	v_add_f32_dpp v162, v162, v162 row_half_mirror row_mask:0xf bank_mask:0xf bound_ctrl:1
	v_add_f32_dpp v161, v161, v161 row_bcast:15 row_mask:0xa bank_mask:0xf
	v_add_f32_dpp v156, v156, v156 quad_perm:[2,3,0,1] row_mask:0xf bank_mask:0xf bound_ctrl:1
	v_add_f32_dpp v162, v162, v162 row_mirror row_mask:0xf bank_mask:0xf bound_ctrl:1
	s_nop 0
	v_add_f32_dpp v156, v156, v156 row_half_mirror row_mask:0xf bank_mask:0xf bound_ctrl:1
	s_add_i32 s8, s28, -8
	v_add_f32_dpp v162, v162, v162 row_bcast:15 row_mask:0xa bank_mask:0xf
	v_add_f32_dpp v156, v156, v156 row_mirror row_mask:0xf bank_mask:0xf bound_ctrl:1
	s_ashr_i32 s9, s8, 31
	s_lshl_b64 s[8:9], s[8:9], 11
	v_add_f32_dpp v156, v156, v156 row_bcast:15 row_mask:0xa bank_mask:0xf
	s_add_u32 s8, s76, s8
	s_addc_u32 s9, s77, s9
	v_add_f32_dpp v105, v105, v105 row_bcast:31 row_mask:0xc bank_mask:0xf
	s_nop 0
	v_readlane_b32 s6, v105, 63
	s_ashr_i32 s29, s28, 31
	v_add_f32_dpp v157, v157, v157 row_bcast:31 row_mask:0xc bank_mask:0xf
	v_fma_f32 v105, s6, v235, v225
	v_readlane_b32 s10, v157, 63
	v_add_f32_dpp v158, v158, v158 row_bcast:31 row_mask:0xc bank_mask:0xf
	s_nop 0
	v_readlane_b32 s11, v158, 63
	s_nop 0
	v_add_f32_dpp v159, v159, v159 row_bcast:31 row_mask:0xc bank_mask:0xf
	s_nop 0
	v_readlane_b32 s57, v159, 63
	s_nop 0
	v_add_f32_dpp v160, v160, v160 row_bcast:31 row_mask:0xc bank_mask:0xf
	s_nop 0
	v_readlane_b32 s56, v160, 63
	s_nop 0
	v_add_f32_dpp v161, v161, v161 row_bcast:31 row_mask:0xc bank_mask:0xf
	s_nop 0
	v_readlane_b32 s55, v161, 63
	s_nop 0
	v_add_f32_dpp v162, v162, v162 row_bcast:31 row_mask:0xc bank_mask:0xf
	v_mov_b32_e32 v163, v131
	v_readlane_b32 s7, v162, 63
	s_nop 0
	v_mov_b32_dpp v163, v156 row_bcast:31 row_mask:0xc bank_mask:0xf
	v_add_f32_e32 v163, v156, v163
	v_rsq_f32_e32 v156, v105
	v_readlane_b32 s6, v163, 63
	v_pk_mul_f32 v[38:39], v[38:39], v[156:157] op_sel_hi:[1,0]
	s_nop 0
	v_pk_fma_f32 v[38:39], v[2:3], v[38:39], v[6:7]
	v_pk_mul_f32 v[40:41], v[40:41], v[156:157] op_sel_hi:[1,0]
	v_mul_f32_e32 v105, 0xbfb8aa3b, v38
	v_exp_f32_e32 v105, v105
	v_mul_f32_e32 v156, 0xbfb8aa3b, v39
	v_exp_f32_e32 v157, v156
	v_pk_fma_f32 v[40:41], v[4:5], v[40:41], v[8:9]
	v_add_f32_e32 v105, 1.0, v105
	v_rcp_f32_e32 v156, v105
	v_add_f32_e32 v105, 1.0, v157
	v_mul_f32_e32 v157, 0xbfb8aa3b, v40
	v_exp_f32_e32 v158, v157
	v_mul_f32_e32 v157, 0xbfb8aa3b, v41
	v_exp_f32_e32 v159, v157
	v_rcp_f32_e32 v157, v105
	v_add_f32_e32 v105, 1.0, v158
	v_rcp_f32_e32 v158, v105
	v_add_f32_e32 v105, 1.0, v159
	v_rcp_f32_e32 v159, v105
	v_pk_mul_f32 v[38:39], v[38:39], v[156:157]
	v_lshlrev_b32_e32 v105, 3, v130
	v_cvt_pk_bf16_f32 v38, v38, v39
	v_pk_mul_f32 v[40:41], v[40:41], v[158:159]
	v_cvt_pk_bf16_f32 v39, v40, v41
	v_fma_f32 v40, s10, v235, v225
	v_rsq_f32_e32 v40, v40
	global_store_dwordx2 v105, v[38:39], s[8:9] offset:512
	s_lshl_b64 s[8:9], s[28:29], 11
	s_add_u32 s8, s76, s8
	v_pk_mul_f32 v[36:37], v[36:37], v[40:41] op_sel_hi:[1,0]
	v_pk_mul_f32 v[34:35], v[34:35], v[40:41] op_sel_hi:[1,0]
	v_pk_fma_f32 v[36:37], v[4:5], v[36:37], v[8:9]
	v_pk_fma_f32 v[34:35], v[2:3], v[34:35], v[6:7]
	v_mul_f32_e32 v130, 0xbfb8aa3b, v36
	v_mul_f32_e32 v40, 0xbfb8aa3b, v34
	v_mul_f32_e32 v41, 0xbfb8aa3b, v35
	v_exp_f32_e32 v130, v130
	v_mul_f32_e32 v156, 0xbfb8aa3b, v37
	v_exp_f32_e32 v40, v40
	v_exp_f32_e32 v41, v41
	v_exp_f32_e32 v157, v156
	v_add_f32_e32 v130, 1.0, v130
	v_add_f32_e32 v40, 1.0, v40
	v_add_f32_e32 v41, 1.0, v41
	v_rcp_f32_e32 v156, v130
	v_add_f32_e32 v130, 1.0, v157
	v_rcp_f32_e32 v40, v40
	v_rcp_f32_e32 v41, v41
	v_rcp_f32_e32 v157, v130
	s_addc_u32 s9, s77, s9
	v_pk_mul_f32 v[34:35], v[34:35], v[40:41]
	v_pk_mul_f32 v[36:37], v[36:37], v[156:157]
	v_cvt_pk_bf16_f32 v34, v34, v35
	v_cvt_pk_bf16_f32 v35, v36, v37
	v_fma_f32 v36, s11, v235, v225
	v_rsq_f32_e32 v36, v36
	global_store_dwordx2 v105, v[34:35], s[8:9] offset:512
	s_add_i32 s8, s28, 8
	s_ashr_i32 s9, s8, 31
	v_pk_mul_f32 v[30:31], v[30:31], v[36:37] op_sel_hi:[1,0]
	v_pk_mul_f32 v[32:33], v[32:33], v[36:37] op_sel_hi:[1,0]
	v_pk_fma_f32 v[30:31], v[2:3], v[30:31], v[6:7]
	v_pk_fma_f32 v[32:33], v[4:5], v[32:33], v[8:9]
	v_mul_f32_e32 v36, 0xbfb8aa3b, v30
	v_mul_f32_e32 v37, 0xbfb8aa3b, v31
	v_mul_f32_e32 v38, 0xbfb8aa3b, v32
	v_mul_f32_e32 v39, 0xbfb8aa3b, v33
	v_exp_f32_e32 v36, v36
	v_exp_f32_e32 v37, v37
	v_exp_f32_e32 v38, v38
	v_exp_f32_e32 v39, v39
	v_add_f32_e32 v36, 1.0, v36
	v_add_f32_e32 v37, 1.0, v37
	v_add_f32_e32 v38, 1.0, v38
	v_add_f32_e32 v39, 1.0, v39
	v_rcp_f32_e32 v36, v36
	v_rcp_f32_e32 v37, v37
	v_rcp_f32_e32 v38, v38
	v_rcp_f32_e32 v39, v39
	s_lshl_b64 s[8:9], s[8:9], 11
	v_pk_mul_f32 v[30:31], v[30:31], v[36:37]
	s_add_u32 s8, s76, s8
	v_pk_mul_f32 v[32:33], v[32:33], v[38:39]
	v_cvt_pk_bf16_f32 v30, v30, v31
	v_cvt_pk_bf16_f32 v31, v32, v33
	v_fma_f32 v32, s57, v235, v225
	v_rsq_f32_e32 v32, v32
	s_addc_u32 s9, s77, s9
	global_store_dwordx2 v105, v[30:31], s[8:9] offset:512
	s_add_i32 s8, s28, 16
	v_pk_mul_f32 v[26:27], v[26:27], v[32:33] op_sel_hi:[1,0]
	v_pk_mul_f32 v[28:29], v[28:29], v[32:33] op_sel_hi:[1,0]
	v_pk_fma_f32 v[26:27], v[2:3], v[26:27], v[6:7]
	v_pk_fma_f32 v[28:29], v[4:5], v[28:29], v[8:9]
	v_mul_f32_e32 v32, 0xbfb8aa3b, v26
	v_mul_f32_e32 v33, 0xbfb8aa3b, v27
	v_mul_f32_e32 v34, 0xbfb8aa3b, v28
	v_mul_f32_e32 v35, 0xbfb8aa3b, v29
	v_exp_f32_e32 v32, v32
	v_exp_f32_e32 v33, v33
	v_exp_f32_e32 v34, v34
	v_exp_f32_e32 v35, v35
	v_add_f32_e32 v32, 1.0, v32
	v_add_f32_e32 v33, 1.0, v33
	v_add_f32_e32 v34, 1.0, v34
	v_add_f32_e32 v35, 1.0, v35
	v_rcp_f32_e32 v32, v32
	v_rcp_f32_e32 v33, v33
	v_rcp_f32_e32 v34, v34
	v_rcp_f32_e32 v35, v35
	s_ashr_i32 s9, s8, 31
	v_pk_mul_f32 v[26:27], v[26:27], v[32:33]
	s_lshl_b64 s[8:9], s[8:9], 11
	v_pk_mul_f32 v[28:29], v[28:29], v[34:35]
	v_cvt_pk_bf16_f32 v26, v26, v27
	v_cvt_pk_bf16_f32 v27, v28, v29
	v_fma_f32 v28, s56, v235, v225
	v_rsq_f32_e32 v28, v28
	s_add_u32 s8, s76, s8
	s_addc_u32 s9, s77, s9
	global_store_dwordx2 v105, v[26:27], s[8:9] offset:512
	v_pk_mul_f32 v[22:23], v[22:23], v[28:29] op_sel_hi:[1,0]
	v_pk_mul_f32 v[24:25], v[24:25], v[28:29] op_sel_hi:[1,0]
	v_pk_fma_f32 v[22:23], v[2:3], v[22:23], v[6:7]
	v_pk_fma_f32 v[24:25], v[4:5], v[24:25], v[8:9]
	v_mul_f32_e32 v28, 0xbfb8aa3b, v22
	v_mul_f32_e32 v29, 0xbfb8aa3b, v23
	v_mul_f32_e32 v30, 0xbfb8aa3b, v24
	v_mul_f32_e32 v31, 0xbfb8aa3b, v25
	v_exp_f32_e32 v28, v28
	v_exp_f32_e32 v29, v29
	v_exp_f32_e32 v30, v30
	v_exp_f32_e32 v31, v31
	v_add_f32_e32 v28, 1.0, v28
	v_add_f32_e32 v29, 1.0, v29
	v_add_f32_e32 v30, 1.0, v30
	v_add_f32_e32 v31, 1.0, v31
	v_rcp_f32_e32 v28, v28
	v_rcp_f32_e32 v29, v29
	v_rcp_f32_e32 v30, v30
	v_rcp_f32_e32 v31, v31
	s_add_i32 s8, s28, 24
	v_pk_mul_f32 v[22:23], v[22:23], v[28:29]
	s_ashr_i32 s9, s8, 31
	v_pk_mul_f32 v[24:25], v[24:25], v[30:31]
	v_cvt_pk_bf16_f32 v22, v22, v23
	v_cvt_pk_bf16_f32 v23, v24, v25
	v_fma_f32 v24, s55, v235, v225
	v_rsq_f32_e32 v24, v24
	s_lshl_b64 s[8:9], s[8:9], 11
	s_add_u32 s8, s76, s8
	s_addc_u32 s9, s77, s9
	v_pk_mul_f32 v[18:19], v[18:19], v[24:25] op_sel_hi:[1,0]
	v_pk_mul_f32 v[20:21], v[20:21], v[24:25] op_sel_hi:[1,0]
	v_pk_fma_f32 v[18:19], v[2:3], v[18:19], v[6:7]
	v_pk_fma_f32 v[20:21], v[4:5], v[20:21], v[8:9]
	v_mul_f32_e32 v24, 0xbfb8aa3b, v18
	v_mul_f32_e32 v25, 0xbfb8aa3b, v19
	v_mul_f32_e32 v26, 0xbfb8aa3b, v20
	v_mul_f32_e32 v27, 0xbfb8aa3b, v21
	v_exp_f32_e32 v24, v24
	v_exp_f32_e32 v25, v25
	v_exp_f32_e32 v26, v26
	v_exp_f32_e32 v27, v27
	v_add_f32_e32 v24, 1.0, v24
	v_add_f32_e32 v25, 1.0, v25
	v_add_f32_e32 v26, 1.0, v26
	v_add_f32_e32 v27, 1.0, v27
	v_rcp_f32_e32 v24, v24
	v_rcp_f32_e32 v25, v25
	v_rcp_f32_e32 v26, v26
	v_rcp_f32_e32 v27, v27
	global_store_dwordx2 v105, v[22:23], s[8:9] offset:512
	v_pk_mul_f32 v[18:19], v[18:19], v[24:25]
	s_add_i32 s8, s28, 32
	v_pk_mul_f32 v[20:21], v[20:21], v[26:27]
	v_cvt_pk_bf16_f32 v18, v18, v19
	v_cvt_pk_bf16_f32 v19, v20, v21
	v_fma_f32 v20, s7, v235, v225
	v_rsq_f32_e32 v20, v20
	s_ashr_i32 s9, s8, 31
	s_lshl_b64 s[8:9], s[8:9], 11
	s_add_u32 s8, s76, s8
	v_pk_mul_f32 v[14:15], v[14:15], v[20:21] op_sel_hi:[1,0]
	v_pk_mul_f32 v[16:17], v[16:17], v[20:21] op_sel_hi:[1,0]
	v_pk_fma_f32 v[14:15], v[2:3], v[14:15], v[6:7]
	v_pk_fma_f32 v[16:17], v[4:5], v[16:17], v[8:9]
	v_mul_f32_e32 v20, 0xbfb8aa3b, v14
	v_mul_f32_e32 v21, 0xbfb8aa3b, v15
	v_mul_f32_e32 v22, 0xbfb8aa3b, v16
	v_mul_f32_e32 v23, 0xbfb8aa3b, v17
	v_exp_f32_e32 v20, v20
	v_exp_f32_e32 v21, v21
	v_exp_f32_e32 v22, v22
	v_exp_f32_e32 v23, v23
	v_add_f32_e32 v20, 1.0, v20
	v_add_f32_e32 v21, 1.0, v21
	v_add_f32_e32 v22, 1.0, v22
	v_add_f32_e32 v23, 1.0, v23
	v_rcp_f32_e32 v20, v20
	v_rcp_f32_e32 v21, v21
	v_rcp_f32_e32 v22, v22
	v_rcp_f32_e32 v23, v23
	s_addc_u32 s9, s77, s9
	v_pk_mul_f32 v[14:15], v[14:15], v[20:21]
	global_store_dwordx2 v105, v[18:19], s[8:9] offset:512
	v_pk_mul_f32 v[16:17], v[16:17], v[22:23]
	v_cvt_pk_bf16_f32 v14, v14, v15
	v_cvt_pk_bf16_f32 v15, v16, v17
	v_fma_f32 v16, s6, v235, v225
	v_rsq_f32_e32 v16, v16
	s_add_i32 s8, s28, 40
	s_ashr_i32 s9, s8, 31
	s_lshl_b64 s[6:7], s[8:9], 11
	v_pk_mul_f32 v[10:11], v[10:11], v[16:17] op_sel_hi:[1,0]
	v_pk_mul_f32 v[12:13], v[12:13], v[16:17] op_sel_hi:[1,0]
	v_pk_fma_f32 v[10:11], v[2:3], v[10:11], v[6:7]
	v_pk_fma_f32 v[12:13], v[4:5], v[12:13], v[8:9]
	v_mul_f32_e32 v16, 0xbfb8aa3b, v10
	v_mul_f32_e32 v17, 0xbfb8aa3b, v11
	v_mul_f32_e32 v18, 0xbfb8aa3b, v12
	v_mul_f32_e32 v19, 0xbfb8aa3b, v13
	v_exp_f32_e32 v16, v16
	v_exp_f32_e32 v17, v17
	v_exp_f32_e32 v18, v18
	v_exp_f32_e32 v19, v19
	s_add_u32 s6, s76, s6
	v_add_f32_e32 v16, 1.0, v16
	v_add_f32_e32 v17, 1.0, v17
	v_add_f32_e32 v18, 1.0, v18
	v_add_f32_e32 v19, 1.0, v19
	s_addc_u32 s7, s77, s7
	v_rcp_f32_e32 v16, v16
	v_rcp_f32_e32 v17, v17
	v_rcp_f32_e32 v18, v18
	v_rcp_f32_e32 v19, v19
	global_store_dwordx2 v105, v[14:15], s[6:7] offset:512
	s_add_i32 s6, s28, 48
	s_ashr_i32 s7, s6, 31
	s_lshl_b64 s[6:7], s[6:7], 11
	v_pk_mul_f32 v[10:11], v[10:11], v[16:17]
	v_pk_mul_f32 v[12:13], v[12:13], v[18:19]
	s_add_u32 s6, s76, s6
	v_cvt_pk_bf16_f32 v10, v10, v11
	v_cvt_pk_bf16_f32 v11, v12, v13
	s_addc_u32 s7, s77, s7
	s_add_i32 s54, s54, s60
	global_store_dwordx2 v105, v[10:11], s[6:7] offset:512
	s_add_i32 s6, s50, s54
	s_add_i32 s52, s52, s53
	s_cmpk_gt_i32 s6, 0x1ff
	s_barrier
	s_cbranch_scc1 .LBB0_282

.LBB0_283:
	s_andn2_b64 vcc, exec, s[28:29]
	s_cbranch_vccnz .LBB0_345
	v_readlane_b32 s6, v250, 24
	v_readlane_b32 s7, v250, 25
	s_mov_b64 s[28:29], -1
	s_and_b64 vcc, exec, s[6:7]
	s_cbranch_vccz .LBB0_317
	s_waitcnt vmcnt(0)
	v_mov_b32_e32 v1, v242
	v_readlane_b32 s65, v250, 26
	v_readfirstlane_b32 s5, v1
	s_ashr_i32 s34, s5, 6
	s_lshl_b32 s6, s34, 4
	s_add_i32 s6, s6, s65
	s_mul_i32 s8, s6, 0x1800
	s_mul_hi_i32 s7, s6, 0x1800
	s_add_u32 s28, s80, s8
	s_addc_u32 s29, s81, s7
	s_or_b32 s7, s6, 1
	s_mul_hi_i32 s8, s7, 0x1800
	s_mulk_i32 s7, 0x1800
	s_add_u32 s40, s80, s7
	v_and_b32_e32 v66, 63, v1
	s_addc_u32 s41, s81, s8
	v_lshlrev_b32_e32 v38, 1, v66
	global_load_ushort v3, v38, s[40:41] offset:512
	global_load_ushort v14, v38, s[40:41] offset:640
	global_load_ushort v20, v38, s[40:41] offset:768
	global_load_ushort v24, v38, s[40:41] offset:896
	global_load_ushort v2, v38, s[28:29] offset:512
	global_load_ushort v15, v38, s[28:29] offset:640
	global_load_ushort v21, v38, s[28:29] offset:768
	global_load_ushort v25, v38, s[28:29] offset:896
	s_or_b32 s7, s6, 2
	s_mul_hi_i32 s9, s7, 0x1800
	s_mulk_i32 s7, 0x1800
	s_add_u32 s8, s80, s7
	s_addc_u32 s9, s81, s9
	s_or_b32 s7, s6, 3
	s_mul_hi_i32 s11, s7, 0x1800
	s_mulk_i32 s7, 0x1800
	s_add_u32 s10, s80, s7
	s_addc_u32 s11, s81, s11
	global_load_ushort v12, v38, s[10:11] offset:512
	global_load_ushort v13, v38, s[10:11] offset:640
	global_load_ushort v16, v38, s[10:11] offset:768
	global_load_ushort v26, v38, s[10:11] offset:896
	global_load_ushort v17, v38, s[8:9] offset:512
	global_load_ushort v22, v38, s[8:9] offset:640
	global_load_ushort v23, v38, s[8:9] offset:768
	global_load_ushort v27, v38, s[8:9] offset:896
	s_mov_b32 s8, 0xbf3a00e3
	v_mov_b64_e32 v[18:19], s[8:9]
	s_mov_b32 s10, 0x3f07dc22
	s_mov_b32 s14, 0x3f35f0e3
	s_mov_b32 s16, 0xbe11a98e
	s_mov_b32 s18, 0x3e027906
	s_or_b32 s7, s6, 4
	s_mul_hi_i32 s8, s7, 0x1800
	s_mulk_i32 s7, 0x1800
	s_add_u32 s28, s80, s7
	s_addc_u32 s29, s81, s8
	s_or_b32 s7, s6, 5
	s_mul_hi_i32 s8, s7, 0x1800
	s_mulk_i32 s7, 0x1800
	s_add_u32 s40, s80, s7
	s_addc_u32 s41, s81, s8
	s_or_b32 s7, s6, 6
	v_writelane_b32 v255, s58, 23
	s_mul_hi_i32 s8, s7, 0x1800
	s_mulk_i32 s7, 0x1800
	v_writelane_b32 v255, s59, 24
	s_add_u32 s58, s80, s7
	s_addc_u32 s59, s81, s8
	s_or_b32 s7, s6, 7
	s_mul_hi_i32 s8, s7, 0x1800
	s_mulk_i32 s7, 0x1800
	s_add_u32 s60, s80, s7
	s_addc_u32 s61, s81, s8
	s_or_b32 s7, s6, 8
	s_mul_hi_i32 s8, s7, 0x1800
	s_mulk_i32 s7, 0x1800
	s_add_u32 s46, s80, s7
	s_addc_u32 s47, s81, s8
	s_or_b32 s7, s6, 9
	s_mul_hi_i32 s8, s7, 0x1800
	s_mulk_i32 s7, 0x1800
	s_add_u32 s54, s80, s7
	s_addc_u32 s55, s81, s8
	s_or_b32 s7, s6, 10
	s_mul_hi_i32 s8, s7, 0x1800
	s_mulk_i32 s7, 0x1800
	s_add_u32 s48, s80, s7
	s_addc_u32 s49, s81, s8
	s_or_b32 s7, s6, 11
	s_mul_hi_i32 s8, s7, 0x1800
	s_mulk_i32 s7, 0x1800
	s_add_u32 s56, s80, s7
	s_addc_u32 s57, s81, s8
	s_or_b32 s7, s6, 12
	s_mul_hi_i32 s8, s7, 0x1800
	s_mulk_i32 s7, 0x1800
	s_add_u32 s42, s80, s7
	s_addc_u32 s43, s81, s8
	s_or_b32 s7, s6, 13
	s_mul_hi_i32 s8, s7, 0x1800
	s_mulk_i32 s7, 0x1800
	s_add_u32 s50, s80, s7
	s_addc_u32 s51, s81, s8
	s_or_b32 s7, s6, 14
	s_mul_hi_i32 s8, s7, 0x1800
	s_mulk_i32 s7, 0x1800
	s_waitcnt vmcnt(15)
	v_lshlrev_b32_e32 v3, 16, v3
	v_mul_f32_e32 v7, v3, v3
	v_mul_f32_e32 v7, 0xbf38aa3b, v7
	v_exp_f32_e32 v7, v7
	s_waitcnt vmcnt(11)
	v_lshlrev_b32_e32 v2, 16, v2
	s_waitcnt lgkmcnt(0)
	v_mul_f32_e32 v5, v2, v2
	v_mul_f32_e32 v5, 0xbf38aa3b, v5
	v_fma_f32 v4, |v2|, s92, 1.0
	v_exp_f32_e32 v6, v5
	v_fma_f32 v5, |v3|, s92, 1.0
	v_rcp_f32_e32 v4, v4
	v_rcp_f32_e32 v5, v5
	v_cmp_gt_f32_e32 vcc, 0, v3
	s_add_u32 s44, s80, s7
	s_addc_u32 s45, s81, s8
	v_pk_fma_f32 v[8:9], v[4:5], s[10:11], v[18:19] op_sel_hi:[1,0,0]
	s_or_b32 s6, s6, 15
	v_pk_fma_f32 v[8:9], v[4:5], v[8:9], s[14:15] op_sel_hi:[1,1,0]
	s_mul_hi_i32 s7, s6, 0x1800
	v_pk_fma_f32 v[8:9], v[4:5], v[8:9], s[16:17] op_sel_hi:[1,1,0]
	s_mulk_i32 s6, 0x1800
	v_pk_fma_f32 v[8:9], v[4:5], v[8:9], s[18:19] op_sel_hi:[1,1,0]
	s_add_u32 s52, s80, s6
	v_pk_mul_f32 v[4:5], v[4:5], v[8:9]
	s_addc_u32 s53, s81, s7
	v_pk_mul_f32 v[4:5], v[6:7], v[4:5]
	s_mov_b32 s8, 0x3b800000
	v_pk_mul_f32 v[6:7], v[4:5], v[2:3]
	v_pk_fma_f32 v[4:5], v[4:5], v[2:3], v[2:3] neg_lo:[1,0,0] neg_hi:[1,0,0]
	s_ashr_i32 s5, s5, 7
	v_cndmask_b32_e32 v11, v5, v7, vcc
	v_cmp_gt_f32_e32 vcc, 0, v2
	s_waitcnt vmcnt(3)
	v_lshlrev_b32_e32 v2, 16, v17
	v_fma_f32 v3, |v2|, s92, 1.0
	v_mul_f32_e32 v5, v2, v2
	v_cndmask_b32_e32 v10, v4, v6, vcc
	v_rcp_f32_e32 v4, v3
	v_mul_f32_e32 v5, 0xbf38aa3b, v5
	v_lshlrev_b32_e32 v3, 16, v12
	v_exp_f32_e32 v6, v5
	v_fma_f32 v5, |v3|, s92, 1.0
	v_rcp_f32_e32 v5, v5
	v_mul_f32_e32 v7, v3, v3
	v_mul_f32_e32 v7, 0xbf38aa3b, v7
	v_exp_f32_e32 v7, v7
	v_pk_fma_f32 v[8:9], v[4:5], s[10:11], v[18:19] op_sel_hi:[1,0,0]
	v_cmp_gt_f32_e32 vcc, 0, v3
	v_pk_fma_f32 v[8:9], v[4:5], v[8:9], s[14:15] op_sel_hi:[1,1,0]
	v_lshlrev_b32_e32 v130, 4, v66
	v_pk_fma_f32 v[8:9], v[4:5], v[8:9], s[16:17] op_sel_hi:[1,1,0]
	s_nop 0
	v_pk_fma_f32 v[8:9], v[4:5], v[8:9], s[18:19] op_sel_hi:[1,1,0]
	v_pk_mul_f32 v[4:5], v[4:5], v[8:9]
	v_pk_mul_f32 v[4:5], v[6:7], v[4:5]
	v_pk_mul_f32 v[6:7], v[4:5], v[2:3]
	v_pk_fma_f32 v[4:5], v[4:5], v[2:3], v[2:3] neg_lo:[1,0,0] neg_hi:[1,0,0]
	s_nop 0
	v_cndmask_b32_e32 v3, v5, v7, vcc
	v_cmp_gt_f32_e32 vcc, 0, v2
	s_nop 1
	v_cndmask_b32_e32 v2, v4, v6, vcc
	s_waitcnt vmcnt(2)
	v_lshlrev_b32_e32 v4, 16, v22
	v_fma_f32 v5, |v4|, s92, 1.0
	v_mul_f32_e32 v7, v4, v4
	v_rcp_f32_e32 v6, v5
	v_mul_f32_e32 v7, 0xbf38aa3b, v7
	v_lshlrev_b32_e32 v5, 16, v13
	v_exp_f32_e32 v8, v7
	v_fma_f32 v7, |v5|, s92, 1.0
	v_rcp_f32_e32 v7, v7
	v_mul_f32_e32 v9, v5, v5
	v_mul_f32_e32 v9, 0xbf38aa3b, v9
	v_exp_f32_e32 v9, v9
	v_pk_fma_f32 v[12:13], v[6:7], s[10:11], v[18:19] op_sel_hi:[1,0,0]
	v_cmp_gt_f32_e32 vcc, 0, v5
	v_pk_fma_f32 v[12:13], v[6:7], v[12:13], s[14:15] op_sel_hi:[1,1,0]
	s_nop 0
	v_pk_fma_f32 v[12:13], v[6:7], v[12:13], s[16:17] op_sel_hi:[1,1,0]
	s_nop 0
	v_pk_fma_f32 v[12:13], v[6:7], v[12:13], s[18:19] op_sel_hi:[1,1,0]
	v_pk_mul_f32 v[6:7], v[6:7], v[12:13]
	v_pk_mul_f32 v[6:7], v[8:9], v[6:7]
	v_pk_mul_f32 v[8:9], v[6:7], v[4:5]
	v_pk_fma_f32 v[6:7], v[6:7], v[4:5], v[4:5] neg_lo:[1,0,0] neg_hi:[1,0,0]
	v_lshlrev_b32_e32 v5, 16, v14
	v_cndmask_b32_e32 v7, v7, v9, vcc
	v_cmp_gt_f32_e32 vcc, 0, v4
	v_lshlrev_b32_e32 v4, 16, v15
	v_mul_f32_e32 v9, v4, v4
	v_mul_f32_e32 v9, 0xbf38aa3b, v9
	v_cndmask_b32_e32 v6, v6, v8, vcc
	v_fma_f32 v8, |v4|, s92, 1.0
	v_exp_f32_e32 v12, v9
	v_fma_f32 v9, |v5|, s92, 1.0
	v_rcp_f32_e32 v8, v8
	v_rcp_f32_e32 v9, v9
	v_mul_f32_e32 v13, v5, v5
	v_mul_f32_e32 v13, 0xbf38aa3b, v13
	v_exp_f32_e32 v13, v13
	v_pk_fma_f32 v[14:15], v[8:9], s[10:11], v[18:19] op_sel_hi:[1,0,0]
	v_cmp_gt_f32_e32 vcc, 0, v5
	v_pk_fma_f32 v[14:15], v[8:9], v[14:15], s[14:15] op_sel_hi:[1,1,0]
	s_nop 0
	v_pk_fma_f32 v[14:15], v[8:9], v[14:15], s[16:17] op_sel_hi:[1,1,0]
	s_nop 0
	v_pk_fma_f32 v[14:15], v[8:9], v[14:15], s[18:19] op_sel_hi:[1,1,0]
	v_pk_mul_f32 v[8:9], v[8:9], v[14:15]
	v_pk_mul_f32 v[8:9], v[12:13], v[8:9]
	v_pk_mul_f32 v[12:13], v[8:9], v[4:5]
	v_pk_fma_f32 v[8:9], v[8:9], v[4:5], v[4:5] neg_lo:[1,0,0] neg_hi:[1,0,0]
	v_lshlrev_b32_e32 v5, 16, v16
	v_cndmask_b32_e32 v13, v9, v13, vcc
	v_cmp_gt_f32_e32 vcc, 0, v4
	s_waitcnt vmcnt(1)
	v_lshlrev_b32_e32 v4, 16, v23
	v_fma_f32 v9, |v5|, s92, 1.0
	v_cndmask_b32_e32 v12, v8, v12, vcc
	v_fma_f32 v8, |v4|, s92, 1.0
	v_rcp_f32_e32 v8, v8
	v_rcp_f32_e32 v9, v9
	v_mul_f32_e32 v14, v4, v4
	v_mul_f32_e32 v15, v5, v5
	v_mul_f32_e32 v14, 0xbf38aa3b, v14
	v_pk_fma_f32 v[16:17], v[8:9], s[10:11], v[18:19] op_sel_hi:[1,0,0]
	v_mul_f32_e32 v15, 0xbf38aa3b, v15
	v_exp_f32_e32 v14, v14
	v_pk_fma_f32 v[16:17], v[8:9], v[16:17], s[14:15] op_sel_hi:[1,1,0]
	v_exp_f32_e32 v15, v15
	v_pk_fma_f32 v[16:17], v[8:9], v[16:17], s[16:17] op_sel_hi:[1,1,0]
	v_cmp_gt_f32_e32 vcc, 0, v5
	v_pk_fma_f32 v[16:17], v[8:9], v[16:17], s[18:19] op_sel_hi:[1,1,0]
	s_nop 0
	v_pk_mul_f32 v[8:9], v[8:9], v[16:17]
	v_pk_mul_f32 v[8:9], v[14:15], v[8:9]
	v_pk_mul_f32 v[14:15], v[8:9], v[4:5]
	v_pk_fma_f32 v[8:9], v[8:9], v[4:5], v[4:5] neg_lo:[1,0,0] neg_hi:[1,0,0]
	v_lshlrev_b32_e32 v5, 16, v20
	v_cndmask_b32_e32 v15, v9, v15, vcc
	v_cmp_gt_f32_e32 vcc, 0, v4
	v_lshlrev_b32_e32 v4, 16, v21
	v_mul_f32_e32 v9, v4, v4
	v_mul_f32_e32 v9, 0xbf38aa3b, v9
	v_cndmask_b32_e32 v14, v8, v14, vcc
	v_fma_f32 v8, |v4|, s92, 1.0
	v_exp_f32_e32 v16, v9
	v_fma_f32 v9, |v5|, s92, 1.0
	v_rcp_f32_e32 v8, v8
	v_rcp_f32_e32 v9, v9
	v_mul_f32_e32 v17, v5, v5
	v_mul_f32_e32 v17, 0xbf38aa3b, v17
	v_exp_f32_e32 v17, v17
	v_pk_fma_f32 v[20:21], v[8:9], s[10:11], v[18:19] op_sel_hi:[1,0,0]
	v_cmp_gt_f32_e32 vcc, 0, v5
	v_pk_fma_f32 v[20:21], v[8:9], v[20:21], s[14:15] op_sel_hi:[1,1,0]
	s_nop 0
	v_pk_fma_f32 v[20:21], v[8:9], v[20:21], s[16:17] op_sel_hi:[1,1,0]
	s_nop 0
	v_pk_fma_f32 v[20:21], v[8:9], v[20:21], s[18:19] op_sel_hi:[1,1,0]
	v_pk_mul_f32 v[8:9], v[8:9], v[20:21]
	v_pk_mul_f32 v[8:9], v[16:17], v[8:9]
	v_pk_mul_f32 v[16:17], v[8:9], v[4:5]
	v_pk_fma_f32 v[8:9], v[8:9], v[4:5], v[4:5] neg_lo:[1,0,0] neg_hi:[1,0,0]
	v_lshlrev_b32_e32 v5, 16, v26
	v_cndmask_b32_e32 v23, v9, v17, vcc
	v_cmp_gt_f32_e32 vcc, 0, v4
	s_waitcnt vmcnt(0)
	v_lshlrev_b32_e32 v4, 16, v27
	v_fma_f32 v9, |v5|, s92, 1.0
	v_cndmask_b32_e32 v22, v8, v16, vcc
	v_fma_f32 v8, |v4|, s92, 1.0
	v_rcp_f32_e32 v8, v8
	v_rcp_f32_e32 v9, v9
	v_mul_f32_e32 v16, v4, v4
	v_mul_f32_e32 v17, v5, v5
	v_mul_f32_e32 v16, 0xbf38aa3b, v16
	v_pk_fma_f32 v[20:21], v[8:9], s[10:11], v[18:19] op_sel_hi:[1,0,0]
	v_mul_f32_e32 v17, 0xbf38aa3b, v17
	v_exp_f32_e32 v16, v16
	v_pk_fma_f32 v[20:21], v[8:9], v[20:21], s[14:15] op_sel_hi:[1,1,0]
	v_exp_f32_e32 v17, v17
	v_pk_fma_f32 v[20:21], v[8:9], v[20:21], s[16:17] op_sel_hi:[1,1,0]
	v_cmp_gt_f32_e32 vcc, 0, v5
	v_pk_fma_f32 v[20:21], v[8:9], v[20:21], s[18:19] op_sel_hi:[1,1,0]
	v_mov_b32_e32 v26, v13
	v_pk_mul_f32 v[8:9], v[8:9], v[20:21]
	v_pk_mul_f32 v[8:9], v[16:17], v[8:9]
	v_pk_mul_f32 v[16:17], v[8:9], v[4:5]
	v_pk_fma_f32 v[8:9], v[8:9], v[4:5], v[4:5] neg_lo:[1,0,0] neg_hi:[1,0,0]
	v_lshlrev_b32_e32 v5, 16, v24
	v_cndmask_b32_e32 v17, v9, v17, vcc
	v_cmp_gt_f32_e32 vcc, 0, v4
	v_lshlrev_b32_e32 v4, 16, v25
	v_mul_f32_e32 v9, v4, v4
	v_mul_f32_e32 v9, 0xbf38aa3b, v9
	v_cndmask_b32_e32 v16, v8, v16, vcc
	v_fma_f32 v8, |v4|, s92, 1.0
	v_exp_f32_e32 v20, v9
	v_fma_f32 v9, |v5|, s92, 1.0
	v_rcp_f32_e32 v8, v8
	v_rcp_f32_e32 v9, v9
	v_mul_f32_e32 v21, v5, v5
	v_mul_f32_e32 v21, 0xbf38aa3b, v21
	v_exp_f32_e32 v21, v21
	v_pk_fma_f32 v[24:25], v[8:9], s[10:11], v[18:19] op_sel_hi:[1,0,0]
	v_cmp_gt_f32_e32 vcc, 0, v5
	v_pk_fma_f32 v[24:25], v[8:9], v[24:25], s[14:15] op_sel_hi:[1,1,0]
	s_nop 0
	v_pk_fma_f32 v[24:25], v[8:9], v[24:25], s[16:17] op_sel_hi:[1,1,0]
	s_nop 0
	v_pk_fma_f32 v[24:25], v[8:9], v[24:25], s[18:19] op_sel_hi:[1,1,0]
	v_pk_mul_f32 v[8:9], v[8:9], v[24:25]
	v_pk_mul_f32 v[8:9], v[20:21], v[8:9]
	v_pk_mul_f32 v[20:21], v[8:9], v[4:5]
	v_pk_fma_f32 v[8:9], v[8:9], v[4:5], v[4:5] neg_lo:[1,0,0] neg_hi:[1,0,0]
	v_mov_b32_e32 v5, v14
	v_cndmask_b32_e32 v25, v9, v21, vcc
	v_cmp_gt_f32_e32 vcc, 0, v4
	v_mov_b32_e32 v4, v2
	v_mov_b32_e32 v9, v16
	v_cndmask_b32_e32 v24, v8, v20, vcc
	v_mov_b32_e32 v8, v6
	v_pk_add_f32 v[4:5], v[4:5], v[8:9]
	v_mov_b32_e32 v8, v3
	v_add_f32_e32 v4, v4, v5
	v_mov_b32_e32 v9, v15
	s_nop 0
	v_add_f32_dpp v4, v4, v4 quad_perm:[1,0,3,2] row_mask:0xf bank_mask:0xf bound_ctrl:1
	v_mov_b32_e32 v20, v7
	v_mov_b32_e32 v21, v17
	v_add_f32_dpp v4, v4, v4 quad_perm:[2,3,0,1] row_mask:0xf bank_mask:0xf bound_ctrl:1
	v_pk_add_f32 v[8:9], v[8:9], v[20:21]
	v_mov_b64_e32 v[20:21], s[8:9]
	v_add_f32_dpp v4, v4, v4 row_half_mirror row_mask:0xf bank_mask:0xf bound_ctrl:1
	v_mov_b32_e32 v27, v25
	s_mov_b32 s8, 0x3e027906
	v_add_f32_dpp v4, v4, v4 row_mirror row_mask:0xf bank_mask:0xf bound_ctrl:1
	s_nop 1
	v_add_f32_dpp v4, v4, v4 row_bcast:15 row_mask:0xa bank_mask:0xf
	s_nop 1
	v_add_f32_dpp v4, v4, v4 row_bcast:31 row_mask:0xc bank_mask:0xf
	v_add_f32_e32 v5, v8, v9
	v_readlane_b32 s6, v4, 63
	s_nop 0
	v_add_f32_dpp v5, v5, v5 quad_perm:[1,0,3,2] row_mask:0xf bank_mask:0xf bound_ctrl:1
	s_xor_b32 s6, s6, 0x80000000
	s_nop 0
	v_add_f32_dpp v5, v5, v5 quad_perm:[2,3,0,1] row_mask:0xf bank_mask:0xf bound_ctrl:1
	s_nop 1
	v_add_f32_dpp v5, v5, v5 row_half_mirror row_mask:0xf bank_mask:0xf bound_ctrl:1
	s_nop 1
	v_add_f32_dpp v5, v5, v5 row_mirror row_mask:0xf bank_mask:0xf bound_ctrl:1
	s_nop 1
	v_add_f32_dpp v5, v5, v5 row_bcast:15 row_mask:0xa bank_mask:0xf
	s_nop 1
	v_add_f32_dpp v5, v5, v5 row_bcast:31 row_mask:0xc bank_mask:0xf
	s_nop 0
	v_readlane_b32 s7, v5, 63
	s_xor_b32 s7, s7, 0x80000000
	s_nop 0
	v_pk_fma_f32 v[4:5], s[6:7], v[20:21], v[2:3] op_sel_hi:[1,0,1]
	v_pk_fma_f32 v[8:9], s[6:7], v[20:21], v[6:7] op_sel_hi:[1,0,1]
	v_pk_fma_f32 v[6:7], s[6:7], v[20:21], v[14:15] op_sel_hi:[1,0,1]
	v_pk_fma_f32 v[2:3], s[6:7], v[20:21], v[16:17] op_sel_hi:[1,0,1]
	v_mov_b32_e32 v14, v10
	v_mov_b32_e32 v15, v22
	v_mov_b32_e32 v16, v12
	v_mov_b32_e32 v17, v24
	v_pk_add_f32 v[14:15], v[14:15], v[16:17]
	v_mov_b32_e32 v16, v11
	v_add_f32_e32 v14, v14, v15
	v_mov_b32_e32 v17, v23
	s_nop 0
	v_add_f32_dpp v14, v14, v14 quad_perm:[1,0,3,2] row_mask:0xf bank_mask:0xf bound_ctrl:1
	v_pk_add_f32 v[16:17], v[16:17], v[26:27]
	s_nop 0
	v_add_f32_dpp v14, v14, v14 quad_perm:[2,3,0,1] row_mask:0xf bank_mask:0xf bound_ctrl:1
	s_nop 1
	v_add_f32_dpp v14, v14, v14 row_half_mirror row_mask:0xf bank_mask:0xf bound_ctrl:1
	s_nop 1
	v_add_f32_dpp v14, v14, v14 row_mirror row_mask:0xf bank_mask:0xf bound_ctrl:1
	s_nop 1
	v_add_f32_dpp v14, v14, v14 row_bcast:15 row_mask:0xa bank_mask:0xf
	s_nop 1
	v_add_f32_dpp v14, v14, v14 row_bcast:31 row_mask:0xc bank_mask:0xf
	v_add_f32_e32 v15, v16, v17
	v_readlane_b32 s6, v14, 63
	s_nop 0
	v_add_f32_dpp v15, v15, v15 quad_perm:[1,0,3,2] row_mask:0xf bank_mask:0xf bound_ctrl:1
	s_xor_b32 s6, s6, 0x80000000
	s_nop 0
	v_add_f32_dpp v15, v15, v15 quad_perm:[2,3,0,1] row_mask:0xf bank_mask:0xf bound_ctrl:1
	s_nop 1
	v_add_f32_dpp v15, v15, v15 row_half_mirror row_mask:0xf bank_mask:0xf bound_ctrl:1
	s_nop 1
	v_add_f32_dpp v15, v15, v15 row_mirror row_mask:0xf bank_mask:0xf bound_ctrl:1
	s_nop 1
	v_add_f32_dpp v15, v15, v15 row_bcast:15 row_mask:0xa bank_mask:0xf
	s_nop 1
	v_add_f32_dpp v15, v15, v15 row_bcast:31 row_mask:0xc bank_mask:0xf
	s_nop 0
	v_readlane_b32 s7, v15, 63
	s_xor_b32 s7, s7, 0x80000000
	s_nop 0
	v_pk_fma_f32 v[16:17], s[6:7], v[20:21], v[10:11] op_sel_hi:[1,0,1]
	v_pk_fma_f32 v[14:15], s[6:7], v[20:21], v[12:13] op_sel_hi:[1,0,1]
	v_pk_fma_f32 v[12:13], s[6:7], v[20:21], v[22:23] op_sel_hi:[1,0,1]
	v_pk_fma_f32 v[10:11], s[6:7], v[20:21], v[24:25] op_sel_hi:[1,0,1]
	global_load_ushort v22, v38, s[60:61] offset:512
	global_load_ushort v32, v38, s[60:61] offset:640
	global_load_ushort v36, v38, s[60:61] offset:768
	global_load_ushort v39, v38, s[60:61] offset:896
	global_load_ushort v24, v38, s[58:59] offset:512
	global_load_ushort v33, v38, s[58:59] offset:640
	global_load_ushort v37, v38, s[58:59] offset:768
	global_load_ushort v42, v38, s[58:59] offset:896
	s_waitcnt vmcnt(7)
	v_lshlrev_b32_e32 v23, 16, v22
	v_fma_f32 v25, |v23|, s92, 1.0
	v_rcp_f32_e32 v25, v25
	v_mul_f32_e32 v27, v23, v23
	s_waitcnt vmcnt(3)
	v_lshlrev_b32_e32 v22, 16, v24
	v_fma_f32 v24, |v22|, s92, 1.0
	v_rcp_f32_e32 v24, v24
	v_mul_f32_e32 v26, v22, v22
	v_mul_f32_e32 v26, 0xbf38aa3b, v26
	v_mul_f32_e32 v27, 0xbf38aa3b, v27
	v_pk_fma_f32 v[28:29], v[24:25], s[10:11], v[18:19] op_sel_hi:[1,0,0]
	v_exp_f32_e32 v26, v26
	v_pk_fma_f32 v[28:29], v[24:25], v[28:29], s[14:15] op_sel_hi:[1,1,0]
	v_exp_f32_e32 v27, v27
	v_pk_fma_f32 v[28:29], v[24:25], v[28:29], s[16:17] op_sel_hi:[1,1,0]
	v_cmp_gt_f32_e32 vcc, 0, v23
	v_pk_fma_f32 v[28:29], v[24:25], v[28:29], s[18:19] op_sel_hi:[1,1,0]
	v_readlane_b32 s11, v254, 26
	v_pk_mul_f32 v[24:25], v[24:25], v[28:29]
	s_nop 0
	v_pk_mul_f32 v[24:25], v[26:27], v[24:25]
	v_pk_mul_f32 v[26:27], v[24:25], v[22:23]
	v_pk_fma_f32 v[24:25], v[24:25], v[22:23], v[22:23] neg_lo:[1,0,0] neg_hi:[1,0,0]
	s_nop 0
	v_cndmask_b32_e32 v23, v25, v27, vcc
	v_cmp_gt_f32_e32 vcc, 0, v22
	s_nop 1
	v_cndmask_b32_e32 v22, v24, v26, vcc
	global_load_ushort v24, v38, s[40:41] offset:512
	global_load_ushort v34, v38, s[40:41] offset:640
	global_load_ushort v40, v38, s[40:41] offset:768
	global_load_ushort v44, v38, s[40:41] offset:896
	global_load_ushort v26, v38, s[28:29] offset:512
	global_load_ushort v35, v38, s[28:29] offset:640
	global_load_ushort v41, v38, s[28:29] offset:768
	global_load_ushort v45, v38, s[28:29] offset:896
	s_waitcnt vmcnt(7)
	v_lshlrev_b32_e32 v25, 16, v24
	s_waitcnt vmcnt(3)
	v_lshlrev_b32_e32 v24, 16, v26
	v_mul_f32_e32 v27, v24, v24
	v_mul_f32_e32 v27, 0xbf38aa3b, v27
	v_fma_f32 v26, |v24|, s92, 1.0
	v_exp_f32_e32 v28, v27
	v_fma_f32 v27, |v25|, s92, 1.0
	v_rcp_f32_e32 v26, v26
	v_rcp_f32_e32 v27, v27
	v_mul_f32_e32 v29, v25, v25
	v_mul_f32_e32 v29, 0xbf38aa3b, v29
	v_exp_f32_e32 v29, v29
	v_pk_fma_f32 v[30:31], v[26:27], s[10:11], v[18:19] op_sel_hi:[1,0,0]
	v_cmp_gt_f32_e32 vcc, 0, v25
	v_pk_fma_f32 v[30:31], v[26:27], v[30:31], s[14:15] op_sel_hi:[1,1,0]
	s_nop 0
	v_pk_fma_f32 v[30:31], v[26:27], v[30:31], s[16:17] op_sel_hi:[1,1,0]
	s_nop 0
	v_pk_fma_f32 v[30:31], v[26:27], v[30:31], s[18:19] op_sel_hi:[1,1,0]
	v_pk_mul_f32 v[26:27], v[26:27], v[30:31]
	v_pk_mul_f32 v[26:27], v[28:29], v[26:27]
	v_pk_mul_f32 v[28:29], v[26:27], v[24:25]
	v_pk_fma_f32 v[26:27], v[26:27], v[24:25], v[24:25] neg_lo:[1,0,0] neg_hi:[1,0,0]
	v_lshlrev_b32_e32 v25, 16, v32
	v_cndmask_b32_e32 v31, v27, v29, vcc
	v_cmp_gt_f32_e32 vcc, 0, v24
	v_lshlrev_b32_e32 v24, 16, v33
	v_fma_f32 v27, |v25|, s92, 1.0
	v_cndmask_b32_e32 v30, v26, v28, vcc
	v_fma_f32 v26, |v24|, s92, 1.0
	v_rcp_f32_e32 v26, v26
	v_rcp_f32_e32 v27, v27
	v_mul_f32_e32 v28, v24, v24
	v_mul_f32_e32 v29, v25, v25
	v_mul_f32_e32 v28, 0xbf38aa3b, v28
	v_pk_fma_f32 v[32:33], v[26:27], s[10:11], v[18:19] op_sel_hi:[1,0,0]
	v_mul_f32_e32 v29, 0xbf38aa3b, v29
	v_exp_f32_e32 v28, v28
	v_pk_fma_f32 v[32:33], v[26:27], v[32:33], s[14:15] op_sel_hi:[1,1,0]
	v_exp_f32_e32 v29, v29
	v_pk_fma_f32 v[32:33], v[26:27], v[32:33], s[16:17] op_sel_hi:[1,1,0]
	v_cmp_gt_f32_e32 vcc, 0, v25
	v_pk_fma_f32 v[32:33], v[26:27], v[32:33], s[18:19] op_sel_hi:[1,1,0]
	s_nop 0
	v_pk_mul_f32 v[26:27], v[26:27], v[32:33]
	v_pk_mul_f32 v[26:27], v[28:29], v[26:27]
	v_pk_mul_f32 v[28:29], v[26:27], v[24:25]
	v_pk_fma_f32 v[26:27], v[26:27], v[24:25], v[24:25] neg_lo:[1,0,0] neg_hi:[1,0,0]
	s_nop 0
	v_cndmask_b32_e32 v25, v27, v29, vcc
	v_cmp_gt_f32_e32 vcc, 0, v24
	v_lshlrev_b32_e32 v27, 16, v34
	v_mul_f32_e32 v33, v27, v27
	v_cndmask_b32_e32 v24, v26, v28, vcc
	s_waitcnt vmcnt(2)
	v_lshlrev_b32_e32 v26, 16, v35
	v_mul_f32_e32 v29, v26, v26
	v_mul_f32_e32 v29, 0xbf38aa3b, v29
	v_fma_f32 v28, |v26|, s92, 1.0
	v_exp_f32_e32 v32, v29
	v_fma_f32 v29, |v27|, s92, 1.0
	v_rcp_f32_e32 v28, v28
	v_rcp_f32_e32 v29, v29
	v_mul_f32_e32 v33, 0xbf38aa3b, v33
	v_exp_f32_e32 v33, v33
	v_cmp_gt_f32_e32 vcc, 0, v27
	v_pk_fma_f32 v[34:35], v[28:29], s[10:11], v[18:19] op_sel_hi:[1,0,0]
	s_nop 0
	v_pk_fma_f32 v[34:35], v[28:29], v[34:35], s[14:15] op_sel_hi:[1,1,0]
	s_nop 0
	v_pk_fma_f32 v[34:35], v[28:29], v[34:35], s[16:17] op_sel_hi:[1,1,0]
	s_nop 0
	v_pk_fma_f32 v[34:35], v[28:29], v[34:35], s[18:19] op_sel_hi:[1,1,0]
	v_pk_mul_f32 v[28:29], v[28:29], v[34:35]
	v_pk_mul_f32 v[28:29], v[32:33], v[28:29]
	v_pk_mul_f32 v[32:33], v[28:29], v[26:27]
	v_pk_fma_f32 v[28:29], v[28:29], v[26:27], v[26:27] neg_lo:[1,0,0] neg_hi:[1,0,0]
	v_lshlrev_b32_e32 v27, 16, v36
	v_cndmask_b32_e32 v33, v29, v33, vcc
	v_cmp_gt_f32_e32 vcc, 0, v26
	v_lshlrev_b32_e32 v26, 16, v37
	v_fma_f32 v29, |v27|, s92, 1.0
	v_cndmask_b32_e32 v32, v28, v32, vcc
	v_fma_f32 v28, |v26|, s92, 1.0
	v_rcp_f32_e32 v28, v28
	v_rcp_f32_e32 v29, v29
	v_mul_f32_e32 v34, v26, v26
	v_mul_f32_e32 v35, v27, v27
	v_mul_f32_e32 v34, 0xbf38aa3b, v34
	v_pk_fma_f32 v[36:37], v[28:29], s[10:11], v[18:19] op_sel_hi:[1,0,0]
	v_mul_f32_e32 v35, 0xbf38aa3b, v35
	v_exp_f32_e32 v34, v34
	v_pk_fma_f32 v[36:37], v[28:29], v[36:37], s[14:15] op_sel_hi:[1,1,0]
	v_exp_f32_e32 v35, v35
	v_pk_fma_f32 v[36:37], v[28:29], v[36:37], s[16:17] op_sel_hi:[1,1,0]
	v_cmp_gt_f32_e32 vcc, 0, v27
	v_pk_fma_f32 v[36:37], v[28:29], v[36:37], s[18:19] op_sel_hi:[1,1,0]
	s_nop 0
	v_pk_mul_f32 v[28:29], v[28:29], v[36:37]
	v_pk_mul_f32 v[28:29], v[34:35], v[28:29]
	v_pk_mul_f32 v[34:35], v[28:29], v[26:27]
	v_pk_fma_f32 v[28:29], v[28:29], v[26:27], v[26:27] neg_lo:[1,0,0] neg_hi:[1,0,0]
	v_lshlrev_b32_e32 v27, 16, v40
	v_cndmask_b32_e32 v35, v29, v35, vcc
	v_cmp_gt_f32_e32 vcc, 0, v26
	s_waitcnt vmcnt(1)
	v_lshlrev_b32_e32 v26, 16, v41
	v_mul_f32_e32 v29, v26, v26
	v_mul_f32_e32 v29, 0xbf38aa3b, v29
	v_cndmask_b32_e32 v34, v28, v34, vcc
	v_fma_f32 v28, |v26|, s92, 1.0
	v_exp_f32_e32 v36, v29
	v_fma_f32 v29, |v27|, s92, 1.0
	v_rcp_f32_e32 v28, v28
	v_rcp_f32_e32 v29, v29
	v_mul_f32_e32 v37, v27, v27
	v_mul_f32_e32 v37, 0xbf38aa3b, v37
	v_exp_f32_e32 v37, v37
	v_pk_fma_f32 v[40:41], v[28:29], s[10:11], v[18:19] op_sel_hi:[1,0,0]
	v_cmp_gt_f32_e32 vcc, 0, v27
	v_pk_fma_f32 v[40:41], v[28:29], v[40:41], s[14:15] op_sel_hi:[1,1,0]
	s_nop 0
	v_pk_fma_f32 v[40:41], v[28:29], v[40:41], s[16:17] op_sel_hi:[1,1,0]
	s_nop 0
	v_pk_fma_f32 v[40:41], v[28:29], v[40:41], s[18:19] op_sel_hi:[1,1,0]
	v_pk_mul_f32 v[28:29], v[28:29], v[40:41]
	v_pk_mul_f32 v[28:29], v[36:37], v[28:29]
	v_pk_mul_f32 v[36:37], v[28:29], v[26:27]
	v_pk_fma_f32 v[28:29], v[28:29], v[26:27], v[26:27] neg_lo:[1,0,0] neg_hi:[1,0,0]
	v_lshlrev_b32_e32 v27, 16, v39
	v_cndmask_b32_e32 v41, v29, v37, vcc
	v_cmp_gt_f32_e32 vcc, 0, v26
	v_lshlrev_b32_e32 v26, 16, v42
	v_fma_f32 v29, |v27|, s92, 1.0
	v_cndmask_b32_e32 v40, v28, v36, vcc
	v_fma_f32 v28, |v26|, s92, 1.0
	v_rcp_f32_e32 v28, v28
	v_rcp_f32_e32 v29, v29
	v_mul_f32_e32 v36, v26, v26
	v_mul_f32_e32 v37, v27, v27
	v_mul_f32_e32 v36, 0xbf38aa3b, v36
	v_pk_fma_f32 v[42:43], v[28:29], s[10:11], v[18:19] op_sel_hi:[1,0,0]
	v_mul_f32_e32 v37, 0xbf38aa3b, v37
	v_exp_f32_e32 v36, v36
	v_pk_fma_f32 v[42:43], v[28:29], v[42:43], s[14:15] op_sel_hi:[1,1,0]
	v_exp_f32_e32 v37, v37
	v_pk_fma_f32 v[42:43], v[28:29], v[42:43], s[16:17] op_sel_hi:[1,1,0]
	v_cmp_gt_f32_e32 vcc, 0, v27
	v_pk_fma_f32 v[42:43], v[28:29], v[42:43], s[18:19] op_sel_hi:[1,1,0]
	s_nop 0
	v_pk_mul_f32 v[28:29], v[28:29], v[42:43]
	v_pk_mul_f32 v[28:29], v[36:37], v[28:29]
	v_pk_mul_f32 v[36:37], v[28:29], v[26:27]
	v_pk_fma_f32 v[28:29], v[28:29], v[26:27], v[26:27] neg_lo:[1,0,0] neg_hi:[1,0,0]
	v_lshlrev_b32_e32 v27, 16, v44
	v_cndmask_b32_e32 v37, v29, v37, vcc
	v_cmp_gt_f32_e32 vcc, 0, v26
	s_waitcnt vmcnt(0)
	v_lshlrev_b32_e32 v26, 16, v45
	v_mul_f32_e32 v29, v26, v26
	v_mul_f32_e32 v29, 0xbf38aa3b, v29
	v_cndmask_b32_e32 v36, v28, v36, vcc
	v_fma_f32 v28, |v26|, s92, 1.0
	v_exp_f32_e32 v42, v29
	v_fma_f32 v29, |v27|, s92, 1.0
	v_rcp_f32_e32 v28, v28
	v_rcp_f32_e32 v29, v29
	v_mul_f32_e32 v39, v27, v27
	v_mul_f32_e32 v39, 0xbf38aa3b, v39
	v_exp_f32_e32 v43, v39
	v_pk_fma_f32 v[44:45], v[28:29], s[10:11], v[18:19] op_sel_hi:[1,0,0]
	v_cmp_gt_f32_e32 vcc, 0, v27
	v_pk_fma_f32 v[44:45], v[28:29], v[44:45], s[14:15] op_sel_hi:[1,1,0]
	s_nop 0
	v_pk_fma_f32 v[44:45], v[28:29], v[44:45], s[16:17] op_sel_hi:[1,1,0]
	s_nop 0
	v_pk_fma_f32 v[44:45], v[28:29], v[44:45], s[18:19] op_sel_hi:[1,1,0]
	v_pk_mul_f32 v[28:29], v[28:29], v[44:45]
	v_mov_b32_e32 v44, v25
	v_pk_mul_f32 v[28:29], v[42:43], v[28:29]
	v_mov_b32_e32 v45, v37
	v_pk_mul_f32 v[42:43], v[28:29], v[26:27]
	v_pk_fma_f32 v[28:29], v[28:29], v[26:27], v[26:27] neg_lo:[1,0,0] neg_hi:[1,0,0]
	v_mov_b32_e32 v27, v34
	v_cndmask_b32_e32 v43, v29, v43, vcc
	v_cmp_gt_f32_e32 vcc, 0, v26
	v_mov_b32_e32 v26, v22
	v_mov_b32_e32 v29, v36
	v_cndmask_b32_e32 v42, v28, v42, vcc
	v_mov_b32_e32 v28, v24
	v_pk_add_f32 v[26:27], v[26:27], v[28:29]
	v_mov_b32_e32 v28, v23
	v_add_f32_e32 v26, v26, v27
	v_mov_b32_e32 v29, v35
	s_nop 0
	v_add_f32_dpp v26, v26, v26 quad_perm:[1,0,3,2] row_mask:0xf bank_mask:0xf bound_ctrl:1
	v_pk_add_f32 v[28:29], v[28:29], v[44:45]
	v_mov_b32_e32 v44, v33
	v_add_f32_dpp v26, v26, v26 quad_perm:[2,3,0,1] row_mask:0xf bank_mask:0xf bound_ctrl:1
	v_mov_b32_e32 v45, v43
	s_nop 0
	v_add_f32_dpp v26, v26, v26 row_half_mirror row_mask:0xf bank_mask:0xf bound_ctrl:1
	s_nop 1
	v_add_f32_dpp v26, v26, v26 row_mirror row_mask:0xf bank_mask:0xf bound_ctrl:1
	s_nop 1
	v_add_f32_dpp v26, v26, v26 row_bcast:15 row_mask:0xa bank_mask:0xf
	s_nop 1
	v_add_f32_dpp v26, v26, v26 row_bcast:31 row_mask:0xc bank_mask:0xf
	v_add_f32_e32 v27, v28, v29
	v_readlane_b32 s6, v26, 63
	s_nop 0
	v_add_f32_dpp v27, v27, v27 quad_perm:[1,0,3,2] row_mask:0xf bank_mask:0xf bound_ctrl:1
	s_xor_b32 s6, s6, 0x80000000
	s_nop 0
	v_add_f32_dpp v27, v27, v27 quad_perm:[2,3,0,1] row_mask:0xf bank_mask:0xf bound_ctrl:1
	s_nop 1
	v_add_f32_dpp v27, v27, v27 row_half_mirror row_mask:0xf bank_mask:0xf bound_ctrl:1
	s_nop 1
	v_add_f32_dpp v27, v27, v27 row_mirror row_mask:0xf bank_mask:0xf bound_ctrl:1
	s_nop 1
	v_add_f32_dpp v27, v27, v27 row_bcast:15 row_mask:0xa bank_mask:0xf
	s_nop 1
	v_add_f32_dpp v27, v27, v27 row_bcast:31 row_mask:0xc bank_mask:0xf
	s_nop 0
	v_readlane_b32 s7, v27, 63
	s_xor_b32 s7, s7, 0x80000000
	s_nop 0
	v_pk_fma_f32 v[28:29], s[6:7], v[20:21], v[22:23] op_sel_hi:[1,0,1]
	v_pk_fma_f32 v[26:27], s[6:7], v[20:21], v[24:25] op_sel_hi:[1,0,1]
	v_pk_fma_f32 v[24:25], s[6:7], v[20:21], v[34:35] op_sel_hi:[1,0,1]
	v_pk_fma_f32 v[22:23], s[6:7], v[20:21], v[36:37] op_sel_hi:[1,0,1]
	v_mov_b32_e32 v34, v30
	v_mov_b32_e32 v35, v40
	v_mov_b32_e32 v36, v32
	v_mov_b32_e32 v37, v42
	v_pk_add_f32 v[34:35], v[34:35], v[36:37]
	v_mov_b32_e32 v36, v31
	v_add_f32_e32 v34, v34, v35
	v_mov_b32_e32 v37, v41
	s_nop 0
	v_add_f32_dpp v34, v34, v34 quad_perm:[1,0,3,2] row_mask:0xf bank_mask:0xf bound_ctrl:1
	v_pk_add_f32 v[36:37], v[36:37], v[44:45]
	s_nop 0
	v_add_f32_dpp v34, v34, v34 quad_perm:[2,3,0,1] row_mask:0xf bank_mask:0xf bound_ctrl:1
	s_nop 1
	v_add_f32_dpp v34, v34, v34 row_half_mirror row_mask:0xf bank_mask:0xf bound_ctrl:1
	s_nop 1
	v_add_f32_dpp v34, v34, v34 row_mirror row_mask:0xf bank_mask:0xf bound_ctrl:1
	s_nop 1
	v_add_f32_dpp v34, v34, v34 row_bcast:15 row_mask:0xa bank_mask:0xf
	s_nop 1
	v_add_f32_dpp v34, v34, v34 row_bcast:31 row_mask:0xc bank_mask:0xf
	v_add_f32_e32 v35, v36, v37
	v_readlane_b32 s6, v34, 63
	s_nop 0
	v_add_f32_dpp v35, v35, v35 quad_perm:[1,0,3,2] row_mask:0xf bank_mask:0xf bound_ctrl:1
	s_xor_b32 s6, s6, 0x80000000
	s_nop 0
	v_add_f32_dpp v35, v35, v35 quad_perm:[2,3,0,1] row_mask:0xf bank_mask:0xf bound_ctrl:1
	s_nop 1
	v_add_f32_dpp v35, v35, v35 row_half_mirror row_mask:0xf bank_mask:0xf bound_ctrl:1
	s_nop 1
	v_add_f32_dpp v35, v35, v35 row_mirror row_mask:0xf bank_mask:0xf bound_ctrl:1
	s_nop 1
	v_add_f32_dpp v35, v35, v35 row_bcast:15 row_mask:0xa bank_mask:0xf
	s_nop 1
	v_add_f32_dpp v35, v35, v35 row_bcast:31 row_mask:0xc bank_mask:0xf
	s_nop 0
	v_readlane_b32 s7, v35, 63
	s_xor_b32 s7, s7, 0x80000000
	s_nop 0
	v_pk_fma_f32 v[34:35], s[6:7], v[20:21], v[32:33] op_sel_hi:[1,0,1]
	v_pk_fma_f32 v[32:33], s[6:7], v[20:21], v[40:41] op_sel_hi:[1,0,1]
	global_load_ushort v46, v38, s[54:55] offset:512
	global_load_ushort v50, v38, s[54:55] offset:640
	global_load_ushort v71, v38, s[54:55] offset:768
	global_load_ushort v76, v38, s[54:55] offset:896
	global_load_ushort v47, v38, s[46:47] offset:512
	global_load_ushort v51, v38, s[46:47] offset:640
	global_load_ushort v72, v38, s[46:47] offset:768
	global_load_ushort v77, v38, s[46:47] offset:896
	global_load_ushort v39, v38, s[56:57] offset:512
	global_load_ushort v48, v38, s[56:57] offset:640
	global_load_ushort v52, v38, s[56:57] offset:768
	global_load_ushort v74, v38, s[56:57] offset:896
	global_load_ushort v40, v38, s[48:49] offset:512
	global_load_ushort v49, v38, s[48:49] offset:640
	global_load_ushort v53, v38, s[48:49] offset:768
	global_load_ushort v75, v38, s[48:49] offset:896
	global_load_ushort v60, v38, s[50:51] offset:512
	global_load_ushort v62, v38, s[50:51] offset:640
	global_load_ushort v67, v38, s[50:51] offset:768
	global_load_ushort v58, v38, s[50:51] offset:896
	global_load_ushort v61, v38, s[42:43] offset:512
	global_load_ushort v63, v38, s[42:43] offset:640
	global_load_ushort v68, v38, s[42:43] offset:768
	global_load_ushort v59, v38, s[42:43] offset:896
	global_load_ushort v54, v38, s[52:53] offset:512
	global_load_ushort v56, v38, s[52:53] offset:640
	global_load_ushort v69, v38, s[52:53] offset:768
	global_load_ushort v64, v38, s[52:53] offset:896
	global_load_ushort v55, v38, s[44:45] offset:512
	global_load_ushort v57, v38, s[44:45] offset:640
	global_load_ushort v70, v38, s[44:45] offset:768
	global_load_ushort v65, v38, s[44:45] offset:896
	v_pk_fma_f32 v[36:37], s[6:7], v[20:21], v[30:31] op_sel_hi:[1,0,1]
	v_pk_fma_f32 v[30:31], s[6:7], v[20:21], v[42:43] op_sel_hi:[1,0,1]
	s_load_dwordx2 s[42:43], s[0:1], 0x30
	s_load_dwordx4 s[52:55], s[0:1], 0x18
	s_waitcnt vmcnt(23)
	v_lshlrev_b32_e32 v39, 16, v39
	v_fma_f32 v41, |v39|, s92, 1.0
	v_rcp_f32_e32 v41, v41
	v_mul_f32_e32 v43, v39, v39
	s_waitcnt vmcnt(19)
	v_lshlrev_b32_e32 v38, 16, v40
	v_fma_f32 v40, |v38|, s92, 1.0
	v_rcp_f32_e32 v40, v40
	v_mul_f32_e32 v42, v38, v38
	v_mul_f32_e32 v42, 0xbf38aa3b, v42
	v_mul_f32_e32 v43, 0xbf38aa3b, v43
	v_pk_fma_f32 v[44:45], v[40:41], s[10:11], v[18:19] op_sel_hi:[1,0,0]
	v_exp_f32_e32 v42, v42
	v_pk_fma_f32 v[44:45], v[40:41], v[44:45], s[14:15] op_sel_hi:[1,1,0]
	v_exp_f32_e32 v43, v43
	v_pk_fma_f32 v[44:45], v[40:41], v[44:45], s[16:17] op_sel_hi:[1,1,0]
	v_cmp_gt_f32_e32 vcc, 0, v39
	v_pk_fma_f32 v[44:45], v[40:41], v[44:45], s[18:19] op_sel_hi:[1,1,0]
	s_waitcnt vmcnt(9)
	v_lshlrev_b32_e32 v68, 16, v68
	v_pk_mul_f32 v[40:41], v[40:41], v[44:45]
	s_waitcnt vmcnt(1)
	v_lshlrev_b32_e32 v70, 16, v70
	v_pk_mul_f32 v[40:41], v[42:43], v[40:41]
	v_pk_mul_f32 v[42:43], v[40:41], v[38:39]
	v_pk_fma_f32 v[40:41], v[40:41], v[38:39], v[38:39] neg_lo:[1,0,0] neg_hi:[1,0,0]
	s_nop 0
	v_cndmask_b32_e32 v39, v41, v43, vcc
	v_cmp_gt_f32_e32 vcc, 0, v38
	v_lshlrev_b32_e32 v41, 16, v46
	v_mul_f32_e32 v45, v41, v41
	v_cndmask_b32_e32 v38, v40, v42, vcc
	v_lshlrev_b32_e32 v40, 16, v47
	v_mul_f32_e32 v43, v40, v40
	v_mul_f32_e32 v43, 0xbf38aa3b, v43
	v_fma_f32 v42, |v40|, s92, 1.0
	v_exp_f32_e32 v44, v43
	v_fma_f32 v43, |v41|, s92, 1.0
	v_rcp_f32_e32 v42, v42
	v_rcp_f32_e32 v43, v43
	v_mul_f32_e32 v45, 0xbf38aa3b, v45
	v_exp_f32_e32 v45, v45
	v_cmp_gt_f32_e32 vcc, 0, v41
	v_pk_fma_f32 v[46:47], v[42:43], s[10:11], v[18:19] op_sel_hi:[1,0,0]
	s_nop 0
	v_pk_fma_f32 v[46:47], v[42:43], v[46:47], s[14:15] op_sel_hi:[1,1,0]
	s_nop 0
	v_pk_fma_f32 v[46:47], v[42:43], v[46:47], s[16:17] op_sel_hi:[1,1,0]
	s_nop 0
	v_pk_fma_f32 v[46:47], v[42:43], v[46:47], s[18:19] op_sel_hi:[1,1,0]
	v_pk_mul_f32 v[42:43], v[42:43], v[46:47]
	v_pk_mul_f32 v[42:43], v[44:45], v[42:43]
	v_pk_mul_f32 v[44:45], v[42:43], v[40:41]
	v_pk_fma_f32 v[42:43], v[42:43], v[40:41], v[40:41] neg_lo:[1,0,0] neg_hi:[1,0,0]
	v_lshlrev_b32_e32 v41, 16, v48
	v_cndmask_b32_e32 v47, v43, v45, vcc
	v_cmp_gt_f32_e32 vcc, 0, v40
	v_lshlrev_b32_e32 v40, 16, v49
	v_fma_f32 v43, |v41|, s92, 1.0
	v_cndmask_b32_e32 v46, v42, v44, vcc
	v_fma_f32 v42, |v40|, s92, 1.0
	v_rcp_f32_e32 v42, v42
	v_rcp_f32_e32 v43, v43
	v_mul_f32_e32 v44, v40, v40
	v_mul_f32_e32 v45, v41, v41
	v_mul_f32_e32 v44, 0xbf38aa3b, v44
	v_pk_fma_f32 v[48:49], v[42:43], s[10:11], v[18:19] op_sel_hi:[1,0,0]
	v_mul_f32_e32 v45, 0xbf38aa3b, v45
	v_exp_f32_e32 v44, v44
	v_pk_fma_f32 v[48:49], v[42:43], v[48:49], s[14:15] op_sel_hi:[1,1,0]
	v_exp_f32_e32 v45, v45
	v_pk_fma_f32 v[48:49], v[42:43], v[48:49], s[16:17] op_sel_hi:[1,1,0]
	v_cmp_gt_f32_e32 vcc, 0, v41
	v_pk_fma_f32 v[48:49], v[42:43], v[48:49], s[18:19] op_sel_hi:[1,1,0]
	s_nop 0
	v_pk_mul_f32 v[42:43], v[42:43], v[48:49]
	v_pk_mul_f32 v[42:43], v[44:45], v[42:43]
	v_pk_mul_f32 v[44:45], v[42:43], v[40:41]
	v_pk_fma_f32 v[42:43], v[42:43], v[40:41], v[40:41] neg_lo:[1,0,0] neg_hi:[1,0,0]
	v_lshlrev_b32_e32 v41, 16, v50
	v_cndmask_b32_e32 v43, v43, v45, vcc
	v_cmp_gt_f32_e32 vcc, 0, v40
	v_lshlrev_b32_e32 v40, 16, v51
	v_mul_f32_e32 v45, v40, v40
	v_mul_f32_e32 v45, 0xbf38aa3b, v45
	v_cndmask_b32_e32 v42, v42, v44, vcc
	v_fma_f32 v44, |v40|, s92, 1.0
	v_exp_f32_e32 v48, v45
	v_fma_f32 v45, |v41|, s92, 1.0
	v_rcp_f32_e32 v44, v44
	v_rcp_f32_e32 v45, v45
	v_mul_f32_e32 v49, v41, v41
	v_mul_f32_e32 v49, 0xbf38aa3b, v49
	v_exp_f32_e32 v49, v49
	v_pk_fma_f32 v[50:51], v[44:45], s[10:11], v[18:19] op_sel_hi:[1,0,0]
	v_cmp_gt_f32_e32 vcc, 0, v41
	v_pk_fma_f32 v[50:51], v[44:45], v[50:51], s[14:15] op_sel_hi:[1,1,0]
	s_nop 0
	v_pk_fma_f32 v[50:51], v[44:45], v[50:51], s[16:17] op_sel_hi:[1,1,0]
	s_nop 0
	v_pk_fma_f32 v[50:51], v[44:45], v[50:51], s[18:19] op_sel_hi:[1,1,0]
	v_pk_mul_f32 v[44:45], v[44:45], v[50:51]
	v_pk_mul_f32 v[44:45], v[48:49], v[44:45]
	v_pk_mul_f32 v[48:49], v[44:45], v[40:41]
	v_pk_fma_f32 v[44:45], v[44:45], v[40:41], v[40:41] neg_lo:[1,0,0] neg_hi:[1,0,0]
	v_lshlrev_b32_e32 v41, 16, v52
	v_cndmask_b32_e32 v49, v45, v49, vcc
	v_cmp_gt_f32_e32 vcc, 0, v40
	v_lshlrev_b32_e32 v40, 16, v53
	v_fma_f32 v45, |v41|, s92, 1.0
	v_cndmask_b32_e32 v48, v44, v48, vcc
	v_fma_f32 v44, |v40|, s92, 1.0
	v_rcp_f32_e32 v44, v44
	v_rcp_f32_e32 v45, v45
	v_mul_f32_e32 v50, v40, v40
	v_mul_f32_e32 v51, v41, v41
	v_mul_f32_e32 v50, 0xbf38aa3b, v50
	v_pk_fma_f32 v[52:53], v[44:45], s[10:11], v[18:19] op_sel_hi:[1,0,0]
	v_mul_f32_e32 v51, 0xbf38aa3b, v51
	v_exp_f32_e32 v50, v50
	v_pk_fma_f32 v[52:53], v[44:45], v[52:53], s[14:15] op_sel_hi:[1,1,0]
	v_exp_f32_e32 v51, v51
	v_pk_fma_f32 v[52:53], v[44:45], v[52:53], s[16:17] op_sel_hi:[1,1,0]
	v_cmp_gt_f32_e32 vcc, 0, v41
	v_pk_fma_f32 v[52:53], v[44:45], v[52:53], s[18:19] op_sel_hi:[1,1,0]
	s_nop 0
	v_pk_mul_f32 v[44:45], v[44:45], v[52:53]
	v_pk_mul_f32 v[44:45], v[50:51], v[44:45]
	v_pk_mul_f32 v[50:51], v[44:45], v[40:41]
	v_pk_fma_f32 v[44:45], v[44:45], v[40:41], v[40:41] neg_lo:[1,0,0] neg_hi:[1,0,0]
	v_lshlrev_b32_e32 v41, 16, v71
	v_cndmask_b32_e32 v51, v45, v51, vcc
	v_cmp_gt_f32_e32 vcc, 0, v40
	v_lshlrev_b32_e32 v40, 16, v72
	v_mul_f32_e32 v45, v40, v40
	v_mul_f32_e32 v45, 0xbf38aa3b, v45
	v_cndmask_b32_e32 v50, v44, v50, vcc
	v_fma_f32 v44, |v40|, s92, 1.0
	v_exp_f32_e32 v52, v45
	v_fma_f32 v45, |v41|, s92, 1.0
	v_rcp_f32_e32 v44, v44
	v_rcp_f32_e32 v45, v45
	v_mul_f32_e32 v53, v41, v41
	v_mul_f32_e32 v53, 0xbf38aa3b, v53
	v_exp_f32_e32 v53, v53
	v_pk_fma_f32 v[72:73], v[44:45], s[10:11], v[18:19] op_sel_hi:[1,0,0]
	v_cmp_gt_f32_e32 vcc, 0, v41
	v_pk_fma_f32 v[72:73], v[44:45], v[72:73], s[14:15] op_sel_hi:[1,1,0]
	s_nop 0
	v_pk_fma_f32 v[72:73], v[44:45], v[72:73], s[16:17] op_sel_hi:[1,1,0]
	s_nop 0
	v_pk_fma_f32 v[72:73], v[44:45], v[72:73], s[18:19] op_sel_hi:[1,1,0]
	v_pk_mul_f32 v[44:45], v[44:45], v[72:73]
	v_pk_mul_f32 v[44:45], v[52:53], v[44:45]
	v_pk_mul_f32 v[52:53], v[44:45], v[40:41]
	v_pk_fma_f32 v[44:45], v[44:45], v[40:41], v[40:41] neg_lo:[1,0,0] neg_hi:[1,0,0]
	v_lshlrev_b32_e32 v41, 16, v74
	v_cndmask_b32_e32 v73, v45, v53, vcc
	v_cmp_gt_f32_e32 vcc, 0, v40
	v_lshlrev_b32_e32 v40, 16, v75
	v_fma_f32 v45, |v41|, s92, 1.0
	v_cndmask_b32_e32 v72, v44, v52, vcc
	v_fma_f32 v44, |v40|, s92, 1.0
	v_rcp_f32_e32 v44, v44
	v_rcp_f32_e32 v45, v45
	v_mul_f32_e32 v52, v40, v40
	v_mul_f32_e32 v53, v41, v41
	v_mul_f32_e32 v52, 0xbf38aa3b, v52
	v_pk_fma_f32 v[74:75], v[44:45], s[10:11], v[18:19] op_sel_hi:[1,0,0]
	v_mul_f32_e32 v53, 0xbf38aa3b, v53
	v_exp_f32_e32 v52, v52
	v_pk_fma_f32 v[74:75], v[44:45], v[74:75], s[14:15] op_sel_hi:[1,1,0]
	v_exp_f32_e32 v53, v53
	v_pk_fma_f32 v[74:75], v[44:45], v[74:75], s[16:17] op_sel_hi:[1,1,0]
	v_cmp_gt_f32_e32 vcc, 0, v41
	v_pk_fma_f32 v[74:75], v[44:45], v[74:75], s[18:19] op_sel_hi:[1,1,0]
	s_nop 0
	v_pk_mul_f32 v[44:45], v[44:45], v[74:75]
	v_pk_mul_f32 v[44:45], v[52:53], v[44:45]
	v_pk_mul_f32 v[52:53], v[44:45], v[40:41]
	v_pk_fma_f32 v[44:45], v[44:45], v[40:41], v[40:41] neg_lo:[1,0,0] neg_hi:[1,0,0]
	v_lshlrev_b32_e32 v41, 16, v76
	v_cndmask_b32_e32 v53, v45, v53, vcc
	v_cmp_gt_f32_e32 vcc, 0, v40
	v_lshlrev_b32_e32 v40, 16, v77
	v_mul_f32_e32 v45, v40, v40
	v_mul_f32_e32 v45, 0xbf38aa3b, v45
	v_cndmask_b32_e32 v52, v44, v52, vcc
	v_fma_f32 v44, |v40|, s92, 1.0
	v_exp_f32_e32 v74, v45
	v_fma_f32 v45, |v41|, s92, 1.0
	v_rcp_f32_e32 v44, v44
	v_rcp_f32_e32 v45, v45
	v_mul_f32_e32 v71, v41, v41
	v_mul_f32_e32 v71, 0xbf38aa3b, v71
	v_exp_f32_e32 v75, v71
	v_pk_fma_f32 v[76:77], v[44:45], s[10:11], v[18:19] op_sel_hi:[1,0,0]
	v_cmp_gt_f32_e32 vcc, 0, v41
	v_pk_fma_f32 v[76:77], v[44:45], v[76:77], s[14:15] op_sel_hi:[1,1,0]
	s_nop 0
	v_pk_fma_f32 v[76:77], v[44:45], v[76:77], s[16:17] op_sel_hi:[1,1,0]
	s_nop 0
	v_pk_fma_f32 v[76:77], v[44:45], v[76:77], s[18:19] op_sel_hi:[1,1,0]
	v_pk_mul_f32 v[44:45], v[44:45], v[76:77]
	v_mov_b32_e32 v76, v43
	v_pk_mul_f32 v[44:45], v[74:75], v[44:45]
	v_mov_b32_e32 v77, v53
	v_pk_mul_f32 v[74:75], v[44:45], v[40:41]
	v_pk_fma_f32 v[44:45], v[44:45], v[40:41], v[40:41] neg_lo:[1,0,0] neg_hi:[1,0,0]
	v_mov_b32_e32 v41, v50
	v_cndmask_b32_e32 v75, v45, v75, vcc
	v_cmp_gt_f32_e32 vcc, 0, v40
	v_mov_b32_e32 v40, v38
	v_mov_b32_e32 v45, v52
	v_cndmask_b32_e32 v74, v44, v74, vcc
	v_mov_b32_e32 v44, v42
	v_pk_add_f32 v[40:41], v[40:41], v[44:45]
	v_mov_b32_e32 v44, v39
	v_add_f32_e32 v40, v40, v41
	v_mov_b32_e32 v45, v51
	s_nop 0
	v_add_f32_dpp v40, v40, v40 quad_perm:[1,0,3,2] row_mask:0xf bank_mask:0xf bound_ctrl:1
	v_pk_add_f32 v[44:45], v[44:45], v[76:77]
	v_mov_b32_e32 v76, v49
	v_add_f32_dpp v40, v40, v40 quad_perm:[2,3,0,1] row_mask:0xf bank_mask:0xf bound_ctrl:1
	v_mov_b32_e32 v77, v75
	s_nop 0
	v_add_f32_dpp v40, v40, v40 row_half_mirror row_mask:0xf bank_mask:0xf bound_ctrl:1
	s_nop 1
	v_add_f32_dpp v40, v40, v40 row_mirror row_mask:0xf bank_mask:0xf bound_ctrl:1
	s_nop 1
	v_add_f32_dpp v40, v40, v40 row_bcast:15 row_mask:0xa bank_mask:0xf
	s_nop 1
	v_add_f32_dpp v40, v40, v40 row_bcast:31 row_mask:0xc bank_mask:0xf
	v_add_f32_e32 v41, v44, v45
	v_readlane_b32 s6, v40, 63
	s_nop 0
	v_add_f32_dpp v41, v41, v41 quad_perm:[1,0,3,2] row_mask:0xf bank_mask:0xf bound_ctrl:1
	s_xor_b32 s6, s6, 0x80000000
	s_nop 0
	v_add_f32_dpp v41, v41, v41 quad_perm:[2,3,0,1] row_mask:0xf bank_mask:0xf bound_ctrl:1
	s_nop 1
	v_add_f32_dpp v41, v41, v41 row_half_mirror row_mask:0xf bank_mask:0xf bound_ctrl:1
	s_nop 1
	v_add_f32_dpp v41, v41, v41 row_mirror row_mask:0xf bank_mask:0xf bound_ctrl:1
	s_nop 1
	v_add_f32_dpp v41, v41, v41 row_bcast:15 row_mask:0xa bank_mask:0xf
	s_nop 1
	v_add_f32_dpp v41, v41, v41 row_bcast:31 row_mask:0xc bank_mask:0xf
	s_nop 0
	v_readlane_b32 s7, v41, 63
	s_xor_b32 s7, s7, 0x80000000
	s_nop 0
	v_pk_fma_f32 v[40:41], s[6:7], v[20:21], v[38:39] op_sel_hi:[1,0,1]
	v_pk_fma_f32 v[44:45], s[6:7], v[20:21], v[42:43] op_sel_hi:[1,0,1]
	v_pk_fma_f32 v[42:43], s[6:7], v[20:21], v[50:51] op_sel_hi:[1,0,1]
	v_pk_fma_f32 v[38:39], s[6:7], v[20:21], v[52:53] op_sel_hi:[1,0,1]
	v_mov_b32_e32 v50, v46
	v_mov_b32_e32 v51, v72
	v_mov_b32_e32 v52, v48
	v_mov_b32_e32 v53, v74
	v_pk_add_f32 v[50:51], v[50:51], v[52:53]
	v_mov_b32_e32 v52, v47
	v_add_f32_e32 v50, v50, v51
	v_mov_b32_e32 v53, v73
	s_nop 0
	v_add_f32_dpp v50, v50, v50 quad_perm:[1,0,3,2] row_mask:0xf bank_mask:0xf bound_ctrl:1
	v_pk_add_f32 v[52:53], v[52:53], v[76:77]
	s_nop 0
	v_add_f32_dpp v50, v50, v50 quad_perm:[2,3,0,1] row_mask:0xf bank_mask:0xf bound_ctrl:1
	s_nop 1
	v_add_f32_dpp v50, v50, v50 row_half_mirror row_mask:0xf bank_mask:0xf bound_ctrl:1
	s_nop 1
	v_add_f32_dpp v50, v50, v50 row_mirror row_mask:0xf bank_mask:0xf bound_ctrl:1
	s_nop 1
	v_add_f32_dpp v50, v50, v50 row_bcast:15 row_mask:0xa bank_mask:0xf
	s_nop 1
	v_add_f32_dpp v50, v50, v50 row_bcast:31 row_mask:0xc bank_mask:0xf
	v_add_f32_e32 v51, v52, v53
	v_readlane_b32 s6, v50, 63
	s_nop 0
	v_add_f32_dpp v51, v51, v51 quad_perm:[1,0,3,2] row_mask:0xf bank_mask:0xf bound_ctrl:1
	s_xor_b32 s6, s6, 0x80000000
	s_nop 0
	v_add_f32_dpp v51, v51, v51 quad_perm:[2,3,0,1] row_mask:0xf bank_mask:0xf bound_ctrl:1
	s_nop 1
	v_add_f32_dpp v51, v51, v51 row_half_mirror row_mask:0xf bank_mask:0xf bound_ctrl:1
	s_nop 1
	v_add_f32_dpp v51, v51, v51 row_mirror row_mask:0xf bank_mask:0xf bound_ctrl:1
	s_nop 1
	v_add_f32_dpp v51, v51, v51 row_bcast:15 row_mask:0xa bank_mask:0xf
	s_nop 1
	v_add_f32_dpp v51, v51, v51 row_bcast:31 row_mask:0xc bank_mask:0xf
	s_nop 0
	v_readlane_b32 s7, v51, 63
	s_xor_b32 s7, s7, 0x80000000
	s_nop 0
	v_pk_fma_f32 v[50:51], s[6:7], v[20:21], v[48:49] op_sel_hi:[1,0,1]
	v_pk_fma_f32 v[48:49], s[6:7], v[20:21], v[72:73] op_sel_hi:[1,0,1]
	v_lshlrev_b32_e32 v73, 16, v54
	v_lshlrev_b32_e32 v72, 16, v55
	v_fma_f32 v54, |v72|, s92, 1.0
	v_fma_f32 v55, |v73|, s92, 1.0
	v_rcp_f32_e32 v54, v54
	v_rcp_f32_e32 v55, v55
	v_mul_f32_e32 v71, v72, v72
	v_mul_f32_e32 v71, 0xbf38aa3b, v71
	v_pk_fma_f32 v[52:53], s[6:7], v[20:21], v[46:47] op_sel_hi:[1,0,1]
	v_pk_fma_f32 v[46:47], s[6:7], v[20:21], v[74:75] op_sel_hi:[1,0,1]
	v_exp_f32_e32 v74, v71
	v_mul_f32_e32 v71, v73, v73
	v_pk_fma_f32 v[76:77], v[54:55], s[10:11], v[18:19] op_sel_hi:[1,0,0]
	v_mul_f32_e32 v71, 0xbf38aa3b, v71
	v_pk_fma_f32 v[76:77], v[54:55], v[76:77], s[14:15] op_sel_hi:[1,1,0]
	v_exp_f32_e32 v75, v71
	v_pk_fma_f32 v[76:77], v[54:55], v[76:77], s[16:17] op_sel_hi:[1,1,0]
	v_cmp_gt_f32_e32 vcc, 0, v73
	v_pk_fma_f32 v[76:77], v[54:55], v[76:77], s[18:19] op_sel_hi:[1,1,0]
	s_mov_b32 s6, 0xbe11a98e
	v_pk_mul_f32 v[54:55], v[54:55], v[76:77]
	v_pk_mul_f32 v[54:55], v[74:75], v[54:55]
	v_pk_mul_f32 v[74:75], v[54:55], v[72:73]
	v_pk_fma_f32 v[54:55], v[54:55], v[72:73], v[72:73] neg_lo:[1,0,0] neg_hi:[1,0,0]
	v_lshlrev_b32_e32 v73, 16, v60
	v_cndmask_b32_e32 v55, v55, v75, vcc
	v_cmp_gt_f32_e32 vcc, 0, v72
	v_lshlrev_b32_e32 v72, 16, v61
	v_mul_f32_e32 v61, v72, v72
	v_mul_f32_e32 v61, 0xbf38aa3b, v61
	v_cndmask_b32_e32 v54, v54, v74, vcc
	v_fma_f32 v60, |v72|, s92, 1.0
	v_exp_f32_e32 v74, v61
	v_fma_f32 v61, |v73|, s92, 1.0
	v_rcp_f32_e32 v60, v60
	v_rcp_f32_e32 v61, v61
	v_mul_f32_e32 v71, v73, v73
	v_mul_f32_e32 v71, 0xbf38aa3b, v71
	v_exp_f32_e32 v75, v71
	v_pk_fma_f32 v[76:77], v[60:61], s[10:11], v[18:19] op_sel_hi:[1,0,0]
	v_cmp_gt_f32_e32 vcc, 0, v73
	v_pk_fma_f32 v[76:77], v[60:61], v[76:77], s[14:15] op_sel_hi:[1,1,0]
	s_nop 0
	v_pk_fma_f32 v[76:77], v[60:61], v[76:77], s[16:17] op_sel_hi:[1,1,0]
	s_nop 0
	v_pk_fma_f32 v[76:77], v[60:61], v[76:77], s[18:19] op_sel_hi:[1,1,0]
	v_pk_mul_f32 v[60:61], v[60:61], v[76:77]
	v_pk_mul_f32 v[60:61], v[74:75], v[60:61]
	v_pk_mul_f32 v[74:75], v[60:61], v[72:73]
	v_pk_fma_f32 v[60:61], v[60:61], v[72:73], v[72:73] neg_lo:[1,0,0] neg_hi:[1,0,0]
	v_lshlrev_b32_e32 v73, 16, v56
	v_cndmask_b32_e32 v61, v61, v75, vcc
	v_cmp_gt_f32_e32 vcc, 0, v72
	v_lshlrev_b32_e32 v72, 16, v57
	v_fma_f32 v56, |v72|, s92, 1.0
	v_fma_f32 v57, |v73|, s92, 1.0
	v_rcp_f32_e32 v56, v56
	v_rcp_f32_e32 v57, v57
	v_mul_f32_e32 v71, v72, v72
	v_mul_f32_e32 v71, 0xbf38aa3b, v71
	v_cndmask_b32_e32 v60, v60, v74, vcc
	v_exp_f32_e32 v74, v71
	v_mul_f32_e32 v71, v73, v73
	v_pk_fma_f32 v[76:77], v[56:57], s[10:11], v[18:19] op_sel_hi:[1,0,0]
	v_mul_f32_e32 v71, 0xbf38aa3b, v71
	v_pk_fma_f32 v[76:77], v[56:57], v[76:77], s[14:15] op_sel_hi:[1,1,0]
	v_exp_f32_e32 v75, v71
	v_pk_fma_f32 v[76:77], v[56:57], v[76:77], s[16:17] op_sel_hi:[1,1,0]
	v_cmp_gt_f32_e32 vcc, 0, v73
	v_pk_fma_f32 v[76:77], v[56:57], v[76:77], s[18:19] op_sel_hi:[1,1,0]
	s_nop 0
	v_pk_mul_f32 v[56:57], v[56:57], v[76:77]
	v_pk_mul_f32 v[56:57], v[74:75], v[56:57]
	v_pk_mul_f32 v[74:75], v[56:57], v[72:73]
	v_pk_fma_f32 v[56:57], v[56:57], v[72:73], v[72:73] neg_lo:[1,0,0] neg_hi:[1,0,0]
	v_lshlrev_b32_e32 v73, 16, v62
	v_cndmask_b32_e32 v57, v57, v75, vcc
	v_cmp_gt_f32_e32 vcc, 0, v72
	v_lshlrev_b32_e32 v72, 16, v63
	v_mul_f32_e32 v63, v72, v72
	v_mul_f32_e32 v63, 0xbf38aa3b, v63
	v_cndmask_b32_e32 v56, v56, v74, vcc
	v_fma_f32 v62, |v72|, s92, 1.0
	v_exp_f32_e32 v74, v63
	v_fma_f32 v63, |v73|, s92, 1.0
	v_rcp_f32_e32 v62, v62
	v_rcp_f32_e32 v63, v63
	v_mul_f32_e32 v71, v73, v73
	v_mul_f32_e32 v71, 0xbf38aa3b, v71
	v_exp_f32_e32 v75, v71
	v_pk_fma_f32 v[76:77], v[62:63], s[10:11], v[18:19] op_sel_hi:[1,0,0]
	v_cmp_gt_f32_e32 vcc, 0, v73
	v_pk_fma_f32 v[76:77], v[62:63], v[76:77], s[14:15] op_sel_hi:[1,1,0]
	v_lshlrev_b32_e32 v71, 16, v69
	v_pk_fma_f32 v[76:77], v[62:63], v[76:77], s[16:17] op_sel_hi:[1,1,0]
	v_fma_f32 v69, |v70|, s92, 1.0
	v_pk_fma_f32 v[76:77], v[62:63], v[76:77], s[18:19] op_sel_hi:[1,1,0]
	v_pk_mul_f32 v[62:63], v[62:63], v[76:77]
	v_pk_mul_f32 v[62:63], v[74:75], v[62:63]
	v_pk_mul_f32 v[74:75], v[62:63], v[72:73]
	v_pk_fma_f32 v[62:63], v[62:63], v[72:73], v[72:73] neg_lo:[1,0,0] neg_hi:[1,0,0]
	s_nop 0
	v_cndmask_b32_e32 v63, v63, v75, vcc
	v_cmp_gt_f32_e32 vcc, 0, v72
	v_rcp_f32_e32 v72, v69
	v_fma_f32 v69, |v71|, s92, 1.0
	v_rcp_f32_e32 v73, v69
	v_mul_f32_e32 v69, v70, v70
	v_mul_f32_e32 v69, 0xbf38aa3b, v69
	v_cndmask_b32_e32 v62, v62, v74, vcc
	v_exp_f32_e32 v74, v69
	v_mul_f32_e32 v69, v71, v71
	v_pk_fma_f32 v[76:77], v[72:73], s[10:11], v[18:19] op_sel_hi:[1,0,0]
	v_mul_f32_e32 v69, 0xbf38aa3b, v69
	v_pk_fma_f32 v[76:77], v[72:73], v[76:77], s[14:15] op_sel_hi:[1,1,0]
	v_exp_f32_e32 v75, v69
	v_pk_fma_f32 v[76:77], v[72:73], v[76:77], s[16:17] op_sel_hi:[1,1,0]
	v_cmp_gt_f32_e32 vcc, 0, v71
	v_pk_fma_f32 v[76:77], v[72:73], v[76:77], s[18:19] op_sel_hi:[1,1,0]
	v_lshlrev_b32_e32 v69, 16, v67
	v_pk_mul_f32 v[72:73], v[72:73], v[76:77]
	v_fma_f32 v67, |v68|, s92, 1.0
	v_pk_mul_f32 v[72:73], v[74:75], v[72:73]
	v_pk_mul_f32 v[74:75], v[72:73], v[70:71]
	v_pk_fma_f32 v[72:73], v[72:73], v[70:71], v[70:71] neg_lo:[1,0,0] neg_hi:[1,0,0]
	s_nop 0
	v_cndmask_b32_e32 v71, v73, v75, vcc
	v_cmp_gt_f32_e32 vcc, 0, v70
	s_nop 1
	v_cndmask_b32_e32 v70, v72, v74, vcc
	v_rcp_f32_e32 v72, v67
	v_mul_f32_e32 v67, v68, v68
	v_mul_f32_e32 v67, 0xbf38aa3b, v67
	v_exp_f32_e32 v74, v67
	v_fma_f32 v67, |v69|, s92, 1.0
	v_rcp_f32_e32 v73, v67
	v_mul_f32_e32 v67, v69, v69
	v_mul_f32_e32 v67, 0xbf38aa3b, v67
	v_exp_f32_e32 v75, v67
	v_pk_fma_f32 v[76:77], v[72:73], s[10:11], v[18:19] op_sel_hi:[1,0,0]
	v_cmp_gt_f32_e32 vcc, 0, v69
	v_pk_fma_f32 v[76:77], v[72:73], v[76:77], s[14:15] op_sel_hi:[1,1,0]
	s_nop 0
	v_pk_fma_f32 v[76:77], v[72:73], v[76:77], s[16:17] op_sel_hi:[1,1,0]
	s_nop 0
	v_pk_fma_f32 v[76:77], v[72:73], v[76:77], s[18:19] op_sel_hi:[1,1,0]
	v_pk_mul_f32 v[72:73], v[72:73], v[76:77]
	v_pk_mul_f32 v[72:73], v[74:75], v[72:73]
	v_pk_mul_f32 v[74:75], v[72:73], v[68:69]
	v_pk_fma_f32 v[72:73], v[72:73], v[68:69], v[68:69] neg_lo:[1,0,0] neg_hi:[1,0,0]
	s_nop 0
	v_cndmask_b32_e32 v69, v73, v75, vcc
	v_cmp_gt_f32_e32 vcc, 0, v68
	v_lshlrev_b32_e32 v73, 16, v64
	s_nop 0
	v_cndmask_b32_e32 v68, v72, v74, vcc
	s_waitcnt vmcnt(0)
	v_lshlrev_b32_e32 v72, 16, v65
	v_fma_f32 v64, |v72|, s92, 1.0
	v_fma_f32 v65, |v73|, s92, 1.0
	v_rcp_f32_e32 v64, v64
	v_rcp_f32_e32 v65, v65
	v_mul_f32_e32 v67, v72, v72
	v_mul_f32_e32 v67, 0xbf38aa3b, v67
	v_exp_f32_e32 v74, v67
	v_mul_f32_e32 v67, v73, v73
	v_pk_fma_f32 v[76:77], v[64:65], s[10:11], v[18:19] op_sel_hi:[1,0,0]
	v_mul_f32_e32 v67, 0xbf38aa3b, v67
	v_pk_fma_f32 v[76:77], v[64:65], v[76:77], s[14:15] op_sel_hi:[1,1,0]
	v_exp_f32_e32 v75, v67
	v_pk_fma_f32 v[76:77], v[64:65], v[76:77], s[16:17] op_sel_hi:[1,1,0]
	v_cmp_gt_f32_e32 vcc, 0, v73
	v_pk_fma_f32 v[76:77], v[64:65], v[76:77], s[18:19] op_sel_hi:[1,1,0]
	s_nop 0
	v_pk_mul_f32 v[64:65], v[64:65], v[76:77]
	v_pk_mul_f32 v[64:65], v[74:75], v[64:65]
	v_pk_mul_f32 v[74:75], v[64:65], v[72:73]
	v_pk_fma_f32 v[64:65], v[64:65], v[72:73], v[72:73] neg_lo:[1,0,0] neg_hi:[1,0,0]
	v_lshlrev_b32_e32 v73, 16, v58
	v_cndmask_b32_e32 v65, v65, v75, vcc
	v_cmp_gt_f32_e32 vcc, 0, v72
	v_lshlrev_b32_e32 v72, 16, v59
	v_mul_f32_e32 v59, v72, v72
	v_mul_f32_e32 v59, 0xbf38aa3b, v59
	v_cndmask_b32_e32 v64, v64, v74, vcc
	v_fma_f32 v58, |v72|, s92, 1.0
	v_exp_f32_e32 v74, v59
	v_fma_f32 v59, |v73|, s92, 1.0
	v_rcp_f32_e32 v58, v58
	v_rcp_f32_e32 v59, v59
	v_mul_f32_e32 v67, v73, v73
	v_mul_f32_e32 v67, 0xbf38aa3b, v67
	v_exp_f32_e32 v75, v67
	v_pk_fma_f32 v[18:19], v[58:59], s[10:11], v[18:19] op_sel_hi:[1,0,0]
	v_cmp_gt_f32_e32 vcc, 0, v73
	v_pk_fma_f32 v[18:19], v[58:59], v[18:19], s[14:15] op_sel_hi:[1,1,0]
	v_mov_b32_e32 v67, v131
	v_pk_fma_f32 v[18:19], v[58:59], v[18:19], s[6:7] op_sel_hi:[1,1,0]
	s_nop 0
	v_pk_fma_f32 v[18:19], v[58:59], v[18:19], s[8:9] op_sel_hi:[1,1,0]
	v_readlane_b32 s9, v253, 54
	v_pk_mul_f32 v[18:19], v[58:59], v[18:19]
	s_nop 0
	v_pk_mul_f32 v[18:19], v[74:75], v[18:19]
	v_mov_b32_e32 v74, v57
	v_pk_mul_f32 v[58:59], v[18:19], v[72:73]
	v_pk_fma_f32 v[18:19], v[18:19], v[72:73], v[72:73] neg_lo:[1,0,0] neg_hi:[1,0,0]
	v_mov_b32_e32 v75, v65
	v_cndmask_b32_e32 v73, v19, v59, vcc
	v_cmp_gt_f32_e32 vcc, 0, v72
	v_mov_b32_e32 v19, v70
	v_mov_b32_e32 v59, v64
	v_cndmask_b32_e32 v72, v18, v58, vcc
	v_mov_b32_e32 v18, v54
	v_mov_b32_e32 v58, v56
	v_pk_add_f32 v[18:19], v[18:19], v[58:59]
	v_mov_b32_e32 v58, v55
	v_add_f32_e32 v18, v18, v19
	v_mov_b32_e32 v59, v71
	s_nop 0
	v_add_f32_dpp v18, v18, v18 quad_perm:[1,0,3,2] row_mask:0xf bank_mask:0xf bound_ctrl:1
	v_pk_add_f32 v[58:59], v[58:59], v[74:75]
	v_mov_b32_e32 v74, v63
	v_add_f32_dpp v18, v18, v18 quad_perm:[2,3,0,1] row_mask:0xf bank_mask:0xf bound_ctrl:1
	v_mov_b32_e32 v75, v73
	s_nop 0
	v_add_f32_dpp v18, v18, v18 row_half_mirror row_mask:0xf bank_mask:0xf bound_ctrl:1
	s_nop 1
	v_add_f32_dpp v18, v18, v18 row_mirror row_mask:0xf bank_mask:0xf bound_ctrl:1
	s_nop 1
	v_add_f32_dpp v18, v18, v18 row_bcast:15 row_mask:0xa bank_mask:0xf
	s_nop 1
	v_add_f32_dpp v18, v18, v18 row_bcast:31 row_mask:0xc bank_mask:0xf
	v_add_f32_e32 v19, v58, v59
	v_readlane_b32 s6, v18, 63
	s_nop 0
	v_add_f32_dpp v19, v19, v19 quad_perm:[1,0,3,2] row_mask:0xf bank_mask:0xf bound_ctrl:1
	s_xor_b32 s6, s6, 0x80000000
	s_nop 0
	v_add_f32_dpp v19, v19, v19 quad_perm:[2,3,0,1] row_mask:0xf bank_mask:0xf bound_ctrl:1
	s_nop 1
	v_add_f32_dpp v19, v19, v19 row_half_mirror row_mask:0xf bank_mask:0xf bound_ctrl:1
	s_nop 1
	v_add_f32_dpp v19, v19, v19 row_mirror row_mask:0xf bank_mask:0xf bound_ctrl:1
	s_nop 1
	v_add_f32_dpp v19, v19, v19 row_bcast:15 row_mask:0xa bank_mask:0xf
	s_nop 1
	v_add_f32_dpp v19, v19, v19 row_bcast:31 row_mask:0xc bank_mask:0xf
	s_nop 0
	v_readlane_b32 s7, v19, 63
	s_xor_b32 s7, s7, 0x80000000
	s_nop 0
	v_pk_fma_f32 v[58:59], s[6:7], v[20:21], v[54:55] op_sel_hi:[1,0,1]
	v_pk_fma_f32 v[54:55], s[6:7], v[20:21], v[70:71] op_sel_hi:[1,0,1]
	v_pk_fma_f32 v[18:19], s[6:7], v[20:21], v[64:65] op_sel_hi:[1,0,1]
	v_mov_b32_e32 v64, v60
	v_mov_b32_e32 v65, v68
	v_mov_b32_e32 v70, v62
	v_mov_b32_e32 v71, v72
	v_pk_add_f32 v[64:65], v[64:65], v[70:71]
	v_mov_b32_e32 v70, v61
	v_add_f32_e32 v64, v64, v65
	v_mov_b32_e32 v71, v69
	s_nop 0
	v_add_f32_dpp v64, v64, v64 quad_perm:[1,0,3,2] row_mask:0xf bank_mask:0xf bound_ctrl:1
	v_pk_add_f32 v[70:71], v[70:71], v[74:75]
	v_pk_fma_f32 v[56:57], s[6:7], v[20:21], v[56:57] op_sel_hi:[1,0,1]
	v_add_f32_dpp v64, v64, v64 quad_perm:[2,3,0,1] row_mask:0xf bank_mask:0xf bound_ctrl:1
	s_nop 1
	v_add_f32_dpp v64, v64, v64 row_half_mirror row_mask:0xf bank_mask:0xf bound_ctrl:1
	s_nop 1
	v_add_f32_dpp v64, v64, v64 row_mirror row_mask:0xf bank_mask:0xf bound_ctrl:1
	s_nop 1
	v_add_f32_dpp v64, v64, v64 row_bcast:15 row_mask:0xa bank_mask:0xf
	s_nop 1
	v_add_f32_dpp v64, v64, v64 row_bcast:31 row_mask:0xc bank_mask:0xf
	v_add_f32_e32 v65, v70, v71
	v_readlane_b32 s6, v64, 63
	s_xor_b32 s6, s6, 0x80000000
	v_add_f32_dpp v65, v65, v65 quad_perm:[1,0,3,2] row_mask:0xf bank_mask:0xf bound_ctrl:1
	v_mov_b32_e32 v70, v14
	v_mov_b32_e32 v71, v10
	v_add_f32_dpp v65, v65, v65 quad_perm:[2,3,0,1] row_mask:0xf bank_mask:0xf bound_ctrl:1
	v_pk_mul_f32 v[70:71], v[70:71], v[70:71]
	s_nop 0
	v_add_f32_dpp v65, v65, v65 row_half_mirror row_mask:0xf bank_mask:0xf bound_ctrl:1
	s_nop 1
	v_add_f32_dpp v65, v65, v65 row_mirror row_mask:0xf bank_mask:0xf bound_ctrl:1
	s_nop 1
	v_mov_b32_dpp v67, v65 row_bcast:15 row_mask:0xa bank_mask:0xf
	v_add_f32_e32 v65, v65, v67
	s_nop 1
	v_add_f32_dpp v65, v65, v65 row_bcast:31 row_mask:0xc bank_mask:0xf
	s_nop 0
	v_readlane_b32 s7, v65, 63
	s_xor_b32 s7, s7, 0x80000000
	s_nop 0
	v_pk_fma_f32 v[64:65], s[6:7], v[20:21], v[60:61] op_sel_hi:[1,0,1]
	v_pk_fma_f32 v[60:61], s[6:7], v[20:21], v[68:69] op_sel_hi:[1,0,1]
	v_mov_b32_e32 v68, v16
	v_mov_b32_e32 v69, v12
	v_pk_fma_f32 v[68:69], v[68:69], v[68:69], v[70:71]
	v_pk_fma_f32 v[62:63], s[6:7], v[20:21], v[62:63] op_sel_hi:[1,0,1]
	v_add_f32_e32 v68, v68, v69
	v_pk_fma_f32 v[20:21], s[6:7], v[20:21], v[72:73] op_sel_hi:[1,0,1]
	s_nop 0
	v_add_f32_dpp v68, v68, v68 quad_perm:[1,0,3,2] row_mask:0xf bank_mask:0xf bound_ctrl:1
	s_lshl_b32 s6, s34, 5
	s_add_i32 s7, s6, 0
	v_add_f32_dpp v68, v68, v68 quad_perm:[2,3,0,1] row_mask:0xf bank_mask:0xf bound_ctrl:1
	v_mov_b32_e32 v70, v15
	v_mov_b32_e32 v71, v11
	v_add_f32_dpp v68, v68, v68 row_half_mirror row_mask:0xf bank_mask:0xf bound_ctrl:1
	v_mov_b32_e32 v67, s7
	v_pk_mul_f32 v[70:71], v[70:71], v[70:71]
	v_add_f32_dpp v68, v68, v68 row_mirror row_mask:0xf bank_mask:0xf bound_ctrl:1
	s_nop 1
	v_add_f32_dpp v68, v68, v68 row_bcast:15 row_mask:0xa bank_mask:0xf
	s_nop 1
	v_add_f32_dpp v68, v68, v68 row_bcast:31 row_mask:0xc bank_mask:0xf
	v_mov_b32_e32 v69, v13
	v_readlane_b32 s7, v68, 63
	v_mov_b32_e32 v68, v17
	v_pk_fma_f32 v[68:69], v[68:69], v[68:69], v[70:71]
	v_mov_b32_e32 v70, v8
	v_add_f32_e32 v68, v68, v69
	v_mov_b32_e32 v71, v2
	s_nop 0
	v_add_f32_dpp v68, v68, v68 quad_perm:[1,0,3,2] row_mask:0xf bank_mask:0xf bound_ctrl:1
	v_fma_f32 v73, s7, v235, v225
	v_pk_mul_f32 v[70:71], v[70:71], v[70:71]
	v_add_f32_dpp v68, v68, v68 quad_perm:[2,3,0,1] row_mask:0xf bank_mask:0xf bound_ctrl:1
	v_rsq_f32_e32 v84, v73
	s_nop 0
	v_add_f32_dpp v68, v68, v68 row_half_mirror row_mask:0xf bank_mask:0xf bound_ctrl:1
	s_nop 1
	v_add_f32_dpp v68, v68, v68 row_mirror row_mask:0xf bank_mask:0xf bound_ctrl:1
	s_nop 1
	v_add_f32_dpp v68, v68, v68 row_bcast:15 row_mask:0xa bank_mask:0xf
	s_nop 1
	v_add_f32_dpp v68, v68, v68 row_bcast:31 row_mask:0xc bank_mask:0xf
	v_mov_b32_e32 v69, v6
	v_readlane_b32 s7, v68, 63
	v_mov_b32_e32 v68, v4
	v_pk_fma_f32 v[68:69], v[68:69], v[68:69], v[70:71]
	v_mov_b32_e32 v70, v9
	v_add_f32_e32 v68, v68, v69
	v_mov_b32_e32 v71, v3
	s_nop 0
	v_add_f32_dpp v68, v68, v68 quad_perm:[1,0,3,2] row_mask:0xf bank_mask:0xf bound_ctrl:1
	v_fma_f32 v75, s7, v235, v225
	v_pk_mul_f32 v[70:71], v[70:71], v[70:71]
	v_add_f32_dpp v68, v68, v68 quad_perm:[2,3,0,1] row_mask:0xf bank_mask:0xf bound_ctrl:1
	v_rsq_f32_e32 v85, v75
	s_nop 0
	v_add_f32_dpp v68, v68, v68 row_half_mirror row_mask:0xf bank_mask:0xf bound_ctrl:1
	v_pk_mul_f32 v[16:17], v[16:17], v[84:85]
	s_nop 0
	v_add_f32_dpp v68, v68, v68 row_mirror row_mask:0xf bank_mask:0xf bound_ctrl:1
	s_nop 1
	v_add_f32_dpp v68, v68, v68 row_bcast:15 row_mask:0xa bank_mask:0xf
	s_nop 1
	v_add_f32_dpp v68, v68, v68 row_bcast:31 row_mask:0xc bank_mask:0xf
	v_mov_b32_e32 v69, v7
	v_readlane_b32 s7, v68, 63
	v_mov_b32_e32 v68, v5
	v_pk_fma_f32 v[68:69], v[68:69], v[68:69], v[70:71]
	v_mov_b32_e32 v70, v34
	v_add_f32_e32 v68, v68, v69
	v_mov_b32_e32 v71, v30
	s_nop 0
	v_add_f32_dpp v68, v68, v68 quad_perm:[1,0,3,2] row_mask:0xf bank_mask:0xf bound_ctrl:1
	v_fma_f32 v77, s7, v235, v225
	v_pk_mul_f32 v[70:71], v[70:71], v[70:71]
	v_add_f32_dpp v68, v68, v68 quad_perm:[2,3,0,1] row_mask:0xf bank_mask:0xf bound_ctrl:1
	v_rsq_f32_e32 v86, v77
	s_nop 0
	v_add_f32_dpp v68, v68, v68 row_half_mirror row_mask:0xf bank_mask:0xf bound_ctrl:1
	s_nop 1
	v_add_f32_dpp v68, v68, v68 row_mirror row_mask:0xf bank_mask:0xf bound_ctrl:1
	s_nop 1
	v_add_f32_dpp v68, v68, v68 row_bcast:15 row_mask:0xa bank_mask:0xf
	s_nop 1
	v_add_f32_dpp v68, v68, v68 row_bcast:31 row_mask:0xc bank_mask:0xf
	v_mov_b32_e32 v69, v32
	v_readlane_b32 s7, v68, 63
	v_mov_b32_e32 v68, v36
	v_pk_fma_f32 v[68:69], v[68:69], v[68:69], v[70:71]
	v_mov_b32_e32 v70, v35
	v_add_f32_e32 v68, v68, v69
	v_mov_b32_e32 v71, v31
	s_nop 0
	v_add_f32_dpp v68, v68, v68 quad_perm:[1,0,3,2] row_mask:0xf bank_mask:0xf bound_ctrl:1
	v_fma_f32 v79, s7, v235, v225
	v_pk_mul_f32 v[70:71], v[70:71], v[70:71]
	v_add_f32_dpp v68, v68, v68 quad_perm:[2,3,0,1] row_mask:0xf bank_mask:0xf bound_ctrl:1
	v_rsq_f32_e32 v87, v79
	s_nop 0
	v_add_f32_dpp v68, v68, v68 row_half_mirror row_mask:0xf bank_mask:0xf bound_ctrl:1
	v_pk_mul_f32 v[4:5], v[4:5], v[86:87]
	s_nop 0
	v_add_f32_dpp v68, v68, v68 row_mirror row_mask:0xf bank_mask:0xf bound_ctrl:1
	v_pk_mul_f32 v[2:3], v[2:3], v[86:87]
	v_pk_mul_f32 v[8:9], v[8:9], v[86:87]
	v_add_f32_dpp v68, v68, v68 row_bcast:15 row_mask:0xa bank_mask:0xf
	v_pk_mul_f32 v[6:7], v[6:7], v[86:87]
	s_nop 0
	v_add_f32_dpp v68, v68, v68 row_bcast:31 row_mask:0xc bank_mask:0xf
	v_mov_b32_e32 v69, v33
	v_readlane_b32 s7, v68, 63
	v_mov_b32_e32 v68, v37
	v_pk_fma_f32 v[68:69], v[68:69], v[68:69], v[70:71]
	v_mov_b32_e32 v70, v26
	v_add_f32_e32 v68, v68, v69
	v_mov_b32_e32 v71, v22
	s_nop 0
	v_add_f32_dpp v68, v68, v68 quad_perm:[1,0,3,2] row_mask:0xf bank_mask:0xf bound_ctrl:1
	v_fma_f32 v81, s7, v235, v225
	v_pk_mul_f32 v[70:71], v[70:71], v[70:71]
	v_add_f32_dpp v68, v68, v68 quad_perm:[2,3,0,1] row_mask:0xf bank_mask:0xf bound_ctrl:1
	s_nop 1
	v_add_f32_dpp v68, v68, v68 row_half_mirror row_mask:0xf bank_mask:0xf bound_ctrl:1
	s_nop 1
	v_add_f32_dpp v68, v68, v68 row_mirror row_mask:0xf bank_mask:0xf bound_ctrl:1
	s_nop 1
	v_add_f32_dpp v68, v68, v68 row_bcast:15 row_mask:0xa bank_mask:0xf
	s_nop 1
	v_add_f32_dpp v68, v68, v68 row_bcast:31 row_mask:0xc bank_mask:0xf
	v_mov_b32_e32 v69, v24
	v_readlane_b32 s7, v68, 63
	v_mov_b32_e32 v68, v28
	v_pk_fma_f32 v[68:69], v[68:69], v[68:69], v[70:71]
	v_mov_b32_e32 v70, v27
	v_add_f32_e32 v68, v68, v69
	v_mov_b32_e32 v71, v23
	s_nop 0
	v_add_f32_dpp v68, v68, v68 quad_perm:[1,0,3,2] row_mask:0xf bank_mask:0xf bound_ctrl:1
	v_fma_f32 v83, s7, v235, v225
	v_pk_mul_f32 v[70:71], v[70:71], v[70:71]
	v_add_f32_dpp v68, v68, v68 quad_perm:[2,3,0,1] row_mask:0xf bank_mask:0xf bound_ctrl:1
	s_nop 1
	v_add_f32_dpp v68, v68, v68 row_half_mirror row_mask:0xf bank_mask:0xf bound_ctrl:1
	s_nop 1
	v_add_f32_dpp v68, v68, v68 row_mirror row_mask:0xf bank_mask:0xf bound_ctrl:1
	s_nop 1
	v_add_f32_dpp v68, v68, v68 row_bcast:15 row_mask:0xa bank_mask:0xf
	s_nop 1
	v_add_f32_dpp v68, v68, v68 row_bcast:31 row_mask:0xc bank_mask:0xf
	v_mov_b32_e32 v69, v25
	v_readlane_b32 s7, v68, 63
	v_mov_b32_e32 v68, v29
	v_pk_fma_f32 v[68:69], v[68:69], v[68:69], v[70:71]
	v_mov_b32_e32 v70, v50
	v_add_f32_e32 v68, v68, v69
	v_mov_b32_e32 v71, v46
	s_nop 0
	v_add_f32_dpp v68, v68, v68 quad_perm:[1,0,3,2] row_mask:0xf bank_mask:0xf bound_ctrl:1
	v_fma_f32 v90, s7, v235, v225
	v_pk_mul_f32 v[70:71], v[70:71], v[70:71]
	v_add_f32_dpp v68, v68, v68 quad_perm:[2,3,0,1] row_mask:0xf bank_mask:0xf bound_ctrl:1
	s_nop 1
	v_add_f32_dpp v68, v68, v68 row_half_mirror row_mask:0xf bank_mask:0xf bound_ctrl:1
	s_nop 1
	v_add_f32_dpp v68, v68, v68 row_mirror row_mask:0xf bank_mask:0xf bound_ctrl:1
	s_nop 1
	v_add_f32_dpp v68, v68, v68 row_bcast:15 row_mask:0xa bank_mask:0xf
	s_nop 1
	v_add_f32_dpp v68, v68, v68 row_bcast:31 row_mask:0xc bank_mask:0xf
	v_mov_b32_e32 v69, v48
	v_readlane_b32 s7, v68, 63
	v_mov_b32_e32 v68, v52
	v_pk_fma_f32 v[68:69], v[68:69], v[68:69], v[70:71]
	v_mov_b32_e32 v70, v51
	v_add_f32_e32 v68, v68, v69
	v_mov_b32_e32 v71, v47
	s_nop 0
	v_add_f32_dpp v68, v68, v68 quad_perm:[1,0,3,2] row_mask:0xf bank_mask:0xf bound_ctrl:1
	v_fma_f32 v91, s7, v235, v225
	v_pk_mul_f32 v[70:71], v[70:71], v[70:71]
	v_add_f32_dpp v68, v68, v68 quad_perm:[2,3,0,1] row_mask:0xf bank_mask:0xf bound_ctrl:1
	s_nop 1
	v_add_f32_dpp v68, v68, v68 row_half_mirror row_mask:0xf bank_mask:0xf bound_ctrl:1
	s_nop 1
	v_add_f32_dpp v68, v68, v68 row_mirror row_mask:0xf bank_mask:0xf bound_ctrl:1
	s_nop 1
	v_add_f32_dpp v68, v68, v68 row_bcast:15 row_mask:0xa bank_mask:0xf
	s_nop 1
	v_add_f32_dpp v68, v68, v68 row_bcast:31 row_mask:0xc bank_mask:0xf
	v_mov_b32_e32 v69, v49
	v_readlane_b32 s7, v68, 63
	v_mov_b32_e32 v68, v53
	v_pk_fma_f32 v[68:69], v[68:69], v[68:69], v[70:71]
	v_mov_b32_e32 v70, v44
	v_add_f32_e32 v68, v68, v69
	v_mov_b32_e32 v71, v38
	s_nop 0
	v_add_f32_dpp v68, v68, v68 quad_perm:[1,0,3,2] row_mask:0xf bank_mask:0xf bound_ctrl:1
	v_fma_f32 v92, s7, v235, v225
	v_pk_mul_f32 v[70:71], v[70:71], v[70:71]
	v_add_f32_dpp v68, v68, v68 quad_perm:[2,3,0,1] row_mask:0xf bank_mask:0xf bound_ctrl:1
	s_nop 1
	v_add_f32_dpp v68, v68, v68 row_half_mirror row_mask:0xf bank_mask:0xf bound_ctrl:1
	s_nop 1
	v_add_f32_dpp v68, v68, v68 row_mirror row_mask:0xf bank_mask:0xf bound_ctrl:1
	s_nop 1
	v_add_f32_dpp v68, v68, v68 row_bcast:15 row_mask:0xa bank_mask:0xf
	s_nop 1
	v_add_f32_dpp v68, v68, v68 row_bcast:31 row_mask:0xc bank_mask:0xf
	v_mov_b32_e32 v69, v42
	v_readlane_b32 s7, v68, 63
	v_mov_b32_e32 v68, v40
	v_pk_fma_f32 v[68:69], v[68:69], v[68:69], v[70:71]
	v_mov_b32_e32 v70, v45
	v_add_f32_e32 v68, v68, v69
	v_mov_b32_e32 v71, v39
	s_nop 0
	v_add_f32_dpp v68, v68, v68 quad_perm:[1,0,3,2] row_mask:0xf bank_mask:0xf bound_ctrl:1
	v_fma_f32 v93, s7, v235, v225
	v_pk_mul_f32 v[70:71], v[70:71], v[70:71]
	v_add_f32_dpp v68, v68, v68 quad_perm:[2,3,0,1] row_mask:0xf bank_mask:0xf bound_ctrl:1
	s_nop 1
	v_add_f32_dpp v68, v68, v68 row_half_mirror row_mask:0xf bank_mask:0xf bound_ctrl:1
	s_nop 1
	v_add_f32_dpp v68, v68, v68 row_mirror row_mask:0xf bank_mask:0xf bound_ctrl:1
	s_nop 1
	v_add_f32_dpp v68, v68, v68 row_bcast:15 row_mask:0xa bank_mask:0xf
	s_nop 1
	v_add_f32_dpp v68, v68, v68 row_bcast:31 row_mask:0xc bank_mask:0xf
	v_mov_b32_e32 v69, v43
	v_readlane_b32 s7, v68, 63
	v_mov_b32_e32 v68, v41
	v_pk_fma_f32 v[68:69], v[68:69], v[68:69], v[70:71]
	v_mov_b32_e32 v70, v62
	v_add_f32_e32 v68, v68, v69
	v_mov_b32_e32 v71, v20
	s_nop 0
	v_add_f32_dpp v68, v68, v68 quad_perm:[1,0,3,2] row_mask:0xf bank_mask:0xf bound_ctrl:1
	v_fma_f32 v94, s7, v235, v225
	v_pk_mul_f32 v[70:71], v[70:71], v[70:71]
	v_add_f32_dpp v68, v68, v68 quad_perm:[2,3,0,1] row_mask:0xf bank_mask:0xf bound_ctrl:1
	s_nop 1
	v_add_f32_dpp v68, v68, v68 row_half_mirror row_mask:0xf bank_mask:0xf bound_ctrl:1
	s_nop 1
	v_add_f32_dpp v68, v68, v68 row_mirror row_mask:0xf bank_mask:0xf bound_ctrl:1
	s_nop 1
	v_add_f32_dpp v68, v68, v68 row_bcast:15 row_mask:0xa bank_mask:0xf
	s_nop 1
	v_add_f32_dpp v68, v68, v68 row_bcast:31 row_mask:0xc bank_mask:0xf
	v_mov_b32_e32 v69, v60
	v_readlane_b32 s7, v68, 63
	v_mov_b32_e32 v68, v64
	v_pk_fma_f32 v[68:69], v[68:69], v[68:69], v[70:71]
	v_mov_b32_e32 v70, v63
	v_add_f32_e32 v68, v68, v69
	v_mov_b32_e32 v71, v21
	s_nop 0
	v_add_f32_dpp v68, v68, v68 quad_perm:[1,0,3,2] row_mask:0xf bank_mask:0xf bound_ctrl:1
	v_fma_f32 v95, s7, v235, v225
	v_pk_mul_f32 v[70:71], v[70:71], v[70:71]
	v_add_f32_dpp v68, v68, v68 quad_perm:[2,3,0,1] row_mask:0xf bank_mask:0xf bound_ctrl:1
	s_nop 1
	v_add_f32_dpp v68, v68, v68 row_half_mirror row_mask:0xf bank_mask:0xf bound_ctrl:1
	s_nop 1
	v_add_f32_dpp v68, v68, v68 row_mirror row_mask:0xf bank_mask:0xf bound_ctrl:1
	s_nop 1
	v_add_f32_dpp v68, v68, v68 row_bcast:15 row_mask:0xa bank_mask:0xf
	s_nop 1
	v_add_f32_dpp v68, v68, v68 row_bcast:31 row_mask:0xc bank_mask:0xf
	v_mov_b32_e32 v69, v61
	v_readlane_b32 s7, v68, 63
	v_mov_b32_e32 v68, v65
	v_pk_fma_f32 v[68:69], v[68:69], v[68:69], v[70:71]
	v_mov_b32_e32 v70, v56
	v_add_f32_e32 v68, v68, v69
	v_mov_b32_e32 v71, v18
	s_nop 0
	v_add_f32_dpp v68, v68, v68 quad_perm:[1,0,3,2] row_mask:0xf bank_mask:0xf bound_ctrl:1
	v_fma_f32 v96, s7, v235, v225
	v_pk_mul_f32 v[70:71], v[70:71], v[70:71]
	v_add_f32_dpp v68, v68, v68 quad_perm:[2,3,0,1] row_mask:0xf bank_mask:0xf bound_ctrl:1
	s_nop 1
	v_add_f32_dpp v68, v68, v68 row_half_mirror row_mask:0xf bank_mask:0xf bound_ctrl:1
	s_nop 1
	v_add_f32_dpp v68, v68, v68 row_mirror row_mask:0xf bank_mask:0xf bound_ctrl:1
	s_nop 1
	v_add_f32_dpp v68, v68, v68 row_bcast:15 row_mask:0xa bank_mask:0xf
	s_nop 1
	v_add_f32_dpp v68, v68, v68 row_bcast:31 row_mask:0xc bank_mask:0xf
	v_mov_b32_e32 v69, v54
	v_readlane_b32 s7, v68, 63
	v_mov_b32_e32 v68, v58
	v_pk_fma_f32 v[68:69], v[68:69], v[68:69], v[70:71]
	v_mov_b32_e32 v70, v57
	v_add_f32_e32 v68, v68, v69
	v_mov_b32_e32 v71, v19
	s_nop 0
	v_add_f32_dpp v68, v68, v68 quad_perm:[1,0,3,2] row_mask:0xf bank_mask:0xf bound_ctrl:1
	v_fma_f32 v97, s7, v235, v225
	v_pk_mul_f32 v[70:71], v[70:71], v[70:71]
	v_add_f32_dpp v68, v68, v68 quad_perm:[2,3,0,1] row_mask:0xf bank_mask:0xf bound_ctrl:1
	s_nop 1
	v_add_f32_dpp v68, v68, v68 row_half_mirror row_mask:0xf bank_mask:0xf bound_ctrl:1
	s_nop 1
	v_add_f32_dpp v68, v68, v68 row_mirror row_mask:0xf bank_mask:0xf bound_ctrl:1
	s_nop 1
	v_add_f32_dpp v68, v68, v68 row_bcast:15 row_mask:0xa bank_mask:0xf
	s_nop 1
	v_add_f32_dpp v68, v68, v68 row_bcast:31 row_mask:0xc bank_mask:0xf
	v_mov_b32_e32 v69, v55
	v_readlane_b32 s7, v68, 63
	v_mov_b32_e32 v68, v59
	v_pk_fma_f32 v[68:69], v[68:69], v[68:69], v[70:71]
	v_fma_f32 v98, s7, v235, v225
	v_add_f32_e32 v68, v68, v69
	s_nop 0
	s_nop 0
	v_add_f32_dpp v68, v68, v68 quad_perm:[1,0,3,2] row_mask:0xf bank_mask:0xf bound_ctrl:1
	s_nop 1
	v_add_f32_dpp v68, v68, v68 quad_perm:[2,3,0,1] row_mask:0xf bank_mask:0xf bound_ctrl:1
	s_nop 1
	v_add_f32_dpp v68, v68, v68 row_half_mirror row_mask:0xf bank_mask:0xf bound_ctrl:1
	s_nop 1
	v_add_f32_dpp v68, v68, v68 row_mirror row_mask:0xf bank_mask:0xf bound_ctrl:1
	s_nop 1
	v_add_f32_dpp v68, v68, v68 row_bcast:15 row_mask:0xa bank_mask:0xf
	s_nop 1
	v_add_f32_dpp v68, v68, v68 row_bcast:31 row_mask:0xc bank_mask:0xf
	s_nop 0
	v_readlane_b32 s7, v68, 63
	v_add_u32_e32 v68, s66, v1
	v_ashrrev_i32_e32 v69, 31, v68
	s_waitcnt lgkmcnt(0)
	v_lshl_add_u64 v[68:69], v[68:69], 2, s[42:43]
	global_load_dword v88, v[68:69], off
	v_or_b32_e32 v68, s84, v66
	v_ashrrev_i32_e32 v69, 31, v68
	v_lshlrev_b64 v[68:69], 2, v[68:69]
	v_lshl_add_u64 v[70:71], s[52:53], 0, v[68:69]
	v_lshl_add_u64 v[68:69], s[54:55], 0, v[68:69]
	global_load_dword v72, v[68:69], off
	global_load_dword v74, v[70:71], off
	global_load_dword v76, v[70:71], off offset:256
	global_load_dword v78, v[68:69], off offset:256
	global_load_dword v80, v[68:69], off offset:512
	global_load_dword v82, v[70:71], off offset:512
	s_nop 0
	global_load_dword v70, v[70:71], off offset:768
	s_nop 0
	global_load_dword v68, v[68:69], off offset:768
	v_lshl_add_u32 v69, v1, 2, s9
	v_fma_f32 v99, s7, v235, v225
	s_add_i32 s7, s5, s11
	s_lshl_b32 s5, s5, 9
	s_add_u32 s34, s78, 0x3420000
	s_mul_hi_i32 s8, s7, 0x5000
	s_mulk_i32 s7, 0x5000
	s_addc_u32 s64, s79, 0
	s_add_u32 s28, s34, s7
	s_addc_u32 s29, s64, s8
	s_movk_i32 s8, 0x110
	v_mad_u32_u24 v67, v66, s8, v67
	s_movk_i32 s7, 0x2000
	s_add_i32 s5, s9, s5
	s_waitcnt vmcnt(8)
	ds_write_b32 v69, v88
	s_waitcnt vmcnt(6)
	v_pk_fma_f32 v[88:89], v[74:75], v[4:5], v[72:73] op_sel_hi:[0,1,0]
	v_pk_mul_f32 v[4:5], v[14:15], v[84:85]
	v_pk_fma_f32 v[16:17], v[74:75], v[16:17], v[72:73] op_sel_hi:[0,1,0]
	s_waitcnt vmcnt(4)
	v_pk_fma_f32 v[14:15], v[76:77], v[4:5], v[78:79] op_sel_hi:[0,1,0]
	v_pk_mul_f32 v[4:5], v[12:13], v[84:85]
	s_waitcnt vmcnt(0)
	v_pk_fma_f32 v[86:87], v[70:71], v[2:3], v[68:69] op_sel_hi:[0,1,0]
	v_pk_fma_f32 v[12:13], v[82:83], v[4:5], v[80:81] op_sel_hi:[0,1,0]
	v_pk_mul_f32 v[4:5], v[10:11], v[84:85]
	v_rsq_f32_e32 v10, v81
	v_rsq_f32_e32 v11, v83
	v_rsq_f32_e32 v84, v90
	v_rsq_f32_e32 v85, v91
	v_pk_fma_f32 v[90:91], v[70:71], v[4:5], v[68:69] op_sel_hi:[0,1,0]
	v_pk_mul_f32 v[2:3], v[36:37], v[10:11]
	v_pk_fma_f32 v[8:9], v[76:77], v[8:9], v[78:79] op_sel_hi:[0,1,0]
	v_pk_mul_f32 v[4:5], v[28:29], v[84:85]
	v_pk_fma_f32 v[2:3], v[74:75], v[2:3], v[72:73] op_sel_hi:[0,1,0]
	v_pk_fma_f32 v[4:5], v[74:75], v[4:5], v[72:73] op_sel_hi:[0,1,0]
	v_cvt_pk_bf16_f32 v5, v4, v5
	v_cvt_pk_bf16_f32 v4, v2, v3
	v_cvt_pk_bf16_f32 v3, v88, v89
	v_cvt_pk_bf16_f32 v2, v16, v17
	ds_write_b128 v67, v[2:5]
	v_pk_mul_f32 v[2:3], v[34:35], v[10:11]
	v_pk_mul_f32 v[4:5], v[26:27], v[84:85]
	v_pk_fma_f32 v[2:3], v[76:77], v[2:3], v[78:79] op_sel_hi:[0,1,0]
	v_pk_fma_f32 v[4:5], v[76:77], v[4:5], v[78:79] op_sel_hi:[0,1,0]
	v_cvt_pk_bf16_f32 v5, v4, v5
	v_cvt_pk_bf16_f32 v4, v2, v3
	v_cvt_pk_bf16_f32 v3, v8, v9
	v_cvt_pk_bf16_f32 v2, v14, v15
	ds_write_b128 v67, v[2:5] offset:17408
	v_pk_mul_f32 v[2:3], v[32:33], v[10:11]
	v_pk_mul_f32 v[4:5], v[24:25], v[84:85]
	v_pk_fma_f32 v[6:7], v[82:83], v[6:7], v[80:81] op_sel_hi:[0,1,0]
	v_pk_fma_f32 v[4:5], v[82:83], v[4:5], v[80:81] op_sel_hi:[0,1,0]
	v_pk_fma_f32 v[2:3], v[82:83], v[2:3], v[80:81] op_sel_hi:[0,1,0]
	v_cvt_pk_bf16_f32 v5, v4, v5
	v_cvt_pk_bf16_f32 v4, v2, v3
	v_cvt_pk_bf16_f32 v3, v6, v7
	v_cvt_pk_bf16_f32 v2, v12, v13
	v_rsq_f32_e32 v6, v92
	v_rsq_f32_e32 v7, v93
	v_rsq_f32_e32 v8, v94
	v_rsq_f32_e32 v9, v95
	ds_write_b128 v67, v[2:5] offset:34816
	v_pk_mul_f32 v[2:3], v[30:31], v[10:11]
	v_pk_mul_f32 v[4:5], v[22:23], v[84:85]
	v_pk_fma_f32 v[2:3], v[70:71], v[2:3], v[68:69] op_sel_hi:[0,1,0]
	v_pk_fma_f32 v[4:5], v[70:71], v[4:5], v[68:69] op_sel_hi:[0,1,0]
	v_cvt_pk_bf16_f32 v5, v4, v5
	v_cvt_pk_bf16_f32 v4, v2, v3
	v_cvt_pk_bf16_f32 v3, v86, v87
	v_cvt_pk_bf16_f32 v2, v90, v91
	ds_write_b128 v67, v[2:5] offset:52224
	v_pk_mul_f32 v[2:3], v[52:53], v[6:7]
	v_pk_mul_f32 v[4:5], v[40:41], v[8:9]
	v_pk_fma_f32 v[12:13], v[74:75], v[2:3], v[72:73] op_sel_hi:[0,1,0]
	v_pk_fma_f32 v[10:11], v[74:75], v[4:5], v[72:73] op_sel_hi:[0,1,0]
	v_pk_mul_f32 v[2:3], v[50:51], v[6:7]
	v_pk_mul_f32 v[4:5], v[44:45], v[8:9]
	v_pk_fma_f32 v[16:17], v[76:77], v[2:3], v[78:79] op_sel_hi:[0,1,0]
	v_pk_fma_f32 v[14:15], v[76:77], v[4:5], v[78:79] op_sel_hi:[0,1,0]
	v_pk_mul_f32 v[2:3], v[48:49], v[6:7]
	v_pk_mul_f32 v[4:5], v[42:43], v[8:9]
	v_pk_fma_f32 v[24:25], v[82:83], v[2:3], v[80:81] op_sel_hi:[0,1,0]
	v_pk_fma_f32 v[22:23], v[82:83], v[4:5], v[80:81] op_sel_hi:[0,1,0]
	v_pk_mul_f32 v[2:3], v[46:47], v[6:7]
	v_pk_mul_f32 v[4:5], v[38:39], v[8:9]
	v_rsq_f32_e32 v6, v96
	v_rsq_f32_e32 v7, v97
	v_rsq_f32_e32 v8, v98
	v_rsq_f32_e32 v9, v99
	v_pk_fma_f32 v[26:27], v[70:71], v[4:5], v[68:69] op_sel_hi:[0,1,0]
	v_pk_fma_f32 v[28:29], v[70:71], v[2:3], v[68:69] op_sel_hi:[0,1,0]
	v_pk_mul_f32 v[2:3], v[64:65], v[6:7]
	v_pk_mul_f32 v[4:5], v[58:59], v[8:9]
	v_pk_fma_f32 v[2:3], v[74:75], v[2:3], v[72:73] op_sel_hi:[0,1,0]
	v_pk_fma_f32 v[4:5], v[74:75], v[4:5], v[72:73] op_sel_hi:[0,1,0]
	v_cvt_pk_bf16_f32 v5, v4, v5
	v_cvt_pk_bf16_f32 v4, v2, v3
	v_cvt_pk_bf16_f32 v3, v10, v11
	v_cvt_pk_bf16_f32 v2, v12, v13
	ds_write_b128 v67, v[2:5] offset:16
	v_pk_mul_f32 v[2:3], v[62:63], v[6:7]
	v_pk_mul_f32 v[4:5], v[56:57], v[8:9]
	v_pk_fma_f32 v[2:3], v[76:77], v[2:3], v[78:79] op_sel_hi:[0,1,0]
	v_pk_fma_f32 v[4:5], v[76:77], v[4:5], v[78:79] op_sel_hi:[0,1,0]
	v_cvt_pk_bf16_f32 v5, v4, v5
	v_cvt_pk_bf16_f32 v4, v2, v3
	v_cvt_pk_bf16_f32 v3, v14, v15
	v_cvt_pk_bf16_f32 v2, v16, v17
	ds_write_b128 v67, v[2:5] offset:17424
	v_pk_mul_f32 v[2:3], v[60:61], v[6:7]
	v_pk_mul_f32 v[4:5], v[54:55], v[8:9]
	v_pk_fma_f32 v[2:3], v[82:83], v[2:3], v[80:81] op_sel_hi:[0,1,0]
	v_pk_fma_f32 v[4:5], v[82:83], v[4:5], v[80:81] op_sel_hi:[0,1,0]
	v_cvt_pk_bf16_f32 v5, v4, v5
	v_cvt_pk_bf16_f32 v4, v2, v3
	v_cvt_pk_bf16_f32 v3, v22, v23
	v_cvt_pk_bf16_f32 v2, v24, v25
	ds_write_b128 v67, v[2:5] offset:34832
	v_pk_mul_f32 v[2:3], v[20:21], v[6:7]
	v_pk_mul_f32 v[4:5], v[18:19], v[8:9]
	v_and_or_b32 v8, v1, 31, s6
	v_pk_fma_f32 v[4:5], v[70:71], v[4:5], v[68:69] op_sel_hi:[0,1,0]
	v_pk_fma_f32 v[2:3], v[70:71], v[2:3], v[68:69] op_sel_hi:[0,1,0]
	v_lshl_add_u64 v[6:7], s[28:29], 0, v[130:131]
	v_bfe_u32 v10, v1, 5, 1
	v_ashrrev_i32_e32 v9, 31, v8
	v_cvt_pk_bf16_f32 v5, v4, v5
	v_cvt_pk_bf16_f32 v4, v2, v3
	v_cvt_pk_bf16_f32 v3, v26, v27
	v_cvt_pk_bf16_f32 v2, v28, v29
	v_add_co_u32_e32 v66, vcc, s90, v6
	v_lshlrev_b32_e32 v1, 2, v10
	v_lshlrev_b64 v[68:69], 1, v[8:9]
	ds_write_b128 v67, v[2:5] offset:52240
	v_addc_co_u32_e32 v67, vcc, 0, v7, vcc
	v_or_b32_e32 v82, s65, v1
	v_lshl_add_u64 v[84:85], s[80:81], 0, v[68:69]
	v_add_co_u32_e32 v86, vcc, s7, v6
	v_mad_u64_u32 v[12:13], s[6:7], v82, s87, v[84:85]
	s_waitcnt lgkmcnt(0)
	s_barrier
	global_load_dwordx4 v[2:5], v130, s[28:29]
	global_load_dwordx4 v[58:61], v130, s[28:29] offset:1024
	global_load_dwordx4 v[22:25], v130, s[28:29] offset:2048
	global_load_dwordx4 v[18:21], v130, s[28:29] offset:3072
	global_load_ushort v9, v[12:13], off
	v_or_b32_e32 v11, 1, v82
	v_mad_u64_u32 v[12:13], s[6:7], v11, s87, v[84:85]
	global_load_ushort v11, v[12:13], off
	v_or_b32_e32 v12, 2, v82
	v_mad_u64_u32 v[12:13], s[6:7], v12, s87, v[84:85]
	global_load_ushort v28, v[12:13], off
	v_or_b32_e32 v12, 3, v82
	v_mad_u64_u32 v[12:13], s[6:7], v12, s87, v[84:85]
	global_load_ushort v29, v[12:13], off
	v_or_b32_e32 v12, 8, v82
	v_or_b32_e32 v14, 9, v82
	v_mad_u64_u32 v[12:13], s[6:7], v12, s87, v[84:85]
	v_mad_u64_u32 v[14:15], s[6:7], v14, s87, v[84:85]
	v_or_b32_e32 v16, 10, v82
	v_or_b32_e32 v26, 11, v82
	v_mad_u64_u32 v[16:17], s[6:7], v16, s87, v[84:85]
	v_mad_u64_u32 v[26:27], s[6:7], v26, s87, v[84:85]
	global_load_ushort v12, v[12:13], off
	s_nop 0
	global_load_ushort v13, v[14:15], off
	s_nop 0
	global_load_ushort v14, v[16:17], off
	global_load_ushort v15, v[26:27], off
	v_addc_co_u32_e32 v87, vcc, 0, v7, vcc
	v_mov_b32_e32 v83, v131
	v_lshl_add_u64 v[88:89], s[76:77], 0, v[68:69]
	v_lshlrev_b64 v[68:69], 11, v[82:83]
	v_lshl_add_u64 v[68:69], v[88:89], 0, v[68:69]
	s_mov_b64 s[28:29], -1
	s_waitcnt vmcnt(7)
	v_lshlrev_b32_e32 v9, 16, v9
	v_fma_f32 v16, |v9|, s92, 1.0
	v_rcp_f32_e32 v16, v16
	v_mul_f32_e32 v26, v9, v9
	v_mul_f32_e32 v26, 0xbf38aa3b, v26
	v_exp_f32_e32 v26, v26
	v_fmamk_f32 v17, v16, 0x3f07dc22, v236
	v_fmaak_f32 v17, v16, v17, 0x3f35f0e3
	v_fmaak_f32 v17, v16, v17, 0xbe11a98e
	v_fmaak_f32 v17, v16, v17, 0x3e027906
	v_mul_f32_e32 v16, v16, v17
	v_mul_f32_e32 v16, v26, v16
	v_mul_f32_e32 v17, v16, v9
	v_fma_f32 v16, -v16, v9, v9
	v_cmp_gt_f32_e32 vcc, 0, v9
	s_waitcnt vmcnt(6)
	v_lshlrev_b32_e32 v9, 16, v11
	v_fma_f32 v11, |v9|, s92, 1.0
	v_rcp_f32_e32 v11, v11
	v_cndmask_b32_e32 v70, v16, v17, vcc
	v_mul_f32_e32 v17, v9, v9
	v_mul_f32_e32 v17, 0xbf38aa3b, v17
	v_fmamk_f32 v16, v11, 0x3f07dc22, v236
	v_fmaak_f32 v16, v11, v16, 0x3f35f0e3
	v_exp_f32_e32 v17, v17
	v_fmaak_f32 v16, v11, v16, 0xbe11a98e
	v_fmaak_f32 v16, v11, v16, 0x3e027906
	v_mul_f32_e32 v11, v11, v16
	v_mul_f32_e32 v11, v17, v11
	v_mul_f32_e32 v16, v11, v9
	v_fma_f32 v11, -v11, v9, v9
	v_cmp_gt_f32_e32 vcc, 0, v9
	s_waitcnt vmcnt(5)
	v_lshlrev_b32_e32 v9, 16, v28
	v_mul_f32_e32 v17, v9, v9
	v_cndmask_b32_e32 v71, v11, v16, vcc
	v_fma_f32 v11, |v9|, s92, 1.0
	v_rcp_f32_e32 v11, v11
	v_mul_f32_e32 v17, 0xbf38aa3b, v17
	v_exp_f32_e32 v17, v17
	v_cmp_gt_f32_e32 vcc, 0, v9
	v_fmamk_f32 v16, v11, 0x3f07dc22, v236
	v_fmaak_f32 v16, v11, v16, 0x3f35f0e3
	v_fmaak_f32 v16, v11, v16, 0xbe11a98e
	v_fmaak_f32 v16, v11, v16, 0x3e027906
	v_mul_f32_e32 v11, v11, v16
	v_mul_f32_e32 v11, v17, v11
	v_mul_f32_e32 v16, v11, v9
	v_fma_f32 v11, -v11, v9, v9
	s_waitcnt vmcnt(4)
	v_lshlrev_b32_e32 v9, 16, v29
	v_cndmask_b32_e32 v72, v11, v16, vcc
	v_fma_f32 v11, |v9|, s92, 1.0
	v_rcp_f32_e32 v11, v11
	v_mul_f32_e32 v17, v9, v9
	v_mul_f32_e32 v17, 0xbf38aa3b, v17
	v_exp_f32_e32 v17, v17
	v_fmamk_f32 v16, v11, 0x3f07dc22, v236
	v_fmaak_f32 v16, v11, v16, 0x3f35f0e3
	v_fmaak_f32 v16, v11, v16, 0xbe11a98e
	v_fmaak_f32 v16, v11, v16, 0x3e027906
	v_mul_f32_e32 v11, v11, v16
	v_mul_f32_e32 v11, v17, v11
	v_mul_f32_e32 v16, v11, v9
	v_fma_f32 v11, -v11, v9, v9
	v_cmp_gt_f32_e32 vcc, 0, v9
	s_waitcnt vmcnt(3)
	v_lshlrev_b32_e32 v9, 16, v12
	v_or_b32_e32 v26, 27, v82
	v_cndmask_b32_e32 v73, v11, v16, vcc
	v_fma_f32 v11, |v9|, s92, 1.0
	v_rcp_f32_e32 v11, v11
	v_mul_f32_e32 v16, v9, v9
	v_mul_f32_e32 v16, 0xbf38aa3b, v16
	v_exp_f32_e32 v16, v16
	v_fmamk_f32 v12, v11, 0x3f07dc22, v236
	v_fmaak_f32 v12, v11, v12, 0x3f35f0e3
	v_fmaak_f32 v12, v11, v12, 0xbe11a98e
	v_fmaak_f32 v12, v11, v12, 0x3e027906
	v_mul_f32_e32 v11, v11, v12
	v_mul_f32_e32 v11, v16, v11
	v_mul_f32_e32 v12, v11, v9
	v_fma_f32 v11, -v11, v9, v9
	v_cmp_gt_f32_e32 vcc, 0, v9
	s_waitcnt vmcnt(2)
	v_lshlrev_b32_e32 v9, 16, v13
	v_mul_f32_e32 v13, v9, v9
	v_cndmask_b32_e32 v74, v11, v12, vcc
	v_fma_f32 v11, |v9|, s92, 1.0
	v_rcp_f32_e32 v11, v11
	v_mul_f32_e32 v13, 0xbf38aa3b, v13
	v_exp_f32_e32 v13, v13
	v_cmp_gt_f32_e32 vcc, 0, v9
	v_fmamk_f32 v12, v11, 0x3f07dc22, v236
	v_fmaak_f32 v12, v11, v12, 0x3f35f0e3
	v_fmaak_f32 v12, v11, v12, 0xbe11a98e
	v_fmaak_f32 v12, v11, v12, 0x3e027906
	v_mul_f32_e32 v11, v11, v12
	v_mul_f32_e32 v11, v13, v11
	v_mul_f32_e32 v12, v11, v9
	v_fma_f32 v11, -v11, v9, v9
	s_waitcnt vmcnt(1)
	v_lshlrev_b32_e32 v9, 16, v14
	v_cndmask_b32_e32 v75, v11, v12, vcc
	v_fma_f32 v11, |v9|, s92, 1.0
	v_rcp_f32_e32 v11, v11
	v_mul_f32_e32 v13, v9, v9
	v_mul_f32_e32 v13, 0xbf38aa3b, v13
	v_exp_f32_e32 v13, v13
	v_fmamk_f32 v12, v11, 0x3f07dc22, v236
	v_fmaak_f32 v12, v11, v12, 0x3f35f0e3
	v_fmaak_f32 v12, v11, v12, 0xbe11a98e
	v_fmaak_f32 v12, v11, v12, 0x3e027906
	v_mul_f32_e32 v11, v11, v12
	v_mul_f32_e32 v11, v13, v11
	v_mul_f32_e32 v12, v11, v9
	v_fma_f32 v11, -v11, v9, v9
	v_cmp_gt_f32_e32 vcc, 0, v9
	s_waitcnt vmcnt(0)
	v_lshlrev_b32_e32 v9, 16, v15
	v_mul_f32_e32 v13, v9, v9
	v_cndmask_b32_e32 v76, v11, v12, vcc
	v_fma_f32 v11, |v9|, s92, 1.0
	v_rcp_f32_e32 v11, v11
	v_mul_f32_e32 v13, 0xbf38aa3b, v13
	v_exp_f32_e32 v13, v13
	v_cmp_gt_f32_e32 vcc, 0, v9
	v_fmamk_f32 v12, v11, 0x3f07dc22, v236
	v_fmaak_f32 v12, v11, v12, 0x3f35f0e3
	v_fmaak_f32 v12, v11, v12, 0xbe11a98e
	v_fmaak_f32 v12, v11, v12, 0x3e027906
	v_mul_f32_e32 v11, v11, v12
	v_mul_f32_e32 v11, v13, v11
	v_mul_f32_e32 v12, v11, v9
	v_fma_f32 v11, -v11, v9, v9
	v_or_b32_e32 v9, 16, v82
	v_cndmask_b32_e32 v77, v11, v12, vcc
	v_mad_u64_u32 v[12:13], s[6:7], v9, s87, v[84:85]
	global_load_ushort v9, v[12:13], off
	v_or_b32_e32 v11, 17, v82
	v_mad_u64_u32 v[12:13], s[6:7], v11, s87, v[84:85]
	global_load_ushort v11, v[12:13], off
	v_or_b32_e32 v12, 18, v82
	v_mad_u64_u32 v[12:13], s[6:7], v12, s87, v[84:85]
	global_load_ushort v28, v[12:13], off
	v_or_b32_e32 v12, 19, v82
	v_mad_u64_u32 v[12:13], s[6:7], v12, s87, v[84:85]
	global_load_ushort v29, v[12:13], off
	v_or_b32_e32 v12, 24, v82
	v_or_b32_e32 v14, 25, v82
	v_mad_u64_u32 v[12:13], s[6:7], v12, s87, v[84:85]
	v_mad_u64_u32 v[14:15], s[6:7], v14, s87, v[84:85]
	v_or_b32_e32 v16, 26, v82
	v_mad_u64_u32 v[16:17], s[6:7], v16, s87, v[84:85]
	v_mad_u64_u32 v[26:27], s[6:7], v26, s87, v[84:85]
	global_load_ushort v12, v[12:13], off
	s_nop 0
	global_load_ushort v13, v[14:15], off
	s_nop 0
	global_load_ushort v14, v[16:17], off
	global_load_ushort v15, v[26:27], off
	s_waitcnt vmcnt(7)
	v_lshlrev_b32_e32 v9, 16, v9
	v_fma_f32 v16, |v9|, s92, 1.0
	v_rcp_f32_e32 v16, v16
	v_mul_f32_e32 v26, v9, v9
	v_mul_f32_e32 v26, 0xbf38aa3b, v26
	v_exp_f32_e32 v26, v26
	v_fmamk_f32 v17, v16, 0x3f07dc22, v236
	v_fmaak_f32 v17, v16, v17, 0x3f35f0e3
	v_fmaak_f32 v17, v16, v17, 0xbe11a98e
	v_fmaak_f32 v17, v16, v17, 0x3e027906
	v_mul_f32_e32 v16, v16, v17
	v_mul_f32_e32 v16, v26, v16
	v_mul_f32_e32 v17, v16, v9
	v_fma_f32 v16, -v16, v9, v9
	v_cmp_gt_f32_e32 vcc, 0, v9
	s_waitcnt vmcnt(6)
	v_lshlrev_b32_e32 v9, 16, v11
	v_fma_f32 v11, |v9|, s92, 1.0
	v_rcp_f32_e32 v11, v11
	v_cndmask_b32_e32 v95, v16, v17, vcc
	v_mul_f32_e32 v17, v9, v9
	v_mul_f32_e32 v17, 0xbf38aa3b, v17
	v_fmamk_f32 v16, v11, 0x3f07dc22, v236
	v_fmaak_f32 v16, v11, v16, 0x3f35f0e3
	v_exp_f32_e32 v17, v17
	v_fmaak_f32 v16, v11, v16, 0xbe11a98e
	v_fmaak_f32 v16, v11, v16, 0x3e027906
	v_mul_f32_e32 v11, v11, v16
	v_mul_f32_e32 v11, v17, v11
	v_mul_f32_e32 v16, v11, v9
	v_fma_f32 v11, -v11, v9, v9
	v_cmp_gt_f32_e32 vcc, 0, v9
	s_waitcnt vmcnt(5)
	v_lshlrev_b32_e32 v9, 16, v28
	v_mul_f32_e32 v17, v9, v9
	v_cndmask_b32_e32 v96, v11, v16, vcc
	v_fma_f32 v11, |v9|, s92, 1.0
	v_rcp_f32_e32 v11, v11
	v_mul_f32_e32 v17, 0xbf38aa3b, v17
	v_exp_f32_e32 v17, v17
	v_cmp_gt_f32_e32 vcc, 0, v9
	v_fmamk_f32 v16, v11, 0x3f07dc22, v236
	v_fmaak_f32 v16, v11, v16, 0x3f35f0e3
	v_fmaak_f32 v16, v11, v16, 0xbe11a98e
	v_fmaak_f32 v16, v11, v16, 0x3e027906
	v_mul_f32_e32 v11, v11, v16
	v_mul_f32_e32 v11, v17, v11
	v_mul_f32_e32 v16, v11, v9
	v_fma_f32 v11, -v11, v9, v9
	s_waitcnt vmcnt(4)
	v_lshlrev_b32_e32 v9, 16, v29
	v_cndmask_b32_e32 v98, v11, v16, vcc
	v_fma_f32 v11, |v9|, s92, 1.0
	v_rcp_f32_e32 v11, v11
	v_mul_f32_e32 v17, v9, v9
	v_mul_f32_e32 v17, 0xbf38aa3b, v17
	v_exp_f32_e32 v17, v17
	v_fmamk_f32 v16, v11, 0x3f07dc22, v236
	v_fmaak_f32 v16, v11, v16, 0x3f35f0e3
	v_fmaak_f32 v16, v11, v16, 0xbe11a98e
	v_fmaak_f32 v16, v11, v16, 0x3e027906
	v_mul_f32_e32 v11, v11, v16
	v_mul_f32_e32 v11, v17, v11
	v_mul_f32_e32 v16, v11, v9
	v_fma_f32 v11, -v11, v9, v9
	v_cmp_gt_f32_e32 vcc, 0, v9
	s_waitcnt vmcnt(3)
	v_lshlrev_b32_e32 v9, 16, v12
	v_or_b32_e32 v26, 43, v82
	v_cndmask_b32_e32 v100, v11, v16, vcc
	v_fma_f32 v11, |v9|, s92, 1.0
	v_rcp_f32_e32 v11, v11
	v_mul_f32_e32 v16, v9, v9
	v_mul_f32_e32 v16, 0xbf38aa3b, v16
	v_exp_f32_e32 v16, v16
	v_fmamk_f32 v12, v11, 0x3f07dc22, v236
	v_fmaak_f32 v12, v11, v12, 0x3f35f0e3
	v_fmaak_f32 v12, v11, v12, 0xbe11a98e
	v_fmaak_f32 v12, v11, v12, 0x3e027906
	v_mul_f32_e32 v11, v11, v12
	v_mul_f32_e32 v11, v16, v11
	v_mul_f32_e32 v12, v11, v9
	v_fma_f32 v11, -v11, v9, v9
	v_cmp_gt_f32_e32 vcc, 0, v9
	s_waitcnt vmcnt(2)
	v_lshlrev_b32_e32 v9, 16, v13
	v_mul_f32_e32 v13, v9, v9
	v_cndmask_b32_e32 v102, v11, v12, vcc
	v_fma_f32 v11, |v9|, s92, 1.0
	v_rcp_f32_e32 v11, v11
	v_mul_f32_e32 v13, 0xbf38aa3b, v13
	v_exp_f32_e32 v13, v13
	v_cmp_gt_f32_e32 vcc, 0, v9
	v_fmamk_f32 v12, v11, 0x3f07dc22, v236
	v_fmaak_f32 v12, v11, v12, 0x3f35f0e3
	v_fmaak_f32 v12, v11, v12, 0xbe11a98e
	v_fmaak_f32 v12, v11, v12, 0x3e027906
	v_mul_f32_e32 v11, v11, v12
	v_mul_f32_e32 v11, v13, v11
	v_mul_f32_e32 v12, v11, v9
	v_fma_f32 v11, -v11, v9, v9
	s_waitcnt vmcnt(1)
	v_lshlrev_b32_e32 v9, 16, v14
	v_cndmask_b32_e32 v104, v11, v12, vcc
	v_fma_f32 v11, |v9|, s92, 1.0
	v_rcp_f32_e32 v11, v11
	v_mul_f32_e32 v13, v9, v9
	v_mul_f32_e32 v13, 0xbf38aa3b, v13
	v_exp_f32_e32 v13, v13
	v_fmamk_f32 v12, v11, 0x3f07dc22, v236
	v_fmaak_f32 v12, v11, v12, 0x3f35f0e3
	v_fmaak_f32 v12, v11, v12, 0xbe11a98e
	v_fmaak_f32 v12, v11, v12, 0x3e027906
	v_mul_f32_e32 v11, v11, v12
	v_mul_f32_e32 v11, v13, v11
	v_mul_f32_e32 v12, v11, v9
	v_fma_f32 v11, -v11, v9, v9
	v_cmp_gt_f32_e32 vcc, 0, v9
	s_waitcnt vmcnt(0)
	v_lshlrev_b32_e32 v9, 16, v15
	v_mul_f32_e32 v13, v9, v9
	v_cndmask_b32_e32 v106, v11, v12, vcc
	v_fma_f32 v11, |v9|, s92, 1.0
	v_rcp_f32_e32 v11, v11
	v_mul_f32_e32 v13, 0xbf38aa3b, v13
	v_exp_f32_e32 v13, v13
	v_cmp_gt_f32_e32 vcc, 0, v9
	v_fmamk_f32 v12, v11, 0x3f07dc22, v236
	v_fmaak_f32 v12, v11, v12, 0x3f35f0e3
	v_fmaak_f32 v12, v11, v12, 0xbe11a98e
	v_fmaak_f32 v12, v11, v12, 0x3e027906
	v_mul_f32_e32 v11, v11, v12
	v_mul_f32_e32 v11, v13, v11
	v_mul_f32_e32 v12, v11, v9
	v_fma_f32 v11, -v11, v9, v9
	v_or_b32_e32 v9, 32, v82
	v_cndmask_b32_e32 v110, v11, v12, vcc
	v_mad_u64_u32 v[12:13], s[6:7], v9, s87, v[84:85]
	global_load_ushort v9, v[12:13], off
	v_or_b32_e32 v11, 33, v82
	v_mad_u64_u32 v[12:13], s[6:7], v11, s87, v[84:85]
	global_load_ushort v11, v[12:13], off
	v_or_b32_e32 v12, 34, v82
	v_mad_u64_u32 v[12:13], s[6:7], v12, s87, v[84:85]
	global_load_ushort v28, v[12:13], off
	v_or_b32_e32 v12, 35, v82
	v_mad_u64_u32 v[12:13], s[6:7], v12, s87, v[84:85]
	global_load_ushort v29, v[12:13], off
	v_or_b32_e32 v12, 40, v82
	v_or_b32_e32 v14, 41, v82
	v_mad_u64_u32 v[12:13], s[6:7], v12, s87, v[84:85]
	v_mad_u64_u32 v[14:15], s[6:7], v14, s87, v[84:85]
	v_or_b32_e32 v16, 42, v82
	v_mad_u64_u32 v[16:17], s[6:7], v16, s87, v[84:85]
	v_mad_u64_u32 v[26:27], s[6:7], v26, s87, v[84:85]
	global_load_ushort v12, v[12:13], off
	s_nop 0
	global_load_ushort v13, v[14:15], off
	s_nop 0
	global_load_ushort v14, v[16:17], off
	global_load_ushort v15, v[26:27], off
	s_waitcnt vmcnt(7)
	v_lshlrev_b32_e32 v9, 16, v9
	v_fma_f32 v16, |v9|, s92, 1.0
	v_rcp_f32_e32 v16, v16
	v_mul_f32_e32 v26, v9, v9
	v_mul_f32_e32 v26, 0xbf38aa3b, v26
	v_exp_f32_e32 v26, v26
	v_fmamk_f32 v17, v16, 0x3f07dc22, v236
	v_fmaak_f32 v17, v16, v17, 0x3f35f0e3
	v_fmaak_f32 v17, v16, v17, 0xbe11a98e
	v_fmaak_f32 v17, v16, v17, 0x3e027906
	v_mul_f32_e32 v16, v16, v17
	v_mul_f32_e32 v16, v26, v16
	v_mul_f32_e32 v17, v16, v9
	v_fma_f32 v16, -v16, v9, v9
	v_cmp_gt_f32_e32 vcc, 0, v9
	s_waitcnt vmcnt(6)
	v_lshlrev_b32_e32 v9, 16, v11
	v_fma_f32 v11, |v9|, s92, 1.0
	v_rcp_f32_e32 v11, v11
	v_cndmask_b32_e32 v97, v16, v17, vcc
	v_mul_f32_e32 v17, v9, v9
	v_mul_f32_e32 v17, 0xbf38aa3b, v17
	v_fmamk_f32 v16, v11, 0x3f07dc22, v236
	v_fmaak_f32 v16, v11, v16, 0x3f35f0e3
	v_exp_f32_e32 v17, v17
	v_fmaak_f32 v16, v11, v16, 0xbe11a98e
	v_fmaak_f32 v16, v11, v16, 0x3e027906
	v_mul_f32_e32 v11, v11, v16
	v_mul_f32_e32 v11, v17, v11
	v_mul_f32_e32 v16, v11, v9
	v_fma_f32 v11, -v11, v9, v9
	v_cmp_gt_f32_e32 vcc, 0, v9
	s_waitcnt vmcnt(5)
	v_lshlrev_b32_e32 v9, 16, v28
	v_mul_f32_e32 v17, v9, v9
	v_cndmask_b32_e32 v99, v11, v16, vcc
	v_fma_f32 v11, |v9|, s92, 1.0
	v_rcp_f32_e32 v11, v11
	v_mul_f32_e32 v17, 0xbf38aa3b, v17
	v_exp_f32_e32 v17, v17
	v_cmp_gt_f32_e32 vcc, 0, v9
	v_fmamk_f32 v16, v11, 0x3f07dc22, v236
	v_fmaak_f32 v16, v11, v16, 0x3f35f0e3
	v_fmaak_f32 v16, v11, v16, 0xbe11a98e
	v_fmaak_f32 v16, v11, v16, 0x3e027906
	v_mul_f32_e32 v11, v11, v16
	v_mul_f32_e32 v11, v17, v11
	v_mul_f32_e32 v16, v11, v9
	v_fma_f32 v11, -v11, v9, v9
	s_waitcnt vmcnt(4)
	v_lshlrev_b32_e32 v9, 16, v29
	v_cndmask_b32_e32 v101, v11, v16, vcc
	v_fma_f32 v11, |v9|, s92, 1.0
	v_rcp_f32_e32 v11, v11
	v_mul_f32_e32 v17, v9, v9
	v_mul_f32_e32 v17, 0xbf38aa3b, v17
	v_exp_f32_e32 v17, v17
	v_fmamk_f32 v16, v11, 0x3f07dc22, v236
	v_fmaak_f32 v16, v11, v16, 0x3f35f0e3
	v_fmaak_f32 v16, v11, v16, 0xbe11a98e
	v_fmaak_f32 v16, v11, v16, 0x3e027906
	v_mul_f32_e32 v11, v11, v16
	v_mul_f32_e32 v11, v17, v11
	v_mul_f32_e32 v16, v11, v9
	v_fma_f32 v11, -v11, v9, v9
	v_cmp_gt_f32_e32 vcc, 0, v9
	s_waitcnt vmcnt(3)
	v_lshlrev_b32_e32 v9, 16, v12
	v_or_b32_e32 v26, 59, v82
	v_cndmask_b32_e32 v103, v11, v16, vcc
	v_fma_f32 v11, |v9|, s92, 1.0
	v_rcp_f32_e32 v11, v11
	v_mul_f32_e32 v16, v9, v9
	v_mul_f32_e32 v16, 0xbf38aa3b, v16
	v_exp_f32_e32 v16, v16
	v_fmamk_f32 v12, v11, 0x3f07dc22, v236
	v_fmaak_f32 v12, v11, v12, 0x3f35f0e3
	v_fmaak_f32 v12, v11, v12, 0xbe11a98e
	v_fmaak_f32 v12, v11, v12, 0x3e027906
	v_mul_f32_e32 v11, v11, v12
	v_mul_f32_e32 v11, v16, v11
	v_mul_f32_e32 v12, v11, v9
	v_fma_f32 v11, -v11, v9, v9
	v_cmp_gt_f32_e32 vcc, 0, v9
	s_waitcnt vmcnt(2)
	v_lshlrev_b32_e32 v9, 16, v13
	v_mul_f32_e32 v13, v9, v9
	v_cndmask_b32_e32 v105, v11, v12, vcc
	v_fma_f32 v11, |v9|, s92, 1.0
	v_rcp_f32_e32 v11, v11
	v_mul_f32_e32 v13, 0xbf38aa3b, v13
	v_exp_f32_e32 v13, v13
	v_cmp_gt_f32_e32 vcc, 0, v9
	v_fmamk_f32 v12, v11, 0x3f07dc22, v236
	v_fmaak_f32 v12, v11, v12, 0x3f35f0e3
	v_fmaak_f32 v12, v11, v12, 0xbe11a98e
	v_fmaak_f32 v12, v11, v12, 0x3e027906
	v_mul_f32_e32 v11, v11, v12
	v_mul_f32_e32 v11, v13, v11
	v_mul_f32_e32 v12, v11, v9
	v_fma_f32 v11, -v11, v9, v9
	s_waitcnt vmcnt(1)
	v_lshlrev_b32_e32 v9, 16, v14
	v_cndmask_b32_e32 v107, v11, v12, vcc
	v_fma_f32 v11, |v9|, s92, 1.0
	v_rcp_f32_e32 v11, v11
	v_mul_f32_e32 v13, v9, v9
	v_mul_f32_e32 v13, 0xbf38aa3b, v13
	v_exp_f32_e32 v13, v13
	v_fmamk_f32 v12, v11, 0x3f07dc22, v236
	v_fmaak_f32 v12, v11, v12, 0x3f35f0e3
	v_fmaak_f32 v12, v11, v12, 0xbe11a98e
	v_fmaak_f32 v12, v11, v12, 0x3e027906
	v_mul_f32_e32 v11, v11, v12
	v_mul_f32_e32 v11, v13, v11
	v_mul_f32_e32 v12, v11, v9
	v_fma_f32 v11, -v11, v9, v9
	v_cmp_gt_f32_e32 vcc, 0, v9
	s_waitcnt vmcnt(0)
	v_lshlrev_b32_e32 v9, 16, v15
	v_mul_f32_e32 v13, v9, v9
	v_cndmask_b32_e32 v108, v11, v12, vcc
	v_fma_f32 v11, |v9|, s92, 1.0
	v_rcp_f32_e32 v11, v11
	v_mul_f32_e32 v13, 0xbf38aa3b, v13
	v_exp_f32_e32 v13, v13
	v_cmp_gt_f32_e32 vcc, 0, v9
	v_fmamk_f32 v12, v11, 0x3f07dc22, v236
	v_fmaak_f32 v12, v11, v12, 0x3f35f0e3
	v_fmaak_f32 v12, v11, v12, 0xbe11a98e
	v_fmaak_f32 v12, v11, v12, 0x3e027906
	v_mul_f32_e32 v11, v11, v12
	v_mul_f32_e32 v11, v13, v11
	v_mul_f32_e32 v12, v11, v9
	v_fma_f32 v11, -v11, v9, v9
	v_or_b32_e32 v9, 48, v82
	v_cndmask_b32_e32 v109, v11, v12, vcc
	v_mad_u64_u32 v[12:13], s[6:7], v9, s87, v[84:85]
	global_load_ushort v9, v[12:13], off
	v_or_b32_e32 v11, 49, v82
	v_mad_u64_u32 v[12:13], s[6:7], v11, s87, v[84:85]
	global_load_ushort v11, v[12:13], off
	v_or_b32_e32 v12, 50, v82
	v_mad_u64_u32 v[12:13], s[6:7], v12, s87, v[84:85]
	global_load_ushort v28, v[12:13], off
	v_or_b32_e32 v12, 51, v82
	v_mad_u64_u32 v[12:13], s[6:7], v12, s87, v[84:85]
	global_load_ushort v29, v[12:13], off
	v_or_b32_e32 v12, 56, v82
	v_or_b32_e32 v14, 57, v82
	v_mad_u64_u32 v[12:13], s[6:7], v12, s87, v[84:85]
	v_mad_u64_u32 v[14:15], s[6:7], v14, s87, v[84:85]
	v_or_b32_e32 v16, 58, v82
	v_mad_u64_u32 v[16:17], s[6:7], v16, s87, v[84:85]
	v_mad_u64_u32 v[26:27], s[6:7], v26, s87, v[84:85]
	global_load_ushort v12, v[12:13], off
	s_nop 0
	global_load_ushort v13, v[14:15], off
	s_nop 0
	global_load_ushort v14, v[16:17], off
	global_load_ushort v15, v[26:27], off
	s_movk_i32 s6, 0x3000
	s_waitcnt vmcnt(7)
	v_lshlrev_b32_e32 v9, 16, v9
	v_fma_f32 v16, |v9|, s92, 1.0
	v_rcp_f32_e32 v16, v16
	v_mul_f32_e32 v26, v9, v9
	v_mul_f32_e32 v26, 0xbf38aa3b, v26
	v_exp_f32_e32 v26, v26
	v_fmamk_f32 v17, v16, 0x3f07dc22, v236
	v_fmaak_f32 v17, v16, v17, 0x3f35f0e3
	v_fmaak_f32 v17, v16, v17, 0xbe11a98e
	v_fmaak_f32 v17, v16, v17, 0x3e027906
	v_mul_f32_e32 v16, v16, v17
	v_mul_f32_e32 v16, v26, v16
	v_mul_f32_e32 v17, v16, v9
	v_fma_f32 v16, -v16, v9, v9
	v_cmp_gt_f32_e32 vcc, 0, v9
	s_waitcnt vmcnt(6)
	v_lshlrev_b32_e32 v9, 16, v11
	v_fma_f32 v11, |v9|, s92, 1.0
	v_rcp_f32_e32 v11, v11
	v_cndmask_b32_e32 v113, v16, v17, vcc
	v_mul_f32_e32 v17, v9, v9
	v_mul_f32_e32 v17, 0xbf38aa3b, v17
	v_fmamk_f32 v16, v11, 0x3f07dc22, v236
	v_fmaak_f32 v16, v11, v16, 0x3f35f0e3
	v_exp_f32_e32 v17, v17
	v_fmaak_f32 v16, v11, v16, 0xbe11a98e
	v_fmaak_f32 v16, v11, v16, 0x3e027906
	v_mul_f32_e32 v11, v11, v16
	v_mul_f32_e32 v11, v17, v11
	v_mul_f32_e32 v16, v11, v9
	v_fma_f32 v11, -v11, v9, v9
	v_cmp_gt_f32_e32 vcc, 0, v9
	s_waitcnt vmcnt(5)
	v_lshlrev_b32_e32 v9, 16, v28
	v_mul_f32_e32 v17, v9, v9
	v_cndmask_b32_e32 v115, v11, v16, vcc
	v_fma_f32 v11, |v9|, s92, 1.0
	v_rcp_f32_e32 v11, v11
	v_mul_f32_e32 v17, 0xbf38aa3b, v17
	v_exp_f32_e32 v17, v17
	v_cmp_gt_f32_e32 vcc, 0, v9
	v_fmamk_f32 v16, v11, 0x3f07dc22, v236
	v_fmaak_f32 v16, v11, v16, 0x3f35f0e3
	v_fmaak_f32 v16, v11, v16, 0xbe11a98e
	v_fmaak_f32 v16, v11, v16, 0x3e027906
	v_mul_f32_e32 v11, v11, v16
	v_mul_f32_e32 v11, v17, v11
	v_mul_f32_e32 v16, v11, v9
	v_fma_f32 v11, -v11, v9, v9
	s_waitcnt vmcnt(4)
	v_lshlrev_b32_e32 v9, 16, v29
	v_cndmask_b32_e32 v117, v11, v16, vcc
	v_fma_f32 v11, |v9|, s92, 1.0
	v_rcp_f32_e32 v11, v11
	v_mul_f32_e32 v17, v9, v9
	v_mul_f32_e32 v17, 0xbf38aa3b, v17
	v_exp_f32_e32 v17, v17
	v_fmamk_f32 v16, v11, 0x3f07dc22, v236
	v_fmaak_f32 v16, v11, v16, 0x3f35f0e3
	v_fmaak_f32 v16, v11, v16, 0xbe11a98e
	v_fmaak_f32 v16, v11, v16, 0x3e027906
	v_mul_f32_e32 v11, v11, v16
	v_mul_f32_e32 v11, v17, v11
	v_mul_f32_e32 v16, v11, v9
	v_fma_f32 v11, -v11, v9, v9
	v_cmp_gt_f32_e32 vcc, 0, v9
	s_waitcnt vmcnt(3)
	v_lshlrev_b32_e32 v9, 16, v12
	v_cndmask_b32_e32 v119, v11, v16, vcc
	v_fma_f32 v11, |v9|, s92, 1.0
	v_rcp_f32_e32 v11, v11
	v_mul_f32_e32 v16, v9, v9
	v_mul_f32_e32 v16, 0xbf38aa3b, v16
	v_exp_f32_e32 v16, v16
	v_fmamk_f32 v12, v11, 0x3f07dc22, v236
	v_fmaak_f32 v12, v11, v12, 0x3f35f0e3
	v_fmaak_f32 v12, v11, v12, 0xbe11a98e
	v_fmaak_f32 v12, v11, v12, 0x3e027906
	v_mul_f32_e32 v11, v11, v12
	v_mul_f32_e32 v11, v16, v11
	v_mul_f32_e32 v12, v11, v9
	v_fma_f32 v11, -v11, v9, v9
	v_cmp_gt_f32_e32 vcc, 0, v9
	s_waitcnt vmcnt(2)
	v_lshlrev_b32_e32 v9, 16, v13
	v_mul_f32_e32 v13, v9, v9
	v_cndmask_b32_e32 v120, v11, v12, vcc
	v_fma_f32 v11, |v9|, s92, 1.0
	v_rcp_f32_e32 v11, v11
	v_mul_f32_e32 v13, 0xbf38aa3b, v13
	v_exp_f32_e32 v13, v13
	v_cmp_gt_f32_e32 vcc, 0, v9
	v_fmamk_f32 v12, v11, 0x3f07dc22, v236
	v_fmaak_f32 v12, v11, v12, 0x3f35f0e3
	v_fmaak_f32 v12, v11, v12, 0xbe11a98e
	v_fmaak_f32 v12, v11, v12, 0x3e027906
	v_mul_f32_e32 v11, v11, v12
	v_mul_f32_e32 v11, v13, v11
	v_mul_f32_e32 v12, v11, v9
	v_fma_f32 v11, -v11, v9, v9
	s_waitcnt vmcnt(1)
	v_lshlrev_b32_e32 v9, 16, v14
	v_cndmask_b32_e32 v121, v11, v12, vcc
	v_fma_f32 v11, |v9|, s92, 1.0
	v_rcp_f32_e32 v11, v11
	v_mul_f32_e32 v13, v9, v9
	v_mul_f32_e32 v13, 0xbf38aa3b, v13
	v_exp_f32_e32 v13, v13
	v_fmamk_f32 v12, v11, 0x3f07dc22, v236
	v_fmaak_f32 v12, v11, v12, 0x3f35f0e3
	v_fmaak_f32 v12, v11, v12, 0xbe11a98e
	v_fmaak_f32 v12, v11, v12, 0x3e027906
	v_mul_f32_e32 v11, v11, v12
	v_mul_f32_e32 v11, v13, v11
	v_mul_f32_e32 v12, v11, v9
	v_fma_f32 v11, -v11, v9, v9
	v_cmp_gt_f32_e32 vcc, 0, v9
	s_waitcnt vmcnt(0)
	v_lshlrev_b32_e32 v9, 16, v15
	v_mul_f32_e32 v13, v9, v9
	v_cndmask_b32_e32 v122, v11, v12, vcc
	v_fma_f32 v11, |v9|, s92, 1.0
	v_rcp_f32_e32 v11, v11
	v_mul_f32_e32 v13, 0xbf38aa3b, v13
	v_exp_f32_e32 v13, v13
	v_cmp_gt_f32_e32 vcc, 0, v9
	v_fmamk_f32 v12, v11, 0x3f07dc22, v236
	v_fmaak_f32 v12, v11, v12, 0x3f35f0e3
	v_fmaak_f32 v12, v11, v12, 0xbe11a98e
	v_fmaak_f32 v12, v11, v12, 0x3e027906
	v_mul_f32_e32 v11, v11, v12
	v_mul_f32_e32 v11, v13, v11
	v_mul_f32_e32 v12, v11, v9
	v_fma_f32 v11, -v11, v9, v9
	v_cndmask_b32_e32 v123, v11, v12, vcc
	v_add_co_u32_e32 v90, vcc, s6, v6
	s_nop 1
	v_addc_co_u32_e32 v91, vcc, 0, v7, vcc
	v_add_co_u32_e32 v92, vcc, s97, v6
	v_lshlrev_b32_e32 v6, 4, v10
	s_nop 0
	v_addc_co_u32_e32 v93, vcc, 0, v7, vcc
	v_mul_lo_u32 v7, v8, s8
	v_add3_u32 v26, 0, v7, v6
	ds_read_b128 v[54:57], v26
	ds_read_b128 v[50:53], v26 offset:32
	ds_read_b128 v[46:49], v26 offset:64
	ds_read_b128 v[42:45], v26 offset:96
	v_add_u32_e32 v94, s5, v6
	s_waitcnt lgkmcnt(3)
	v_mfma_f32_32x32x16_bf16 v[2:17], v[2:5], v[54:57], 0
	global_load_dwordx4 v[78:81], v[66:67], off offset:1024
	ds_read_b128 v[38:41], v26 offset:128
	ds_read_b128 v[34:37], v26 offset:160
	ds_read_b128 v[30:33], v26 offset:192
	ds_read_b128 v[26:29], v26 offset:224
	global_load_dwordx4 v[62:65], v[86:87], off offset:-4096
	ds_read_b128 v[124:127], v94
	v_readlane_b32 s5, v251, 32
	s_waitcnt lgkmcnt(7)
	v_mfma_f32_32x32x16_bf16 v[2:17], v[58:61], v[50:53], v[2:17]
	ds_read_b128 v[58:61], v94 offset:32
	v_or_b32_e32 v130, s5, v1
	v_readlane_b32 s5, v251, 33
	s_waitcnt lgkmcnt(1)
	s_nop 7
	v_add_f32_e32 v2, v2, v124
	v_mul_f32_e32 v2, v70, v2
	v_cvt_pk_bf16_f32 v2, v2, s0
	global_store_short v[68:69], v2, off
	v_add_f32_e32 v2, v3, v125
	v_mul_f32_e32 v2, v71, v2
	v_cvt_pk_bf16_f32 v68, v2, s0
	v_lshlrev_b64 v[2:3], 11, v[130:131]
	v_lshl_add_u64 v[2:3], v[88:89], 0, v[2:3]
	global_store_short v[2:3], v68, off
	v_add_f32_e32 v2, v4, v126
	v_mul_f32_e32 v2, v72, v2
	v_or_b32_e32 v130, s5, v1
	v_cvt_pk_bf16_f32 v4, v2, s0
	v_lshlrev_b64 v[2:3], 11, v[130:131]
	v_lshl_add_u64 v[2:3], v[88:89], 0, v[2:3]
	global_store_short v[2:3], v4, off
	v_add_f32_e32 v2, v5, v127
	v_readlane_b32 s5, v251, 34
	v_mul_f32_e32 v2, v73, v2
	v_cvt_pk_bf16_f32 v4, v2, s0
	v_or_b32_e32 v130, s5, v1
	v_lshlrev_b64 v[2:3], 11, v[130:131]
	v_lshl_add_u64 v[2:3], v[88:89], 0, v[2:3]
	global_store_short v[2:3], v4, off
	s_waitcnt lgkmcnt(0)
	v_add_f32_e32 v2, v6, v58
	v_readlane_b32 s5, v251, 35
	v_mul_f32_e32 v2, v74, v2
	v_cvt_pk_bf16_f32 v4, v2, s0
	v_or_b32_e32 v130, s5, v1
	v_lshlrev_b64 v[2:3], 11, v[130:131]
	v_lshl_add_u64 v[2:3], v[88:89], 0, v[2:3]
	global_store_short v[2:3], v4, off
	v_add_f32_e32 v2, v7, v59
	v_readlane_b32 s5, v251, 36
	v_mul_f32_e32 v2, v75, v2
	v_cvt_pk_bf16_f32 v4, v2, s0
	v_or_b32_e32 v130, s5, v1
	v_lshlrev_b64 v[2:3], 11, v[130:131]
	v_lshl_add_u64 v[2:3], v[88:89], 0, v[2:3]
	global_store_short v[2:3], v4, off
	v_add_f32_e32 v2, v8, v60
	v_readlane_b32 s5, v251, 37
	v_mul_f32_e32 v2, v76, v2
	v_cvt_pk_bf16_f32 v4, v2, s0
	v_or_b32_e32 v130, s5, v1
	v_lshlrev_b64 v[2:3], 11, v[130:131]
	v_lshl_add_u64 v[2:3], v[88:89], 0, v[2:3]
	global_store_short v[2:3], v4, off
	v_add_f32_e32 v2, v9, v61
	v_mul_f32_e32 v2, v77, v2
	v_cvt_pk_bf16_f32 v8, v2, s0
	ds_read_b128 v[2:5], v94 offset:64
	v_readlane_b32 s5, v251, 38
	s_nop 1
	v_or_b32_e32 v130, s5, v1
	v_lshlrev_b64 v[6:7], 11, v[130:131]
	v_lshl_add_u64 v[6:7], v[88:89], 0, v[6:7]
	v_readlane_b32 s5, v251, 39
	global_store_short v[6:7], v8, off
	ds_read_b128 v[6:9], v94 offset:96
	s_waitcnt lgkmcnt(1)
	v_add_f32_e32 v2, v10, v2
	v_or_b32_e32 v130, s5, v1
	v_mul_f32_e32 v2, v95, v2
	v_lshlrev_b64 v[58:59], 11, v[130:131]
	v_cvt_pk_bf16_f32 v2, v2, s0
	v_lshl_add_u64 v[58:59], v[88:89], 0, v[58:59]
	global_store_short v[58:59], v2, off
	v_add_f32_e32 v2, v11, v3
	v_readlane_b32 s5, v251, 40
	v_mul_f32_e32 v2, v96, v2
	v_cvt_pk_bf16_f32 v10, v2, s0
	v_or_b32_e32 v130, s5, v1
	v_lshlrev_b64 v[2:3], 11, v[130:131]
	v_lshl_add_u64 v[2:3], v[88:89], 0, v[2:3]
	global_store_short v[2:3], v10, off
	v_add_f32_e32 v2, v12, v4
	v_readlane_b32 s5, v251, 41
	v_mul_f32_e32 v2, v98, v2
	v_cvt_pk_bf16_f32 v4, v2, s0
	v_or_b32_e32 v130, s5, v1
	v_lshlrev_b64 v[2:3], 11, v[130:131]
	v_lshl_add_u64 v[2:3], v[88:89], 0, v[2:3]
	global_store_short v[2:3], v4, off
	v_add_f32_e32 v2, v13, v5
	v_readlane_b32 s5, v251, 42
	v_mul_f32_e32 v2, v100, v2
	v_cvt_pk_bf16_f32 v4, v2, s0
	v_or_b32_e32 v130, s5, v1
	v_lshlrev_b64 v[2:3], 11, v[130:131]
	v_lshl_add_u64 v[2:3], v[88:89], 0, v[2:3]
	global_store_short v[2:3], v4, off
	s_waitcnt lgkmcnt(0)
	v_add_f32_e32 v2, v14, v6
	v_readlane_b32 s5, v251, 43
	v_mul_f32_e32 v2, v102, v2
	v_cvt_pk_bf16_f32 v4, v2, s0
	v_or_b32_e32 v130, s5, v1
	v_lshlrev_b64 v[2:3], 11, v[130:131]
	v_lshl_add_u64 v[2:3], v[88:89], 0, v[2:3]
	global_store_short v[2:3], v4, off
	v_add_f32_e32 v2, v15, v7
	v_readlane_b32 s5, v251, 44
	v_mul_f32_e32 v2, v104, v2
	v_cvt_pk_bf16_f32 v4, v2, s0
	v_or_b32_e32 v130, s5, v1
	v_lshlrev_b64 v[2:3], 11, v[130:131]
	v_lshl_add_u64 v[2:3], v[88:89], 0, v[2:3]
	global_store_short v[2:3], v4, off
	v_add_f32_e32 v2, v16, v8
	v_readlane_b32 s5, v251, 45
	v_mul_f32_e32 v2, v106, v2
	v_cvt_pk_bf16_f32 v4, v2, s0
	v_or_b32_e32 v130, s5, v1
	v_lshlrev_b64 v[2:3], 11, v[130:131]
	v_lshl_add_u64 v[2:3], v[88:89], 0, v[2:3]
	global_store_short v[2:3], v4, off
	v_add_f32_e32 v2, v17, v9
	v_readlane_b32 s5, v251, 46
	v_mul_f32_e32 v2, v110, v2
	v_cvt_pk_bf16_f32 v4, v2, s0
	v_or_b32_e32 v130, s5, v1
	v_lshlrev_b64 v[2:3], 11, v[130:131]
	v_lshl_add_u64 v[2:3], v[88:89], 0, v[2:3]
	global_store_short v[2:3], v4, off
	v_or_b32_e32 v2, 64, v82
	v_mad_i64_i32 v[2:3], s[6:7], v2, s87, v[84:85]
	global_load_ushort v10, v[2:3], off
	v_or_b32_e32 v2, 0x41, v82
	v_mad_i64_i32 v[2:3], s[6:7], v2, s87, v[84:85]
	global_load_ushort v11, v[2:3], off
	v_or_b32_e32 v2, 0x42, v82
	v_mad_i64_i32 v[2:3], s[6:7], v2, s87, v[84:85]
	global_load_ushort v12, v[2:3], off
	v_or_b32_e32 v2, 0x43, v82
	v_mad_i64_i32 v[2:3], s[6:7], v2, s87, v[84:85]
	global_load_ushort v13, v[2:3], off
	v_or_b32_e32 v2, 0x48, v82
	v_or_b32_e32 v4, 0x49, v82
	v_mad_i64_i32 v[2:3], s[6:7], v2, s87, v[84:85]
	v_mad_i64_i32 v[4:5], s[6:7], v4, s87, v[84:85]
	v_or_b32_e32 v6, 0x4a, v82
	v_or_b32_e32 v8, 0x4b, v82
	v_mad_i64_i32 v[6:7], s[6:7], v6, s87, v[84:85]
	v_mad_i64_i32 v[8:9], s[6:7], v8, s87, v[84:85]
	global_load_ushort v2, v[2:3], off
	s_nop 0
	global_load_ushort v3, v[4:5], off
	s_nop 0
	global_load_ushort v4, v[6:7], off
	global_load_ushort v5, v[8:9], off
	v_readlane_b32 s5, v251, 47
	s_waitcnt vmcnt(7)
	v_lshlrev_b32_e32 v6, 16, v10
	v_fma_f32 v7, |v6|, s92, 1.0
	v_rcp_f32_e32 v7, v7
	v_mul_f32_e32 v9, v6, v6
	v_mul_f32_e32 v9, 0xbf38aa3b, v9
	v_exp_f32_e32 v9, v9
	v_fmamk_f32 v8, v7, 0x3f07dc22, v236
	v_fmaak_f32 v8, v7, v8, 0x3f35f0e3
	v_fmaak_f32 v8, v7, v8, 0xbe11a98e
	v_fmaak_f32 v8, v7, v8, 0x3e027906
	v_mul_f32_e32 v7, v7, v8
	v_mul_f32_e32 v7, v9, v7
	v_mul_f32_e32 v8, v7, v6
	v_fma_f32 v7, -v7, v6, v6
	v_cmp_gt_f32_e32 vcc, 0, v6
	s_waitcnt vmcnt(6)
	v_lshlrev_b32_e32 v6, 16, v11
	v_mul_f32_e32 v9, v6, v6
	v_cndmask_b32_e32 v83, v7, v8, vcc
	v_fma_f32 v7, |v6|, s92, 1.0
	v_rcp_f32_e32 v7, v7
	v_mul_f32_e32 v9, 0xbf38aa3b, v9
	v_exp_f32_e32 v9, v9
	v_cmp_gt_f32_e32 vcc, 0, v6
	v_fmamk_f32 v8, v7, 0x3f07dc22, v236
	v_fmaak_f32 v8, v7, v8, 0x3f35f0e3
	v_fmaak_f32 v8, v7, v8, 0xbe11a98e
	v_fmaak_f32 v8, v7, v8, 0x3e027906
	v_mul_f32_e32 v7, v7, v8
	v_mul_f32_e32 v7, v9, v7
	v_mul_f32_e32 v8, v7, v6
	v_fma_f32 v7, -v7, v6, v6
	s_waitcnt vmcnt(5)
	v_lshlrev_b32_e32 v6, 16, v12
	v_cndmask_b32_e32 v95, v7, v8, vcc
	v_fma_f32 v7, |v6|, s92, 1.0
	v_rcp_f32_e32 v7, v7
	v_mul_f32_e32 v9, v6, v6
	v_mul_f32_e32 v9, 0xbf38aa3b, v9
	v_exp_f32_e32 v9, v9
	v_fmamk_f32 v8, v7, 0x3f07dc22, v236
	v_fmaak_f32 v8, v7, v8, 0x3f35f0e3
	v_fmaak_f32 v8, v7, v8, 0xbe11a98e
	v_fmaak_f32 v8, v7, v8, 0x3e027906
	v_mul_f32_e32 v7, v7, v8
	v_mul_f32_e32 v7, v9, v7
	v_mul_f32_e32 v8, v7, v6
	v_fma_f32 v7, -v7, v6, v6
	v_cmp_gt_f32_e32 vcc, 0, v6
	s_waitcnt vmcnt(4)
	v_lshlrev_b32_e32 v6, 16, v13
	v_mul_f32_e32 v9, v6, v6
	v_cndmask_b32_e32 v96, v7, v8, vcc
	v_fma_f32 v7, |v6|, s92, 1.0
	v_rcp_f32_e32 v7, v7
	v_mul_f32_e32 v9, 0xbf38aa3b, v9
	v_exp_f32_e32 v9, v9
	s_waitcnt vmcnt(3)
	v_lshlrev_b32_e32 v2, 16, v2
	v_fmamk_f32 v8, v7, 0x3f07dc22, v236
	v_fmaak_f32 v8, v7, v8, 0x3f35f0e3
	v_fmaak_f32 v8, v7, v8, 0xbe11a98e
	v_fmaak_f32 v8, v7, v8, 0x3e027906
	v_mul_f32_e32 v7, v7, v8
	v_mul_f32_e32 v7, v9, v7
	v_mul_f32_e32 v8, v7, v6
	v_fma_f32 v7, -v7, v6, v6
	v_cmp_gt_f32_e32 vcc, 0, v6
	v_fma_f32 v6, |v2|, s92, 1.0
	v_rcp_f32_e32 v6, v6
	v_cndmask_b32_e32 v98, v7, v8, vcc
	v_mul_f32_e32 v8, v2, v2
	v_mul_f32_e32 v8, 0xbf38aa3b, v8
	v_fmamk_f32 v7, v6, 0x3f07dc22, v236
	v_fmaak_f32 v7, v6, v7, 0x3f35f0e3
	v_exp_f32_e32 v8, v8
	v_fmaak_f32 v7, v6, v7, 0xbe11a98e
	v_fmaak_f32 v7, v6, v7, 0x3e027906
	v_mul_f32_e32 v6, v6, v7
	v_mul_f32_e32 v6, v8, v6
	v_mul_f32_e32 v7, v6, v2
	v_fma_f32 v6, -v6, v2, v2
	v_cmp_gt_f32_e32 vcc, 0, v2
	s_waitcnt vmcnt(2)
	v_lshlrev_b32_e32 v2, 16, v3
	v_fma_f32 v3, |v2|, s92, 1.0
	v_rcp_f32_e32 v3, v3
	v_cndmask_b32_e32 v100, v6, v7, vcc
	v_mul_f32_e32 v7, v2, v2
	v_mul_f32_e32 v7, 0xbf38aa3b, v7
	v_fmamk_f32 v6, v3, 0x3f07dc22, v236
	v_fmaak_f32 v6, v3, v6, 0x3f35f0e3
	v_exp_f32_e32 v7, v7
	v_fmaak_f32 v6, v3, v6, 0xbe11a98e
	v_fmaak_f32 v6, v3, v6, 0x3e027906
	v_mul_f32_e32 v3, v3, v6
	v_mul_f32_e32 v3, v7, v3
	v_mul_f32_e32 v6, v3, v2
	v_fma_f32 v3, -v3, v2, v2
	v_cmp_gt_f32_e32 vcc, 0, v2
	s_waitcnt vmcnt(1)
	v_lshlrev_b32_e32 v2, 16, v4
	v_or_b32_e32 v8, 0x5b, v82
	v_cndmask_b32_e32 v102, v3, v6, vcc
	v_fma_f32 v3, |v2|, s92, 1.0
	v_rcp_f32_e32 v3, v3
	v_mul_f32_e32 v6, v2, v2
	v_mul_f32_e32 v6, 0xbf38aa3b, v6
	v_exp_f32_e32 v6, v6
	v_fmamk_f32 v4, v3, 0x3f07dc22, v236
	v_fmaak_f32 v4, v3, v4, 0x3f35f0e3
	v_fmaak_f32 v4, v3, v4, 0xbe11a98e
	v_fmaak_f32 v4, v3, v4, 0x3e027906
	v_mul_f32_e32 v3, v3, v4
	v_mul_f32_e32 v3, v6, v3
	v_mul_f32_e32 v4, v3, v2
	v_fma_f32 v3, -v3, v2, v2
	v_cmp_gt_f32_e32 vcc, 0, v2
	s_waitcnt vmcnt(0)
	v_lshlrev_b32_e32 v2, 16, v5
	v_mul_f32_e32 v5, v2, v2
	v_cndmask_b32_e32 v104, v3, v4, vcc
	v_fma_f32 v3, |v2|, s92, 1.0
	v_rcp_f32_e32 v3, v3
	v_mul_f32_e32 v5, 0xbf38aa3b, v5
	v_exp_f32_e32 v5, v5
	v_cmp_gt_f32_e32 vcc, 0, v2
	v_fmamk_f32 v4, v3, 0x3f07dc22, v236
	v_fmaak_f32 v4, v3, v4, 0x3f35f0e3
	v_fmaak_f32 v4, v3, v4, 0xbe11a98e
	v_fmaak_f32 v4, v3, v4, 0x3e027906
	v_mul_f32_e32 v3, v3, v4
	v_mul_f32_e32 v3, v5, v3
	v_mul_f32_e32 v4, v3, v2
	v_fma_f32 v3, -v3, v2, v2
	v_or_b32_e32 v2, 0x50, v82
	v_cndmask_b32_e32 v106, v3, v4, vcc
	v_mad_i64_i32 v[2:3], s[6:7], v2, s87, v[84:85]
	global_load_ushort v10, v[2:3], off
	v_or_b32_e32 v2, 0x51, v82
	v_mad_i64_i32 v[2:3], s[6:7], v2, s87, v[84:85]
	global_load_ushort v11, v[2:3], off
	v_or_b32_e32 v2, 0x52, v82
	v_mad_i64_i32 v[2:3], s[6:7], v2, s87, v[84:85]
	global_load_ushort v12, v[2:3], off
	v_or_b32_e32 v2, 0x53, v82
	v_mad_i64_i32 v[2:3], s[6:7], v2, s87, v[84:85]
	global_load_ushort v13, v[2:3], off
	v_or_b32_e32 v2, 0x58, v82
	v_or_b32_e32 v4, 0x59, v82
	v_mad_i64_i32 v[2:3], s[6:7], v2, s87, v[84:85]
	v_mad_i64_i32 v[4:5], s[6:7], v4, s87, v[84:85]
	v_or_b32_e32 v6, 0x5a, v82
	v_mad_i64_i32 v[6:7], s[6:7], v6, s87, v[84:85]
	v_mad_i64_i32 v[8:9], s[6:7], v8, s87, v[84:85]
	global_load_ushort v2, v[2:3], off
	s_nop 0
	global_load_ushort v3, v[4:5], off
	s_nop 0
	global_load_ushort v4, v[6:7], off
	global_load_ushort v58, v[8:9], off
	v_or_b32_e32 v130, s5, v1
	v_readlane_b32 s5, v251, 48
	s_waitcnt vmcnt(7)
	v_lshlrev_b32_e32 v5, 16, v10
	v_fma_f32 v6, |v5|, s92, 1.0
	v_rcp_f32_e32 v6, v6
	v_mul_f32_e32 v8, v5, v5
	v_mul_f32_e32 v8, 0xbf38aa3b, v8
	v_exp_f32_e32 v8, v8
	v_fmamk_f32 v7, v6, 0x3f07dc22, v236
	v_fmaak_f32 v7, v6, v7, 0x3f35f0e3
	v_fmaak_f32 v7, v6, v7, 0xbe11a98e
	v_fmaak_f32 v7, v6, v7, 0x3e027906
	v_mul_f32_e32 v6, v6, v7
	v_mul_f32_e32 v6, v8, v6
	v_mul_f32_e32 v7, v6, v5
	v_fma_f32 v6, -v6, v5, v5
	v_cmp_gt_f32_e32 vcc, 0, v5
	s_waitcnt vmcnt(6)
	v_lshlrev_b32_e32 v5, 16, v11
	v_mul_f32_e32 v8, v5, v5
	v_cndmask_b32_e32 v110, v6, v7, vcc
	v_fma_f32 v6, |v5|, s92, 1.0
	v_rcp_f32_e32 v6, v6
	v_mul_f32_e32 v8, 0xbf38aa3b, v8
	v_exp_f32_e32 v8, v8
	v_cmp_gt_f32_e32 vcc, 0, v5
	v_fmamk_f32 v7, v6, 0x3f07dc22, v236
	v_fmaak_f32 v7, v6, v7, 0x3f35f0e3
	v_fmaak_f32 v7, v6, v7, 0xbe11a98e
	v_fmaak_f32 v7, v6, v7, 0x3e027906
	v_mul_f32_e32 v6, v6, v7
	v_mul_f32_e32 v6, v8, v6
	v_mul_f32_e32 v7, v6, v5
	v_fma_f32 v6, -v6, v5, v5
	s_waitcnt vmcnt(5)
	v_lshlrev_b32_e32 v5, 16, v12
	v_cndmask_b32_e32 v111, v6, v7, vcc
	v_fma_f32 v6, |v5|, s92, 1.0
	v_rcp_f32_e32 v6, v6
	v_mul_f32_e32 v8, v5, v5
	v_mul_f32_e32 v8, 0xbf38aa3b, v8
	v_exp_f32_e32 v8, v8
	v_fmamk_f32 v7, v6, 0x3f07dc22, v236
	v_fmaak_f32 v7, v6, v7, 0x3f35f0e3
	v_fmaak_f32 v7, v6, v7, 0xbe11a98e
	v_fmaak_f32 v7, v6, v7, 0x3e027906
	v_mul_f32_e32 v6, v6, v7
	v_mul_f32_e32 v6, v8, v6
	v_mul_f32_e32 v7, v6, v5
	v_fma_f32 v6, -v6, v5, v5
	v_cmp_gt_f32_e32 vcc, 0, v5
	s_waitcnt vmcnt(4)
	v_lshlrev_b32_e32 v5, 16, v13
	v_mul_f32_e32 v8, v5, v5
	v_cndmask_b32_e32 v112, v6, v7, vcc
	v_fma_f32 v6, |v5|, s92, 1.0
	v_rcp_f32_e32 v6, v6
	v_mul_f32_e32 v8, 0xbf38aa3b, v8
	v_exp_f32_e32 v8, v8
	s_waitcnt vmcnt(3)
	v_lshlrev_b32_e32 v2, 16, v2
	v_fmamk_f32 v7, v6, 0x3f07dc22, v236
	v_fmaak_f32 v7, v6, v7, 0x3f35f0e3
	v_fmaak_f32 v7, v6, v7, 0xbe11a98e
	v_fmaak_f32 v7, v6, v7, 0x3e027906
	v_mul_f32_e32 v6, v6, v7
	v_mul_f32_e32 v6, v8, v6
	v_mul_f32_e32 v7, v6, v5
	v_fma_f32 v6, -v6, v5, v5
	v_cmp_gt_f32_e32 vcc, 0, v5
	v_fma_f32 v5, |v2|, s92, 1.0
	v_rcp_f32_e32 v5, v5
	v_cndmask_b32_e32 v114, v6, v7, vcc
	v_mul_f32_e32 v7, v2, v2
	v_mul_f32_e32 v7, 0xbf38aa3b, v7
	v_fmamk_f32 v6, v5, 0x3f07dc22, v236
	v_fmaak_f32 v6, v5, v6, 0x3f35f0e3
	v_exp_f32_e32 v7, v7
	v_fmaak_f32 v6, v5, v6, 0xbe11a98e
	v_fmaak_f32 v6, v5, v6, 0x3e027906
	v_mul_f32_e32 v5, v5, v6
	v_mul_f32_e32 v5, v7, v5
	v_mul_f32_e32 v6, v5, v2
	v_fma_f32 v5, -v5, v2, v2
	v_cmp_gt_f32_e32 vcc, 0, v2
	s_waitcnt vmcnt(2)
	v_lshlrev_b32_e32 v2, 16, v3
	v_fma_f32 v3, |v2|, s92, 1.0
	v_rcp_f32_e32 v3, v3
	v_cndmask_b32_e32 v116, v5, v6, vcc
	v_mul_f32_e32 v6, v2, v2
	v_mul_f32_e32 v6, 0xbf38aa3b, v6
	v_fmamk_f32 v5, v3, 0x3f07dc22, v236
	v_fmaak_f32 v5, v3, v5, 0x3f35f0e3
	v_exp_f32_e32 v6, v6
	v_fmaak_f32 v5, v3, v5, 0xbe11a98e
	v_fmaak_f32 v5, v3, v5, 0x3e027906
	v_mul_f32_e32 v3, v3, v5
	v_mul_f32_e32 v3, v6, v3
	s_waitcnt vmcnt(1)
	v_lshlrev_b32_e32 v59, 16, v4
	v_mul_f32_e32 v5, v3, v2
	v_fma_f32 v3, -v3, v2, v2
	v_cmp_gt_f32_e32 vcc, 0, v2
	v_fma_f32 v2, |v59|, s92, 1.0
	v_rcp_f32_e32 v60, v2
	v_cndmask_b32_e32 v118, v3, v5, vcc
	v_mfma_f32_32x32x16_bf16 v[2:17], v[22:25], v[54:57], 0
	v_mul_f32_e32 v23, v59, v59
	v_fmamk_f32 v22, v60, 0x3f07dc22, v236
	v_mul_f32_e32 v23, 0xbf38aa3b, v23
	v_fmaak_f32 v22, v60, v22, 0x3f35f0e3
	v_exp_f32_e32 v23, v23
	v_fmaak_f32 v22, v60, v22, 0xbe11a98e
	v_fmaak_f32 v22, v60, v22, 0x3e027906
	v_mfma_f32_32x32x16_bf16 v[2:17], v[18:21], v[50:53], v[2:17]
	v_mul_f32_e32 v22, v60, v22
	v_mul_f32_e32 v22, v23, v22
	v_mul_f32_e32 v23, v22, v59
	v_fma_f32 v22, -v22, v59, v59
	v_cmp_gt_f32_e32 vcc, 0, v59
	s_nop 1
	v_cndmask_b32_e32 v24, v22, v23, vcc
	s_waitcnt vmcnt(0)
	v_lshlrev_b32_e32 v22, 16, v58
	v_fma_f32 v23, |v22|, s92, 1.0
	v_rcp_f32_e32 v23, v23
	v_mfma_f32_32x32x16_bf16 v[2:17], v[62:65], v[46:49], v[2:17]
	v_mul_f32_e32 v19, v22, v22
	v_mul_f32_e32 v19, 0xbf38aa3b, v19
	v_fmamk_f32 v18, v23, 0x3f07dc22, v236
	v_fmaak_f32 v18, v23, v18, 0x3f35f0e3
	v_exp_f32_e32 v19, v19
	v_fmaak_f32 v18, v23, v18, 0xbe11a98e
	v_fmaak_f32 v18, v23, v18, 0x3e027906
	v_mul_f32_e32 v18, v23, v18
	v_mul_f32_e32 v18, v19, v18
	v_mfma_f32_32x32x16_bf16 v[2:17], v[78:81], v[42:45], v[2:17]
	v_mul_f32_e32 v19, v18, v22
	v_fma_f32 v18, -v18, v22, v22
	v_cmp_gt_f32_e32 vcc, 0, v22
	v_lshlrev_b64 v[22:23], 11, v[130:131]
	v_lshl_add_u64 v[22:23], v[88:89], 0, v[22:23]
	v_cndmask_b32_e32 v25, v18, v19, vcc
	global_load_dwordx4 v[18:21], v[66:67], off offset:2048
	global_load_dwordx4 v[74:77], v[66:67], off offset:3072
	global_load_dwordx4 v[70:73], v[86:87], off
	s_nop 0
	global_load_dwordx4 v[66:69], v[86:87], off offset:1024
	global_load_dwordx4 v[62:65], v[86:87], off offset:2048
	global_load_dwordx4 v[58:61], v[86:87], off offset:3072
	ds_read_b128 v[124:127], v94 offset:128
	ds_read_b128 v[78:81], v94 offset:160
	v_or_b32_e32 v130, s5, v1
	v_readlane_b32 s5, v251, 49
	s_waitcnt lgkmcnt(1)
	v_add_f32_e32 v2, v2, v124
	v_mul_f32_e32 v2, v97, v2
	v_cvt_pk_bf16_f32 v2, v2, s0
	global_store_short v[22:23], v2, off
	v_add_f32_e32 v2, v3, v125
	v_mul_f32_e32 v2, v99, v2
	v_cvt_pk_bf16_f32 v22, v2, s0
	v_lshlrev_b64 v[2:3], 11, v[130:131]
	v_lshl_add_u64 v[2:3], v[88:89], 0, v[2:3]
	global_store_short v[2:3], v22, off
	v_add_f32_e32 v2, v4, v126
	v_mul_f32_e32 v2, v101, v2
	v_or_b32_e32 v130, s5, v1
	v_cvt_pk_bf16_f32 v4, v2, s0
	v_lshlrev_b64 v[2:3], 11, v[130:131]
	v_lshl_add_u64 v[2:3], v[88:89], 0, v[2:3]
	global_store_short v[2:3], v4, off
	v_add_f32_e32 v2, v5, v127
	v_readlane_b32 s5, v251, 50
	v_mul_f32_e32 v2, v103, v2
	v_cvt_pk_bf16_f32 v4, v2, s0
	v_or_b32_e32 v130, s5, v1
	v_lshlrev_b64 v[2:3], 11, v[130:131]
	v_lshl_add_u64 v[2:3], v[88:89], 0, v[2:3]
	global_store_short v[2:3], v4, off
	s_waitcnt lgkmcnt(0)
	v_add_f32_e32 v2, v6, v78
	v_readlane_b32 s5, v251, 51
	v_mul_f32_e32 v2, v105, v2
	v_cvt_pk_bf16_f32 v4, v2, s0
	v_or_b32_e32 v130, s5, v1
	v_lshlrev_b64 v[2:3], 11, v[130:131]
	v_lshl_add_u64 v[2:3], v[88:89], 0, v[2:3]
	global_store_short v[2:3], v4, off
	v_add_f32_e32 v2, v7, v79
	v_readlane_b32 s5, v251, 52
	v_mul_f32_e32 v2, v107, v2
	v_cvt_pk_bf16_f32 v4, v2, s0
	v_or_b32_e32 v130, s5, v1
	v_lshlrev_b64 v[2:3], 11, v[130:131]
	v_lshl_add_u64 v[2:3], v[88:89], 0, v[2:3]
	global_store_short v[2:3], v4, off
	v_add_f32_e32 v2, v8, v80
	v_readlane_b32 s5, v251, 53
	v_mul_f32_e32 v2, v108, v2
	v_cvt_pk_bf16_f32 v4, v2, s0
	v_or_b32_e32 v130, s5, v1
	v_lshlrev_b64 v[2:3], 11, v[130:131]
	v_lshl_add_u64 v[2:3], v[88:89], 0, v[2:3]
	global_store_short v[2:3], v4, off
	v_add_f32_e32 v2, v9, v81
	v_mul_f32_e32 v2, v109, v2
	v_cvt_pk_bf16_f32 v8, v2, s0
	ds_read_b128 v[2:5], v94 offset:192
	v_readlane_b32 s5, v251, 54
	s_nop 1
	v_or_b32_e32 v130, s5, v1
	v_lshlrev_b64 v[6:7], 11, v[130:131]
	v_lshl_add_u64 v[6:7], v[88:89], 0, v[6:7]
	v_readlane_b32 s5, v251, 55
	global_store_short v[6:7], v8, off
	ds_read_b128 v[6:9], v94 offset:224
	s_waitcnt lgkmcnt(1)
	v_add_f32_e32 v2, v10, v2
	v_or_b32_e32 v130, s5, v1
	v_mul_f32_e32 v2, v113, v2
	v_lshlrev_b64 v[22:23], 11, v[130:131]
	v_cvt_pk_bf16_f32 v2, v2, s0
	v_lshl_add_u64 v[22:23], v[88:89], 0, v[22:23]
	global_store_short v[22:23], v2, off
	v_add_f32_e32 v2, v11, v3
	v_readlane_b32 s5, v251, 56
	v_mul_f32_e32 v2, v115, v2
	v_cvt_pk_bf16_f32 v10, v2, s0
	v_or_b32_e32 v130, s5, v1
	v_lshlrev_b64 v[2:3], 11, v[130:131]
	v_lshl_add_u64 v[2:3], v[88:89], 0, v[2:3]
	global_store_short v[2:3], v10, off
	v_add_f32_e32 v2, v12, v4
	v_readlane_b32 s5, v251, 57
	v_mul_f32_e32 v2, v117, v2
	v_cvt_pk_bf16_f32 v4, v2, s0
	v_or_b32_e32 v130, s5, v1
	v_lshlrev_b64 v[2:3], 11, v[130:131]
	v_lshl_add_u64 v[2:3], v[88:89], 0, v[2:3]
	global_store_short v[2:3], v4, off
	v_add_f32_e32 v2, v13, v5
	v_readlane_b32 s5, v251, 58
	v_mul_f32_e32 v2, v119, v2
	v_cvt_pk_bf16_f32 v4, v2, s0
	v_or_b32_e32 v130, s5, v1
	v_lshlrev_b64 v[2:3], 11, v[130:131]
	v_lshl_add_u64 v[2:3], v[88:89], 0, v[2:3]
	global_store_short v[2:3], v4, off
	s_waitcnt lgkmcnt(0)
	v_add_f32_e32 v2, v14, v6
	v_readlane_b32 s5, v251, 59
	v_mul_f32_e32 v2, v120, v2
	v_cvt_pk_bf16_f32 v4, v2, s0
	v_or_b32_e32 v130, s5, v1
	v_lshlrev_b64 v[2:3], 11, v[130:131]
	v_lshl_add_u64 v[2:3], v[88:89], 0, v[2:3]
	global_store_short v[2:3], v4, off
	v_add_f32_e32 v2, v15, v7
	v_readlane_b32 s5, v251, 60
	v_mul_f32_e32 v2, v121, v2
	v_cvt_pk_bf16_f32 v4, v2, s0
	v_or_b32_e32 v130, s5, v1
	v_lshlrev_b64 v[2:3], 11, v[130:131]
	v_lshl_add_u64 v[2:3], v[88:89], 0, v[2:3]
	global_store_short v[2:3], v4, off
	v_add_f32_e32 v2, v16, v8
	v_readlane_b32 s5, v251, 61
	v_mul_f32_e32 v2, v122, v2
	v_cvt_pk_bf16_f32 v4, v2, s0
	v_or_b32_e32 v130, s5, v1
	v_lshlrev_b64 v[2:3], 11, v[130:131]
	v_lshl_add_u64 v[2:3], v[88:89], 0, v[2:3]
	global_store_short v[2:3], v4, off
	v_add_f32_e32 v2, v17, v9
	v_readlane_b32 s5, v251, 62
	v_mul_f32_e32 v2, v123, v2
	v_cvt_pk_bf16_f32 v4, v2, s0
	v_or_b32_e32 v130, s5, v1
	v_lshlrev_b64 v[2:3], 11, v[130:131]
	v_lshl_add_u64 v[2:3], v[88:89], 0, v[2:3]
	global_store_short v[2:3], v4, off
	v_or_b32_e32 v2, 0x60, v82
	v_mad_i64_i32 v[2:3], s[6:7], v2, s87, v[84:85]
	global_load_ushort v10, v[2:3], off
	v_or_b32_e32 v2, 0x61, v82
	v_mad_i64_i32 v[2:3], s[6:7], v2, s87, v[84:85]
	global_load_ushort v11, v[2:3], off
	v_or_b32_e32 v2, 0x62, v82
	v_mad_i64_i32 v[2:3], s[6:7], v2, s87, v[84:85]
	global_load_ushort v12, v[2:3], off
	v_or_b32_e32 v2, 0x63, v82
	v_mad_i64_i32 v[2:3], s[6:7], v2, s87, v[84:85]
	global_load_ushort v13, v[2:3], off
	v_or_b32_e32 v2, 0x68, v82
	v_or_b32_e32 v4, 0x69, v82
	v_mad_i64_i32 v[2:3], s[6:7], v2, s87, v[84:85]
	v_mad_i64_i32 v[4:5], s[6:7], v4, s87, v[84:85]
	v_or_b32_e32 v6, 0x6a, v82
	v_or_b32_e32 v8, 0x6b, v82
	v_mad_i64_i32 v[6:7], s[6:7], v6, s87, v[84:85]
	v_mad_i64_i32 v[8:9], s[6:7], v8, s87, v[84:85]
	global_load_ushort v2, v[2:3], off
	s_nop 0
	global_load_ushort v3, v[4:5], off
	s_nop 0
	global_load_ushort v4, v[6:7], off
	global_load_ushort v5, v[8:9], off
	v_readlane_b32 s5, v251, 63
	s_waitcnt vmcnt(7)
	v_lshlrev_b32_e32 v6, 16, v10
	v_fma_f32 v7, |v6|, s92, 1.0
	v_rcp_f32_e32 v7, v7
	v_mul_f32_e32 v9, v6, v6
	v_mul_f32_e32 v9, 0xbf38aa3b, v9
	v_exp_f32_e32 v9, v9
	v_fmamk_f32 v8, v7, 0x3f07dc22, v236
	v_fmaak_f32 v8, v7, v8, 0x3f35f0e3
	v_fmaak_f32 v8, v7, v8, 0xbe11a98e
	v_fmaak_f32 v8, v7, v8, 0x3e027906
	v_mul_f32_e32 v7, v7, v8
	v_mul_f32_e32 v7, v9, v7
	v_mul_f32_e32 v8, v7, v6
	v_fma_f32 v7, -v7, v6, v6
	v_cmp_gt_f32_e32 vcc, 0, v6
	s_waitcnt vmcnt(6)
	v_lshlrev_b32_e32 v6, 16, v11
	v_mul_f32_e32 v9, v6, v6
	v_cndmask_b32_e32 v78, v7, v8, vcc
	v_fma_f32 v7, |v6|, s92, 1.0
	v_rcp_f32_e32 v7, v7
	v_mul_f32_e32 v9, 0xbf38aa3b, v9
	v_exp_f32_e32 v9, v9
	v_cmp_gt_f32_e32 vcc, 0, v6
	v_fmamk_f32 v8, v7, 0x3f07dc22, v236
	v_fmaak_f32 v8, v7, v8, 0x3f35f0e3
	v_fmaak_f32 v8, v7, v8, 0xbe11a98e
	v_fmaak_f32 v8, v7, v8, 0x3e027906
	v_mul_f32_e32 v7, v7, v8
	v_mul_f32_e32 v7, v9, v7
	v_mul_f32_e32 v8, v7, v6
	v_fma_f32 v7, -v7, v6, v6
	s_waitcnt vmcnt(5)
	v_lshlrev_b32_e32 v6, 16, v12
	v_cndmask_b32_e32 v79, v7, v8, vcc
	v_fma_f32 v7, |v6|, s92, 1.0
	v_rcp_f32_e32 v7, v7
	v_mul_f32_e32 v9, v6, v6
	v_mul_f32_e32 v9, 0xbf38aa3b, v9
	v_exp_f32_e32 v9, v9
	v_fmamk_f32 v8, v7, 0x3f07dc22, v236
	v_fmaak_f32 v8, v7, v8, 0x3f35f0e3
	v_fmaak_f32 v8, v7, v8, 0xbe11a98e
	v_fmaak_f32 v8, v7, v8, 0x3e027906
	v_mul_f32_e32 v7, v7, v8
	v_mul_f32_e32 v7, v9, v7
	v_mul_f32_e32 v8, v7, v6
	v_fma_f32 v7, -v7, v6, v6
	v_cmp_gt_f32_e32 vcc, 0, v6
	s_waitcnt vmcnt(4)
	v_lshlrev_b32_e32 v6, 16, v13
	v_mul_f32_e32 v9, v6, v6
	v_cndmask_b32_e32 v80, v7, v8, vcc
	v_fma_f32 v7, |v6|, s92, 1.0
	v_rcp_f32_e32 v7, v7
	v_mul_f32_e32 v9, 0xbf38aa3b, v9
	v_exp_f32_e32 v9, v9
	s_waitcnt vmcnt(3)
	v_lshlrev_b32_e32 v2, 16, v2
	v_fmamk_f32 v8, v7, 0x3f07dc22, v236
	v_fmaak_f32 v8, v7, v8, 0x3f35f0e3
	v_fmaak_f32 v8, v7, v8, 0xbe11a98e
	v_fmaak_f32 v8, v7, v8, 0x3e027906
	v_mul_f32_e32 v7, v7, v8
	v_mul_f32_e32 v7, v9, v7
	v_mul_f32_e32 v8, v7, v6
	v_fma_f32 v7, -v7, v6, v6
	v_cmp_gt_f32_e32 vcc, 0, v6
	v_fma_f32 v6, |v2|, s92, 1.0
	v_rcp_f32_e32 v6, v6
	v_cndmask_b32_e32 v81, v7, v8, vcc
	v_mul_f32_e32 v8, v2, v2
	v_mul_f32_e32 v8, 0xbf38aa3b, v8
	v_fmamk_f32 v7, v6, 0x3f07dc22, v236
	v_fmaak_f32 v7, v6, v7, 0x3f35f0e3
	v_exp_f32_e32 v8, v8
	v_fmaak_f32 v7, v6, v7, 0xbe11a98e
	v_fmaak_f32 v7, v6, v7, 0x3e027906
	v_mul_f32_e32 v6, v6, v7
	v_mul_f32_e32 v6, v8, v6
	v_mul_f32_e32 v7, v6, v2
	v_fma_f32 v6, -v6, v2, v2
	v_cmp_gt_f32_e32 vcc, 0, v2
	s_waitcnt vmcnt(2)
	v_lshlrev_b32_e32 v2, 16, v3
	v_fma_f32 v3, |v2|, s92, 1.0
	v_rcp_f32_e32 v3, v3
	v_cndmask_b32_e32 v86, v6, v7, vcc
	v_mul_f32_e32 v7, v2, v2
	v_mul_f32_e32 v7, 0xbf38aa3b, v7
	v_fmamk_f32 v6, v3, 0x3f07dc22, v236
	v_fmaak_f32 v6, v3, v6, 0x3f35f0e3
	v_exp_f32_e32 v7, v7
	v_fmaak_f32 v6, v3, v6, 0xbe11a98e
	v_fmaak_f32 v6, v3, v6, 0x3e027906
	v_mul_f32_e32 v3, v3, v6
	v_mul_f32_e32 v3, v7, v3
	v_mul_f32_e32 v6, v3, v2
	v_fma_f32 v3, -v3, v2, v2
	v_cmp_gt_f32_e32 vcc, 0, v2
	s_waitcnt vmcnt(1)
	v_lshlrev_b32_e32 v2, 16, v4
	v_or_b32_e32 v8, 0x7b, v82
	v_cndmask_b32_e32 v87, v3, v6, vcc
	v_fma_f32 v3, |v2|, s92, 1.0
	v_rcp_f32_e32 v3, v3
	v_mul_f32_e32 v6, v2, v2
	v_mul_f32_e32 v6, 0xbf38aa3b, v6
	v_exp_f32_e32 v6, v6
	v_fmamk_f32 v4, v3, 0x3f07dc22, v236
	v_fmaak_f32 v4, v3, v4, 0x3f35f0e3
	v_fmaak_f32 v4, v3, v4, 0xbe11a98e
	v_fmaak_f32 v4, v3, v4, 0x3e027906
	v_mul_f32_e32 v3, v3, v4
	v_mul_f32_e32 v3, v6, v3
	v_mul_f32_e32 v4, v3, v2
	v_fma_f32 v3, -v3, v2, v2
	v_cmp_gt_f32_e32 vcc, 0, v2
	s_waitcnt vmcnt(0)
	v_lshlrev_b32_e32 v2, 16, v5
	v_mul_f32_e32 v5, v2, v2
	v_cndmask_b32_e32 v97, v3, v4, vcc
	v_fma_f32 v3, |v2|, s92, 1.0
	v_rcp_f32_e32 v3, v3
	v_mul_f32_e32 v5, 0xbf38aa3b, v5
	v_exp_f32_e32 v5, v5
	v_cmp_gt_f32_e32 vcc, 0, v2
	v_fmamk_f32 v4, v3, 0x3f07dc22, v236
	v_fmaak_f32 v4, v3, v4, 0x3f35f0e3
	v_fmaak_f32 v4, v3, v4, 0xbe11a98e
	v_fmaak_f32 v4, v3, v4, 0x3e027906
	v_mul_f32_e32 v3, v3, v4
	v_mul_f32_e32 v3, v5, v3
	v_mul_f32_e32 v4, v3, v2
	v_fma_f32 v3, -v3, v2, v2
	v_or_b32_e32 v2, 0x70, v82
	v_cndmask_b32_e32 v99, v3, v4, vcc
	v_mad_i64_i32 v[2:3], s[6:7], v2, s87, v[84:85]
	global_load_ushort v10, v[2:3], off
	v_or_b32_e32 v2, 0x71, v82
	v_mad_i64_i32 v[2:3], s[6:7], v2, s87, v[84:85]
	global_load_ushort v11, v[2:3], off
	v_or_b32_e32 v2, 0x72, v82
	v_mad_i64_i32 v[2:3], s[6:7], v2, s87, v[84:85]
	global_load_ushort v12, v[2:3], off
	v_or_b32_e32 v2, 0x73, v82
	v_mad_i64_i32 v[2:3], s[6:7], v2, s87, v[84:85]
	global_load_ushort v13, v[2:3], off
	v_or_b32_e32 v2, 0x78, v82
	v_or_b32_e32 v4, 0x79, v82
	v_mad_i64_i32 v[2:3], s[6:7], v2, s87, v[84:85]
	v_mad_i64_i32 v[4:5], s[6:7], v4, s87, v[84:85]
	v_or_b32_e32 v6, 0x7a, v82
	v_mad_i64_i32 v[6:7], s[6:7], v6, s87, v[84:85]
	v_mad_i64_i32 v[8:9], s[6:7], v8, s87, v[84:85]
	global_load_ushort v2, v[2:3], off
	s_nop 0
	global_load_ushort v3, v[4:5], off
	s_nop 0
	global_load_ushort v4, v[6:7], off
	global_load_ushort v5, v[8:9], off
	v_or_b32_e32 v130, s5, v1
	v_readlane_b32 s5, v252, 0
	v_readlane_b32 s6, v250, 27
	v_readlane_b32 s7, v250, 28
	s_waitcnt vmcnt(7)
	v_lshlrev_b32_e32 v6, 16, v10
	v_fma_f32 v7, |v6|, s92, 1.0
	v_rcp_f32_e32 v7, v7
	v_mul_f32_e32 v9, v6, v6
	v_mul_f32_e32 v9, 0xbf38aa3b, v9
	v_exp_f32_e32 v9, v9
	v_fmamk_f32 v8, v7, 0x3f07dc22, v236
	v_fmaak_f32 v8, v7, v8, 0x3f35f0e3
	v_fmaak_f32 v8, v7, v8, 0xbe11a98e
	v_fmaak_f32 v8, v7, v8, 0x3e027906
	v_mul_f32_e32 v7, v7, v8
	v_mul_f32_e32 v7, v9, v7
	v_mul_f32_e32 v8, v7, v6
	v_fma_f32 v7, -v7, v6, v6
	v_cmp_gt_f32_e32 vcc, 0, v6
	s_waitcnt vmcnt(6)
	v_lshlrev_b32_e32 v6, 16, v11
	v_mul_f32_e32 v9, v6, v6
	v_cndmask_b32_e32 v82, v7, v8, vcc
	v_fma_f32 v7, |v6|, s92, 1.0
	v_rcp_f32_e32 v7, v7
	v_mul_f32_e32 v9, 0xbf38aa3b, v9
	v_exp_f32_e32 v9, v9
	v_cmp_gt_f32_e32 vcc, 0, v6
	v_fmamk_f32 v8, v7, 0x3f07dc22, v236
	v_fmaak_f32 v8, v7, v8, 0x3f35f0e3
	v_fmaak_f32 v8, v7, v8, 0xbe11a98e
	v_fmaak_f32 v8, v7, v8, 0x3e027906
	v_mul_f32_e32 v7, v7, v8
	v_mul_f32_e32 v7, v9, v7
	v_mul_f32_e32 v8, v7, v6
	v_fma_f32 v7, -v7, v6, v6
	s_waitcnt vmcnt(5)
	v_lshlrev_b32_e32 v6, 16, v12
	v_cndmask_b32_e32 v84, v7, v8, vcc
	v_fma_f32 v7, |v6|, s92, 1.0
	v_rcp_f32_e32 v7, v7
	v_mul_f32_e32 v9, v6, v6
	v_mul_f32_e32 v9, 0xbf38aa3b, v9
	v_exp_f32_e32 v9, v9
	v_fmamk_f32 v8, v7, 0x3f07dc22, v236
	v_fmaak_f32 v8, v7, v8, 0x3f35f0e3
	v_fmaak_f32 v8, v7, v8, 0xbe11a98e
	v_fmaak_f32 v8, v7, v8, 0x3e027906
	v_mul_f32_e32 v7, v7, v8
	v_mul_f32_e32 v7, v9, v7
	v_mul_f32_e32 v8, v7, v6
	v_fma_f32 v7, -v7, v6, v6
	v_cmp_gt_f32_e32 vcc, 0, v6
	s_waitcnt vmcnt(4)
	v_lshlrev_b32_e32 v6, 16, v13
	v_mul_f32_e32 v9, v6, v6
	v_cndmask_b32_e32 v85, v7, v8, vcc
	v_fma_f32 v7, |v6|, s92, 1.0
	v_rcp_f32_e32 v7, v7
	v_mul_f32_e32 v9, 0xbf38aa3b, v9
	v_exp_f32_e32 v9, v9
	s_waitcnt vmcnt(3)
	v_lshlrev_b32_e32 v2, 16, v2
	v_fmamk_f32 v8, v7, 0x3f07dc22, v236
	v_fmaak_f32 v8, v7, v8, 0x3f35f0e3
	v_fmaak_f32 v8, v7, v8, 0xbe11a98e
	v_fmaak_f32 v8, v7, v8, 0x3e027906
	v_mul_f32_e32 v7, v7, v8
	v_mul_f32_e32 v7, v9, v7
	v_mul_f32_e32 v8, v7, v6
	v_fma_f32 v7, -v7, v6, v6
	v_cmp_gt_f32_e32 vcc, 0, v6
	v_fma_f32 v6, |v2|, s92, 1.0
	v_rcp_f32_e32 v6, v6
	v_cndmask_b32_e32 v101, v7, v8, vcc
	v_mul_f32_e32 v8, v2, v2
	v_mul_f32_e32 v8, 0xbf38aa3b, v8
	v_fmamk_f32 v7, v6, 0x3f07dc22, v236
	v_fmaak_f32 v7, v6, v7, 0x3f35f0e3
	v_exp_f32_e32 v8, v8
	v_fmaak_f32 v7, v6, v7, 0xbe11a98e
	v_fmaak_f32 v7, v6, v7, 0x3e027906
	v_mul_f32_e32 v6, v6, v7
	v_mul_f32_e32 v6, v8, v6
	v_mul_f32_e32 v7, v6, v2
	v_fma_f32 v6, -v6, v2, v2
	v_cmp_gt_f32_e32 vcc, 0, v2
	s_waitcnt vmcnt(2)
	v_lshlrev_b32_e32 v2, 16, v3
	v_fma_f32 v3, |v2|, s92, 1.0
	v_rcp_f32_e32 v3, v3
	v_cndmask_b32_e32 v107, v6, v7, vcc
	v_mul_f32_e32 v7, v2, v2
	v_mul_f32_e32 v7, 0xbf38aa3b, v7
	v_fmamk_f32 v6, v3, 0x3f07dc22, v236
	v_fmaak_f32 v6, v3, v6, 0x3f35f0e3
	v_exp_f32_e32 v7, v7
	v_fmaak_f32 v6, v3, v6, 0xbe11a98e
	v_fmaak_f32 v6, v3, v6, 0x3e027906
	v_mul_f32_e32 v3, v3, v6
	v_mul_f32_e32 v3, v7, v3
	v_mul_f32_e32 v6, v3, v2
	v_fma_f32 v3, -v3, v2, v2
	v_cmp_gt_f32_e32 vcc, 0, v2
	s_waitcnt vmcnt(1)
	v_lshlrev_b32_e32 v2, 16, v4
	v_mfma_f32_32x32x16_bf16 v[8:23], v[18:21], v[54:57], 0
	v_cndmask_b32_e32 v108, v3, v6, vcc
	v_fma_f32 v3, |v2|, s92, 1.0
	v_rcp_f32_e32 v3, v3
	v_mul_f32_e32 v6, v2, v2
	v_mul_f32_e32 v6, 0xbf38aa3b, v6
	v_exp_f32_e32 v6, v6
	v_fmamk_f32 v4, v3, 0x3f07dc22, v236
	v_fmaak_f32 v4, v3, v4, 0x3f35f0e3
	v_fmaak_f32 v4, v3, v4, 0xbe11a98e
	v_fmaak_f32 v4, v3, v4, 0x3e027906
	v_mfma_f32_32x32x16_bf16 v[8:23], v[74:77], v[50:53], v[8:23]
	v_mul_f32_e32 v3, v3, v4
	v_mul_f32_e32 v3, v6, v3
	v_mul_f32_e32 v4, v3, v2
	v_fma_f32 v3, -v3, v2, v2
	v_cmp_gt_f32_e32 vcc, 0, v2
	s_waitcnt vmcnt(0)
	v_lshlrev_b32_e32 v2, 16, v5
	v_mul_f32_e32 v5, v2, v2
	v_cndmask_b32_e32 v109, v3, v4, vcc
	v_fma_f32 v3, |v2|, s92, 1.0
	v_rcp_f32_e32 v3, v3
	v_mfma_f32_32x32x16_bf16 v[8:23], v[70:73], v[46:49], v[8:23]
	v_mul_f32_e32 v5, 0xbf38aa3b, v5
	v_exp_f32_e32 v5, v5
	v_fmamk_f32 v4, v3, 0x3f07dc22, v236
	v_fmaak_f32 v4, v3, v4, 0x3f35f0e3
	v_fmaak_f32 v4, v3, v4, 0xbe11a98e
	v_fmaak_f32 v4, v3, v4, 0x3e027906
	v_mul_f32_e32 v3, v3, v4
	v_mul_f32_e32 v3, v5, v3
	v_mul_f32_e32 v4, v3, v2
	v_fma_f32 v3, -v3, v2, v2
	v_cmp_gt_f32_e32 vcc, 0, v2
	v_mfma_f32_32x32x16_bf16 v[8:23], v[66:69], v[42:45], v[8:23]
	s_nop 0
	v_cndmask_b32_e32 v113, v3, v4, vcc
	global_load_dwordx4 v[2:5], v[92:93], off offset:-4096
	global_load_dwordx4 v[66:69], v[90:91], off offset:1024
	global_load_dwordx4 v[70:73], v[90:91], off offset:2048
	s_and_b64 vcc, exec, s[6:7]
	v_mfma_f32_32x32x16_bf16 v[8:23], v[62:65], v[38:41], v[8:23]
	global_load_dwordx4 v[62:65], v[90:91], off offset:3072
	global_load_dwordx4 v[74:77], v[92:93], off
	global_load_dwordx4 v[120:123], v[92:93], off offset:1024
	global_load_dwordx4 v[124:127], v[92:93], off offset:2048
	s_nop 0
	global_load_dwordx4 v[90:93], v[92:93], off offset:3072
	ds_read_b128 v[132:135], v94 offset:256
	v_mfma_f32_32x32x16_bf16 v[8:23], v[58:61], v[34:37], v[8:23]
	ds_read_b128 v[58:61], v94 offset:288
	s_waitcnt lgkmcnt(1)
	s_nop 9
	v_add_f32_e32 v6, v8, v132
	v_mul_f32_e32 v6, v83, v6
	v_cvt_pk_bf16_f32 v8, v6, s0
	v_lshlrev_b64 v[6:7], 11, v[130:131]
	v_lshl_add_u64 v[6:7], v[88:89], 0, v[6:7]
	global_store_short v[6:7], v8, off
	v_add_f32_e32 v6, v9, v133
	v_mul_f32_e32 v6, v95, v6
	v_or_b32_e32 v130, s5, v1
	v_cvt_pk_bf16_f32 v8, v6, s0
	v_lshlrev_b64 v[6:7], 11, v[130:131]
	v_lshl_add_u64 v[6:7], v[88:89], 0, v[6:7]
	global_store_short v[6:7], v8, off
	v_add_f32_e32 v6, v10, v134
	v_readlane_b32 s5, v252, 1
	v_mul_f32_e32 v6, v96, v6
	v_cvt_pk_bf16_f32 v8, v6, s0
	v_or_b32_e32 v130, s5, v1
	v_lshlrev_b64 v[6:7], 11, v[130:131]
	v_lshl_add_u64 v[6:7], v[88:89], 0, v[6:7]
	global_store_short v[6:7], v8, off
	v_add_f32_e32 v6, v11, v135
	v_readlane_b32 s5, v252, 2
	v_mul_f32_e32 v6, v98, v6
	v_cvt_pk_bf16_f32 v8, v6, s0
	v_or_b32_e32 v130, s5, v1
	v_lshlrev_b64 v[6:7], 11, v[130:131]
	v_lshl_add_u64 v[6:7], v[88:89], 0, v[6:7]
	global_store_short v[6:7], v8, off
	s_waitcnt lgkmcnt(0)
	v_add_f32_e32 v6, v12, v58
	v_readlane_b32 s5, v252, 3
	v_mul_f32_e32 v6, v100, v6
	v_cvt_pk_bf16_f32 v8, v6, s0
	v_or_b32_e32 v130, s5, v1
	v_lshlrev_b64 v[6:7], 11, v[130:131]
	v_lshl_add_u64 v[6:7], v[88:89], 0, v[6:7]
	global_store_short v[6:7], v8, off
	v_add_f32_e32 v6, v13, v59
	v_readlane_b32 s5, v252, 4
	v_mul_f32_e32 v6, v102, v6
	v_cvt_pk_bf16_f32 v8, v6, s0
	v_or_b32_e32 v130, s5, v1
	v_lshlrev_b64 v[6:7], 11, v[130:131]
	v_lshl_add_u64 v[6:7], v[88:89], 0, v[6:7]
	global_store_short v[6:7], v8, off
	v_add_f32_e32 v6, v14, v60
	v_readlane_b32 s5, v252, 5
	v_mul_f32_e32 v6, v104, v6
	v_cvt_pk_bf16_f32 v8, v6, s0
	v_or_b32_e32 v130, s5, v1
	v_lshlrev_b64 v[6:7], 11, v[130:131]
	v_lshl_add_u64 v[6:7], v[88:89], 0, v[6:7]
	global_store_short v[6:7], v8, off
	v_add_f32_e32 v6, v15, v61
	ds_read_b128 v[58:61], v94 offset:320
	ds_read_b128 v[102:105], v94 offset:352
	v_readlane_b32 s5, v252, 6
	v_mul_f32_e32 v6, v106, v6
	v_cvt_pk_bf16_f32 v8, v6, s0
	v_or_b32_e32 v130, s5, v1
	v_lshlrev_b64 v[6:7], 11, v[130:131]
	v_lshl_add_u64 v[6:7], v[88:89], 0, v[6:7]
	global_store_short v[6:7], v8, off
	s_waitcnt lgkmcnt(1)
	v_add_f32_e32 v6, v16, v58
	v_readlane_b32 s5, v252, 7
	v_mul_f32_e32 v6, v110, v6
	v_cvt_pk_bf16_f32 v8, v6, s0
	v_or_b32_e32 v130, s5, v1
	v_lshlrev_b64 v[6:7], 11, v[130:131]
	v_lshl_add_u64 v[6:7], v[88:89], 0, v[6:7]
	global_store_short v[6:7], v8, off
	v_add_f32_e32 v6, v17, v59
	v_mul_f32_e32 v58, v111, v6
	s_waitcnt vmcnt(16)
	v_mfma_f32_32x32x16_bf16 v[2:17], v[2:5], v[54:57], 0
	v_readlane_b32 s5, v252, 8
	v_add_f32_e32 v18, v18, v60
	v_mul_f32_e32 v18, v112, v18
	v_or_b32_e32 v130, s5, v1
	v_readlane_b32 s5, v252, 9
	v_lshlrev_b64 v[54:55], 11, v[130:131]
	v_cvt_pk_bf16_f32 v18, v18, s0
	s_waitcnt vmcnt(15)
	v_mfma_f32_32x32x16_bf16 v[2:17], v[66:69], v[50:53], v[2:17]
	v_or_b32_e32 v130, s5, v1
	v_lshlrev_b64 v[50:51], 11, v[130:131]
	v_lshl_add_u64 v[50:51], v[88:89], 0, v[50:51]
	global_store_short v[50:51], v18, off
	v_add_f32_e32 v18, v19, v61
	v_readlane_b32 s5, v252, 10
	v_mul_f32_e32 v18, v114, v18
	s_waitcnt vmcnt(15)
	v_mfma_f32_32x32x16_bf16 v[2:17], v[70:73], v[46:49], v[2:17]
	v_or_b32_e32 v130, s5, v1
	v_cvt_pk_bf16_f32 v46, v18, s0
	v_lshlrev_b64 v[18:19], 11, v[130:131]
	v_lshl_add_u64 v[18:19], v[88:89], 0, v[18:19]
	global_store_short v[18:19], v46, off
	s_waitcnt lgkmcnt(0)
	v_add_f32_e32 v18, v20, v102
	v_readlane_b32 s5, v252, 11
	s_waitcnt vmcnt(15)
	v_mfma_f32_32x32x16_bf16 v[2:17], v[62:65], v[42:45], v[2:17]
	v_mul_f32_e32 v18, v116, v18
	v_or_b32_e32 v130, s5, v1
	v_cvt_pk_bf16_f32 v20, v18, s0
	v_lshlrev_b64 v[18:19], 11, v[130:131]
	v_lshl_add_u64 v[18:19], v[88:89], 0, v[18:19]
	global_store_short v[18:19], v20, off
	v_add_f32_e32 v18, v21, v103
	s_waitcnt vmcnt(15)
	v_mfma_f32_32x32x16_bf16 v[2:17], v[74:77], v[38:41], v[2:17]
	v_readlane_b32 s5, v252, 12
	v_mul_f32_e32 v18, v118, v18
	v_cvt_pk_bf16_f32 v20, v18, s0
	v_or_b32_e32 v130, s5, v1
	v_lshlrev_b64 v[18:19], 11, v[130:131]
	v_lshl_add_u64 v[18:19], v[88:89], 0, v[18:19]
	global_store_short v[18:19], v20, off
	s_waitcnt vmcnt(15)
	v_mfma_f32_32x32x16_bf16 v[2:17], v[120:123], v[34:37], v[2:17]
	v_add_f32_e32 v18, v22, v104
	v_readlane_b32 s5, v252, 13
	v_mul_f32_e32 v18, v24, v18
	v_cvt_pk_bf16_f32 v20, v18, s0
	v_or_b32_e32 v130, s5, v1
	v_lshlrev_b64 v[18:19], 11, v[130:131]
	v_lshl_add_u64 v[18:19], v[88:89], 0, v[18:19]
	s_waitcnt vmcnt(14)
	v_mfma_f32_32x32x16_bf16 v[2:17], v[124:127], v[30:33], v[2:17]
	global_store_short v[18:19], v20, off
	v_add_f32_e32 v18, v23, v105
	v_readlane_b32 s5, v252, 14
	v_mul_f32_e32 v18, v25, v18
	v_cvt_pk_bf16_f32 v20, v18, s0
	v_or_b32_e32 v130, s5, v1
	v_lshlrev_b64 v[18:19], 11, v[130:131]
	v_cvt_pk_bf16_f32 v56, v58, s0
	v_lshl_add_u64 v[54:55], v[88:89], 0, v[54:55]
	v_lshl_add_u64 v[18:19], v[88:89], 0, v[18:19]
	s_waitcnt vmcnt(14)
	v_mfma_f32_32x32x16_bf16 v[2:17], v[90:93], v[26:29], v[2:17]
	global_store_short v[54:55], v56, off
	global_store_short v[18:19], v20, off
	ds_read_b128 v[18:21], v94 offset:384
	ds_read_b128 v[22:25], v94 offset:416
	v_readlane_b32 s5, v252, 15
	s_waitcnt lgkmcnt(1)
	s_nop 5
	v_add_f32_e32 v2, v2, v18
	v_or_b32_e32 v130, s5, v1
	v_mul_f32_e32 v2, v78, v2
	v_lshlrev_b64 v[26:27], 11, v[130:131]
	v_cvt_pk_bf16_f32 v2, v2, s0
	v_lshl_add_u64 v[26:27], v[88:89], 0, v[26:27]
	global_store_short v[26:27], v2, off
	v_add_f32_e32 v2, v3, v19
	v_readlane_b32 s5, v252, 16
	v_mul_f32_e32 v2, v79, v2
	v_cvt_pk_bf16_f32 v18, v2, s0
	v_or_b32_e32 v130, s5, v1
	v_lshlrev_b64 v[2:3], 11, v[130:131]
	v_lshl_add_u64 v[2:3], v[88:89], 0, v[2:3]
	global_store_short v[2:3], v18, off
	v_add_f32_e32 v2, v4, v20
	v_readlane_b32 s5, v252, 17
	v_mul_f32_e32 v2, v80, v2
	v_cvt_pk_bf16_f32 v4, v2, s0
	v_or_b32_e32 v130, s5, v1
	v_lshlrev_b64 v[2:3], 11, v[130:131]
	v_lshl_add_u64 v[2:3], v[88:89], 0, v[2:3]
	global_store_short v[2:3], v4, off
	v_add_f32_e32 v2, v5, v21
	v_readlane_b32 s5, v252, 18
	v_mul_f32_e32 v2, v81, v2
	v_cvt_pk_bf16_f32 v4, v2, s0
	v_or_b32_e32 v130, s5, v1
	v_lshlrev_b64 v[2:3], 11, v[130:131]
	v_lshl_add_u64 v[2:3], v[88:89], 0, v[2:3]
	global_store_short v[2:3], v4, off
	s_waitcnt lgkmcnt(0)
	v_add_f32_e32 v2, v6, v22
	v_readlane_b32 s5, v252, 19
	v_mul_f32_e32 v2, v86, v2
	v_cvt_pk_bf16_f32 v4, v2, s0
	v_or_b32_e32 v130, s5, v1
	v_lshlrev_b64 v[2:3], 11, v[130:131]
	v_lshl_add_u64 v[2:3], v[88:89], 0, v[2:3]
	global_store_short v[2:3], v4, off
	v_add_f32_e32 v2, v7, v23
	v_readlane_b32 s5, v252, 20
	v_mul_f32_e32 v2, v87, v2
	v_cvt_pk_bf16_f32 v4, v2, s0
	v_or_b32_e32 v130, s5, v1
	v_lshlrev_b64 v[2:3], 11, v[130:131]
	v_lshl_add_u64 v[2:3], v[88:89], 0, v[2:3]
	global_store_short v[2:3], v4, off
	v_add_f32_e32 v2, v8, v24
	v_readlane_b32 s5, v252, 21
	v_mul_f32_e32 v2, v97, v2
	v_cvt_pk_bf16_f32 v4, v2, s0
	v_or_b32_e32 v130, s5, v1
	v_lshlrev_b64 v[2:3], 11, v[130:131]
	v_lshl_add_u64 v[2:3], v[88:89], 0, v[2:3]
	global_store_short v[2:3], v4, off
	v_add_f32_e32 v2, v9, v25
	v_mul_f32_e32 v2, v99, v2
	v_cvt_pk_bf16_f32 v8, v2, s0
	ds_read_b128 v[2:5], v94 offset:448
	v_readlane_b32 s5, v252, 22
	s_nop 1
	v_or_b32_e32 v130, s5, v1
	v_lshlrev_b64 v[6:7], 11, v[130:131]
	v_lshl_add_u64 v[6:7], v[88:89], 0, v[6:7]
	v_readlane_b32 s5, v252, 23
	global_store_short v[6:7], v8, off
	ds_read_b128 v[6:9], v94 offset:480
	s_waitcnt lgkmcnt(1)
	v_add_f32_e32 v2, v10, v2
	v_or_b32_e32 v130, s5, v1
	v_mul_f32_e32 v2, v82, v2
	v_lshlrev_b64 v[18:19], 11, v[130:131]
	v_cvt_pk_bf16_f32 v2, v2, s0
	v_lshl_add_u64 v[18:19], v[88:89], 0, v[18:19]
	global_store_short v[18:19], v2, off
	v_add_f32_e32 v2, v11, v3
	v_readlane_b32 s5, v252, 24
	v_mul_f32_e32 v2, v84, v2
	v_cvt_pk_bf16_f32 v10, v2, s0
	v_or_b32_e32 v130, s5, v1
	v_lshlrev_b64 v[2:3], 11, v[130:131]
	v_lshl_add_u64 v[2:3], v[88:89], 0, v[2:3]
	global_store_short v[2:3], v10, off
	v_add_f32_e32 v2, v12, v4
	v_readlane_b32 s5, v252, 25
	v_mul_f32_e32 v2, v85, v2
	v_cvt_pk_bf16_f32 v4, v2, s0
	v_or_b32_e32 v130, s5, v1
	v_lshlrev_b64 v[2:3], 11, v[130:131]
	v_lshl_add_u64 v[2:3], v[88:89], 0, v[2:3]
	global_store_short v[2:3], v4, off
	v_add_f32_e32 v2, v13, v5
	v_readlane_b32 s5, v252, 26
	v_mul_f32_e32 v2, v101, v2
	v_cvt_pk_bf16_f32 v4, v2, s0
	v_or_b32_e32 v130, s5, v1
	v_lshlrev_b64 v[2:3], 11, v[130:131]
	v_lshl_add_u64 v[2:3], v[88:89], 0, v[2:3]
	global_store_short v[2:3], v4, off
	s_waitcnt lgkmcnt(0)
	v_add_f32_e32 v2, v14, v6
	v_readlane_b32 s5, v252, 27
	v_mul_f32_e32 v2, v107, v2
	v_cvt_pk_bf16_f32 v4, v2, s0
	v_or_b32_e32 v130, s5, v1
	v_lshlrev_b64 v[2:3], 11, v[130:131]
	v_lshl_add_u64 v[2:3], v[88:89], 0, v[2:3]
	global_store_short v[2:3], v4, off
	v_add_f32_e32 v2, v15, v7
	v_readlane_b32 s5, v252, 28
	v_mul_f32_e32 v2, v108, v2
	v_cvt_pk_bf16_f32 v4, v2, s0
	v_or_b32_e32 v130, s5, v1
	v_lshlrev_b64 v[2:3], 11, v[130:131]
	v_lshl_add_u64 v[2:3], v[88:89], 0, v[2:3]
	global_store_short v[2:3], v4, off
	v_add_f32_e32 v2, v16, v8
	v_readlane_b32 s5, v252, 29
	v_mul_f32_e32 v2, v109, v2
	v_cvt_pk_bf16_f32 v4, v2, s0
	v_or_b32_e32 v130, s5, v1
	v_lshlrev_b64 v[2:3], 11, v[130:131]
	v_lshl_add_u64 v[2:3], v[88:89], 0, v[2:3]
	global_store_short v[2:3], v4, off
	v_add_f32_e32 v2, v17, v9
	v_readlane_b32 s5, v252, 30
	v_mul_f32_e32 v2, v113, v2
	v_cvt_pk_bf16_f32 v4, v2, s0
	v_or_b32_e32 v130, s5, v1
	v_lshlrev_b64 v[2:3], 11, v[130:131]
	v_lshl_add_u64 v[2:3], v[88:89], 0, v[2:3]
	global_store_short v[2:3], v4, off
	s_barrier
	s_cbranch_vccz .LBB0_314
	v_readlane_b32 s6, v253, 48
	v_mov_b32_e32 v1, v242
	v_readlane_b32 s7, v253, 49
	s_andn2_b64 vcc, exec, s[6:7]
	v_readfirstlane_b32 s5, v1
	s_cbranch_vccnz .LBB0_313
	s_load_dwordx8 s[44:51], s[0:1], 0x38
	v_mov_b32_e32 v2, 2
	v_lshlrev_b32_sdwa v130, v2, v1 dst_sel:DWORD dst_unused:UNUSED_PAD src0_sel:DWORD src1_sel:BYTE_0
	v_readlane_b32 s8, v254, 39
	v_readlane_b32 s9, v254, 40
	s_waitcnt lgkmcnt(0)
	v_lshl_add_u64 v[2:3], s[44:45], 0, v[130:131]
	v_lshl_add_u64 v[4:5], v[2:3], 0, s[62:63]
	global_load_dword v42, v[4:5], off
	v_lshl_add_u64 v[4:5], v[2:3], 0, s[8:9]
	v_readlane_b32 s8, v254, 41
	v_readlane_b32 s9, v254, 42
	global_load_dword v43, v[4:5], off
	s_ashr_i32 s6, s5, 6
	v_lshl_add_u64 v[4:5], v[2:3], 0, s[8:9]
	v_readlane_b32 s8, v254, 43
	v_readlane_b32 s9, v254, 44
	global_load_dword v45, v[4:5], off
	v_mov_b32_e32 v10, s46
	v_lshl_add_u64 v[4:5], v[2:3], 0, s[8:9]
	v_readlane_b32 s8, v254, 45
	v_readlane_b32 s9, v254, 46
	global_load_dword v47, v[4:5], off
	v_mov_b32_e32 v11, s47
	v_lshl_add_u64 v[4:5], v[2:3], 0, s[8:9]
	v_readlane_b32 s8, v254, 47
	v_readlane_b32 s9, v254, 48
	global_load_dword v49, v[4:5], off
	v_readlane_b32 s57, v253, 32
	v_lshl_add_u64 v[4:5], v[2:3], 0, s[8:9]
	v_readlane_b32 s8, v254, 49
	v_readlane_b32 s9, v254, 50
	global_load_dword v51, v[4:5], off
	s_mov_b32 s58, s2
	v_lshl_add_u64 v[4:5], v[2:3], 0, s[8:9]
	v_readlane_b32 s8, v254, 51
	v_readlane_b32 s9, v254, 52
	global_load_dword v53, v[4:5], off
	s_waitcnt vmcnt(5)
	v_mov_b32_e32 v44, v43
	v_lshl_add_u64 v[4:5], v[2:3], 0, s[8:9]
	v_readlane_b32 s8, v254, 53
	v_readlane_b32 s9, v254, 54
	global_load_dword v55, v[4:5], off
	s_waitcnt vmcnt(5)
	v_mov_b32_e32 v46, v45
	v_lshl_add_u64 v[4:5], v[2:3], 0, s[8:9]
	v_readlane_b32 s8, v254, 55
	v_readlane_b32 s9, v254, 56
	global_load_dword v57, v[4:5], off
	s_waitcnt vmcnt(5)
	v_mov_b32_e32 v48, v47
	v_lshl_add_u64 v[4:5], v[2:3], 0, s[8:9]
	v_readlane_b32 s8, v254, 57
	v_readlane_b32 s9, v254, 58
	global_load_dword v59, v[4:5], off
	s_waitcnt vmcnt(5)
	v_mov_b32_e32 v50, v49
	v_lshl_add_u64 v[4:5], v[2:3], 0, s[8:9]
	v_readlane_b32 s8, v254, 59
	v_readlane_b32 s9, v254, 60
	global_load_dword v61, v[4:5], off
	s_waitcnt vmcnt(5)
	v_mov_b32_e32 v52, v51
	v_lshl_add_u64 v[4:5], v[2:3], 0, s[8:9]
	v_readlane_b32 s8, v254, 61
	v_readlane_b32 s9, v254, 62
	global_load_dword v63, v[4:5], off
	s_waitcnt vmcnt(5)
	v_mov_b32_e32 v54, v53
	v_lshl_add_u64 v[4:5], v[2:3], 0, s[8:9]
	v_readlane_b32 s8, v254, 63
	v_readlane_b32 s9, v255, 0
	global_load_dword v65, v[4:5], off
	s_waitcnt vmcnt(5)
	v_mov_b32_e32 v56, v55
	v_lshl_add_u64 v[4:5], v[2:3], 0, s[8:9]
	v_readlane_b32 s8, v255, 1
	v_readlane_b32 s9, v255, 2
	global_load_dword v67, v[4:5], off
	s_waitcnt vmcnt(5)
	v_mov_b32_e32 v58, v57
	v_lshl_add_u64 v[4:5], v[2:3], 0, s[8:9]
	v_readlane_b32 s8, v255, 3
	v_readlane_b32 s9, v255, 4
	global_load_dword v69, v[4:5], off
	s_waitcnt vmcnt(5)
	v_mov_b32_e32 v60, v59
	v_lshl_add_u64 v[4:5], v[2:3], 0, s[8:9]
	v_readlane_b32 s8, v255, 5
	v_readlane_b32 s9, v255, 6
	global_load_dword v71, v[4:5], off
	s_waitcnt vmcnt(5)
	v_mov_b32_e32 v62, v61
	v_lshl_add_u64 v[4:5], v[2:3], 0, s[8:9]
	v_readlane_b32 s8, v255, 7
	v_readlane_b32 s9, v255, 8
	global_load_dword v73, v[4:5], off
	s_waitcnt vmcnt(5)
	v_mov_b32_e32 v64, v63
	v_lshl_add_u64 v[4:5], v[2:3], 0, s[8:9]
	v_readlane_b32 s8, v255, 9
	v_readlane_b32 s9, v255, 10
	global_load_dword v75, v[4:5], off
	s_waitcnt vmcnt(5)
	v_mov_b32_e32 v66, v65
	v_lshl_add_u64 v[4:5], v[2:3], 0, s[8:9]
	v_readlane_b32 s8, v255, 11
	v_readlane_b32 s9, v255, 12
	global_load_dword v77, v[4:5], off
	s_waitcnt vmcnt(5)
	v_mov_b32_e32 v68, v67
	v_lshl_add_u64 v[4:5], v[2:3], 0, s[8:9]
	v_readlane_b32 s8, v255, 13
	v_readlane_b32 s9, v255, 14
	global_load_dword v79, v[4:5], off
	s_waitcnt vmcnt(5)
	v_mov_b32_e32 v70, v69
	v_lshl_add_u64 v[4:5], v[2:3], 0, s[8:9]
	v_readlane_b32 s8, v255, 15
	v_readlane_b32 s9, v255, 16
	global_load_dword v81, v[4:5], off
	s_waitcnt vmcnt(5)
	v_mov_b32_e32 v72, v71
	v_lshl_add_u64 v[4:5], v[2:3], 0, s[8:9]
	v_readlane_b32 s8, v255, 17
	v_readlane_b32 s9, v255, 18
	global_load_dword v83, v[4:5], off
	s_waitcnt vmcnt(5)
	v_mov_b32_e32 v74, v73
	v_lshl_add_u64 v[4:5], v[2:3], 0, s[8:9]
	v_readlane_b32 s8, v255, 19
	v_readlane_b32 s9, v255, 20
	global_load_dword v85, v[4:5], off
	s_waitcnt vmcnt(5)
	v_mov_b32_e32 v76, v75
	v_lshl_add_u64 v[4:5], v[2:3], 0, s[8:9]
	v_readlane_b32 s8, v255, 21
	v_readlane_b32 s9, v255, 22
	global_load_dword v87, v[4:5], off
	s_waitcnt vmcnt(5)
	v_mov_b32_e32 v78, v77
	v_lshl_add_u64 v[4:5], v[2:3], 0, s[8:9]
	v_readlane_b32 s8, v254, 37
	v_readlane_b32 s9, v254, 38
	global_load_dword v89, v[4:5], off
	s_waitcnt vmcnt(5)
	v_mov_b32_e32 v80, v79
	v_lshl_add_u64 v[4:5], v[2:3], 0, s[8:9]
	v_readlane_b32 s8, v254, 35
	v_readlane_b32 s9, v254, 36
	global_load_dword v91, v[4:5], off
	s_waitcnt vmcnt(5)
	v_mov_b32_e32 v82, v81
	v_lshl_add_u64 v[4:5], v[2:3], 0, s[8:9]
	v_readlane_b32 s8, v255, 23
	v_readlane_b32 s9, v255, 24
	global_load_dword v93, v[4:5], off
	s_waitcnt vmcnt(5)
	v_mov_b32_e32 v84, v83
	v_lshl_add_u64 v[4:5], v[2:3], 0, s[8:9]
	global_load_dword v95, v[4:5], off
	v_lshl_add_u64 v[4:5], v[2:3], 0, s[68:69]
	s_lshl_b64 s[8:9], s[84:85], 2
	global_load_dword v97, v[4:5], off
	v_lshl_add_u64 v[4:5], v[2:3], 0, s[94:95]
	v_lshl_add_u64 v[2:3], v[2:3], 0, s[88:89]
	s_add_u32 s10, s48, s8
	global_load_dword v99, v[4:5], off
	global_load_dword v101, v[2:3], off
	s_addc_u32 s11, s49, s9
	v_lshlrev_b32_e32 v2, 2, v1
	v_and_b32_e32 v12, 0xfc, v2
	s_add_u32 s8, s50, s8
	v_lshlrev_b32_e32 v6, 2, v12
	s_addc_u32 s9, s51, s9
	s_min_i32 s5, s6, 5
	global_load_dwordx4 v[2:5], v6, s[10:11]
	s_addk_i32 s5, 0x58
	v_readlane_b32 s10, v250, 29
	s_add_i32 s7, s5, s10
	v_lshlrev_b32_e32 v130, 1, v12
	s_max_i32 s7, s7, 0
	v_readlane_b32 s11, v250, 30
	s_min_i32 s40, s6, 13
	v_lshl_add_u64 v[102:103], s[80:81], 0, v[130:131]
	s_add_i32 s7, s7, s11
	s_addk_i32 s40, 0x50
	global_load_dwordx4 v[6:9], v6, s[8:9]
	v_mad_u64_u32 v[12:13], s[8:9], s7, v238, v[102:103]
	s_add_i32 s7, s40, s10
	s_max_i32 s7, s7, 0
	s_min_i32 s41, s6, 21
	s_add_i32 s7, s7, s11
	s_addk_i32 s41, 0x48
	global_load_dwordx2 v[106:107], v[12:13], off offset:1536
	global_load_dwordx2 v[104:105], v[12:13], off offset:1024
	v_mad_u64_u32 v[12:13], s[8:9], s7, v238, v[102:103]
	s_add_i32 s7, s41, s10
	s_max_i32 s7, s7, 0
	s_min_i32 s44, s6, 29
	s_add_i32 s7, s7, s11
	s_add_i32 s44, s44, 64
	global_load_dwordx2 v[112:113], v[12:13], off offset:1536
	global_load_dwordx2 v[110:111], v[12:13], off offset:1024
	v_mad_u64_u32 v[12:13], s[8:9], s7, v238, v[102:103]
	s_add_i32 s7, s44, s10
	s_max_i32 s7, s7, 0
	s_min_i32 s45, s6, 37
	s_add_i32 s7, s7, s11
	s_add_i32 s45, s45, 56
	global_load_dwordx2 v[116:117], v[12:13], off offset:1536
	global_load_dwordx2 v[114:115], v[12:13], off offset:1024
	v_mad_u64_u32 v[12:13], s[8:9], s7, v238, v[102:103]
	s_add_i32 s7, s45, s10
	s_max_i32 s7, s7, 0
	s_min_i32 s46, s6, 45
	s_add_i32 s7, s7, s11
	s_add_i32 s46, s46, 48
	global_load_dwordx2 v[120:121], v[12:13], off offset:1536
	global_load_dwordx2 v[118:119], v[12:13], off offset:1024
	v_mad_u64_u32 v[12:13], s[8:9], s7, v238, v[102:103]
	s_add_i32 s7, s46, s10
	s_max_i32 s7, s7, 0
	s_min_i32 s47, s6, 53
	s_add_i32 s7, s7, s11
	s_add_i32 s47, s47, 40
	global_load_dwordx2 v[124:125], v[12:13], off offset:1536
	global_load_dwordx2 v[122:123], v[12:13], off offset:1024
	v_mad_u64_u32 v[12:13], s[8:9], s7, v238, v[102:103]
	s_add_i32 s7, s47, s10
	s_max_i32 s7, s7, 0
	s_min_i32 s48, s6, 61
	s_add_i32 s7, s7, s11
	s_add_i32 s48, s48, 32
	global_load_dwordx2 v[128:129], v[12:13], off offset:1536
	global_load_dwordx2 v[126:127], v[12:13], off offset:1024
	v_mad_u64_u32 v[12:13], s[8:9], s7, v238, v[102:103]
	s_add_i32 s7, s48, s10
	s_max_i32 s7, s7, 0
	s_min_i32 s49, s6, 0x45
	s_add_i32 s7, s7, s11
	s_add_i32 s49, s49, 24
	global_load_dwordx2 v[134:135], v[12:13], off offset:1536
	global_load_dwordx2 v[132:133], v[12:13], off offset:1024
	v_mad_u64_u32 v[12:13], s[8:9], s7, v238, v[102:103]
	s_add_i32 s7, s49, s10
	s_max_i32 s7, s7, 0
	s_min_i32 s50, s6, 0x4d
	s_add_i32 s7, s7, s11
	s_add_i32 s50, s50, 16
	global_load_dwordx2 v[138:139], v[12:13], off offset:1536
	global_load_dwordx2 v[136:137], v[12:13], off offset:1024
	v_mad_u64_u32 v[12:13], s[8:9], s7, v238, v[102:103]
	s_add_i32 s7, s50, s10
	s_max_i32 s7, s7, 0
	s_min_i32 s51, s6, 0x55
	s_add_i32 s7, s7, s11
	s_add_i32 s51, s51, 8
	global_load_dwordx2 v[142:143], v[12:13], off offset:1536
	global_load_dwordx2 v[140:141], v[12:13], off offset:1024
	v_mad_u64_u32 v[12:13], s[8:9], s7, v238, v[102:103]
	s_add_i32 s7, s51, s10
	s_min_i32 s56, s6, 0x5d
	s_max_i32 s7, s7, 0
	s_add_i32 s6, s56, s10
	s_add_i32 s7, s7, s11
	s_max_i32 s6, s6, 0
	global_load_dwordx2 v[146:147], v[12:13], off offset:1536
	global_load_dwordx2 v[144:145], v[12:13], off offset:1024
	v_mad_u64_u32 v[12:13], s[8:9], s7, v238, v[102:103]
	s_add_i32 s6, s6, s11
	global_load_dwordx2 v[150:151], v[12:13], off offset:1536
	global_load_dwordx2 v[148:149], v[12:13], off offset:1024
	v_mad_u64_u32 v[12:13], s[6:7], s6, v238, v[102:103]
	global_load_dwordx2 v[154:155], v[12:13], off offset:1536
	global_load_dwordx2 v[152:153], v[12:13], off offset:1024
	v_or_b32_sdwa v12, v1, s84 dst_sel:DWORD dst_unused:UNUSED_PAD src0_sel:BYTE_0 src1_sel:DWORD
	v_ashrrev_i32_e32 v13, 31, v12
	v_lshl_add_u64 v[10:11], v[12:13], 2, v[10:11]
	global_load_dword v108, v[10:11], off
	s_waitcnt vmcnt(35)
	v_mov_b32_e32 v86, v85
	s_waitcnt vmcnt(34)
	v_mov_b32_e32 v88, v87
	s_waitcnt vmcnt(33)
	v_mov_b32_e32 v90, v89
	s_waitcnt vmcnt(32)
	v_mov_b32_e32 v92, v91
	s_waitcnt vmcnt(31)
	v_mov_b32_e32 v94, v93
	s_waitcnt vmcnt(30)
	v_mov_b32_e32 v96, v95
	s_waitcnt vmcnt(29)
	v_mov_b32_e32 v98, v97
	s_waitcnt vmcnt(28)
	v_mov_b32_e32 v100, v99
	s_branch .LBB0_289
.LBB0_288:
	s_add_i32 s59, s58, 0xffffff80
	s_cmpk_lt_i32 s59, 0x100
	s_cselect_b32 s7, s58, s59
	s_lshl_b32 s7, s7, 6
	s_and_b32 s8, s7, 0xfc0
	s_sub_i32 s10, s8, 30
	s_add_i32 s8, s10, s56
	s_and_b32 s7, s7, 0xfffff000
	s_max_i32 s8, s8, 0
	s_add_i32 s8, s8, s7
	v_and_b32_e32 v14, 0xff, v10
	v_mad_i64_i32 v[10:11], s[8:9], s8, v238, v[102:103]
	s_add_i32 s8, s10, s51
	s_max_i32 s8, s8, 0
	s_add_i32 s8, s8, s7
	v_mad_i64_i32 v[12:13], s[8:9], s8, v238, v[102:103]
	s_add_i32 s8, s10, s50
	s_max_i32 s8, s8, 0
	s_add_i32 s8, s8, s7
	s_waitcnt lgkmcnt(0)
	s_barrier
	global_load_dwordx2 v[152:153], v[10:11], off offset:1024
	global_load_dwordx2 v[154:155], v[10:11], off offset:1536
	global_load_dwordx2 v[148:149], v[12:13], off offset:1024
	global_load_dwordx2 v[150:151], v[12:13], off offset:1536
	v_mad_i64_i32 v[10:11], s[8:9], s8, v238, v[102:103]
	s_add_i32 s8, s10, s49
	s_max_i32 s8, s8, 0
	s_add_i32 s8, s8, s7
	v_mad_i64_i32 v[12:13], s[8:9], s8, v238, v[102:103]
	s_add_i32 s8, s10, s48
	s_max_i32 s8, s8, 0
	s_add_i32 s8, s8, s7
	global_load_dwordx2 v[144:145], v[10:11], off offset:1024
	global_load_dwordx2 v[146:147], v[10:11], off offset:1536
	global_load_dwordx2 v[140:141], v[12:13], off offset:1024
	global_load_dwordx2 v[142:143], v[12:13], off offset:1536
	v_mad_i64_i32 v[10:11], s[8:9], s8, v238, v[102:103]
	s_add_i32 s8, s10, s47
	s_max_i32 s8, s8, 0
	s_add_i32 s8, s8, s7
	v_mad_i64_i32 v[12:13], s[8:9], s8, v238, v[102:103]
	s_add_i32 s8, s10, s46
	s_max_i32 s8, s8, 0
	s_add_i32 s8, s8, s7
	global_load_dwordx2 v[136:137], v[10:11], off offset:1024
	global_load_dwordx2 v[138:139], v[10:11], off offset:1536
	global_load_dwordx2 v[132:133], v[12:13], off offset:1024
	global_load_dwordx2 v[134:135], v[12:13], off offset:1536
	v_mad_i64_i32 v[10:11], s[8:9], s8, v238, v[102:103]
	s_add_i32 s8, s10, s45
	s_max_i32 s8, s8, 0
	s_add_i32 s8, s8, s7
	v_mad_i64_i32 v[12:13], s[8:9], s8, v238, v[102:103]
	s_add_i32 s8, s10, s44
	s_max_i32 s8, s8, 0
	s_add_i32 s8, s8, s7
	global_load_dwordx2 v[126:127], v[10:11], off offset:1024
	global_load_dwordx2 v[128:129], v[10:11], off offset:1536
	global_load_dwordx2 v[122:123], v[12:13], off offset:1024
	global_load_dwordx2 v[124:125], v[12:13], off offset:1536
	v_mad_i64_i32 v[10:11], s[8:9], s8, v238, v[102:103]
	s_add_i32 s8, s10, s41
	s_max_i32 s8, s8, 0
	s_add_i32 s8, s8, s7
	v_mad_i64_i32 v[12:13], s[8:9], s8, v238, v[102:103]
	s_add_i32 s8, s10, s40
	s_max_i32 s8, s8, 0
	s_add_i32 s8, s8, s7
	global_load_dwordx2 v[118:119], v[10:11], off offset:1024
	global_load_dwordx2 v[120:121], v[10:11], off offset:1536
	global_load_dwordx2 v[114:115], v[12:13], off offset:1024
	global_load_dwordx2 v[116:117], v[12:13], off offset:1536
	v_mad_i64_i32 v[10:11], s[8:9], s8, v238, v[102:103]
	s_add_i32 s10, s10, s5
	s_lshl_b32 s6, s6, 7
	s_max_i32 s8, s10, 0
	s_and_b32 s6, s6, 0xffff8000
	s_add_i32 s8, s8, s7
	s_add_i32 s6, s6, 0
	v_mad_i64_i32 v[12:13], s[8:9], s8, v238, v[102:103]
	v_lshl_add_u32 v163, v14, 2, s6
	global_load_dwordx2 v[110:111], v[10:11], off offset:1024
	global_load_dwordx2 v[112:113], v[10:11], off offset:1536
	global_load_dwordx2 v[104:105], v[12:13], off offset:1024
	global_load_dwordx2 v[106:107], v[12:13], off offset:1536
	ds_read2st64_b32 v[26:27], v163 offset1:4
	ds_read2st64_b32 v[28:29], v163 offset0:8 offset1:12
	ds_read2st64_b32 v[30:31], v163 offset0:16 offset1:20
	ds_read2st64_b32 v[32:33], v163 offset0:24 offset1:28
	ds_read2st64_b32 v[160:161], v163 offset0:32 offset1:36
	ds_read2st64_b32 v[158:159], v163 offset0:40 offset1:44
	ds_read2st64_b32 v[156:157], v163 offset0:48 offset1:52
	ds_read2st64_b32 v[40:41], v163 offset0:56 offset1:60
	ds_read2st64_b32 v[38:39], v163 offset0:64 offset1:68
	ds_read2st64_b32 v[36:37], v163 offset0:72 offset1:76
	ds_read2st64_b32 v[34:35], v163 offset0:80 offset1:84
	ds_read2st64_b32 v[24:25], v163 offset0:88 offset1:92
	ds_read2st64_b32 v[22:23], v163 offset0:96 offset1:100
	ds_read2st64_b32 v[20:21], v163 offset0:104 offset1:108
	ds_read2st64_b32 v[10:11], v163 offset0:120 offset1:124
	ds_read2st64_b32 v[18:19], v163 offset0:112 offset1:116
	ds_read2st64_b32 v[12:13], v163 offset0:128 offset1:132
	ds_read2st64_b32 v[14:15], v163 offset0:136 offset1:140
	ds_read2st64_b32 v[16:17], v163 offset0:144 offset1:148
	s_waitcnt vmcnt(51) lgkmcnt(4)
	v_mul_f32_e32 v109, v101, v10
	v_mul_f32_e32 v165, v42, v27
	s_waitcnt vmcnt(24)
	v_mov_b32_e32 v164, v108
	v_pk_fma_f32 v[26:27], v[42:43], v[26:27], v[108:109]
	v_pk_fma_f32 v[164:165], v[44:45], v[28:29], v[164:165]
	v_pk_fma_f32 v[26:27], v[46:47], v[28:29], v[26:27]
	v_pk_fma_f32 v[164:165], v[48:49], v[30:31], v[164:165]
	v_pk_fma_f32 v[26:27], v[50:51], v[30:31], v[26:27]
	v_pk_fma_f32 v[164:165], v[52:53], v[32:33], v[164:165]
	v_pk_fma_f32 v[26:27], v[54:55], v[32:33], v[26:27]
	v_pk_fma_f32 v[164:165], v[56:57], v[160:161], v[164:165]
	v_pk_fma_f32 v[26:27], v[58:59], v[160:161], v[26:27]
	v_pk_fma_f32 v[164:165], v[60:61], v[158:159], v[164:165]
	v_pk_fma_f32 v[26:27], v[62:63], v[158:159], v[26:27]
	v_pk_fma_f32 v[164:165], v[64:65], v[156:157], v[164:165]
	v_pk_fma_f32 v[26:27], v[66:67], v[156:157], v[26:27]
	v_pk_fma_f32 v[164:165], v[68:69], v[40:41], v[164:165]
	v_pk_fma_f32 v[26:27], v[70:71], v[40:41], v[26:27]
	v_pk_fma_f32 v[164:165], v[72:73], v[38:39], v[164:165]
	v_pk_fma_f32 v[26:27], v[74:75], v[38:39], v[26:27]
	v_pk_fma_f32 v[164:165], v[76:77], v[36:37], v[164:165]
	v_pk_fma_f32 v[26:27], v[78:79], v[36:37], v[26:27]
	v_pk_fma_f32 v[164:165], v[80:81], v[34:35], v[164:165]
	v_pk_fma_f32 v[26:27], v[82:83], v[34:35], v[26:27]
	v_pk_fma_f32 v[164:165], v[84:85], v[24:25], v[164:165]
	v_pk_fma_f32 v[26:27], v[86:87], v[24:25], v[26:27]
	v_pk_fma_f32 v[164:165], v[88:89], v[22:23], v[164:165]
	v_pk_fma_f32 v[26:27], v[90:91], v[22:23], v[26:27]
	v_pk_fma_f32 v[164:165], v[92:93], v[20:21], v[164:165]
	v_pk_fma_f32 v[26:27], v[94:95], v[20:21], v[26:27]
	s_waitcnt lgkmcnt(3)
	v_pk_fma_f32 v[164:165], v[96:97], v[18:19], v[164:165]
	v_pk_fma_f32 v[26:27], v[98:99], v[18:19], v[26:27]
	v_pk_fma_f32 v[166:167], v[100:101], v[10:11], v[164:165]
	v_add_f32_e32 v164, v26, v27
	v_mul_f32_e32 v27, v42, v29
	v_mov_b32_e32 v26, v108
	v_pk_fma_f32 v[26:27], v[44:45], v[30:31], v[26:27]
	v_add_f32_e32 v165, v166, v167
	v_pk_fma_f32 v[26:27], v[48:49], v[32:33], v[26:27]
	s_waitcnt lgkmcnt(2)
	v_mul_f32_e32 v109, v101, v12
	v_pk_fma_f32 v[26:27], v[52:53], v[160:161], v[26:27]
	v_pk_fma_f32 v[28:29], v[42:43], v[28:29], v[108:109]
	v_pk_fma_f32 v[26:27], v[56:57], v[158:159], v[26:27]
	v_pk_fma_f32 v[28:29], v[46:47], v[30:31], v[28:29]
	v_pk_fma_f32 v[26:27], v[60:61], v[156:157], v[26:27]
	v_pk_fma_f32 v[28:29], v[50:51], v[32:33], v[28:29]
	v_pk_fma_f32 v[26:27], v[64:65], v[40:41], v[26:27]
	v_pk_fma_f32 v[28:29], v[54:55], v[160:161], v[28:29]
	v_pk_fma_f32 v[26:27], v[68:69], v[38:39], v[26:27]
	v_pk_fma_f32 v[28:29], v[58:59], v[158:159], v[28:29]
	v_pk_fma_f32 v[26:27], v[72:73], v[36:37], v[26:27]
	v_pk_fma_f32 v[28:29], v[62:63], v[156:157], v[28:29]
	v_pk_fma_f32 v[26:27], v[76:77], v[34:35], v[26:27]
	v_pk_fma_f32 v[28:29], v[66:67], v[40:41], v[28:29]
	v_pk_fma_f32 v[26:27], v[80:81], v[24:25], v[26:27]
	v_pk_fma_f32 v[28:29], v[70:71], v[38:39], v[28:29]
	v_pk_fma_f32 v[26:27], v[84:85], v[22:23], v[26:27]
	v_pk_fma_f32 v[28:29], v[74:75], v[36:37], v[28:29]
	v_pk_fma_f32 v[26:27], v[88:89], v[20:21], v[26:27]
	v_pk_fma_f32 v[28:29], v[78:79], v[34:35], v[28:29]
	v_pk_fma_f32 v[26:27], v[92:93], v[18:19], v[26:27]
	v_pk_fma_f32 v[28:29], v[82:83], v[24:25], v[28:29]
	v_pk_fma_f32 v[26:27], v[96:97], v[10:11], v[26:27]
	v_pk_fma_f32 v[28:29], v[86:87], v[22:23], v[28:29]
	v_pk_fma_f32 v[26:27], v[100:101], v[12:13], v[26:27]
	v_pk_fma_f32 v[28:29], v[90:91], v[20:21], v[28:29]
	v_add_f32_e32 v167, v26, v27
	v_mul_f32_e32 v27, v42, v31
	v_mov_b32_e32 v26, v108
	v_pk_fma_f32 v[26:27], v[44:45], v[32:33], v[26:27]
	v_pk_fma_f32 v[28:29], v[94:95], v[18:19], v[28:29]
	v_pk_fma_f32 v[26:27], v[48:49], v[160:161], v[26:27]
	v_pk_fma_f32 v[28:29], v[98:99], v[10:11], v[28:29]
	v_pk_fma_f32 v[26:27], v[52:53], v[158:159], v[26:27]
	s_waitcnt lgkmcnt(1)
	v_mul_f32_e32 v109, v101, v14
	v_pk_fma_f32 v[26:27], v[56:57], v[156:157], v[26:27]
	v_add_f32_e32 v166, v28, v29
	v_pk_fma_f32 v[26:27], v[60:61], v[40:41], v[26:27]
	v_pk_fma_f32 v[28:29], v[42:43], v[30:31], v[108:109]
	v_pk_fma_f32 v[26:27], v[64:65], v[38:39], v[26:27]
	v_pk_fma_f32 v[28:29], v[46:47], v[32:33], v[28:29]
	v_pk_fma_f32 v[26:27], v[68:69], v[36:37], v[26:27]
	v_pk_fma_f32 v[28:29], v[50:51], v[160:161], v[28:29]
	v_pk_fma_f32 v[26:27], v[72:73], v[34:35], v[26:27]
	v_pk_fma_f32 v[28:29], v[54:55], v[158:159], v[28:29]
	v_pk_fma_f32 v[26:27], v[76:77], v[24:25], v[26:27]
	v_pk_fma_f32 v[28:29], v[58:59], v[156:157], v[28:29]
	v_pk_fma_f32 v[26:27], v[80:81], v[22:23], v[26:27]
	v_pk_fma_f32 v[28:29], v[62:63], v[40:41], v[28:29]
	v_pk_fma_f32 v[26:27], v[84:85], v[20:21], v[26:27]
	v_pk_fma_f32 v[28:29], v[66:67], v[38:39], v[28:29]
	v_pk_fma_f32 v[26:27], v[88:89], v[18:19], v[26:27]
	v_pk_fma_f32 v[28:29], v[70:71], v[36:37], v[28:29]
	v_pk_fma_f32 v[26:27], v[92:93], v[10:11], v[26:27]
	v_pk_fma_f32 v[28:29], v[74:75], v[34:35], v[28:29]
	v_pk_fma_f32 v[26:27], v[96:97], v[12:13], v[26:27]
	v_pk_fma_f32 v[28:29], v[78:79], v[24:25], v[28:29]
	v_pk_fma_f32 v[26:27], v[100:101], v[14:15], v[26:27]
	v_pk_fma_f32 v[28:29], v[82:83], v[22:23], v[28:29]
	v_add_f32_e32 v169, v26, v27
	v_mul_f32_e32 v27, v42, v33
	v_mov_b32_e32 v26, v108
	v_pk_fma_f32 v[26:27], v[44:45], v[160:161], v[26:27]
	v_pk_fma_f32 v[28:29], v[86:87], v[20:21], v[28:29]
	v_pk_fma_f32 v[26:27], v[48:49], v[158:159], v[26:27]
	v_pk_fma_f32 v[28:29], v[90:91], v[18:19], v[28:29]
	v_pk_fma_f32 v[26:27], v[52:53], v[156:157], v[26:27]
	v_pk_fma_f32 v[28:29], v[94:95], v[10:11], v[28:29]
	v_pk_fma_f32 v[26:27], v[56:57], v[40:41], v[26:27]
	v_pk_fma_f32 v[28:29], v[98:99], v[12:13], v[28:29]
	v_pk_fma_f32 v[26:27], v[60:61], v[38:39], v[26:27]
	s_waitcnt lgkmcnt(0)
	v_mul_f32_e32 v109, v101, v16
	v_pk_fma_f32 v[26:27], v[64:65], v[36:37], v[26:27]
	v_add_f32_e32 v168, v28, v29
	v_pk_fma_f32 v[26:27], v[68:69], v[34:35], v[26:27]
	v_pk_fma_f32 v[28:29], v[42:43], v[32:33], v[108:109]
	v_pk_fma_f32 v[26:27], v[72:73], v[24:25], v[26:27]
	v_pk_fma_f32 v[28:29], v[46:47], v[160:161], v[28:29]
	v_pk_fma_f32 v[26:27], v[76:77], v[22:23], v[26:27]
	v_pk_fma_f32 v[28:29], v[50:51], v[158:159], v[28:29]
	v_pk_fma_f32 v[26:27], v[80:81], v[20:21], v[26:27]
	v_pk_fma_f32 v[28:29], v[54:55], v[156:157], v[28:29]
	v_pk_fma_f32 v[26:27], v[84:85], v[18:19], v[26:27]
	v_pk_fma_f32 v[28:29], v[58:59], v[40:41], v[28:29]
	v_pk_fma_f32 v[26:27], v[88:89], v[10:11], v[26:27]
	v_mul_f32_e32 v173, v42, v161
	v_pk_fma_f32 v[26:27], v[92:93], v[12:13], v[26:27]
	v_pk_fma_f32 v[28:29], v[62:63], v[38:39], v[28:29]
	v_pk_fma_f32 v[26:27], v[96:97], v[14:15], v[26:27]
	v_pk_fma_f32 v[28:29], v[66:67], v[36:37], v[28:29]
	v_pk_fma_f32 v[30:31], v[100:101], v[16:17], v[26:27]
	ds_read2st64_b32 v[26:27], v163 offset0:152 offset1:156
	v_pk_fma_f32 v[28:29], v[70:71], v[34:35], v[28:29]
	v_add_f32_e32 v171, v30, v31
	v_pk_fma_f32 v[28:29], v[74:75], v[24:25], v[28:29]
	v_mov_b32_e32 v172, v108
	s_waitcnt lgkmcnt(0)
	v_mul_f32_e32 v109, v101, v26
	v_pk_fma_f32 v[160:161], v[42:43], v[160:161], v[108:109]
	v_pk_fma_f32 v[28:29], v[78:79], v[22:23], v[28:29]
	v_pk_fma_f32 v[160:161], v[46:47], v[158:159], v[160:161]
	v_pk_fma_f32 v[28:29], v[82:83], v[20:21], v[28:29]
	v_pk_fma_f32 v[160:161], v[50:51], v[156:157], v[160:161]
	v_pk_fma_f32 v[28:29], v[86:87], v[18:19], v[28:29]
	v_pk_fma_f32 v[160:161], v[54:55], v[40:41], v[160:161]
	v_pk_fma_f32 v[28:29], v[90:91], v[10:11], v[28:29]
	v_pk_fma_f32 v[160:161], v[58:59], v[38:39], v[160:161]
	v_pk_fma_f32 v[28:29], v[94:95], v[12:13], v[28:29]
	v_pk_fma_f32 v[160:161], v[62:63], v[36:37], v[160:161]
	v_pk_fma_f32 v[28:29], v[98:99], v[14:15], v[28:29]
	v_pk_fma_f32 v[160:161], v[66:67], v[34:35], v[160:161]
	v_add_f32_e32 v170, v28, v29
	v_pk_fma_f32 v[160:161], v[70:71], v[24:25], v[160:161]
	ds_read2st64_b32 v[28:29], v163 offset0:160 offset1:164
	ds_read2st64_b32 v[30:31], v163 offset0:168 offset1:172
	ds_read2st64_b32 v[32:33], v163 offset0:176 offset1:180
	v_pk_fma_f32 v[160:161], v[74:75], v[22:23], v[160:161]
	v_pk_fma_f32 v[172:173], v[44:45], v[158:159], v[172:173]
	v_pk_fma_f32 v[160:161], v[78:79], v[20:21], v[160:161]
	s_waitcnt lgkmcnt(2)
	v_mul_f32_e32 v109, v101, v28
	v_pk_fma_f32 v[160:161], v[82:83], v[18:19], v[160:161]
	v_pk_fma_f32 v[172:173], v[48:49], v[156:157], v[172:173]
	v_pk_fma_f32 v[160:161], v[86:87], v[10:11], v[160:161]
	v_pk_fma_f32 v[172:173], v[52:53], v[40:41], v[172:173]
	v_pk_fma_f32 v[160:161], v[90:91], v[12:13], v[160:161]
	v_pk_fma_f32 v[172:173], v[56:57], v[38:39], v[172:173]
	v_pk_fma_f32 v[160:161], v[94:95], v[14:15], v[160:161]
	v_pk_fma_f32 v[172:173], v[60:61], v[36:37], v[172:173]
	v_pk_fma_f32 v[160:161], v[98:99], v[16:17], v[160:161]
	v_pk_fma_f32 v[172:173], v[64:65], v[34:35], v[172:173]
	v_add_f32_e32 v174, v160, v161
	v_mul_f32_e32 v161, v42, v159
	v_pk_fma_f32 v[158:159], v[42:43], v[158:159], v[108:109]
	v_mov_b32_e32 v160, v108
	v_pk_fma_f32 v[158:159], v[46:47], v[156:157], v[158:159]
	s_waitcnt lgkmcnt(1)
	v_mul_f32_e32 v109, v101, v30
	v_pk_fma_f32 v[158:159], v[50:51], v[40:41], v[158:159]
	v_pk_fma_f32 v[160:161], v[44:45], v[156:157], v[160:161]
	v_pk_fma_f32 v[158:159], v[54:55], v[38:39], v[158:159]
	v_pk_fma_f32 v[160:161], v[48:49], v[40:41], v[160:161]
	v_pk_fma_f32 v[158:159], v[58:59], v[36:37], v[158:159]
	v_pk_fma_f32 v[172:173], v[68:69], v[24:25], v[172:173]
	v_pk_fma_f32 v[158:159], v[62:63], v[34:35], v[158:159]
	v_pk_fma_f32 v[172:173], v[72:73], v[22:23], v[172:173]
	v_pk_fma_f32 v[158:159], v[66:67], v[24:25], v[158:159]
	v_pk_fma_f32 v[172:173], v[76:77], v[20:21], v[172:173]
	v_pk_fma_f32 v[158:159], v[70:71], v[22:23], v[158:159]
	v_pk_fma_f32 v[172:173], v[80:81], v[18:19], v[172:173]
	v_pk_fma_f32 v[158:159], v[74:75], v[20:21], v[158:159]
	v_pk_fma_f32 v[172:173], v[84:85], v[10:11], v[172:173]
	v_pk_fma_f32 v[158:159], v[78:79], v[18:19], v[158:159]
	v_pk_fma_f32 v[172:173], v[88:89], v[12:13], v[172:173]
	v_pk_fma_f32 v[158:159], v[82:83], v[10:11], v[158:159]
	v_pk_fma_f32 v[172:173], v[92:93], v[14:15], v[172:173]
	v_pk_fma_f32 v[158:159], v[86:87], v[12:13], v[158:159]
	v_pk_fma_f32 v[172:173], v[96:97], v[16:17], v[172:173]
	v_pk_fma_f32 v[158:159], v[90:91], v[14:15], v[158:159]
	v_pk_fma_f32 v[160:161], v[52:53], v[38:39], v[160:161]
	v_pk_fma_f32 v[158:159], v[94:95], v[16:17], v[158:159]
	v_pk_fma_f32 v[172:173], v[100:101], v[26:27], v[172:173]
	v_pk_fma_f32 v[158:159], v[98:99], v[26:27], v[158:159]
	v_pk_fma_f32 v[160:161], v[56:57], v[36:37], v[160:161]
	v_add_f32_e32 v176, v158, v159
	v_mul_f32_e32 v159, v42, v157
	v_pk_fma_f32 v[156:157], v[42:43], v[156:157], v[108:109]
	v_mov_b32_e32 v158, v108
	v_pk_fma_f32 v[156:157], v[46:47], v[40:41], v[156:157]
	s_waitcnt lgkmcnt(0)
	v_mul_f32_e32 v109, v101, v32
	v_pk_fma_f32 v[156:157], v[50:51], v[38:39], v[156:157]
	v_pk_fma_f32 v[158:159], v[44:45], v[40:41], v[158:159]
	v_pk_fma_f32 v[156:157], v[54:55], v[36:37], v[156:157]
	v_pk_fma_f32 v[158:159], v[48:49], v[38:39], v[158:159]
	v_pk_fma_f32 v[156:157], v[58:59], v[34:35], v[156:157]
	v_pk_fma_f32 v[158:159], v[52:53], v[36:37], v[158:159]
	v_pk_fma_f32 v[156:157], v[62:63], v[24:25], v[156:157]
	v_pk_fma_f32 v[158:159], v[56:57], v[34:35], v[158:159]
	v_pk_fma_f32 v[156:157], v[66:67], v[22:23], v[156:157]
	v_add_f32_e32 v175, v172, v173
	v_pk_fma_f32 v[156:157], v[70:71], v[20:21], v[156:157]
	v_pk_fma_f32 v[160:161], v[60:61], v[34:35], v[160:161]
	v_pk_fma_f32 v[156:157], v[74:75], v[18:19], v[156:157]
	v_pk_fma_f32 v[158:159], v[60:61], v[24:25], v[158:159]
	v_pk_fma_f32 v[156:157], v[78:79], v[10:11], v[156:157]
	v_mul_f32_e32 v173, v42, v39
	v_pk_fma_f32 v[156:157], v[82:83], v[12:13], v[156:157]
	v_pk_fma_f32 v[160:161], v[64:65], v[24:25], v[160:161]
	v_pk_fma_f32 v[156:157], v[86:87], v[14:15], v[156:157]
	v_pk_fma_f32 v[158:159], v[64:65], v[22:23], v[158:159]
	v_pk_fma_f32 v[156:157], v[90:91], v[16:17], v[156:157]
	v_pk_fma_f32 v[160:161], v[68:69], v[22:23], v[160:161]
	v_pk_fma_f32 v[156:157], v[94:95], v[26:27], v[156:157]
	v_pk_fma_f32 v[158:159], v[68:69], v[20:21], v[158:159]
	v_pk_fma_f32 v[156:157], v[98:99], v[28:29], v[156:157]
	v_pk_fma_f32 v[160:161], v[72:73], v[20:21], v[160:161]
	v_add_f32_e32 v178, v156, v157
	v_mul_f32_e32 v157, v42, v41
	v_pk_fma_f32 v[40:41], v[42:43], v[40:41], v[108:109]
	v_mov_b32_e32 v156, v108
	v_pk_fma_f32 v[40:41], v[46:47], v[38:39], v[40:41]
	v_pk_fma_f32 v[156:157], v[44:45], v[38:39], v[156:157]
	v_pk_fma_f32 v[40:41], v[50:51], v[36:37], v[40:41]
	v_pk_fma_f32 v[156:157], v[48:49], v[36:37], v[156:157]
	v_pk_fma_f32 v[40:41], v[54:55], v[34:35], v[40:41]
	v_pk_fma_f32 v[156:157], v[52:53], v[34:35], v[156:157]
	v_pk_fma_f32 v[40:41], v[58:59], v[24:25], v[40:41]
	v_pk_fma_f32 v[156:157], v[56:57], v[24:25], v[156:157]
	v_pk_fma_f32 v[40:41], v[62:63], v[22:23], v[40:41]
	v_pk_fma_f32 v[156:157], v[60:61], v[22:23], v[156:157]
	v_pk_fma_f32 v[40:41], v[66:67], v[20:21], v[40:41]
	v_pk_fma_f32 v[156:157], v[64:65], v[20:21], v[156:157]
	v_pk_fma_f32 v[40:41], v[70:71], v[18:19], v[40:41]
	v_pk_fma_f32 v[156:157], v[68:69], v[18:19], v[156:157]
	v_pk_fma_f32 v[40:41], v[74:75], v[10:11], v[40:41]
	v_pk_fma_f32 v[158:159], v[72:73], v[18:19], v[158:159]
	v_pk_fma_f32 v[40:41], v[78:79], v[12:13], v[40:41]
	v_pk_fma_f32 v[156:157], v[72:73], v[10:11], v[156:157]
	v_pk_fma_f32 v[40:41], v[82:83], v[14:15], v[40:41]
	v_pk_fma_f32 v[160:161], v[76:77], v[18:19], v[160:161]
	v_pk_fma_f32 v[40:41], v[86:87], v[16:17], v[40:41]
	v_pk_fma_f32 v[158:159], v[76:77], v[10:11], v[158:159]
	v_pk_fma_f32 v[40:41], v[90:91], v[26:27], v[40:41]
	v_pk_fma_f32 v[156:157], v[76:77], v[12:13], v[156:157]
	v_pk_fma_f32 v[40:41], v[94:95], v[28:29], v[40:41]
	v_pk_fma_f32 v[160:161], v[80:81], v[10:11], v[160:161]
	v_pk_fma_f32 v[40:41], v[98:99], v[30:31], v[40:41]
	v_pk_fma_f32 v[158:159], v[80:81], v[12:13], v[158:159]
	v_add_f32_e32 v180, v40, v41
	ds_read2st64_b32 v[40:41], v163 offset0:184 offset1:188
	v_pk_fma_f32 v[156:157], v[80:81], v[14:15], v[156:157]
	v_pk_fma_f32 v[160:161], v[84:85], v[12:13], v[160:161]
	v_pk_fma_f32 v[158:159], v[84:85], v[14:15], v[158:159]
	v_pk_fma_f32 v[156:157], v[84:85], v[16:17], v[156:157]
	s_waitcnt lgkmcnt(0)
	v_mul_f32_e32 v109, v101, v40
	v_pk_fma_f32 v[38:39], v[42:43], v[38:39], v[108:109]
	v_pk_fma_f32 v[160:161], v[88:89], v[14:15], v[160:161]
	v_pk_fma_f32 v[38:39], v[46:47], v[36:37], v[38:39]
	v_pk_fma_f32 v[158:159], v[88:89], v[16:17], v[158:159]
	v_pk_fma_f32 v[38:39], v[50:51], v[34:35], v[38:39]
	v_pk_fma_f32 v[156:157], v[88:89], v[26:27], v[156:157]
	v_pk_fma_f32 v[38:39], v[54:55], v[24:25], v[38:39]
	v_pk_fma_f32 v[160:161], v[92:93], v[16:17], v[160:161]
	v_pk_fma_f32 v[38:39], v[58:59], v[22:23], v[38:39]
	v_pk_fma_f32 v[158:159], v[92:93], v[26:27], v[158:159]
	v_pk_fma_f32 v[38:39], v[62:63], v[20:21], v[38:39]
	v_pk_fma_f32 v[156:157], v[92:93], v[28:29], v[156:157]
	v_pk_fma_f32 v[38:39], v[66:67], v[18:19], v[38:39]
	v_pk_fma_f32 v[160:161], v[96:97], v[26:27], v[160:161]
	v_pk_fma_f32 v[38:39], v[70:71], v[10:11], v[38:39]
	v_pk_fma_f32 v[158:159], v[96:97], v[28:29], v[158:159]
	v_pk_fma_f32 v[38:39], v[74:75], v[12:13], v[38:39]
	v_pk_fma_f32 v[156:157], v[96:97], v[30:31], v[156:157]
	v_pk_fma_f32 v[38:39], v[78:79], v[14:15], v[38:39]
	v_pk_fma_f32 v[160:161], v[100:101], v[28:29], v[160:161]
	v_pk_fma_f32 v[158:159], v[100:101], v[30:31], v[158:159]
	v_pk_fma_f32 v[156:157], v[100:101], v[32:33], v[156:157]
	v_pk_fma_f32 v[38:39], v[82:83], v[16:17], v[38:39]
	v_add_f32_e32 v177, v160, v161
	v_add_f32_e32 v179, v158, v159
	v_add_f32_e32 v181, v156, v157
	ds_read2st64_b32 v[156:157], v163 offset0:192 offset1:196
	ds_read2st64_b32 v[158:159], v163 offset0:200 offset1:204
	ds_read2st64_b32 v[160:161], v163 offset0:208 offset1:212
	v_pk_fma_f32 v[38:39], v[86:87], v[26:27], v[38:39]
	v_mov_b32_e32 v172, v108
	v_pk_fma_f32 v[38:39], v[90:91], v[28:29], v[38:39]
	s_waitcnt lgkmcnt(2)
	v_mul_f32_e32 v109, v101, v156
	v_pk_fma_f32 v[38:39], v[94:95], v[30:31], v[38:39]
	v_pk_fma_f32 v[172:173], v[44:45], v[36:37], v[172:173]
	v_pk_fma_f32 v[38:39], v[98:99], v[32:33], v[38:39]
	v_pk_fma_f32 v[172:173], v[48:49], v[34:35], v[172:173]
	v_add_f32_e32 v182, v38, v39
	v_mul_f32_e32 v39, v42, v37
	v_pk_fma_f32 v[36:37], v[42:43], v[36:37], v[108:109]
	v_mov_b32_e32 v38, v108
	v_pk_fma_f32 v[36:37], v[46:47], v[34:35], v[36:37]
	s_waitcnt lgkmcnt(1)
	v_mul_f32_e32 v109, v101, v158
	v_pk_fma_f32 v[36:37], v[50:51], v[24:25], v[36:37]
	v_pk_fma_f32 v[38:39], v[44:45], v[34:35], v[38:39]
	v_pk_fma_f32 v[36:37], v[54:55], v[22:23], v[36:37]
	v_pk_fma_f32 v[172:173], v[52:53], v[24:25], v[172:173]
	v_pk_fma_f32 v[36:37], v[58:59], v[20:21], v[36:37]
	v_pk_fma_f32 v[38:39], v[48:49], v[24:25], v[38:39]
	v_pk_fma_f32 v[36:37], v[62:63], v[18:19], v[36:37]
	v_pk_fma_f32 v[172:173], v[56:57], v[22:23], v[172:173]
	v_pk_fma_f32 v[36:37], v[66:67], v[10:11], v[36:37]
	v_pk_fma_f32 v[172:173], v[60:61], v[20:21], v[172:173]
	v_pk_fma_f32 v[36:37], v[70:71], v[12:13], v[36:37]
	v_pk_fma_f32 v[172:173], v[64:65], v[18:19], v[172:173]
	v_pk_fma_f32 v[36:37], v[74:75], v[14:15], v[36:37]
	v_pk_fma_f32 v[172:173], v[68:69], v[10:11], v[172:173]
	v_pk_fma_f32 v[36:37], v[78:79], v[16:17], v[36:37]
	v_pk_fma_f32 v[172:173], v[72:73], v[12:13], v[172:173]
	v_pk_fma_f32 v[36:37], v[82:83], v[26:27], v[36:37]
	v_pk_fma_f32 v[172:173], v[76:77], v[14:15], v[172:173]
	v_pk_fma_f32 v[36:37], v[86:87], v[28:29], v[36:37]
	v_pk_fma_f32 v[172:173], v[80:81], v[16:17], v[172:173]
	v_pk_fma_f32 v[36:37], v[90:91], v[30:31], v[36:37]
	v_pk_fma_f32 v[172:173], v[84:85], v[26:27], v[172:173]
	v_pk_fma_f32 v[36:37], v[94:95], v[32:33], v[36:37]
	v_pk_fma_f32 v[172:173], v[88:89], v[28:29], v[172:173]
	v_pk_fma_f32 v[36:37], v[98:99], v[40:41], v[36:37]
	v_pk_fma_f32 v[172:173], v[92:93], v[30:31], v[172:173]
	v_add_f32_e32 v184, v36, v37
	v_mul_f32_e32 v37, v42, v35
	v_pk_fma_f32 v[34:35], v[42:43], v[34:35], v[108:109]
	v_mov_b32_e32 v36, v108
	v_pk_fma_f32 v[34:35], v[46:47], v[24:25], v[34:35]
	s_waitcnt lgkmcnt(0)
	v_mul_f32_e32 v109, v101, v160
	v_pk_fma_f32 v[34:35], v[50:51], v[22:23], v[34:35]
	v_pk_fma_f32 v[36:37], v[44:45], v[24:25], v[36:37]
	v_pk_fma_f32 v[34:35], v[54:55], v[20:21], v[34:35]
	v_pk_fma_f32 v[36:37], v[48:49], v[22:23], v[36:37]
	v_pk_fma_f32 v[34:35], v[58:59], v[18:19], v[34:35]
	v_pk_fma_f32 v[172:173], v[96:97], v[32:33], v[172:173]
	v_pk_fma_f32 v[34:35], v[62:63], v[10:11], v[34:35]
	v_pk_fma_f32 v[38:39], v[52:53], v[22:23], v[38:39]
	v_pk_fma_f32 v[34:35], v[66:67], v[12:13], v[34:35]
	v_pk_fma_f32 v[36:37], v[52:53], v[20:21], v[36:37]
	v_pk_fma_f32 v[34:35], v[70:71], v[14:15], v[34:35]
	v_pk_fma_f32 v[172:173], v[100:101], v[40:41], v[172:173]
	v_pk_fma_f32 v[34:35], v[74:75], v[16:17], v[34:35]
	v_pk_fma_f32 v[38:39], v[56:57], v[20:21], v[38:39]
	v_pk_fma_f32 v[34:35], v[78:79], v[26:27], v[34:35]
	v_pk_fma_f32 v[36:37], v[56:57], v[18:19], v[36:37]
	v_pk_fma_f32 v[34:35], v[82:83], v[28:29], v[34:35]
	v_add_f32_e32 v183, v172, v173
	v_pk_fma_f32 v[34:35], v[86:87], v[30:31], v[34:35]
	v_pk_fma_f32 v[38:39], v[60:61], v[18:19], v[38:39]
	v_pk_fma_f32 v[34:35], v[90:91], v[32:33], v[34:35]
	v_pk_fma_f32 v[36:37], v[60:61], v[10:11], v[36:37]
	v_pk_fma_f32 v[34:35], v[94:95], v[40:41], v[34:35]
	v_mul_f32_e32 v173, v42, v23
	v_pk_fma_f32 v[34:35], v[98:99], v[156:157], v[34:35]
	v_pk_fma_f32 v[38:39], v[64:65], v[10:11], v[38:39]
	v_add_f32_e32 v186, v34, v35
	v_mul_f32_e32 v35, v42, v25
	v_pk_fma_f32 v[24:25], v[42:43], v[24:25], v[108:109]
	v_mov_b32_e32 v34, v108
	v_pk_fma_f32 v[24:25], v[46:47], v[22:23], v[24:25]
	v_pk_fma_f32 v[34:35], v[44:45], v[22:23], v[34:35]
	v_pk_fma_f32 v[24:25], v[50:51], v[20:21], v[24:25]
	v_pk_fma_f32 v[34:35], v[48:49], v[20:21], v[34:35]
	v_pk_fma_f32 v[24:25], v[54:55], v[18:19], v[24:25]
	v_pk_fma_f32 v[34:35], v[52:53], v[18:19], v[34:35]
	v_pk_fma_f32 v[24:25], v[58:59], v[10:11], v[24:25]
	v_pk_fma_f32 v[34:35], v[56:57], v[10:11], v[34:35]
	v_pk_fma_f32 v[24:25], v[62:63], v[12:13], v[24:25]
	v_pk_fma_f32 v[34:35], v[60:61], v[12:13], v[34:35]
	v_pk_fma_f32 v[24:25], v[66:67], v[14:15], v[24:25]
	v_pk_fma_f32 v[36:37], v[64:65], v[12:13], v[36:37]
	v_pk_fma_f32 v[24:25], v[70:71], v[16:17], v[24:25]
	v_pk_fma_f32 v[34:35], v[64:65], v[14:15], v[34:35]
	v_pk_fma_f32 v[24:25], v[74:75], v[26:27], v[24:25]
	v_pk_fma_f32 v[38:39], v[68:69], v[12:13], v[38:39]
	v_pk_fma_f32 v[24:25], v[78:79], v[28:29], v[24:25]
	v_pk_fma_f32 v[36:37], v[68:69], v[14:15], v[36:37]
	v_pk_fma_f32 v[24:25], v[82:83], v[30:31], v[24:25]
	v_pk_fma_f32 v[34:35], v[68:69], v[16:17], v[34:35]
	v_pk_fma_f32 v[24:25], v[86:87], v[32:33], v[24:25]
	v_pk_fma_f32 v[38:39], v[72:73], v[14:15], v[38:39]
	v_pk_fma_f32 v[24:25], v[90:91], v[40:41], v[24:25]
	v_pk_fma_f32 v[36:37], v[72:73], v[16:17], v[36:37]
	v_pk_fma_f32 v[24:25], v[94:95], v[156:157], v[24:25]
	v_pk_fma_f32 v[34:35], v[72:73], v[26:27], v[34:35]
	v_pk_fma_f32 v[24:25], v[98:99], v[158:159], v[24:25]
	v_pk_fma_f32 v[38:39], v[76:77], v[16:17], v[38:39]
	v_add_f32_e32 v188, v24, v25
	ds_read2st64_b32 v[24:25], v163 offset0:216 offset1:220
	v_pk_fma_f32 v[36:37], v[76:77], v[26:27], v[36:37]
	v_pk_fma_f32 v[34:35], v[76:77], v[28:29], v[34:35]
	v_pk_fma_f32 v[38:39], v[80:81], v[26:27], v[38:39]
	v_pk_fma_f32 v[36:37], v[80:81], v[28:29], v[36:37]
	s_waitcnt lgkmcnt(0)
	v_mul_f32_e32 v109, v101, v24
	v_pk_fma_f32 v[22:23], v[42:43], v[22:23], v[108:109]
	v_pk_fma_f32 v[34:35], v[80:81], v[30:31], v[34:35]
	v_pk_fma_f32 v[22:23], v[46:47], v[20:21], v[22:23]
	v_pk_fma_f32 v[38:39], v[84:85], v[28:29], v[38:39]
	v_pk_fma_f32 v[22:23], v[50:51], v[18:19], v[22:23]
	v_pk_fma_f32 v[36:37], v[84:85], v[30:31], v[36:37]
	v_pk_fma_f32 v[22:23], v[54:55], v[10:11], v[22:23]
	v_pk_fma_f32 v[34:35], v[84:85], v[32:33], v[34:35]
	v_pk_fma_f32 v[22:23], v[58:59], v[12:13], v[22:23]
	v_pk_fma_f32 v[38:39], v[88:89], v[30:31], v[38:39]
	v_pk_fma_f32 v[22:23], v[62:63], v[14:15], v[22:23]
	v_pk_fma_f32 v[36:37], v[88:89], v[32:33], v[36:37]
	v_pk_fma_f32 v[22:23], v[66:67], v[16:17], v[22:23]
	v_pk_fma_f32 v[34:35], v[88:89], v[40:41], v[34:35]
	v_pk_fma_f32 v[22:23], v[70:71], v[26:27], v[22:23]
	v_pk_fma_f32 v[38:39], v[92:93], v[32:33], v[38:39]
	v_pk_fma_f32 v[36:37], v[92:93], v[40:41], v[36:37]
	v_pk_fma_f32 v[34:35], v[92:93], v[156:157], v[34:35]
	v_pk_fma_f32 v[22:23], v[74:75], v[28:29], v[22:23]
	v_pk_fma_f32 v[38:39], v[96:97], v[40:41], v[38:39]
	v_pk_fma_f32 v[36:37], v[96:97], v[156:157], v[36:37]
	v_pk_fma_f32 v[34:35], v[96:97], v[158:159], v[34:35]
	v_pk_fma_f32 v[22:23], v[78:79], v[30:31], v[22:23]
	v_pk_fma_f32 v[38:39], v[100:101], v[156:157], v[38:39]
	v_pk_fma_f32 v[36:37], v[100:101], v[158:159], v[36:37]
	v_pk_fma_f32 v[34:35], v[100:101], v[160:161], v[34:35]
	v_pk_fma_f32 v[22:23], v[82:83], v[32:33], v[22:23]
	v_add_f32_e32 v185, v38, v39
	v_add_f32_e32 v187, v36, v37
	v_add_f32_e32 v189, v34, v35
	ds_read2st64_b32 v[34:35], v163 offset0:224 offset1:228
	ds_read2st64_b32 v[36:37], v163 offset0:232 offset1:236
	ds_read2st64_b32 v[38:39], v163 offset0:240 offset1:244
	v_pk_fma_f32 v[22:23], v[86:87], v[40:41], v[22:23]
	v_mov_b32_e32 v172, v108
	v_pk_fma_f32 v[22:23], v[90:91], v[156:157], v[22:23]
	s_waitcnt lgkmcnt(2)
	v_mul_f32_e32 v109, v101, v34
	v_pk_fma_f32 v[22:23], v[94:95], v[158:159], v[22:23]
	v_pk_fma_f32 v[172:173], v[44:45], v[20:21], v[172:173]
	v_pk_fma_f32 v[22:23], v[98:99], v[160:161], v[22:23]
	v_pk_fma_f32 v[172:173], v[48:49], v[18:19], v[172:173]
	v_add_f32_e32 v190, v22, v23
	v_mul_f32_e32 v23, v42, v21
	v_pk_fma_f32 v[20:21], v[42:43], v[20:21], v[108:109]
	v_pk_fma_f32 v[172:173], v[52:53], v[10:11], v[172:173]
	v_pk_fma_f32 v[20:21], v[46:47], v[18:19], v[20:21]
	v_pk_fma_f32 v[172:173], v[56:57], v[12:13], v[172:173]
	v_pk_fma_f32 v[20:21], v[50:51], v[10:11], v[20:21]
	v_pk_fma_f32 v[172:173], v[60:61], v[14:15], v[172:173]
	v_pk_fma_f32 v[20:21], v[54:55], v[12:13], v[20:21]
	v_pk_fma_f32 v[172:173], v[64:65], v[16:17], v[172:173]
	v_pk_fma_f32 v[20:21], v[58:59], v[14:15], v[20:21]
	v_pk_fma_f32 v[172:173], v[68:69], v[26:27], v[172:173]
	v_pk_fma_f32 v[20:21], v[62:63], v[16:17], v[20:21]
	v_pk_fma_f32 v[172:173], v[72:73], v[28:29], v[172:173]
	v_pk_fma_f32 v[20:21], v[66:67], v[26:27], v[20:21]
	v_pk_fma_f32 v[172:173], v[76:77], v[30:31], v[172:173]
	v_pk_fma_f32 v[20:21], v[70:71], v[28:29], v[20:21]
	v_pk_fma_f32 v[172:173], v[80:81], v[32:33], v[172:173]
	v_pk_fma_f32 v[20:21], v[74:75], v[30:31], v[20:21]
	v_pk_fma_f32 v[172:173], v[84:85], v[40:41], v[172:173]
	v_pk_fma_f32 v[20:21], v[78:79], v[32:33], v[20:21]
	v_pk_fma_f32 v[172:173], v[88:89], v[156:157], v[172:173]
	v_pk_fma_f32 v[20:21], v[82:83], v[40:41], v[20:21]
	v_pk_fma_f32 v[172:173], v[92:93], v[158:159], v[172:173]
	v_pk_fma_f32 v[20:21], v[86:87], v[156:157], v[20:21]
	v_pk_fma_f32 v[172:173], v[96:97], v[160:161], v[172:173]
	v_pk_fma_f32 v[20:21], v[90:91], v[158:159], v[20:21]
	v_pk_fma_f32 v[172:173], v[100:101], v[24:25], v[172:173]
	v_pk_fma_f32 v[20:21], v[94:95], v[160:161], v[20:21]
	v_mov_b32_e32 v22, v108
	v_pk_fma_f32 v[20:21], v[98:99], v[24:25], v[20:21]
	s_waitcnt lgkmcnt(1)
	v_mul_f32_e32 v109, v101, v36
	v_add_f32_e32 v172, v172, v173
	v_pk_fma_f32 v[22:23], v[44:45], v[18:19], v[22:23]
	v_add_f32_e32 v173, v20, v21
	v_mul_f32_e32 v21, v42, v19
	v_pk_fma_f32 v[18:19], v[42:43], v[18:19], v[108:109]
	v_pk_fma_f32 v[22:23], v[48:49], v[10:11], v[22:23]
	v_pk_fma_f32 v[18:19], v[46:47], v[10:11], v[18:19]
	v_pk_fma_f32 v[22:23], v[52:53], v[12:13], v[22:23]
	v_pk_fma_f32 v[18:19], v[50:51], v[12:13], v[18:19]
	v_pk_fma_f32 v[22:23], v[56:57], v[14:15], v[22:23]
	v_pk_fma_f32 v[18:19], v[54:55], v[14:15], v[18:19]
	v_pk_fma_f32 v[22:23], v[60:61], v[16:17], v[22:23]
	v_pk_fma_f32 v[18:19], v[58:59], v[16:17], v[18:19]
	v_pk_fma_f32 v[22:23], v[64:65], v[26:27], v[22:23]
	v_pk_fma_f32 v[18:19], v[62:63], v[26:27], v[18:19]
	v_pk_fma_f32 v[22:23], v[68:69], v[28:29], v[22:23]
	v_pk_fma_f32 v[18:19], v[66:67], v[28:29], v[18:19]
	v_pk_fma_f32 v[22:23], v[72:73], v[30:31], v[22:23]
	v_pk_fma_f32 v[18:19], v[70:71], v[30:31], v[18:19]
	v_pk_fma_f32 v[22:23], v[76:77], v[32:33], v[22:23]
	v_pk_fma_f32 v[18:19], v[74:75], v[32:33], v[18:19]
	v_pk_fma_f32 v[22:23], v[80:81], v[40:41], v[22:23]
	v_pk_fma_f32 v[18:19], v[78:79], v[40:41], v[18:19]
	v_pk_fma_f32 v[22:23], v[84:85], v[156:157], v[22:23]
	v_pk_fma_f32 v[18:19], v[82:83], v[156:157], v[18:19]
	v_pk_fma_f32 v[22:23], v[88:89], v[158:159], v[22:23]
	v_pk_fma_f32 v[18:19], v[86:87], v[158:159], v[18:19]
	v_pk_fma_f32 v[22:23], v[92:93], v[160:161], v[22:23]
	v_pk_fma_f32 v[18:19], v[90:91], v[160:161], v[18:19]
	v_pk_fma_f32 v[22:23], v[96:97], v[24:25], v[22:23]
	v_pk_fma_f32 v[18:19], v[94:95], v[24:25], v[18:19]
	v_pk_fma_f32 v[22:23], v[100:101], v[34:35], v[22:23]
	v_pk_fma_f32 v[18:19], v[98:99], v[34:35], v[18:19]
	v_add_f32_e32 v22, v22, v23
	v_mov_b32_e32 v20, v108
	v_add_f32_e32 v23, v18, v19
	s_waitcnt lgkmcnt(0)
	v_mul_f32_e32 v109, v101, v38
	v_mul_f32_e32 v19, v42, v11
	v_mov_b32_e32 v18, v108
	v_pk_fma_f32 v[20:21], v[44:45], v[10:11], v[20:21]
	v_pk_fma_f32 v[10:11], v[42:43], v[10:11], v[108:109]
	v_pk_fma_f32 v[18:19], v[44:45], v[12:13], v[18:19]
	v_pk_fma_f32 v[20:21], v[48:49], v[12:13], v[20:21]
	v_pk_fma_f32 v[10:11], v[46:47], v[12:13], v[10:11]
	v_pk_fma_f32 v[12:13], v[48:49], v[14:15], v[18:19]
	v_pk_fma_f32 v[20:21], v[52:53], v[14:15], v[20:21]
	v_pk_fma_f32 v[10:11], v[50:51], v[14:15], v[10:11]
	v_pk_fma_f32 v[12:13], v[52:53], v[16:17], v[12:13]
	v_pk_fma_f32 v[20:21], v[56:57], v[16:17], v[20:21]
	v_pk_fma_f32 v[10:11], v[54:55], v[16:17], v[10:11]
	v_pk_fma_f32 v[12:13], v[56:57], v[26:27], v[12:13]
	v_pk_fma_f32 v[20:21], v[60:61], v[26:27], v[20:21]
	v_pk_fma_f32 v[10:11], v[58:59], v[26:27], v[10:11]
	v_pk_fma_f32 v[12:13], v[60:61], v[28:29], v[12:13]
	v_pk_fma_f32 v[20:21], v[64:65], v[28:29], v[20:21]
	v_pk_fma_f32 v[10:11], v[62:63], v[28:29], v[10:11]
	v_pk_fma_f32 v[12:13], v[64:65], v[30:31], v[12:13]
	v_pk_fma_f32 v[20:21], v[68:69], v[30:31], v[20:21]
	v_pk_fma_f32 v[10:11], v[66:67], v[30:31], v[10:11]
	v_pk_fma_f32 v[12:13], v[68:69], v[32:33], v[12:13]
	v_pk_fma_f32 v[20:21], v[72:73], v[32:33], v[20:21]
	v_pk_fma_f32 v[10:11], v[70:71], v[32:33], v[10:11]
	v_pk_fma_f32 v[12:13], v[72:73], v[40:41], v[12:13]
	v_pk_fma_f32 v[20:21], v[76:77], v[40:41], v[20:21]
	v_pk_fma_f32 v[10:11], v[74:75], v[40:41], v[10:11]
	v_pk_fma_f32 v[12:13], v[76:77], v[156:157], v[12:13]
	v_pk_fma_f32 v[20:21], v[80:81], v[156:157], v[20:21]
	v_pk_fma_f32 v[10:11], v[78:79], v[156:157], v[10:11]
	v_pk_fma_f32 v[12:13], v[80:81], v[158:159], v[12:13]
	v_pk_fma_f32 v[20:21], v[84:85], v[158:159], v[20:21]
	v_pk_fma_f32 v[10:11], v[82:83], v[158:159], v[10:11]
	v_pk_fma_f32 v[12:13], v[84:85], v[160:161], v[12:13]
	v_pk_fma_f32 v[20:21], v[88:89], v[160:161], v[20:21]
	v_pk_fma_f32 v[10:11], v[86:87], v[160:161], v[10:11]
	v_pk_fma_f32 v[12:13], v[88:89], v[24:25], v[12:13]
	v_pk_fma_f32 v[20:21], v[92:93], v[24:25], v[20:21]
	v_pk_fma_f32 v[10:11], v[90:91], v[24:25], v[10:11]
	v_pk_fma_f32 v[12:13], v[92:93], v[34:35], v[12:13]
	s_lshl_b32 s6, s28, 10
	v_pk_fma_f32 v[20:21], v[96:97], v[34:35], v[20:21]
	v_pk_fma_f32 v[10:11], v[94:95], v[34:35], v[10:11]
	v_pk_fma_f32 v[12:13], v[96:97], v[36:37], v[12:13]
	s_add_i32 s6, s6, 0
	v_pk_fma_f32 v[20:21], v[100:101], v[36:37], v[20:21]
	v_pk_fma_f32 v[10:11], v[98:99], v[36:37], v[10:11]
	v_pk_fma_f32 v[12:13], v[100:101], v[38:39], v[12:13]
	v_add_u32_e32 v109, s6, v162
	v_add_f32_e32 v20, v20, v21
	v_add_f32_e32 v10, v10, v11
	v_add_f32_e32 v11, v12, v13
	s_barrier
	ds_write2st64_b32 v163, v164, v165 offset1:4
	ds_write2st64_b32 v163, v166, v167 offset0:8 offset1:12
	ds_write2st64_b32 v163, v168, v169 offset0:16 offset1:20
	ds_write2st64_b32 v163, v170, v171 offset0:24 offset1:28
	ds_write2st64_b32 v163, v174, v175 offset0:32 offset1:36
	ds_write2st64_b32 v163, v176, v177 offset0:40 offset1:44
	ds_write2st64_b32 v163, v178, v179 offset0:48 offset1:52
	ds_write2st64_b32 v163, v180, v181 offset0:56 offset1:60
	ds_write2st64_b32 v163, v182, v183 offset0:64 offset1:68
	ds_write2st64_b32 v163, v184, v185 offset0:72 offset1:76
	ds_write2st64_b32 v163, v186, v187 offset0:80 offset1:84
	ds_write2st64_b32 v163, v188, v189 offset0:88 offset1:92
	ds_write2st64_b32 v163, v190, v172 offset0:96 offset1:100
	ds_write2st64_b32 v163, v173, v22 offset0:104 offset1:108
	ds_write2st64_b32 v163, v23, v20 offset0:112 offset1:116
	ds_write2st64_b32 v163, v10, v11 offset0:120 offset1:124
	s_waitcnt lgkmcnt(0)
	s_barrier
	ds_read_b128 v[38:41], v109
	ds_read_b128 v[34:37], v109 offset:8192
	ds_read_b128 v[30:33], v109 offset:16384
	ds_read_b128 v[26:29], v109 offset:24576
	ds_read_b128 v[22:25], v109 offset:32768
	ds_read_b128 v[18:21], v109 offset:40960
	s_waitcnt lgkmcnt(5)
	v_mov_b32_e32 v10, v39
	v_mov_b32_e32 v11, v40
	v_mov_b32_e32 v12, v38
	v_mov_b32_e32 v13, v41
	v_pk_add_f32 v[10:11], v[10:11], v[12:13]
	s_waitcnt lgkmcnt(4)
	v_mov_b32_e32 v12, v34
	v_add_f32_e32 v160, v10, v11
	v_mov_b32_e32 v10, v35
	v_mov_b32_e32 v11, v36
	v_mov_b32_e32 v13, v37
	v_pk_add_f32 v[10:11], v[10:11], v[12:13]
	s_waitcnt lgkmcnt(3)
	v_mov_b32_e32 v12, v30
	v_add_f32_e32 v161, v10, v11
	v_mov_b32_e32 v10, v31
	v_mov_b32_e32 v11, v32
	v_mov_b32_e32 v13, v33
	v_pk_add_f32 v[10:11], v[10:11], v[12:13]
	s_waitcnt lgkmcnt(2)
	v_mov_b32_e32 v12, v26
	v_add_f32_e32 v162, v10, v11
	v_mov_b32_e32 v10, v27
	v_mov_b32_e32 v11, v28
	v_mov_b32_e32 v13, v29
	v_pk_add_f32 v[10:11], v[10:11], v[12:13]
	s_waitcnt lgkmcnt(1)
	v_mov_b32_e32 v12, v22
	v_add_f32_e32 v163, v10, v11
	v_mov_b32_e32 v10, v23
	v_mov_b32_e32 v11, v24
	v_mov_b32_e32 v13, v25
	v_pk_add_f32 v[10:11], v[10:11], v[12:13]
	s_waitcnt lgkmcnt(0)
	v_mov_b32_e32 v12, v18
	v_add_f32_e32 v164, v10, v11
	v_mov_b32_e32 v10, v19
	v_mov_b32_e32 v11, v20
	ds_read_b128 v[14:17], v109 offset:49152
	v_mov_b32_e32 v13, v21
	v_pk_add_f32 v[10:11], v[10:11], v[12:13]
	s_add_i32 s28, s57, s28
	v_add_f32_e32 v165, v10, v11
	ds_read_b128 v[10:13], v109 offset:57344
	s_waitcnt lgkmcnt(1)
	v_mov_b32_e32 v156, v15
	v_mov_b32_e32 v157, v16
	v_mov_b32_e32 v158, v14
	v_mov_b32_e32 v159, v17
	v_pk_add_f32 v[156:157], v[156:157], v[158:159]
	s_waitcnt lgkmcnt(0)
	v_mov_b32_e32 v158, v10
	v_add_f32_e32 v109, v156, v157
	v_mov_b32_e32 v156, v11
	v_mov_b32_e32 v157, v12
	v_mov_b32_e32 v159, v13
	v_pk_add_f32 v[156:157], v[156:157], v[158:159]
	v_add_f32_dpp v158, v161, v161 quad_perm:[1,0,3,2] row_mask:0xf bank_mask:0xf bound_ctrl:1
	v_add_f32_e32 v156, v156, v157
	v_add_f32_dpp v157, v160, v160 quad_perm:[1,0,3,2] row_mask:0xf bank_mask:0xf bound_ctrl:1
	v_add_f32_dpp v160, v163, v163 quad_perm:[1,0,3,2] row_mask:0xf bank_mask:0xf bound_ctrl:1
	v_add_f32_dpp v158, v158, v158 quad_perm:[2,3,0,1] row_mask:0xf bank_mask:0xf bound_ctrl:1
	v_add_f32_dpp v157, v157, v157 quad_perm:[2,3,0,1] row_mask:0xf bank_mask:0xf bound_ctrl:1
	v_add_f32_dpp v159, v162, v162 quad_perm:[1,0,3,2] row_mask:0xf bank_mask:0xf bound_ctrl:1
	s_nop 0
	v_add_f32_dpp v157, v157, v157 row_half_mirror row_mask:0xf bank_mask:0xf bound_ctrl:1
	v_add_f32_dpp v158, v158, v158 row_half_mirror row_mask:0xf bank_mask:0xf bound_ctrl:1
	v_add_f32_dpp v159, v159, v159 quad_perm:[2,3,0,1] row_mask:0xf bank_mask:0xf bound_ctrl:1
	v_add_f32_dpp v157, v157, v157 row_mirror row_mask:0xf bank_mask:0xf bound_ctrl:1
	v_add_f32_dpp v158, v158, v158 row_mirror row_mask:0xf bank_mask:0xf bound_ctrl:1
	v_add_f32_dpp v159, v159, v159 row_half_mirror row_mask:0xf bank_mask:0xf bound_ctrl:1
	v_add_f32_dpp v157, v157, v157 row_bcast:15 row_mask:0xa bank_mask:0xf
	v_add_f32_dpp v160, v160, v160 quad_perm:[2,3,0,1] row_mask:0xf bank_mask:0xf bound_ctrl:1
	v_add_f32_dpp v159, v159, v159 row_mirror row_mask:0xf bank_mask:0xf bound_ctrl:1
	v_add_f32_dpp v158, v158, v158 row_bcast:15 row_mask:0xa bank_mask:0xf
	v_add_f32_dpp v161, v164, v164 quad_perm:[1,0,3,2] row_mask:0xf bank_mask:0xf bound_ctrl:1
	v_add_f32_dpp v160, v160, v160 row_half_mirror row_mask:0xf bank_mask:0xf bound_ctrl:1
	v_add_f32_dpp v159, v159, v159 row_bcast:15 row_mask:0xa bank_mask:0xf
	v_add_f32_dpp v161, v161, v161 quad_perm:[2,3,0,1] row_mask:0xf bank_mask:0xf bound_ctrl:1
	v_add_f32_dpp v160, v160, v160 row_mirror row_mask:0xf bank_mask:0xf bound_ctrl:1
	v_add_f32_dpp v162, v165, v165 quad_perm:[1,0,3,2] row_mask:0xf bank_mask:0xf bound_ctrl:1
	v_add_f32_dpp v161, v161, v161 row_half_mirror row_mask:0xf bank_mask:0xf bound_ctrl:1
	v_add_f32_dpp v160, v160, v160 row_bcast:15 row_mask:0xa bank_mask:0xf
	v_add_f32_dpp v162, v162, v162 quad_perm:[2,3,0,1] row_mask:0xf bank_mask:0xf bound_ctrl:1
	v_add_f32_dpp v161, v161, v161 row_mirror row_mask:0xf bank_mask:0xf bound_ctrl:1
	v_add_f32_dpp v109, v109, v109 quad_perm:[1,0,3,2] row_mask:0xf bank_mask:0xf bound_ctrl:1
	v_add_f32_dpp v162, v162, v162 row_half_mirror row_mask:0xf bank_mask:0xf bound_ctrl:1
	v_add_f32_dpp v161, v161, v161 row_bcast:15 row_mask:0xa bank_mask:0xf
	v_add_f32_dpp v109, v109, v109 quad_perm:[2,3,0,1] row_mask:0xf bank_mask:0xf bound_ctrl:1
	v_add_f32_dpp v162, v162, v162 row_mirror row_mask:0xf bank_mask:0xf bound_ctrl:1
	v_add_f32_dpp v156, v156, v156 quad_perm:[1,0,3,2] row_mask:0xf bank_mask:0xf bound_ctrl:1
	v_add_f32_dpp v109, v109, v109 row_half_mirror row_mask:0xf bank_mask:0xf bound_ctrl:1
	v_add_f32_dpp v162, v162, v162 row_bcast:15 row_mask:0xa bank_mask:0xf
	v_add_f32_dpp v156, v156, v156 quad_perm:[2,3,0,1] row_mask:0xf bank_mask:0xf bound_ctrl:1
	v_add_f32_dpp v109, v109, v109 row_mirror row_mask:0xf bank_mask:0xf bound_ctrl:1
	s_nop 0
	v_add_f32_dpp v156, v156, v156 row_half_mirror row_mask:0xf bank_mask:0xf bound_ctrl:1
	s_nop 0
	v_add_f32_dpp v109, v109, v109 row_bcast:15 row_mask:0xa bank_mask:0xf
	v_add_f32_dpp v156, v156, v156 row_mirror row_mask:0xf bank_mask:0xf bound_ctrl:1
	s_nop 1
	v_add_f32_dpp v156, v156, v156 row_bcast:15 row_mask:0xa bank_mask:0xf
	s_nop 1
	v_add_f32_dpp v157, v157, v157 row_bcast:31 row_mask:0xc bank_mask:0xf
	s_nop 0
	v_readlane_b32 s6, v157, 63
	s_nop 0
	v_add_f32_dpp v158, v158, v158 row_bcast:31 row_mask:0xc bank_mask:0xf
	v_fma_f32 v39, s6, v239, v39
	v_fma_f32 v38, s6, v239, v38
	v_add_f32_dpp v159, v159, v159 row_bcast:31 row_mask:0xc bank_mask:0xf
	v_fma_f32 v41, s6, v239, v41
	v_fmac_f32_e32 v40, s6, v239
	v_add_f32_dpp v160, v160, v160 row_bcast:31 row_mask:0xc bank_mask:0xf
	v_readlane_b32 s7, v158, 63
	v_readlane_b32 s8, v159, 63
	v_add_f32_dpp v161, v161, v161 row_bcast:31 row_mask:0xc bank_mask:0xf
	v_pk_mul_f32 v[158:159], v[38:39], v[38:39]
	v_readlane_b32 s9, v160, 63
	v_add_f32_dpp v162, v162, v162 row_bcast:31 row_mask:0xc bank_mask:0xf
	v_readlane_b32 s10, v161, 63
	v_fma_f32 v35, s7, v239, v35
	v_add_f32_dpp v109, v109, v109 row_bcast:31 row_mask:0xc bank_mask:0xf
	v_fma_f32 v34, s7, v239, v34
	v_fma_f32 v37, s7, v239, v37
	v_add_f32_dpp v156, v156, v156 row_bcast:31 row_mask:0xc bank_mask:0xf
	v_fmac_f32_e32 v36, s7, v239
	v_readlane_b32 s60, v156, 63
	v_pk_mul_f32 v[156:157], v[40:41], v[40:41]
	v_readlane_b32 s29, v109, 63
	v_pk_mov_b32 v[160:161], v[158:159], v[156:157] op_sel:[1,0]
	v_mov_b32_e32 v159, v157
	v_pk_add_f32 v[156:157], v[160:161], v[158:159]
	v_pk_mul_f32 v[158:159], v[34:35], v[34:35]
	v_add_f32_e32 v109, v156, v157
	v_pk_mul_f32 v[156:157], v[36:37], v[36:37]
	v_fma_f32 v31, s8, v239, v31
	v_pk_mov_b32 v[160:161], v[158:159], v[156:157] op_sel:[1,0]
	v_mov_b32_e32 v159, v157
	v_pk_add_f32 v[156:157], v[160:161], v[158:159]
	v_fma_f32 v30, s8, v239, v30
	v_fma_f32 v33, s8, v239, v33
	v_fmac_f32_e32 v32, s8, v239
	v_readlane_b32 s11, v162, 63
	v_add_f32_e32 v162, v156, v157
	v_pk_mul_f32 v[156:157], v[32:33], v[32:33]
	v_pk_mul_f32 v[158:159], v[30:31], v[30:31]
	v_fma_f32 v27, s9, v239, v27
	v_pk_mov_b32 v[160:161], v[158:159], v[156:157] op_sel:[1,0]
	v_mov_b32_e32 v159, v157
	v_pk_add_f32 v[156:157], v[160:161], v[158:159]
	v_fma_f32 v26, s9, v239, v26
	v_fma_f32 v29, s9, v239, v29
	v_fmac_f32_e32 v28, s9, v239
	v_add_f32_e32 v163, v156, v157
	v_pk_mul_f32 v[156:157], v[28:29], v[28:29]
	v_pk_mul_f32 v[158:159], v[26:27], v[26:27]
	v_fma_f32 v23, s10, v239, v23
	v_pk_mov_b32 v[160:161], v[158:159], v[156:157] op_sel:[1,0]
	v_mov_b32_e32 v159, v157
	v_pk_add_f32 v[156:157], v[160:161], v[158:159]
	v_fma_f32 v22, s10, v239, v22
	v_fma_f32 v25, s10, v239, v25
	v_fmac_f32_e32 v24, s10, v239
	v_add_f32_e32 v164, v156, v157
	v_pk_mul_f32 v[156:157], v[24:25], v[24:25]
	v_pk_mul_f32 v[158:159], v[22:23], v[22:23]
	v_fma_f32 v19, s11, v239, v19
	v_pk_mov_b32 v[160:161], v[158:159], v[156:157] op_sel:[1,0]
	v_mov_b32_e32 v159, v157
	v_pk_add_f32 v[156:157], v[160:161], v[158:159]
	v_fma_f32 v18, s11, v239, v18
	v_fma_f32 v21, s11, v239, v21
	v_fmac_f32_e32 v20, s11, v239
	v_add_f32_e32 v165, v156, v157
	v_pk_mul_f32 v[156:157], v[20:21], v[20:21]
	v_pk_mul_f32 v[158:159], v[18:19], v[18:19]
	v_fma_f32 v15, s29, v239, v15
	v_pk_mov_b32 v[160:161], v[158:159], v[156:157] op_sel:[1,0]
	v_mov_b32_e32 v159, v157
	v_pk_add_f32 v[156:157], v[160:161], v[158:159]
	v_fma_f32 v14, s29, v239, v14
	v_fma_f32 v17, s29, v239, v17
	v_fmac_f32_e32 v16, s29, v239
	v_add_f32_e32 v166, v156, v157
	v_pk_mul_f32 v[156:157], v[16:17], v[16:17]
	v_pk_mul_f32 v[158:159], v[14:15], v[14:15]
	v_fma_f32 v11, s60, v239, v11
	v_pk_mov_b32 v[160:161], v[158:159], v[156:157] op_sel:[1,0]
	v_mov_b32_e32 v159, v157
	v_pk_add_f32 v[156:157], v[160:161], v[158:159]
	v_fma_f32 v10, s60, v239, v10
	v_fma_f32 v13, s60, v239, v13
	v_fmac_f32_e32 v12, s60, v239
	v_add_f32_e32 v167, v156, v157
	v_pk_mul_f32 v[156:157], v[12:13], v[12:13]
	v_pk_mul_f32 v[158:159], v[10:11], v[10:11]
	v_add_f32_dpp v109, v109, v109 quad_perm:[1,0,3,2] row_mask:0xf bank_mask:0xf bound_ctrl:1
	v_pk_mov_b32 v[160:161], v[158:159], v[156:157] op_sel:[1,0]
	v_mov_b32_e32 v159, v157
	v_pk_add_f32 v[156:157], v[160:161], v[158:159]
	v_add_f32_dpp v109, v109, v109 quad_perm:[2,3,0,1] row_mask:0xf bank_mask:0xf bound_ctrl:1
	v_add_f32_e32 v156, v156, v157
	v_add_f32_dpp v157, v162, v162 quad_perm:[1,0,3,2] row_mask:0xf bank_mask:0xf bound_ctrl:1
	v_add_f32_dpp v109, v109, v109 row_half_mirror row_mask:0xf bank_mask:0xf bound_ctrl:1
	v_add_f32_dpp v158, v163, v163 quad_perm:[1,0,3,2] row_mask:0xf bank_mask:0xf bound_ctrl:1
	v_add_f32_dpp v157, v157, v157 quad_perm:[2,3,0,1] row_mask:0xf bank_mask:0xf bound_ctrl:1
	v_add_f32_dpp v109, v109, v109 row_mirror row_mask:0xf bank_mask:0xf bound_ctrl:1
	s_nop 0
	v_add_f32_dpp v157, v157, v157 row_half_mirror row_mask:0xf bank_mask:0xf bound_ctrl:1
	v_add_f32_dpp v158, v158, v158 quad_perm:[2,3,0,1] row_mask:0xf bank_mask:0xf bound_ctrl:1
	v_add_f32_dpp v109, v109, v109 row_bcast:15 row_mask:0xa bank_mask:0xf
	v_add_f32_dpp v157, v157, v157 row_mirror row_mask:0xf bank_mask:0xf bound_ctrl:1
	v_add_f32_dpp v159, v164, v164 quad_perm:[1,0,3,2] row_mask:0xf bank_mask:0xf bound_ctrl:1
	v_add_f32_dpp v158, v158, v158 row_half_mirror row_mask:0xf bank_mask:0xf bound_ctrl:1
	v_add_f32_dpp v157, v157, v157 row_bcast:15 row_mask:0xa bank_mask:0xf
	v_add_f32_dpp v159, v159, v159 quad_perm:[2,3,0,1] row_mask:0xf bank_mask:0xf bound_ctrl:1
	v_add_f32_dpp v158, v158, v158 row_mirror row_mask:0xf bank_mask:0xf bound_ctrl:1
	v_add_f32_dpp v160, v165, v165 quad_perm:[1,0,3,2] row_mask:0xf bank_mask:0xf bound_ctrl:1
	v_add_f32_dpp v159, v159, v159 row_half_mirror row_mask:0xf bank_mask:0xf bound_ctrl:1
	v_add_f32_dpp v158, v158, v158 row_bcast:15 row_mask:0xa bank_mask:0xf
	v_add_f32_dpp v160, v160, v160 quad_perm:[2,3,0,1] row_mask:0xf bank_mask:0xf bound_ctrl:1
	v_add_f32_dpp v159, v159, v159 row_mirror row_mask:0xf bank_mask:0xf bound_ctrl:1
	v_add_f32_dpp v161, v166, v166 quad_perm:[1,0,3,2] row_mask:0xf bank_mask:0xf bound_ctrl:1
	v_add_f32_dpp v160, v160, v160 row_half_mirror row_mask:0xf bank_mask:0xf bound_ctrl:1
	v_add_f32_dpp v159, v159, v159 row_bcast:15 row_mask:0xa bank_mask:0xf
	v_add_f32_dpp v161, v161, v161 quad_perm:[2,3,0,1] row_mask:0xf bank_mask:0xf bound_ctrl:1
	v_add_f32_dpp v160, v160, v160 row_mirror row_mask:0xf bank_mask:0xf bound_ctrl:1
	v_add_f32_dpp v162, v167, v167 quad_perm:[1,0,3,2] row_mask:0xf bank_mask:0xf bound_ctrl:1
	v_add_f32_dpp v161, v161, v161 row_half_mirror row_mask:0xf bank_mask:0xf bound_ctrl:1
	v_add_f32_dpp v160, v160, v160 row_bcast:15 row_mask:0xa bank_mask:0xf
	v_add_f32_dpp v162, v162, v162 quad_perm:[2,3,0,1] row_mask:0xf bank_mask:0xf bound_ctrl:1
	v_add_f32_dpp v161, v161, v161 row_mirror row_mask:0xf bank_mask:0xf bound_ctrl:1
	v_add_f32_dpp v156, v156, v156 quad_perm:[1,0,3,2] row_mask:0xf bank_mask:0xf bound_ctrl:1
	v_add_f32_dpp v162, v162, v162 row_half_mirror row_mask:0xf bank_mask:0xf bound_ctrl:1
	v_add_f32_dpp v161, v161, v161 row_bcast:15 row_mask:0xa bank_mask:0xf
	v_add_f32_dpp v156, v156, v156 quad_perm:[2,3,0,1] row_mask:0xf bank_mask:0xf bound_ctrl:1
	v_add_f32_dpp v162, v162, v162 row_mirror row_mask:0xf bank_mask:0xf bound_ctrl:1
	s_nop 0
	v_add_f32_dpp v156, v156, v156 row_half_mirror row_mask:0xf bank_mask:0xf bound_ctrl:1
	s_ashr_i32 s29, s28, 31
	v_add_f32_dpp v162, v162, v162 row_bcast:15 row_mask:0xa bank_mask:0xf
	v_add_f32_dpp v156, v156, v156 row_mirror row_mask:0xf bank_mask:0xf bound_ctrl:1
	s_lshl_b64 s[8:9], s[28:29], 11
	s_add_u32 s8, s76, s8
	v_add_f32_dpp v156, v156, v156 row_bcast:15 row_mask:0xa bank_mask:0xf
	s_addc_u32 s9, s77, s9
	s_nop 0
	v_add_f32_dpp v109, v109, v109 row_bcast:31 row_mask:0xc bank_mask:0xf
	s_nop 0
	v_readlane_b32 s6, v109, 63
	s_nop 0
	v_add_f32_dpp v157, v157, v157 row_bcast:31 row_mask:0xc bank_mask:0xf
	v_fma_f32 v109, s6, v235, v225
	v_readlane_b32 s10, v157, 63
	v_add_f32_dpp v158, v158, v158 row_bcast:31 row_mask:0xc bank_mask:0xf
	s_nop 0
	v_readlane_b32 s11, v158, 63
	s_nop 0
	v_add_f32_dpp v159, v159, v159 row_bcast:31 row_mask:0xc bank_mask:0xf
	s_nop 0
	v_readlane_b32 s65, v159, 63
	s_nop 0
	v_add_f32_dpp v160, v160, v160 row_bcast:31 row_mask:0xc bank_mask:0xf
	s_nop 0
	v_readlane_b32 s61, v160, 63
	s_nop 0
	v_add_f32_dpp v161, v161, v161 row_bcast:31 row_mask:0xc bank_mask:0xf
	s_nop 0
	v_readlane_b32 s60, v161, 63
	s_nop 0
	v_add_f32_dpp v162, v162, v162 row_bcast:31 row_mask:0xc bank_mask:0xf
	v_mov_b32_e32 v163, v131
	v_readlane_b32 s7, v162, 63
	s_nop 0
	v_mov_b32_dpp v163, v156 row_bcast:31 row_mask:0xc bank_mask:0xf
	v_add_f32_e32 v163, v156, v163
	v_rsq_f32_e32 v156, v109
	v_readlane_b32 s6, v163, 63
	v_pk_mul_f32 v[38:39], v[38:39], v[156:157] op_sel_hi:[1,0]
	s_nop 0
	v_pk_fma_f32 v[38:39], v[2:3], v[38:39], v[6:7]
	v_pk_mul_f32 v[40:41], v[40:41], v[156:157] op_sel_hi:[1,0]
	v_mul_f32_e32 v109, 0xbfb8aa3b, v38
	v_exp_f32_e32 v109, v109
	v_mul_f32_e32 v156, 0xbfb8aa3b, v39
	v_exp_f32_e32 v157, v156
	v_pk_fma_f32 v[40:41], v[4:5], v[40:41], v[8:9]
	v_add_f32_e32 v109, 1.0, v109
	v_rcp_f32_e32 v156, v109
	v_add_f32_e32 v109, 1.0, v157
	v_mul_f32_e32 v157, 0xbfb8aa3b, v40
	v_exp_f32_e32 v158, v157
	v_mul_f32_e32 v157, 0xbfb8aa3b, v41
	v_exp_f32_e32 v159, v157
	v_rcp_f32_e32 v157, v109
	v_add_f32_e32 v109, 1.0, v158
	v_rcp_f32_e32 v158, v109
	v_add_f32_e32 v109, 1.0, v159
	v_rcp_f32_e32 v159, v109
	v_pk_mul_f32 v[38:39], v[38:39], v[156:157]
	v_lshlrev_b32_e32 v109, 3, v130
	v_cvt_pk_bf16_f32 v38, v38, v39
	v_pk_mul_f32 v[40:41], v[40:41], v[158:159]
	v_cvt_pk_bf16_f32 v39, v40, v41
	v_fma_f32 v40, s10, v235, v225
	v_rsq_f32_e32 v40, v40
	global_store_dwordx2 v109, v[38:39], s[8:9] offset:512
	s_add_i32 s8, s28, 8
	s_ashr_i32 s9, s8, 31
	v_pk_mul_f32 v[36:37], v[36:37], v[40:41] op_sel_hi:[1,0]
	v_pk_mul_f32 v[34:35], v[34:35], v[40:41] op_sel_hi:[1,0]
	v_pk_fma_f32 v[36:37], v[4:5], v[36:37], v[8:9]
	v_pk_fma_f32 v[34:35], v[2:3], v[34:35], v[6:7]
	v_mul_f32_e32 v130, 0xbfb8aa3b, v36
	v_mul_f32_e32 v40, 0xbfb8aa3b, v34
	v_mul_f32_e32 v41, 0xbfb8aa3b, v35
	v_exp_f32_e32 v130, v130
	v_mul_f32_e32 v156, 0xbfb8aa3b, v37
	v_exp_f32_e32 v40, v40
	v_exp_f32_e32 v41, v41
	v_exp_f32_e32 v157, v156
	v_add_f32_e32 v130, 1.0, v130
	v_add_f32_e32 v40, 1.0, v40
	v_add_f32_e32 v41, 1.0, v41
	v_rcp_f32_e32 v156, v130
	v_add_f32_e32 v130, 1.0, v157
	v_rcp_f32_e32 v40, v40
	v_rcp_f32_e32 v41, v41
	v_rcp_f32_e32 v157, v130
	s_lshl_b64 s[8:9], s[8:9], 11
	s_add_u32 s8, s76, s8
	v_pk_mul_f32 v[34:35], v[34:35], v[40:41]
	v_pk_mul_f32 v[36:37], v[36:37], v[156:157]
	v_cvt_pk_bf16_f32 v34, v34, v35
	v_cvt_pk_bf16_f32 v35, v36, v37
	v_fma_f32 v36, s11, v235, v225
	v_rsq_f32_e32 v36, v36
	s_addc_u32 s9, s77, s9
	global_store_dwordx2 v109, v[34:35], s[8:9] offset:512
	s_add_i32 s8, s28, 16
	v_pk_mul_f32 v[30:31], v[30:31], v[36:37] op_sel_hi:[1,0]
	v_pk_mul_f32 v[32:33], v[32:33], v[36:37] op_sel_hi:[1,0]
	v_pk_fma_f32 v[30:31], v[2:3], v[30:31], v[6:7]
	v_pk_fma_f32 v[32:33], v[4:5], v[32:33], v[8:9]
	v_mul_f32_e32 v36, 0xbfb8aa3b, v30
	v_mul_f32_e32 v37, 0xbfb8aa3b, v31
	v_mul_f32_e32 v38, 0xbfb8aa3b, v32
	v_mul_f32_e32 v39, 0xbfb8aa3b, v33
	v_exp_f32_e32 v36, v36
	v_exp_f32_e32 v37, v37
	v_exp_f32_e32 v38, v38
	v_exp_f32_e32 v39, v39
	v_add_f32_e32 v36, 1.0, v36
	v_add_f32_e32 v37, 1.0, v37
	v_add_f32_e32 v38, 1.0, v38
	v_add_f32_e32 v39, 1.0, v39
	v_rcp_f32_e32 v36, v36
	v_rcp_f32_e32 v37, v37
	v_rcp_f32_e32 v38, v38
	v_rcp_f32_e32 v39, v39
	s_ashr_i32 s9, s8, 31
	v_pk_mul_f32 v[30:31], v[30:31], v[36:37]
	s_lshl_b64 s[8:9], s[8:9], 11
	v_pk_mul_f32 v[32:33], v[32:33], v[38:39]
	v_cvt_pk_bf16_f32 v30, v30, v31
	v_cvt_pk_bf16_f32 v31, v32, v33
	v_fma_f32 v32, s65, v235, v225
	v_rsq_f32_e32 v32, v32
	s_add_u32 s8, s76, s8
	s_addc_u32 s9, s77, s9
	global_store_dwordx2 v109, v[30:31], s[8:9] offset:512
	v_pk_mul_f32 v[26:27], v[26:27], v[32:33] op_sel_hi:[1,0]
	v_pk_mul_f32 v[28:29], v[28:29], v[32:33] op_sel_hi:[1,0]
	v_pk_fma_f32 v[26:27], v[2:3], v[26:27], v[6:7]
	v_pk_fma_f32 v[28:29], v[4:5], v[28:29], v[8:9]
	v_mul_f32_e32 v32, 0xbfb8aa3b, v26
	v_mul_f32_e32 v33, 0xbfb8aa3b, v27
	v_mul_f32_e32 v34, 0xbfb8aa3b, v28
	v_mul_f32_e32 v35, 0xbfb8aa3b, v29
	v_exp_f32_e32 v32, v32
	v_exp_f32_e32 v33, v33
	v_exp_f32_e32 v34, v34
	v_exp_f32_e32 v35, v35
	v_add_f32_e32 v32, 1.0, v32
	v_add_f32_e32 v33, 1.0, v33
	v_add_f32_e32 v34, 1.0, v34
	v_add_f32_e32 v35, 1.0, v35
	v_rcp_f32_e32 v32, v32
	v_rcp_f32_e32 v33, v33
	v_rcp_f32_e32 v34, v34
	v_rcp_f32_e32 v35, v35
	s_add_i32 s8, s28, 24
	v_pk_mul_f32 v[26:27], v[26:27], v[32:33]
	s_ashr_i32 s9, s8, 31
	v_pk_mul_f32 v[28:29], v[28:29], v[34:35]
	v_cvt_pk_bf16_f32 v26, v26, v27
	v_cvt_pk_bf16_f32 v27, v28, v29
	v_fma_f32 v28, s61, v235, v225
	v_rsq_f32_e32 v28, v28
	s_lshl_b64 s[8:9], s[8:9], 11
	s_add_u32 s8, s76, s8
	s_addc_u32 s9, s77, s9
	v_pk_mul_f32 v[22:23], v[22:23], v[28:29] op_sel_hi:[1,0]
	v_pk_mul_f32 v[24:25], v[24:25], v[28:29] op_sel_hi:[1,0]
	v_pk_fma_f32 v[22:23], v[2:3], v[22:23], v[6:7]
	v_pk_fma_f32 v[24:25], v[4:5], v[24:25], v[8:9]
	v_mul_f32_e32 v28, 0xbfb8aa3b, v22
	v_mul_f32_e32 v29, 0xbfb8aa3b, v23
	v_mul_f32_e32 v30, 0xbfb8aa3b, v24
	v_mul_f32_e32 v31, 0xbfb8aa3b, v25
	v_exp_f32_e32 v28, v28
	v_exp_f32_e32 v29, v29
	v_exp_f32_e32 v30, v30
	v_exp_f32_e32 v31, v31
	v_add_f32_e32 v28, 1.0, v28
	v_add_f32_e32 v29, 1.0, v29
	v_add_f32_e32 v30, 1.0, v30
	v_add_f32_e32 v31, 1.0, v31
	v_rcp_f32_e32 v28, v28
	v_rcp_f32_e32 v29, v29
	v_rcp_f32_e32 v30, v30
	v_rcp_f32_e32 v31, v31
	global_store_dwordx2 v109, v[26:27], s[8:9] offset:512
	v_pk_mul_f32 v[22:23], v[22:23], v[28:29]
	s_add_i32 s8, s28, 32
	v_pk_mul_f32 v[24:25], v[24:25], v[30:31]
	v_cvt_pk_bf16_f32 v22, v22, v23
	v_cvt_pk_bf16_f32 v23, v24, v25
	v_fma_f32 v24, s60, v235, v225
	v_rsq_f32_e32 v24, v24
	s_ashr_i32 s9, s8, 31
	s_lshl_b64 s[8:9], s[8:9], 11
	s_add_u32 s8, s76, s8
	v_pk_mul_f32 v[18:19], v[18:19], v[24:25] op_sel_hi:[1,0]
	v_pk_mul_f32 v[20:21], v[20:21], v[24:25] op_sel_hi:[1,0]
	v_pk_fma_f32 v[18:19], v[2:3], v[18:19], v[6:7]
	v_pk_fma_f32 v[20:21], v[4:5], v[20:21], v[8:9]
	v_mul_f32_e32 v24, 0xbfb8aa3b, v18
	v_mul_f32_e32 v25, 0xbfb8aa3b, v19
	v_mul_f32_e32 v26, 0xbfb8aa3b, v20
	v_mul_f32_e32 v27, 0xbfb8aa3b, v21
	v_exp_f32_e32 v24, v24
	v_exp_f32_e32 v25, v25
	v_exp_f32_e32 v26, v26
	v_exp_f32_e32 v27, v27
	v_add_f32_e32 v24, 1.0, v24
	v_add_f32_e32 v25, 1.0, v25
	v_add_f32_e32 v26, 1.0, v26
	v_add_f32_e32 v27, 1.0, v27
	v_rcp_f32_e32 v24, v24
	v_rcp_f32_e32 v25, v25
	v_rcp_f32_e32 v26, v26
	v_rcp_f32_e32 v27, v27
	s_addc_u32 s9, s77, s9
	v_pk_mul_f32 v[18:19], v[18:19], v[24:25]
	global_store_dwordx2 v109, v[22:23], s[8:9] offset:512
	v_pk_mul_f32 v[20:21], v[20:21], v[26:27]
	v_cvt_pk_bf16_f32 v18, v18, v19
	v_cvt_pk_bf16_f32 v19, v20, v21
	v_fma_f32 v20, s7, v235, v225
	v_rsq_f32_e32 v20, v20
	s_add_i32 s8, s28, 40
	s_ashr_i32 s9, s8, 31
	s_lshl_b64 s[8:9], s[8:9], 11
	v_pk_mul_f32 v[14:15], v[14:15], v[20:21] op_sel_hi:[1,0]
	v_pk_mul_f32 v[16:17], v[16:17], v[20:21] op_sel_hi:[1,0]
	v_pk_fma_f32 v[14:15], v[2:3], v[14:15], v[6:7]
	v_pk_fma_f32 v[16:17], v[4:5], v[16:17], v[8:9]
	v_mul_f32_e32 v20, 0xbfb8aa3b, v14
	v_mul_f32_e32 v21, 0xbfb8aa3b, v15
	v_mul_f32_e32 v22, 0xbfb8aa3b, v16
	v_mul_f32_e32 v23, 0xbfb8aa3b, v17
	v_exp_f32_e32 v20, v20
	v_exp_f32_e32 v21, v21
	v_exp_f32_e32 v22, v22
	v_exp_f32_e32 v23, v23
	v_add_f32_e32 v20, 1.0, v20
	v_add_f32_e32 v21, 1.0, v21
	v_add_f32_e32 v22, 1.0, v22
	v_add_f32_e32 v23, 1.0, v23
	v_rcp_f32_e32 v20, v20
	v_rcp_f32_e32 v21, v21
	v_rcp_f32_e32 v22, v22
	v_rcp_f32_e32 v23, v23
	s_add_u32 s8, s76, s8
	v_pk_mul_f32 v[14:15], v[14:15], v[20:21]
	s_addc_u32 s9, s77, s9
	v_pk_mul_f32 v[16:17], v[16:17], v[22:23]
	v_cvt_pk_bf16_f32 v14, v14, v15
	v_cvt_pk_bf16_f32 v15, v16, v17
	v_fma_f32 v16, s6, v235, v225
	v_rsq_f32_e32 v16, v16
	global_store_dwordx2 v109, v[18:19], s[8:9] offset:512
	s_add_i32 s8, s28, 48
	s_ashr_i32 s9, s8, 31
	v_pk_mul_f32 v[10:11], v[10:11], v[16:17] op_sel_hi:[1,0]
	v_pk_mul_f32 v[12:13], v[12:13], v[16:17] op_sel_hi:[1,0]
	v_pk_fma_f32 v[10:11], v[2:3], v[10:11], v[6:7]
	v_pk_fma_f32 v[12:13], v[4:5], v[12:13], v[8:9]
	v_mul_f32_e32 v16, 0xbfb8aa3b, v10
	v_mul_f32_e32 v17, 0xbfb8aa3b, v11
	v_mul_f32_e32 v18, 0xbfb8aa3b, v12
	v_mul_f32_e32 v19, 0xbfb8aa3b, v13
	v_exp_f32_e32 v16, v16
	v_exp_f32_e32 v17, v17
	v_exp_f32_e32 v18, v18
	v_exp_f32_e32 v19, v19
	s_lshl_b64 s[6:7], s[8:9], 11
	s_add_u32 s6, s76, s6
	s_addc_u32 s7, s77, s7
	v_add_f32_e32 v16, 1.0, v16
	v_add_f32_e32 v17, 1.0, v17
	v_add_f32_e32 v18, 1.0, v18
	v_add_f32_e32 v19, 1.0, v19
	v_rcp_f32_e32 v16, v16
	v_rcp_f32_e32 v17, v17
	v_rcp_f32_e32 v18, v18
	v_rcp_f32_e32 v19, v19
	global_store_dwordx2 v109, v[14:15], s[6:7] offset:512
	s_add_i32 s6, s28, 56
	s_ashr_i32 s7, s6, 31
	s_lshl_b64 s[6:7], s[6:7], 11
	s_add_u32 s6, s76, s6
	v_pk_mul_f32 v[10:11], v[10:11], v[16:17]
	v_pk_mul_f32 v[12:13], v[12:13], v[18:19]
	s_addc_u32 s7, s77, s7
	s_addk_i32 s58, 0x80
	s_addk_i32 s57, 0x2000
	v_cvt_pk_bf16_f32 v10, v10, v11
	v_cvt_pk_bf16_f32 v11, v12, v13
	s_cmpk_gt_i32 s59, 0xff
	global_store_dwordx2 v109, v[10:11], s[6:7] offset:512
	s_barrier
	s_cbranch_scc1 .LBB0_313

.LBB0_314:
	s_andn2_b64 vcc, exec, s[28:29]
	s_cbranch_vccnz .LBB0_316
	v_mov_b32_e32 v1, v242
	s_mov_b32 s73, s11
	v_readfirstlane_b32 s5, v1
	s_ashr_i32 s65, s5, 6
	v_add_u32_e32 v6, s66, v1
	s_lshl_b32 s6, s65, 4
	v_readlane_b32 s66, v250, 31
	s_add_i32 s6, s6, s66
	s_mul_i32 s8, s6, 0x1800
	s_mul_hi_i32 s7, s6, 0x1800
	s_add_u32 s28, s80, s8
	s_addc_u32 s29, s81, s7
	s_or_b32 s7, s6, 1
	s_mul_hi_i32 s8, s7, 0x1800
	s_mulk_i32 s7, 0x1800
	v_and_b32_e32 v74, 63, v1
	s_add_u32 s40, s80, s7
	s_addc_u32 s41, s81, s8
	v_lshlrev_b32_e32 v44, 1, v74
	global_load_ushort v9, v44, s[40:41] offset:512
	global_load_ushort v20, v44, s[40:41] offset:640
	global_load_ushort v26, v44, s[40:41] offset:768
	global_load_ushort v30, v44, s[40:41] offset:896
	global_load_ushort v8, v44, s[28:29] offset:512
	global_load_ushort v21, v44, s[28:29] offset:640
	global_load_ushort v27, v44, s[28:29] offset:768
	global_load_ushort v31, v44, s[28:29] offset:896
	s_or_b32 s7, s6, 2
	s_mul_hi_i32 s9, s7, 0x1800
	s_mulk_i32 s7, 0x1800
	s_add_u32 s8, s80, s7
	s_addc_u32 s9, s81, s9
	s_or_b32 s7, s6, 3
	s_mul_hi_i32 s11, s7, 0x1800
	s_mulk_i32 s7, 0x1800
	s_add_u32 s10, s80, s7
	s_addc_u32 s11, s81, s11
	global_load_ushort v18, v44, s[10:11] offset:512
	global_load_ushort v19, v44, s[10:11] offset:640
	global_load_ushort v22, v44, s[10:11] offset:768
	global_load_ushort v32, v44, s[10:11] offset:896
	global_load_ushort v23, v44, s[8:9] offset:512
	global_load_ushort v28, v44, s[8:9] offset:640
	global_load_ushort v29, v44, s[8:9] offset:768
	global_load_ushort v33, v44, s[8:9] offset:896
	s_mov_b32 s8, 0xbf3a00e3
	v_mov_b64_e32 v[24:25], s[8:9]
	s_mov_b64 s[10:11], s[68:69]
	s_mov_b64 s[68:69], s[12:13]
	s_mov_b32 s12, 0x3f07dc22
	s_mov_b32 s14, 0x3f35f0e3
	s_mov_b32 s16, 0xbe11a98e
	s_mov_b32 s18, 0x3e027906
	s_or_b32 s7, s6, 4
	s_mul_hi_i32 s8, s7, 0x1800
	s_mulk_i32 s7, 0x1800
	s_add_u32 s28, s80, s7
	s_addc_u32 s29, s81, s8
	s_or_b32 s7, s6, 5
	s_mul_hi_i32 s8, s7, 0x1800
	s_mulk_i32 s7, 0x1800
	s_add_u32 s40, s80, s7
	s_addc_u32 s41, s81, s8
	s_or_b32 s7, s6, 6
	s_mul_hi_i32 s8, s7, 0x1800
	s_mulk_i32 s7, 0x1800
	s_add_u32 s58, s80, s7
	s_addc_u32 s59, s81, s8
	s_or_b32 s7, s6, 7
	s_mul_hi_i32 s8, s7, 0x1800
	s_mulk_i32 s7, 0x1800
	s_add_u32 s60, s80, s7
	s_addc_u32 s61, s81, s8
	s_or_b32 s7, s6, 8
	s_mul_hi_i32 s8, s7, 0x1800
	s_mulk_i32 s7, 0x1800
	v_or_b32_e32 v2, s84, v74
	s_add_u32 s46, s80, s7
	v_ashrrev_i32_e32 v3, 31, v2
	s_addc_u32 s47, s81, s8
	s_or_b32 s7, s6, 9
	v_lshlrev_b64 v[4:5], 2, v[2:3]
	s_mul_hi_i32 s8, s7, 0x1800
	s_mulk_i32 s7, 0x1800
	v_lshl_add_u64 v[2:3], s[52:53], 0, v[4:5]
	v_lshl_add_u64 v[4:5], s[54:55], 0, v[4:5]
	s_add_u32 s54, s80, s7
	s_addc_u32 s55, s81, s8
	s_or_b32 s7, s6, 10
	s_mul_hi_i32 s8, s7, 0x1800
	s_mulk_i32 s7, 0x1800
	s_add_u32 s48, s80, s7
	s_addc_u32 s49, s81, s8
	s_or_b32 s7, s6, 11
	s_mul_hi_i32 s8, s7, 0x1800
	s_mulk_i32 s7, 0x1800
	s_add_u32 s56, s80, s7
	s_addc_u32 s57, s81, s8
	s_or_b32 s7, s6, 12
	v_ashrrev_i32_e32 v7, 31, v6
	s_mul_hi_i32 s8, s7, 0x1800
	s_mulk_i32 s7, 0x1800
	v_lshl_add_u64 v[6:7], v[6:7], 2, s[42:43]
	s_add_u32 s42, s80, s7
	s_addc_u32 s43, s81, s8
	s_or_b32 s7, s6, 13
	s_waitcnt vmcnt(15)
	v_lshlrev_b32_e32 v9, 16, v9
	v_mul_f32_e32 v13, v9, v9
	v_mul_f32_e32 v13, 0xbf38aa3b, v13
	v_exp_f32_e32 v13, v13
	s_waitcnt vmcnt(11)
	v_lshlrev_b32_e32 v8, 16, v8
	v_mul_f32_e32 v11, v8, v8
	v_mul_f32_e32 v11, 0xbf38aa3b, v11
	v_fma_f32 v10, |v8|, s92, 1.0
	v_exp_f32_e32 v12, v11
	v_fma_f32 v11, |v9|, s92, 1.0
	v_rcp_f32_e32 v10, v10
	v_rcp_f32_e32 v11, v11
	v_cmp_gt_f32_e32 vcc, 0, v9
	s_mul_hi_i32 s8, s7, 0x1800
	s_mulk_i32 s7, 0x1800
	v_pk_fma_f32 v[14:15], v[10:11], s[12:13], v[24:25] op_sel_hi:[1,0,0]
	s_add_u32 s50, s80, s7
	v_pk_fma_f32 v[14:15], v[10:11], v[14:15], s[14:15] op_sel_hi:[1,1,0]
	s_addc_u32 s51, s81, s8
	v_pk_fma_f32 v[14:15], v[10:11], v[14:15], s[16:17] op_sel_hi:[1,1,0]
	s_or_b32 s7, s6, 14
	v_pk_fma_f32 v[14:15], v[10:11], v[14:15], s[18:19] op_sel_hi:[1,1,0]
	s_mul_hi_i32 s8, s7, 0x1800
	v_pk_mul_f32 v[10:11], v[10:11], v[14:15]
	s_mulk_i32 s7, 0x1800
	v_pk_mul_f32 v[10:11], v[12:13], v[10:11]
	s_add_u32 s44, s80, s7
	v_pk_mul_f32 v[12:13], v[10:11], v[8:9]
	v_pk_fma_f32 v[10:11], v[10:11], v[8:9], v[8:9] neg_lo:[1,0,0] neg_hi:[1,0,0]
	s_addc_u32 s45, s81, s8
	v_cndmask_b32_e32 v17, v11, v13, vcc
	v_cmp_gt_f32_e32 vcc, 0, v8
	s_waitcnt vmcnt(3)
	v_lshlrev_b32_e32 v8, 16, v23
	v_fma_f32 v9, |v8|, s92, 1.0
	v_mul_f32_e32 v11, v8, v8
	v_cndmask_b32_e32 v16, v10, v12, vcc
	v_rcp_f32_e32 v10, v9
	v_mul_f32_e32 v11, 0xbf38aa3b, v11
	v_lshlrev_b32_e32 v9, 16, v18
	v_exp_f32_e32 v12, v11
	v_fma_f32 v11, |v9|, s92, 1.0
	v_rcp_f32_e32 v11, v11
	v_mul_f32_e32 v13, v9, v9
	v_mul_f32_e32 v13, 0xbf38aa3b, v13
	v_exp_f32_e32 v13, v13
	v_pk_fma_f32 v[14:15], v[10:11], s[12:13], v[24:25] op_sel_hi:[1,0,0]
	v_cmp_gt_f32_e32 vcc, 0, v9
	v_pk_fma_f32 v[14:15], v[10:11], v[14:15], s[14:15] op_sel_hi:[1,1,0]
	s_or_b32 s6, s6, 15
	v_pk_fma_f32 v[14:15], v[10:11], v[14:15], s[16:17] op_sel_hi:[1,1,0]
	s_mul_hi_i32 s7, s6, 0x1800
	v_pk_fma_f32 v[14:15], v[10:11], v[14:15], s[18:19] op_sel_hi:[1,1,0]
	s_mulk_i32 s6, 0x1800
	v_pk_mul_f32 v[10:11], v[10:11], v[14:15]
	s_add_u32 s52, s80, s6
	v_pk_mul_f32 v[10:11], v[12:13], v[10:11]
	s_addc_u32 s53, s81, s7
	v_pk_mul_f32 v[12:13], v[10:11], v[8:9]
	v_pk_fma_f32 v[10:11], v[10:11], v[8:9], v[8:9] neg_lo:[1,0,0] neg_hi:[1,0,0]
	s_mov_b32 s8, 0x3b800000
	v_cndmask_b32_e32 v9, v11, v13, vcc
	v_cmp_gt_f32_e32 vcc, 0, v8
	s_ashr_i32 s5, s5, 7
	v_lshlrev_b32_e32 v130, 4, v74
	v_cndmask_b32_e32 v8, v10, v12, vcc
	s_waitcnt vmcnt(2)
	v_lshlrev_b32_e32 v10, 16, v28
	v_fma_f32 v11, |v10|, s92, 1.0
	v_rcp_f32_e32 v12, v11
	v_lshlrev_b32_e32 v11, 16, v19
	v_fma_f32 v13, |v11|, s92, 1.0
	v_rcp_f32_e32 v13, v13
	v_mul_f32_e32 v14, v10, v10
	v_mul_f32_e32 v15, v11, v11
	v_mul_f32_e32 v14, 0xbf38aa3b, v14
	v_pk_fma_f32 v[18:19], v[12:13], s[12:13], v[24:25] op_sel_hi:[1,0,0]
	v_mul_f32_e32 v15, 0xbf38aa3b, v15
	v_exp_f32_e32 v14, v14
	v_pk_fma_f32 v[18:19], v[12:13], v[18:19], s[14:15] op_sel_hi:[1,1,0]
	v_exp_f32_e32 v15, v15
	v_pk_fma_f32 v[18:19], v[12:13], v[18:19], s[16:17] op_sel_hi:[1,1,0]
	v_cmp_gt_f32_e32 vcc, 0, v11
	v_pk_fma_f32 v[18:19], v[12:13], v[18:19], s[18:19] op_sel_hi:[1,1,0]
	s_nop 0
	v_pk_mul_f32 v[12:13], v[12:13], v[18:19]
	v_pk_mul_f32 v[12:13], v[14:15], v[12:13]
	v_pk_mul_f32 v[14:15], v[12:13], v[10:11]
	v_pk_fma_f32 v[12:13], v[12:13], v[10:11], v[10:11] neg_lo:[1,0,0] neg_hi:[1,0,0]
	v_lshlrev_b32_e32 v11, 16, v20
	v_cndmask_b32_e32 v13, v13, v15, vcc
	v_cmp_gt_f32_e32 vcc, 0, v10
	v_lshlrev_b32_e32 v10, 16, v21
	v_mul_f32_e32 v15, v10, v10
	v_mul_f32_e32 v15, 0xbf38aa3b, v15
	v_cndmask_b32_e32 v12, v12, v14, vcc
	v_fma_f32 v14, |v10|, s92, 1.0
	v_exp_f32_e32 v18, v15
	v_fma_f32 v15, |v11|, s92, 1.0
	v_rcp_f32_e32 v14, v14
	v_rcp_f32_e32 v15, v15
	v_mul_f32_e32 v19, v11, v11
	v_mul_f32_e32 v19, 0xbf38aa3b, v19
	v_exp_f32_e32 v19, v19
	v_pk_fma_f32 v[20:21], v[14:15], s[12:13], v[24:25] op_sel_hi:[1,0,0]
	v_cmp_gt_f32_e32 vcc, 0, v11
	v_pk_fma_f32 v[20:21], v[14:15], v[20:21], s[14:15] op_sel_hi:[1,1,0]
	s_nop 0
	v_pk_fma_f32 v[20:21], v[14:15], v[20:21], s[16:17] op_sel_hi:[1,1,0]
	s_nop 0
	v_pk_fma_f32 v[20:21], v[14:15], v[20:21], s[18:19] op_sel_hi:[1,1,0]
	v_pk_mul_f32 v[14:15], v[14:15], v[20:21]
	v_pk_mul_f32 v[14:15], v[18:19], v[14:15]
	v_pk_mul_f32 v[18:19], v[14:15], v[10:11]
	v_pk_fma_f32 v[14:15], v[14:15], v[10:11], v[10:11] neg_lo:[1,0,0] neg_hi:[1,0,0]
	v_lshlrev_b32_e32 v11, 16, v22
	v_cndmask_b32_e32 v19, v15, v19, vcc
	v_cmp_gt_f32_e32 vcc, 0, v10
	s_waitcnt vmcnt(1)
	v_lshlrev_b32_e32 v10, 16, v29
	v_fma_f32 v15, |v11|, s92, 1.0
	v_cndmask_b32_e32 v18, v14, v18, vcc
	v_fma_f32 v14, |v10|, s92, 1.0
	v_rcp_f32_e32 v14, v14
	v_rcp_f32_e32 v15, v15
	v_mul_f32_e32 v20, v10, v10
	v_mul_f32_e32 v21, v11, v11
	v_mul_f32_e32 v20, 0xbf38aa3b, v20
	v_pk_fma_f32 v[22:23], v[14:15], s[12:13], v[24:25] op_sel_hi:[1,0,0]
	v_mul_f32_e32 v21, 0xbf38aa3b, v21
	v_exp_f32_e32 v20, v20
	v_pk_fma_f32 v[22:23], v[14:15], v[22:23], s[14:15] op_sel_hi:[1,1,0]
	v_exp_f32_e32 v21, v21
	v_pk_fma_f32 v[22:23], v[14:15], v[22:23], s[16:17] op_sel_hi:[1,1,0]
	v_cmp_gt_f32_e32 vcc, 0, v11
	v_pk_fma_f32 v[22:23], v[14:15], v[22:23], s[18:19] op_sel_hi:[1,1,0]
	s_nop 0
	v_pk_mul_f32 v[14:15], v[14:15], v[22:23]
	v_pk_mul_f32 v[14:15], v[20:21], v[14:15]
	v_pk_mul_f32 v[20:21], v[14:15], v[10:11]
	v_pk_fma_f32 v[14:15], v[14:15], v[10:11], v[10:11] neg_lo:[1,0,0] neg_hi:[1,0,0]
	v_lshlrev_b32_e32 v11, 16, v26
	v_cndmask_b32_e32 v21, v15, v21, vcc
	v_cmp_gt_f32_e32 vcc, 0, v10
	v_lshlrev_b32_e32 v10, 16, v27
	v_mul_f32_e32 v15, v10, v10
	v_mul_f32_e32 v15, 0xbf38aa3b, v15
	v_cndmask_b32_e32 v20, v14, v20, vcc
	v_fma_f32 v14, |v10|, s92, 1.0
	v_exp_f32_e32 v22, v15
	v_fma_f32 v15, |v11|, s92, 1.0
	v_rcp_f32_e32 v14, v14
	v_rcp_f32_e32 v15, v15
	v_mul_f32_e32 v23, v11, v11
	v_mul_f32_e32 v23, 0xbf38aa3b, v23
	v_exp_f32_e32 v23, v23
	v_pk_fma_f32 v[26:27], v[14:15], s[12:13], v[24:25] op_sel_hi:[1,0,0]
	v_cmp_gt_f32_e32 vcc, 0, v11
	v_pk_fma_f32 v[26:27], v[14:15], v[26:27], s[14:15] op_sel_hi:[1,1,0]
	s_nop 0
	v_pk_fma_f32 v[26:27], v[14:15], v[26:27], s[16:17] op_sel_hi:[1,1,0]
	s_nop 0
	v_pk_fma_f32 v[26:27], v[14:15], v[26:27], s[18:19] op_sel_hi:[1,1,0]
	v_pk_mul_f32 v[14:15], v[14:15], v[26:27]
	v_pk_mul_f32 v[14:15], v[22:23], v[14:15]
	v_pk_mul_f32 v[22:23], v[14:15], v[10:11]
	v_pk_fma_f32 v[14:15], v[14:15], v[10:11], v[10:11] neg_lo:[1,0,0] neg_hi:[1,0,0]
	v_lshlrev_b32_e32 v11, 16, v32
	v_cndmask_b32_e32 v29, v15, v23, vcc
	v_cmp_gt_f32_e32 vcc, 0, v10
	s_waitcnt vmcnt(0)
	v_lshlrev_b32_e32 v10, 16, v33
	v_fma_f32 v15, |v11|, s92, 1.0
	v_cndmask_b32_e32 v28, v14, v22, vcc
	v_fma_f32 v14, |v10|, s92, 1.0
	v_rcp_f32_e32 v14, v14
	v_rcp_f32_e32 v15, v15
	v_mul_f32_e32 v22, v10, v10
	v_mul_f32_e32 v23, v11, v11
	v_mul_f32_e32 v22, 0xbf38aa3b, v22
	v_pk_fma_f32 v[26:27], v[14:15], s[12:13], v[24:25] op_sel_hi:[1,0,0]
	v_mul_f32_e32 v23, 0xbf38aa3b, v23
	v_exp_f32_e32 v22, v22
	v_pk_fma_f32 v[26:27], v[14:15], v[26:27], s[14:15] op_sel_hi:[1,1,0]
	v_exp_f32_e32 v23, v23
	v_pk_fma_f32 v[26:27], v[14:15], v[26:27], s[16:17] op_sel_hi:[1,1,0]
	v_cmp_gt_f32_e32 vcc, 0, v11
	v_pk_fma_f32 v[26:27], v[14:15], v[26:27], s[18:19] op_sel_hi:[1,1,0]
	v_mov_b32_e32 v32, v19
	v_pk_mul_f32 v[14:15], v[14:15], v[26:27]
	v_pk_mul_f32 v[14:15], v[22:23], v[14:15]
	v_pk_mul_f32 v[22:23], v[14:15], v[10:11]
	v_pk_fma_f32 v[14:15], v[14:15], v[10:11], v[10:11] neg_lo:[1,0,0] neg_hi:[1,0,0]
	v_lshlrev_b32_e32 v11, 16, v30
	v_cndmask_b32_e32 v23, v15, v23, vcc
	v_cmp_gt_f32_e32 vcc, 0, v10
	v_lshlrev_b32_e32 v10, 16, v31
	v_mul_f32_e32 v15, v10, v10
	v_mul_f32_e32 v15, 0xbf38aa3b, v15
	v_cndmask_b32_e32 v22, v14, v22, vcc
	v_fma_f32 v14, |v10|, s92, 1.0
	v_exp_f32_e32 v26, v15
	v_fma_f32 v15, |v11|, s92, 1.0
	v_rcp_f32_e32 v14, v14
	v_rcp_f32_e32 v15, v15
	v_mul_f32_e32 v27, v11, v11
	v_mul_f32_e32 v27, 0xbf38aa3b, v27
	v_exp_f32_e32 v27, v27
	v_pk_fma_f32 v[30:31], v[14:15], s[12:13], v[24:25] op_sel_hi:[1,0,0]
	v_cmp_gt_f32_e32 vcc, 0, v11
	v_pk_fma_f32 v[30:31], v[14:15], v[30:31], s[14:15] op_sel_hi:[1,1,0]
	s_nop 0
	v_pk_fma_f32 v[30:31], v[14:15], v[30:31], s[16:17] op_sel_hi:[1,1,0]
	s_nop 0
	v_pk_fma_f32 v[30:31], v[14:15], v[30:31], s[18:19] op_sel_hi:[1,1,0]
	v_pk_mul_f32 v[14:15], v[14:15], v[30:31]
	v_pk_mul_f32 v[14:15], v[26:27], v[14:15]
	v_pk_mul_f32 v[26:27], v[14:15], v[10:11]
	v_pk_fma_f32 v[14:15], v[14:15], v[10:11], v[10:11] neg_lo:[1,0,0] neg_hi:[1,0,0]
	v_mov_b32_e32 v11, v20
	v_cndmask_b32_e32 v31, v15, v27, vcc
	v_cmp_gt_f32_e32 vcc, 0, v10
	v_mov_b32_e32 v10, v8
	v_mov_b32_e32 v15, v22
	v_cndmask_b32_e32 v30, v14, v26, vcc
	v_mov_b32_e32 v14, v12
	v_pk_add_f32 v[10:11], v[10:11], v[14:15]
	v_mov_b32_e32 v14, v9
	v_add_f32_e32 v10, v10, v11
	v_mov_b32_e32 v15, v21
	s_nop 0
	v_add_f32_dpp v10, v10, v10 quad_perm:[1,0,3,2] row_mask:0xf bank_mask:0xf bound_ctrl:1
	v_mov_b32_e32 v26, v13
	v_mov_b32_e32 v27, v23
	v_add_f32_dpp v10, v10, v10 quad_perm:[2,3,0,1] row_mask:0xf bank_mask:0xf bound_ctrl:1
	v_pk_add_f32 v[14:15], v[14:15], v[26:27]
	v_mov_b64_e32 v[26:27], s[8:9]
	v_add_f32_dpp v10, v10, v10 row_half_mirror row_mask:0xf bank_mask:0xf bound_ctrl:1
	v_mov_b32_e32 v33, v31
	s_mov_b32 s8, 0x3e027906
	v_add_f32_dpp v10, v10, v10 row_mirror row_mask:0xf bank_mask:0xf bound_ctrl:1
	s_nop 1
	v_add_f32_dpp v10, v10, v10 row_bcast:15 row_mask:0xa bank_mask:0xf
	s_nop 1
	v_add_f32_dpp v10, v10, v10 row_bcast:31 row_mask:0xc bank_mask:0xf
	v_add_f32_e32 v11, v14, v15
	v_readlane_b32 s6, v10, 63
	s_nop 0
	v_add_f32_dpp v11, v11, v11 quad_perm:[1,0,3,2] row_mask:0xf bank_mask:0xf bound_ctrl:1
	s_xor_b32 s6, s6, 0x80000000
	s_nop 0
	v_add_f32_dpp v11, v11, v11 quad_perm:[2,3,0,1] row_mask:0xf bank_mask:0xf bound_ctrl:1
	s_nop 1
	v_add_f32_dpp v11, v11, v11 row_half_mirror row_mask:0xf bank_mask:0xf bound_ctrl:1
	s_nop 1
	v_add_f32_dpp v11, v11, v11 row_mirror row_mask:0xf bank_mask:0xf bound_ctrl:1
	s_nop 1
	v_add_f32_dpp v11, v11, v11 row_bcast:15 row_mask:0xa bank_mask:0xf
	s_nop 1
	v_add_f32_dpp v11, v11, v11 row_bcast:31 row_mask:0xc bank_mask:0xf
	s_nop 0
	v_readlane_b32 s7, v11, 63
	s_xor_b32 s7, s7, 0x80000000
	s_nop 0
	v_pk_fma_f32 v[10:11], s[6:7], v[26:27], v[8:9] op_sel_hi:[1,0,1]
	v_pk_fma_f32 v[14:15], s[6:7], v[26:27], v[12:13] op_sel_hi:[1,0,1]
	v_pk_fma_f32 v[12:13], s[6:7], v[26:27], v[20:21] op_sel_hi:[1,0,1]
	v_pk_fma_f32 v[8:9], s[6:7], v[26:27], v[22:23] op_sel_hi:[1,0,1]
	v_mov_b32_e32 v20, v16
	v_mov_b32_e32 v21, v28
	v_mov_b32_e32 v22, v18
	v_mov_b32_e32 v23, v30
	v_pk_add_f32 v[20:21], v[20:21], v[22:23]
	v_mov_b32_e32 v22, v17
	v_add_f32_e32 v20, v20, v21
	v_mov_b32_e32 v23, v29
	s_nop 0
	v_add_f32_dpp v20, v20, v20 quad_perm:[1,0,3,2] row_mask:0xf bank_mask:0xf bound_ctrl:1
	v_pk_add_f32 v[22:23], v[22:23], v[32:33]
	s_nop 0
	v_add_f32_dpp v20, v20, v20 quad_perm:[2,3,0,1] row_mask:0xf bank_mask:0xf bound_ctrl:1
	s_nop 1
	v_add_f32_dpp v20, v20, v20 row_half_mirror row_mask:0xf bank_mask:0xf bound_ctrl:1
	s_nop 1
	v_add_f32_dpp v20, v20, v20 row_mirror row_mask:0xf bank_mask:0xf bound_ctrl:1
	s_nop 1
	v_add_f32_dpp v20, v20, v20 row_bcast:15 row_mask:0xa bank_mask:0xf
	s_nop 1
	v_add_f32_dpp v20, v20, v20 row_bcast:31 row_mask:0xc bank_mask:0xf
	v_add_f32_e32 v21, v22, v23
	v_readlane_b32 s6, v20, 63
	s_nop 0
	v_add_f32_dpp v21, v21, v21 quad_perm:[1,0,3,2] row_mask:0xf bank_mask:0xf bound_ctrl:1
	s_xor_b32 s6, s6, 0x80000000
	s_nop 0
	v_add_f32_dpp v21, v21, v21 quad_perm:[2,3,0,1] row_mask:0xf bank_mask:0xf bound_ctrl:1
	s_nop 1
	v_add_f32_dpp v21, v21, v21 row_half_mirror row_mask:0xf bank_mask:0xf bound_ctrl:1
	s_nop 1
	v_add_f32_dpp v21, v21, v21 row_mirror row_mask:0xf bank_mask:0xf bound_ctrl:1
	s_nop 1
	v_add_f32_dpp v21, v21, v21 row_bcast:15 row_mask:0xa bank_mask:0xf
	s_nop 1
	v_add_f32_dpp v21, v21, v21 row_bcast:31 row_mask:0xc bank_mask:0xf
	s_nop 0
	v_readlane_b32 s7, v21, 63
	s_xor_b32 s7, s7, 0x80000000
	s_nop 0
	v_pk_fma_f32 v[22:23], s[6:7], v[26:27], v[16:17] op_sel_hi:[1,0,1]
	v_pk_fma_f32 v[20:21], s[6:7], v[26:27], v[18:19] op_sel_hi:[1,0,1]
	v_pk_fma_f32 v[18:19], s[6:7], v[26:27], v[28:29] op_sel_hi:[1,0,1]
	v_pk_fma_f32 v[16:17], s[6:7], v[26:27], v[30:31] op_sel_hi:[1,0,1]
	global_load_ushort v28, v44, s[60:61] offset:512
	global_load_ushort v38, v44, s[60:61] offset:640
	global_load_ushort v42, v44, s[60:61] offset:768
	global_load_ushort v45, v44, s[60:61] offset:896
	global_load_ushort v30, v44, s[58:59] offset:512
	global_load_ushort v39, v44, s[58:59] offset:640
	global_load_ushort v43, v44, s[58:59] offset:768
	global_load_ushort v48, v44, s[58:59] offset:896
	s_waitcnt vmcnt(7)
	v_lshlrev_b32_e32 v29, 16, v28
	v_fma_f32 v31, |v29|, s92, 1.0
	v_rcp_f32_e32 v31, v31
	v_mul_f32_e32 v33, v29, v29
	s_waitcnt vmcnt(3)
	v_lshlrev_b32_e32 v28, 16, v30
	v_fma_f32 v30, |v28|, s92, 1.0
	v_rcp_f32_e32 v30, v30
	v_mul_f32_e32 v32, v28, v28
	v_mul_f32_e32 v32, 0xbf38aa3b, v32
	v_mul_f32_e32 v33, 0xbf38aa3b, v33
	v_pk_fma_f32 v[34:35], v[30:31], s[12:13], v[24:25] op_sel_hi:[1,0,0]
	v_exp_f32_e32 v32, v32
	v_pk_fma_f32 v[34:35], v[30:31], v[34:35], s[14:15] op_sel_hi:[1,1,0]
	v_exp_f32_e32 v33, v33
	v_pk_fma_f32 v[34:35], v[30:31], v[34:35], s[16:17] op_sel_hi:[1,1,0]
	v_cmp_gt_f32_e32 vcc, 0, v29
	v_pk_fma_f32 v[34:35], v[30:31], v[34:35], s[18:19] op_sel_hi:[1,1,0]
	s_nop 0
	v_pk_mul_f32 v[30:31], v[30:31], v[34:35]
	v_pk_mul_f32 v[30:31], v[32:33], v[30:31]
	v_pk_mul_f32 v[32:33], v[30:31], v[28:29]
	v_pk_fma_f32 v[30:31], v[30:31], v[28:29], v[28:29] neg_lo:[1,0,0] neg_hi:[1,0,0]
	s_nop 0
	v_cndmask_b32_e32 v29, v31, v33, vcc
	v_cmp_gt_f32_e32 vcc, 0, v28
	s_nop 1
	v_cndmask_b32_e32 v28, v30, v32, vcc
	global_load_ushort v30, v44, s[40:41] offset:512
	global_load_ushort v40, v44, s[40:41] offset:640
	global_load_ushort v46, v44, s[40:41] offset:768
	global_load_ushort v50, v44, s[40:41] offset:896
	global_load_ushort v32, v44, s[28:29] offset:512
	global_load_ushort v41, v44, s[28:29] offset:640
	global_load_ushort v47, v44, s[28:29] offset:768
	global_load_ushort v51, v44, s[28:29] offset:896
	s_movk_i32 s40, 0x110
	s_movk_i32 s41, 0x3000
	s_waitcnt vmcnt(7)
	v_lshlrev_b32_e32 v31, 16, v30
	v_mul_f32_e32 v35, v31, v31
	v_mul_f32_e32 v35, 0xbf38aa3b, v35
	v_exp_f32_e32 v35, v35
	s_waitcnt vmcnt(3)
	v_lshlrev_b32_e32 v30, 16, v32
	v_mul_f32_e32 v33, v30, v30
	v_mul_f32_e32 v33, 0xbf38aa3b, v33
	v_fma_f32 v32, |v30|, s92, 1.0
	v_exp_f32_e32 v34, v33
	v_fma_f32 v33, |v31|, s92, 1.0
	v_rcp_f32_e32 v32, v32
	v_rcp_f32_e32 v33, v33
	v_cmp_gt_f32_e32 vcc, 0, v31
	v_pk_fma_f32 v[36:37], v[32:33], s[12:13], v[24:25] op_sel_hi:[1,0,0]
	s_nop 0
	v_pk_fma_f32 v[36:37], v[32:33], v[36:37], s[14:15] op_sel_hi:[1,1,0]
	s_nop 0
	v_pk_fma_f32 v[36:37], v[32:33], v[36:37], s[16:17] op_sel_hi:[1,1,0]
	s_nop 0
	v_pk_fma_f32 v[36:37], v[32:33], v[36:37], s[18:19] op_sel_hi:[1,1,0]
	v_pk_mul_f32 v[32:33], v[32:33], v[36:37]
	v_pk_mul_f32 v[32:33], v[34:35], v[32:33]
	v_pk_mul_f32 v[34:35], v[32:33], v[30:31]
	v_pk_fma_f32 v[32:33], v[32:33], v[30:31], v[30:31] neg_lo:[1,0,0] neg_hi:[1,0,0]
	v_lshlrev_b32_e32 v31, 16, v38
	v_cndmask_b32_e32 v37, v33, v35, vcc
	v_cmp_gt_f32_e32 vcc, 0, v30
	v_lshlrev_b32_e32 v30, 16, v39
	v_fma_f32 v33, |v31|, s92, 1.0
	v_cndmask_b32_e32 v36, v32, v34, vcc
	v_fma_f32 v32, |v30|, s92, 1.0
	v_rcp_f32_e32 v32, v32
	v_rcp_f32_e32 v33, v33
	v_mul_f32_e32 v34, v30, v30
	v_mul_f32_e32 v35, v31, v31
	v_mul_f32_e32 v34, 0xbf38aa3b, v34
	v_pk_fma_f32 v[38:39], v[32:33], s[12:13], v[24:25] op_sel_hi:[1,0,0]
	v_mul_f32_e32 v35, 0xbf38aa3b, v35
	v_exp_f32_e32 v34, v34
	v_pk_fma_f32 v[38:39], v[32:33], v[38:39], s[14:15] op_sel_hi:[1,1,0]
	v_exp_f32_e32 v35, v35
	v_pk_fma_f32 v[38:39], v[32:33], v[38:39], s[16:17] op_sel_hi:[1,1,0]
	v_cmp_gt_f32_e32 vcc, 0, v31
	v_pk_fma_f32 v[38:39], v[32:33], v[38:39], s[18:19] op_sel_hi:[1,1,0]
	s_nop 0
	v_pk_mul_f32 v[32:33], v[32:33], v[38:39]
	v_pk_mul_f32 v[32:33], v[34:35], v[32:33]
	v_pk_mul_f32 v[34:35], v[32:33], v[30:31]
	v_pk_fma_f32 v[32:33], v[32:33], v[30:31], v[30:31] neg_lo:[1,0,0] neg_hi:[1,0,0]
	s_nop 0
	v_cndmask_b32_e32 v31, v33, v35, vcc
	v_cmp_gt_f32_e32 vcc, 0, v30
	v_lshlrev_b32_e32 v33, 16, v40
	v_mul_f32_e32 v39, v33, v33
	v_cndmask_b32_e32 v30, v32, v34, vcc
	s_waitcnt vmcnt(2)
	v_lshlrev_b32_e32 v32, 16, v41
	v_mul_f32_e32 v35, v32, v32
	v_mul_f32_e32 v35, 0xbf38aa3b, v35
	v_fma_f32 v34, |v32|, s92, 1.0
	v_exp_f32_e32 v38, v35
	v_fma_f32 v35, |v33|, s92, 1.0
	v_rcp_f32_e32 v34, v34
	v_rcp_f32_e32 v35, v35
	v_mul_f32_e32 v39, 0xbf38aa3b, v39
	v_exp_f32_e32 v39, v39
	v_cmp_gt_f32_e32 vcc, 0, v33
	v_pk_fma_f32 v[40:41], v[34:35], s[12:13], v[24:25] op_sel_hi:[1,0,0]
	s_nop 0
	v_pk_fma_f32 v[40:41], v[34:35], v[40:41], s[14:15] op_sel_hi:[1,1,0]
	s_nop 0
	v_pk_fma_f32 v[40:41], v[34:35], v[40:41], s[16:17] op_sel_hi:[1,1,0]
	s_nop 0
	v_pk_fma_f32 v[40:41], v[34:35], v[40:41], s[18:19] op_sel_hi:[1,1,0]
	v_pk_mul_f32 v[34:35], v[34:35], v[40:41]
	v_pk_mul_f32 v[34:35], v[38:39], v[34:35]
	v_pk_mul_f32 v[38:39], v[34:35], v[32:33]
	v_pk_fma_f32 v[34:35], v[34:35], v[32:33], v[32:33] neg_lo:[1,0,0] neg_hi:[1,0,0]
	v_lshlrev_b32_e32 v33, 16, v42
	v_cndmask_b32_e32 v39, v35, v39, vcc
	v_cmp_gt_f32_e32 vcc, 0, v32
	v_lshlrev_b32_e32 v32, 16, v43
	v_fma_f32 v35, |v33|, s92, 1.0
	v_cndmask_b32_e32 v38, v34, v38, vcc
	v_fma_f32 v34, |v32|, s92, 1.0
	v_rcp_f32_e32 v34, v34
	v_rcp_f32_e32 v35, v35
	v_mul_f32_e32 v40, v32, v32
	v_mul_f32_e32 v41, v33, v33
	v_mul_f32_e32 v40, 0xbf38aa3b, v40
	v_pk_fma_f32 v[42:43], v[34:35], s[12:13], v[24:25] op_sel_hi:[1,0,0]
	v_mul_f32_e32 v41, 0xbf38aa3b, v41
	v_exp_f32_e32 v40, v40
	v_pk_fma_f32 v[42:43], v[34:35], v[42:43], s[14:15] op_sel_hi:[1,1,0]
	v_exp_f32_e32 v41, v41
	v_pk_fma_f32 v[42:43], v[34:35], v[42:43], s[16:17] op_sel_hi:[1,1,0]
	v_cmp_gt_f32_e32 vcc, 0, v33
	v_pk_fma_f32 v[42:43], v[34:35], v[42:43], s[18:19] op_sel_hi:[1,1,0]
	s_nop 0
	v_pk_mul_f32 v[34:35], v[34:35], v[42:43]
	v_pk_mul_f32 v[34:35], v[40:41], v[34:35]
	v_pk_mul_f32 v[40:41], v[34:35], v[32:33]
	v_pk_fma_f32 v[34:35], v[34:35], v[32:33], v[32:33] neg_lo:[1,0,0] neg_hi:[1,0,0]
	v_lshlrev_b32_e32 v33, 16, v46
	v_cndmask_b32_e32 v41, v35, v41, vcc
	v_cmp_gt_f32_e32 vcc, 0, v32
	s_waitcnt vmcnt(1)
	v_lshlrev_b32_e32 v32, 16, v47
	v_mul_f32_e32 v35, v32, v32
	v_mul_f32_e32 v35, 0xbf38aa3b, v35
	v_cndmask_b32_e32 v40, v34, v40, vcc
	v_fma_f32 v34, |v32|, s92, 1.0
	v_exp_f32_e32 v42, v35
	v_fma_f32 v35, |v33|, s92, 1.0
	v_rcp_f32_e32 v34, v34
	v_rcp_f32_e32 v35, v35
	v_mul_f32_e32 v43, v33, v33
	v_mul_f32_e32 v43, 0xbf38aa3b, v43
	v_exp_f32_e32 v43, v43
	v_pk_fma_f32 v[46:47], v[34:35], s[12:13], v[24:25] op_sel_hi:[1,0,0]
	v_cmp_gt_f32_e32 vcc, 0, v33
	v_pk_fma_f32 v[46:47], v[34:35], v[46:47], s[14:15] op_sel_hi:[1,1,0]
	s_nop 0
	v_pk_fma_f32 v[46:47], v[34:35], v[46:47], s[16:17] op_sel_hi:[1,1,0]
	s_nop 0
	v_pk_fma_f32 v[46:47], v[34:35], v[46:47], s[18:19] op_sel_hi:[1,1,0]
	v_pk_mul_f32 v[34:35], v[34:35], v[46:47]
	v_pk_mul_f32 v[34:35], v[42:43], v[34:35]
	v_pk_mul_f32 v[42:43], v[34:35], v[32:33]
	v_pk_fma_f32 v[34:35], v[34:35], v[32:33], v[32:33] neg_lo:[1,0,0] neg_hi:[1,0,0]
	v_lshlrev_b32_e32 v33, 16, v45
	v_cndmask_b32_e32 v47, v35, v43, vcc
	v_cmp_gt_f32_e32 vcc, 0, v32
	v_lshlrev_b32_e32 v32, 16, v48
	v_fma_f32 v35, |v33|, s92, 1.0
	v_cndmask_b32_e32 v46, v34, v42, vcc
	v_fma_f32 v34, |v32|, s92, 1.0
	v_rcp_f32_e32 v34, v34
	v_rcp_f32_e32 v35, v35
	v_mul_f32_e32 v42, v32, v32
	v_mul_f32_e32 v43, v33, v33
	v_mul_f32_e32 v42, 0xbf38aa3b, v42
	v_pk_fma_f32 v[48:49], v[34:35], s[12:13], v[24:25] op_sel_hi:[1,0,0]
	v_mul_f32_e32 v43, 0xbf38aa3b, v43
	v_exp_f32_e32 v42, v42
	v_pk_fma_f32 v[48:49], v[34:35], v[48:49], s[14:15] op_sel_hi:[1,1,0]
	v_exp_f32_e32 v43, v43
	v_pk_fma_f32 v[48:49], v[34:35], v[48:49], s[16:17] op_sel_hi:[1,1,0]
	v_cmp_gt_f32_e32 vcc, 0, v33
	v_pk_fma_f32 v[48:49], v[34:35], v[48:49], s[18:19] op_sel_hi:[1,1,0]
	s_nop 0
	v_pk_mul_f32 v[34:35], v[34:35], v[48:49]
	v_pk_mul_f32 v[34:35], v[42:43], v[34:35]
	v_pk_mul_f32 v[42:43], v[34:35], v[32:33]
	v_pk_fma_f32 v[34:35], v[34:35], v[32:33], v[32:33] neg_lo:[1,0,0] neg_hi:[1,0,0]
	v_lshlrev_b32_e32 v33, 16, v50
	v_cndmask_b32_e32 v43, v35, v43, vcc
	v_cmp_gt_f32_e32 vcc, 0, v32
	s_waitcnt vmcnt(0)
	v_lshlrev_b32_e32 v32, 16, v51
	v_mul_f32_e32 v35, v32, v32
	v_mul_f32_e32 v35, 0xbf38aa3b, v35
	v_cndmask_b32_e32 v42, v34, v42, vcc
	v_fma_f32 v34, |v32|, s92, 1.0
	v_exp_f32_e32 v48, v35
	v_fma_f32 v35, |v33|, s92, 1.0
	v_rcp_f32_e32 v34, v34
	v_rcp_f32_e32 v35, v35
	v_mul_f32_e32 v45, v33, v33
	v_mul_f32_e32 v45, 0xbf38aa3b, v45
	v_exp_f32_e32 v49, v45
	v_pk_fma_f32 v[50:51], v[34:35], s[12:13], v[24:25] op_sel_hi:[1,0,0]
	v_cmp_gt_f32_e32 vcc, 0, v33
	v_pk_fma_f32 v[50:51], v[34:35], v[50:51], s[14:15] op_sel_hi:[1,1,0]
	s_nop 0
	v_pk_fma_f32 v[50:51], v[34:35], v[50:51], s[16:17] op_sel_hi:[1,1,0]
	s_nop 0
	v_pk_fma_f32 v[50:51], v[34:35], v[50:51], s[18:19] op_sel_hi:[1,1,0]
	v_pk_mul_f32 v[34:35], v[34:35], v[50:51]
	v_mov_b32_e32 v50, v31
	v_pk_mul_f32 v[34:35], v[48:49], v[34:35]
	v_mov_b32_e32 v51, v43
	v_pk_mul_f32 v[48:49], v[34:35], v[32:33]
	v_pk_fma_f32 v[34:35], v[34:35], v[32:33], v[32:33] neg_lo:[1,0,0] neg_hi:[1,0,0]
	v_mov_b32_e32 v33, v40
	v_cndmask_b32_e32 v49, v35, v49, vcc
	v_cmp_gt_f32_e32 vcc, 0, v32
	v_mov_b32_e32 v32, v28
	v_mov_b32_e32 v35, v42
	v_cndmask_b32_e32 v48, v34, v48, vcc
	v_mov_b32_e32 v34, v30
	v_pk_add_f32 v[32:33], v[32:33], v[34:35]
	v_mov_b32_e32 v34, v29
	v_add_f32_e32 v32, v32, v33
	v_mov_b32_e32 v35, v41
	s_nop 0
	v_add_f32_dpp v32, v32, v32 quad_perm:[1,0,3,2] row_mask:0xf bank_mask:0xf bound_ctrl:1
	v_pk_add_f32 v[34:35], v[34:35], v[50:51]
	v_mov_b32_e32 v50, v39
	v_add_f32_dpp v32, v32, v32 quad_perm:[2,3,0,1] row_mask:0xf bank_mask:0xf bound_ctrl:1
	v_mov_b32_e32 v51, v49
	s_nop 0
	v_add_f32_dpp v32, v32, v32 row_half_mirror row_mask:0xf bank_mask:0xf bound_ctrl:1
	s_nop 1
	v_add_f32_dpp v32, v32, v32 row_mirror row_mask:0xf bank_mask:0xf bound_ctrl:1
	s_nop 1
	v_add_f32_dpp v32, v32, v32 row_bcast:15 row_mask:0xa bank_mask:0xf
	s_nop 1
	v_add_f32_dpp v32, v32, v32 row_bcast:31 row_mask:0xc bank_mask:0xf
	v_add_f32_e32 v33, v34, v35
	v_readlane_b32 s6, v32, 63
	s_nop 0
	v_add_f32_dpp v33, v33, v33 quad_perm:[1,0,3,2] row_mask:0xf bank_mask:0xf bound_ctrl:1
	s_xor_b32 s6, s6, 0x80000000
	s_nop 0
	v_add_f32_dpp v33, v33, v33 quad_perm:[2,3,0,1] row_mask:0xf bank_mask:0xf bound_ctrl:1
	s_nop 1
	v_add_f32_dpp v33, v33, v33 row_half_mirror row_mask:0xf bank_mask:0xf bound_ctrl:1
	s_nop 1
	v_add_f32_dpp v33, v33, v33 row_mirror row_mask:0xf bank_mask:0xf bound_ctrl:1
	s_nop 1
	v_add_f32_dpp v33, v33, v33 row_bcast:15 row_mask:0xa bank_mask:0xf
	s_nop 1
	v_add_f32_dpp v33, v33, v33 row_bcast:31 row_mask:0xc bank_mask:0xf
	s_nop 0
	v_readlane_b32 s7, v33, 63
	s_xor_b32 s7, s7, 0x80000000
	s_nop 0
	v_pk_fma_f32 v[34:35], s[6:7], v[26:27], v[28:29] op_sel_hi:[1,0,1]
	v_pk_fma_f32 v[32:33], s[6:7], v[26:27], v[30:31] op_sel_hi:[1,0,1]
	v_pk_fma_f32 v[30:31], s[6:7], v[26:27], v[40:41] op_sel_hi:[1,0,1]
	v_pk_fma_f32 v[28:29], s[6:7], v[26:27], v[42:43] op_sel_hi:[1,0,1]
	v_mov_b32_e32 v40, v36
	v_mov_b32_e32 v41, v46
	v_mov_b32_e32 v42, v38
	v_mov_b32_e32 v43, v48
	v_pk_add_f32 v[40:41], v[40:41], v[42:43]
	v_mov_b32_e32 v42, v37
	v_add_f32_e32 v40, v40, v41
	v_mov_b32_e32 v43, v47
	s_nop 0
	v_add_f32_dpp v40, v40, v40 quad_perm:[1,0,3,2] row_mask:0xf bank_mask:0xf bound_ctrl:1
	v_pk_add_f32 v[42:43], v[42:43], v[50:51]
	s_nop 0
	v_add_f32_dpp v40, v40, v40 quad_perm:[2,3,0,1] row_mask:0xf bank_mask:0xf bound_ctrl:1
	s_nop 1
	v_add_f32_dpp v40, v40, v40 row_half_mirror row_mask:0xf bank_mask:0xf bound_ctrl:1
	s_nop 1
	v_add_f32_dpp v40, v40, v40 row_mirror row_mask:0xf bank_mask:0xf bound_ctrl:1
	s_nop 1
	v_add_f32_dpp v40, v40, v40 row_bcast:15 row_mask:0xa bank_mask:0xf
	s_nop 1
	v_add_f32_dpp v40, v40, v40 row_bcast:31 row_mask:0xc bank_mask:0xf
	v_add_f32_e32 v41, v42, v43
	v_readlane_b32 s6, v40, 63
	s_nop 0
	v_add_f32_dpp v41, v41, v41 quad_perm:[1,0,3,2] row_mask:0xf bank_mask:0xf bound_ctrl:1
	s_xor_b32 s6, s6, 0x80000000
	s_nop 0
	v_add_f32_dpp v41, v41, v41 quad_perm:[2,3,0,1] row_mask:0xf bank_mask:0xf bound_ctrl:1
	s_nop 1
	v_add_f32_dpp v41, v41, v41 row_half_mirror row_mask:0xf bank_mask:0xf bound_ctrl:1
	s_nop 1
	v_add_f32_dpp v41, v41, v41 row_mirror row_mask:0xf bank_mask:0xf bound_ctrl:1
	s_nop 1
	v_add_f32_dpp v41, v41, v41 row_bcast:15 row_mask:0xa bank_mask:0xf
	s_nop 1
	v_add_f32_dpp v41, v41, v41 row_bcast:31 row_mask:0xc bank_mask:0xf
	s_nop 0
	v_readlane_b32 s7, v41, 63
	s_xor_b32 s7, s7, 0x80000000
	s_nop 0
	v_pk_fma_f32 v[40:41], s[6:7], v[26:27], v[38:39] op_sel_hi:[1,0,1]
	v_pk_fma_f32 v[38:39], s[6:7], v[26:27], v[46:47] op_sel_hi:[1,0,1]
	global_load_ushort v52, v44, s[54:55] offset:512
	global_load_ushort v56, v44, s[54:55] offset:640
	global_load_ushort v77, v44, s[54:55] offset:768
	global_load_ushort v82, v44, s[54:55] offset:896
	global_load_ushort v53, v44, s[46:47] offset:512
	global_load_ushort v57, v44, s[46:47] offset:640
	global_load_ushort v78, v44, s[46:47] offset:768
	global_load_ushort v83, v44, s[46:47] offset:896
	global_load_ushort v45, v44, s[56:57] offset:512
	global_load_ushort v54, v44, s[56:57] offset:640
	global_load_ushort v58, v44, s[56:57] offset:768
	global_load_ushort v80, v44, s[56:57] offset:896
	global_load_ushort v46, v44, s[48:49] offset:512
	global_load_ushort v55, v44, s[48:49] offset:640
	global_load_ushort v59, v44, s[48:49] offset:768
	global_load_ushort v81, v44, s[48:49] offset:896
	global_load_ushort v66, v44, s[50:51] offset:512
	global_load_ushort v68, v44, s[50:51] offset:640
	global_load_ushort v72, v44, s[50:51] offset:768
	global_load_ushort v64, v44, s[50:51] offset:896
	global_load_ushort v67, v44, s[42:43] offset:512
	global_load_ushort v69, v44, s[42:43] offset:640
	global_load_ushort v73, v44, s[42:43] offset:768
	global_load_ushort v65, v44, s[42:43] offset:896
	global_load_ushort v60, v44, s[52:53] offset:512
	global_load_ushort v62, v44, s[52:53] offset:640
	global_load_ushort v75, v44, s[52:53] offset:768
	global_load_ushort v70, v44, s[52:53] offset:896
	global_load_ushort v61, v44, s[44:45] offset:512
	global_load_ushort v63, v44, s[44:45] offset:640
	global_load_ushort v76, v44, s[44:45] offset:768
	global_load_ushort v71, v44, s[44:45] offset:896
	v_pk_fma_f32 v[42:43], s[6:7], v[26:27], v[36:37] op_sel_hi:[1,0,1]
	v_pk_fma_f32 v[36:37], s[6:7], v[26:27], v[48:49] op_sel_hi:[1,0,1]
	s_movk_i32 s46, 0x2000
	s_waitcnt vmcnt(23)
	v_lshlrev_b32_e32 v45, 16, v45
	v_fma_f32 v47, |v45|, s92, 1.0
	v_rcp_f32_e32 v47, v47
	v_mul_f32_e32 v49, v45, v45
	s_waitcnt vmcnt(19)
	v_lshlrev_b32_e32 v44, 16, v46
	v_fma_f32 v46, |v44|, s92, 1.0
	v_rcp_f32_e32 v46, v46
	v_mul_f32_e32 v48, v44, v44
	v_mul_f32_e32 v48, 0xbf38aa3b, v48
	v_mul_f32_e32 v49, 0xbf38aa3b, v49
	v_pk_fma_f32 v[50:51], v[46:47], s[12:13], v[24:25] op_sel_hi:[1,0,0]
	v_exp_f32_e32 v48, v48
	v_pk_fma_f32 v[50:51], v[46:47], v[50:51], s[14:15] op_sel_hi:[1,1,0]
	v_exp_f32_e32 v49, v49
	v_pk_fma_f32 v[50:51], v[46:47], v[50:51], s[16:17] op_sel_hi:[1,1,0]
	v_cmp_gt_f32_e32 vcc, 0, v45
	v_pk_fma_f32 v[50:51], v[46:47], v[50:51], s[18:19] op_sel_hi:[1,1,0]
	s_waitcnt vmcnt(1)
	v_lshlrev_b32_e32 v76, 16, v76
	v_pk_mul_f32 v[46:47], v[46:47], v[50:51]
	v_pk_mul_f32 v[46:47], v[48:49], v[46:47]
	v_pk_mul_f32 v[48:49], v[46:47], v[44:45]
	v_pk_fma_f32 v[46:47], v[46:47], v[44:45], v[44:45] neg_lo:[1,0,0] neg_hi:[1,0,0]
	s_nop 0
	v_cndmask_b32_e32 v45, v47, v49, vcc
	v_cmp_gt_f32_e32 vcc, 0, v44
	v_lshlrev_b32_e32 v47, 16, v52
	v_mul_f32_e32 v51, v47, v47
	v_cndmask_b32_e32 v44, v46, v48, vcc
	v_lshlrev_b32_e32 v46, 16, v53
	v_mul_f32_e32 v49, v46, v46
	v_mul_f32_e32 v49, 0xbf38aa3b, v49
	v_fma_f32 v48, |v46|, s92, 1.0
	v_exp_f32_e32 v50, v49
	v_fma_f32 v49, |v47|, s92, 1.0
	v_rcp_f32_e32 v48, v48
	v_rcp_f32_e32 v49, v49
	v_mul_f32_e32 v51, 0xbf38aa3b, v51
	v_exp_f32_e32 v51, v51
	v_cmp_gt_f32_e32 vcc, 0, v47
	v_pk_fma_f32 v[52:53], v[48:49], s[12:13], v[24:25] op_sel_hi:[1,0,0]
	s_nop 0
	v_pk_fma_f32 v[52:53], v[48:49], v[52:53], s[14:15] op_sel_hi:[1,1,0]
	s_nop 0
	v_pk_fma_f32 v[52:53], v[48:49], v[52:53], s[16:17] op_sel_hi:[1,1,0]
	s_nop 0
	v_pk_fma_f32 v[52:53], v[48:49], v[52:53], s[18:19] op_sel_hi:[1,1,0]
	v_pk_mul_f32 v[48:49], v[48:49], v[52:53]
	v_pk_mul_f32 v[48:49], v[50:51], v[48:49]
	v_pk_mul_f32 v[50:51], v[48:49], v[46:47]
	v_pk_fma_f32 v[48:49], v[48:49], v[46:47], v[46:47] neg_lo:[1,0,0] neg_hi:[1,0,0]
	v_lshlrev_b32_e32 v47, 16, v54
	v_cndmask_b32_e32 v53, v49, v51, vcc
	v_cmp_gt_f32_e32 vcc, 0, v46
	v_lshlrev_b32_e32 v46, 16, v55
	v_fma_f32 v49, |v47|, s92, 1.0
	v_cndmask_b32_e32 v52, v48, v50, vcc
	v_fma_f32 v48, |v46|, s92, 1.0
	v_rcp_f32_e32 v48, v48
	v_rcp_f32_e32 v49, v49
	v_mul_f32_e32 v50, v46, v46
	v_mul_f32_e32 v51, v47, v47
	v_mul_f32_e32 v50, 0xbf38aa3b, v50
	v_pk_fma_f32 v[54:55], v[48:49], s[12:13], v[24:25] op_sel_hi:[1,0,0]
	v_mul_f32_e32 v51, 0xbf38aa3b, v51
	v_exp_f32_e32 v50, v50
	v_pk_fma_f32 v[54:55], v[48:49], v[54:55], s[14:15] op_sel_hi:[1,1,0]
	v_exp_f32_e32 v51, v51
	v_pk_fma_f32 v[54:55], v[48:49], v[54:55], s[16:17] op_sel_hi:[1,1,0]
	v_cmp_gt_f32_e32 vcc, 0, v47
	v_pk_fma_f32 v[54:55], v[48:49], v[54:55], s[18:19] op_sel_hi:[1,1,0]
	s_nop 0
	v_pk_mul_f32 v[48:49], v[48:49], v[54:55]
	v_pk_mul_f32 v[48:49], v[50:51], v[48:49]
	v_pk_mul_f32 v[50:51], v[48:49], v[46:47]
	v_pk_fma_f32 v[48:49], v[48:49], v[46:47], v[46:47] neg_lo:[1,0,0] neg_hi:[1,0,0]
	v_lshlrev_b32_e32 v47, 16, v56
	v_cndmask_b32_e32 v49, v49, v51, vcc
	v_cmp_gt_f32_e32 vcc, 0, v46
	v_lshlrev_b32_e32 v46, 16, v57
	v_mul_f32_e32 v51, v46, v46
	v_mul_f32_e32 v51, 0xbf38aa3b, v51
	v_cndmask_b32_e32 v48, v48, v50, vcc
	v_fma_f32 v50, |v46|, s92, 1.0
	v_exp_f32_e32 v54, v51
	v_fma_f32 v51, |v47|, s92, 1.0
	v_rcp_f32_e32 v50, v50
	v_rcp_f32_e32 v51, v51
	v_mul_f32_e32 v55, v47, v47
	v_mul_f32_e32 v55, 0xbf38aa3b, v55
	v_exp_f32_e32 v55, v55
	v_pk_fma_f32 v[56:57], v[50:51], s[12:13], v[24:25] op_sel_hi:[1,0,0]
	v_cmp_gt_f32_e32 vcc, 0, v47
	v_pk_fma_f32 v[56:57], v[50:51], v[56:57], s[14:15] op_sel_hi:[1,1,0]
	s_nop 0
	v_pk_fma_f32 v[56:57], v[50:51], v[56:57], s[16:17] op_sel_hi:[1,1,0]
	s_nop 0
	v_pk_fma_f32 v[56:57], v[50:51], v[56:57], s[18:19] op_sel_hi:[1,1,0]
	v_pk_mul_f32 v[50:51], v[50:51], v[56:57]
	v_pk_mul_f32 v[50:51], v[54:55], v[50:51]
	v_pk_mul_f32 v[54:55], v[50:51], v[46:47]
	v_pk_fma_f32 v[50:51], v[50:51], v[46:47], v[46:47] neg_lo:[1,0,0] neg_hi:[1,0,0]
	v_lshlrev_b32_e32 v47, 16, v58
	v_cndmask_b32_e32 v55, v51, v55, vcc
	v_cmp_gt_f32_e32 vcc, 0, v46
	v_lshlrev_b32_e32 v46, 16, v59
	v_fma_f32 v51, |v47|, s92, 1.0
	v_cndmask_b32_e32 v54, v50, v54, vcc
	v_fma_f32 v50, |v46|, s92, 1.0
	v_rcp_f32_e32 v50, v50
	v_rcp_f32_e32 v51, v51
	v_mul_f32_e32 v56, v46, v46
	v_mul_f32_e32 v57, v47, v47
	v_mul_f32_e32 v56, 0xbf38aa3b, v56
	v_pk_fma_f32 v[58:59], v[50:51], s[12:13], v[24:25] op_sel_hi:[1,0,0]
	v_mul_f32_e32 v57, 0xbf38aa3b, v57
	v_exp_f32_e32 v56, v56
	v_pk_fma_f32 v[58:59], v[50:51], v[58:59], s[14:15] op_sel_hi:[1,1,0]
	v_exp_f32_e32 v57, v57
	v_pk_fma_f32 v[58:59], v[50:51], v[58:59], s[16:17] op_sel_hi:[1,1,0]
	v_cmp_gt_f32_e32 vcc, 0, v47
	v_pk_fma_f32 v[58:59], v[50:51], v[58:59], s[18:19] op_sel_hi:[1,1,0]
	s_nop 0
	v_pk_mul_f32 v[50:51], v[50:51], v[58:59]
	v_pk_mul_f32 v[50:51], v[56:57], v[50:51]
	v_pk_mul_f32 v[56:57], v[50:51], v[46:47]
	v_pk_fma_f32 v[50:51], v[50:51], v[46:47], v[46:47] neg_lo:[1,0,0] neg_hi:[1,0,0]
	v_lshlrev_b32_e32 v47, 16, v77
	v_cndmask_b32_e32 v57, v51, v57, vcc
	v_cmp_gt_f32_e32 vcc, 0, v46
	v_lshlrev_b32_e32 v46, 16, v78
	v_mul_f32_e32 v51, v46, v46
	v_mul_f32_e32 v51, 0xbf38aa3b, v51
	v_cndmask_b32_e32 v56, v50, v56, vcc
	v_fma_f32 v50, |v46|, s92, 1.0
	v_exp_f32_e32 v58, v51
	v_fma_f32 v51, |v47|, s92, 1.0
	v_rcp_f32_e32 v50, v50
	v_rcp_f32_e32 v51, v51
	v_mul_f32_e32 v59, v47, v47
	v_mul_f32_e32 v59, 0xbf38aa3b, v59
	v_exp_f32_e32 v59, v59
	v_pk_fma_f32 v[78:79], v[50:51], s[12:13], v[24:25] op_sel_hi:[1,0,0]
	v_cmp_gt_f32_e32 vcc, 0, v47
	v_pk_fma_f32 v[78:79], v[50:51], v[78:79], s[14:15] op_sel_hi:[1,1,0]
	s_nop 0
	v_pk_fma_f32 v[78:79], v[50:51], v[78:79], s[16:17] op_sel_hi:[1,1,0]
	s_nop 0
	v_pk_fma_f32 v[78:79], v[50:51], v[78:79], s[18:19] op_sel_hi:[1,1,0]
	v_pk_mul_f32 v[50:51], v[50:51], v[78:79]
	v_pk_mul_f32 v[50:51], v[58:59], v[50:51]
	v_pk_mul_f32 v[58:59], v[50:51], v[46:47]
	v_pk_fma_f32 v[50:51], v[50:51], v[46:47], v[46:47] neg_lo:[1,0,0] neg_hi:[1,0,0]
	v_lshlrev_b32_e32 v47, 16, v80
	v_cndmask_b32_e32 v79, v51, v59, vcc
	v_cmp_gt_f32_e32 vcc, 0, v46
	v_lshlrev_b32_e32 v46, 16, v81
	v_fma_f32 v51, |v47|, s92, 1.0
	v_cndmask_b32_e32 v78, v50, v58, vcc
	v_fma_f32 v50, |v46|, s92, 1.0
	v_rcp_f32_e32 v50, v50
	v_rcp_f32_e32 v51, v51
	v_mul_f32_e32 v58, v46, v46
	v_mul_f32_e32 v59, v47, v47
	v_mul_f32_e32 v58, 0xbf38aa3b, v58
	v_pk_fma_f32 v[80:81], v[50:51], s[12:13], v[24:25] op_sel_hi:[1,0,0]
	v_mul_f32_e32 v59, 0xbf38aa3b, v59
	v_exp_f32_e32 v58, v58
	v_pk_fma_f32 v[80:81], v[50:51], v[80:81], s[14:15] op_sel_hi:[1,1,0]
	v_exp_f32_e32 v59, v59
	v_pk_fma_f32 v[80:81], v[50:51], v[80:81], s[16:17] op_sel_hi:[1,1,0]
	v_cmp_gt_f32_e32 vcc, 0, v47
	v_pk_fma_f32 v[80:81], v[50:51], v[80:81], s[18:19] op_sel_hi:[1,1,0]
	s_nop 0
	v_pk_mul_f32 v[50:51], v[50:51], v[80:81]
	v_pk_mul_f32 v[50:51], v[58:59], v[50:51]
	v_pk_mul_f32 v[58:59], v[50:51], v[46:47]
	v_pk_fma_f32 v[50:51], v[50:51], v[46:47], v[46:47] neg_lo:[1,0,0] neg_hi:[1,0,0]
	v_lshlrev_b32_e32 v47, 16, v82
	v_cndmask_b32_e32 v59, v51, v59, vcc
	v_cmp_gt_f32_e32 vcc, 0, v46
	v_lshlrev_b32_e32 v46, 16, v83
	v_mul_f32_e32 v51, v46, v46
	v_mul_f32_e32 v51, 0xbf38aa3b, v51
	v_cndmask_b32_e32 v58, v50, v58, vcc
	v_fma_f32 v50, |v46|, s92, 1.0
	v_exp_f32_e32 v80, v51
	v_fma_f32 v51, |v47|, s92, 1.0
	v_rcp_f32_e32 v50, v50
	v_rcp_f32_e32 v51, v51
	v_mul_f32_e32 v77, v47, v47
	v_mul_f32_e32 v77, 0xbf38aa3b, v77
	v_exp_f32_e32 v81, v77
	v_pk_fma_f32 v[82:83], v[50:51], s[12:13], v[24:25] op_sel_hi:[1,0,0]
	v_cmp_gt_f32_e32 vcc, 0, v47
	v_pk_fma_f32 v[82:83], v[50:51], v[82:83], s[14:15] op_sel_hi:[1,1,0]
	s_nop 0
	v_pk_fma_f32 v[82:83], v[50:51], v[82:83], s[16:17] op_sel_hi:[1,1,0]
	s_nop 0
	v_pk_fma_f32 v[82:83], v[50:51], v[82:83], s[18:19] op_sel_hi:[1,1,0]
	v_pk_mul_f32 v[50:51], v[50:51], v[82:83]
	v_mov_b32_e32 v82, v49
	v_pk_mul_f32 v[50:51], v[80:81], v[50:51]
	v_mov_b32_e32 v83, v59
	v_pk_mul_f32 v[80:81], v[50:51], v[46:47]
	v_pk_fma_f32 v[50:51], v[50:51], v[46:47], v[46:47] neg_lo:[1,0,0] neg_hi:[1,0,0]
	v_mov_b32_e32 v47, v56
	v_cndmask_b32_e32 v81, v51, v81, vcc
	v_cmp_gt_f32_e32 vcc, 0, v46
	v_mov_b32_e32 v46, v44
	v_mov_b32_e32 v51, v58
	v_cndmask_b32_e32 v80, v50, v80, vcc
	v_mov_b32_e32 v50, v48
	v_pk_add_f32 v[46:47], v[46:47], v[50:51]
	v_mov_b32_e32 v50, v45
	v_add_f32_e32 v46, v46, v47
	v_mov_b32_e32 v51, v57
	s_nop 0
	v_add_f32_dpp v46, v46, v46 quad_perm:[1,0,3,2] row_mask:0xf bank_mask:0xf bound_ctrl:1
	v_pk_add_f32 v[50:51], v[50:51], v[82:83]
	v_mov_b32_e32 v82, v55
	v_add_f32_dpp v46, v46, v46 quad_perm:[2,3,0,1] row_mask:0xf bank_mask:0xf bound_ctrl:1
	v_mov_b32_e32 v83, v81
	s_nop 0
	v_add_f32_dpp v46, v46, v46 row_half_mirror row_mask:0xf bank_mask:0xf bound_ctrl:1
	s_nop 1
	v_add_f32_dpp v46, v46, v46 row_mirror row_mask:0xf bank_mask:0xf bound_ctrl:1
	s_nop 1
	v_add_f32_dpp v46, v46, v46 row_bcast:15 row_mask:0xa bank_mask:0xf
	s_nop 1
	v_add_f32_dpp v46, v46, v46 row_bcast:31 row_mask:0xc bank_mask:0xf
	v_add_f32_e32 v47, v50, v51
	v_readlane_b32 s6, v46, 63
	s_nop 0
	v_add_f32_dpp v47, v47, v47 quad_perm:[1,0,3,2] row_mask:0xf bank_mask:0xf bound_ctrl:1
	s_xor_b32 s6, s6, 0x80000000
	s_nop 0
	v_add_f32_dpp v47, v47, v47 quad_perm:[2,3,0,1] row_mask:0xf bank_mask:0xf bound_ctrl:1
	s_nop 1
	v_add_f32_dpp v47, v47, v47 row_half_mirror row_mask:0xf bank_mask:0xf bound_ctrl:1
	s_nop 1
	v_add_f32_dpp v47, v47, v47 row_mirror row_mask:0xf bank_mask:0xf bound_ctrl:1
	s_nop 1
	v_add_f32_dpp v47, v47, v47 row_bcast:15 row_mask:0xa bank_mask:0xf
	s_nop 1
	v_add_f32_dpp v47, v47, v47 row_bcast:31 row_mask:0xc bank_mask:0xf
	s_nop 0
	v_readlane_b32 s7, v47, 63
	s_xor_b32 s7, s7, 0x80000000
	s_nop 0
	v_pk_fma_f32 v[46:47], s[6:7], v[26:27], v[44:45] op_sel_hi:[1,0,1]
	v_pk_fma_f32 v[50:51], s[6:7], v[26:27], v[48:49] op_sel_hi:[1,0,1]
	v_pk_fma_f32 v[48:49], s[6:7], v[26:27], v[56:57] op_sel_hi:[1,0,1]
	v_pk_fma_f32 v[44:45], s[6:7], v[26:27], v[58:59] op_sel_hi:[1,0,1]
	v_mov_b32_e32 v56, v52
	v_mov_b32_e32 v57, v78
	v_mov_b32_e32 v58, v54
	v_mov_b32_e32 v59, v80
	v_pk_add_f32 v[56:57], v[56:57], v[58:59]
	v_mov_b32_e32 v58, v53
	v_add_f32_e32 v56, v56, v57
	v_mov_b32_e32 v59, v79
	s_nop 0
	v_add_f32_dpp v56, v56, v56 quad_perm:[1,0,3,2] row_mask:0xf bank_mask:0xf bound_ctrl:1
	v_pk_add_f32 v[58:59], v[58:59], v[82:83]
	s_nop 0
	v_add_f32_dpp v56, v56, v56 quad_perm:[2,3,0,1] row_mask:0xf bank_mask:0xf bound_ctrl:1
	s_nop 1
	v_add_f32_dpp v56, v56, v56 row_half_mirror row_mask:0xf bank_mask:0xf bound_ctrl:1
	s_nop 1
	v_add_f32_dpp v56, v56, v56 row_mirror row_mask:0xf bank_mask:0xf bound_ctrl:1
	s_nop 1
	v_add_f32_dpp v56, v56, v56 row_bcast:15 row_mask:0xa bank_mask:0xf
	s_nop 1
	v_add_f32_dpp v56, v56, v56 row_bcast:31 row_mask:0xc bank_mask:0xf
	v_add_f32_e32 v57, v58, v59
	v_readlane_b32 s6, v56, 63
	s_nop 0
	v_add_f32_dpp v57, v57, v57 quad_perm:[1,0,3,2] row_mask:0xf bank_mask:0xf bound_ctrl:1
	s_xor_b32 s6, s6, 0x80000000
	s_nop 0
	v_add_f32_dpp v57, v57, v57 quad_perm:[2,3,0,1] row_mask:0xf bank_mask:0xf bound_ctrl:1
	s_nop 1
	v_add_f32_dpp v57, v57, v57 row_half_mirror row_mask:0xf bank_mask:0xf bound_ctrl:1
	s_nop 1
	v_add_f32_dpp v57, v57, v57 row_mirror row_mask:0xf bank_mask:0xf bound_ctrl:1
	s_nop 1
	v_add_f32_dpp v57, v57, v57 row_bcast:15 row_mask:0xa bank_mask:0xf
	s_nop 1
	v_add_f32_dpp v57, v57, v57 row_bcast:31 row_mask:0xc bank_mask:0xf
	s_nop 0
	v_readlane_b32 s7, v57, 63
	s_xor_b32 s7, s7, 0x80000000
	s_nop 0
	v_pk_fma_f32 v[56:57], s[6:7], v[26:27], v[54:55] op_sel_hi:[1,0,1]
	v_pk_fma_f32 v[54:55], s[6:7], v[26:27], v[78:79] op_sel_hi:[1,0,1]
	v_lshlrev_b32_e32 v79, 16, v60
	v_lshlrev_b32_e32 v78, 16, v61
	v_fma_f32 v60, |v78|, s92, 1.0
	v_fma_f32 v61, |v79|, s92, 1.0
	v_rcp_f32_e32 v60, v60
	v_rcp_f32_e32 v61, v61
	v_mul_f32_e32 v77, v78, v78
	v_mul_f32_e32 v77, 0xbf38aa3b, v77
	v_pk_fma_f32 v[58:59], s[6:7], v[26:27], v[52:53] op_sel_hi:[1,0,1]
	v_pk_fma_f32 v[52:53], s[6:7], v[26:27], v[80:81] op_sel_hi:[1,0,1]
	v_exp_f32_e32 v80, v77
	v_mul_f32_e32 v77, v79, v79
	v_pk_fma_f32 v[82:83], v[60:61], s[12:13], v[24:25] op_sel_hi:[1,0,0]
	v_mul_f32_e32 v77, 0xbf38aa3b, v77
	v_pk_fma_f32 v[82:83], v[60:61], v[82:83], s[14:15] op_sel_hi:[1,1,0]
	v_exp_f32_e32 v81, v77
	v_pk_fma_f32 v[82:83], v[60:61], v[82:83], s[16:17] op_sel_hi:[1,1,0]
	v_cmp_gt_f32_e32 vcc, 0, v79
	v_pk_fma_f32 v[82:83], v[60:61], v[82:83], s[18:19] op_sel_hi:[1,1,0]
	s_mov_b32 s6, 0xbe11a98e
	v_pk_mul_f32 v[60:61], v[60:61], v[82:83]
	v_pk_mul_f32 v[60:61], v[80:81], v[60:61]
	v_pk_mul_f32 v[80:81], v[60:61], v[78:79]
	v_pk_fma_f32 v[60:61], v[60:61], v[78:79], v[78:79] neg_lo:[1,0,0] neg_hi:[1,0,0]
	v_lshlrev_b32_e32 v79, 16, v66
	v_cndmask_b32_e32 v61, v61, v81, vcc
	v_cmp_gt_f32_e32 vcc, 0, v78
	v_lshlrev_b32_e32 v78, 16, v67
	v_mul_f32_e32 v67, v78, v78
	v_mul_f32_e32 v67, 0xbf38aa3b, v67
	v_cndmask_b32_e32 v60, v60, v80, vcc
	v_fma_f32 v66, |v78|, s92, 1.0
	v_exp_f32_e32 v80, v67
	v_fma_f32 v67, |v79|, s92, 1.0
	v_rcp_f32_e32 v66, v66
	v_rcp_f32_e32 v67, v67
	v_mul_f32_e32 v77, v79, v79
	v_mul_f32_e32 v77, 0xbf38aa3b, v77
	v_exp_f32_e32 v81, v77
	v_pk_fma_f32 v[82:83], v[66:67], s[12:13], v[24:25] op_sel_hi:[1,0,0]
	v_cmp_gt_f32_e32 vcc, 0, v79
	v_pk_fma_f32 v[82:83], v[66:67], v[82:83], s[14:15] op_sel_hi:[1,1,0]
	s_nop 0
	v_pk_fma_f32 v[82:83], v[66:67], v[82:83], s[16:17] op_sel_hi:[1,1,0]
	s_nop 0
	v_pk_fma_f32 v[82:83], v[66:67], v[82:83], s[18:19] op_sel_hi:[1,1,0]
	v_pk_mul_f32 v[66:67], v[66:67], v[82:83]
	v_pk_mul_f32 v[66:67], v[80:81], v[66:67]
	v_pk_mul_f32 v[80:81], v[66:67], v[78:79]
	v_pk_fma_f32 v[66:67], v[66:67], v[78:79], v[78:79] neg_lo:[1,0,0] neg_hi:[1,0,0]
	v_lshlrev_b32_e32 v79, 16, v62
	v_cndmask_b32_e32 v67, v67, v81, vcc
	v_cmp_gt_f32_e32 vcc, 0, v78
	v_lshlrev_b32_e32 v78, 16, v63
	v_fma_f32 v62, |v78|, s92, 1.0
	v_fma_f32 v63, |v79|, s92, 1.0
	v_rcp_f32_e32 v62, v62
	v_rcp_f32_e32 v63, v63
	v_mul_f32_e32 v77, v78, v78
	v_mul_f32_e32 v77, 0xbf38aa3b, v77
	v_cndmask_b32_e32 v66, v66, v80, vcc
	v_exp_f32_e32 v80, v77
	v_mul_f32_e32 v77, v79, v79
	v_pk_fma_f32 v[82:83], v[62:63], s[12:13], v[24:25] op_sel_hi:[1,0,0]
	v_mul_f32_e32 v77, 0xbf38aa3b, v77
	v_pk_fma_f32 v[82:83], v[62:63], v[82:83], s[14:15] op_sel_hi:[1,1,0]
	v_exp_f32_e32 v81, v77
	v_pk_fma_f32 v[82:83], v[62:63], v[82:83], s[16:17] op_sel_hi:[1,1,0]
	v_cmp_gt_f32_e32 vcc, 0, v79
	v_pk_fma_f32 v[82:83], v[62:63], v[82:83], s[18:19] op_sel_hi:[1,1,0]
	s_nop 0
	v_pk_mul_f32 v[62:63], v[62:63], v[82:83]
	v_pk_mul_f32 v[62:63], v[80:81], v[62:63]
	v_pk_mul_f32 v[80:81], v[62:63], v[78:79]
	v_pk_fma_f32 v[62:63], v[62:63], v[78:79], v[78:79] neg_lo:[1,0,0] neg_hi:[1,0,0]
	v_lshlrev_b32_e32 v79, 16, v68
	v_cndmask_b32_e32 v63, v63, v81, vcc
	v_cmp_gt_f32_e32 vcc, 0, v78
	v_lshlrev_b32_e32 v78, 16, v69
	v_mul_f32_e32 v69, v78, v78
	v_mul_f32_e32 v69, 0xbf38aa3b, v69
	v_cndmask_b32_e32 v62, v62, v80, vcc
	v_fma_f32 v68, |v78|, s92, 1.0
	v_exp_f32_e32 v80, v69
	v_fma_f32 v69, |v79|, s92, 1.0
	v_rcp_f32_e32 v68, v68
	v_rcp_f32_e32 v69, v69
	v_mul_f32_e32 v77, v79, v79
	v_mul_f32_e32 v77, 0xbf38aa3b, v77
	v_exp_f32_e32 v81, v77
	v_pk_fma_f32 v[82:83], v[68:69], s[12:13], v[24:25] op_sel_hi:[1,0,0]
	v_cmp_gt_f32_e32 vcc, 0, v79
	v_pk_fma_f32 v[82:83], v[68:69], v[82:83], s[14:15] op_sel_hi:[1,1,0]
	v_lshlrev_b32_e32 v77, 16, v75
	v_pk_fma_f32 v[82:83], v[68:69], v[82:83], s[16:17] op_sel_hi:[1,1,0]
	v_fma_f32 v75, |v76|, s92, 1.0
	v_pk_fma_f32 v[82:83], v[68:69], v[82:83], s[18:19] op_sel_hi:[1,1,0]
	v_pk_mul_f32 v[68:69], v[68:69], v[82:83]
	v_pk_mul_f32 v[68:69], v[80:81], v[68:69]
	v_pk_mul_f32 v[80:81], v[68:69], v[78:79]
	v_pk_fma_f32 v[68:69], v[68:69], v[78:79], v[78:79] neg_lo:[1,0,0] neg_hi:[1,0,0]
	s_nop 0
	v_cndmask_b32_e32 v69, v69, v81, vcc
	v_cmp_gt_f32_e32 vcc, 0, v78
	v_rcp_f32_e32 v78, v75
	v_fma_f32 v75, |v77|, s92, 1.0
	v_rcp_f32_e32 v79, v75
	v_mul_f32_e32 v75, v76, v76
	v_mul_f32_e32 v75, 0xbf38aa3b, v75
	v_cndmask_b32_e32 v68, v68, v80, vcc
	v_exp_f32_e32 v80, v75
	v_mul_f32_e32 v75, v77, v77
	v_pk_fma_f32 v[82:83], v[78:79], s[12:13], v[24:25] op_sel_hi:[1,0,0]
	v_mul_f32_e32 v75, 0xbf38aa3b, v75
	v_pk_fma_f32 v[82:83], v[78:79], v[82:83], s[14:15] op_sel_hi:[1,1,0]
	v_exp_f32_e32 v81, v75
	v_pk_fma_f32 v[82:83], v[78:79], v[82:83], s[16:17] op_sel_hi:[1,1,0]
	v_cmp_gt_f32_e32 vcc, 0, v77
	v_pk_fma_f32 v[82:83], v[78:79], v[82:83], s[18:19] op_sel_hi:[1,1,0]
	s_nop 0
	v_pk_mul_f32 v[78:79], v[78:79], v[82:83]
	v_pk_mul_f32 v[78:79], v[80:81], v[78:79]
	v_pk_mul_f32 v[80:81], v[78:79], v[76:77]
	v_pk_fma_f32 v[78:79], v[78:79], v[76:77], v[76:77] neg_lo:[1,0,0] neg_hi:[1,0,0]
	s_nop 0
	v_cndmask_b32_e32 v77, v79, v81, vcc
	v_cmp_gt_f32_e32 vcc, 0, v76
	v_lshlrev_b32_e32 v79, 16, v72
	v_mul_f32_e32 v75, v79, v79
	v_cndmask_b32_e32 v76, v78, v80, vcc
	v_lshlrev_b32_e32 v78, 16, v73
	v_mul_f32_e32 v73, v78, v78
	v_mul_f32_e32 v73, 0xbf38aa3b, v73
	v_fma_f32 v72, |v78|, s92, 1.0
	v_exp_f32_e32 v80, v73
	v_fma_f32 v73, |v79|, s92, 1.0
	v_rcp_f32_e32 v72, v72
	v_rcp_f32_e32 v73, v73
	v_mul_f32_e32 v75, 0xbf38aa3b, v75
	v_exp_f32_e32 v81, v75
	v_cmp_gt_f32_e32 vcc, 0, v79
	v_pk_fma_f32 v[82:83], v[72:73], s[12:13], v[24:25] op_sel_hi:[1,0,0]
	s_nop 0
	v_pk_fma_f32 v[82:83], v[72:73], v[82:83], s[14:15] op_sel_hi:[1,1,0]
	s_nop 0
	v_pk_fma_f32 v[82:83], v[72:73], v[82:83], s[16:17] op_sel_hi:[1,1,0]
	s_nop 0
	v_pk_fma_f32 v[82:83], v[72:73], v[82:83], s[18:19] op_sel_hi:[1,1,0]
	v_pk_mul_f32 v[72:73], v[72:73], v[82:83]
	v_pk_mul_f32 v[72:73], v[80:81], v[72:73]
	v_pk_mul_f32 v[80:81], v[72:73], v[78:79]
	v_pk_fma_f32 v[72:73], v[72:73], v[78:79], v[78:79] neg_lo:[1,0,0] neg_hi:[1,0,0]
	v_lshlrev_b32_e32 v79, 16, v70
	v_cndmask_b32_e32 v73, v73, v81, vcc
	v_cmp_gt_f32_e32 vcc, 0, v78
	s_waitcnt vmcnt(0)
	v_lshlrev_b32_e32 v78, 16, v71
	v_fma_f32 v70, |v78|, s92, 1.0
	v_fma_f32 v71, |v79|, s92, 1.0
	v_rcp_f32_e32 v70, v70
	v_rcp_f32_e32 v71, v71
	v_mul_f32_e32 v75, v78, v78
	v_mul_f32_e32 v75, 0xbf38aa3b, v75
	v_cndmask_b32_e32 v72, v72, v80, vcc
	v_exp_f32_e32 v80, v75
	v_mul_f32_e32 v75, v79, v79
	v_pk_fma_f32 v[82:83], v[70:71], s[12:13], v[24:25] op_sel_hi:[1,0,0]
	v_mul_f32_e32 v75, 0xbf38aa3b, v75
	v_pk_fma_f32 v[82:83], v[70:71], v[82:83], s[14:15] op_sel_hi:[1,1,0]
	v_exp_f32_e32 v81, v75
	v_pk_fma_f32 v[82:83], v[70:71], v[82:83], s[16:17] op_sel_hi:[1,1,0]
	v_cmp_gt_f32_e32 vcc, 0, v79
	v_pk_fma_f32 v[82:83], v[70:71], v[82:83], s[18:19] op_sel_hi:[1,1,0]
	s_nop 0
	v_pk_mul_f32 v[70:71], v[70:71], v[82:83]
	v_pk_mul_f32 v[70:71], v[80:81], v[70:71]
	v_pk_mul_f32 v[80:81], v[70:71], v[78:79]
	v_pk_fma_f32 v[70:71], v[70:71], v[78:79], v[78:79] neg_lo:[1,0,0] neg_hi:[1,0,0]
	v_lshlrev_b32_e32 v79, 16, v64
	v_cndmask_b32_e32 v71, v71, v81, vcc
	v_cmp_gt_f32_e32 vcc, 0, v78
	v_lshlrev_b32_e32 v78, 16, v65
	v_mul_f32_e32 v65, v78, v78
	v_mul_f32_e32 v65, 0xbf38aa3b, v65
	v_cndmask_b32_e32 v70, v70, v80, vcc
	v_fma_f32 v64, |v78|, s92, 1.0
	v_exp_f32_e32 v80, v65
	v_fma_f32 v65, |v79|, s92, 1.0
	v_rcp_f32_e32 v64, v64
	v_rcp_f32_e32 v65, v65
	v_mul_f32_e32 v75, v79, v79
	v_mul_f32_e32 v75, 0xbf38aa3b, v75
	v_exp_f32_e32 v81, v75
	v_pk_fma_f32 v[24:25], v[64:65], s[12:13], v[24:25] op_sel_hi:[1,0,0]
	v_cmp_gt_f32_e32 vcc, 0, v79
	v_pk_fma_f32 v[24:25], v[64:65], v[24:25], s[14:15] op_sel_hi:[1,1,0]
	v_mov_b32_e32 v75, v131
	v_pk_fma_f32 v[24:25], v[64:65], v[24:25], s[6:7] op_sel_hi:[1,1,0]
	s_mov_b64 s[12:13], s[68:69]
	v_pk_fma_f32 v[24:25], v[64:65], v[24:25], s[8:9] op_sel_hi:[1,1,0]
	s_mov_b64 s[68:69], s[10:11]
	v_pk_mul_f32 v[24:25], v[64:65], v[24:25]
	v_pk_mul_f32 v[24:25], v[80:81], v[24:25]
	v_mov_b32_e32 v80, v63
	v_pk_mul_f32 v[64:65], v[24:25], v[78:79]
	v_pk_fma_f32 v[24:25], v[24:25], v[78:79], v[78:79] neg_lo:[1,0,0] neg_hi:[1,0,0]
	v_mov_b32_e32 v81, v71
	v_cndmask_b32_e32 v79, v25, v65, vcc
	v_cmp_gt_f32_e32 vcc, 0, v78
	v_mov_b32_e32 v25, v76
	v_mov_b32_e32 v65, v70
	v_cndmask_b32_e32 v78, v24, v64, vcc
	v_mov_b32_e32 v24, v60
	v_mov_b32_e32 v64, v62
	v_pk_add_f32 v[24:25], v[24:25], v[64:65]
	v_mov_b32_e32 v64, v61
	v_add_f32_e32 v24, v24, v25
	v_mov_b32_e32 v65, v77
	s_nop 0
	v_add_f32_dpp v24, v24, v24 quad_perm:[1,0,3,2] row_mask:0xf bank_mask:0xf bound_ctrl:1
	v_pk_add_f32 v[64:65], v[64:65], v[80:81]
	v_mov_b32_e32 v80, v69
	v_add_f32_dpp v24, v24, v24 quad_perm:[2,3,0,1] row_mask:0xf bank_mask:0xf bound_ctrl:1
	v_mov_b32_e32 v81, v79
	s_nop 0
	v_add_f32_dpp v24, v24, v24 row_half_mirror row_mask:0xf bank_mask:0xf bound_ctrl:1
	s_nop 1
	v_add_f32_dpp v24, v24, v24 row_mirror row_mask:0xf bank_mask:0xf bound_ctrl:1
	s_nop 1
	v_add_f32_dpp v24, v24, v24 row_bcast:15 row_mask:0xa bank_mask:0xf
	s_nop 1
	v_add_f32_dpp v24, v24, v24 row_bcast:31 row_mask:0xc bank_mask:0xf
	v_add_f32_e32 v25, v64, v65
	v_readlane_b32 s6, v24, 63
	s_nop 0
	v_add_f32_dpp v25, v25, v25 quad_perm:[1,0,3,2] row_mask:0xf bank_mask:0xf bound_ctrl:1
	s_xor_b32 s6, s6, 0x80000000
	s_nop 0
	v_add_f32_dpp v25, v25, v25 quad_perm:[2,3,0,1] row_mask:0xf bank_mask:0xf bound_ctrl:1
	s_nop 1
	v_add_f32_dpp v25, v25, v25 row_half_mirror row_mask:0xf bank_mask:0xf bound_ctrl:1
	s_nop 1
	v_add_f32_dpp v25, v25, v25 row_mirror row_mask:0xf bank_mask:0xf bound_ctrl:1
	s_nop 1
	v_add_f32_dpp v25, v25, v25 row_bcast:15 row_mask:0xa bank_mask:0xf
	s_nop 1
	v_add_f32_dpp v25, v25, v25 row_bcast:31 row_mask:0xc bank_mask:0xf
	s_nop 0
	v_readlane_b32 s7, v25, 63
	s_xor_b32 s7, s7, 0x80000000
	s_nop 0
	v_pk_fma_f32 v[64:65], s[6:7], v[26:27], v[60:61] op_sel_hi:[1,0,1]
	v_pk_fma_f32 v[60:61], s[6:7], v[26:27], v[76:77] op_sel_hi:[1,0,1]
	v_pk_fma_f32 v[24:25], s[6:7], v[26:27], v[70:71] op_sel_hi:[1,0,1]
	v_mov_b32_e32 v70, v66
	v_mov_b32_e32 v71, v72
	v_mov_b32_e32 v76, v68
	v_mov_b32_e32 v77, v78
	v_pk_add_f32 v[70:71], v[70:71], v[76:77]
	v_mov_b32_e32 v76, v67
	v_add_f32_e32 v70, v70, v71
	v_mov_b32_e32 v77, v73
	s_nop 0
	v_add_f32_dpp v70, v70, v70 quad_perm:[1,0,3,2] row_mask:0xf bank_mask:0xf bound_ctrl:1
	v_pk_add_f32 v[76:77], v[76:77], v[80:81]
	v_pk_fma_f32 v[62:63], s[6:7], v[26:27], v[62:63] op_sel_hi:[1,0,1]
	v_add_f32_dpp v70, v70, v70 quad_perm:[2,3,0,1] row_mask:0xf bank_mask:0xf bound_ctrl:1
	s_nop 1
	v_add_f32_dpp v70, v70, v70 row_half_mirror row_mask:0xf bank_mask:0xf bound_ctrl:1
	s_nop 1
	v_add_f32_dpp v70, v70, v70 row_mirror row_mask:0xf bank_mask:0xf bound_ctrl:1
	s_nop 1
	v_add_f32_dpp v70, v70, v70 row_bcast:15 row_mask:0xa bank_mask:0xf
	s_nop 1
	v_add_f32_dpp v70, v70, v70 row_bcast:31 row_mask:0xc bank_mask:0xf
	v_add_f32_e32 v71, v76, v77
	v_readlane_b32 s6, v70, 63
	s_xor_b32 s6, s6, 0x80000000
	v_add_f32_dpp v71, v71, v71 quad_perm:[1,0,3,2] row_mask:0xf bank_mask:0xf bound_ctrl:1
	v_mov_b32_e32 v76, v20
	v_mov_b32_e32 v77, v16
	v_add_f32_dpp v71, v71, v71 quad_perm:[2,3,0,1] row_mask:0xf bank_mask:0xf bound_ctrl:1
	v_pk_mul_f32 v[76:77], v[76:77], v[76:77]
	s_nop 0
	v_add_f32_dpp v71, v71, v71 row_half_mirror row_mask:0xf bank_mask:0xf bound_ctrl:1
	s_nop 1
	v_add_f32_dpp v71, v71, v71 row_mirror row_mask:0xf bank_mask:0xf bound_ctrl:1
	s_nop 1
	v_mov_b32_dpp v75, v71 row_bcast:15 row_mask:0xa bank_mask:0xf
	v_add_f32_e32 v71, v71, v75
	v_mov_b32_e32 v75, v131
	s_nop 1
	v_mov_b32_dpp v75, v71 row_bcast:31 row_mask:0xc bank_mask:0xf
	v_add_f32_e32 v71, v71, v75
	s_nop 0
	v_readlane_b32 s7, v71, 63
	s_xor_b32 s7, s7, 0x80000000
	s_nop 0
	v_pk_fma_f32 v[70:71], s[6:7], v[26:27], v[66:67] op_sel_hi:[1,0,1]
	v_pk_fma_f32 v[66:67], s[6:7], v[26:27], v[72:73] op_sel_hi:[1,0,1]
	v_mov_b32_e32 v72, v22
	v_mov_b32_e32 v73, v18
	v_pk_fma_f32 v[72:73], v[72:73], v[72:73], v[76:77]
	v_pk_fma_f32 v[68:69], s[6:7], v[26:27], v[68:69] op_sel_hi:[1,0,1]
	v_add_f32_e32 v72, v72, v73
	v_pk_fma_f32 v[26:27], s[6:7], v[26:27], v[78:79] op_sel_hi:[1,0,1]
	s_nop 0
	v_add_f32_dpp v72, v72, v72 quad_perm:[1,0,3,2] row_mask:0xf bank_mask:0xf bound_ctrl:1
	s_lshl_b32 s6, s65, 5
	s_add_i32 s7, s5, s73
	v_add_f32_dpp v72, v72, v72 quad_perm:[2,3,0,1] row_mask:0xf bank_mask:0xf bound_ctrl:1
	s_mul_hi_i32 s8, s7, 0x5000
	s_mulk_i32 s7, 0x5000
	v_add_f32_dpp v72, v72, v72 row_half_mirror row_mask:0xf bank_mask:0xf bound_ctrl:1
	s_lshl_b32 s5, s5, 9
	s_add_i32 s9, s6, 0
	v_add_f32_dpp v72, v72, v72 row_mirror row_mask:0xf bank_mask:0xf bound_ctrl:1
	v_mov_b32_e32 v76, v21
	v_mov_b32_e32 v77, v17
	v_add_f32_dpp v72, v72, v72 row_bcast:15 row_mask:0xa bank_mask:0xf
	s_add_u32 s28, s34, s7
	v_pk_mul_f32 v[76:77], v[76:77], v[76:77]
	v_add_f32_dpp v72, v72, v72 row_bcast:31 row_mask:0xc bank_mask:0xf
	v_mov_b32_e32 v73, v19
	v_readlane_b32 s7, v72, 63
	v_mov_b32_e32 v72, v23
	v_pk_fma_f32 v[72:73], v[72:73], v[72:73], v[76:77]
	v_mov_b32_e32 v76, v14
	v_add_f32_e32 v72, v72, v73
	v_mov_b32_e32 v77, v8
	s_nop 0
	v_add_f32_dpp v72, v72, v72 quad_perm:[1,0,3,2] row_mask:0xf bank_mask:0xf bound_ctrl:1
	v_fma_f32 v79, s7, v235, v225
	v_pk_mul_f32 v[76:77], v[76:77], v[76:77]
	v_add_f32_dpp v72, v72, v72 quad_perm:[2,3,0,1] row_mask:0xf bank_mask:0xf bound_ctrl:1
	s_addc_u32 s29, s64, s8
	v_readlane_b32 s8, v253, 54
	v_add_f32_dpp v72, v72, v72 row_half_mirror row_mask:0xf bank_mask:0xf bound_ctrl:1
	v_mov_b32_e32 v75, s9
	s_add_i32 s5, s8, s5
	v_add_f32_dpp v72, v72, v72 row_mirror row_mask:0xf bank_mask:0xf bound_ctrl:1
	s_nop 1
	v_add_f32_dpp v72, v72, v72 row_bcast:15 row_mask:0xa bank_mask:0xf
	s_nop 1
	v_add_f32_dpp v72, v72, v72 row_bcast:31 row_mask:0xc bank_mask:0xf
	v_mov_b32_e32 v73, v12
	v_readlane_b32 s7, v72, 63
	v_mov_b32_e32 v72, v10
	v_pk_fma_f32 v[72:73], v[72:73], v[72:73], v[76:77]
	v_mov_b32_e32 v76, v15
	v_add_f32_e32 v72, v72, v73
	v_mov_b32_e32 v77, v9
	s_nop 0
	v_add_f32_dpp v72, v72, v72 quad_perm:[1,0,3,2] row_mask:0xf bank_mask:0xf bound_ctrl:1
	v_fma_f32 v81, s7, v235, v225
	v_pk_mul_f32 v[76:77], v[76:77], v[76:77]
	v_add_f32_dpp v72, v72, v72 quad_perm:[2,3,0,1] row_mask:0xf bank_mask:0xf bound_ctrl:1
	s_nop 1
	v_add_f32_dpp v72, v72, v72 row_half_mirror row_mask:0xf bank_mask:0xf bound_ctrl:1
	s_nop 1
	v_add_f32_dpp v72, v72, v72 row_mirror row_mask:0xf bank_mask:0xf bound_ctrl:1
	s_nop 1
	v_add_f32_dpp v72, v72, v72 row_bcast:15 row_mask:0xa bank_mask:0xf
	s_nop 1
	v_add_f32_dpp v72, v72, v72 row_bcast:31 row_mask:0xc bank_mask:0xf
	v_mov_b32_e32 v73, v13
	v_readlane_b32 s7, v72, 63
	v_mov_b32_e32 v72, v11
	v_pk_fma_f32 v[72:73], v[72:73], v[72:73], v[76:77]
	v_mov_b32_e32 v76, v40
	v_add_f32_e32 v72, v72, v73
	v_mov_b32_e32 v77, v36
	s_nop 0
	v_add_f32_dpp v72, v72, v72 quad_perm:[1,0,3,2] row_mask:0xf bank_mask:0xf bound_ctrl:1
	v_fma_f32 v83, s7, v235, v225
	v_pk_mul_f32 v[76:77], v[76:77], v[76:77]
	v_add_f32_dpp v72, v72, v72 quad_perm:[2,3,0,1] row_mask:0xf bank_mask:0xf bound_ctrl:1
	s_nop 1
	v_add_f32_dpp v72, v72, v72 row_half_mirror row_mask:0xf bank_mask:0xf bound_ctrl:1
	s_nop 1
	v_add_f32_dpp v72, v72, v72 row_mirror row_mask:0xf bank_mask:0xf bound_ctrl:1
	s_nop 1
	v_add_f32_dpp v72, v72, v72 row_bcast:15 row_mask:0xa bank_mask:0xf
	s_nop 1
	v_add_f32_dpp v72, v72, v72 row_bcast:31 row_mask:0xc bank_mask:0xf
	v_mov_b32_e32 v73, v38
	v_readlane_b32 s7, v72, 63
	v_mov_b32_e32 v72, v42
	v_pk_fma_f32 v[72:73], v[72:73], v[72:73], v[76:77]
	v_mov_b32_e32 v76, v41
	v_add_f32_e32 v72, v72, v73
	v_mov_b32_e32 v77, v37
	s_nop 0
	v_add_f32_dpp v72, v72, v72 quad_perm:[1,0,3,2] row_mask:0xf bank_mask:0xf bound_ctrl:1
	v_fma_f32 v85, s7, v235, v225
	v_pk_mul_f32 v[76:77], v[76:77], v[76:77]
	v_add_f32_dpp v72, v72, v72 quad_perm:[2,3,0,1] row_mask:0xf bank_mask:0xf bound_ctrl:1
	s_nop 1
	v_add_f32_dpp v72, v72, v72 row_half_mirror row_mask:0xf bank_mask:0xf bound_ctrl:1
	s_nop 1
	v_add_f32_dpp v72, v72, v72 row_mirror row_mask:0xf bank_mask:0xf bound_ctrl:1
	s_nop 1
	v_add_f32_dpp v72, v72, v72 row_bcast:15 row_mask:0xa bank_mask:0xf
	s_nop 1
	v_add_f32_dpp v72, v72, v72 row_bcast:31 row_mask:0xc bank_mask:0xf
	v_mov_b32_e32 v73, v39
	v_readlane_b32 s7, v72, 63
	v_mov_b32_e32 v72, v43
	v_pk_fma_f32 v[72:73], v[72:73], v[72:73], v[76:77]
	v_mov_b32_e32 v76, v32
	v_add_f32_e32 v72, v72, v73
	v_mov_b32_e32 v77, v28
	s_nop 0
	v_add_f32_dpp v72, v72, v72 quad_perm:[1,0,3,2] row_mask:0xf bank_mask:0xf bound_ctrl:1
	v_fma_f32 v87, s7, v235, v225
	v_pk_mul_f32 v[76:77], v[76:77], v[76:77]
	v_add_f32_dpp v72, v72, v72 quad_perm:[2,3,0,1] row_mask:0xf bank_mask:0xf bound_ctrl:1
	s_nop 1
	v_add_f32_dpp v72, v72, v72 row_half_mirror row_mask:0xf bank_mask:0xf bound_ctrl:1
	s_nop 1
	v_add_f32_dpp v72, v72, v72 row_mirror row_mask:0xf bank_mask:0xf bound_ctrl:1
	s_nop 1
	v_add_f32_dpp v72, v72, v72 row_bcast:15 row_mask:0xa bank_mask:0xf
	s_nop 1
	v_add_f32_dpp v72, v72, v72 row_bcast:31 row_mask:0xc bank_mask:0xf
	v_mov_b32_e32 v73, v30
	v_readlane_b32 s7, v72, 63
	v_mov_b32_e32 v72, v34
	v_pk_fma_f32 v[72:73], v[72:73], v[72:73], v[76:77]
	v_mov_b32_e32 v76, v33
	v_add_f32_e32 v72, v72, v73
	v_mov_b32_e32 v77, v29
	s_nop 0
	v_add_f32_dpp v72, v72, v72 quad_perm:[1,0,3,2] row_mask:0xf bank_mask:0xf bound_ctrl:1
	v_fma_f32 v88, s7, v235, v225
	v_pk_mul_f32 v[76:77], v[76:77], v[76:77]
	v_add_f32_dpp v72, v72, v72 quad_perm:[2,3,0,1] row_mask:0xf bank_mask:0xf bound_ctrl:1
	s_nop 1
	v_add_f32_dpp v72, v72, v72 row_half_mirror row_mask:0xf bank_mask:0xf bound_ctrl:1
	s_nop 1
	v_add_f32_dpp v72, v72, v72 row_mirror row_mask:0xf bank_mask:0xf bound_ctrl:1
	s_nop 1
	v_add_f32_dpp v72, v72, v72 row_bcast:15 row_mask:0xa bank_mask:0xf
	s_nop 1
	v_add_f32_dpp v72, v72, v72 row_bcast:31 row_mask:0xc bank_mask:0xf
	v_mov_b32_e32 v73, v31
	v_readlane_b32 s7, v72, 63
	v_mov_b32_e32 v72, v35
	v_pk_fma_f32 v[72:73], v[72:73], v[72:73], v[76:77]
	v_mov_b32_e32 v76, v56
	v_add_f32_e32 v72, v72, v73
	v_mov_b32_e32 v77, v52
	s_nop 0
	v_add_f32_dpp v72, v72, v72 quad_perm:[1,0,3,2] row_mask:0xf bank_mask:0xf bound_ctrl:1
	v_fma_f32 v89, s7, v235, v225
	v_pk_mul_f32 v[76:77], v[76:77], v[76:77]
	v_add_f32_dpp v72, v72, v72 quad_perm:[2,3,0,1] row_mask:0xf bank_mask:0xf bound_ctrl:1
	s_nop 1
	v_add_f32_dpp v72, v72, v72 row_half_mirror row_mask:0xf bank_mask:0xf bound_ctrl:1
	s_nop 1
	v_add_f32_dpp v72, v72, v72 row_mirror row_mask:0xf bank_mask:0xf bound_ctrl:1
	s_nop 1
	v_add_f32_dpp v72, v72, v72 row_bcast:15 row_mask:0xa bank_mask:0xf
	s_nop 1
	v_add_f32_dpp v72, v72, v72 row_bcast:31 row_mask:0xc bank_mask:0xf
	v_mov_b32_e32 v73, v54
	v_readlane_b32 s7, v72, 63
	v_mov_b32_e32 v72, v58
	v_pk_fma_f32 v[72:73], v[72:73], v[72:73], v[76:77]
	v_mov_b32_e32 v76, v57
	v_add_f32_e32 v72, v72, v73
	v_mov_b32_e32 v77, v53
	s_nop 0
	v_add_f32_dpp v72, v72, v72 quad_perm:[1,0,3,2] row_mask:0xf bank_mask:0xf bound_ctrl:1
	v_fma_f32 v90, s7, v235, v225
	v_pk_mul_f32 v[76:77], v[76:77], v[76:77]
	v_add_f32_dpp v72, v72, v72 quad_perm:[2,3,0,1] row_mask:0xf bank_mask:0xf bound_ctrl:1
	s_nop 1
	v_add_f32_dpp v72, v72, v72 row_half_mirror row_mask:0xf bank_mask:0xf bound_ctrl:1
	s_nop 1
	v_add_f32_dpp v72, v72, v72 row_mirror row_mask:0xf bank_mask:0xf bound_ctrl:1
	s_nop 1
	v_add_f32_dpp v72, v72, v72 row_bcast:15 row_mask:0xa bank_mask:0xf
	s_nop 1
	v_add_f32_dpp v72, v72, v72 row_bcast:31 row_mask:0xc bank_mask:0xf
	v_mov_b32_e32 v73, v55
	v_readlane_b32 s7, v72, 63
	v_mov_b32_e32 v72, v59
	v_pk_fma_f32 v[72:73], v[72:73], v[72:73], v[76:77]
	v_mov_b32_e32 v76, v50
	v_add_f32_e32 v72, v72, v73
	v_mov_b32_e32 v77, v44
	s_nop 0
	v_add_f32_dpp v72, v72, v72 quad_perm:[1,0,3,2] row_mask:0xf bank_mask:0xf bound_ctrl:1
	v_fma_f32 v92, s7, v235, v225
	v_pk_mul_f32 v[76:77], v[76:77], v[76:77]
	v_add_f32_dpp v72, v72, v72 quad_perm:[2,3,0,1] row_mask:0xf bank_mask:0xf bound_ctrl:1
	s_nop 1
	v_add_f32_dpp v72, v72, v72 row_half_mirror row_mask:0xf bank_mask:0xf bound_ctrl:1
	s_nop 1
	v_add_f32_dpp v72, v72, v72 row_mirror row_mask:0xf bank_mask:0xf bound_ctrl:1
	s_nop 1
	v_add_f32_dpp v72, v72, v72 row_bcast:15 row_mask:0xa bank_mask:0xf
	s_nop 1
	v_add_f32_dpp v72, v72, v72 row_bcast:31 row_mask:0xc bank_mask:0xf
	v_mov_b32_e32 v73, v48
	v_readlane_b32 s7, v72, 63
	v_mov_b32_e32 v72, v46
	v_pk_fma_f32 v[72:73], v[72:73], v[72:73], v[76:77]
	v_mov_b32_e32 v76, v51
	v_add_f32_e32 v72, v72, v73
	v_mov_b32_e32 v77, v45
	s_nop 0
	v_add_f32_dpp v72, v72, v72 quad_perm:[1,0,3,2] row_mask:0xf bank_mask:0xf bound_ctrl:1
	v_fma_f32 v93, s7, v235, v225
	v_pk_mul_f32 v[76:77], v[76:77], v[76:77]
	v_add_f32_dpp v72, v72, v72 quad_perm:[2,3,0,1] row_mask:0xf bank_mask:0xf bound_ctrl:1
	s_nop 1
	v_add_f32_dpp v72, v72, v72 row_half_mirror row_mask:0xf bank_mask:0xf bound_ctrl:1
	s_nop 1
	v_add_f32_dpp v72, v72, v72 row_mirror row_mask:0xf bank_mask:0xf bound_ctrl:1
	s_nop 1
	v_add_f32_dpp v72, v72, v72 row_bcast:15 row_mask:0xa bank_mask:0xf
	s_nop 1
	v_add_f32_dpp v72, v72, v72 row_bcast:31 row_mask:0xc bank_mask:0xf
	v_mov_b32_e32 v73, v49
	v_readlane_b32 s7, v72, 63
	v_mov_b32_e32 v72, v47
	v_pk_fma_f32 v[72:73], v[72:73], v[72:73], v[76:77]
	v_mov_b32_e32 v76, v68
	v_add_f32_e32 v72, v72, v73
	v_mov_b32_e32 v77, v26
	s_nop 0
	v_add_f32_dpp v72, v72, v72 quad_perm:[1,0,3,2] row_mask:0xf bank_mask:0xf bound_ctrl:1
	v_fma_f32 v94, s7, v235, v225
	v_pk_mul_f32 v[76:77], v[76:77], v[76:77]
	v_add_f32_dpp v72, v72, v72 quad_perm:[2,3,0,1] row_mask:0xf bank_mask:0xf bound_ctrl:1
	s_nop 1
	v_add_f32_dpp v72, v72, v72 row_half_mirror row_mask:0xf bank_mask:0xf bound_ctrl:1
	s_nop 1
	v_add_f32_dpp v72, v72, v72 row_mirror row_mask:0xf bank_mask:0xf bound_ctrl:1
	s_nop 1
	v_add_f32_dpp v72, v72, v72 row_bcast:15 row_mask:0xa bank_mask:0xf
	s_nop 1
	v_add_f32_dpp v72, v72, v72 row_bcast:31 row_mask:0xc bank_mask:0xf
	v_mov_b32_e32 v73, v66
	v_readlane_b32 s7, v72, 63
	v_mov_b32_e32 v72, v70
	v_pk_fma_f32 v[72:73], v[72:73], v[72:73], v[76:77]
	v_mov_b32_e32 v76, v69
	v_add_f32_e32 v72, v72, v73
	v_mov_b32_e32 v77, v27
	s_nop 0
	v_add_f32_dpp v72, v72, v72 quad_perm:[1,0,3,2] row_mask:0xf bank_mask:0xf bound_ctrl:1
	v_fma_f32 v95, s7, v235, v225
	v_pk_mul_f32 v[76:77], v[76:77], v[76:77]
	v_add_f32_dpp v72, v72, v72 quad_perm:[2,3,0,1] row_mask:0xf bank_mask:0xf bound_ctrl:1
	s_nop 1
	v_add_f32_dpp v72, v72, v72 row_half_mirror row_mask:0xf bank_mask:0xf bound_ctrl:1
	s_nop 1
	v_add_f32_dpp v72, v72, v72 row_mirror row_mask:0xf bank_mask:0xf bound_ctrl:1
	s_nop 1
	v_add_f32_dpp v72, v72, v72 row_bcast:15 row_mask:0xa bank_mask:0xf
	s_nop 1
	v_add_f32_dpp v72, v72, v72 row_bcast:31 row_mask:0xc bank_mask:0xf
	v_mov_b32_e32 v73, v67
	v_readlane_b32 s7, v72, 63
	v_mov_b32_e32 v72, v71
	v_pk_fma_f32 v[72:73], v[72:73], v[72:73], v[76:77]
	v_mov_b32_e32 v76, v62
	v_add_f32_e32 v72, v72, v73
	v_mov_b32_e32 v77, v24
	s_nop 0
	v_add_f32_dpp v72, v72, v72 quad_perm:[1,0,3,2] row_mask:0xf bank_mask:0xf bound_ctrl:1
	v_fma_f32 v96, s7, v235, v225
	v_pk_mul_f32 v[76:77], v[76:77], v[76:77]
	v_add_f32_dpp v72, v72, v72 quad_perm:[2,3,0,1] row_mask:0xf bank_mask:0xf bound_ctrl:1
	s_nop 1
	v_add_f32_dpp v72, v72, v72 row_half_mirror row_mask:0xf bank_mask:0xf bound_ctrl:1
	s_nop 1
	v_add_f32_dpp v72, v72, v72 row_mirror row_mask:0xf bank_mask:0xf bound_ctrl:1
	s_nop 1
	v_add_f32_dpp v72, v72, v72 row_bcast:15 row_mask:0xa bank_mask:0xf
	s_nop 1
	v_add_f32_dpp v72, v72, v72 row_bcast:31 row_mask:0xc bank_mask:0xf
	v_mov_b32_e32 v73, v60
	v_readlane_b32 s7, v72, 63
	v_mov_b32_e32 v72, v64
	v_pk_fma_f32 v[72:73], v[72:73], v[72:73], v[76:77]
	v_mov_b32_e32 v76, v63
	v_add_f32_e32 v72, v72, v73
	v_mov_b32_e32 v77, v25
	s_nop 0
	v_add_f32_dpp v72, v72, v72 quad_perm:[1,0,3,2] row_mask:0xf bank_mask:0xf bound_ctrl:1
	v_fma_f32 v97, s7, v235, v225
	v_pk_mul_f32 v[76:77], v[76:77], v[76:77]
	v_add_f32_dpp v72, v72, v72 quad_perm:[2,3,0,1] row_mask:0xf bank_mask:0xf bound_ctrl:1
	s_nop 1
	v_add_f32_dpp v72, v72, v72 row_half_mirror row_mask:0xf bank_mask:0xf bound_ctrl:1
	s_nop 1
	v_add_f32_dpp v72, v72, v72 row_mirror row_mask:0xf bank_mask:0xf bound_ctrl:1
	s_nop 1
	v_add_f32_dpp v72, v72, v72 row_bcast:15 row_mask:0xa bank_mask:0xf
	s_nop 1
	v_add_f32_dpp v72, v72, v72 row_bcast:31 row_mask:0xc bank_mask:0xf
	v_mov_b32_e32 v73, v61
	v_readlane_b32 s7, v72, 63
	v_mov_b32_e32 v72, v65
	v_pk_fma_f32 v[72:73], v[72:73], v[72:73], v[76:77]
	v_fma_f32 v98, s7, v235, v225
	v_add_f32_e32 v72, v72, v73
	v_lshl_add_u32 v77, v1, 2, s8
	s_nop 0
	v_add_f32_dpp v72, v72, v72 quad_perm:[1,0,3,2] row_mask:0xf bank_mask:0xf bound_ctrl:1
	s_nop 1
	v_add_f32_dpp v72, v72, v72 quad_perm:[2,3,0,1] row_mask:0xf bank_mask:0xf bound_ctrl:1
	s_nop 1
	v_add_f32_dpp v72, v72, v72 row_half_mirror row_mask:0xf bank_mask:0xf bound_ctrl:1
	s_nop 1
	v_add_f32_dpp v72, v72, v72 row_mirror row_mask:0xf bank_mask:0xf bound_ctrl:1
	s_nop 1
	v_add_f32_dpp v72, v72, v72 row_bcast:15 row_mask:0xa bank_mask:0xf
	s_nop 1
	v_add_f32_dpp v72, v72, v72 row_bcast:31 row_mask:0xc bank_mask:0xf
	s_nop 0
	v_readlane_b32 s7, v72, 63
	global_load_dword v7, v[6:7], off
	s_nop 0
	global_load_dword v6, v[4:5], off
	global_load_dword v72, v[2:3], off
	global_load_dword v76, v[2:3], off offset:256
	global_load_dword v78, v[4:5], off offset:256
	global_load_dword v80, v[4:5], off offset:512
	global_load_dword v82, v[2:3], off offset:512
	global_load_dword v84, v[2:3], off offset:768
	global_load_dword v86, v[4:5], off offset:768
	v_rsq_f32_e32 v2, v79
	v_rsq_f32_e32 v3, v81
	v_rsq_f32_e32 v4, v83
	v_rsq_f32_e32 v5, v85
	v_fma_f32 v73, s7, v235, v225
	v_pk_mul_f32 v[22:23], v[22:23], v[2:3]
	v_pk_mul_f32 v[20:21], v[20:21], v[2:3]
	v_pk_mul_f32 v[10:11], v[10:11], v[4:5]
	v_pk_mul_f32 v[14:15], v[14:15], v[4:5]
	v_pk_mul_f32 v[18:19], v[18:19], v[2:3]
	v_pk_mul_f32 v[12:13], v[12:13], v[4:5]
	v_pk_mul_f32 v[2:3], v[16:17], v[2:3]
	v_pk_mul_f32 v[4:5], v[8:9], v[4:5]
	v_rsq_f32_e32 v8, v87
	v_rsq_f32_e32 v9, v88
	v_rsq_f32_e32 v16, v89
	v_rsq_f32_e32 v17, v90
	s_waitcnt vmcnt(8)
	ds_write_b32 v77, v7
	v_mad_u32_u24 v7, v74, s40, v75
	s_waitcnt vmcnt(6)
	v_pk_fma_f32 v[10:11], v[72:73], v[10:11], v[6:7] op_sel_hi:[0,1,0]
	v_pk_fma_f32 v[22:23], v[72:73], v[22:23], v[6:7] op_sel_hi:[0,1,0]
	s_waitcnt vmcnt(4)
	v_pk_fma_f32 v[14:15], v[76:77], v[14:15], v[78:79] op_sel_hi:[0,1,0]
	v_pk_fma_f32 v[20:21], v[76:77], v[20:21], v[78:79] op_sel_hi:[0,1,0]
	s_waitcnt vmcnt(2)
	v_pk_fma_f32 v[12:13], v[82:83], v[12:13], v[80:81] op_sel_hi:[0,1,0]
	v_pk_fma_f32 v[18:19], v[82:83], v[18:19], v[80:81] op_sel_hi:[0,1,0]
	s_waitcnt vmcnt(0)
	v_pk_fma_f32 v[88:89], v[84:85], v[4:5], v[86:87] op_sel_hi:[0,1,0]
	v_pk_fma_f32 v[90:91], v[84:85], v[2:3], v[86:87] op_sel_hi:[0,1,0]
	v_pk_mul_f32 v[2:3], v[42:43], v[8:9]
	v_pk_mul_f32 v[4:5], v[34:35], v[16:17]
	v_pk_fma_f32 v[2:3], v[72:73], v[2:3], v[6:7] op_sel_hi:[0,1,0]
	v_pk_fma_f32 v[4:5], v[72:73], v[4:5], v[6:7] op_sel_hi:[0,1,0]
	v_cvt_pk_bf16_f32 v5, v4, v5
	v_cvt_pk_bf16_f32 v4, v2, v3
	v_cvt_pk_bf16_f32 v3, v10, v11
	v_cvt_pk_bf16_f32 v2, v22, v23
	ds_write_b128 v7, v[2:5]
	v_pk_mul_f32 v[2:3], v[40:41], v[8:9]
	v_pk_mul_f32 v[4:5], v[32:33], v[16:17]
	v_pk_fma_f32 v[2:3], v[76:77], v[2:3], v[78:79] op_sel_hi:[0,1,0]
	v_pk_fma_f32 v[4:5], v[76:77], v[4:5], v[78:79] op_sel_hi:[0,1,0]
	v_cvt_pk_bf16_f32 v5, v4, v5
	v_cvt_pk_bf16_f32 v4, v2, v3
	v_cvt_pk_bf16_f32 v3, v14, v15
	v_cvt_pk_bf16_f32 v2, v20, v21
	ds_write_b128 v7, v[2:5] offset:17408
	v_pk_mul_f32 v[2:3], v[38:39], v[8:9]
	v_pk_mul_f32 v[4:5], v[30:31], v[16:17]
	v_pk_fma_f32 v[2:3], v[82:83], v[2:3], v[80:81] op_sel_hi:[0,1,0]
	v_pk_fma_f32 v[4:5], v[82:83], v[4:5], v[80:81] op_sel_hi:[0,1,0]
	v_cvt_pk_bf16_f32 v5, v4, v5
	v_cvt_pk_bf16_f32 v4, v2, v3
	v_cvt_pk_bf16_f32 v3, v12, v13
	v_cvt_pk_bf16_f32 v2, v18, v19
	ds_write_b128 v7, v[2:5] offset:34816
	v_pk_mul_f32 v[2:3], v[36:37], v[8:9]
	v_rsq_f32_e32 v8, v92
	v_rsq_f32_e32 v9, v93
	v_rsq_f32_e32 v10, v94
	v_rsq_f32_e32 v11, v95
	v_pk_mul_f32 v[4:5], v[28:29], v[16:17]
	v_pk_fma_f32 v[2:3], v[84:85], v[2:3], v[86:87] op_sel_hi:[0,1,0]
	v_pk_fma_f32 v[4:5], v[84:85], v[4:5], v[86:87] op_sel_hi:[0,1,0]
	v_cvt_pk_bf16_f32 v5, v4, v5
	v_cvt_pk_bf16_f32 v4, v2, v3
	v_cvt_pk_bf16_f32 v3, v88, v89
	v_cvt_pk_bf16_f32 v2, v90, v91
	ds_write_b128 v7, v[2:5] offset:52224
	v_pk_mul_f32 v[2:3], v[58:59], v[8:9]
	v_pk_mul_f32 v[4:5], v[46:47], v[10:11]
	v_pk_fma_f32 v[14:15], v[72:73], v[2:3], v[6:7] op_sel_hi:[0,1,0]
	v_pk_fma_f32 v[12:13], v[72:73], v[4:5], v[6:7] op_sel_hi:[0,1,0]
	v_pk_mul_f32 v[2:3], v[56:57], v[8:9]
	v_pk_mul_f32 v[4:5], v[50:51], v[10:11]
	v_pk_fma_f32 v[18:19], v[76:77], v[2:3], v[78:79] op_sel_hi:[0,1,0]
	v_pk_fma_f32 v[16:17], v[76:77], v[4:5], v[78:79] op_sel_hi:[0,1,0]
	v_pk_mul_f32 v[2:3], v[54:55], v[8:9]
	v_pk_mul_f32 v[4:5], v[48:49], v[10:11]
	v_pk_fma_f32 v[22:23], v[82:83], v[2:3], v[80:81] op_sel_hi:[0,1,0]
	v_pk_fma_f32 v[20:21], v[82:83], v[4:5], v[80:81] op_sel_hi:[0,1,0]
	v_pk_mul_f32 v[2:3], v[52:53], v[8:9]
	v_pk_mul_f32 v[4:5], v[44:45], v[10:11]
	v_rsq_f32_e32 v8, v96
	v_rsq_f32_e32 v9, v97
	v_rsq_f32_e32 v10, v98
	v_rsq_f32_e32 v11, v73
	v_pk_fma_f32 v[28:29], v[84:85], v[4:5], v[86:87] op_sel_hi:[0,1,0]
	v_pk_fma_f32 v[30:31], v[84:85], v[2:3], v[86:87] op_sel_hi:[0,1,0]
	v_pk_mul_f32 v[2:3], v[70:71], v[8:9]
	v_pk_mul_f32 v[4:5], v[64:65], v[10:11]
	v_pk_fma_f32 v[2:3], v[72:73], v[2:3], v[6:7] op_sel_hi:[0,1,0]
	v_pk_fma_f32 v[4:5], v[72:73], v[4:5], v[6:7] op_sel_hi:[0,1,0]
	v_cvt_pk_bf16_f32 v5, v4, v5
	v_cvt_pk_bf16_f32 v4, v2, v3
	v_cvt_pk_bf16_f32 v3, v12, v13
	v_cvt_pk_bf16_f32 v2, v14, v15
	ds_write_b128 v7, v[2:5] offset:16
	v_pk_mul_f32 v[2:3], v[68:69], v[8:9]
	v_pk_mul_f32 v[4:5], v[62:63], v[10:11]
	v_pk_fma_f32 v[2:3], v[76:77], v[2:3], v[78:79] op_sel_hi:[0,1,0]
	v_pk_fma_f32 v[4:5], v[76:77], v[4:5], v[78:79] op_sel_hi:[0,1,0]
	v_cvt_pk_bf16_f32 v5, v4, v5
	v_cvt_pk_bf16_f32 v4, v2, v3
	v_cvt_pk_bf16_f32 v3, v16, v17
	v_cvt_pk_bf16_f32 v2, v18, v19
	ds_write_b128 v7, v[2:5] offset:17424
	v_pk_mul_f32 v[2:3], v[66:67], v[8:9]
	v_pk_mul_f32 v[4:5], v[60:61], v[10:11]
	v_pk_fma_f32 v[2:3], v[82:83], v[2:3], v[80:81] op_sel_hi:[0,1,0]
	v_pk_fma_f32 v[4:5], v[82:83], v[4:5], v[80:81] op_sel_hi:[0,1,0]
	v_cvt_pk_bf16_f32 v5, v4, v5
	v_cvt_pk_bf16_f32 v4, v2, v3
	v_cvt_pk_bf16_f32 v3, v20, v21
	v_cvt_pk_bf16_f32 v2, v22, v23
	ds_write_b128 v7, v[2:5] offset:34832
	v_pk_mul_f32 v[2:3], v[26:27], v[8:9]
	v_pk_mul_f32 v[4:5], v[24:25], v[10:11]
	v_pk_fma_f32 v[2:3], v[84:85], v[2:3], v[86:87] op_sel_hi:[0,1,0]
	v_pk_fma_f32 v[4:5], v[84:85], v[4:5], v[86:87] op_sel_hi:[0,1,0]
	v_cvt_pk_bf16_f32 v5, v4, v5
	v_cvt_pk_bf16_f32 v4, v2, v3
	v_cvt_pk_bf16_f32 v3, v28, v29
	v_cvt_pk_bf16_f32 v2, v30, v31
	v_lshl_add_u64 v[8:9], s[28:29], 0, v[130:131]
	v_and_or_b32 v6, v1, 31, s6
	v_bfe_u32 v73, v1, 5, 1
	ds_write_b128 v7, v[2:5] offset:52240
	v_add_co_u32_e32 v70, vcc, s90, v8
	v_lshlrev_b32_e32 v1, 2, v73
	v_ashrrev_i32_e32 v7, 31, v6
	v_addc_co_u32_e32 v71, vcc, 0, v9, vcc
	v_or_b32_e32 v72, s66, v1
	v_lshlrev_b64 v[74:75], 1, v[6:7]
	v_add_co_u32_e32 v82, vcc, s46, v8
	v_lshl_add_u64 v[26:27], s[80:81], 0, v[74:75]
	v_mul_lo_u32 v10, v72, s87
	v_mov_b32_e32 v11, v131
	v_addc_co_u32_e32 v83, vcc, 0, v9, vcc
	v_lshl_add_u64 v[10:11], v[26:27], 0, v[10:11]
	v_add_co_u32_e32 v94, vcc, s90, v10
	s_mov_b32 s6, 0xc000
	s_nop 0
	v_addc_co_u32_e32 v95, vcc, 0, v11, vcc
	v_add_co_u32_e32 v28, vcc, s41, v10
	v_or_b32_e32 v7, s33, v1
	s_nop 0
	v_addc_co_u32_e32 v29, vcc, 0, v11, vcc
	v_add_co_u32_e32 v76, vcc, s97, v10
	s_waitcnt lgkmcnt(0)
	s_nop 0
	v_addc_co_u32_e32 v77, vcc, 0, v11, vcc
	v_add_co_u32_e32 v78, vcc, s6, v10
	s_mov_b32 s6, 0xd000
	s_nop 0
	v_addc_co_u32_e32 v79, vcc, 0, v11, vcc
	v_add_co_u32_e32 v80, vcc, s6, v10
	s_mov_b32 s6, 0xf000
	s_nop 0
	v_addc_co_u32_e32 v81, vcc, 0, v11, vcc
	v_add_co_u32_e32 v84, vcc, s6, v10
	s_mov_b32 s6, 0x10000
	s_nop 0
	v_addc_co_u32_e32 v85, vcc, 0, v11, vcc
	v_add_co_u32_e32 v86, vcc, s6, v10
	s_mov_b32 s6, 0x18000
	s_nop 0
	v_addc_co_u32_e32 v87, vcc, 0, v11, vcc
	v_add_co_u32_e32 v88, vcc, s6, v10
	s_mov_b32 s6, 0x19000
	s_nop 0
	v_addc_co_u32_e32 v89, vcc, 0, v11, vcc
	v_add_co_u32_e32 v90, vcc, s6, v10
	s_mov_b32 s6, 0x1b000
	s_nop 0
	v_addc_co_u32_e32 v91, vcc, 0, v11, vcc
	v_add_co_u32_e32 v92, vcc, s6, v10
	s_mov_b32 s6, 0x1c000
	s_nop 0
	v_addc_co_u32_e32 v93, vcc, 0, v11, vcc
	v_add_co_u32_e32 v54, vcc, s6, v10
	s_mov_b32 s6, 0x24000
	s_nop 0
	v_addc_co_u32_e32 v55, vcc, 0, v11, vcc
	v_add_co_u32_e32 v56, vcc, s6, v10
	s_mov_b32 s6, 0x25000
	s_nop 0
	v_addc_co_u32_e32 v57, vcc, 0, v11, vcc
	v_add_co_u32_e32 v58, vcc, s6, v10
	s_mov_b32 s6, 0x27000
	s_nop 0
	v_addc_co_u32_e32 v59, vcc, 0, v11, vcc
	v_add_co_u32_e32 v60, vcc, s6, v10
	s_mov_b32 s6, 0x28000
	s_nop 0
	v_addc_co_u32_e32 v61, vcc, 0, v11, vcc
	v_add_co_u32_e32 v62, vcc, s6, v10
	v_mul_lo_u32 v10, v7, s87
	s_nop 0
	v_addc_co_u32_e32 v63, vcc, 0, v11, vcc
	v_mov_b32_e32 v11, v131
	v_lshl_add_u64 v[10:11], v[26:27], 0, v[10:11]
	s_mov_b32 s6, 0x6030000
	v_add_co_u32_e32 v64, vcc, s6, v10
	s_mov_b32 s6, 0x6031000
	s_nop 0
	v_addc_co_u32_e32 v65, vcc, 0, v11, vcc
	v_add_co_u32_e32 v66, vcc, s6, v10
	s_mov_b32 s6, 0x6033000
	s_nop 0
	v_addc_co_u32_e32 v67, vcc, 0, v11, vcc
	v_add_co_u32_e32 v68, vcc, s6, v10
	s_mov_b32 s6, 0x6034000
	s_nop 0
	v_addc_co_u32_e32 v69, vcc, 0, v11, vcc
	v_add_co_u32_e32 v38, vcc, s6, v10
	s_mov_b32 s6, 0x603c000
	s_nop 0
	v_addc_co_u32_e32 v39, vcc, 0, v11, vcc
	v_add_co_u32_e32 v40, vcc, s6, v10
	s_mov_b32 s6, 0x603d000
	s_nop 0
	v_addc_co_u32_e32 v41, vcc, 0, v11, vcc
	v_add_co_u32_e32 v42, vcc, s6, v10
	s_mov_b32 s6, 0x603f000
	s_nop 0
	v_addc_co_u32_e32 v43, vcc, 0, v11, vcc
	v_add_co_u32_e32 v44, vcc, s6, v10
	s_mov_b32 s6, 0x6040000
	s_nop 0
	v_addc_co_u32_e32 v45, vcc, 0, v11, vcc
	v_add_co_u32_e32 v46, vcc, s6, v10
	s_mov_b32 s6, 0x6048000
	s_nop 0
	v_addc_co_u32_e32 v47, vcc, 0, v11, vcc
	v_add_co_u32_e32 v48, vcc, s6, v10
	s_mov_b32 s6, 0x6049000
	s_nop 0
	v_addc_co_u32_e32 v49, vcc, 0, v11, vcc
	v_add_co_u32_e32 v50, vcc, s6, v10
	s_mov_b32 s6, 0x604b000
	s_nop 0
	v_addc_co_u32_e32 v51, vcc, 0, v11, vcc
	v_add_co_u32_e32 v52, vcc, s6, v10
	s_mov_b32 s6, 0x604c000
	s_nop 0
	v_addc_co_u32_e32 v53, vcc, 0, v11, vcc
	v_add_co_u32_e32 v12, vcc, s6, v10
	s_mov_b32 s6, 0x6054000
	s_nop 0
	v_addc_co_u32_e32 v13, vcc, 0, v11, vcc
	v_add_co_u32_e32 v14, vcc, s6, v10
	s_mov_b32 s6, 0x6055000
	s_nop 0
	v_addc_co_u32_e32 v15, vcc, 0, v11, vcc
	v_add_co_u32_e32 v16, vcc, s6, v10
	s_mov_b32 s6, 0x6057000
	s_nop 0
	v_addc_co_u32_e32 v17, vcc, 0, v11, vcc
	v_add_co_u32_e32 v34, vcc, s6, v10
	s_mov_b32 s6, 0x6058000
	s_nop 0
	v_addc_co_u32_e32 v35, vcc, 0, v11, vcc
	v_add_co_u32_e32 v36, vcc, s6, v10
	v_mad_u64_u32 v[26:27], s[6:7], v72, s87, v[26:27]
	s_barrier
	global_load_dwordx4 v[2:5], v130, s[28:29]
	global_load_dwordx4 v[30:33], v130, s[28:29] offset:1024
	global_load_dwordx4 v[22:25], v130, s[28:29] offset:2048
	global_load_dwordx4 v[18:21], v130, s[28:29] offset:3072
	global_load_ushort v96, v[26:27], off
	global_load_ushort v7, v[28:29], off
	s_nop 0
	global_load_dwordx4 v[26:29], v[70:71], off offset:1024
	v_addc_co_u32_e32 v37, vcc, 0, v11, vcc
	global_load_ushort v94, v[94:95], off offset:2048
	s_mov_b32 s6, 0x6060000
	v_mul_lo_u32 v6, v6, s40
	s_waitcnt vmcnt(3)
	v_lshlrev_b32_e32 v96, 16, v96
	v_fma_f32 v97, |v96|, s92, 1.0
	v_rcp_f32_e32 v97, v97
	v_mul_f32_e32 v99, v96, v96
	v_mul_f32_e32 v99, 0xbf38aa3b, v99
	v_exp_f32_e32 v99, v99
	v_fmamk_f32 v98, v97, 0x3f07dc22, v236
	v_fmaak_f32 v98, v97, v98, 0x3f35f0e3
	v_fmaak_f32 v98, v97, v98, 0xbe11a98e
	s_waitcnt vmcnt(0)
	v_lshlrev_b32_e32 v94, 16, v94
	v_fmaak_f32 v98, v97, v98, 0x3e027906
	v_fma_f32 v95, |v94|, s92, 1.0
	v_mul_f32_e32 v97, v97, v98
	v_rcp_f32_e32 v95, v95
	v_mul_f32_e32 v97, v99, v97
	v_mul_f32_e32 v98, v97, v96
	v_fma_f32 v97, -v97, v96, v96
	v_cmp_gt_f32_e32 vcc, 0, v96
	v_fmamk_f32 v96, v95, 0x3f07dc22, v236
	v_fmaak_f32 v96, v95, v96, 0x3f35f0e3
	v_cndmask_b32_e32 v130, v97, v98, vcc
	v_mul_f32_e32 v97, v94, v94
	v_mul_f32_e32 v97, 0xbf38aa3b, v97
	v_exp_f32_e32 v97, v97
	v_fmaak_f32 v96, v95, v96, 0xbe11a98e
	v_fmaak_f32 v96, v95, v96, 0x3e027906
	v_mul_f32_e32 v95, v95, v96
	v_mul_f32_e32 v95, v97, v95
	v_lshlrev_b32_e32 v7, 16, v7
	v_mul_f32_e32 v96, v95, v94
	v_fma_f32 v95, -v95, v94, v94
	v_cmp_gt_f32_e32 vcc, 0, v94
	v_fma_f32 v94, |v7|, s92, 1.0
	v_rcp_f32_e32 v94, v94
	v_cndmask_b32_e32 v167, v95, v96, vcc
	v_mul_f32_e32 v96, v7, v7
	v_mul_f32_e32 v96, 0xbf38aa3b, v96
	v_fmamk_f32 v95, v94, 0x3f07dc22, v236
	v_fmaak_f32 v95, v94, v95, 0x3f35f0e3
	v_exp_f32_e32 v96, v96
	v_fmaak_f32 v95, v94, v95, 0xbe11a98e
	v_fmaak_f32 v95, v94, v95, 0x3e027906
	v_mul_f32_e32 v94, v94, v95
	v_mul_f32_e32 v94, v96, v94
	v_mul_f32_e32 v95, v94, v7
	v_fma_f32 v94, -v94, v7, v7
	v_cmp_gt_f32_e32 vcc, 0, v7
	global_load_ushort v7, v[76:77], off offset:2048
	s_nop 0
	global_load_ushort v76, v[78:79], off
	global_load_ushort v77, v[80:81], off offset:2048
	s_nop 0
	global_load_ushort v78, v[84:85], off
	global_load_ushort v79, v[86:87], off offset:2048
	global_load_ushort v80, v[88:89], off
	global_load_ushort v81, v[90:91], off offset:2048
	s_nop 0
	global_load_ushort v84, v[92:93], off
	v_cndmask_b32_e32 v168, v94, v95, vcc
	s_waitcnt vmcnt(7)
	v_lshlrev_b32_e32 v7, 16, v7
	v_fma_f32 v85, |v7|, s92, 1.0
	v_rcp_f32_e32 v85, v85
	v_mul_f32_e32 v87, v7, v7
	v_mul_f32_e32 v87, 0xbf38aa3b, v87
	v_exp_f32_e32 v87, v87
	v_fmamk_f32 v86, v85, 0x3f07dc22, v236
	v_fmaak_f32 v86, v85, v86, 0x3f35f0e3
	v_fmaak_f32 v86, v85, v86, 0xbe11a98e
	v_fmaak_f32 v86, v85, v86, 0x3e027906
	v_mul_f32_e32 v85, v85, v86
	v_mul_f32_e32 v85, v87, v85
	v_mul_f32_e32 v86, v85, v7
	v_fma_f32 v85, -v85, v7, v7
	v_cmp_gt_f32_e32 vcc, 0, v7
	s_waitcnt vmcnt(6)
	v_lshlrev_b32_e32 v7, 16, v76
	v_fma_f32 v76, |v7|, s92, 1.0
	v_rcp_f32_e32 v76, v76
	v_cndmask_b32_e32 v169, v85, v86, vcc
	v_mul_f32_e32 v86, v7, v7
	v_mul_f32_e32 v86, 0xbf38aa3b, v86
	v_fmamk_f32 v85, v76, 0x3f07dc22, v236
	v_fmaak_f32 v85, v76, v85, 0x3f35f0e3
	v_exp_f32_e32 v86, v86
	v_fmaak_f32 v85, v76, v85, 0xbe11a98e
	v_fmaak_f32 v85, v76, v85, 0x3e027906
	v_mul_f32_e32 v76, v76, v85
	v_mul_f32_e32 v76, v86, v76
	v_mul_f32_e32 v85, v76, v7
	v_fma_f32 v76, -v76, v7, v7
	v_cmp_gt_f32_e32 vcc, 0, v7
	s_waitcnt vmcnt(5)
	v_lshlrev_b32_e32 v7, 16, v77
	v_cndmask_b32_e32 v170, v76, v85, vcc
	v_fma_f32 v76, |v7|, s92, 1.0
	v_rcp_f32_e32 v76, v76
	v_mul_f32_e32 v85, v7, v7
	v_mul_f32_e32 v85, 0xbf38aa3b, v85
	v_exp_f32_e32 v85, v85
	v_fmamk_f32 v77, v76, 0x3f07dc22, v236
	v_fmaak_f32 v77, v76, v77, 0x3f35f0e3
	v_fmaak_f32 v77, v76, v77, 0xbe11a98e
	v_fmaak_f32 v77, v76, v77, 0x3e027906
	v_mul_f32_e32 v76, v76, v77
	v_mul_f32_e32 v76, v85, v76
	v_mul_f32_e32 v77, v76, v7
	v_fma_f32 v76, -v76, v7, v7
	v_cmp_gt_f32_e32 vcc, 0, v7
	s_waitcnt vmcnt(4)
	v_lshlrev_b32_e32 v7, 16, v78
	v_mul_f32_e32 v78, v7, v7
	v_cndmask_b32_e32 v171, v76, v77, vcc
	v_fma_f32 v76, |v7|, s92, 1.0
	v_rcp_f32_e32 v76, v76
	v_mul_f32_e32 v78, 0xbf38aa3b, v78
	v_exp_f32_e32 v78, v78
	v_cmp_gt_f32_e32 vcc, 0, v7
	v_fmamk_f32 v77, v76, 0x3f07dc22, v236
	v_fmaak_f32 v77, v76, v77, 0x3f35f0e3
	v_fmaak_f32 v77, v76, v77, 0xbe11a98e
	v_fmaak_f32 v77, v76, v77, 0x3e027906
	v_mul_f32_e32 v76, v76, v77
	v_mul_f32_e32 v76, v78, v76
	v_mul_f32_e32 v77, v76, v7
	v_fma_f32 v76, -v76, v7, v7
	s_waitcnt vmcnt(3)
	v_lshlrev_b32_e32 v7, 16, v79
	v_cndmask_b32_e32 v172, v76, v77, vcc
	v_fma_f32 v76, |v7|, s92, 1.0
	v_rcp_f32_e32 v76, v76
	v_mul_f32_e32 v78, v7, v7
	v_mul_f32_e32 v78, 0xbf38aa3b, v78
	v_exp_f32_e32 v78, v78
	v_fmamk_f32 v77, v76, 0x3f07dc22, v236
	v_fmaak_f32 v77, v76, v77, 0x3f35f0e3
	v_fmaak_f32 v77, v76, v77, 0xbe11a98e
	v_fmaak_f32 v77, v76, v77, 0x3e027906
	v_mul_f32_e32 v76, v76, v77
	v_mul_f32_e32 v76, v78, v76
	v_mul_f32_e32 v77, v76, v7
	v_fma_f32 v76, -v76, v7, v7
	v_cmp_gt_f32_e32 vcc, 0, v7
	s_waitcnt vmcnt(2)
	v_lshlrev_b32_e32 v7, 16, v80
	v_mul_f32_e32 v78, v7, v7
	v_cndmask_b32_e32 v173, v76, v77, vcc
	v_fma_f32 v76, |v7|, s92, 1.0
	v_rcp_f32_e32 v76, v76
	v_mul_f32_e32 v78, 0xbf38aa3b, v78
	v_exp_f32_e32 v78, v78
	v_cmp_gt_f32_e32 vcc, 0, v7
	v_fmamk_f32 v77, v76, 0x3f07dc22, v236
	v_fmaak_f32 v77, v76, v77, 0x3f35f0e3
	v_fmaak_f32 v77, v76, v77, 0xbe11a98e
	v_fmaak_f32 v77, v76, v77, 0x3e027906
	v_mul_f32_e32 v76, v76, v77
	v_mul_f32_e32 v76, v78, v76
	v_mul_f32_e32 v77, v76, v7
	v_fma_f32 v76, -v76, v7, v7
	s_waitcnt vmcnt(1)
	v_lshlrev_b32_e32 v7, 16, v81
	v_cndmask_b32_e32 v174, v76, v77, vcc
	v_fma_f32 v76, |v7|, s92, 1.0
	v_rcp_f32_e32 v76, v76
	v_mul_f32_e32 v78, v7, v7
	v_mul_f32_e32 v78, 0xbf38aa3b, v78
	v_exp_f32_e32 v78, v78
	v_fmamk_f32 v77, v76, 0x3f07dc22, v236
	v_fmaak_f32 v77, v76, v77, 0x3f35f0e3
	v_fmaak_f32 v77, v76, v77, 0xbe11a98e
	v_fmaak_f32 v77, v76, v77, 0x3e027906
	v_mul_f32_e32 v76, v76, v77
	v_mul_f32_e32 v76, v78, v76
	v_mul_f32_e32 v77, v76, v7
	v_fma_f32 v76, -v76, v7, v7
	v_cmp_gt_f32_e32 vcc, 0, v7
	s_waitcnt vmcnt(0)
	v_lshlrev_b32_e32 v7, 16, v84
	v_mul_f32_e32 v78, v7, v7
	v_cndmask_b32_e32 v175, v76, v77, vcc
	v_fma_f32 v76, |v7|, s92, 1.0
	v_rcp_f32_e32 v76, v76
	v_mul_f32_e32 v78, 0xbf38aa3b, v78
	v_exp_f32_e32 v78, v78
	v_cmp_gt_f32_e32 vcc, 0, v7
	v_fmamk_f32 v77, v76, 0x3f07dc22, v236
	v_fmaak_f32 v77, v76, v77, 0x3f35f0e3
	v_fmaak_f32 v77, v76, v77, 0xbe11a98e
	v_fmaak_f32 v77, v76, v77, 0x3e027906
	v_mul_f32_e32 v76, v76, v77
	v_mul_f32_e32 v76, v78, v76
	v_mul_f32_e32 v77, v76, v7
	v_fma_f32 v76, -v76, v7, v7
	global_load_ushort v7, v[54:55], off offset:2048
	s_nop 0
	global_load_ushort v54, v[56:57], off
	global_load_ushort v55, v[58:59], off offset:2048
	s_nop 0
	global_load_ushort v56, v[60:61], off
	global_load_ushort v57, v[62:63], off offset:2048
	global_load_ushort v58, v[64:65], off
	global_load_ushort v59, v[66:67], off offset:2048
	s_nop 0
	global_load_ushort v60, v[68:69], off
	v_cndmask_b32_e32 v176, v76, v77, vcc
	v_lshl_add_u64 v[84:85], s[76:77], 0, v[74:75]
	s_waitcnt vmcnt(7)
	v_lshlrev_b32_e32 v7, 16, v7
	v_fma_f32 v61, |v7|, s92, 1.0
	v_rcp_f32_e32 v61, v61
	v_mul_f32_e32 v63, v7, v7
	v_mul_f32_e32 v63, 0xbf38aa3b, v63
	v_exp_f32_e32 v63, v63
	v_fmamk_f32 v62, v61, 0x3f07dc22, v236
	v_fmaak_f32 v62, v61, v62, 0x3f35f0e3
	v_fmaak_f32 v62, v61, v62, 0xbe11a98e
	v_fmaak_f32 v62, v61, v62, 0x3e027906
	v_mul_f32_e32 v61, v61, v62
	v_mul_f32_e32 v61, v63, v61
	v_mul_f32_e32 v62, v61, v7
	v_fma_f32 v61, -v61, v7, v7
	v_cmp_gt_f32_e32 vcc, 0, v7
	s_waitcnt vmcnt(6)
	v_lshlrev_b32_e32 v7, 16, v54
	v_fma_f32 v54, |v7|, s92, 1.0
	v_rcp_f32_e32 v54, v54
	v_cndmask_b32_e32 v177, v61, v62, vcc
	v_mul_f32_e32 v62, v7, v7
	v_mul_f32_e32 v62, 0xbf38aa3b, v62
	v_fmamk_f32 v61, v54, 0x3f07dc22, v236
	v_fmaak_f32 v61, v54, v61, 0x3f35f0e3
	v_exp_f32_e32 v62, v62
	v_fmaak_f32 v61, v54, v61, 0xbe11a98e
	v_fmaak_f32 v61, v54, v61, 0x3e027906
	v_mul_f32_e32 v54, v54, v61
	v_mul_f32_e32 v54, v62, v54
	v_mul_f32_e32 v61, v54, v7
	v_fma_f32 v54, -v54, v7, v7
	v_cmp_gt_f32_e32 vcc, 0, v7
	s_waitcnt vmcnt(5)
	v_lshlrev_b32_e32 v7, 16, v55
	v_cndmask_b32_e32 v178, v54, v61, vcc
	v_fma_f32 v54, |v7|, s92, 1.0
	v_rcp_f32_e32 v54, v54
	v_mul_f32_e32 v61, v7, v7
	v_mul_f32_e32 v61, 0xbf38aa3b, v61
	v_exp_f32_e32 v61, v61
	v_fmamk_f32 v55, v54, 0x3f07dc22, v236
	v_fmaak_f32 v55, v54, v55, 0x3f35f0e3
	v_fmaak_f32 v55, v54, v55, 0xbe11a98e
	v_fmaak_f32 v55, v54, v55, 0x3e027906
	v_mul_f32_e32 v54, v54, v55
	v_mul_f32_e32 v54, v61, v54
	v_mul_f32_e32 v55, v54, v7
	v_fma_f32 v54, -v54, v7, v7
	v_cmp_gt_f32_e32 vcc, 0, v7
	s_waitcnt vmcnt(4)
	v_lshlrev_b32_e32 v7, 16, v56
	v_mul_f32_e32 v56, v7, v7
	v_cndmask_b32_e32 v179, v54, v55, vcc
	v_fma_f32 v54, |v7|, s92, 1.0
	v_rcp_f32_e32 v54, v54
	v_mul_f32_e32 v56, 0xbf38aa3b, v56
	v_exp_f32_e32 v56, v56
	v_cmp_gt_f32_e32 vcc, 0, v7
	v_fmamk_f32 v55, v54, 0x3f07dc22, v236
	v_fmaak_f32 v55, v54, v55, 0x3f35f0e3
	v_fmaak_f32 v55, v54, v55, 0xbe11a98e
	v_fmaak_f32 v55, v54, v55, 0x3e027906
	v_mul_f32_e32 v54, v54, v55
	v_mul_f32_e32 v54, v56, v54
	v_mul_f32_e32 v55, v54, v7
	v_fma_f32 v54, -v54, v7, v7
	s_waitcnt vmcnt(3)
	v_lshlrev_b32_e32 v7, 16, v57
	v_cndmask_b32_e32 v180, v54, v55, vcc
	v_fma_f32 v54, |v7|, s92, 1.0
	v_rcp_f32_e32 v54, v54
	v_mul_f32_e32 v56, v7, v7
	v_mul_f32_e32 v56, 0xbf38aa3b, v56
	v_exp_f32_e32 v56, v56
	v_fmamk_f32 v55, v54, 0x3f07dc22, v236
	v_fmaak_f32 v55, v54, v55, 0x3f35f0e3
	v_fmaak_f32 v55, v54, v55, 0xbe11a98e
	v_fmaak_f32 v55, v54, v55, 0x3e027906
	v_mul_f32_e32 v54, v54, v55
	v_mul_f32_e32 v54, v56, v54
	v_mul_f32_e32 v55, v54, v7
	v_fma_f32 v54, -v54, v7, v7
	v_cmp_gt_f32_e32 vcc, 0, v7
	s_waitcnt vmcnt(2)
	v_lshlrev_b32_e32 v7, 16, v58
	v_mul_f32_e32 v56, v7, v7
	v_cndmask_b32_e32 v181, v54, v55, vcc
	v_add_co_u32_e32 v134, vcc, s6, v10
	s_mov_b32 s6, 0x6061000
	s_nop 0
	v_addc_co_u32_e32 v135, vcc, 0, v11, vcc
	v_add_co_u32_e32 v136, vcc, s6, v10
	s_mov_b32 s6, 0x6063000
	s_nop 0
	v_addc_co_u32_e32 v137, vcc, 0, v11, vcc
	v_add_co_u32_e32 v138, vcc, s6, v10
	s_mov_b32 s6, 0x6064000
	s_nop 0
	v_addc_co_u32_e32 v139, vcc, 0, v11, vcc
	v_add_co_u32_e32 v140, vcc, s6, v10
	s_mov_b32 s6, 0x606c000
	s_nop 0
	v_addc_co_u32_e32 v141, vcc, 0, v11, vcc
	v_add_co_u32_e32 v142, vcc, s6, v10
	s_mov_b32 s6, 0x606d000
	s_nop 0
	v_addc_co_u32_e32 v143, vcc, 0, v11, vcc
	v_add_co_u32_e32 v144, vcc, s6, v10
	s_mov_b32 s6, 0x606f000
	s_nop 0
	v_addc_co_u32_e32 v145, vcc, 0, v11, vcc
	v_add_co_u32_e32 v146, vcc, s6, v10
	s_mov_b32 s6, 0x6070000
	s_nop 0
	v_addc_co_u32_e32 v147, vcc, 0, v11, vcc
	v_add_co_u32_e32 v148, vcc, s6, v10
	s_mov_b32 s6, 0x6078000
	s_nop 0
	v_addc_co_u32_e32 v149, vcc, 0, v11, vcc
	v_add_co_u32_e32 v76, vcc, s6, v10
	s_mov_b32 s6, 0x6079000
	s_nop 0
	v_addc_co_u32_e32 v77, vcc, 0, v11, vcc
	v_add_co_u32_e32 v78, vcc, s6, v10
	s_mov_b32 s6, 0x607b000
	s_nop 0
	v_addc_co_u32_e32 v79, vcc, 0, v11, vcc
	v_add_co_u32_e32 v80, vcc, s6, v10
	s_mov_b32 s6, 0x607c000
	s_nop 0
	v_addc_co_u32_e32 v81, vcc, 0, v11, vcc
	v_fma_f32 v54, |v7|, s92, 1.0
	v_add_co_u32_e32 v122, vcc, s6, v10
	v_rcp_f32_e32 v54, v54
	s_nop 0
	v_addc_co_u32_e32 v123, vcc, 0, v11, vcc
	s_mov_b32 s6, 0x6084000
	v_add_co_u32_e32 v124, vcc, s6, v10
	s_mov_b32 s6, 0x6085000
	s_nop 0
	v_addc_co_u32_e32 v125, vcc, 0, v11, vcc
	v_add_co_u32_e32 v126, vcc, s6, v10
	v_fmamk_f32 v55, v54, 0x3f07dc22, v236
	v_mul_f32_e32 v56, 0xbf38aa3b, v56
	v_addc_co_u32_e32 v127, vcc, 0, v11, vcc
	s_mov_b32 s6, 0x6087000
	v_fmaak_f32 v55, v54, v55, 0x3f35f0e3
	v_exp_f32_e32 v56, v56
	v_add_co_u32_e32 v128, vcc, s6, v10
	v_fmaak_f32 v55, v54, v55, 0xbe11a98e
	s_nop 0
	v_addc_co_u32_e32 v129, vcc, 0, v11, vcc
	s_mov_b32 s6, 0x6088000
	v_fmaak_f32 v55, v54, v55, 0x3e027906
	v_add_co_u32_e32 v132, vcc, s6, v10
	v_mul_f32_e32 v54, v54, v55
	s_nop 0
	v_addc_co_u32_e32 v133, vcc, 0, v11, vcc
	v_mul_f32_e32 v54, v56, v54
	v_mul_f32_e32 v55, v54, v7
	v_fma_f32 v54, -v54, v7, v7
	v_cmp_gt_f32_e32 vcc, 0, v7
	s_waitcnt vmcnt(1)
	v_lshlrev_b32_e32 v7, 16, v59
	v_mul_f32_e32 v56, v7, v7
	v_cndmask_b32_e32 v151, v54, v55, vcc
	v_fma_f32 v54, |v7|, s92, 1.0
	v_rcp_f32_e32 v54, v54
	v_mul_f32_e32 v56, 0xbf38aa3b, v56
	v_exp_f32_e32 v56, v56
	v_cmp_gt_f32_e32 vcc, 0, v7
	v_fmamk_f32 v55, v54, 0x3f07dc22, v236
	v_fmaak_f32 v55, v54, v55, 0x3f35f0e3
	v_fmaak_f32 v55, v54, v55, 0xbe11a98e
	v_fmaak_f32 v55, v54, v55, 0x3e027906
	v_mul_f32_e32 v54, v54, v55
	v_mul_f32_e32 v54, v56, v54
	v_mul_f32_e32 v55, v54, v7
	v_fma_f32 v54, -v54, v7, v7
	s_waitcnt vmcnt(0)
	v_lshlrev_b32_e32 v7, 16, v60
	v_cndmask_b32_e32 v152, v54, v55, vcc
	v_fma_f32 v54, |v7|, s92, 1.0
	v_rcp_f32_e32 v54, v54
	v_mul_f32_e32 v56, v7, v7
	v_mul_f32_e32 v56, 0xbf38aa3b, v56
	v_exp_f32_e32 v56, v56
	v_fmamk_f32 v55, v54, 0x3f07dc22, v236
	v_fmaak_f32 v55, v54, v55, 0x3f35f0e3
	v_fmaak_f32 v55, v54, v55, 0xbe11a98e
	v_fmaak_f32 v55, v54, v55, 0x3e027906
	v_mul_f32_e32 v54, v54, v55
	v_mul_f32_e32 v54, v56, v54
	v_mul_f32_e32 v55, v54, v7
	v_fma_f32 v54, -v54, v7, v7
	v_cmp_gt_f32_e32 vcc, 0, v7
	global_load_ushort v7, v[38:39], off offset:2048
	s_nop 0
	global_load_ushort v38, v[40:41], off
	global_load_ushort v39, v[42:43], off offset:2048
	s_nop 0
	global_load_ushort v40, v[44:45], off
	global_load_ushort v41, v[46:47], off offset:2048
	global_load_ushort v42, v[48:49], off
	global_load_ushort v43, v[50:51], off offset:2048
	s_nop 0
	global_load_ushort v44, v[52:53], off
	v_cndmask_b32_e32 v153, v54, v55, vcc
	s_mov_b32 s6, 0x6090000
	s_waitcnt vmcnt(7)
	v_lshlrev_b32_e32 v7, 16, v7
	v_fma_f32 v45, |v7|, s92, 1.0
	v_rcp_f32_e32 v45, v45
	v_mul_f32_e32 v47, v7, v7
	v_mul_f32_e32 v47, 0xbf38aa3b, v47
	v_exp_f32_e32 v47, v47
	v_fmamk_f32 v46, v45, 0x3f07dc22, v236
	v_fmaak_f32 v46, v45, v46, 0x3f35f0e3
	v_fmaak_f32 v46, v45, v46, 0xbe11a98e
	v_fmaak_f32 v46, v45, v46, 0x3e027906
	v_mul_f32_e32 v45, v45, v46
	v_mul_f32_e32 v45, v47, v45
	v_mul_f32_e32 v46, v45, v7
	v_fma_f32 v45, -v45, v7, v7
	v_cmp_gt_f32_e32 vcc, 0, v7
	s_waitcnt vmcnt(6)
	v_lshlrev_b32_e32 v7, 16, v38
	v_fma_f32 v38, |v7|, s92, 1.0
	v_rcp_f32_e32 v38, v38
	v_cndmask_b32_e32 v154, v45, v46, vcc
	v_mul_f32_e32 v46, v7, v7
	v_mul_f32_e32 v46, 0xbf38aa3b, v46
	v_fmamk_f32 v45, v38, 0x3f07dc22, v236
	v_fmaak_f32 v45, v38, v45, 0x3f35f0e3
	v_exp_f32_e32 v46, v46
	v_fmaak_f32 v45, v38, v45, 0xbe11a98e
	v_fmaak_f32 v45, v38, v45, 0x3e027906
	v_mul_f32_e32 v38, v38, v45
	v_mul_f32_e32 v38, v46, v38
	v_mul_f32_e32 v45, v38, v7
	v_fma_f32 v38, -v38, v7, v7
	v_cmp_gt_f32_e32 vcc, 0, v7
	s_waitcnt vmcnt(5)
	v_lshlrev_b32_e32 v7, 16, v39
	v_cndmask_b32_e32 v155, v38, v45, vcc
	v_fma_f32 v38, |v7|, s92, 1.0
	v_rcp_f32_e32 v38, v38
	v_mul_f32_e32 v45, v7, v7
	v_mul_f32_e32 v45, 0xbf38aa3b, v45
	v_exp_f32_e32 v45, v45
	v_fmamk_f32 v39, v38, 0x3f07dc22, v236
	v_fmaak_f32 v39, v38, v39, 0x3f35f0e3
	v_fmaak_f32 v39, v38, v39, 0xbe11a98e
	v_fmaak_f32 v39, v38, v39, 0x3e027906
	v_mul_f32_e32 v38, v38, v39
	v_mul_f32_e32 v38, v45, v38
	v_mul_f32_e32 v39, v38, v7
	v_fma_f32 v38, -v38, v7, v7
	v_cmp_gt_f32_e32 vcc, 0, v7
	s_waitcnt vmcnt(4)
	v_lshlrev_b32_e32 v7, 16, v40
	v_mul_f32_e32 v40, v7, v7
	v_cndmask_b32_e32 v156, v38, v39, vcc
	v_fma_f32 v38, |v7|, s92, 1.0
	v_rcp_f32_e32 v38, v38
	v_mul_f32_e32 v40, 0xbf38aa3b, v40
	v_exp_f32_e32 v40, v40
	v_cmp_gt_f32_e32 vcc, 0, v7
	v_fmamk_f32 v39, v38, 0x3f07dc22, v236
	v_fmaak_f32 v39, v38, v39, 0x3f35f0e3
	v_fmaak_f32 v39, v38, v39, 0xbe11a98e
	v_fmaak_f32 v39, v38, v39, 0x3e027906
	v_mul_f32_e32 v38, v38, v39
	v_mul_f32_e32 v38, v40, v38
	v_mul_f32_e32 v39, v38, v7
	v_fma_f32 v38, -v38, v7, v7
	s_waitcnt vmcnt(3)
	v_lshlrev_b32_e32 v7, 16, v41
	v_cndmask_b32_e32 v157, v38, v39, vcc
	v_fma_f32 v38, |v7|, s92, 1.0
	v_rcp_f32_e32 v38, v38
	v_mul_f32_e32 v40, v7, v7
	v_mul_f32_e32 v40, 0xbf38aa3b, v40
	v_exp_f32_e32 v40, v40
	v_fmamk_f32 v39, v38, 0x3f07dc22, v236
	v_fmaak_f32 v39, v38, v39, 0x3f35f0e3
	v_fmaak_f32 v39, v38, v39, 0xbe11a98e
	v_fmaak_f32 v39, v38, v39, 0x3e027906
	v_mul_f32_e32 v38, v38, v39
	v_mul_f32_e32 v38, v40, v38
	v_mul_f32_e32 v39, v38, v7
	v_fma_f32 v38, -v38, v7, v7
	v_cmp_gt_f32_e32 vcc, 0, v7
	s_waitcnt vmcnt(2)
	v_lshlrev_b32_e32 v7, 16, v42
	v_mul_f32_e32 v40, v7, v7
	v_cndmask_b32_e32 v158, v38, v39, vcc
	v_fma_f32 v38, |v7|, s92, 1.0
	v_rcp_f32_e32 v38, v38
	v_mul_f32_e32 v40, 0xbf38aa3b, v40
	v_exp_f32_e32 v40, v40
	v_cmp_gt_f32_e32 vcc, 0, v7
	v_fmamk_f32 v39, v38, 0x3f07dc22, v236
	v_fmaak_f32 v39, v38, v39, 0x3f35f0e3
	v_fmaak_f32 v39, v38, v39, 0xbe11a98e
	v_fmaak_f32 v39, v38, v39, 0x3e027906
	v_mul_f32_e32 v38, v38, v39
	v_mul_f32_e32 v38, v40, v38
	v_mul_f32_e32 v39, v38, v7
	v_fma_f32 v38, -v38, v7, v7
	s_waitcnt vmcnt(1)
	v_lshlrev_b32_e32 v7, 16, v43
	v_cndmask_b32_e32 v159, v38, v39, vcc
	v_fma_f32 v38, |v7|, s92, 1.0
	v_rcp_f32_e32 v38, v38
	v_mul_f32_e32 v40, v7, v7
	v_mul_f32_e32 v40, 0xbf38aa3b, v40
	v_exp_f32_e32 v40, v40
	v_fmamk_f32 v39, v38, 0x3f07dc22, v236
	v_fmaak_f32 v39, v38, v39, 0x3f35f0e3
	v_fmaak_f32 v39, v38, v39, 0xbe11a98e
	v_fmaak_f32 v39, v38, v39, 0x3e027906
	v_mul_f32_e32 v38, v38, v39
	v_mul_f32_e32 v38, v40, v38
	v_mul_f32_e32 v39, v38, v7
	v_fma_f32 v38, -v38, v7, v7
	v_cmp_gt_f32_e32 vcc, 0, v7
	s_waitcnt vmcnt(0)
	v_lshlrev_b32_e32 v7, 16, v44
	v_mul_f32_e32 v40, v7, v7
	v_cndmask_b32_e32 v160, v38, v39, vcc
	v_fma_f32 v38, |v7|, s92, 1.0
	v_rcp_f32_e32 v38, v38
	v_mul_f32_e32 v40, 0xbf38aa3b, v40
	v_exp_f32_e32 v40, v40
	v_cmp_gt_f32_e32 vcc, 0, v7
	v_fmamk_f32 v39, v38, 0x3f07dc22, v236
	v_fmaak_f32 v39, v38, v39, 0x3f35f0e3
	v_fmaak_f32 v39, v38, v39, 0xbe11a98e
	v_fmaak_f32 v39, v38, v39, 0x3e027906
	v_mul_f32_e32 v38, v38, v39
	v_mul_f32_e32 v38, v40, v38
	v_mul_f32_e32 v39, v38, v7
	v_fma_f32 v38, -v38, v7, v7
	global_load_ushort v7, v[12:13], off offset:2048
	s_nop 0
	global_load_ushort v12, v[14:15], off
	global_load_ushort v13, v[16:17], off offset:2048
	s_nop 0
	global_load_ushort v14, v[34:35], off
	global_load_ushort v15, v[36:37], off offset:2048
	v_cndmask_b32_e32 v161, v38, v39, vcc
	s_waitcnt vmcnt(4)
	v_lshlrev_b32_e32 v7, 16, v7
	v_fma_f32 v16, |v7|, s92, 1.0
	v_rcp_f32_e32 v16, v16
	v_mul_f32_e32 v34, v7, v7
	v_mul_f32_e32 v34, 0xbf38aa3b, v34
	v_exp_f32_e32 v34, v34
	v_fmamk_f32 v17, v16, 0x3f07dc22, v236
	v_fmaak_f32 v17, v16, v17, 0x3f35f0e3
	v_fmaak_f32 v17, v16, v17, 0xbe11a98e
	v_fmaak_f32 v17, v16, v17, 0x3e027906
	v_mul_f32_e32 v16, v16, v17
	v_mul_f32_e32 v16, v34, v16
	v_mul_f32_e32 v17, v16, v7
	v_fma_f32 v16, -v16, v7, v7
	v_cmp_gt_f32_e32 vcc, 0, v7
	s_waitcnt vmcnt(3)
	v_lshlrev_b32_e32 v7, 16, v12
	v_fma_f32 v12, |v7|, s92, 1.0
	v_rcp_f32_e32 v12, v12
	v_cndmask_b32_e32 v162, v16, v17, vcc
	v_mul_f32_e32 v17, v7, v7
	v_mul_f32_e32 v17, 0xbf38aa3b, v17
	v_fmamk_f32 v16, v12, 0x3f07dc22, v236
	v_fmaak_f32 v16, v12, v16, 0x3f35f0e3
	v_exp_f32_e32 v17, v17
	v_fmaak_f32 v16, v12, v16, 0xbe11a98e
	v_fmaak_f32 v16, v12, v16, 0x3e027906
	v_mul_f32_e32 v12, v12, v16
	v_mul_f32_e32 v12, v17, v12
	v_mul_f32_e32 v16, v12, v7
	v_fma_f32 v12, -v12, v7, v7
	v_cmp_gt_f32_e32 vcc, 0, v7
	s_waitcnt vmcnt(2)
	v_lshlrev_b32_e32 v7, 16, v13
	v_cndmask_b32_e32 v163, v12, v16, vcc
	v_fma_f32 v12, |v7|, s92, 1.0
	v_rcp_f32_e32 v12, v12
	v_mul_f32_e32 v16, v7, v7
	v_mul_f32_e32 v16, 0xbf38aa3b, v16
	v_exp_f32_e32 v16, v16
	v_fmamk_f32 v13, v12, 0x3f07dc22, v236
	v_fmaak_f32 v13, v12, v13, 0x3f35f0e3
	v_fmaak_f32 v13, v12, v13, 0xbe11a98e
	v_fmaak_f32 v13, v12, v13, 0x3e027906
	v_mul_f32_e32 v12, v12, v13
	v_mul_f32_e32 v12, v16, v12
	v_mul_f32_e32 v13, v12, v7
	v_fma_f32 v12, -v12, v7, v7
	v_cmp_gt_f32_e32 vcc, 0, v7
	s_waitcnt vmcnt(1)
	v_lshlrev_b32_e32 v7, 16, v14
	v_mul_f32_e32 v14, v7, v7
	v_cndmask_b32_e32 v164, v12, v13, vcc
	v_fma_f32 v12, |v7|, s92, 1.0
	v_rcp_f32_e32 v12, v12
	v_mul_f32_e32 v14, 0xbf38aa3b, v14
	v_exp_f32_e32 v14, v14
	v_cmp_gt_f32_e32 vcc, 0, v7
	v_fmamk_f32 v13, v12, 0x3f07dc22, v236
	v_fmaak_f32 v13, v12, v13, 0x3f35f0e3
	v_fmaak_f32 v13, v12, v13, 0xbe11a98e
	v_fmaak_f32 v13, v12, v13, 0x3e027906
	v_mul_f32_e32 v12, v12, v13
	v_mul_f32_e32 v12, v14, v12
	v_mul_f32_e32 v13, v12, v7
	v_fma_f32 v12, -v12, v7, v7
	s_waitcnt vmcnt(0)
	v_lshlrev_b32_e32 v7, 16, v15
	v_cndmask_b32_e32 v165, v12, v13, vcc
	v_fma_f32 v12, |v7|, s92, 1.0
	v_rcp_f32_e32 v12, v12
	v_mul_f32_e32 v14, v7, v7
	v_mul_f32_e32 v14, 0xbf38aa3b, v14
	v_exp_f32_e32 v14, v14
	v_fmamk_f32 v13, v12, 0x3f07dc22, v236
	v_fmaak_f32 v13, v12, v13, 0x3f35f0e3
	v_fmaak_f32 v13, v12, v13, 0xbe11a98e
	v_fmaak_f32 v13, v12, v13, 0x3e027906
	v_mul_f32_e32 v12, v12, v13
	v_mul_f32_e32 v12, v14, v12
	v_mul_f32_e32 v13, v12, v7
	v_fma_f32 v12, -v12, v7, v7
	v_cmp_gt_f32_e32 vcc, 0, v7
	v_lshlrev_b32_e32 v7, 4, v73
	v_add3_u32 v34, 0, v6, v7
	v_cndmask_b32_e32 v166, v12, v13, vcc
	v_add_co_u32_e32 v88, vcc, s41, v8
	ds_read_b128 v[62:65], v34
	ds_read_b128 v[58:61], v34 offset:32
	ds_read_b128 v[54:57], v34 offset:64
	ds_read_b128 v[50:53], v34 offset:96
	v_addc_co_u32_e32 v89, vcc, 0, v9, vcc
	v_add_co_u32_e32 v86, vcc, s97, v8
	v_add_u32_e32 v150, s5, v7
	s_nop 0
	v_addc_co_u32_e32 v87, vcc, 0, v9, vcc
	v_add_co_u32_e32 v116, vcc, s6, v10
	s_mov_b32 s6, 0x6091000
	s_nop 0
	v_addc_co_u32_e32 v117, vcc, 0, v11, vcc
	v_add_co_u32_e32 v118, vcc, s6, v10
	s_mov_b32 s6, 0x6093000
	s_nop 0
	v_addc_co_u32_e32 v119, vcc, 0, v11, vcc
	v_add_co_u32_e32 v120, vcc, s6, v10
	s_mov_b32 s6, 0x6094000
	s_nop 0
	v_addc_co_u32_e32 v121, vcc, 0, v11, vcc
	v_add_co_u32_e32 v100, vcc, s6, v10
	s_mov_b32 s6, 0x609c000
	s_nop 0
	v_addc_co_u32_e32 v101, vcc, 0, v11, vcc
	v_add_co_u32_e32 v102, vcc, s6, v10
	s_mov_b32 s6, 0x609d000
	s_nop 0
	v_addc_co_u32_e32 v103, vcc, 0, v11, vcc
	v_add_co_u32_e32 v104, vcc, s6, v10
	s_mov_b32 s6, 0x609f000
	s_nop 0
	v_addc_co_u32_e32 v105, vcc, 0, v11, vcc
	v_add_co_u32_e32 v106, vcc, s6, v10
	s_mov_b32 s6, 0x60a0000
	s_nop 0
	v_addc_co_u32_e32 v107, vcc, 0, v11, vcc
	v_add_co_u32_e32 v108, vcc, s6, v10
	s_mov_b32 s6, 0x60a8000
	s_nop 0
	v_addc_co_u32_e32 v109, vcc, 0, v11, vcc
	v_add_co_u32_e32 v110, vcc, s6, v10
	s_mov_b32 s6, 0x60a9000
	s_nop 0
	v_addc_co_u32_e32 v111, vcc, 0, v11, vcc
	v_add_co_u32_e32 v112, vcc, s6, v10
	s_mov_b32 s6, 0x60ab000
	s_nop 0
	v_addc_co_u32_e32 v113, vcc, 0, v11, vcc
	v_add_co_u32_e32 v114, vcc, s6, v10
	s_mov_b32 s6, 0x60ac000
	s_nop 0
	v_addc_co_u32_e32 v115, vcc, 0, v11, vcc
	v_add_co_u32_e32 v90, vcc, s6, v10
	s_mov_b32 s6, 0x60b4000
	s_nop 0
	v_addc_co_u32_e32 v91, vcc, 0, v11, vcc
	v_add_co_u32_e32 v92, vcc, s6, v10
	s_mov_b32 s6, 0x60b5000
	s_nop 0
	v_addc_co_u32_e32 v93, vcc, 0, v11, vcc
	v_add_co_u32_e32 v94, vcc, s6, v10
	s_mov_b32 s6, 0x60b7000
	s_nop 0
	v_addc_co_u32_e32 v95, vcc, 0, v11, vcc
	v_add_co_u32_e32 v96, vcc, s6, v10
	s_mov_b32 s6, 0x60b8000
	s_nop 0
	v_addc_co_u32_e32 v97, vcc, 0, v11, vcc
	v_add_co_u32_e32 v98, vcc, s6, v10
	ds_read_b128 v[46:49], v34 offset:128
	ds_read_b128 v[42:45], v34 offset:160
	ds_read_b128 v[38:41], v34 offset:192
	ds_read_b128 v[34:37], v34 offset:224
	v_addc_co_u32_e32 v99, vcc, 0, v11, vcc
	s_waitcnt lgkmcnt(7)
	v_mfma_f32_32x32x16_bf16 v[2:17], v[2:5], v[62:65], 0
	global_load_dwordx4 v[66:69], v[82:83], off offset:-4096
	ds_read_b128 v[182:185], v150
	v_mov_b32_e32 v73, v131
	v_lshlrev_b64 v[72:73], 11, v[72:73]
	v_lshl_add_u64 v[72:73], v[84:85], 0, v[72:73]
	v_readlane_b32 s5, v252, 31
	s_waitcnt lgkmcnt(7)
	v_mfma_f32_32x32x16_bf16 v[2:17], v[30:33], v[58:61], v[2:17]
	ds_read_b128 v[30:33], v150 offset:32
	s_waitcnt lgkmcnt(1)
	s_nop 9
	v_add_f32_e32 v2, v2, v182
	v_mul_f32_e32 v2, v130, v2
	v_cvt_pk_bf16_f32 v2, v2, s0
	global_store_short v[72:73], v2, off
	v_add_f32_e32 v2, v3, v183
	v_mul_f32_e32 v2, v167, v2
	v_cvt_pk_bf16_f32 v72, v2, s0
	v_or_b32_e32 v2, s5, v1
	v_lshlrev_b32_e32 v130, 11, v2
	v_lshl_add_u64 v[2:3], v[84:85], 0, v[130:131]
	global_store_short v[2:3], v72, off
	v_add_f32_e32 v2, v4, v184
	v_mul_f32_e32 v2, v168, v2
	v_readlane_b32 s5, v252, 32
	v_cvt_pk_bf16_f32 v4, v2, s0
	s_nop 0
	v_or_b32_e32 v2, s5, v1
	v_lshlrev_b32_e32 v130, 11, v2
	v_lshl_add_u64 v[2:3], v[84:85], 0, v[130:131]
	global_store_short v[2:3], v4, off
	v_add_f32_e32 v2, v5, v185
	v_mul_f32_e32 v2, v169, v2
	v_readlane_b32 s5, v252, 33
	v_cvt_pk_bf16_f32 v4, v2, s0
	s_nop 0
	v_or_b32_e32 v2, s5, v1
	v_lshlrev_b32_e32 v130, 11, v2
	v_lshl_add_u64 v[2:3], v[84:85], 0, v[130:131]
	global_store_short v[2:3], v4, off
	s_waitcnt lgkmcnt(0)
	v_add_f32_e32 v2, v6, v30
	v_mul_f32_e32 v2, v170, v2
	v_readlane_b32 s5, v252, 34
	v_cvt_pk_bf16_f32 v4, v2, s0
	s_nop 0
	v_or_b32_e32 v2, s5, v1
	v_lshlrev_b32_e32 v130, 11, v2
	v_lshl_add_u64 v[2:3], v[84:85], 0, v[130:131]
	global_store_short v[2:3], v4, off
	v_add_f32_e32 v2, v7, v31
	v_mul_f32_e32 v2, v171, v2
	v_readlane_b32 s5, v252, 35
	v_cvt_pk_bf16_f32 v4, v2, s0
	s_nop 0
	v_or_b32_e32 v2, s5, v1
	v_lshlrev_b32_e32 v130, 11, v2
	v_lshl_add_u64 v[2:3], v[84:85], 0, v[130:131]
	global_store_short v[2:3], v4, off
	v_add_f32_e32 v2, v8, v32
	v_mul_f32_e32 v2, v172, v2
	v_readlane_b32 s5, v252, 36
	v_cvt_pk_bf16_f32 v4, v2, s0
	s_nop 0
	v_or_b32_e32 v2, s5, v1
	v_lshlrev_b32_e32 v130, 11, v2
	v_lshl_add_u64 v[2:3], v[84:85], 0, v[130:131]
	global_store_short v[2:3], v4, off
	v_add_f32_e32 v2, v9, v33
	v_mul_f32_e32 v2, v173, v2
	v_cvt_pk_bf16_f32 v8, v2, s0
	ds_read_b128 v[2:5], v150 offset:64
	v_readlane_b32 s5, v252, 37
	s_nop 1
	v_or_b32_e32 v6, s5, v1
	v_lshlrev_b32_e32 v130, 11, v6
	v_lshl_add_u64 v[6:7], v[84:85], 0, v[130:131]
	v_readlane_b32 s5, v252, 38
	global_store_short v[6:7], v8, off
	ds_read_b128 v[6:9], v150 offset:96
	s_waitcnt lgkmcnt(1)
	v_add_f32_e32 v2, v10, v2
	v_or_b32_e32 v10, s5, v1
	v_mul_f32_e32 v2, v174, v2
	v_lshlrev_b32_e32 v130, 11, v10
	v_cvt_pk_bf16_f32 v2, v2, s0
	v_lshl_add_u64 v[30:31], v[84:85], 0, v[130:131]
	global_store_short v[30:31], v2, off
	v_add_f32_e32 v2, v11, v3
	v_mul_f32_e32 v2, v175, v2
	v_readlane_b32 s5, v252, 39
	v_cvt_pk_bf16_f32 v10, v2, s0
	s_nop 0
	v_or_b32_e32 v2, s5, v1
	v_lshlrev_b32_e32 v130, 11, v2
	v_lshl_add_u64 v[2:3], v[84:85], 0, v[130:131]
	global_store_short v[2:3], v10, off
	v_add_f32_e32 v2, v12, v4
	v_mul_f32_e32 v2, v176, v2
	v_readlane_b32 s5, v252, 40
	v_cvt_pk_bf16_f32 v4, v2, s0
	s_nop 0
	v_or_b32_e32 v2, s5, v1
	v_lshlrev_b32_e32 v130, 11, v2
	v_lshl_add_u64 v[2:3], v[84:85], 0, v[130:131]
	global_store_short v[2:3], v4, off
	v_add_f32_e32 v2, v13, v5
	v_mul_f32_e32 v2, v177, v2
	v_readlane_b32 s5, v252, 41
	v_cvt_pk_bf16_f32 v4, v2, s0
	s_nop 0
	v_or_b32_e32 v2, s5, v1
	v_lshlrev_b32_e32 v130, 11, v2
	v_lshl_add_u64 v[2:3], v[84:85], 0, v[130:131]
	global_store_short v[2:3], v4, off
	s_waitcnt lgkmcnt(0)
	v_add_f32_e32 v2, v14, v6
	v_mul_f32_e32 v2, v178, v2
	v_readlane_b32 s5, v252, 42
	v_cvt_pk_bf16_f32 v4, v2, s0
	s_nop 0
	v_or_b32_e32 v2, s5, v1
	v_lshlrev_b32_e32 v130, 11, v2
	v_lshl_add_u64 v[2:3], v[84:85], 0, v[130:131]
	global_store_short v[2:3], v4, off
	v_add_f32_e32 v2, v15, v7
	v_mul_f32_e32 v2, v179, v2
	v_readlane_b32 s5, v252, 43
	v_cvt_pk_bf16_f32 v4, v2, s0
	s_nop 0
	v_or_b32_e32 v2, s5, v1
	v_lshlrev_b32_e32 v130, 11, v2
	v_lshl_add_u64 v[2:3], v[84:85], 0, v[130:131]
	global_store_short v[2:3], v4, off
	v_add_f32_e32 v2, v16, v8
	v_mul_f32_e32 v2, v180, v2
	v_readlane_b32 s5, v252, 44
	v_cvt_pk_bf16_f32 v4, v2, s0
	s_nop 0
	v_or_b32_e32 v2, s5, v1
	v_lshlrev_b32_e32 v130, 11, v2
	v_lshl_add_u64 v[2:3], v[84:85], 0, v[130:131]
	global_store_short v[2:3], v4, off
	v_add_f32_e32 v2, v17, v9
	v_mul_f32_e32 v2, v181, v2
	v_readlane_b32 s5, v252, 45
	v_cvt_pk_bf16_f32 v4, v2, s0
	s_nop 0
	v_or_b32_e32 v2, s5, v1
	v_lshlrev_b32_e32 v130, 11, v2
	v_lshl_add_u64 v[2:3], v[84:85], 0, v[130:131]
	global_store_short v[2:3], v4, off
	global_load_ushort v2, v[134:135], off
	global_load_ushort v3, v[136:137], off offset:2048
	global_load_ushort v4, v[138:139], off
	global_load_ushort v5, v[140:141], off offset:2048
	global_load_ushort v6, v[142:143], off
	global_load_ushort v7, v[144:145], off offset:2048
	global_load_ushort v8, v[146:147], off
	global_load_ushort v9, v[148:149], off offset:2048
	v_readlane_b32 s5, v252, 46
	s_waitcnt vmcnt(7)
	v_lshlrev_b32_e32 v2, 16, v2
	v_fma_f32 v10, |v2|, s92, 1.0
	v_rcp_f32_e32 v10, v10
	v_mul_f32_e32 v12, v2, v2
	v_mul_f32_e32 v12, 0xbf38aa3b, v12
	v_exp_f32_e32 v12, v12
	v_fmamk_f32 v11, v10, 0x3f07dc22, v236
	v_fmaak_f32 v11, v10, v11, 0x3f35f0e3
	v_fmaak_f32 v11, v10, v11, 0xbe11a98e
	v_fmaak_f32 v11, v10, v11, 0x3e027906
	v_mul_f32_e32 v10, v10, v11
	v_mul_f32_e32 v10, v12, v10
	v_mul_f32_e32 v11, v10, v2
	v_fma_f32 v10, -v10, v2, v2
	v_cmp_gt_f32_e32 vcc, 0, v2
	s_waitcnt vmcnt(6)
	v_lshlrev_b32_e32 v2, 16, v3
	v_fma_f32 v3, |v2|, s92, 1.0
	v_rcp_f32_e32 v3, v3
	v_cndmask_b32_e32 v134, v10, v11, vcc
	v_mul_f32_e32 v11, v2, v2
	v_mul_f32_e32 v11, 0xbf38aa3b, v11
	v_fmamk_f32 v10, v3, 0x3f07dc22, v236
	v_fmaak_f32 v10, v3, v10, 0x3f35f0e3
	v_exp_f32_e32 v11, v11
	v_fmaak_f32 v10, v3, v10, 0xbe11a98e
	v_fmaak_f32 v10, v3, v10, 0x3e027906
	v_mul_f32_e32 v3, v3, v10
	v_mul_f32_e32 v3, v11, v3
	v_mul_f32_e32 v10, v3, v2
	v_fma_f32 v3, -v3, v2, v2
	v_cmp_gt_f32_e32 vcc, 0, v2
	s_waitcnt vmcnt(5)
	v_lshlrev_b32_e32 v2, 16, v4
	v_cndmask_b32_e32 v135, v3, v10, vcc
	v_fma_f32 v3, |v2|, s92, 1.0
	v_rcp_f32_e32 v3, v3
	v_mul_f32_e32 v10, v2, v2
	v_mul_f32_e32 v10, 0xbf38aa3b, v10
	v_exp_f32_e32 v10, v10
	v_fmamk_f32 v4, v3, 0x3f07dc22, v236
	v_fmaak_f32 v4, v3, v4, 0x3f35f0e3
	v_fmaak_f32 v4, v3, v4, 0xbe11a98e
	v_fmaak_f32 v4, v3, v4, 0x3e027906
	v_mul_f32_e32 v3, v3, v4
	v_mul_f32_e32 v3, v10, v3
	v_mul_f32_e32 v4, v3, v2
	v_fma_f32 v3, -v3, v2, v2
	v_cmp_gt_f32_e32 vcc, 0, v2
	s_waitcnt vmcnt(4)
	v_lshlrev_b32_e32 v2, 16, v5
	v_mul_f32_e32 v5, v2, v2
	v_cndmask_b32_e32 v136, v3, v4, vcc
	v_fma_f32 v3, |v2|, s92, 1.0
	v_rcp_f32_e32 v3, v3
	v_mul_f32_e32 v5, 0xbf38aa3b, v5
	v_exp_f32_e32 v5, v5
	v_cmp_gt_f32_e32 vcc, 0, v2
	v_fmamk_f32 v4, v3, 0x3f07dc22, v236
	v_fmaak_f32 v4, v3, v4, 0x3f35f0e3
	v_fmaak_f32 v4, v3, v4, 0xbe11a98e
	v_fmaak_f32 v4, v3, v4, 0x3e027906
	v_mul_f32_e32 v3, v3, v4
	v_mul_f32_e32 v3, v5, v3
	v_mul_f32_e32 v4, v3, v2
	v_fma_f32 v3, -v3, v2, v2
	s_waitcnt vmcnt(3)
	v_lshlrev_b32_e32 v2, 16, v6
	v_cndmask_b32_e32 v137, v3, v4, vcc
	v_fma_f32 v3, |v2|, s92, 1.0
	v_rcp_f32_e32 v3, v3
	v_mul_f32_e32 v5, v2, v2
	v_mul_f32_e32 v5, 0xbf38aa3b, v5
	v_exp_f32_e32 v5, v5
	v_fmamk_f32 v4, v3, 0x3f07dc22, v236
	v_fmaak_f32 v4, v3, v4, 0x3f35f0e3
	v_fmaak_f32 v4, v3, v4, 0xbe11a98e
	v_fmaak_f32 v4, v3, v4, 0x3e027906
	v_mul_f32_e32 v3, v3, v4
	v_mul_f32_e32 v3, v5, v3
	v_mul_f32_e32 v4, v3, v2
	v_fma_f32 v3, -v3, v2, v2
	v_cmp_gt_f32_e32 vcc, 0, v2
	s_waitcnt vmcnt(2)
	v_lshlrev_b32_e32 v2, 16, v7
	v_mul_f32_e32 v5, v2, v2
	v_cndmask_b32_e32 v138, v3, v4, vcc
	v_fma_f32 v3, |v2|, s92, 1.0
	v_rcp_f32_e32 v3, v3
	v_mul_f32_e32 v5, 0xbf38aa3b, v5
	v_exp_f32_e32 v5, v5
	v_cmp_gt_f32_e32 vcc, 0, v2
	v_fmamk_f32 v4, v3, 0x3f07dc22, v236
	v_fmaak_f32 v4, v3, v4, 0x3f35f0e3
	v_fmaak_f32 v4, v3, v4, 0xbe11a98e
	v_fmaak_f32 v4, v3, v4, 0x3e027906
	v_mul_f32_e32 v3, v3, v4
	v_mul_f32_e32 v3, v5, v3
	v_mul_f32_e32 v4, v3, v2
	v_fma_f32 v3, -v3, v2, v2
	s_waitcnt vmcnt(1)
	v_lshlrev_b32_e32 v2, 16, v8
	v_cndmask_b32_e32 v139, v3, v4, vcc
	v_fma_f32 v3, |v2|, s92, 1.0
	v_rcp_f32_e32 v3, v3
	v_mul_f32_e32 v5, v2, v2
	v_mul_f32_e32 v5, 0xbf38aa3b, v5
	v_exp_f32_e32 v5, v5
	v_fmamk_f32 v4, v3, 0x3f07dc22, v236
	v_fmaak_f32 v4, v3, v4, 0x3f35f0e3
	v_fmaak_f32 v4, v3, v4, 0xbe11a98e
	v_fmaak_f32 v4, v3, v4, 0x3e027906
	v_mul_f32_e32 v3, v3, v4
	v_mul_f32_e32 v3, v5, v3
	v_mul_f32_e32 v4, v3, v2
	v_fma_f32 v3, -v3, v2, v2
	v_cmp_gt_f32_e32 vcc, 0, v2
	s_waitcnt vmcnt(0)
	v_lshlrev_b32_e32 v2, 16, v9
	v_mul_f32_e32 v5, v2, v2
	v_cndmask_b32_e32 v140, v3, v4, vcc
	v_fma_f32 v3, |v2|, s92, 1.0
	v_rcp_f32_e32 v3, v3
	v_mul_f32_e32 v5, 0xbf38aa3b, v5
	v_exp_f32_e32 v5, v5
	v_cmp_gt_f32_e32 vcc, 0, v2
	v_fmamk_f32 v4, v3, 0x3f07dc22, v236
	v_fmaak_f32 v4, v3, v4, 0x3f35f0e3
	v_fmaak_f32 v4, v3, v4, 0xbe11a98e
	v_fmaak_f32 v4, v3, v4, 0x3e027906
	v_mul_f32_e32 v3, v3, v4
	v_mul_f32_e32 v3, v5, v3
	v_mul_f32_e32 v4, v3, v2
	v_fma_f32 v3, -v3, v2, v2
	v_cndmask_b32_e32 v141, v3, v4, vcc
	global_load_ushort v2, v[76:77], off
	global_load_ushort v3, v[78:79], off offset:2048
	global_load_ushort v4, v[80:81], off
	global_load_ushort v5, v[122:123], off offset:2048
	global_load_ushort v6, v[124:125], off
	global_load_ushort v7, v[126:127], off offset:2048
	global_load_ushort v8, v[128:129], off
	global_load_ushort v30, v[132:133], off offset:2048
	s_waitcnt vmcnt(7)
	v_lshlrev_b32_e32 v2, 16, v2
	v_fma_f32 v9, |v2|, s92, 1.0
	v_rcp_f32_e32 v9, v9
	v_mul_f32_e32 v11, v2, v2
	v_mul_f32_e32 v11, 0xbf38aa3b, v11
	v_exp_f32_e32 v11, v11
	v_fmamk_f32 v10, v9, 0x3f07dc22, v236
	v_fmaak_f32 v10, v9, v10, 0x3f35f0e3
	v_fmaak_f32 v10, v9, v10, 0xbe11a98e
	v_fmaak_f32 v10, v9, v10, 0x3e027906
	v_mul_f32_e32 v9, v9, v10
	v_mul_f32_e32 v9, v11, v9
	v_mul_f32_e32 v10, v9, v2
	v_fma_f32 v9, -v9, v2, v2
	v_cmp_gt_f32_e32 vcc, 0, v2
	s_waitcnt vmcnt(6)
	v_lshlrev_b32_e32 v2, 16, v3
	v_fma_f32 v3, |v2|, s92, 1.0
	v_rcp_f32_e32 v3, v3
	v_cndmask_b32_e32 v122, v9, v10, vcc
	v_mul_f32_e32 v10, v2, v2
	v_mul_f32_e32 v10, 0xbf38aa3b, v10
	v_fmamk_f32 v9, v3, 0x3f07dc22, v236
	v_fmaak_f32 v9, v3, v9, 0x3f35f0e3
	v_exp_f32_e32 v10, v10
	v_fmaak_f32 v9, v3, v9, 0xbe11a98e
	v_fmaak_f32 v9, v3, v9, 0x3e027906
	v_mul_f32_e32 v3, v3, v9
	v_mul_f32_e32 v3, v10, v3
	v_mul_f32_e32 v9, v3, v2
	v_fma_f32 v3, -v3, v2, v2
	v_cmp_gt_f32_e32 vcc, 0, v2
	s_waitcnt vmcnt(5)
	v_lshlrev_b32_e32 v2, 16, v4
	s_waitcnt vmcnt(1)
	v_lshlrev_b32_e32 v31, 16, v8
	v_cndmask_b32_e32 v123, v3, v9, vcc
	v_fma_f32 v3, |v2|, s92, 1.0
	v_rcp_f32_e32 v3, v3
	v_mul_f32_e32 v9, v2, v2
	v_mul_f32_e32 v9, 0xbf38aa3b, v9
	v_exp_f32_e32 v9, v9
	v_fmamk_f32 v4, v3, 0x3f07dc22, v236
	v_fmaak_f32 v4, v3, v4, 0x3f35f0e3
	v_fmaak_f32 v4, v3, v4, 0xbe11a98e
	v_fmaak_f32 v4, v3, v4, 0x3e027906
	v_mul_f32_e32 v3, v3, v4
	v_mul_f32_e32 v3, v9, v3
	v_mul_f32_e32 v4, v3, v2
	v_fma_f32 v3, -v3, v2, v2
	v_cmp_gt_f32_e32 vcc, 0, v2
	v_lshlrev_b32_e32 v2, 16, v5
	v_mul_f32_e32 v5, v2, v2
	v_cndmask_b32_e32 v124, v3, v4, vcc
	v_fma_f32 v3, |v2|, s92, 1.0
	v_rcp_f32_e32 v3, v3
	v_mul_f32_e32 v5, 0xbf38aa3b, v5
	v_exp_f32_e32 v5, v5
	v_cmp_gt_f32_e32 vcc, 0, v2
	v_fmamk_f32 v4, v3, 0x3f07dc22, v236
	v_fmaak_f32 v4, v3, v4, 0x3f35f0e3
	v_fmaak_f32 v4, v3, v4, 0xbe11a98e
	v_fmaak_f32 v4, v3, v4, 0x3e027906
	v_mul_f32_e32 v3, v3, v4
	v_mul_f32_e32 v3, v5, v3
	v_mul_f32_e32 v4, v3, v2
	v_fma_f32 v3, -v3, v2, v2
	v_lshlrev_b32_e32 v2, 16, v6
	v_cndmask_b32_e32 v125, v3, v4, vcc
	v_fma_f32 v3, |v2|, s92, 1.0
	v_rcp_f32_e32 v3, v3
	v_mul_f32_e32 v5, v2, v2
	v_mul_f32_e32 v5, 0xbf38aa3b, v5
	v_exp_f32_e32 v5, v5
	v_fmamk_f32 v4, v3, 0x3f07dc22, v236
	v_fmaak_f32 v4, v3, v4, 0x3f35f0e3
	v_fmaak_f32 v4, v3, v4, 0xbe11a98e
	v_fmaak_f32 v4, v3, v4, 0x3e027906
	v_mul_f32_e32 v3, v3, v4
	v_mul_f32_e32 v3, v5, v3
	v_mul_f32_e32 v4, v3, v2
	v_fma_f32 v3, -v3, v2, v2
	v_cmp_gt_f32_e32 vcc, 0, v2
	v_lshlrev_b32_e32 v2, 16, v7
	v_mul_f32_e32 v5, v2, v2
	v_cndmask_b32_e32 v126, v3, v4, vcc
	v_fma_f32 v3, |v2|, s92, 1.0
	v_rcp_f32_e32 v3, v3
	v_mul_f32_e32 v5, 0xbf38aa3b, v5
	v_exp_f32_e32 v5, v5
	v_cmp_gt_f32_e32 vcc, 0, v2
	v_fmamk_f32 v4, v3, 0x3f07dc22, v236
	v_fmaak_f32 v4, v3, v4, 0x3f35f0e3
	v_fmaak_f32 v4, v3, v4, 0xbe11a98e
	v_fmaak_f32 v4, v3, v4, 0x3e027906
	v_mul_f32_e32 v3, v3, v4
	v_mul_f32_e32 v3, v5, v3
	v_mul_f32_e32 v4, v3, v2
	v_fma_f32 v3, -v3, v2, v2
	v_fma_f32 v2, |v31|, s92, 1.0
	v_cndmask_b32_e32 v127, v3, v4, vcc
	v_rcp_f32_e32 v32, v2
	v_mfma_f32_32x32x16_bf16 v[2:17], v[22:25], v[62:65], 0
	v_mul_f32_e32 v23, v31, v31
	v_mul_f32_e32 v23, 0xbf38aa3b, v23
	v_fmamk_f32 v22, v32, 0x3f07dc22, v236
	v_fmaak_f32 v22, v32, v22, 0x3f35f0e3
	v_exp_f32_e32 v23, v23
	v_fmaak_f32 v22, v32, v22, 0xbe11a98e
	v_fmaak_f32 v22, v32, v22, 0x3e027906
	v_mfma_f32_32x32x16_bf16 v[2:17], v[18:21], v[58:61], v[2:17]
	v_mul_f32_e32 v22, v32, v22
	v_mul_f32_e32 v22, v23, v22
	v_mul_f32_e32 v23, v22, v31
	v_fma_f32 v22, -v22, v31, v31
	v_cmp_gt_f32_e32 vcc, 0, v31
	s_nop 1
	v_cndmask_b32_e32 v128, v22, v23, vcc
	s_waitcnt vmcnt(0)
	v_lshlrev_b32_e32 v22, 16, v30
	v_fma_f32 v23, |v22|, s92, 1.0
	v_rcp_f32_e32 v23, v23
	v_mfma_f32_32x32x16_bf16 v[2:17], v[66:69], v[54:57], v[2:17]
	v_mul_f32_e32 v19, v22, v22
	v_mul_f32_e32 v19, 0xbf38aa3b, v19
	v_fmamk_f32 v18, v23, 0x3f07dc22, v236
	v_fmaak_f32 v18, v23, v18, 0x3f35f0e3
	v_exp_f32_e32 v19, v19
	v_fmaak_f32 v18, v23, v18, 0xbe11a98e
	v_fmaak_f32 v18, v23, v18, 0x3e027906
	v_mul_f32_e32 v18, v23, v18
	v_mul_f32_e32 v18, v19, v18
	v_mfma_f32_32x32x16_bf16 v[2:17], v[26:29], v[50:53], v[2:17]
	v_mul_f32_e32 v19, v18, v22
	v_fma_f32 v18, -v18, v22, v22
	v_cmp_gt_f32_e32 vcc, 0, v22
	s_nop 1
	v_cndmask_b32_e32 v129, v18, v19, vcc
	global_load_dwordx4 v[18:21], v[70:71], off offset:2048
	global_load_dwordx4 v[78:81], v[70:71], off offset:3072
	global_load_dwordx4 v[74:77], v[82:83], off
	s_nop 0
	global_load_dwordx4 v[70:73], v[82:83], off offset:1024
	global_load_dwordx4 v[66:69], v[82:83], off offset:2048
	global_load_dwordx4 v[30:33], v[82:83], off offset:3072
	ds_read_b128 v[22:25], v150 offset:128
	ds_read_b128 v[26:29], v150 offset:160
	s_waitcnt lgkmcnt(1)
	v_add_f32_e32 v2, v2, v22
	v_or_b32_e32 v22, s5, v1
	v_mul_f32_e32 v2, v151, v2
	v_lshlrev_b32_e32 v130, 11, v22
	v_cvt_pk_bf16_f32 v2, v2, s0
	v_lshl_add_u64 v[82:83], v[84:85], 0, v[130:131]
	global_store_short v[82:83], v2, off
	v_add_f32_e32 v2, v3, v23
	v_mul_f32_e32 v2, v152, v2
	v_readlane_b32 s5, v252, 47
	v_cvt_pk_bf16_f32 v22, v2, s0
	s_nop 0
	v_or_b32_e32 v2, s5, v1
	v_lshlrev_b32_e32 v130, 11, v2
	v_lshl_add_u64 v[2:3], v[84:85], 0, v[130:131]
	global_store_short v[2:3], v22, off
	v_add_f32_e32 v2, v4, v24
	v_mul_f32_e32 v2, v153, v2
	v_readlane_b32 s5, v252, 48
	v_cvt_pk_bf16_f32 v4, v2, s0
	s_nop 0
	v_or_b32_e32 v2, s5, v1
	v_lshlrev_b32_e32 v130, 11, v2
	v_lshl_add_u64 v[2:3], v[84:85], 0, v[130:131]
	global_store_short v[2:3], v4, off
	v_add_f32_e32 v2, v5, v25
	v_mul_f32_e32 v2, v154, v2
	v_readlane_b32 s5, v252, 49
	v_cvt_pk_bf16_f32 v4, v2, s0
	s_nop 0
	v_or_b32_e32 v2, s5, v1
	v_lshlrev_b32_e32 v130, 11, v2
	v_lshl_add_u64 v[2:3], v[84:85], 0, v[130:131]
	global_store_short v[2:3], v4, off
	s_waitcnt lgkmcnt(0)
	v_add_f32_e32 v2, v6, v26
	v_mul_f32_e32 v2, v155, v2
	v_readlane_b32 s5, v252, 50
	v_cvt_pk_bf16_f32 v4, v2, s0
	s_nop 0
	v_or_b32_e32 v2, s5, v1
	v_lshlrev_b32_e32 v130, 11, v2
	v_lshl_add_u64 v[2:3], v[84:85], 0, v[130:131]
	global_store_short v[2:3], v4, off
	v_add_f32_e32 v2, v7, v27
	v_mul_f32_e32 v2, v156, v2
	v_readlane_b32 s5, v252, 51
	v_cvt_pk_bf16_f32 v4, v2, s0
	s_nop 0
	v_or_b32_e32 v2, s5, v1
	v_lshlrev_b32_e32 v130, 11, v2
	v_lshl_add_u64 v[2:3], v[84:85], 0, v[130:131]
	global_store_short v[2:3], v4, off
	v_add_f32_e32 v2, v8, v28
	v_mul_f32_e32 v2, v157, v2
	v_readlane_b32 s5, v252, 52
	v_cvt_pk_bf16_f32 v4, v2, s0
	s_nop 0
	v_or_b32_e32 v2, s5, v1
	v_lshlrev_b32_e32 v130, 11, v2
	v_lshl_add_u64 v[2:3], v[84:85], 0, v[130:131]
	global_store_short v[2:3], v4, off
	v_add_f32_e32 v2, v9, v29
	v_mul_f32_e32 v2, v158, v2
	v_cvt_pk_bf16_f32 v8, v2, s0
	ds_read_b128 v[2:5], v150 offset:192
	v_readlane_b32 s5, v252, 53
	s_nop 1
	v_or_b32_e32 v6, s5, v1
	v_lshlrev_b32_e32 v130, 11, v6
	v_lshl_add_u64 v[6:7], v[84:85], 0, v[130:131]
	v_readlane_b32 s5, v252, 54
	global_store_short v[6:7], v8, off
	ds_read_b128 v[6:9], v150 offset:224
	s_waitcnt lgkmcnt(1)
	v_add_f32_e32 v2, v10, v2
	v_or_b32_e32 v10, s5, v1
	v_mul_f32_e32 v2, v159, v2
	v_lshlrev_b32_e32 v130, 11, v10
	v_cvt_pk_bf16_f32 v2, v2, s0
	v_lshl_add_u64 v[22:23], v[84:85], 0, v[130:131]
	global_store_short v[22:23], v2, off
	v_add_f32_e32 v2, v11, v3
	v_mul_f32_e32 v2, v160, v2
	v_readlane_b32 s5, v252, 55
	v_cvt_pk_bf16_f32 v10, v2, s0
	s_nop 0
	v_or_b32_e32 v2, s5, v1
	v_lshlrev_b32_e32 v130, 11, v2
	v_lshl_add_u64 v[2:3], v[84:85], 0, v[130:131]
	global_store_short v[2:3], v10, off
	v_add_f32_e32 v2, v12, v4
	v_mul_f32_e32 v2, v161, v2
	v_readlane_b32 s5, v252, 56
	v_cvt_pk_bf16_f32 v4, v2, s0
	s_nop 0
	v_or_b32_e32 v2, s5, v1
	v_lshlrev_b32_e32 v130, 11, v2
	v_lshl_add_u64 v[2:3], v[84:85], 0, v[130:131]
	global_store_short v[2:3], v4, off
	v_add_f32_e32 v2, v13, v5
	v_mul_f32_e32 v2, v162, v2
	v_readlane_b32 s5, v252, 57
	v_cvt_pk_bf16_f32 v4, v2, s0
	s_nop 0
	v_or_b32_e32 v2, s5, v1
	v_lshlrev_b32_e32 v130, 11, v2
	v_lshl_add_u64 v[2:3], v[84:85], 0, v[130:131]
	global_store_short v[2:3], v4, off
	s_waitcnt lgkmcnt(0)
	v_add_f32_e32 v2, v14, v6
	v_mul_f32_e32 v2, v163, v2
	v_readlane_b32 s5, v252, 58
	v_cvt_pk_bf16_f32 v4, v2, s0
	s_nop 0
	v_or_b32_e32 v2, s5, v1
	v_lshlrev_b32_e32 v130, 11, v2
	v_lshl_add_u64 v[2:3], v[84:85], 0, v[130:131]
	global_store_short v[2:3], v4, off
	v_add_f32_e32 v2, v15, v7
	v_mul_f32_e32 v2, v164, v2
	v_readlane_b32 s5, v252, 59
	v_cvt_pk_bf16_f32 v4, v2, s0
	s_nop 0
	v_or_b32_e32 v2, s5, v1
	v_lshlrev_b32_e32 v130, 11, v2
	v_lshl_add_u64 v[2:3], v[84:85], 0, v[130:131]
	global_store_short v[2:3], v4, off
	v_add_f32_e32 v2, v16, v8
	v_mul_f32_e32 v2, v165, v2
	v_readlane_b32 s5, v252, 60
	v_cvt_pk_bf16_f32 v4, v2, s0
	s_nop 0
	v_or_b32_e32 v2, s5, v1
	v_lshlrev_b32_e32 v130, 11, v2
	v_lshl_add_u64 v[2:3], v[84:85], 0, v[130:131]
	global_store_short v[2:3], v4, off
	v_add_f32_e32 v2, v17, v9
	v_mul_f32_e32 v2, v166, v2
	v_readlane_b32 s5, v252, 61
	v_cvt_pk_bf16_f32 v4, v2, s0
	s_nop 0
	v_or_b32_e32 v2, s5, v1
	v_lshlrev_b32_e32 v130, 11, v2
	v_lshl_add_u64 v[2:3], v[84:85], 0, v[130:131]
	global_store_short v[2:3], v4, off
	global_load_ushort v4, v[116:117], off
	global_load_ushort v3, v[118:119], off offset:2048
	global_load_ushort v2, v[120:121], off
	global_load_dwordx4 v[24:27], v[88:89], off offset:3072
	v_readlane_b32 s5, v252, 62
	s_waitcnt vmcnt(3)
	v_lshlrev_b32_e32 v4, 16, v4
	v_fma_f32 v5, |v4|, s92, 1.0
	v_rcp_f32_e32 v5, v5
	v_mul_f32_e32 v7, v4, v4
	v_mul_f32_e32 v7, 0xbf38aa3b, v7
	v_exp_f32_e32 v7, v7
	v_fmamk_f32 v6, v5, 0x3f07dc22, v236
	v_fmaak_f32 v6, v5, v6, 0x3f35f0e3
	v_fmaak_f32 v6, v5, v6, 0xbe11a98e
	v_fmaak_f32 v6, v5, v6, 0x3e027906
	v_mul_f32_e32 v5, v5, v6
	v_mul_f32_e32 v5, v7, v5
	s_waitcnt vmcnt(2)
	v_lshlrev_b32_e32 v3, 16, v3
	v_mul_f32_e32 v6, v5, v4
	v_fma_f32 v5, -v5, v4, v4
	v_cmp_gt_f32_e32 vcc, 0, v4
	v_fma_f32 v4, |v3|, s92, 1.0
	v_rcp_f32_e32 v4, v4
	v_cndmask_b32_e32 v28, v5, v6, vcc
	v_mul_f32_e32 v6, v3, v3
	v_mul_f32_e32 v6, 0xbf38aa3b, v6
	v_fmamk_f32 v5, v4, 0x3f07dc22, v236
	v_fmaak_f32 v5, v4, v5, 0x3f35f0e3
	v_exp_f32_e32 v6, v6
	v_fmaak_f32 v5, v4, v5, 0xbe11a98e
	v_fmaak_f32 v5, v4, v5, 0x3e027906
	v_mul_f32_e32 v4, v4, v5
	v_mul_f32_e32 v4, v6, v4
	s_waitcnt vmcnt(1)
	v_lshlrev_b32_e32 v2, 16, v2
	v_mul_f32_e32 v5, v4, v3
	v_fma_f32 v4, -v4, v3, v3
	v_cmp_gt_f32_e32 vcc, 0, v3
	v_fma_f32 v3, |v2|, s92, 1.0
	v_rcp_f32_e32 v3, v3
	v_cndmask_b32_e32 v29, v4, v5, vcc
	v_mul_f32_e32 v5, v2, v2
	v_mul_f32_e32 v5, 0xbf38aa3b, v5
	v_fmamk_f32 v4, v3, 0x3f07dc22, v236
	v_fmaak_f32 v4, v3, v4, 0x3f35f0e3
	v_exp_f32_e32 v5, v5
	v_fmaak_f32 v4, v3, v4, 0xbe11a98e
	v_fmaak_f32 v4, v3, v4, 0x3e027906
	v_mul_f32_e32 v3, v3, v4
	v_mul_f32_e32 v3, v5, v3
	v_mul_f32_e32 v4, v3, v2
	v_fma_f32 v3, -v3, v2, v2
	v_cmp_gt_f32_e32 vcc, 0, v2
	s_nop 1
	v_cndmask_b32_e32 v82, v3, v4, vcc
	global_load_ushort v2, v[100:101], off offset:2048
	global_load_ushort v3, v[102:103], off
	global_load_ushort v4, v[104:105], off offset:2048
	global_load_ushort v5, v[106:107], off
	global_load_ushort v6, v[108:109], off offset:2048
	global_load_ushort v7, v[110:111], off
	global_load_ushort v8, v[112:113], off offset:2048
	global_load_ushort v9, v[114:115], off
	s_waitcnt vmcnt(7)
	v_lshlrev_b32_e32 v2, 16, v2
	v_fma_f32 v10, |v2|, s92, 1.0
	v_rcp_f32_e32 v10, v10
	v_mul_f32_e32 v12, v2, v2
	v_mul_f32_e32 v12, 0xbf38aa3b, v12
	v_exp_f32_e32 v12, v12
	v_fmamk_f32 v11, v10, 0x3f07dc22, v236
	v_fmaak_f32 v11, v10, v11, 0x3f35f0e3
	v_fmaak_f32 v11, v10, v11, 0xbe11a98e
	v_fmaak_f32 v11, v10, v11, 0x3e027906
	v_mul_f32_e32 v10, v10, v11
	v_mul_f32_e32 v10, v12, v10
	v_mul_f32_e32 v11, v10, v2
	v_fma_f32 v10, -v10, v2, v2
	v_cmp_gt_f32_e32 vcc, 0, v2
	s_waitcnt vmcnt(6)
	v_lshlrev_b32_e32 v2, 16, v3
	v_fma_f32 v3, |v2|, s92, 1.0
	v_rcp_f32_e32 v3, v3
	v_cndmask_b32_e32 v83, v10, v11, vcc
	v_mul_f32_e32 v11, v2, v2
	v_mul_f32_e32 v11, 0xbf38aa3b, v11
	v_fmamk_f32 v10, v3, 0x3f07dc22, v236
	v_fmaak_f32 v10, v3, v10, 0x3f35f0e3
	v_exp_f32_e32 v11, v11
	v_fmaak_f32 v10, v3, v10, 0xbe11a98e
	v_fmaak_f32 v10, v3, v10, 0x3e027906
	v_mul_f32_e32 v3, v3, v10
	v_mul_f32_e32 v3, v11, v3
	v_mul_f32_e32 v10, v3, v2
	v_fma_f32 v3, -v3, v2, v2
	v_cmp_gt_f32_e32 vcc, 0, v2
	s_waitcnt vmcnt(5)
	v_lshlrev_b32_e32 v2, 16, v4
	v_cndmask_b32_e32 v100, v3, v10, vcc
	v_fma_f32 v3, |v2|, s92, 1.0
	v_rcp_f32_e32 v3, v3
	v_mul_f32_e32 v10, v2, v2
	v_mul_f32_e32 v10, 0xbf38aa3b, v10
	v_exp_f32_e32 v10, v10
	v_fmamk_f32 v4, v3, 0x3f07dc22, v236
	v_fmaak_f32 v4, v3, v4, 0x3f35f0e3
	v_fmaak_f32 v4, v3, v4, 0xbe11a98e
	v_fmaak_f32 v4, v3, v4, 0x3e027906
	v_mul_f32_e32 v3, v3, v4
	v_mul_f32_e32 v3, v10, v3
	v_mul_f32_e32 v4, v3, v2
	v_fma_f32 v3, -v3, v2, v2
	v_cmp_gt_f32_e32 vcc, 0, v2
	s_waitcnt vmcnt(4)
	v_lshlrev_b32_e32 v2, 16, v5
	v_mul_f32_e32 v5, v2, v2
	v_cndmask_b32_e32 v101, v3, v4, vcc
	v_fma_f32 v3, |v2|, s92, 1.0
	v_rcp_f32_e32 v3, v3
	v_mul_f32_e32 v5, 0xbf38aa3b, v5
	v_exp_f32_e32 v5, v5
	v_cmp_gt_f32_e32 vcc, 0, v2
	v_fmamk_f32 v4, v3, 0x3f07dc22, v236
	v_fmaak_f32 v4, v3, v4, 0x3f35f0e3
	v_fmaak_f32 v4, v3, v4, 0xbe11a98e
	v_fmaak_f32 v4, v3, v4, 0x3e027906
	v_mul_f32_e32 v3, v3, v4
	v_mul_f32_e32 v3, v5, v3
	v_mul_f32_e32 v4, v3, v2
	v_fma_f32 v3, -v3, v2, v2
	s_waitcnt vmcnt(3)
	v_lshlrev_b32_e32 v2, 16, v6
	v_cndmask_b32_e32 v102, v3, v4, vcc
	v_fma_f32 v3, |v2|, s92, 1.0
	v_rcp_f32_e32 v3, v3
	v_mul_f32_e32 v5, v2, v2
	v_mul_f32_e32 v5, 0xbf38aa3b, v5
	v_exp_f32_e32 v5, v5
	v_fmamk_f32 v4, v3, 0x3f07dc22, v236
	v_fmaak_f32 v4, v3, v4, 0x3f35f0e3
	v_fmaak_f32 v4, v3, v4, 0xbe11a98e
	v_fmaak_f32 v4, v3, v4, 0x3e027906
	v_mul_f32_e32 v3, v3, v4
	v_mul_f32_e32 v3, v5, v3
	v_mul_f32_e32 v4, v3, v2
	v_fma_f32 v3, -v3, v2, v2
	v_cmp_gt_f32_e32 vcc, 0, v2
	s_waitcnt vmcnt(2)
	v_lshlrev_b32_e32 v2, 16, v7
	v_mul_f32_e32 v5, v2, v2
	v_cndmask_b32_e32 v103, v3, v4, vcc
	v_fma_f32 v3, |v2|, s92, 1.0
	v_rcp_f32_e32 v3, v3
	v_mul_f32_e32 v5, 0xbf38aa3b, v5
	v_exp_f32_e32 v5, v5
	v_cmp_gt_f32_e32 vcc, 0, v2
	v_fmamk_f32 v4, v3, 0x3f07dc22, v236
	v_fmaak_f32 v4, v3, v4, 0x3f35f0e3
	v_fmaak_f32 v4, v3, v4, 0xbe11a98e
	v_fmaak_f32 v4, v3, v4, 0x3e027906
	v_mul_f32_e32 v3, v3, v4
	v_mul_f32_e32 v3, v5, v3
	v_mul_f32_e32 v4, v3, v2
	v_fma_f32 v3, -v3, v2, v2
	s_waitcnt vmcnt(1)
	v_lshlrev_b32_e32 v2, 16, v8
	v_cndmask_b32_e32 v104, v3, v4, vcc
	v_fma_f32 v3, |v2|, s92, 1.0
	v_rcp_f32_e32 v3, v3
	v_mul_f32_e32 v5, v2, v2
	v_mul_f32_e32 v5, 0xbf38aa3b, v5
	v_exp_f32_e32 v5, v5
	v_fmamk_f32 v4, v3, 0x3f07dc22, v236
	v_fmaak_f32 v4, v3, v4, 0x3f35f0e3
	v_fmaak_f32 v4, v3, v4, 0xbe11a98e
	v_fmaak_f32 v4, v3, v4, 0x3e027906
	v_mul_f32_e32 v3, v3, v4
	v_mul_f32_e32 v3, v5, v3
	v_mul_f32_e32 v4, v3, v2
	v_fma_f32 v3, -v3, v2, v2
	v_cmp_gt_f32_e32 vcc, 0, v2
	s_waitcnt vmcnt(0)
	v_lshlrev_b32_e32 v2, 16, v9
	v_mul_f32_e32 v5, v2, v2
	v_cndmask_b32_e32 v105, v3, v4, vcc
	v_fma_f32 v3, |v2|, s92, 1.0
	v_rcp_f32_e32 v3, v3
	v_mul_f32_e32 v5, 0xbf38aa3b, v5
	v_exp_f32_e32 v5, v5
	v_cmp_gt_f32_e32 vcc, 0, v2
	v_fmamk_f32 v4, v3, 0x3f07dc22, v236
	v_fmaak_f32 v4, v3, v4, 0x3f35f0e3
	v_fmaak_f32 v4, v3, v4, 0xbe11a98e
	v_fmaak_f32 v4, v3, v4, 0x3e027906
	v_mul_f32_e32 v3, v3, v4
	v_mul_f32_e32 v3, v5, v3
	v_mul_f32_e32 v4, v3, v2
	v_fma_f32 v3, -v3, v2, v2
	v_cndmask_b32_e32 v106, v3, v4, vcc
	global_load_ushort v2, v[90:91], off offset:2048
	global_load_ushort v3, v[92:93], off
	global_load_ushort v4, v[94:95], off offset:2048
	global_load_ushort v5, v[96:97], off
	global_load_ushort v6, v[98:99], off offset:2048
	s_waitcnt vmcnt(4)
	v_lshlrev_b32_e32 v2, 16, v2
	v_fma_f32 v7, |v2|, s92, 1.0
	v_rcp_f32_e32 v7, v7
	v_mul_f32_e32 v9, v2, v2
	v_mul_f32_e32 v9, 0xbf38aa3b, v9
	v_exp_f32_e32 v9, v9
	v_fmamk_f32 v8, v7, 0x3f07dc22, v236
	v_fmaak_f32 v8, v7, v8, 0x3f35f0e3
	v_fmaak_f32 v8, v7, v8, 0xbe11a98e
	v_fmaak_f32 v8, v7, v8, 0x3e027906
	v_mul_f32_e32 v7, v7, v8
	v_mul_f32_e32 v7, v9, v7
	v_mul_f32_e32 v8, v7, v2
	v_fma_f32 v7, -v7, v2, v2
	v_cmp_gt_f32_e32 vcc, 0, v2
	s_waitcnt vmcnt(3)
	v_lshlrev_b32_e32 v2, 16, v3
	v_fma_f32 v3, |v2|, s92, 1.0
	v_rcp_f32_e32 v3, v3
	v_cndmask_b32_e32 v107, v7, v8, vcc
	v_mul_f32_e32 v8, v2, v2
	v_mul_f32_e32 v8, 0xbf38aa3b, v8
	v_fmamk_f32 v7, v3, 0x3f07dc22, v236
	v_fmaak_f32 v7, v3, v7, 0x3f35f0e3
	v_exp_f32_e32 v8, v8
	v_fmaak_f32 v7, v3, v7, 0xbe11a98e
	v_fmaak_f32 v7, v3, v7, 0x3e027906
	v_mul_f32_e32 v3, v3, v7
	v_mul_f32_e32 v3, v8, v3
	v_mul_f32_e32 v7, v3, v2
	v_fma_f32 v3, -v3, v2, v2
	v_cmp_gt_f32_e32 vcc, 0, v2
	s_waitcnt vmcnt(2)
	v_lshlrev_b32_e32 v2, 16, v4
	v_mfma_f32_32x32x16_bf16 v[8:23], v[18:21], v[62:65], 0
	v_cndmask_b32_e32 v108, v3, v7, vcc
	v_fma_f32 v3, |v2|, s92, 1.0
	v_rcp_f32_e32 v3, v3
	v_mul_f32_e32 v7, v2, v2
	v_mul_f32_e32 v7, 0xbf38aa3b, v7
	v_exp_f32_e32 v7, v7
	v_fmamk_f32 v4, v3, 0x3f07dc22, v236
	v_fmaak_f32 v4, v3, v4, 0x3f35f0e3
	v_fmaak_f32 v4, v3, v4, 0xbe11a98e
	v_fmaak_f32 v4, v3, v4, 0x3e027906
	v_mul_f32_e32 v3, v3, v4
	v_mul_f32_e32 v3, v7, v3
	v_mul_f32_e32 v4, v3, v2
	v_fma_f32 v3, -v3, v2, v2
	v_cmp_gt_f32_e32 vcc, 0, v2
	s_waitcnt vmcnt(1)
	v_lshlrev_b32_e32 v2, 16, v5
	v_mul_f32_e32 v5, v2, v2
	v_cndmask_b32_e32 v109, v3, v4, vcc
	v_fma_f32 v3, |v2|, s92, 1.0
	v_rcp_f32_e32 v3, v3
	v_mul_f32_e32 v5, 0xbf38aa3b, v5
	v_exp_f32_e32 v5, v5
	v_cmp_gt_f32_e32 vcc, 0, v2
	v_fmamk_f32 v4, v3, 0x3f07dc22, v236
	v_fmaak_f32 v4, v3, v4, 0x3f35f0e3
	v_fmaak_f32 v4, v3, v4, 0xbe11a98e
	v_fmaak_f32 v4, v3, v4, 0x3e027906
	v_mul_f32_e32 v3, v3, v4
	v_mul_f32_e32 v3, v5, v3
	v_mul_f32_e32 v4, v3, v2
	v_fma_f32 v3, -v3, v2, v2
	s_waitcnt vmcnt(0)
	v_lshlrev_b32_e32 v2, 16, v6
	v_cndmask_b32_e32 v110, v3, v4, vcc
	v_fma_f32 v3, |v2|, s92, 1.0
	v_rcp_f32_e32 v3, v3
	v_mul_f32_e32 v5, v2, v2
	v_mul_f32_e32 v5, 0xbf38aa3b, v5
	v_mfma_f32_32x32x16_bf16 v[8:23], v[78:81], v[58:61], v[8:23]
	v_fmamk_f32 v4, v3, 0x3f07dc22, v236
	v_fmaak_f32 v4, v3, v4, 0x3f35f0e3
	v_exp_f32_e32 v5, v5
	v_fmaak_f32 v4, v3, v4, 0xbe11a98e
	v_fmaak_f32 v4, v3, v4, 0x3e027906
	v_mul_f32_e32 v3, v3, v4
	v_mul_f32_e32 v3, v5, v3
	v_mul_f32_e32 v4, v3, v2
	v_fma_f32 v3, -v3, v2, v2
	v_cmp_gt_f32_e32 vcc, 0, v2
	v_mfma_f32_32x32x16_bf16 v[8:23], v[74:77], v[54:57], v[8:23]
	s_nop 0
	v_cndmask_b32_e32 v111, v3, v4, vcc
	global_load_dwordx4 v[2:5], v[86:87], off offset:-4096
	v_mfma_f32_32x32x16_bf16 v[8:23], v[70:73], v[50:53], v[8:23]
	v_mfma_f32_32x32x16_bf16 v[8:23], v[66:69], v[46:49], v[8:23]
	global_load_dwordx4 v[66:69], v[88:89], off offset:1024
	global_load_dwordx4 v[70:73], v[88:89], off offset:2048
	global_load_dwordx4 v[74:77], v[86:87], off
	global_load_dwordx4 v[78:81], v[86:87], off offset:1024
	s_nop 0
	global_load_dwordx4 v[88:91], v[86:87], off offset:2048
	global_load_dwordx4 v[92:95], v[86:87], off offset:3072
	ds_read_b128 v[96:99], v150 offset:256
	v_mfma_f32_32x32x16_bf16 v[8:23], v[30:33], v[42:45], v[8:23]
	ds_read_b128 v[30:33], v150 offset:288
	s_waitcnt lgkmcnt(1)
	s_nop 9
	v_add_f32_e32 v6, v8, v96
	v_mul_f32_e32 v6, v134, v6
	v_cvt_pk_bf16_f32 v8, v6, s0
	v_or_b32_e32 v6, s5, v1
	v_lshlrev_b32_e32 v130, 11, v6
	v_lshl_add_u64 v[6:7], v[84:85], 0, v[130:131]
	global_store_short v[6:7], v8, off
	v_add_f32_e32 v6, v9, v97
	v_mul_f32_e32 v6, v135, v6
	v_readlane_b32 s5, v252, 63
	v_cvt_pk_bf16_f32 v8, v6, s0
	s_nop 0
	v_or_b32_e32 v6, s5, v1
	v_lshlrev_b32_e32 v130, 11, v6
	v_lshl_add_u64 v[6:7], v[84:85], 0, v[130:131]
	global_store_short v[6:7], v8, off
	v_add_f32_e32 v6, v10, v98
	v_mul_f32_e32 v6, v136, v6
	v_readlane_b32 s5, v253, 0
	v_cvt_pk_bf16_f32 v8, v6, s0
	s_nop 0
	v_or_b32_e32 v6, s5, v1
	v_lshlrev_b32_e32 v130, 11, v6
	v_lshl_add_u64 v[6:7], v[84:85], 0, v[130:131]
	global_store_short v[6:7], v8, off
	v_add_f32_e32 v6, v11, v99
	v_mul_f32_e32 v6, v137, v6
	v_readlane_b32 s5, v253, 1
	v_cvt_pk_bf16_f32 v8, v6, s0
	ds_read_b128 v[96:99], v150 offset:352
	v_or_b32_e32 v6, s5, v1
	v_lshlrev_b32_e32 v130, 11, v6
	v_lshl_add_u64 v[6:7], v[84:85], 0, v[130:131]
	global_store_short v[6:7], v8, off
	s_waitcnt lgkmcnt(1)
	v_add_f32_e32 v6, v12, v30
	v_mul_f32_e32 v6, v138, v6
	v_readlane_b32 s5, v253, 2
	v_cvt_pk_bf16_f32 v8, v6, s0
	s_nop 0
	v_or_b32_e32 v6, s5, v1
	v_lshlrev_b32_e32 v130, 11, v6
	v_lshl_add_u64 v[6:7], v[84:85], 0, v[130:131]
	global_store_short v[6:7], v8, off
	v_add_f32_e32 v6, v13, v31
	v_mul_f32_e32 v6, v139, v6
	v_readlane_b32 s5, v253, 3
	v_cvt_pk_bf16_f32 v8, v6, s0
	s_nop 0
	v_or_b32_e32 v6, s5, v1
	v_lshlrev_b32_e32 v130, 11, v6
	v_lshl_add_u64 v[6:7], v[84:85], 0, v[130:131]
	global_store_short v[6:7], v8, off
	v_add_f32_e32 v6, v14, v32
	v_mul_f32_e32 v6, v140, v6
	v_readlane_b32 s5, v253, 4
	v_cvt_pk_bf16_f32 v8, v6, s0
	s_nop 0
	v_or_b32_e32 v6, s5, v1
	v_lshlrev_b32_e32 v130, 11, v6
	v_lshl_add_u64 v[6:7], v[84:85], 0, v[130:131]
	global_store_short v[6:7], v8, off
	v_add_f32_e32 v6, v15, v33
	ds_read_b128 v[30:33], v150 offset:320
	v_mul_f32_e32 v6, v141, v6
	v_readlane_b32 s5, v253, 5
	v_cvt_pk_bf16_f32 v8, v6, s0
	s_waitcnt lgkmcnt(0)
	v_add_f32_e32 v18, v18, v32
	v_or_b32_e32 v6, s5, v1
	v_lshlrev_b32_e32 v130, 11, v6
	v_lshl_add_u64 v[6:7], v[84:85], 0, v[130:131]
	global_store_short v[6:7], v8, off
	v_add_f32_e32 v6, v16, v30
	v_mul_f32_e32 v6, v122, v6
	v_readlane_b32 s5, v253, 6
	v_cvt_pk_bf16_f32 v8, v6, s0
	v_mul_f32_e32 v18, v124, v18
	v_or_b32_e32 v6, s5, v1
	v_lshlrev_b32_e32 v130, 11, v6
	v_lshl_add_u64 v[6:7], v[84:85], 0, v[130:131]
	global_store_short v[6:7], v8, off
	v_add_f32_e32 v6, v17, v31
	v_mul_f32_e32 v30, v123, v6
	s_waitcnt vmcnt(15)
	v_mfma_f32_32x32x16_bf16 v[2:17], v[2:5], v[62:65], 0
	v_readlane_b32 s5, v253, 7
	v_cvt_pk_bf16_f32 v62, v30, s0
	v_cvt_pk_bf16_f32 v18, v18, s0
	v_or_b32_e32 v30, s5, v1
	v_lshlrev_b32_e32 v130, 11, v30
	v_lshl_add_u64 v[30:31], v[84:85], 0, v[130:131]
	v_readlane_b32 s5, v253, 8
	s_waitcnt vmcnt(14)
	v_mfma_f32_32x32x16_bf16 v[2:17], v[66:69], v[58:61], v[2:17]
	global_store_short v[30:31], v62, off
	v_or_b32_e32 v30, s5, v1
	v_lshlrev_b32_e32 v130, 11, v30
	v_lshl_add_u64 v[30:31], v[84:85], 0, v[130:131]
	global_store_short v[30:31], v18, off
	v_add_f32_e32 v18, v19, v33
	v_mul_f32_e32 v18, v125, v18
	s_waitcnt vmcnt(15)
	v_mfma_f32_32x32x16_bf16 v[2:17], v[70:73], v[54:57], v[2:17]
	v_readlane_b32 s5, v253, 9
	v_cvt_pk_bf16_f32 v30, v18, s0
	s_nop 0
	v_or_b32_e32 v18, s5, v1
	v_lshlrev_b32_e32 v130, 11, v18
	v_lshl_add_u64 v[18:19], v[84:85], 0, v[130:131]
	global_store_short v[18:19], v30, off
	v_mfma_f32_32x32x16_bf16 v[2:17], v[24:27], v[50:53], v[2:17]
	v_add_f32_e32 v18, v20, v96
	v_mul_f32_e32 v18, v126, v18
	v_readlane_b32 s5, v253, 10
	v_cvt_pk_bf16_f32 v20, v18, s0
	s_nop 0
	v_or_b32_e32 v18, s5, v1
	v_lshlrev_b32_e32 v130, 11, v18
	s_waitcnt vmcnt(15)
	v_mfma_f32_32x32x16_bf16 v[2:17], v[74:77], v[46:49], v[2:17]
	v_lshl_add_u64 v[18:19], v[84:85], 0, v[130:131]
	global_store_short v[18:19], v20, off
	v_add_f32_e32 v18, v21, v97
	v_mul_f32_e32 v18, v127, v18
	v_readlane_b32 s5, v253, 11
	v_cvt_pk_bf16_f32 v20, v18, s0
	s_waitcnt vmcnt(15)
	v_mfma_f32_32x32x16_bf16 v[2:17], v[78:81], v[42:45], v[2:17]
	v_or_b32_e32 v18, s5, v1
	v_lshlrev_b32_e32 v130, 11, v18
	v_lshl_add_u64 v[18:19], v[84:85], 0, v[130:131]
	global_store_short v[18:19], v20, off
	v_add_f32_e32 v18, v22, v98
	v_mul_f32_e32 v18, v128, v18
	v_readlane_b32 s5, v253, 12
	s_waitcnt vmcnt(15)
	v_mfma_f32_32x32x16_bf16 v[2:17], v[88:91], v[38:41], v[2:17]
	v_cvt_pk_bf16_f32 v20, v18, s0
	v_or_b32_e32 v18, s5, v1
	v_lshlrev_b32_e32 v130, 11, v18
	v_lshl_add_u64 v[18:19], v[84:85], 0, v[130:131]
	global_store_short v[18:19], v20, off
	v_add_f32_e32 v18, v23, v99
	v_mul_f32_e32 v18, v129, v18
	v_readlane_b32 s5, v253, 13
	v_cvt_pk_bf16_f32 v20, v18, s0
	s_waitcnt vmcnt(15)
	v_mfma_f32_32x32x16_bf16 v[2:17], v[92:95], v[34:37], v[2:17]
	v_or_b32_e32 v18, s5, v1
	v_lshlrev_b32_e32 v130, 11, v18
	v_lshl_add_u64 v[18:19], v[84:85], 0, v[130:131]
	global_store_short v[18:19], v20, off
	ds_read_b128 v[18:21], v150 offset:384
	ds_read_b128 v[22:25], v150 offset:416
	v_readlane_b32 s5, v253, 14
	s_waitcnt lgkmcnt(1)
	s_nop 3
	v_add_f32_e32 v2, v2, v18
	v_or_b32_e32 v18, s5, v1
	v_mul_f32_e32 v2, v28, v2
	v_lshlrev_b32_e32 v130, 11, v18
	v_cvt_pk_bf16_f32 v2, v2, s0
	v_lshl_add_u64 v[26:27], v[84:85], 0, v[130:131]
	global_store_short v[26:27], v2, off
	v_add_f32_e32 v2, v3, v19
	v_mul_f32_e32 v2, v29, v2
	v_readlane_b32 s5, v253, 15
	v_cvt_pk_bf16_f32 v18, v2, s0
	s_nop 0
	v_or_b32_e32 v2, s5, v1
	v_lshlrev_b32_e32 v130, 11, v2
	v_lshl_add_u64 v[2:3], v[84:85], 0, v[130:131]
	global_store_short v[2:3], v18, off
	v_add_f32_e32 v2, v4, v20
	v_mul_f32_e32 v2, v82, v2
	v_readlane_b32 s5, v253, 16
	v_cvt_pk_bf16_f32 v4, v2, s0
	s_nop 0
	v_or_b32_e32 v2, s5, v1
	v_lshlrev_b32_e32 v130, 11, v2
	v_lshl_add_u64 v[2:3], v[84:85], 0, v[130:131]
	global_store_short v[2:3], v4, off
	v_add_f32_e32 v2, v5, v21
	v_mul_f32_e32 v2, v83, v2
	v_readlane_b32 s5, v253, 17
	v_cvt_pk_bf16_f32 v4, v2, s0
	s_nop 0
	v_or_b32_e32 v2, s5, v1
	v_lshlrev_b32_e32 v130, 11, v2
	v_lshl_add_u64 v[2:3], v[84:85], 0, v[130:131]
	global_store_short v[2:3], v4, off
	s_waitcnt lgkmcnt(0)
	v_add_f32_e32 v2, v6, v22
	v_mul_f32_e32 v2, v100, v2
	v_readlane_b32 s5, v253, 18
	v_cvt_pk_bf16_f32 v4, v2, s0
	s_nop 0
	v_or_b32_e32 v2, s5, v1
	v_lshlrev_b32_e32 v130, 11, v2
	v_lshl_add_u64 v[2:3], v[84:85], 0, v[130:131]
	global_store_short v[2:3], v4, off
	v_add_f32_e32 v2, v7, v23
	v_mul_f32_e32 v2, v101, v2
	v_readlane_b32 s5, v253, 19
	v_cvt_pk_bf16_f32 v4, v2, s0
	s_nop 0
	v_or_b32_e32 v2, s5, v1
	v_lshlrev_b32_e32 v130, 11, v2
	v_lshl_add_u64 v[2:3], v[84:85], 0, v[130:131]
	global_store_short v[2:3], v4, off
	v_add_f32_e32 v2, v8, v24
	v_mul_f32_e32 v2, v102, v2
	v_readlane_b32 s5, v253, 20
	v_cvt_pk_bf16_f32 v4, v2, s0
	s_nop 0
	v_or_b32_e32 v2, s5, v1
	v_lshlrev_b32_e32 v130, 11, v2
	v_lshl_add_u64 v[2:3], v[84:85], 0, v[130:131]
	global_store_short v[2:3], v4, off
	v_add_f32_e32 v2, v9, v25
	v_mul_f32_e32 v2, v103, v2
	v_cvt_pk_bf16_f32 v8, v2, s0
	ds_read_b128 v[2:5], v150 offset:448
	v_readlane_b32 s5, v253, 21
	s_nop 1
	v_or_b32_e32 v6, s5, v1
	v_lshlrev_b32_e32 v130, 11, v6
	v_lshl_add_u64 v[6:7], v[84:85], 0, v[130:131]
	v_readlane_b32 s5, v253, 22
	global_store_short v[6:7], v8, off
	ds_read_b128 v[6:9], v150 offset:480
	s_waitcnt lgkmcnt(1)
	v_add_f32_e32 v2, v10, v2
	v_or_b32_e32 v10, s5, v1
	v_mul_f32_e32 v2, v104, v2
	v_lshlrev_b32_e32 v130, 11, v10
	v_cvt_pk_bf16_f32 v2, v2, s0
	v_lshl_add_u64 v[18:19], v[84:85], 0, v[130:131]
	global_store_short v[18:19], v2, off
	v_add_f32_e32 v2, v11, v3
	v_mul_f32_e32 v2, v105, v2
	v_readlane_b32 s5, v253, 23
	v_cvt_pk_bf16_f32 v10, v2, s0
	s_nop 0
	v_or_b32_e32 v2, s5, v1
	v_lshlrev_b32_e32 v130, 11, v2
	v_lshl_add_u64 v[2:3], v[84:85], 0, v[130:131]
	global_store_short v[2:3], v10, off
	v_add_f32_e32 v2, v12, v4
	v_mul_f32_e32 v2, v106, v2
	v_readlane_b32 s5, v253, 24
	v_cvt_pk_bf16_f32 v4, v2, s0
	s_nop 0
	v_or_b32_e32 v2, s5, v1
	v_lshlrev_b32_e32 v130, 11, v2
	v_lshl_add_u64 v[2:3], v[84:85], 0, v[130:131]
	global_store_short v[2:3], v4, off
	v_add_f32_e32 v2, v13, v5
	v_mul_f32_e32 v2, v107, v2
	v_readlane_b32 s5, v253, 25
	v_cvt_pk_bf16_f32 v4, v2, s0
	s_nop 0
	v_or_b32_e32 v2, s5, v1
	v_lshlrev_b32_e32 v130, 11, v2
	v_lshl_add_u64 v[2:3], v[84:85], 0, v[130:131]
	global_store_short v[2:3], v4, off
	s_waitcnt lgkmcnt(0)
	v_add_f32_e32 v2, v14, v6
	v_mul_f32_e32 v2, v108, v2
	v_readlane_b32 s5, v253, 26
	v_cvt_pk_bf16_f32 v4, v2, s0
	s_nop 0
	v_or_b32_e32 v2, s5, v1
	v_lshlrev_b32_e32 v130, 11, v2
	v_lshl_add_u64 v[2:3], v[84:85], 0, v[130:131]
	global_store_short v[2:3], v4, off
	v_add_f32_e32 v2, v15, v7
	v_mul_f32_e32 v2, v109, v2
	v_readlane_b32 s5, v253, 27
	v_cvt_pk_bf16_f32 v4, v2, s0
	s_nop 0
	v_or_b32_e32 v2, s5, v1
	v_lshlrev_b32_e32 v130, 11, v2
	v_lshl_add_u64 v[2:3], v[84:85], 0, v[130:131]
	global_store_short v[2:3], v4, off
	v_add_f32_e32 v2, v16, v8
	v_mul_f32_e32 v2, v110, v2
	v_readlane_b32 s5, v253, 28
	v_cvt_pk_bf16_f32 v4, v2, s0
	s_nop 0
	v_or_b32_e32 v2, s5, v1
	v_lshlrev_b32_e32 v130, 11, v2
	v_lshl_add_u64 v[2:3], v[84:85], 0, v[130:131]
	v_readlane_b32 s5, v253, 29
	global_store_short v[2:3], v4, off
	v_add_f32_e32 v2, v17, v9
	v_or_b32_e32 v1, s5, v1
	v_mul_f32_e32 v2, v111, v2
	v_lshlrev_b32_e32 v130, 11, v1
	v_cvt_pk_bf16_f32 v4, v2, s0
	v_lshl_add_u64 v[2:3], v[84:85], 0, v[130:131]
	global_store_short v[2:3], v4, off
	s_barrier

.LBB0_319:
	s_add_i32 s65, s6, 32
	s_add_i32 s6, s6, 64
	s_cmpk_lt_i32 s65, 0x1e0
	s_cselect_b32 s6, s6, s65
	s_lshl_b32 s6, s6, 6
	s_and_b32 s8, s6, 0xfc0
	s_sub_i32 s8, s8, 30
	s_add_i32 s9, s8, s63
	s_and_b32 s6, s6, 0xfffff000
	s_max_i32 s9, s9, 0
	s_add_i32 s66, s9, s6
	s_add_i32 s9, s8, s62
	s_max_i32 s9, s9, 0
	s_add_i32 s67, s9, s6
	s_add_i32 s9, s8, s61
	s_max_i32 s9, s9, 0
	s_add_i32 s68, s9, s6
	s_add_i32 s9, s8, s60
	s_max_i32 s9, s9, 0
	s_add_i32 s69, s9, s6
	s_add_i32 s9, s8, s59
	s_max_i32 s9, s9, 0
	s_add_i32 s72, s9, s6
	s_add_i32 s9, s8, s58
	s_max_i32 s9, s9, 0
	s_add_i32 s73, s9, s6
	s_add_i32 s9, s8, s41
	s_max_i32 s9, s9, 0
	s_add_i32 s84, s9, s6
	s_add_i32 s9, s8, s40
	s_max_i32 s9, s9, 0
	s_add_i32 s85, s9, s6
	s_add_i32 s9, s8, s34
	s_max_i32 s9, s9, 0
	s_add_i32 s88, s9, s6
	s_add_i32 s9, s8, s29
	s_max_i32 s9, s9, 0
	s_add_i32 s89, s9, s6
	s_add_i32 s9, s8, s28
	s_add_i32 s8, s8, s5
	s_max_i32 s9, s9, 0
	s_max_i32 s8, s8, 0
	s_add_i32 s94, s9, s6
	s_add_i32 s95, s8, s6
	s_lshl_b32 s6, s42, 7
	s_add_i32 s8, s64, s7
	s_and_b32 s6, s6, 0xffff8000
	s_sub_i32 s10, s8, 56
	s_add_i32 vcc_lo, s6, 0
	s_lshl_b32 s6, s7, 10
	s_ashr_i32 s11, s10, 31
	s_add_i32 s6, s6, 0
	s_lshl_b64 s[10:11], s[10:11], 11
	s_add_u32 s56, s76, s10
	s_addc_u32 s57, s77, s11
	s_sub_i32 s10, s8, 48
	s_ashr_i32 s11, s10, 31
	s_lshl_b64 s[10:11], s[10:11], 11
	s_add_u32 s54, s76, s10
	s_addc_u32 s55, s77, s11
	s_sub_i32 s10, s8, 40
	s_ashr_i32 s11, s10, 31
	s_lshl_b64 s[10:11], s[10:11], 11
	s_add_u32 s52, s76, s10
	s_addc_u32 s53, s77, s11
	s_sub_i32 s10, s8, 32
	s_ashr_i32 s11, s10, 31
	s_lshl_b64 s[10:11], s[10:11], 11
	s_add_u32 s50, s76, s10
	s_addc_u32 s51, s77, s11
	s_sub_i32 s10, s8, 24
	s_ashr_i32 s11, s10, 31
	s_lshl_b64 s[10:11], s[10:11], 11
	s_add_u32 s48, s76, s10
	s_addc_u32 s49, s77, s11
	s_add_i32 s10, s8, -16
	s_ashr_i32 s11, s10, 31
	s_lshl_b64 s[10:11], s[10:11], 11
	s_add_u32 s46, s76, s10
	s_addc_u32 s47, s77, s11
	s_add_i32 s10, s8, -8
	s_ashr_i32 s11, s10, 31
	s_lshl_b64 s[10:11], s[10:11], 11
	s_add_u32 s44, s76, s10
	s_addc_u32 s45, s77, s11
	s_ashr_i32 s9, s8, 31
	s_lshl_b64 s[8:9], s[8:9], 11
	s_add_u32 s42, s76, s8
	v_and_b32_e32 v12, 0xff, v10
	s_addc_u32 s43, s77, s9
	v_mad_i64_i32 v[10:11], s[8:9], s66, v238, v[102:103]
	s_waitcnt lgkmcnt(0)
	s_barrier
	global_load_dwordx2 v[152:153], v[10:11], off offset:1024
	global_load_dwordx2 v[154:155], v[10:11], off offset:1536
	v_mad_i64_i32 v[10:11], s[8:9], s67, v238, v[102:103]
	global_load_dwordx2 v[148:149], v[10:11], off offset:1024
	global_load_dwordx2 v[150:151], v[10:11], off offset:1536
	v_mad_i64_i32 v[10:11], s[8:9], s68, v238, v[102:103]
	global_load_dwordx2 v[144:145], v[10:11], off offset:1024
	global_load_dwordx2 v[146:147], v[10:11], off offset:1536
	v_mad_i64_i32 v[10:11], s[8:9], s69, v238, v[102:103]
	global_load_dwordx2 v[140:141], v[10:11], off offset:1024
	global_load_dwordx2 v[142:143], v[10:11], off offset:1536
	v_mad_i64_i32 v[10:11], s[8:9], s72, v238, v[102:103]
	global_load_dwordx2 v[136:137], v[10:11], off offset:1024
	global_load_dwordx2 v[138:139], v[10:11], off offset:1536
	v_mad_i64_i32 v[10:11], s[8:9], s73, v238, v[102:103]
	global_load_dwordx2 v[132:133], v[10:11], off offset:1024
	global_load_dwordx2 v[134:135], v[10:11], off offset:1536
	v_mad_i64_i32 v[10:11], s[8:9], s84, v238, v[102:103]
	global_load_dwordx2 v[126:127], v[10:11], off offset:1024
	global_load_dwordx2 v[128:129], v[10:11], off offset:1536
	v_mad_i64_i32 v[10:11], s[8:9], s85, v238, v[102:103]
	global_load_dwordx2 v[122:123], v[10:11], off offset:1024
	global_load_dwordx2 v[124:125], v[10:11], off offset:1536
	v_mad_i64_i32 v[10:11], s[8:9], s88, v238, v[102:103]
	global_load_dwordx2 v[118:119], v[10:11], off offset:1024
	global_load_dwordx2 v[120:121], v[10:11], off offset:1536
	v_mad_i64_i32 v[10:11], s[8:9], s89, v238, v[102:103]
	global_load_dwordx2 v[114:115], v[10:11], off offset:1024
	global_load_dwordx2 v[116:117], v[10:11], off offset:1536
	v_mad_i64_i32 v[10:11], s[8:9], s94, v238, v[102:103]
	global_load_dwordx2 v[110:111], v[10:11], off offset:1024
	global_load_dwordx2 v[112:113], v[10:11], off offset:1536
	v_mad_i64_i32 v[10:11], s[8:9], s95, v238, v[102:103]
	v_lshl_add_u32 v163, v12, 2, vcc_lo
	global_load_dwordx2 v[106:107], v[10:11], off offset:1024
	global_load_dwordx2 v[108:109], v[10:11], off offset:1536
	ds_read2st64_b32 v[26:27], v163 offset1:4
	ds_read2st64_b32 v[28:29], v163 offset0:8 offset1:12
	ds_read2st64_b32 v[30:31], v163 offset0:16 offset1:20
	ds_read2st64_b32 v[32:33], v163 offset0:24 offset1:28
	ds_read2st64_b32 v[160:161], v163 offset0:32 offset1:36
	ds_read2st64_b32 v[158:159], v163 offset0:40 offset1:44
	ds_read2st64_b32 v[156:157], v163 offset0:48 offset1:52
	ds_read2st64_b32 v[40:41], v163 offset0:56 offset1:60
	ds_read2st64_b32 v[38:39], v163 offset0:64 offset1:68
	ds_read2st64_b32 v[36:37], v163 offset0:72 offset1:76
	ds_read2st64_b32 v[34:35], v163 offset0:80 offset1:84
	ds_read2st64_b32 v[24:25], v163 offset0:88 offset1:92
	ds_read2st64_b32 v[22:23], v163 offset0:96 offset1:100
	ds_read2st64_b32 v[20:21], v163 offset0:104 offset1:108
	ds_read2st64_b32 v[18:19], v163 offset0:112 offset1:116
	ds_read2st64_b32 v[10:11], v163 offset0:120 offset1:124
	ds_read2st64_b32 v[12:13], v163 offset0:128 offset1:132
	ds_read2st64_b32 v[14:15], v163 offset0:136 offset1:140
	ds_read2st64_b32 v[16:17], v163 offset0:144 offset1:148
	s_waitcnt lgkmcnt(14)
	v_mul_f32_e32 v165, v42, v27
	s_waitcnt vmcnt(51) lgkmcnt(3)
	v_mul_f32_e32 v105, v101, v10
	s_waitcnt vmcnt(24)
	v_mov_b32_e32 v164, v104
	v_pk_fma_f32 v[26:27], v[42:43], v[26:27], v[104:105]
	v_pk_fma_f32 v[164:165], v[44:45], v[28:29], v[164:165]
	v_pk_fma_f32 v[26:27], v[46:47], v[28:29], v[26:27]
	v_pk_fma_f32 v[164:165], v[48:49], v[30:31], v[164:165]
	v_pk_fma_f32 v[26:27], v[50:51], v[30:31], v[26:27]
	v_pk_fma_f32 v[164:165], v[52:53], v[32:33], v[164:165]
	v_pk_fma_f32 v[26:27], v[54:55], v[32:33], v[26:27]
	v_pk_fma_f32 v[164:165], v[56:57], v[160:161], v[164:165]
	v_pk_fma_f32 v[26:27], v[58:59], v[160:161], v[26:27]
	v_pk_fma_f32 v[164:165], v[60:61], v[158:159], v[164:165]
	v_pk_fma_f32 v[26:27], v[62:63], v[158:159], v[26:27]
	v_pk_fma_f32 v[164:165], v[64:65], v[156:157], v[164:165]
	v_pk_fma_f32 v[26:27], v[66:67], v[156:157], v[26:27]
	v_pk_fma_f32 v[164:165], v[68:69], v[40:41], v[164:165]
	v_pk_fma_f32 v[26:27], v[70:71], v[40:41], v[26:27]
	v_pk_fma_f32 v[164:165], v[72:73], v[38:39], v[164:165]
	v_pk_fma_f32 v[26:27], v[74:75], v[38:39], v[26:27]
	v_pk_fma_f32 v[164:165], v[76:77], v[36:37], v[164:165]
	v_pk_fma_f32 v[26:27], v[78:79], v[36:37], v[26:27]
	v_pk_fma_f32 v[164:165], v[80:81], v[34:35], v[164:165]
	v_pk_fma_f32 v[26:27], v[82:83], v[34:35], v[26:27]
	v_pk_fma_f32 v[164:165], v[84:85], v[24:25], v[164:165]
	v_pk_fma_f32 v[26:27], v[86:87], v[24:25], v[26:27]
	v_pk_fma_f32 v[164:165], v[88:89], v[22:23], v[164:165]
	v_pk_fma_f32 v[26:27], v[90:91], v[22:23], v[26:27]
	v_pk_fma_f32 v[164:165], v[92:93], v[20:21], v[164:165]
	v_pk_fma_f32 v[26:27], v[94:95], v[20:21], v[26:27]
	v_pk_fma_f32 v[164:165], v[96:97], v[18:19], v[164:165]
	v_pk_fma_f32 v[26:27], v[98:99], v[18:19], v[26:27]
	v_pk_fma_f32 v[166:167], v[100:101], v[10:11], v[164:165]
	v_add_f32_e32 v164, v26, v27
	v_mul_f32_e32 v27, v42, v29
	v_mov_b32_e32 v26, v104
	v_pk_fma_f32 v[26:27], v[44:45], v[30:31], v[26:27]
	s_waitcnt lgkmcnt(2)
	v_mul_f32_e32 v105, v101, v12
	v_pk_fma_f32 v[26:27], v[48:49], v[32:33], v[26:27]
	v_pk_fma_f32 v[28:29], v[42:43], v[28:29], v[104:105]
	v_pk_fma_f32 v[26:27], v[52:53], v[160:161], v[26:27]
	v_pk_fma_f32 v[28:29], v[46:47], v[30:31], v[28:29]
	v_pk_fma_f32 v[26:27], v[56:57], v[158:159], v[26:27]
	v_pk_fma_f32 v[28:29], v[50:51], v[32:33], v[28:29]
	v_pk_fma_f32 v[26:27], v[60:61], v[156:157], v[26:27]
	v_pk_fma_f32 v[28:29], v[54:55], v[160:161], v[28:29]
	v_pk_fma_f32 v[26:27], v[64:65], v[40:41], v[26:27]
	v_pk_fma_f32 v[28:29], v[58:59], v[158:159], v[28:29]
	v_pk_fma_f32 v[26:27], v[68:69], v[38:39], v[26:27]
	v_pk_fma_f32 v[28:29], v[62:63], v[156:157], v[28:29]
	v_pk_fma_f32 v[26:27], v[72:73], v[36:37], v[26:27]
	v_pk_fma_f32 v[28:29], v[66:67], v[40:41], v[28:29]
	v_pk_fma_f32 v[26:27], v[76:77], v[34:35], v[26:27]
	v_pk_fma_f32 v[28:29], v[70:71], v[38:39], v[28:29]
	v_pk_fma_f32 v[26:27], v[80:81], v[24:25], v[26:27]
	v_pk_fma_f32 v[28:29], v[74:75], v[36:37], v[28:29]
	v_pk_fma_f32 v[26:27], v[84:85], v[22:23], v[26:27]
	v_pk_fma_f32 v[28:29], v[78:79], v[34:35], v[28:29]
	v_pk_fma_f32 v[26:27], v[88:89], v[20:21], v[26:27]
	v_pk_fma_f32 v[28:29], v[82:83], v[24:25], v[28:29]
	v_pk_fma_f32 v[26:27], v[92:93], v[18:19], v[26:27]
	v_pk_fma_f32 v[28:29], v[86:87], v[22:23], v[28:29]
	v_pk_fma_f32 v[26:27], v[96:97], v[10:11], v[26:27]
	v_pk_fma_f32 v[28:29], v[90:91], v[20:21], v[28:29]
	v_pk_fma_f32 v[26:27], v[100:101], v[12:13], v[26:27]
	v_add_f32_e32 v165, v166, v167
	v_pk_fma_f32 v[28:29], v[94:95], v[18:19], v[28:29]
	v_add_f32_e32 v167, v26, v27
	v_mul_f32_e32 v27, v42, v31
	v_mov_b32_e32 v26, v104
	v_pk_fma_f32 v[28:29], v[98:99], v[10:11], v[28:29]
	s_waitcnt lgkmcnt(1)
	v_mul_f32_e32 v105, v101, v14
	v_pk_fma_f32 v[26:27], v[44:45], v[32:33], v[26:27]
	v_add_f32_e32 v166, v28, v29
	v_pk_fma_f32 v[28:29], v[42:43], v[30:31], v[104:105]
	v_pk_fma_f32 v[26:27], v[48:49], v[160:161], v[26:27]
	v_pk_fma_f32 v[28:29], v[46:47], v[32:33], v[28:29]
	v_pk_fma_f32 v[26:27], v[52:53], v[158:159], v[26:27]
	v_pk_fma_f32 v[28:29], v[50:51], v[160:161], v[28:29]
	v_pk_fma_f32 v[26:27], v[56:57], v[156:157], v[26:27]
	v_pk_fma_f32 v[28:29], v[54:55], v[158:159], v[28:29]
	v_pk_fma_f32 v[26:27], v[60:61], v[40:41], v[26:27]
	v_pk_fma_f32 v[28:29], v[58:59], v[156:157], v[28:29]
	v_pk_fma_f32 v[26:27], v[64:65], v[38:39], v[26:27]
	v_pk_fma_f32 v[28:29], v[62:63], v[40:41], v[28:29]
	v_pk_fma_f32 v[26:27], v[68:69], v[36:37], v[26:27]
	v_pk_fma_f32 v[28:29], v[66:67], v[38:39], v[28:29]
	v_pk_fma_f32 v[26:27], v[72:73], v[34:35], v[26:27]
	v_pk_fma_f32 v[28:29], v[70:71], v[36:37], v[28:29]
	v_pk_fma_f32 v[26:27], v[76:77], v[24:25], v[26:27]
	v_pk_fma_f32 v[28:29], v[74:75], v[34:35], v[28:29]
	v_pk_fma_f32 v[26:27], v[80:81], v[22:23], v[26:27]
	v_pk_fma_f32 v[28:29], v[78:79], v[24:25], v[28:29]
	v_pk_fma_f32 v[26:27], v[84:85], v[20:21], v[26:27]
	v_pk_fma_f32 v[28:29], v[82:83], v[22:23], v[28:29]
	v_pk_fma_f32 v[26:27], v[88:89], v[18:19], v[26:27]
	v_pk_fma_f32 v[28:29], v[86:87], v[20:21], v[28:29]
	v_pk_fma_f32 v[26:27], v[92:93], v[10:11], v[26:27]
	v_pk_fma_f32 v[28:29], v[90:91], v[18:19], v[28:29]
	v_pk_fma_f32 v[26:27], v[96:97], v[12:13], v[26:27]
	v_pk_fma_f32 v[28:29], v[94:95], v[10:11], v[28:29]
	v_pk_fma_f32 v[26:27], v[100:101], v[14:15], v[26:27]
	v_pk_fma_f32 v[28:29], v[98:99], v[12:13], v[28:29]
	v_add_f32_e32 v169, v26, v27
	s_waitcnt lgkmcnt(0)
	v_mul_f32_e32 v105, v101, v16
	v_mul_f32_e32 v27, v42, v33
	v_mov_b32_e32 v26, v104
	v_add_f32_e32 v168, v28, v29
	v_pk_fma_f32 v[28:29], v[42:43], v[32:33], v[104:105]
	v_pk_fma_f32 v[26:27], v[44:45], v[160:161], v[26:27]
	v_pk_fma_f32 v[28:29], v[46:47], v[160:161], v[28:29]
	v_pk_fma_f32 v[26:27], v[48:49], v[158:159], v[26:27]
	v_pk_fma_f32 v[28:29], v[50:51], v[158:159], v[28:29]
	v_pk_fma_f32 v[26:27], v[52:53], v[156:157], v[26:27]
	v_pk_fma_f32 v[28:29], v[54:55], v[156:157], v[28:29]
	v_pk_fma_f32 v[26:27], v[56:57], v[40:41], v[26:27]
	v_pk_fma_f32 v[28:29], v[58:59], v[40:41], v[28:29]
	v_pk_fma_f32 v[26:27], v[60:61], v[38:39], v[26:27]
	v_pk_fma_f32 v[28:29], v[62:63], v[38:39], v[28:29]
	v_pk_fma_f32 v[26:27], v[64:65], v[36:37], v[26:27]
	v_pk_fma_f32 v[28:29], v[66:67], v[36:37], v[28:29]
	v_pk_fma_f32 v[26:27], v[68:69], v[34:35], v[26:27]
	v_pk_fma_f32 v[28:29], v[70:71], v[34:35], v[28:29]
	v_pk_fma_f32 v[26:27], v[72:73], v[24:25], v[26:27]
	v_pk_fma_f32 v[28:29], v[74:75], v[24:25], v[28:29]
	v_pk_fma_f32 v[26:27], v[76:77], v[22:23], v[26:27]
	v_pk_fma_f32 v[28:29], v[78:79], v[22:23], v[28:29]
	v_pk_fma_f32 v[26:27], v[80:81], v[20:21], v[26:27]
	v_pk_fma_f32 v[28:29], v[82:83], v[20:21], v[28:29]
	v_pk_fma_f32 v[26:27], v[84:85], v[18:19], v[26:27]
	v_pk_fma_f32 v[28:29], v[86:87], v[18:19], v[28:29]
	v_pk_fma_f32 v[26:27], v[88:89], v[10:11], v[26:27]
	v_pk_fma_f32 v[28:29], v[90:91], v[10:11], v[28:29]
	v_pk_fma_f32 v[26:27], v[92:93], v[12:13], v[26:27]
	v_pk_fma_f32 v[28:29], v[94:95], v[12:13], v[28:29]
	v_pk_fma_f32 v[26:27], v[96:97], v[14:15], v[26:27]
	v_pk_fma_f32 v[28:29], v[98:99], v[14:15], v[28:29]
	v_pk_fma_f32 v[26:27], v[100:101], v[16:17], v[26:27]
	v_add_f32_e32 v170, v28, v29
	v_add_f32_e32 v171, v26, v27
	ds_read2st64_b32 v[26:27], v163 offset0:152 offset1:156
	ds_read2st64_b32 v[28:29], v163 offset0:160 offset1:164
	ds_read2st64_b32 v[30:31], v163 offset0:168 offset1:172
	ds_read2st64_b32 v[32:33], v163 offset0:176 offset1:180
	v_mul_f32_e32 v173, v42, v161
	s_waitcnt lgkmcnt(3)
	v_mul_f32_e32 v105, v101, v26
	v_pk_fma_f32 v[160:161], v[42:43], v[160:161], v[104:105]
	v_mov_b32_e32 v172, v104
	v_pk_fma_f32 v[160:161], v[46:47], v[158:159], v[160:161]
	s_waitcnt lgkmcnt(2)
	v_mul_f32_e32 v105, v101, v28
	v_pk_fma_f32 v[160:161], v[50:51], v[156:157], v[160:161]
	v_pk_fma_f32 v[172:173], v[44:45], v[158:159], v[172:173]
	v_pk_fma_f32 v[160:161], v[54:55], v[40:41], v[160:161]
	v_pk_fma_f32 v[172:173], v[48:49], v[156:157], v[172:173]
	v_pk_fma_f32 v[160:161], v[58:59], v[38:39], v[160:161]
	v_pk_fma_f32 v[172:173], v[52:53], v[40:41], v[172:173]
	v_pk_fma_f32 v[160:161], v[62:63], v[36:37], v[160:161]
	v_pk_fma_f32 v[172:173], v[56:57], v[38:39], v[172:173]
	v_pk_fma_f32 v[160:161], v[66:67], v[34:35], v[160:161]
	v_pk_fma_f32 v[172:173], v[60:61], v[36:37], v[172:173]
	v_pk_fma_f32 v[160:161], v[70:71], v[24:25], v[160:161]
	v_pk_fma_f32 v[172:173], v[64:65], v[34:35], v[172:173]
	v_pk_fma_f32 v[160:161], v[74:75], v[22:23], v[160:161]
	v_pk_fma_f32 v[172:173], v[68:69], v[24:25], v[172:173]
	v_pk_fma_f32 v[160:161], v[78:79], v[20:21], v[160:161]
	v_pk_fma_f32 v[172:173], v[72:73], v[22:23], v[172:173]
	v_pk_fma_f32 v[160:161], v[82:83], v[18:19], v[160:161]
	v_pk_fma_f32 v[172:173], v[76:77], v[20:21], v[172:173]
	v_pk_fma_f32 v[160:161], v[86:87], v[10:11], v[160:161]
	v_pk_fma_f32 v[172:173], v[80:81], v[18:19], v[172:173]
	v_pk_fma_f32 v[160:161], v[90:91], v[12:13], v[160:161]
	v_pk_fma_f32 v[172:173], v[84:85], v[10:11], v[172:173]
	v_pk_fma_f32 v[160:161], v[94:95], v[14:15], v[160:161]
	v_pk_fma_f32 v[172:173], v[88:89], v[12:13], v[172:173]
	v_pk_fma_f32 v[160:161], v[98:99], v[16:17], v[160:161]
	v_pk_fma_f32 v[172:173], v[92:93], v[14:15], v[172:173]
	v_add_f32_e32 v174, v160, v161
	v_mul_f32_e32 v161, v42, v159
	v_pk_fma_f32 v[158:159], v[42:43], v[158:159], v[104:105]
	v_mov_b32_e32 v160, v104
	v_pk_fma_f32 v[158:159], v[46:47], v[156:157], v[158:159]
	s_waitcnt lgkmcnt(1)
	v_mul_f32_e32 v105, v101, v30
	v_pk_fma_f32 v[158:159], v[50:51], v[40:41], v[158:159]
	v_pk_fma_f32 v[160:161], v[44:45], v[156:157], v[160:161]
	v_pk_fma_f32 v[158:159], v[54:55], v[38:39], v[158:159]
	v_pk_fma_f32 v[160:161], v[48:49], v[40:41], v[160:161]
	v_pk_fma_f32 v[158:159], v[58:59], v[36:37], v[158:159]
	v_pk_fma_f32 v[160:161], v[52:53], v[38:39], v[160:161]
	v_pk_fma_f32 v[158:159], v[62:63], v[34:35], v[158:159]
	v_pk_fma_f32 v[160:161], v[56:57], v[36:37], v[160:161]
	v_pk_fma_f32 v[158:159], v[66:67], v[24:25], v[158:159]
	v_pk_fma_f32 v[160:161], v[60:61], v[34:35], v[160:161]
	v_pk_fma_f32 v[158:159], v[70:71], v[22:23], v[158:159]
	v_pk_fma_f32 v[160:161], v[64:65], v[24:25], v[160:161]
	v_pk_fma_f32 v[158:159], v[74:75], v[20:21], v[158:159]
	v_pk_fma_f32 v[160:161], v[68:69], v[22:23], v[160:161]
	v_pk_fma_f32 v[158:159], v[78:79], v[18:19], v[158:159]
	v_pk_fma_f32 v[160:161], v[72:73], v[20:21], v[160:161]
	v_pk_fma_f32 v[158:159], v[82:83], v[10:11], v[158:159]
	v_pk_fma_f32 v[160:161], v[76:77], v[18:19], v[160:161]
	v_pk_fma_f32 v[158:159], v[86:87], v[12:13], v[158:159]
	v_pk_fma_f32 v[160:161], v[80:81], v[10:11], v[160:161]
	v_pk_fma_f32 v[158:159], v[90:91], v[14:15], v[158:159]
	v_pk_fma_f32 v[160:161], v[84:85], v[12:13], v[160:161]
	v_pk_fma_f32 v[158:159], v[94:95], v[16:17], v[158:159]
	v_pk_fma_f32 v[160:161], v[88:89], v[14:15], v[160:161]
	v_pk_fma_f32 v[158:159], v[98:99], v[26:27], v[158:159]
	v_pk_fma_f32 v[160:161], v[92:93], v[16:17], v[160:161]
	v_add_f32_e32 v176, v158, v159
	v_mul_f32_e32 v159, v42, v157
	v_pk_fma_f32 v[156:157], v[42:43], v[156:157], v[104:105]
	v_mov_b32_e32 v158, v104
	v_pk_fma_f32 v[156:157], v[46:47], v[40:41], v[156:157]
	s_waitcnt lgkmcnt(0)
	v_mul_f32_e32 v105, v101, v32
	v_pk_fma_f32 v[156:157], v[50:51], v[38:39], v[156:157]
	v_pk_fma_f32 v[158:159], v[44:45], v[40:41], v[158:159]
	v_pk_fma_f32 v[156:157], v[54:55], v[36:37], v[156:157]
	v_pk_fma_f32 v[158:159], v[48:49], v[38:39], v[158:159]
	v_pk_fma_f32 v[156:157], v[58:59], v[34:35], v[156:157]
	v_pk_fma_f32 v[158:159], v[52:53], v[36:37], v[158:159]
	v_pk_fma_f32 v[156:157], v[62:63], v[24:25], v[156:157]
	v_pk_fma_f32 v[158:159], v[56:57], v[34:35], v[158:159]
	v_pk_fma_f32 v[156:157], v[66:67], v[22:23], v[156:157]
	v_pk_fma_f32 v[158:159], v[60:61], v[24:25], v[158:159]
	v_pk_fma_f32 v[156:157], v[70:71], v[20:21], v[156:157]
	v_pk_fma_f32 v[158:159], v[64:65], v[22:23], v[158:159]
	v_pk_fma_f32 v[156:157], v[74:75], v[18:19], v[156:157]
	v_pk_fma_f32 v[158:159], v[68:69], v[20:21], v[158:159]
	v_pk_fma_f32 v[156:157], v[78:79], v[10:11], v[156:157]
	v_pk_fma_f32 v[158:159], v[72:73], v[18:19], v[158:159]
	v_pk_fma_f32 v[156:157], v[82:83], v[12:13], v[156:157]
	v_pk_fma_f32 v[158:159], v[76:77], v[10:11], v[158:159]
	v_pk_fma_f32 v[156:157], v[86:87], v[14:15], v[156:157]
	v_pk_fma_f32 v[158:159], v[80:81], v[12:13], v[158:159]
	v_pk_fma_f32 v[156:157], v[90:91], v[16:17], v[156:157]
	v_pk_fma_f32 v[158:159], v[84:85], v[14:15], v[158:159]
	v_pk_fma_f32 v[156:157], v[94:95], v[26:27], v[156:157]
	v_pk_fma_f32 v[158:159], v[88:89], v[16:17], v[158:159]
	v_pk_fma_f32 v[156:157], v[98:99], v[28:29], v[156:157]
	v_pk_fma_f32 v[158:159], v[92:93], v[26:27], v[158:159]
	v_add_f32_e32 v178, v156, v157
	v_mul_f32_e32 v157, v42, v41
	v_mov_b32_e32 v156, v104
	v_pk_fma_f32 v[40:41], v[42:43], v[40:41], v[104:105]
	v_pk_fma_f32 v[156:157], v[44:45], v[38:39], v[156:157]
	v_pk_fma_f32 v[40:41], v[46:47], v[38:39], v[40:41]
	v_pk_fma_f32 v[156:157], v[48:49], v[36:37], v[156:157]
	v_pk_fma_f32 v[40:41], v[50:51], v[36:37], v[40:41]
	v_pk_fma_f32 v[156:157], v[52:53], v[34:35], v[156:157]
	v_pk_fma_f32 v[40:41], v[54:55], v[34:35], v[40:41]
	v_pk_fma_f32 v[156:157], v[56:57], v[24:25], v[156:157]
	v_pk_fma_f32 v[40:41], v[58:59], v[24:25], v[40:41]
	v_pk_fma_f32 v[156:157], v[60:61], v[22:23], v[156:157]
	v_pk_fma_f32 v[40:41], v[62:63], v[22:23], v[40:41]
	v_pk_fma_f32 v[156:157], v[64:65], v[20:21], v[156:157]
	v_pk_fma_f32 v[40:41], v[66:67], v[20:21], v[40:41]
	v_pk_fma_f32 v[156:157], v[68:69], v[18:19], v[156:157]
	v_pk_fma_f32 v[40:41], v[70:71], v[18:19], v[40:41]
	v_pk_fma_f32 v[156:157], v[72:73], v[10:11], v[156:157]
	v_pk_fma_f32 v[40:41], v[74:75], v[10:11], v[40:41]
	v_pk_fma_f32 v[156:157], v[76:77], v[12:13], v[156:157]
	v_pk_fma_f32 v[40:41], v[78:79], v[12:13], v[40:41]
	v_pk_fma_f32 v[156:157], v[80:81], v[14:15], v[156:157]
	v_pk_fma_f32 v[40:41], v[82:83], v[14:15], v[40:41]
	v_pk_fma_f32 v[156:157], v[84:85], v[16:17], v[156:157]
	v_pk_fma_f32 v[40:41], v[86:87], v[16:17], v[40:41]
	v_pk_fma_f32 v[156:157], v[88:89], v[26:27], v[156:157]
	v_pk_fma_f32 v[40:41], v[90:91], v[26:27], v[40:41]
	v_pk_fma_f32 v[156:157], v[92:93], v[28:29], v[156:157]
	v_pk_fma_f32 v[160:161], v[96:97], v[26:27], v[160:161]
	v_pk_fma_f32 v[158:159], v[96:97], v[28:29], v[158:159]
	v_pk_fma_f32 v[40:41], v[94:95], v[28:29], v[40:41]
	v_pk_fma_f32 v[156:157], v[96:97], v[30:31], v[156:157]
	v_pk_fma_f32 v[160:161], v[100:101], v[28:29], v[160:161]
	v_pk_fma_f32 v[158:159], v[100:101], v[30:31], v[158:159]
	v_pk_fma_f32 v[40:41], v[98:99], v[30:31], v[40:41]
	v_pk_fma_f32 v[156:157], v[100:101], v[32:33], v[156:157]
	v_add_f32_e32 v177, v160, v161
	v_add_f32_e32 v179, v158, v159
	v_add_f32_e32 v180, v40, v41
	v_add_f32_e32 v181, v156, v157
	ds_read2st64_b32 v[40:41], v163 offset0:184 offset1:188
	ds_read2st64_b32 v[156:157], v163 offset0:192 offset1:196
	ds_read2st64_b32 v[158:159], v163 offset0:200 offset1:204
	ds_read2st64_b32 v[160:161], v163 offset0:208 offset1:212
	v_pk_fma_f32 v[172:173], v[96:97], v[16:17], v[172:173]
	s_waitcnt lgkmcnt(3)
	v_mul_f32_e32 v105, v101, v40
	v_pk_fma_f32 v[172:173], v[100:101], v[26:27], v[172:173]
	s_addk_i32 s64, 0x800
	v_add_f32_e32 v175, v172, v173
	v_mul_f32_e32 v173, v42, v39
	v_pk_fma_f32 v[38:39], v[42:43], v[38:39], v[104:105]
	v_mov_b32_e32 v172, v104
	v_pk_fma_f32 v[38:39], v[46:47], v[36:37], v[38:39]
	s_waitcnt lgkmcnt(2)
	v_mul_f32_e32 v105, v101, v156
	v_pk_fma_f32 v[38:39], v[50:51], v[34:35], v[38:39]
	v_pk_fma_f32 v[172:173], v[44:45], v[36:37], v[172:173]
	v_pk_fma_f32 v[38:39], v[54:55], v[24:25], v[38:39]
	v_pk_fma_f32 v[172:173], v[48:49], v[34:35], v[172:173]
	v_pk_fma_f32 v[38:39], v[58:59], v[22:23], v[38:39]
	v_pk_fma_f32 v[172:173], v[52:53], v[24:25], v[172:173]
	v_pk_fma_f32 v[38:39], v[62:63], v[20:21], v[38:39]
	v_pk_fma_f32 v[172:173], v[56:57], v[22:23], v[172:173]
	v_pk_fma_f32 v[38:39], v[66:67], v[18:19], v[38:39]
	v_pk_fma_f32 v[172:173], v[60:61], v[20:21], v[172:173]
	v_pk_fma_f32 v[38:39], v[70:71], v[10:11], v[38:39]
	v_pk_fma_f32 v[172:173], v[64:65], v[18:19], v[172:173]
	v_pk_fma_f32 v[38:39], v[74:75], v[12:13], v[38:39]
	v_pk_fma_f32 v[172:173], v[68:69], v[10:11], v[172:173]
	v_pk_fma_f32 v[38:39], v[78:79], v[14:15], v[38:39]
	v_pk_fma_f32 v[172:173], v[72:73], v[12:13], v[172:173]
	v_pk_fma_f32 v[38:39], v[82:83], v[16:17], v[38:39]
	v_pk_fma_f32 v[172:173], v[76:77], v[14:15], v[172:173]
	v_pk_fma_f32 v[38:39], v[86:87], v[26:27], v[38:39]
	v_pk_fma_f32 v[172:173], v[80:81], v[16:17], v[172:173]
	v_pk_fma_f32 v[38:39], v[90:91], v[28:29], v[38:39]
	v_pk_fma_f32 v[172:173], v[84:85], v[26:27], v[172:173]
	v_pk_fma_f32 v[38:39], v[94:95], v[30:31], v[38:39]
	v_pk_fma_f32 v[172:173], v[88:89], v[28:29], v[172:173]
	v_pk_fma_f32 v[38:39], v[98:99], v[32:33], v[38:39]
	v_pk_fma_f32 v[172:173], v[92:93], v[30:31], v[172:173]
	v_add_f32_e32 v182, v38, v39
	v_mul_f32_e32 v39, v42, v37
	v_pk_fma_f32 v[36:37], v[42:43], v[36:37], v[104:105]
	v_mov_b32_e32 v38, v104
	v_pk_fma_f32 v[36:37], v[46:47], v[34:35], v[36:37]
	s_waitcnt lgkmcnt(1)
	v_mul_f32_e32 v105, v101, v158
	v_pk_fma_f32 v[36:37], v[50:51], v[24:25], v[36:37]
	v_pk_fma_f32 v[38:39], v[44:45], v[34:35], v[38:39]
	v_pk_fma_f32 v[36:37], v[54:55], v[22:23], v[36:37]
	v_pk_fma_f32 v[38:39], v[48:49], v[24:25], v[38:39]
	v_pk_fma_f32 v[36:37], v[58:59], v[20:21], v[36:37]
	v_pk_fma_f32 v[38:39], v[52:53], v[22:23], v[38:39]
	v_pk_fma_f32 v[36:37], v[62:63], v[18:19], v[36:37]
	v_pk_fma_f32 v[38:39], v[56:57], v[20:21], v[38:39]
	v_pk_fma_f32 v[36:37], v[66:67], v[10:11], v[36:37]
	v_pk_fma_f32 v[38:39], v[60:61], v[18:19], v[38:39]
	v_pk_fma_f32 v[36:37], v[70:71], v[12:13], v[36:37]
	v_pk_fma_f32 v[38:39], v[64:65], v[10:11], v[38:39]
	v_pk_fma_f32 v[36:37], v[74:75], v[14:15], v[36:37]
	v_pk_fma_f32 v[38:39], v[68:69], v[12:13], v[38:39]
	v_pk_fma_f32 v[36:37], v[78:79], v[16:17], v[36:37]
	v_pk_fma_f32 v[38:39], v[72:73], v[14:15], v[38:39]
	v_pk_fma_f32 v[36:37], v[82:83], v[26:27], v[36:37]
	v_pk_fma_f32 v[38:39], v[76:77], v[16:17], v[38:39]
	v_pk_fma_f32 v[36:37], v[86:87], v[28:29], v[36:37]
	v_pk_fma_f32 v[38:39], v[80:81], v[26:27], v[38:39]
	v_pk_fma_f32 v[36:37], v[90:91], v[30:31], v[36:37]
	v_pk_fma_f32 v[38:39], v[84:85], v[28:29], v[38:39]
	v_pk_fma_f32 v[36:37], v[94:95], v[32:33], v[36:37]
	v_pk_fma_f32 v[38:39], v[88:89], v[30:31], v[38:39]
	v_pk_fma_f32 v[36:37], v[98:99], v[40:41], v[36:37]
	v_pk_fma_f32 v[38:39], v[92:93], v[32:33], v[38:39]
	v_add_f32_e32 v184, v36, v37
	v_mul_f32_e32 v37, v42, v35
	v_pk_fma_f32 v[34:35], v[42:43], v[34:35], v[104:105]
	v_mov_b32_e32 v36, v104
	v_pk_fma_f32 v[34:35], v[46:47], v[24:25], v[34:35]
	s_waitcnt lgkmcnt(0)
	v_mul_f32_e32 v105, v101, v160
	v_pk_fma_f32 v[34:35], v[50:51], v[22:23], v[34:35]
	v_pk_fma_f32 v[36:37], v[44:45], v[24:25], v[36:37]
	v_pk_fma_f32 v[34:35], v[54:55], v[20:21], v[34:35]
	v_pk_fma_f32 v[36:37], v[48:49], v[22:23], v[36:37]
	v_pk_fma_f32 v[34:35], v[58:59], v[18:19], v[34:35]
	v_pk_fma_f32 v[36:37], v[52:53], v[20:21], v[36:37]
	v_pk_fma_f32 v[34:35], v[62:63], v[10:11], v[34:35]
	v_pk_fma_f32 v[36:37], v[56:57], v[18:19], v[36:37]
	v_pk_fma_f32 v[34:35], v[66:67], v[12:13], v[34:35]
	v_pk_fma_f32 v[36:37], v[60:61], v[10:11], v[36:37]
	v_pk_fma_f32 v[34:35], v[70:71], v[14:15], v[34:35]
	v_pk_fma_f32 v[36:37], v[64:65], v[12:13], v[36:37]
	v_pk_fma_f32 v[34:35], v[74:75], v[16:17], v[34:35]
	v_pk_fma_f32 v[36:37], v[68:69], v[14:15], v[36:37]
	v_pk_fma_f32 v[34:35], v[78:79], v[26:27], v[34:35]
	v_pk_fma_f32 v[36:37], v[72:73], v[16:17], v[36:37]
	v_pk_fma_f32 v[34:35], v[82:83], v[28:29], v[34:35]
	v_pk_fma_f32 v[36:37], v[76:77], v[26:27], v[36:37]
	v_pk_fma_f32 v[34:35], v[86:87], v[30:31], v[34:35]
	v_pk_fma_f32 v[36:37], v[80:81], v[28:29], v[36:37]
	v_pk_fma_f32 v[34:35], v[90:91], v[32:33], v[34:35]
	v_pk_fma_f32 v[36:37], v[84:85], v[30:31], v[36:37]
	v_pk_fma_f32 v[34:35], v[94:95], v[40:41], v[34:35]
	v_pk_fma_f32 v[36:37], v[88:89], v[32:33], v[36:37]
	v_pk_fma_f32 v[34:35], v[98:99], v[156:157], v[34:35]
	v_pk_fma_f32 v[36:37], v[92:93], v[40:41], v[36:37]
	v_add_f32_e32 v186, v34, v35
	v_mul_f32_e32 v35, v42, v25
	v_mov_b32_e32 v34, v104
	v_pk_fma_f32 v[24:25], v[42:43], v[24:25], v[104:105]
	v_pk_fma_f32 v[34:35], v[44:45], v[22:23], v[34:35]
	v_pk_fma_f32 v[24:25], v[46:47], v[22:23], v[24:25]
	v_pk_fma_f32 v[34:35], v[48:49], v[20:21], v[34:35]
	v_pk_fma_f32 v[24:25], v[50:51], v[20:21], v[24:25]
	v_pk_fma_f32 v[34:35], v[52:53], v[18:19], v[34:35]
	v_pk_fma_f32 v[24:25], v[54:55], v[18:19], v[24:25]
	v_pk_fma_f32 v[34:35], v[56:57], v[10:11], v[34:35]
	v_pk_fma_f32 v[24:25], v[58:59], v[10:11], v[24:25]
	v_pk_fma_f32 v[34:35], v[60:61], v[12:13], v[34:35]
	v_pk_fma_f32 v[24:25], v[62:63], v[12:13], v[24:25]
	v_pk_fma_f32 v[34:35], v[64:65], v[14:15], v[34:35]
	v_pk_fma_f32 v[24:25], v[66:67], v[14:15], v[24:25]
	v_pk_fma_f32 v[34:35], v[68:69], v[16:17], v[34:35]
	v_pk_fma_f32 v[24:25], v[70:71], v[16:17], v[24:25]
	v_pk_fma_f32 v[34:35], v[72:73], v[26:27], v[34:35]
	v_pk_fma_f32 v[24:25], v[74:75], v[26:27], v[24:25]
	v_pk_fma_f32 v[34:35], v[76:77], v[28:29], v[34:35]
	v_pk_fma_f32 v[24:25], v[78:79], v[28:29], v[24:25]
	v_pk_fma_f32 v[34:35], v[80:81], v[30:31], v[34:35]
	v_pk_fma_f32 v[24:25], v[82:83], v[30:31], v[24:25]
	v_pk_fma_f32 v[34:35], v[84:85], v[32:33], v[34:35]
	v_pk_fma_f32 v[24:25], v[86:87], v[32:33], v[24:25]
	v_pk_fma_f32 v[34:35], v[88:89], v[40:41], v[34:35]
	v_pk_fma_f32 v[24:25], v[90:91], v[40:41], v[24:25]
	v_pk_fma_f32 v[34:35], v[92:93], v[156:157], v[34:35]
	v_pk_fma_f32 v[38:39], v[96:97], v[40:41], v[38:39]
	v_pk_fma_f32 v[36:37], v[96:97], v[156:157], v[36:37]
	v_pk_fma_f32 v[24:25], v[94:95], v[156:157], v[24:25]
	v_pk_fma_f32 v[34:35], v[96:97], v[158:159], v[34:35]
	v_pk_fma_f32 v[38:39], v[100:101], v[156:157], v[38:39]
	v_pk_fma_f32 v[36:37], v[100:101], v[158:159], v[36:37]
	v_pk_fma_f32 v[24:25], v[98:99], v[158:159], v[24:25]
	v_pk_fma_f32 v[34:35], v[100:101], v[160:161], v[34:35]
	v_add_f32_e32 v185, v38, v39
	v_add_f32_e32 v187, v36, v37
	v_add_f32_e32 v188, v24, v25
	v_add_f32_e32 v189, v34, v35
	ds_read2st64_b32 v[24:25], v163 offset0:216 offset1:220
	ds_read2st64_b32 v[34:35], v163 offset0:224 offset1:228
	ds_read2st64_b32 v[36:37], v163 offset0:232 offset1:236
	ds_read2st64_b32 v[38:39], v163 offset0:240 offset1:244
	v_pk_fma_f32 v[172:173], v[96:97], v[32:33], v[172:173]
	s_waitcnt lgkmcnt(3)
	v_mul_f32_e32 v105, v101, v24
	v_pk_fma_f32 v[172:173], v[100:101], v[40:41], v[172:173]
	s_waitcnt lgkmcnt(0)
	v_add_f32_e32 v183, v172, v173
	v_mul_f32_e32 v173, v42, v23
	v_pk_fma_f32 v[22:23], v[42:43], v[22:23], v[104:105]
	v_mov_b32_e32 v172, v104
	v_pk_fma_f32 v[22:23], v[46:47], v[20:21], v[22:23]
	v_mul_f32_e32 v105, v101, v34
	v_pk_fma_f32 v[22:23], v[50:51], v[18:19], v[22:23]
	v_pk_fma_f32 v[172:173], v[44:45], v[20:21], v[172:173]
	v_pk_fma_f32 v[22:23], v[54:55], v[10:11], v[22:23]
	v_pk_fma_f32 v[172:173], v[48:49], v[18:19], v[172:173]
	v_pk_fma_f32 v[22:23], v[58:59], v[12:13], v[22:23]
	v_pk_fma_f32 v[172:173], v[52:53], v[10:11], v[172:173]
	v_pk_fma_f32 v[22:23], v[62:63], v[14:15], v[22:23]
	v_pk_fma_f32 v[172:173], v[56:57], v[12:13], v[172:173]
	v_pk_fma_f32 v[22:23], v[66:67], v[16:17], v[22:23]
	v_pk_fma_f32 v[172:173], v[60:61], v[14:15], v[172:173]
	v_pk_fma_f32 v[22:23], v[70:71], v[26:27], v[22:23]
	v_pk_fma_f32 v[172:173], v[64:65], v[16:17], v[172:173]
	v_pk_fma_f32 v[22:23], v[74:75], v[28:29], v[22:23]
	v_pk_fma_f32 v[172:173], v[68:69], v[26:27], v[172:173]
	v_pk_fma_f32 v[22:23], v[78:79], v[30:31], v[22:23]
	v_pk_fma_f32 v[172:173], v[72:73], v[28:29], v[172:173]
	v_pk_fma_f32 v[22:23], v[82:83], v[32:33], v[22:23]
	v_pk_fma_f32 v[172:173], v[76:77], v[30:31], v[172:173]
	v_pk_fma_f32 v[22:23], v[86:87], v[40:41], v[22:23]
	v_pk_fma_f32 v[172:173], v[80:81], v[32:33], v[172:173]
	v_pk_fma_f32 v[22:23], v[90:91], v[156:157], v[22:23]
	v_pk_fma_f32 v[172:173], v[84:85], v[40:41], v[172:173]
	v_pk_fma_f32 v[22:23], v[94:95], v[158:159], v[22:23]
	v_pk_fma_f32 v[172:173], v[88:89], v[156:157], v[172:173]
	v_pk_fma_f32 v[22:23], v[98:99], v[160:161], v[22:23]
	v_pk_fma_f32 v[172:173], v[92:93], v[158:159], v[172:173]
	v_add_f32_e32 v190, v22, v23
	v_mul_f32_e32 v23, v42, v21
	v_pk_fma_f32 v[20:21], v[42:43], v[20:21], v[104:105]
	v_pk_fma_f32 v[172:173], v[96:97], v[160:161], v[172:173]
	v_pk_fma_f32 v[20:21], v[46:47], v[18:19], v[20:21]
	v_pk_fma_f32 v[172:173], v[100:101], v[24:25], v[172:173]
	v_pk_fma_f32 v[20:21], v[50:51], v[10:11], v[20:21]
	v_mov_b32_e32 v22, v104
	v_pk_fma_f32 v[20:21], v[54:55], v[12:13], v[20:21]
	v_mul_f32_e32 v105, v101, v36
	v_pk_fma_f32 v[20:21], v[58:59], v[14:15], v[20:21]
	v_add_f32_e32 v172, v172, v173
	v_pk_fma_f32 v[20:21], v[62:63], v[16:17], v[20:21]
	v_pk_fma_f32 v[22:23], v[44:45], v[18:19], v[22:23]
	v_pk_fma_f32 v[20:21], v[66:67], v[26:27], v[20:21]
	v_pk_fma_f32 v[22:23], v[48:49], v[10:11], v[22:23]
	v_pk_fma_f32 v[20:21], v[70:71], v[28:29], v[20:21]
	v_pk_fma_f32 v[22:23], v[52:53], v[12:13], v[22:23]
	v_pk_fma_f32 v[20:21], v[74:75], v[30:31], v[20:21]
	v_pk_fma_f32 v[22:23], v[56:57], v[14:15], v[22:23]
	v_pk_fma_f32 v[20:21], v[78:79], v[32:33], v[20:21]
	v_pk_fma_f32 v[22:23], v[60:61], v[16:17], v[22:23]
	v_pk_fma_f32 v[20:21], v[82:83], v[40:41], v[20:21]
	v_pk_fma_f32 v[22:23], v[64:65], v[26:27], v[22:23]
	v_pk_fma_f32 v[20:21], v[86:87], v[156:157], v[20:21]
	v_pk_fma_f32 v[22:23], v[68:69], v[28:29], v[22:23]
	v_pk_fma_f32 v[20:21], v[90:91], v[158:159], v[20:21]
	v_pk_fma_f32 v[22:23], v[72:73], v[30:31], v[22:23]
	v_pk_fma_f32 v[20:21], v[94:95], v[160:161], v[20:21]
	v_pk_fma_f32 v[22:23], v[76:77], v[32:33], v[22:23]
	v_pk_fma_f32 v[20:21], v[98:99], v[24:25], v[20:21]
	v_pk_fma_f32 v[22:23], v[80:81], v[40:41], v[22:23]
	v_add_f32_e32 v173, v20, v21
	v_mul_f32_e32 v21, v42, v19
	v_pk_fma_f32 v[18:19], v[42:43], v[18:19], v[104:105]
	v_pk_fma_f32 v[22:23], v[84:85], v[156:157], v[22:23]
	v_pk_fma_f32 v[18:19], v[46:47], v[10:11], v[18:19]
	v_pk_fma_f32 v[22:23], v[88:89], v[158:159], v[22:23]
	v_pk_fma_f32 v[18:19], v[50:51], v[12:13], v[18:19]
	v_pk_fma_f32 v[22:23], v[92:93], v[160:161], v[22:23]
	v_pk_fma_f32 v[18:19], v[54:55], v[14:15], v[18:19]
	v_pk_fma_f32 v[22:23], v[96:97], v[24:25], v[22:23]
	v_pk_fma_f32 v[18:19], v[58:59], v[16:17], v[18:19]
	v_pk_fma_f32 v[22:23], v[100:101], v[34:35], v[22:23]
	v_pk_fma_f32 v[18:19], v[62:63], v[26:27], v[18:19]
	v_add_f32_e32 v22, v22, v23
	v_pk_fma_f32 v[18:19], v[66:67], v[28:29], v[18:19]
	v_mov_b32_e32 v20, v104
	v_pk_fma_f32 v[18:19], v[70:71], v[30:31], v[18:19]
	v_mul_f32_e32 v105, v101, v38
	v_pk_fma_f32 v[18:19], v[74:75], v[32:33], v[18:19]
	v_pk_fma_f32 v[20:21], v[44:45], v[10:11], v[20:21]
	v_pk_fma_f32 v[18:19], v[78:79], v[40:41], v[18:19]
	v_pk_fma_f32 v[20:21], v[48:49], v[12:13], v[20:21]
	v_pk_fma_f32 v[18:19], v[82:83], v[156:157], v[18:19]
	v_pk_fma_f32 v[20:21], v[52:53], v[14:15], v[20:21]
	v_pk_fma_f32 v[18:19], v[86:87], v[158:159], v[18:19]
	v_pk_fma_f32 v[20:21], v[56:57], v[16:17], v[20:21]
	v_pk_fma_f32 v[18:19], v[90:91], v[160:161], v[18:19]
	v_pk_fma_f32 v[20:21], v[60:61], v[26:27], v[20:21]
	v_pk_fma_f32 v[18:19], v[94:95], v[24:25], v[18:19]
	v_pk_fma_f32 v[20:21], v[64:65], v[28:29], v[20:21]
	v_pk_fma_f32 v[18:19], v[98:99], v[34:35], v[18:19]
	v_pk_fma_f32 v[20:21], v[68:69], v[30:31], v[20:21]
	v_add_f32_e32 v23, v18, v19
	v_mul_f32_e32 v19, v42, v11
	v_mov_b32_e32 v18, v104
	v_pk_fma_f32 v[10:11], v[42:43], v[10:11], v[104:105]
	v_pk_fma_f32 v[18:19], v[44:45], v[12:13], v[18:19]
	v_pk_fma_f32 v[10:11], v[46:47], v[12:13], v[10:11]
	v_pk_fma_f32 v[12:13], v[48:49], v[14:15], v[18:19]
	v_pk_fma_f32 v[10:11], v[50:51], v[14:15], v[10:11]
	v_pk_fma_f32 v[12:13], v[52:53], v[16:17], v[12:13]
	v_pk_fma_f32 v[10:11], v[54:55], v[16:17], v[10:11]
	v_pk_fma_f32 v[12:13], v[56:57], v[26:27], v[12:13]
	v_pk_fma_f32 v[10:11], v[58:59], v[26:27], v[10:11]
	v_pk_fma_f32 v[12:13], v[60:61], v[28:29], v[12:13]
	v_pk_fma_f32 v[10:11], v[62:63], v[28:29], v[10:11]
	v_pk_fma_f32 v[12:13], v[64:65], v[30:31], v[12:13]
	v_pk_fma_f32 v[10:11], v[66:67], v[30:31], v[10:11]
	v_pk_fma_f32 v[12:13], v[68:69], v[32:33], v[12:13]
	v_pk_fma_f32 v[20:21], v[72:73], v[32:33], v[20:21]
	v_pk_fma_f32 v[10:11], v[70:71], v[32:33], v[10:11]
	v_pk_fma_f32 v[12:13], v[72:73], v[40:41], v[12:13]
	v_pk_fma_f32 v[20:21], v[76:77], v[40:41], v[20:21]
	v_pk_fma_f32 v[10:11], v[74:75], v[40:41], v[10:11]
	v_pk_fma_f32 v[12:13], v[76:77], v[156:157], v[12:13]
	v_pk_fma_f32 v[20:21], v[80:81], v[156:157], v[20:21]
	v_pk_fma_f32 v[10:11], v[78:79], v[156:157], v[10:11]
	v_pk_fma_f32 v[12:13], v[80:81], v[158:159], v[12:13]
	v_pk_fma_f32 v[20:21], v[84:85], v[158:159], v[20:21]
	v_pk_fma_f32 v[10:11], v[82:83], v[158:159], v[10:11]
	v_pk_fma_f32 v[12:13], v[84:85], v[160:161], v[12:13]
	v_pk_fma_f32 v[20:21], v[88:89], v[160:161], v[20:21]
	v_pk_fma_f32 v[10:11], v[86:87], v[160:161], v[10:11]
	v_pk_fma_f32 v[12:13], v[88:89], v[24:25], v[12:13]
	v_pk_fma_f32 v[20:21], v[92:93], v[24:25], v[20:21]
	v_pk_fma_f32 v[10:11], v[90:91], v[24:25], v[10:11]
	v_pk_fma_f32 v[12:13], v[92:93], v[34:35], v[12:13]
	v_pk_fma_f32 v[20:21], v[96:97], v[34:35], v[20:21]
	v_pk_fma_f32 v[10:11], v[94:95], v[34:35], v[10:11]
	v_pk_fma_f32 v[12:13], v[96:97], v[36:37], v[12:13]
	v_pk_fma_f32 v[20:21], v[100:101], v[36:37], v[20:21]
	v_pk_fma_f32 v[10:11], v[98:99], v[36:37], v[10:11]
	v_pk_fma_f32 v[12:13], v[100:101], v[38:39], v[12:13]
	v_add_u32_e32 v105, s6, v162
	v_add_f32_e32 v20, v20, v21
	v_add_f32_e32 v10, v10, v11
	v_add_f32_e32 v11, v12, v13
	s_barrier
	ds_write2st64_b32 v163, v164, v165 offset1:4
	ds_write2st64_b32 v163, v166, v167 offset0:8 offset1:12
	ds_write2st64_b32 v163, v168, v169 offset0:16 offset1:20
	ds_write2st64_b32 v163, v170, v171 offset0:24 offset1:28
	ds_write2st64_b32 v163, v174, v175 offset0:32 offset1:36
	ds_write2st64_b32 v163, v176, v177 offset0:40 offset1:44
	ds_write2st64_b32 v163, v178, v179 offset0:48 offset1:52
	ds_write2st64_b32 v163, v180, v181 offset0:56 offset1:60
	ds_write2st64_b32 v163, v182, v183 offset0:64 offset1:68
	ds_write2st64_b32 v163, v184, v185 offset0:72 offset1:76
	ds_write2st64_b32 v163, v186, v187 offset0:80 offset1:84
	ds_write2st64_b32 v163, v188, v189 offset0:88 offset1:92
	ds_write2st64_b32 v163, v190, v172 offset0:96 offset1:100
	ds_write2st64_b32 v163, v173, v22 offset0:104 offset1:108
	ds_write2st64_b32 v163, v23, v20 offset0:112 offset1:116
	ds_write2st64_b32 v163, v10, v11 offset0:120 offset1:124
	s_waitcnt lgkmcnt(0)
	s_barrier
	ds_read_b128 v[38:41], v105
	ds_read_b128 v[14:17], v105 offset:49152
	ds_read_b128 v[34:37], v105 offset:8192
	ds_read_b128 v[30:33], v105 offset:16384
	ds_read_b128 v[26:29], v105 offset:24576
	s_waitcnt lgkmcnt(4)
	v_mov_b32_e32 v10, v39
	v_mov_b32_e32 v11, v40
	v_mov_b32_e32 v12, v38
	v_mov_b32_e32 v13, v41
	v_pk_add_f32 v[10:11], v[10:11], v[12:13]
	s_waitcnt lgkmcnt(2)
	v_mov_b32_e32 v12, v34
	v_add_f32_e32 v160, v10, v11
	v_mov_b32_e32 v10, v35
	v_mov_b32_e32 v11, v36
	v_mov_b32_e32 v13, v37
	v_pk_add_f32 v[10:11], v[10:11], v[12:13]
	ds_read_b128 v[22:25], v105 offset:32768
	ds_read_b128 v[18:21], v105 offset:40960
	v_add_f32_e32 v161, v10, v11
	s_waitcnt lgkmcnt(3)
	v_mov_b32_e32 v10, v31
	v_mov_b32_e32 v11, v32
	v_mov_b32_e32 v12, v30
	v_mov_b32_e32 v13, v33
	v_pk_add_f32 v[10:11], v[10:11], v[12:13]
	s_waitcnt lgkmcnt(2)
	v_mov_b32_e32 v12, v26
	v_add_f32_e32 v162, v10, v11
	v_mov_b32_e32 v10, v27
	v_mov_b32_e32 v11, v28
	v_mov_b32_e32 v13, v29
	v_pk_add_f32 v[10:11], v[10:11], v[12:13]
	s_waitcnt lgkmcnt(1)
	v_mov_b32_e32 v12, v22
	v_add_f32_e32 v163, v10, v11
	v_mov_b32_e32 v10, v23
	v_mov_b32_e32 v11, v24
	v_mov_b32_e32 v13, v25
	v_pk_add_f32 v[10:11], v[10:11], v[12:13]
	s_waitcnt lgkmcnt(0)
	v_mov_b32_e32 v12, v18
	v_add_f32_e32 v164, v10, v11
	v_mov_b32_e32 v10, v19
	v_mov_b32_e32 v11, v20
	v_mov_b32_e32 v13, v21
	v_pk_add_f32 v[10:11], v[10:11], v[12:13]
	v_mov_b32_e32 v12, v14
	v_add_f32_e32 v165, v10, v11
	v_mov_b32_e32 v10, v15
	v_mov_b32_e32 v11, v16
	v_mov_b32_e32 v13, v17
	v_pk_add_f32 v[10:11], v[10:11], v[12:13]
	s_cmpk_gt_i32 s65, 0x1df
	v_add_f32_e32 v166, v10, v11
	ds_read_b128 v[10:13], v105 offset:57344
	s_waitcnt lgkmcnt(0)
	v_mov_b32_e32 v156, v11
	v_mov_b32_e32 v157, v12
	v_mov_b32_e32 v158, v10
	v_mov_b32_e32 v159, v13
	v_pk_add_f32 v[156:157], v[156:157], v[158:159]
	v_add_f32_dpp v158, v162, v162 quad_perm:[1,0,3,2] row_mask:0xf bank_mask:0xf bound_ctrl:1
	v_add_f32_e32 v105, v156, v157
	v_add_f32_dpp v156, v160, v160 quad_perm:[1,0,3,2] row_mask:0xf bank_mask:0xf bound_ctrl:1
	v_add_f32_dpp v157, v161, v161 quad_perm:[1,0,3,2] row_mask:0xf bank_mask:0xf bound_ctrl:1
	v_add_f32_dpp v159, v163, v163 quad_perm:[1,0,3,2] row_mask:0xf bank_mask:0xf bound_ctrl:1
	v_add_f32_dpp v156, v156, v156 quad_perm:[2,3,0,1] row_mask:0xf bank_mask:0xf bound_ctrl:1
	v_add_f32_dpp v157, v157, v157 quad_perm:[2,3,0,1] row_mask:0xf bank_mask:0xf bound_ctrl:1
	s_nop 0
	v_add_f32_dpp v156, v156, v156 row_half_mirror row_mask:0xf bank_mask:0xf bound_ctrl:1
	s_nop 0
	v_add_f32_dpp v157, v157, v157 row_half_mirror row_mask:0xf bank_mask:0xf bound_ctrl:1
	v_add_f32_dpp v158, v158, v158 quad_perm:[2,3,0,1] row_mask:0xf bank_mask:0xf bound_ctrl:1
	v_add_f32_dpp v156, v156, v156 row_mirror row_mask:0xf bank_mask:0xf bound_ctrl:1
	v_add_f32_dpp v157, v157, v157 row_mirror row_mask:0xf bank_mask:0xf bound_ctrl:1
	v_add_f32_dpp v158, v158, v158 row_half_mirror row_mask:0xf bank_mask:0xf bound_ctrl:1
	v_add_f32_dpp v156, v156, v156 row_bcast:15 row_mask:0xa bank_mask:0xf
	v_add_f32_dpp v159, v159, v159 quad_perm:[2,3,0,1] row_mask:0xf bank_mask:0xf bound_ctrl:1
	v_add_f32_dpp v158, v158, v158 row_mirror row_mask:0xf bank_mask:0xf bound_ctrl:1
	v_add_f32_dpp v157, v157, v157 row_bcast:15 row_mask:0xa bank_mask:0xf
	v_add_f32_dpp v160, v164, v164 quad_perm:[1,0,3,2] row_mask:0xf bank_mask:0xf bound_ctrl:1
	v_add_f32_dpp v159, v159, v159 row_half_mirror row_mask:0xf bank_mask:0xf bound_ctrl:1
	v_add_f32_dpp v158, v158, v158 row_bcast:15 row_mask:0xa bank_mask:0xf
	v_add_f32_dpp v160, v160, v160 quad_perm:[2,3,0,1] row_mask:0xf bank_mask:0xf bound_ctrl:1
	v_add_f32_dpp v159, v159, v159 row_mirror row_mask:0xf bank_mask:0xf bound_ctrl:1
	v_add_f32_dpp v161, v165, v165 quad_perm:[1,0,3,2] row_mask:0xf bank_mask:0xf bound_ctrl:1
	v_add_f32_dpp v160, v160, v160 row_half_mirror row_mask:0xf bank_mask:0xf bound_ctrl:1
	v_add_f32_dpp v159, v159, v159 row_bcast:15 row_mask:0xa bank_mask:0xf
	v_add_f32_dpp v161, v161, v161 quad_perm:[2,3,0,1] row_mask:0xf bank_mask:0xf bound_ctrl:1
	v_add_f32_dpp v160, v160, v160 row_mirror row_mask:0xf bank_mask:0xf bound_ctrl:1
	v_add_f32_dpp v162, v166, v166 quad_perm:[1,0,3,2] row_mask:0xf bank_mask:0xf bound_ctrl:1
	v_add_f32_dpp v161, v161, v161 row_half_mirror row_mask:0xf bank_mask:0xf bound_ctrl:1
	v_add_f32_dpp v160, v160, v160 row_bcast:15 row_mask:0xa bank_mask:0xf
	v_add_f32_dpp v162, v162, v162 quad_perm:[2,3,0,1] row_mask:0xf bank_mask:0xf bound_ctrl:1
	v_add_f32_dpp v161, v161, v161 row_mirror row_mask:0xf bank_mask:0xf bound_ctrl:1
	v_add_f32_dpp v105, v105, v105 quad_perm:[1,0,3,2] row_mask:0xf bank_mask:0xf bound_ctrl:1
	v_add_f32_dpp v162, v162, v162 row_half_mirror row_mask:0xf bank_mask:0xf bound_ctrl:1
	v_add_f32_dpp v161, v161, v161 row_bcast:15 row_mask:0xa bank_mask:0xf
	v_add_f32_dpp v105, v105, v105 quad_perm:[2,3,0,1] row_mask:0xf bank_mask:0xf bound_ctrl:1
	v_add_f32_dpp v162, v162, v162 row_mirror row_mask:0xf bank_mask:0xf bound_ctrl:1
	s_nop 0
	v_add_f32_dpp v105, v105, v105 row_half_mirror row_mask:0xf bank_mask:0xf bound_ctrl:1
	s_nop 0
	v_add_f32_dpp v162, v162, v162 row_bcast:15 row_mask:0xa bank_mask:0xf
	v_add_f32_dpp v105, v105, v105 row_mirror row_mask:0xf bank_mask:0xf bound_ctrl:1
	s_nop 1
	v_add_f32_dpp v105, v105, v105 row_bcast:15 row_mask:0xa bank_mask:0xf
	s_nop 1
	v_add_f32_dpp v156, v156, v156 row_bcast:31 row_mask:0xc bank_mask:0xf
	s_nop 0
	v_readlane_b32 s6, v156, 63
	s_nop 0
	v_add_f32_dpp v157, v157, v157 row_bcast:31 row_mask:0xc bank_mask:0xf
	v_fma_f32 v39, s6, v239, v39
	v_fma_f32 v38, s6, v239, v38
	v_add_f32_dpp v158, v158, v158 row_bcast:31 row_mask:0xc bank_mask:0xf
	v_fma_f32 v41, s6, v239, v41
	v_fmac_f32_e32 v40, s6, v239
	v_add_f32_dpp v159, v159, v159 row_bcast:31 row_mask:0xc bank_mask:0xf
	v_readlane_b32 s7, v157, 63
	v_readlane_b32 s8, v158, 63
	v_add_f32_dpp v160, v160, v160 row_bcast:31 row_mask:0xc bank_mask:0xf
	v_readlane_b32 s9, v159, 63
	v_pk_mul_f32 v[156:157], v[40:41], v[40:41]
	v_add_f32_dpp v161, v161, v161 row_bcast:31 row_mask:0xc bank_mask:0xf
	v_pk_mul_f32 v[158:159], v[38:39], v[38:39]
	v_readlane_b32 s10, v160, 63
	v_add_f32_dpp v162, v162, v162 row_bcast:31 row_mask:0xc bank_mask:0xf
	v_readlane_b32 s11, v161, 63
	v_pk_mov_b32 v[160:161], v[158:159], v[156:157] op_sel:[1,0]
	v_add_f32_dpp v105, v105, v105 row_bcast:31 row_mask:0xc bank_mask:0xf
	v_mov_b32_e32 v159, v157
	v_pk_add_f32 v[156:157], v[160:161], v[158:159]
	v_fma_f32 v35, s7, v239, v35
	v_fma_f32 v34, s7, v239, v34
	v_fma_f32 v37, s7, v239, v37
	v_fmac_f32_e32 v36, s7, v239
	v_readlane_b32 s67, v105, 63
	v_add_f32_e32 v105, v156, v157
	v_pk_mul_f32 v[156:157], v[36:37], v[36:37]
	v_pk_mul_f32 v[158:159], v[34:35], v[34:35]
	v_fma_f32 v31, s8, v239, v31
	v_pk_mov_b32 v[160:161], v[158:159], v[156:157] op_sel:[1,0]
	v_mov_b32_e32 v159, v157
	v_pk_add_f32 v[156:157], v[160:161], v[158:159]
	v_fma_f32 v30, s8, v239, v30
	v_fma_f32 v33, s8, v239, v33
	v_fmac_f32_e32 v32, s8, v239
	v_readlane_b32 s66, v162, 63
	v_add_f32_e32 v162, v156, v157
	v_pk_mul_f32 v[156:157], v[32:33], v[32:33]
	v_pk_mul_f32 v[158:159], v[30:31], v[30:31]
	v_fma_f32 v27, s9, v239, v27
	v_pk_mov_b32 v[160:161], v[158:159], v[156:157] op_sel:[1,0]
	v_mov_b32_e32 v159, v157
	v_pk_add_f32 v[156:157], v[160:161], v[158:159]
	v_fma_f32 v26, s9, v239, v26
	v_fma_f32 v29, s9, v239, v29
	v_fmac_f32_e32 v28, s9, v239
	v_add_f32_e32 v163, v156, v157
	v_pk_mul_f32 v[156:157], v[28:29], v[28:29]
	v_pk_mul_f32 v[158:159], v[26:27], v[26:27]
	v_fma_f32 v23, s10, v239, v23
	v_pk_mov_b32 v[160:161], v[158:159], v[156:157] op_sel:[1,0]
	v_mov_b32_e32 v159, v157
	v_pk_add_f32 v[156:157], v[160:161], v[158:159]
	v_fma_f32 v22, s10, v239, v22
	v_fma_f32 v25, s10, v239, v25
	v_fmac_f32_e32 v24, s10, v239
	v_add_f32_e32 v164, v156, v157
	v_pk_mul_f32 v[156:157], v[24:25], v[24:25]
	v_pk_mul_f32 v[158:159], v[22:23], v[22:23]
	v_fma_f32 v19, s11, v239, v19
	v_pk_mov_b32 v[160:161], v[158:159], v[156:157] op_sel:[1,0]
	v_mov_b32_e32 v159, v157
	v_pk_add_f32 v[156:157], v[160:161], v[158:159]
	v_fma_f32 v18, s11, v239, v18
	v_fma_f32 v21, s11, v239, v21
	v_fmac_f32_e32 v20, s11, v239
	v_add_f32_e32 v165, v156, v157
	v_pk_mul_f32 v[156:157], v[20:21], v[20:21]
	v_pk_mul_f32 v[158:159], v[18:19], v[18:19]
	v_fma_f32 v15, s66, v239, v15
	v_pk_mov_b32 v[160:161], v[158:159], v[156:157] op_sel:[1,0]
	v_mov_b32_e32 v159, v157
	v_pk_add_f32 v[156:157], v[160:161], v[158:159]
	v_fma_f32 v14, s66, v239, v14
	v_fma_f32 v17, s66, v239, v17
	v_fmac_f32_e32 v16, s66, v239
	v_add_f32_e32 v166, v156, v157
	v_pk_mul_f32 v[156:157], v[16:17], v[16:17]
	v_pk_mul_f32 v[158:159], v[14:15], v[14:15]
	v_fma_f32 v11, s67, v239, v11
	v_pk_mov_b32 v[160:161], v[158:159], v[156:157] op_sel:[1,0]
	v_mov_b32_e32 v159, v157
	v_pk_add_f32 v[156:157], v[160:161], v[158:159]
	v_fma_f32 v10, s67, v239, v10
	v_fma_f32 v13, s67, v239, v13
	v_fmac_f32_e32 v12, s67, v239
	v_add_f32_e32 v167, v156, v157
	v_pk_mul_f32 v[156:157], v[12:13], v[12:13]
	v_pk_mul_f32 v[158:159], v[10:11], v[10:11]
	v_add_f32_dpp v105, v105, v105 quad_perm:[1,0,3,2] row_mask:0xf bank_mask:0xf bound_ctrl:1
	v_pk_mov_b32 v[160:161], v[158:159], v[156:157] op_sel:[1,0]
	v_mov_b32_e32 v159, v157
	v_pk_add_f32 v[156:157], v[160:161], v[158:159]
	v_add_f32_dpp v105, v105, v105 quad_perm:[2,3,0,1] row_mask:0xf bank_mask:0xf bound_ctrl:1
	v_add_f32_e32 v156, v156, v157
	v_add_f32_dpp v157, v162, v162 quad_perm:[1,0,3,2] row_mask:0xf bank_mask:0xf bound_ctrl:1
	v_add_f32_dpp v105, v105, v105 row_half_mirror row_mask:0xf bank_mask:0xf bound_ctrl:1
	v_add_f32_dpp v158, v163, v163 quad_perm:[1,0,3,2] row_mask:0xf bank_mask:0xf bound_ctrl:1
	v_add_f32_dpp v157, v157, v157 quad_perm:[2,3,0,1] row_mask:0xf bank_mask:0xf bound_ctrl:1
	v_add_f32_dpp v105, v105, v105 row_mirror row_mask:0xf bank_mask:0xf bound_ctrl:1
	s_nop 0
	v_add_f32_dpp v157, v157, v157 row_half_mirror row_mask:0xf bank_mask:0xf bound_ctrl:1
	v_add_f32_dpp v158, v158, v158 quad_perm:[2,3,0,1] row_mask:0xf bank_mask:0xf bound_ctrl:1
	v_add_f32_dpp v105, v105, v105 row_bcast:15 row_mask:0xa bank_mask:0xf
	v_add_f32_dpp v157, v157, v157 row_mirror row_mask:0xf bank_mask:0xf bound_ctrl:1
	v_add_f32_dpp v159, v164, v164 quad_perm:[1,0,3,2] row_mask:0xf bank_mask:0xf bound_ctrl:1
	v_add_f32_dpp v158, v158, v158 row_half_mirror row_mask:0xf bank_mask:0xf bound_ctrl:1
	v_add_f32_dpp v157, v157, v157 row_bcast:15 row_mask:0xa bank_mask:0xf
	v_add_f32_dpp v159, v159, v159 quad_perm:[2,3,0,1] row_mask:0xf bank_mask:0xf bound_ctrl:1
	v_add_f32_dpp v158, v158, v158 row_mirror row_mask:0xf bank_mask:0xf bound_ctrl:1
	v_add_f32_dpp v160, v165, v165 quad_perm:[1,0,3,2] row_mask:0xf bank_mask:0xf bound_ctrl:1
	v_add_f32_dpp v159, v159, v159 row_half_mirror row_mask:0xf bank_mask:0xf bound_ctrl:1
	v_add_f32_dpp v158, v158, v158 row_bcast:15 row_mask:0xa bank_mask:0xf
	v_add_f32_dpp v160, v160, v160 quad_perm:[2,3,0,1] row_mask:0xf bank_mask:0xf bound_ctrl:1
	v_add_f32_dpp v159, v159, v159 row_mirror row_mask:0xf bank_mask:0xf bound_ctrl:1
	v_add_f32_dpp v161, v166, v166 quad_perm:[1,0,3,2] row_mask:0xf bank_mask:0xf bound_ctrl:1
	v_add_f32_dpp v160, v160, v160 row_half_mirror row_mask:0xf bank_mask:0xf bound_ctrl:1
	v_add_f32_dpp v159, v159, v159 row_bcast:15 row_mask:0xa bank_mask:0xf
	v_add_f32_dpp v161, v161, v161 quad_perm:[2,3,0,1] row_mask:0xf bank_mask:0xf bound_ctrl:1
	v_add_f32_dpp v160, v160, v160 row_mirror row_mask:0xf bank_mask:0xf bound_ctrl:1
	v_add_f32_dpp v162, v167, v167 quad_perm:[1,0,3,2] row_mask:0xf bank_mask:0xf bound_ctrl:1
	v_add_f32_dpp v161, v161, v161 row_half_mirror row_mask:0xf bank_mask:0xf bound_ctrl:1
	v_add_f32_dpp v160, v160, v160 row_bcast:15 row_mask:0xa bank_mask:0xf
	v_add_f32_dpp v162, v162, v162 quad_perm:[2,3,0,1] row_mask:0xf bank_mask:0xf bound_ctrl:1
	v_add_f32_dpp v161, v161, v161 row_mirror row_mask:0xf bank_mask:0xf bound_ctrl:1
	v_add_f32_dpp v156, v156, v156 quad_perm:[1,0,3,2] row_mask:0xf bank_mask:0xf bound_ctrl:1
	v_add_f32_dpp v162, v162, v162 row_half_mirror row_mask:0xf bank_mask:0xf bound_ctrl:1
	v_add_f32_dpp v161, v161, v161 row_bcast:15 row_mask:0xa bank_mask:0xf
	v_add_f32_dpp v156, v156, v156 quad_perm:[2,3,0,1] row_mask:0xf bank_mask:0xf bound_ctrl:1
	v_add_f32_dpp v162, v162, v162 row_mirror row_mask:0xf bank_mask:0xf bound_ctrl:1
	s_nop 0
	v_add_f32_dpp v156, v156, v156 row_half_mirror row_mask:0xf bank_mask:0xf bound_ctrl:1
	s_nop 0
	v_add_f32_dpp v162, v162, v162 row_bcast:15 row_mask:0xa bank_mask:0xf
	v_add_f32_dpp v156, v156, v156 row_mirror row_mask:0xf bank_mask:0xf bound_ctrl:1
	s_nop 1
	v_add_f32_dpp v156, v156, v156 row_bcast:15 row_mask:0xa bank_mask:0xf
	s_nop 1
	v_add_f32_dpp v105, v105, v105 row_bcast:31 row_mask:0xc bank_mask:0xf
	s_nop 0
	v_readlane_b32 s8, v105, 63
	s_nop 0
	v_add_f32_dpp v157, v157, v157 row_bcast:31 row_mask:0xc bank_mask:0xf
	v_fma_f32 v105, s8, v235, v225
	v_readlane_b32 s9, v157, 63
	v_add_f32_dpp v158, v158, v158 row_bcast:31 row_mask:0xc bank_mask:0xf
	s_nop 0
	v_readlane_b32 s69, v158, 63
	s_nop 0
	v_add_f32_dpp v159, v159, v159 row_bcast:31 row_mask:0xc bank_mask:0xf
	s_nop 0
	v_readlane_b32 s68, v159, 63
	s_nop 0
	v_add_f32_dpp v160, v160, v160 row_bcast:31 row_mask:0xc bank_mask:0xf
	s_nop 0
	v_readlane_b32 s67, v160, 63
	s_nop 0
	v_add_f32_dpp v161, v161, v161 row_bcast:31 row_mask:0xc bank_mask:0xf
	s_nop 0
	v_readlane_b32 s66, v161, 63
	s_nop 0
	v_add_f32_dpp v162, v162, v162 row_bcast:31 row_mask:0xc bank_mask:0xf
	v_mov_b32_e32 v163, v131
	v_readlane_b32 s7, v162, 63
	s_nop 0
	v_mov_b32_dpp v163, v156 row_bcast:31 row_mask:0xc bank_mask:0xf
	v_add_f32_e32 v156, v156, v163
	s_nop 0
	v_readlane_b32 s6, v156, 63
	v_rsq_f32_e32 v156, v105
	s_nop 0
	v_pk_mul_f32 v[38:39], v[38:39], v[156:157] op_sel_hi:[1,0]
	v_pk_fma_f32 v[38:39], v[2:3], v[38:39], v[6:7]
	v_pk_mul_f32 v[40:41], v[40:41], v[156:157] op_sel_hi:[1,0]
	v_mul_f32_e32 v105, 0xbfb8aa3b, v38
	v_exp_f32_e32 v105, v105
	v_pk_fma_f32 v[40:41], v[4:5], v[40:41], v[8:9]
	v_add_f32_e32 v105, 1.0, v105
	v_rcp_f32_e32 v156, v105
	v_mul_f32_e32 v105, 0xbfb8aa3b, v39
	v_exp_f32_e32 v105, v105
	s_nop 0
	v_add_f32_e32 v105, 1.0, v105
	v_rcp_f32_e32 v157, v105
	v_mul_f32_e32 v105, 0xbfb8aa3b, v40
	v_exp_f32_e32 v105, v105
	v_pk_mul_f32 v[38:39], v[38:39], v[156:157]
	v_add_f32_e32 v105, 1.0, v105
	v_rcp_f32_e32 v156, v105
	v_mul_f32_e32 v105, 0xbfb8aa3b, v41
	v_exp_f32_e32 v105, v105
	s_nop 0
	v_add_f32_e32 v105, 1.0, v105
	v_rcp_f32_e32 v157, v105
	s_nop 0
	v_pk_mul_f32 v[40:41], v[40:41], v[156:157]
	v_cvt_pk_bf16_f32 v156, v38, v39
	v_fma_f32 v39, s9, v235, v225
	v_cvt_pk_bf16_f32 v157, v40, v41
	v_rsq_f32_e32 v40, v39
	v_lshlrev_b32_e32 v38, 3, v130
	global_store_dwordx2 v38, v[156:157], s[56:57] offset:512
	v_pk_mul_f32 v[34:35], v[34:35], v[40:41] op_sel_hi:[1,0]
	s_nop 0
	v_pk_fma_f32 v[34:35], v[2:3], v[34:35], v[6:7]
	v_pk_mul_f32 v[36:37], v[36:37], v[40:41] op_sel_hi:[1,0]
	v_mul_f32_e32 v39, 0xbfb8aa3b, v34
	v_exp_f32_e32 v39, v39
	v_pk_fma_f32 v[36:37], v[4:5], v[36:37], v[8:9]
	v_add_f32_e32 v39, 1.0, v39
	v_rcp_f32_e32 v40, v39
	v_mul_f32_e32 v39, 0xbfb8aa3b, v35
	v_exp_f32_e32 v39, v39
	s_nop 0
	v_add_f32_e32 v39, 1.0, v39
	v_rcp_f32_e32 v41, v39
	v_mul_f32_e32 v39, 0xbfb8aa3b, v36
	v_exp_f32_e32 v39, v39
	v_pk_mul_f32 v[34:35], v[34:35], v[40:41]
	s_nop 0
	v_cvt_pk_bf16_f32 v34, v34, v35
	v_add_f32_e32 v39, 1.0, v39
	v_rcp_f32_e32 v40, v39
	v_mul_f32_e32 v39, 0xbfb8aa3b, v37
	v_exp_f32_e32 v39, v39
	s_nop 0
	v_add_f32_e32 v39, 1.0, v39
	v_rcp_f32_e32 v41, v39
	s_nop 0
	v_pk_mul_f32 v[36:37], v[36:37], v[40:41]
	v_cvt_pk_bf16_f32 v35, v36, v37
	global_store_dwordx2 v38, v[34:35], s[54:55] offset:512
	v_fma_f32 v34, s69, v235, v225
	v_rsq_f32_e32 v34, v34
	s_nop 0
	v_pk_mul_f32 v[30:31], v[30:31], v[34:35] op_sel_hi:[1,0]
	v_pk_fma_f32 v[30:31], v[2:3], v[30:31], v[6:7]
	v_pk_mul_f32 v[32:33], v[32:33], v[34:35] op_sel_hi:[1,0]
	v_mul_f32_e32 v34, 0xbfb8aa3b, v30
	v_mul_f32_e32 v35, 0xbfb8aa3b, v31
	v_exp_f32_e32 v34, v34
	v_exp_f32_e32 v35, v35
	v_pk_fma_f32 v[32:33], v[4:5], v[32:33], v[8:9]
	v_add_f32_e32 v34, 1.0, v34
	v_add_f32_e32 v35, 1.0, v35
	v_rcp_f32_e32 v34, v34
	v_rcp_f32_e32 v35, v35
	s_nop 0
	v_pk_mul_f32 v[30:31], v[30:31], v[34:35]
	v_mul_f32_e32 v34, 0xbfb8aa3b, v32
	v_mul_f32_e32 v35, 0xbfb8aa3b, v33
	v_exp_f32_e32 v34, v34
	v_exp_f32_e32 v35, v35
	v_cvt_pk_bf16_f32 v30, v30, v31
	v_add_f32_e32 v34, 1.0, v34
	v_add_f32_e32 v35, 1.0, v35
	v_rcp_f32_e32 v34, v34
	v_rcp_f32_e32 v35, v35
	s_nop 0
	v_pk_mul_f32 v[32:33], v[32:33], v[34:35]
	v_cvt_pk_bf16_f32 v31, v32, v33
	global_store_dwordx2 v38, v[30:31], s[52:53] offset:512
	v_fma_f32 v30, s68, v235, v225
	v_rsq_f32_e32 v30, v30
	s_nop 0
	v_pk_mul_f32 v[26:27], v[26:27], v[30:31] op_sel_hi:[1,0]
	v_pk_fma_f32 v[26:27], v[2:3], v[26:27], v[6:7]
	v_pk_mul_f32 v[28:29], v[28:29], v[30:31] op_sel_hi:[1,0]
	v_mul_f32_e32 v30, 0xbfb8aa3b, v26
	v_mul_f32_e32 v31, 0xbfb8aa3b, v27
	v_exp_f32_e32 v30, v30
	v_exp_f32_e32 v31, v31
	v_pk_fma_f32 v[28:29], v[4:5], v[28:29], v[8:9]
	v_add_f32_e32 v30, 1.0, v30
	v_add_f32_e32 v31, 1.0, v31
	v_rcp_f32_e32 v30, v30
	v_rcp_f32_e32 v31, v31
	s_nop 0
	v_pk_mul_f32 v[26:27], v[26:27], v[30:31]
	v_mul_f32_e32 v30, 0xbfb8aa3b, v28
	v_mul_f32_e32 v31, 0xbfb8aa3b, v29
	v_exp_f32_e32 v30, v30
	v_exp_f32_e32 v31, v31
	v_cvt_pk_bf16_f32 v26, v26, v27
	v_add_f32_e32 v30, 1.0, v30
	v_add_f32_e32 v31, 1.0, v31
	v_rcp_f32_e32 v30, v30
	v_rcp_f32_e32 v31, v31
	s_nop 0
	v_pk_mul_f32 v[28:29], v[28:29], v[30:31]
	v_cvt_pk_bf16_f32 v27, v28, v29
	global_store_dwordx2 v38, v[26:27], s[50:51] offset:512
	v_fma_f32 v26, s67, v235, v225
	v_rsq_f32_e32 v26, v26
	s_nop 0
	v_pk_mul_f32 v[22:23], v[22:23], v[26:27] op_sel_hi:[1,0]
	v_pk_fma_f32 v[22:23], v[2:3], v[22:23], v[6:7]
	v_pk_mul_f32 v[24:25], v[24:25], v[26:27] op_sel_hi:[1,0]
	v_mul_f32_e32 v26, 0xbfb8aa3b, v22
	v_mul_f32_e32 v27, 0xbfb8aa3b, v23
	v_exp_f32_e32 v26, v26
	v_exp_f32_e32 v27, v27
	v_pk_fma_f32 v[24:25], v[4:5], v[24:25], v[8:9]
	v_add_f32_e32 v26, 1.0, v26
	v_add_f32_e32 v27, 1.0, v27
	v_rcp_f32_e32 v26, v26
	v_rcp_f32_e32 v27, v27
	s_nop 0
	v_pk_mul_f32 v[22:23], v[22:23], v[26:27]
	v_mul_f32_e32 v26, 0xbfb8aa3b, v24
	v_mul_f32_e32 v27, 0xbfb8aa3b, v25
	v_exp_f32_e32 v26, v26
	v_exp_f32_e32 v27, v27
	v_cvt_pk_bf16_f32 v22, v22, v23
	v_add_f32_e32 v26, 1.0, v26
	v_add_f32_e32 v27, 1.0, v27
	v_rcp_f32_e32 v26, v26
	v_rcp_f32_e32 v27, v27
	s_nop 0
	v_pk_mul_f32 v[24:25], v[24:25], v[26:27]
	v_cvt_pk_bf16_f32 v23, v24, v25
	global_store_dwordx2 v38, v[22:23], s[48:49] offset:512
	v_fma_f32 v22, s66, v235, v225
	v_rsq_f32_e32 v22, v22
	s_nop 0
	v_pk_mul_f32 v[18:19], v[18:19], v[22:23] op_sel_hi:[1,0]
	v_pk_fma_f32 v[18:19], v[2:3], v[18:19], v[6:7]
	v_pk_mul_f32 v[20:21], v[20:21], v[22:23] op_sel_hi:[1,0]
	v_mul_f32_e32 v22, 0xbfb8aa3b, v18
	v_mul_f32_e32 v23, 0xbfb8aa3b, v19
	v_exp_f32_e32 v22, v22
	v_exp_f32_e32 v23, v23
	v_pk_fma_f32 v[20:21], v[4:5], v[20:21], v[8:9]
	v_add_f32_e32 v22, 1.0, v22
	v_add_f32_e32 v23, 1.0, v23
	v_rcp_f32_e32 v22, v22
	v_rcp_f32_e32 v23, v23
	s_nop 0
	v_pk_mul_f32 v[18:19], v[18:19], v[22:23]
	v_mul_f32_e32 v22, 0xbfb8aa3b, v20
	v_mul_f32_e32 v23, 0xbfb8aa3b, v21
	v_exp_f32_e32 v22, v22
	v_exp_f32_e32 v23, v23
	v_cvt_pk_bf16_f32 v18, v18, v19
	v_add_f32_e32 v22, 1.0, v22
	v_add_f32_e32 v23, 1.0, v23
	v_rcp_f32_e32 v22, v22
	v_rcp_f32_e32 v23, v23
	s_nop 0
	v_pk_mul_f32 v[20:21], v[20:21], v[22:23]
	v_cvt_pk_bf16_f32 v19, v20, v21
	global_store_dwordx2 v38, v[18:19], s[46:47] offset:512
	v_fma_f32 v18, s7, v235, v225
	v_rsq_f32_e32 v18, v18
	s_nop 0
	v_pk_mul_f32 v[14:15], v[14:15], v[18:19] op_sel_hi:[1,0]
	v_pk_fma_f32 v[14:15], v[2:3], v[14:15], v[6:7]
	v_pk_mul_f32 v[16:17], v[16:17], v[18:19] op_sel_hi:[1,0]
	v_mul_f32_e32 v18, 0xbfb8aa3b, v14
	v_mul_f32_e32 v19, 0xbfb8aa3b, v15
	v_exp_f32_e32 v18, v18
	v_exp_f32_e32 v19, v19
	v_pk_fma_f32 v[16:17], v[4:5], v[16:17], v[8:9]
	v_add_f32_e32 v18, 1.0, v18
	v_add_f32_e32 v19, 1.0, v19
	v_rcp_f32_e32 v18, v18
	v_rcp_f32_e32 v19, v19
	s_nop 0
	v_pk_mul_f32 v[14:15], v[14:15], v[18:19]
	v_mul_f32_e32 v18, 0xbfb8aa3b, v16
	v_mul_f32_e32 v19, 0xbfb8aa3b, v17
	v_exp_f32_e32 v18, v18
	v_exp_f32_e32 v19, v19
	v_cvt_pk_bf16_f32 v14, v14, v15
	v_add_f32_e32 v18, 1.0, v18
	v_add_f32_e32 v19, 1.0, v19
	v_rcp_f32_e32 v18, v18
	v_rcp_f32_e32 v19, v19
	s_nop 0
	v_pk_mul_f32 v[16:17], v[16:17], v[18:19]
	v_cvt_pk_bf16_f32 v15, v16, v17
	global_store_dwordx2 v38, v[14:15], s[44:45] offset:512
	v_fma_f32 v14, s6, v235, v225
	v_rsq_f32_e32 v14, v14
	s_mov_b32 s6, s65
	v_pk_mul_f32 v[10:11], v[10:11], v[14:15] op_sel_hi:[1,0]
	v_pk_fma_f32 v[10:11], v[2:3], v[10:11], v[6:7]
	v_pk_mul_f32 v[12:13], v[12:13], v[14:15] op_sel_hi:[1,0]
	v_mul_f32_e32 v14, 0xbfb8aa3b, v10
	v_mul_f32_e32 v15, 0xbfb8aa3b, v11
	v_exp_f32_e32 v14, v14
	v_exp_f32_e32 v15, v15
	v_pk_fma_f32 v[12:13], v[4:5], v[12:13], v[8:9]
	v_add_f32_e32 v14, 1.0, v14
	v_add_f32_e32 v15, 1.0, v15
	v_rcp_f32_e32 v14, v14
	v_rcp_f32_e32 v15, v15
	s_nop 0
	v_pk_mul_f32 v[10:11], v[10:11], v[14:15]
	v_mul_f32_e32 v14, 0xbfb8aa3b, v12
	v_mul_f32_e32 v15, 0xbfb8aa3b, v13
	v_exp_f32_e32 v14, v14
	v_exp_f32_e32 v15, v15
	v_cvt_pk_bf16_f32 v10, v10, v11
	v_add_f32_e32 v14, 1.0, v14
	v_add_f32_e32 v15, 1.0, v15
	v_rcp_f32_e32 v14, v14
	v_rcp_f32_e32 v15, v15
	s_nop 0
	v_pk_mul_f32 v[12:13], v[12:13], v[14:15]
	v_cvt_pk_bf16_f32 v11, v12, v13
	global_store_dwordx2 v38, v[10:11], s[42:43] offset:512
	s_barrier
	s_cbranch_scc1 .LBB0_344

.LBB0_571:
	s_mov_b32 s4, s36
	s_add_i32 s36, s36, s30
	s_cmpk_gt_i32 s36, 0x7fff
	s_cselect_b64 s[40:41], -1, 0
	s_cmp_lt_i32 s36, 0x8000
	s_cselect_b32 s4, s36, s4
	s_ashr_i32 s5, s4, 31
	s_lshl_b64 s[4:5], s[4:5], 12
	v_lshl_add_u64 v[14:15], v[34:35], 0, s[4:5]
	global_load_dwordx4 v[30:33], v[14:15], off
	global_load_dwordx4 v[26:29], v[14:15], off offset:1024
	global_load_dwordx4 v[22:25], v[14:15], off offset:2048
	s_nop 0
	global_load_dwordx4 v[14:17], v[14:15], off offset:3072
	s_waitcnt vmcnt(7)
	v_mul_f32_e32 v1, v19, v19
	v_cvt_pk_bf16_f32 v42, v18, v19
	v_fmac_f32_e32 v1, v18, v18
	v_mul_f32_e32 v18, v21, v21
	v_fmac_f32_e32 v18, v20, v20
	v_add_f32_e32 v1, v1, v18
	s_waitcnt vmcnt(6)
	v_cvt_pk_bf16_f32 v18, v10, v11
	v_mul_f32_e32 v11, v11, v11
	v_fmac_f32_e32 v11, v10, v10
	v_mul_f32_e32 v10, v13, v13
	v_fmac_f32_e32 v10, v12, v12
	v_add_f32_e32 v10, v11, v10
	v_add_f32_e32 v1, v1, v10
	s_waitcnt vmcnt(5)
	v_cvt_pk_bf16_f32 v10, v6, v7
	v_mul_f32_e32 v7, v7, v7
	v_fmac_f32_e32 v7, v6, v6
	v_mul_f32_e32 v6, v9, v9
	v_fmac_f32_e32 v6, v8, v8
	v_add_f32_e32 v6, v7, v6
	v_add_f32_e32 v1, v6, v1
	s_waitcnt vmcnt(4)
	v_cvt_pk_bf16_f32 v6, v2, v3
	v_mul_f32_e32 v3, v3, v3
	v_fmac_f32_e32 v3, v2, v2
	v_mul_f32_e32 v2, v5, v5
	v_fmac_f32_e32 v2, v4, v4
	v_add_f32_e32 v2, v3, v2
	v_add_f32_e32 v1, v2, v1
	v_lshl_add_u64 v[40:41], s[78:79], 0, v[38:39]
	s_nop 0
	v_add_f32_dpp v1, v1, v1 quad_perm:[1,0,3,2] row_mask:0xf bank_mask:0xf bound_ctrl:1
	s_brev_b32 s4, 32
	v_add_co_u32_e32 v40, vcc, s4, v40
	v_add_f32_dpp v1, v1, v1 quad_perm:[2,3,0,1] row_mask:0xf bank_mask:0xf bound_ctrl:1
	v_cvt_pk_bf16_f32 v43, v20, v21
	v_addc_co_u32_e32 v41, vcc, 0, v41, vcc
	v_add_f32_dpp v1, v1, v1 row_half_mirror row_mask:0xf bank_mask:0xf bound_ctrl:1
	v_cvt_pk_bf16_f32 v19, v12, v13
	v_cvt_pk_bf16_f32 v11, v8, v9
	v_add_f32_dpp v1, v1, v1 row_mirror row_mask:0xf bank_mask:0xf bound_ctrl:1
	v_cvt_pk_bf16_f32 v7, v4, v5
	global_store_dwordx2 v[40:41], v[42:43], off
	v_add_f32_dpp v1, v1, v1 row_bcast:15 row_mask:0xa bank_mask:0xf
	global_store_dwordx2 v[40:41], v[18:19], off offset:512
	global_store_dwordx2 v[40:41], v[10:11], off offset:1024
	v_add_f32_dpp v1, v1, v1 row_bcast:31 row_mask:0xc bank_mask:0xf
	global_store_dwordx2 v[40:41], v[6:7], off offset:1536
	v_readlane_b32 s4, v1, 63
	s_and_saveexec_b64 s[46:47], s[42:43]
	s_cbranch_execz .LBB0_570
	v_mov_b32_e32 v1, s4
	v_cndmask_b32_e64 v130, 0, v1, s[44:45]
	v_lshl_add_u64 v[2:3], s[78:79], 0, v[36:37]
	v_mov_b32_e32 v132, v131
	v_mov_b32_e32 v133, v131
	global_store_dwordx4 v[2:3], v[130:133], off
	s_branch .LBB0_570
